# GEMM epilogue stores write-through (sc1) so the following grid barrier's L2 write-back is cheap
# baseline (speedup 1.0000x reference)
; __device__ __forceinline__ unsigned pk2(float lo, float hi) { unsigned r; asm("v_cvt_pk_bf16_f32 %0, %1, %2" : "=v"(r) : "v"(lo), "v"(hi)); return r; }
;     __device__ __forceinline__ void operator()(EPI_ARGS) const {
;     ...
;         } else {
;             const bool kv = (seg == 1 || seg == 2);
; #pragma unroll
;             for (int ai = 0; ai < 2; ++ai)
; #pragma unroll
;                 for (int m = 0; m < 4; ++m) { const int row = row0 + ai * 128 + m * 16;
; #pragma unroll
;                     for (int bj = 0; bj < 2; ++bj) { const f32x4 v0 = acc[ai][bj][m][0], v1 = acc[ai][bj][m][1]; const int col = colt + bj * 128;
;                         u32x4 w; w.x = pk2(v0[0], v0[1]); w.y = pk2(v0[2], v0[3]); w.z = pk2(v1[0], v1[1]); w.w = pk2(v1[2], v1[3]);
;                         *(u32x4*)(proj + (size_t)row * NIN + col) = w;
;                         if (kv) { const int c = col - seg * 1024; float* dst = nullptr;
;                             if (row >= TP - 512 && row < TP) dst = out + (seg == 1 ? OFF_KP : OFF_VP) + ((size_t)layer * 512 + (row - (TP - 512))) * 1024 + c;
;                             else if (row >= TP && row < MROWS) dst = out + (seg == 1 ? OFF_KS : OFF_VS) + ((size_t)layer * 128 + (row - TP)) * 1024 + c;
;                             if (dst) { *(f32x4*)dst = v0; *(f32x4*)(dst + 4) = v1; } } } }
.LBB0_77:
	s_ashr_i32 s4, s0, 2
	s_cmp_lg_u32 s4, 8
	s_mov_b64 s[0:1], -1
	s_cbranch_scc0 .LBB0_175
	s_add_i32 s0, s4, -1
	s_cmp_lt_u32 s0, 2
	s_cselect_b64 s[2:3], -1, 0
	s_lshl_b32 s8, s4, 10
	s_cmp_eq_u32 s4, 1
	s_mov_b32 s1, 0x12c5800
	s_cselect_b32 s14, s1, 0x1305800
	s_mov_b32 s1, 0x1040000
	s_cselect_b32 s9, s1, 0x1140000
	s_and_b32 s1, s15, 0xfffffe00
	s_cmpk_lg_i32 s1, 0x1e00
	s_cselect_b64 s[4:5], -1, 0
	s_and_b32 s1, s15, 0xffffff80
	v_lshlrev_b32_e32 v130, 10, v150
	s_cmpk_eq_i32 s1, 0x2000
	v_add_u32_e32 v8, 0xff800000, v130
	v_add_u32_e32 v132, 0xff880000, v130
	v_mov_b64_e32 v[130:131], s[30:31]
	s_cselect_b64 s[38:39], -1, 0
	s_cmp_gt_u32 s0, 1
	v_mad_i64_i32 v[130:131], s[0:1], v150, s13, v[130:131]
	v_ashrrev_i32_e32 v153, 31, v152
	v_mov_b32_e32 v133, v9
	v_lshl_add_u64 v[134:135], v[152:153], 1, v[130:131]
	v_subrev_u32_e32 v130, s8, v152
	v_cvt_pk_bf16_f32 v154, v126, v127
	v_cvt_pk_bf16_f32 v155, v128, v129
	v_cvt_pk_bf16_f32 v156, v122, v123
	v_cvt_pk_bf16_f32 v157, v124, v125
	global_store_dwordx4 v[134:135], v[154:157], off sc1
	s_cbranch_scc1 .LBB0_84
	v_ashrrev_i32_e32 v131, 31, v130
	s_mov_b64 s[0:1], -1
	s_and_b64 vcc, exec, s[4:5]
	s_cbranch_vccnz .LBB0_185
	s_andn2_b64 vcc, exec, s[0:1]
	s_cbranch_vccz .LBB0_186

;     __device__ __forceinline__ void operator()(EPI_ARGS) const {
;     ...
;                         if (kv) { const int c = col - seg * 1024; float* dst = nullptr;
;                             if (row >= TP - 512 && row < TP) dst = out + (seg == 1 ? OFF_KP : OFF_VP) + ((size_t)layer * 512 + (row - (TP - 512))) * 1024 + c;
;                             else if (row >= TP && row < MROWS) dst = out + (seg == 1 ? OFF_KS : OFF_VS) + ((size_t)layer * 128 + (row - TP)) * 1024 + c;
;                             if (dst) { *(f32x4*)dst = v0; *(f32x4*)(dst + 4) = v1; } } } }
.LBB0_82:
	global_store_dwordx4 v[136:137], v[126:129], off sc1
	global_store_dwordx4 v[136:137], v[122:125], off offset:16 sc1

; __device__ __forceinline__ unsigned pk2(float lo, float hi) { unsigned r; asm("v_cvt_pk_bf16_f32 %0, %1, %2" : "=v"(r) : "v"(lo), "v"(hi)); return r; }
;     __device__ __forceinline__ void operator()(EPI_ARGS) const {
;     ...
;                     for (int bj = 0; bj < 2; ++bj) { const f32x4 v0 = acc[ai][bj][m][0], v1 = acc[ai][bj][m][1]; const int col = colt + bj * 128;
;                         u32x4 w; w.x = pk2(v0[0], v0[1]); w.y = pk2(v0[2], v0[3]); w.z = pk2(v1[0], v1[1]); w.w = pk2(v1[2], v1[3]);
;                         *(u32x4*)(proj + (size_t)row * NIN + col) = w;
.LBB0_84:
	v_cndmask_b32_e64 v131, 0, 1, s[2:3]
	v_cmp_ne_u32_e64 s[0:1], 1, v131
	v_cndmask_b32_e64 v131, 0, 1, s[4:5]
	s_andn2_b64 vcc, exec, s[2:3]
	v_cmp_ne_u32_e64 s[40:41], 1, v131
	v_cvt_pk_bf16_f32 v154, v118, v119
	v_cvt_pk_bf16_f32 v155, v120, v121
	v_cvt_pk_bf16_f32 v156, v114, v115
	v_cvt_pk_bf16_f32 v157, v116, v117
	global_store_dwordx4 v[134:135], v[154:157], off offset:256 sc1
	s_cbranch_vccnz .LBB0_90
	s_and_b64 vcc, exec, s[40:41]
	s_mov_b64 s[2:3], -1
	s_cbranch_vccz .LBB0_187
	s_andn2_b64 vcc, exec, s[2:3]
	s_cbranch_vccz .LBB0_188

;     __device__ __forceinline__ void operator()(EPI_ARGS) const {
;     ...
;                         if (kv) { const int c = col - seg * 1024; float* dst = nullptr;
;                             if (row >= TP - 512 && row < TP) dst = out + (seg == 1 ? OFF_KP : OFF_VP) + ((size_t)layer * 512 + (row - (TP - 512))) * 1024 + c;
;                             else if (row >= TP && row < MROWS) dst = out + (seg == 1 ? OFF_KS : OFF_VS) + ((size_t)layer * 128 + (row - TP)) * 1024 + c;
;                             if (dst) { *(f32x4*)dst = v0; *(f32x4*)(dst + 4) = v1; } } } }
.LBB0_88:
	global_store_dwordx4 v[134:135], v[118:121], off sc1
	global_store_dwordx4 v[134:135], v[114:117], off offset:16 sc1

; __device__ __forceinline__ unsigned pk2(float lo, float hi) { unsigned r; asm("v_cvt_pk_bf16_f32 %0, %1, %2" : "=v"(r) : "v"(lo), "v"(hi)); return r; }
;     __device__ __forceinline__ void operator()(EPI_ARGS) const {
;     ...
;                 for (int m = 0; m < 4; ++m) { const int row = row0 + ai * 128 + m * 16;
; #pragma unroll
;                     for (int bj = 0; bj < 2; ++bj) { const f32x4 v0 = acc[ai][bj][m][0], v1 = acc[ai][bj][m][1]; const int col = colt + bj * 128;
;                         u32x4 w; w.x = pk2(v0[0], v0[1]); w.y = pk2(v0[2], v0[3]); w.z = pk2(v1[0], v1[1]); w.w = pk2(v1[2], v1[3]);
;                         *(u32x4*)(proj + (size_t)row * NIN + col) = w;
.LBB0_90:
	v_or_b32_e32 v8, 16, v150
	v_mov_b64_e32 v[132:133], s[30:31]
	v_lshlrev_b32_e32 v131, 10, v8
	v_mad_i64_i32 v[132:133], s[2:3], v8, s13, v[132:133]
	v_add_u32_e32 v137, 0xff800000, v131
	v_add_u32_e32 v136, 0xff880000, v131
	v_lshl_add_u64 v[132:133], v[152:153], 1, v[132:133]
	s_and_b64 vcc, exec, s[0:1]
	v_cvt_pk_bf16_f32 v154, v110, v111
	v_cvt_pk_bf16_f32 v155, v112, v113
	v_cvt_pk_bf16_f32 v156, v106, v107
	v_cvt_pk_bf16_f32 v157, v108, v109
	global_store_dwordx4 v[132:133], v[154:157], off sc1
	s_cbranch_vccnz .LBB0_96
	s_and_b64 vcc, exec, s[40:41]
	s_mov_b64 s[2:3], -1
	s_cbranch_vccz .LBB0_189
	s_andn2_b64 vcc, exec, s[2:3]
	s_cbranch_vccz .LBB0_192

;     __device__ __forceinline__ void operator()(EPI_ARGS) const {
;     ...
;                         if (kv) { const int c = col - seg * 1024; float* dst = nullptr;
;                             if (row >= TP - 512 && row < TP) dst = out + (seg == 1 ? OFF_KP : OFF_VP) + ((size_t)layer * 512 + (row - (TP - 512))) * 1024 + c;
;                             else if (row >= TP && row < MROWS) dst = out + (seg == 1 ? OFF_KS : OFF_VS) + ((size_t)layer * 128 + (row - TP)) * 1024 + c;
;                             if (dst) { *(f32x4*)dst = v0; *(f32x4*)(dst + 4) = v1; } } } }
.LBB0_94:
	global_store_dwordx4 v[134:135], v[110:113], off sc1
	global_store_dwordx4 v[134:135], v[106:109], off offset:16 sc1

; __device__ __forceinline__ unsigned pk2(float lo, float hi) { unsigned r; asm("v_cvt_pk_bf16_f32 %0, %1, %2" : "=v"(r) : "v"(lo), "v"(hi)); return r; }
;     __device__ __forceinline__ void operator()(EPI_ARGS) const {
;     ...
;                     for (int bj = 0; bj < 2; ++bj) { const f32x4 v0 = acc[ai][bj][m][0], v1 = acc[ai][bj][m][1]; const int col = colt + bj * 128;
;                         u32x4 w; w.x = pk2(v0[0], v0[1]); w.y = pk2(v0[2], v0[3]); w.z = pk2(v1[0], v1[1]); w.w = pk2(v1[2], v1[3]);
;                         *(u32x4*)(proj + (size_t)row * NIN + col) = w;
.LBB0_96:
	s_and_b64 vcc, exec, s[0:1]
	v_cvt_pk_bf16_f32 v154, v102, v103
	v_cvt_pk_bf16_f32 v155, v104, v105
	v_cvt_pk_bf16_f32 v156, v98, v99
	v_cvt_pk_bf16_f32 v157, v100, v101
	global_store_dwordx4 v[132:133], v[154:157], off offset:256 sc1
	s_cbranch_vccnz .LBB0_102
	s_and_b64 vcc, exec, s[40:41]
	s_mov_b64 s[2:3], -1
	s_cbranch_vccz .LBB0_193
	s_andn2_b64 vcc, exec, s[2:3]
	s_cbranch_vccz .LBB0_196

;     __device__ __forceinline__ void operator()(EPI_ARGS) const {
;     ...
;                         if (kv) { const int c = col - seg * 1024; float* dst = nullptr;
;                             if (row >= TP - 512 && row < TP) dst = out + (seg == 1 ? OFF_KP : OFF_VP) + ((size_t)layer * 512 + (row - (TP - 512))) * 1024 + c;
;                             else if (row >= TP && row < MROWS) dst = out + (seg == 1 ? OFF_KS : OFF_VS) + ((size_t)layer * 128 + (row - TP)) * 1024 + c;
;                             if (dst) { *(f32x4*)dst = v0; *(f32x4*)(dst + 4) = v1; } } } }
.LBB0_100:
	global_store_dwordx4 v[132:133], v[102:105], off sc1
	global_store_dwordx4 v[132:133], v[98:101], off offset:16 sc1

; __device__ __forceinline__ unsigned pk2(float lo, float hi) { unsigned r; asm("v_cvt_pk_bf16_f32 %0, %1, %2" : "=v"(r) : "v"(lo), "v"(hi)); return r; }
;     __device__ __forceinline__ void operator()(EPI_ARGS) const {
;     ...
;                 for (int m = 0; m < 4; ++m) { const int row = row0 + ai * 128 + m * 16;
; #pragma unroll
;                     for (int bj = 0; bj < 2; ++bj) { const f32x4 v0 = acc[ai][bj][m][0], v1 = acc[ai][bj][m][1]; const int col = colt + bj * 128;
;                         u32x4 w; w.x = pk2(v0[0], v0[1]); w.y = pk2(v0[2], v0[3]); w.z = pk2(v1[0], v1[1]); w.w = pk2(v1[2], v1[3]);
;                         *(u32x4*)(proj + (size_t)row * NIN + col) = w;
.LBB0_102:
	v_or_b32_e32 v8, 32, v150
	v_mov_b64_e32 v[132:133], s[30:31]
	v_lshlrev_b32_e32 v131, 10, v8
	v_mad_i64_i32 v[132:133], s[2:3], v8, s13, v[132:133]
	v_add_u32_e32 v137, 0xff800000, v131
	v_add_u32_e32 v136, 0xff880000, v131
	v_lshl_add_u64 v[132:133], v[152:153], 1, v[132:133]
	s_and_b64 vcc, exec, s[0:1]
	v_cvt_pk_bf16_f32 v154, v94, v95
	v_cvt_pk_bf16_f32 v155, v96, v97
	v_cvt_pk_bf16_f32 v156, v90, v91
	v_cvt_pk_bf16_f32 v157, v92, v93
	global_store_dwordx4 v[132:133], v[154:157], off sc1
	s_cbranch_vccnz .LBB0_108
	s_and_b64 vcc, exec, s[40:41]
	s_mov_b64 s[2:3], -1
	s_cbranch_vccz .LBB0_197
	s_andn2_b64 vcc, exec, s[2:3]
	s_cbranch_vccz .LBB0_200

;     __device__ __forceinline__ void operator()(EPI_ARGS) const {
;     ...
;                         if (kv) { const int c = col - seg * 1024; float* dst = nullptr;
;                             if (row >= TP - 512 && row < TP) dst = out + (seg == 1 ? OFF_KP : OFF_VP) + ((size_t)layer * 512 + (row - (TP - 512))) * 1024 + c;
;                             else if (row >= TP && row < MROWS) dst = out + (seg == 1 ? OFF_KS : OFF_VS) + ((size_t)layer * 128 + (row - TP)) * 1024 + c;
;                             if (dst) { *(f32x4*)dst = v0; *(f32x4*)(dst + 4) = v1; } } } }
.LBB0_106:
	global_store_dwordx4 v[134:135], v[94:97], off sc1
	global_store_dwordx4 v[134:135], v[90:93], off offset:16 sc1

; __device__ __forceinline__ unsigned pk2(float lo, float hi) { unsigned r; asm("v_cvt_pk_bf16_f32 %0, %1, %2" : "=v"(r) : "v"(lo), "v"(hi)); return r; }
;     __device__ __forceinline__ void operator()(EPI_ARGS) const {
;     ...
;                     for (int bj = 0; bj < 2; ++bj) { const f32x4 v0 = acc[ai][bj][m][0], v1 = acc[ai][bj][m][1]; const int col = colt + bj * 128;
;                         u32x4 w; w.x = pk2(v0[0], v0[1]); w.y = pk2(v0[2], v0[3]); w.z = pk2(v1[0], v1[1]); w.w = pk2(v1[2], v1[3]);
;                         *(u32x4*)(proj + (size_t)row * NIN + col) = w;
.LBB0_108:
	s_and_b64 vcc, exec, s[0:1]
	v_cvt_pk_bf16_f32 v154, v86, v87
	v_cvt_pk_bf16_f32 v155, v88, v89
	v_cvt_pk_bf16_f32 v156, v82, v83
	v_cvt_pk_bf16_f32 v157, v84, v85
	global_store_dwordx4 v[132:133], v[154:157], off offset:256 sc1
	s_cbranch_vccnz .LBB0_114
	s_and_b64 vcc, exec, s[40:41]
	s_mov_b64 s[2:3], -1
	s_cbranch_vccz .LBB0_201
	s_andn2_b64 vcc, exec, s[2:3]
	s_cbranch_vccz .LBB0_204

;     __device__ __forceinline__ void operator()(EPI_ARGS) const {
;     ...
;                         if (kv) { const int c = col - seg * 1024; float* dst = nullptr;
;                             if (row >= TP - 512 && row < TP) dst = out + (seg == 1 ? OFF_KP : OFF_VP) + ((size_t)layer * 512 + (row - (TP - 512))) * 1024 + c;
;                             else if (row >= TP && row < MROWS) dst = out + (seg == 1 ? OFF_KS : OFF_VS) + ((size_t)layer * 128 + (row - TP)) * 1024 + c;
;                             if (dst) { *(f32x4*)dst = v0; *(f32x4*)(dst + 4) = v1; } } } }
.LBB0_112:
	global_store_dwordx4 v[132:133], v[86:89], off sc1
	global_store_dwordx4 v[132:133], v[82:85], off offset:16 sc1

; __device__ __forceinline__ unsigned pk2(float lo, float hi) { unsigned r; asm("v_cvt_pk_bf16_f32 %0, %1, %2" : "=v"(r) : "v"(lo), "v"(hi)); return r; }
;     __device__ __forceinline__ void operator()(EPI_ARGS) const {
;     ...
;                 for (int m = 0; m < 4; ++m) { const int row = row0 + ai * 128 + m * 16;
; #pragma unroll
;                     for (int bj = 0; bj < 2; ++bj) { const f32x4 v0 = acc[ai][bj][m][0], v1 = acc[ai][bj][m][1]; const int col = colt + bj * 128;
;                         u32x4 w; w.x = pk2(v0[0], v0[1]); w.y = pk2(v0[2], v0[3]); w.z = pk2(v1[0], v1[1]); w.w = pk2(v1[2], v1[3]);
;                         *(u32x4*)(proj + (size_t)row * NIN + col) = w;
.LBB0_114:
	v_or_b32_e32 v8, 48, v150
	v_mov_b64_e32 v[132:133], s[30:31]
	v_lshlrev_b32_e32 v131, 10, v8
	v_mad_i64_i32 v[132:133], s[2:3], v8, s13, v[132:133]
	v_add_u32_e32 v137, 0xff800000, v131
	v_add_u32_e32 v136, 0xff880000, v131
	v_lshl_add_u64 v[132:133], v[152:153], 1, v[132:133]
	s_and_b64 vcc, exec, s[0:1]
	v_cvt_pk_bf16_f32 v154, v78, v79
	v_cvt_pk_bf16_f32 v155, v80, v81
	v_cvt_pk_bf16_f32 v156, v74, v75
	v_cvt_pk_bf16_f32 v157, v76, v77
	global_store_dwordx4 v[132:133], v[154:157], off sc1
	s_cbranch_vccnz .LBB0_120
	s_and_b64 vcc, exec, s[40:41]
	s_mov_b64 s[2:3], -1
	s_cbranch_vccz .LBB0_205
	s_andn2_b64 vcc, exec, s[2:3]
	s_cbranch_vccz .LBB0_208

;     __device__ __forceinline__ void operator()(EPI_ARGS) const {
;     ...
;                         if (kv) { const int c = col - seg * 1024; float* dst = nullptr;
;                             if (row >= TP - 512 && row < TP) dst = out + (seg == 1 ? OFF_KP : OFF_VP) + ((size_t)layer * 512 + (row - (TP - 512))) * 1024 + c;
;                             else if (row >= TP && row < MROWS) dst = out + (seg == 1 ? OFF_KS : OFF_VS) + ((size_t)layer * 128 + (row - TP)) * 1024 + c;
;                             if (dst) { *(f32x4*)dst = v0; *(f32x4*)(dst + 4) = v1; } } } }
.LBB0_118:
	global_store_dwordx4 v[134:135], v[78:81], off sc1
	global_store_dwordx4 v[134:135], v[74:77], off offset:16 sc1

; __device__ __forceinline__ unsigned pk2(float lo, float hi) { unsigned r; asm("v_cvt_pk_bf16_f32 %0, %1, %2" : "=v"(r) : "v"(lo), "v"(hi)); return r; }
;     __device__ __forceinline__ void operator()(EPI_ARGS) const {
;     ...
;                     for (int bj = 0; bj < 2; ++bj) { const f32x4 v0 = acc[ai][bj][m][0], v1 = acc[ai][bj][m][1]; const int col = colt + bj * 128;
;                         u32x4 w; w.x = pk2(v0[0], v0[1]); w.y = pk2(v0[2], v0[3]); w.z = pk2(v1[0], v1[1]); w.w = pk2(v1[2], v1[3]);
;                         *(u32x4*)(proj + (size_t)row * NIN + col) = w;
.LBB0_120:
	s_and_b64 vcc, exec, s[0:1]
	v_cvt_pk_bf16_f32 v154, v70, v71
	v_cvt_pk_bf16_f32 v155, v72, v73
	v_cvt_pk_bf16_f32 v156, v66, v67
	v_cvt_pk_bf16_f32 v157, v68, v69
	global_store_dwordx4 v[132:133], v[154:157], off offset:256 sc1
	s_cbranch_vccnz .LBB0_126
	s_and_b64 vcc, exec, s[40:41]
	s_mov_b64 s[2:3], -1
	s_cbranch_vccz .LBB0_209
	s_andn2_b64 vcc, exec, s[2:3]
	s_cbranch_vccz .LBB0_212

;     __device__ __forceinline__ void operator()(EPI_ARGS) const {
;     ...
;                         if (kv) { const int c = col - seg * 1024; float* dst = nullptr;
;                             if (row >= TP - 512 && row < TP) dst = out + (seg == 1 ? OFF_KP : OFF_VP) + ((size_t)layer * 512 + (row - (TP - 512))) * 1024 + c;
;                             else if (row >= TP && row < MROWS) dst = out + (seg == 1 ? OFF_KS : OFF_VS) + ((size_t)layer * 128 + (row - TP)) * 1024 + c;
;                             if (dst) { *(f32x4*)dst = v0; *(f32x4*)(dst + 4) = v1; } } } }
.LBB0_124:
	global_store_dwordx4 v[132:133], v[70:73], off sc1
	global_store_dwordx4 v[132:133], v[66:69], off offset:16 sc1

; __device__ __forceinline__ unsigned pk2(float lo, float hi) { unsigned r; asm("v_cvt_pk_bf16_f32 %0, %1, %2" : "=v"(r) : "v"(lo), "v"(hi)); return r; }
;     __device__ __forceinline__ void operator()(EPI_ARGS) const {
;     ...
;             for (int ai = 0; ai < 2; ++ai)
; #pragma unroll
;                 for (int m = 0; m < 4; ++m) { const int row = row0 + ai * 128 + m * 16;
; #pragma unroll
;                     for (int bj = 0; bj < 2; ++bj) { const f32x4 v0 = acc[ai][bj][m][0], v1 = acc[ai][bj][m][1]; const int col = colt + bj * 128;
;                         u32x4 w; w.x = pk2(v0[0], v0[1]); w.y = pk2(v0[2], v0[3]); w.z = pk2(v1[0], v1[1]); w.w = pk2(v1[2], v1[3]);
;                         *(u32x4*)(proj + (size_t)row * NIN + col) = w;
;                         if (kv) { const int c = col - seg * 1024; float* dst = nullptr;
;                             if (row >= TP - 512 && row < TP) dst = out + (seg == 1 ? OFF_KP : OFF_VP) + ((size_t)layer * 512 + (row - (TP - 512))) * 1024 + c;
;                             else if (row >= TP && row < MROWS) dst = out + (seg == 1 ? OFF_KS : OFF_VS) + ((size_t)layer * 128 + (row - TP)) * 1024 + c;
.LBB0_126:
	v_add_u32_e32 v131, 0x80, v150
	v_and_b32_e32 v8, 0xfffffe00, v131
	s_movk_i32 s2, 0x1e00
	v_mov_b64_e32 v[134:135], s[30:31]
	v_cmp_ne_u32_e64 s[40:41], s2, v8
	v_and_b32_e32 v8, 0xffffff80, v131
	v_lshlrev_b32_e32 v132, 10, v131
	v_mad_i64_i32 v[134:135], s[2:3], v131, s13, v[134:135]
	v_cmp_eq_u32_e64 s[38:39], s77, v8
	v_add_u32_e32 v8, 0xff800000, v132
	v_add_u32_e32 v132, 0xff880000, v132
	v_mov_b32_e32 v133, v9
	v_lshl_add_u64 v[134:135], v[152:153], 1, v[134:135]
	s_and_b64 vcc, exec, s[0:1]
	v_cvt_pk_bf16_f32 v154, v62, v63
	v_cvt_pk_bf16_f32 v155, v64, v65
	v_cvt_pk_bf16_f32 v156, v58, v59
	v_cvt_pk_bf16_f32 v157, v60, v61
	global_store_dwordx4 v[134:135], v[154:157], off sc1
	s_cbranch_vccnz .LBB0_132
	v_ashrrev_i32_e32 v131, 31, v130
	s_and_saveexec_b64 s[2:3], s[40:41]
	s_xor_b64 s[2:3], exec, s[2:3]
	s_cbranch_execnz .LBB0_213
	s_andn2_saveexec_b64 s[2:3], s[2:3]
	s_cbranch_execnz .LBB0_214

;     __device__ __forceinline__ void operator()(EPI_ARGS) const {
;     ...
;                         if (kv) { const int c = col - seg * 1024; float* dst = nullptr;
;                             if (row >= TP - 512 && row < TP) dst = out + (seg == 1 ? OFF_KP : OFF_VP) + ((size_t)layer * 512 + (row - (TP - 512))) * 1024 + c;
;                             else if (row >= TP && row < MROWS) dst = out + (seg == 1 ? OFF_KS : OFF_VS) + ((size_t)layer * 128 + (row - TP)) * 1024 + c;
;                             if (dst) { *(f32x4*)dst = v0; *(f32x4*)(dst + 4) = v1; } } } }
.LBB0_130:
	global_store_dwordx4 v[136:137], v[62:65], off sc1
	global_store_dwordx4 v[136:137], v[58:61], off offset:16 sc1

; __device__ __forceinline__ unsigned pk2(float lo, float hi) { unsigned r; asm("v_cvt_pk_bf16_f32 %0, %1, %2" : "=v"(r) : "v"(lo), "v"(hi)); return r; }
;     __device__ __forceinline__ void operator()(EPI_ARGS) const {
;     ...
;                     for (int bj = 0; bj < 2; ++bj) { const f32x4 v0 = acc[ai][bj][m][0], v1 = acc[ai][bj][m][1]; const int col = colt + bj * 128;
;                         u32x4 w; w.x = pk2(v0[0], v0[1]); w.y = pk2(v0[2], v0[3]); w.z = pk2(v1[0], v1[1]); w.w = pk2(v1[2], v1[3]);
;                         *(u32x4*)(proj + (size_t)row * NIN + col) = w;
.LBB0_132:
	s_and_b64 vcc, exec, s[0:1]
	v_cvt_pk_bf16_f32 v154, v54, v55
	v_cvt_pk_bf16_f32 v155, v56, v57
	v_cvt_pk_bf16_f32 v156, v50, v51
	v_cvt_pk_bf16_f32 v157, v52, v53
	global_store_dwordx4 v[134:135], v[154:157], off offset:256 sc1
	s_cbranch_vccnz .LBB0_138
	s_and_saveexec_b64 s[2:3], s[40:41]
	s_xor_b64 s[2:3], exec, s[2:3]
	s_cbranch_execnz .LBB0_215
	s_andn2_saveexec_b64 s[2:3], s[2:3]
	s_cbranch_execnz .LBB0_216

;     __device__ __forceinline__ void operator()(EPI_ARGS) const {
;     ...
;                         if (kv) { const int c = col - seg * 1024; float* dst = nullptr;
;                             if (row >= TP - 512 && row < TP) dst = out + (seg == 1 ? OFF_KP : OFF_VP) + ((size_t)layer * 512 + (row - (TP - 512))) * 1024 + c;
;                             else if (row >= TP && row < MROWS) dst = out + (seg == 1 ? OFF_KS : OFF_VS) + ((size_t)layer * 128 + (row - TP)) * 1024 + c;
;                             if (dst) { *(f32x4*)dst = v0; *(f32x4*)(dst + 4) = v1; } } } }
.LBB0_136:
	global_store_dwordx4 v[134:135], v[54:57], off sc1
	global_store_dwordx4 v[134:135], v[50:53], off offset:16 sc1

; __device__ __forceinline__ unsigned pk2(float lo, float hi) { unsigned r; asm("v_cvt_pk_bf16_f32 %0, %1, %2" : "=v"(r) : "v"(lo), "v"(hi)); return r; }
;     __device__ __forceinline__ void operator()(EPI_ARGS) const {
;     ...
;                 for (int m = 0; m < 4; ++m) { const int row = row0 + ai * 128 + m * 16;
; #pragma unroll
;                     for (int bj = 0; bj < 2; ++bj) { const f32x4 v0 = acc[ai][bj][m][0], v1 = acc[ai][bj][m][1]; const int col = colt + bj * 128;
;                         u32x4 w; w.x = pk2(v0[0], v0[1]); w.y = pk2(v0[2], v0[3]); w.z = pk2(v1[0], v1[1]); w.w = pk2(v1[2], v1[3]);
;                         *(u32x4*)(proj + (size_t)row * NIN + col) = w;
.LBB0_138:
	v_add_u32_e32 v8, 0x90, v150
	v_mov_b64_e32 v[132:133], s[30:31]
	v_lshlrev_b32_e32 v131, 10, v8
	v_mad_i64_i32 v[132:133], s[2:3], v8, s13, v[132:133]
	v_add_u32_e32 v137, 0xff800000, v131
	v_add_u32_e32 v136, 0xff880000, v131
	v_lshl_add_u64 v[132:133], v[152:153], 1, v[132:133]
	s_and_b64 vcc, exec, s[0:1]
	v_cvt_pk_bf16_f32 v154, v46, v47
	v_cvt_pk_bf16_f32 v155, v48, v49
	v_cvt_pk_bf16_f32 v156, v42, v43
	v_cvt_pk_bf16_f32 v157, v44, v45
	global_store_dwordx4 v[132:133], v[154:157], off sc1
	s_cbranch_vccnz .LBB0_144
	s_and_saveexec_b64 s[2:3], s[40:41]
	s_xor_b64 s[2:3], exec, s[2:3]
	s_cbranch_execnz .LBB0_217
	s_andn2_saveexec_b64 s[2:3], s[2:3]
	s_cbranch_execnz .LBB0_220

;     __device__ __forceinline__ void operator()(EPI_ARGS) const {
;     ...
;                         if (kv) { const int c = col - seg * 1024; float* dst = nullptr;
;                             if (row >= TP - 512 && row < TP) dst = out + (seg == 1 ? OFF_KP : OFF_VP) + ((size_t)layer * 512 + (row - (TP - 512))) * 1024 + c;
;                             else if (row >= TP && row < MROWS) dst = out + (seg == 1 ? OFF_KS : OFF_VS) + ((size_t)layer * 128 + (row - TP)) * 1024 + c;
;                             if (dst) { *(f32x4*)dst = v0; *(f32x4*)(dst + 4) = v1; } } } }
.LBB0_142:
	global_store_dwordx4 v[134:135], v[46:49], off sc1
	global_store_dwordx4 v[134:135], v[42:45], off offset:16 sc1

; __device__ __forceinline__ unsigned pk2(float lo, float hi) { unsigned r; asm("v_cvt_pk_bf16_f32 %0, %1, %2" : "=v"(r) : "v"(lo), "v"(hi)); return r; }
;     __device__ __forceinline__ void operator()(EPI_ARGS) const {
;     ...
;                     for (int bj = 0; bj < 2; ++bj) { const f32x4 v0 = acc[ai][bj][m][0], v1 = acc[ai][bj][m][1]; const int col = colt + bj * 128;
;                         u32x4 w; w.x = pk2(v0[0], v0[1]); w.y = pk2(v0[2], v0[3]); w.z = pk2(v1[0], v1[1]); w.w = pk2(v1[2], v1[3]);
;                         *(u32x4*)(proj + (size_t)row * NIN + col) = w;
.LBB0_144:
	s_and_b64 vcc, exec, s[0:1]
	v_cvt_pk_bf16_f32 v154, v38, v39
	v_cvt_pk_bf16_f32 v155, v40, v41
	v_cvt_pk_bf16_f32 v156, v34, v35
	v_cvt_pk_bf16_f32 v157, v36, v37
	global_store_dwordx4 v[132:133], v[154:157], off offset:256 sc1
	s_cbranch_vccnz .LBB0_150
	s_and_saveexec_b64 s[2:3], s[40:41]
	s_xor_b64 s[2:3], exec, s[2:3]
	s_cbranch_execnz .LBB0_221
	s_andn2_saveexec_b64 s[2:3], s[2:3]
	s_cbranch_execnz .LBB0_224

;     __device__ __forceinline__ void operator()(EPI_ARGS) const {
;     ...
;                         if (kv) { const int c = col - seg * 1024; float* dst = nullptr;
;                             if (row >= TP - 512 && row < TP) dst = out + (seg == 1 ? OFF_KP : OFF_VP) + ((size_t)layer * 512 + (row - (TP - 512))) * 1024 + c;
;                             else if (row >= TP && row < MROWS) dst = out + (seg == 1 ? OFF_KS : OFF_VS) + ((size_t)layer * 128 + (row - TP)) * 1024 + c;
;                             if (dst) { *(f32x4*)dst = v0; *(f32x4*)(dst + 4) = v1; } } } }
.LBB0_148:
	global_store_dwordx4 v[132:133], v[38:41], off sc1
	global_store_dwordx4 v[132:133], v[34:37], off offset:16 sc1

; __device__ __forceinline__ unsigned pk2(float lo, float hi) { unsigned r; asm("v_cvt_pk_bf16_f32 %0, %1, %2" : "=v"(r) : "v"(lo), "v"(hi)); return r; }
;     __device__ __forceinline__ void operator()(EPI_ARGS) const {
;     ...
;                 for (int m = 0; m < 4; ++m) { const int row = row0 + ai * 128 + m * 16;
; #pragma unroll
;                     for (int bj = 0; bj < 2; ++bj) { const f32x4 v0 = acc[ai][bj][m][0], v1 = acc[ai][bj][m][1]; const int col = colt + bj * 128;
;                         u32x4 w; w.x = pk2(v0[0], v0[1]); w.y = pk2(v0[2], v0[3]); w.z = pk2(v1[0], v1[1]); w.w = pk2(v1[2], v1[3]);
;                         *(u32x4*)(proj + (size_t)row * NIN + col) = w;
.LBB0_150:
	v_add_u32_e32 v8, 0xa0, v150
	v_mov_b64_e32 v[132:133], s[30:31]
	v_lshlrev_b32_e32 v131, 10, v8
	v_mad_i64_i32 v[132:133], s[2:3], v8, s13, v[132:133]
	v_add_u32_e32 v137, 0xff800000, v131
	v_add_u32_e32 v136, 0xff880000, v131
	v_lshl_add_u64 v[132:133], v[152:153], 1, v[132:133]
	s_and_b64 vcc, exec, s[0:1]
	v_cvt_pk_bf16_f32 v154, v30, v31
	v_cvt_pk_bf16_f32 v155, v32, v33
	v_cvt_pk_bf16_f32 v156, v26, v27
	v_cvt_pk_bf16_f32 v157, v28, v29
	global_store_dwordx4 v[132:133], v[154:157], off sc1
	s_cbranch_vccnz .LBB0_156
	s_and_saveexec_b64 s[2:3], s[40:41]
	s_xor_b64 s[2:3], exec, s[2:3]
	s_cbranch_execnz .LBB0_225
	s_andn2_saveexec_b64 s[2:3], s[2:3]
	s_cbranch_execnz .LBB0_228

;     __device__ __forceinline__ void operator()(EPI_ARGS) const {
;     ...
;                         if (kv) { const int c = col - seg * 1024; float* dst = nullptr;
;                             if (row >= TP - 512 && row < TP) dst = out + (seg == 1 ? OFF_KP : OFF_VP) + ((size_t)layer * 512 + (row - (TP - 512))) * 1024 + c;
;                             else if (row >= TP && row < MROWS) dst = out + (seg == 1 ? OFF_KS : OFF_VS) + ((size_t)layer * 128 + (row - TP)) * 1024 + c;
;                             if (dst) { *(f32x4*)dst = v0; *(f32x4*)(dst + 4) = v1; } } } }
.LBB0_154:
	global_store_dwordx4 v[134:135], v[30:33], off sc1
	global_store_dwordx4 v[134:135], v[26:29], off offset:16 sc1

; __device__ __forceinline__ unsigned pk2(float lo, float hi) { unsigned r; asm("v_cvt_pk_bf16_f32 %0, %1, %2" : "=v"(r) : "v"(lo), "v"(hi)); return r; }
;     __device__ __forceinline__ void operator()(EPI_ARGS) const {
;     ...
;                     for (int bj = 0; bj < 2; ++bj) { const f32x4 v0 = acc[ai][bj][m][0], v1 = acc[ai][bj][m][1]; const int col = colt + bj * 128;
;                         u32x4 w; w.x = pk2(v0[0], v0[1]); w.y = pk2(v0[2], v0[3]); w.z = pk2(v1[0], v1[1]); w.w = pk2(v1[2], v1[3]);
;                         *(u32x4*)(proj + (size_t)row * NIN + col) = w;
.LBB0_156:
	s_and_b64 vcc, exec, s[0:1]
	v_cvt_pk_bf16_f32 v154, v22, v23
	v_cvt_pk_bf16_f32 v155, v24, v25
	v_cvt_pk_bf16_f32 v156, v18, v19
	v_cvt_pk_bf16_f32 v157, v20, v21
	global_store_dwordx4 v[132:133], v[154:157], off offset:256 sc1
	s_cbranch_vccnz .LBB0_162
	s_and_saveexec_b64 s[2:3], s[40:41]
	s_xor_b64 s[2:3], exec, s[2:3]
	s_cbranch_execnz .LBB0_229
	s_andn2_saveexec_b64 s[2:3], s[2:3]
	s_cbranch_execnz .LBB0_232

;     __device__ __forceinline__ void operator()(EPI_ARGS) const {
;     ...
;                         if (kv) { const int c = col - seg * 1024; float* dst = nullptr;
;                             if (row >= TP - 512 && row < TP) dst = out + (seg == 1 ? OFF_KP : OFF_VP) + ((size_t)layer * 512 + (row - (TP - 512))) * 1024 + c;
;                             else if (row >= TP && row < MROWS) dst = out + (seg == 1 ? OFF_KS : OFF_VS) + ((size_t)layer * 128 + (row - TP)) * 1024 + c;
;                             if (dst) { *(f32x4*)dst = v0; *(f32x4*)(dst + 4) = v1; } } } }
.LBB0_160:
	global_store_dwordx4 v[132:133], v[22:25], off sc1
	global_store_dwordx4 v[132:133], v[18:21], off offset:16 sc1

; __device__ __forceinline__ unsigned pk2(float lo, float hi) { unsigned r; asm("v_cvt_pk_bf16_f32 %0, %1, %2" : "=v"(r) : "v"(lo), "v"(hi)); return r; }
;     __device__ __forceinline__ void operator()(EPI_ARGS) const {
;     ...
;                 for (int m = 0; m < 4; ++m) { const int row = row0 + ai * 128 + m * 16;
; #pragma unroll
;                     for (int bj = 0; bj < 2; ++bj) { const f32x4 v0 = acc[ai][bj][m][0], v1 = acc[ai][bj][m][1]; const int col = colt + bj * 128;
;                         u32x4 w; w.x = pk2(v0[0], v0[1]); w.y = pk2(v0[2], v0[3]); w.z = pk2(v1[0], v1[1]); w.w = pk2(v1[2], v1[3]);
;                         *(u32x4*)(proj + (size_t)row * NIN + col) = w;
.LBB0_162:
	v_add_u32_e32 v8, 0xb0, v150
	v_mov_b64_e32 v[132:133], s[30:31]
	v_lshlrev_b32_e32 v131, 10, v8
	v_mad_i64_i32 v[132:133], s[2:3], v8, s13, v[132:133]
	v_add_u32_e32 v137, 0xff800000, v131
	v_add_u32_e32 v136, 0xff880000, v131
	v_lshl_add_u64 v[132:133], v[152:153], 1, v[132:133]
	s_and_b64 vcc, exec, s[0:1]
	v_cvt_pk_bf16_f32 v154, v14, v15
	v_cvt_pk_bf16_f32 v155, v16, v17
	v_cvt_pk_bf16_f32 v156, v10, v11
	v_cvt_pk_bf16_f32 v157, v12, v13
	global_store_dwordx4 v[132:133], v[154:157], off sc1
	s_cbranch_vccnz .LBB0_168
	s_and_saveexec_b64 s[2:3], s[40:41]
	s_xor_b64 s[2:3], exec, s[2:3]
	s_cbranch_execnz .LBB0_233
	s_andn2_saveexec_b64 s[2:3], s[2:3]
	s_cbranch_execnz .LBB0_236

;     __device__ __forceinline__ void operator()(EPI_ARGS) const {
;     ...
;                         if (kv) { const int c = col - seg * 1024; float* dst = nullptr;
;                             if (row >= TP - 512 && row < TP) dst = out + (seg == 1 ? OFF_KP : OFF_VP) + ((size_t)layer * 512 + (row - (TP - 512))) * 1024 + c;
;                             else if (row >= TP && row < MROWS) dst = out + (seg == 1 ? OFF_KS : OFF_VS) + ((size_t)layer * 128 + (row - TP)) * 1024 + c;
;                             if (dst) { *(f32x4*)dst = v0; *(f32x4*)(dst + 4) = v1; } } } }
.LBB0_166:
	global_store_dwordx4 v[134:135], v[14:17], off sc1
	global_store_dwordx4 v[134:135], v[10:13], off offset:16 sc1

; __device__ __forceinline__ unsigned pk2(float lo, float hi) { unsigned r; asm("v_cvt_pk_bf16_f32 %0, %1, %2" : "=v"(r) : "v"(lo), "v"(hi)); return r; }
;     __device__ __forceinline__ void operator()(EPI_ARGS) const {
;     ...
;                     for (int bj = 0; bj < 2; ++bj) { const f32x4 v0 = acc[ai][bj][m][0], v1 = acc[ai][bj][m][1]; const int col = colt + bj * 128;
;                         u32x4 w; w.x = pk2(v0[0], v0[1]); w.y = pk2(v0[2], v0[3]); w.z = pk2(v1[0], v1[1]); w.w = pk2(v1[2], v1[3]);
;                         *(u32x4*)(proj + (size_t)row * NIN + col) = w;
.LBB0_168:
	s_and_b64 vcc, exec, s[0:1]
	v_cvt_pk_bf16_f32 v154, v4, v5
	v_cvt_pk_bf16_f32 v155, v6, v7
	v_cvt_pk_bf16_f32 v156, v0, v1
	v_cvt_pk_bf16_f32 v157, v2, v3
	global_store_dwordx4 v[132:133], v[154:157], off offset:256 sc1
	s_cbranch_vccnz .LBB0_174
	s_and_saveexec_b64 s[0:1], s[40:41]
	s_xor_b64 s[0:1], exec, s[0:1]
	s_cbranch_execnz .LBB0_237
	s_andn2_saveexec_b64 s[0:1], s[0:1]
	s_cbranch_execnz .LBB0_240

;     __device__ __forceinline__ void operator()(EPI_ARGS) const {
;     ...
;                         if (kv) { const int c = col - seg * 1024; float* dst = nullptr;
;                             if (row >= TP - 512 && row < TP) dst = out + (seg == 1 ? OFF_KP : OFF_VP) + ((size_t)layer * 512 + (row - (TP - 512))) * 1024 + c;
;                             else if (row >= TP && row < MROWS) dst = out + (seg == 1 ? OFF_KS : OFF_VS) + ((size_t)layer * 128 + (row - TP)) * 1024 + c;
;                             if (dst) { *(f32x4*)dst = v0; *(f32x4*)(dst + 4) = v1; } } } }
.LBB0_172:
	global_store_dwordx4 v[130:131], v[4:7], off sc1
	global_store_dwordx4 v[130:131], v[0:3], off offset:16 sc1

; __device__ __forceinline__ float lbound(float h0, float h1) { return 1.f / (1.f + expf(h0 - h1)); }
; __device__ __forceinline__ float logf_gate(float x, float lb) {
;     const float t = __expf(-fmaxf(x, -80.f));
;     return __logf(lb + (1.f - lb) * __builtin_amdgcn_rcpf(1.f + t));
; }
;     __device__ __forceinline__ void operator()(EPI_ARGS) const {
;     ...
;         } else if (seg == 8) {
; #pragma unroll
;             for (int bj = 0; bj < 2; ++bj) { const int c0 = colt + bj * 128 - 8192;
;                 f32x4 lb0 = (f32x4){0.f, 0.f, 0.f, 0.f}, lb1 = lb0;
;                 if (layer != 0) { const f32x4 a0 = *(const f32x4*)(hlb + c0), a1 = *(const f32x4*)(hlb + c0 + 4), b0 = *(const f32x4*)(hlb + WMIX + c0), b1 = *(const f32x4*)(hlb + WMIX + c0 + 4);
;                     lb0 = (f32x4){lbound(a0[0], b0[0]), lbound(a0[1], b0[1]), lbound(a0[2], b0[2]), lbound(a0[3], b0[3])};
;                     lb1 = (f32x4){lbound(a1[0], b1[0]), lbound(a1[1], b1[1]), lbound(a1[2], b1[2]), lbound(a1[3], b1[3])}; }
; #pragma unroll
;                 for (int ai = 0; ai < 2; ++ai)
; #pragma unroll
;                     for (int m = 0; m < 4; ++m) { const int row = row0 + ai * 128 + m * 16;
;                         const f32x4 v0 = acc[ai][bj][m][0], v1 = acc[ai][bj][m][1];
;                         const f32x4 o0 = (f32x4){logf_gate(v0[0], lb0[0]), logf_gate(v0[1], lb0[1]), logf_gate(v0[2], lb0[2]), logf_gate(v0[3], lb0[3])};
;                         const f32x4 o1 = (f32x4){logf_gate(v1[0], lb1[0]), logf_gate(v1[1], lb1[1]), logf_gate(v1[2], lb1[2]), logf_gate(v1[3], lb1[3])};
;                         float* p = lf_out + (size_t)row * WMIX + c0;
;                         *(f32x4*)p = o0; *(f32x4*)(p + 4) = o1; } }
.LBB0_178:
	v_max_f32_e32 v130, v126, v126
	v_max_f32_e32 v130, 0xc2a00000, v130
	v_mul_f32_e32 v130, 0xbfb8aa3b, v130
	v_exp_f32_e32 v130, v130
	v_sub_f32_e32 v188, 1.0, v171
	v_sub_f32_e32 v187, 1.0, v170
	v_sub_f32_e32 v186, 1.0, v8
	v_add_f32_e32 v130, 1.0, v130
	v_rcp_f32_e32 v130, v130
	v_sub_f32_e32 v185, 1.0, v172
	v_sub_f32_e32 v184, 1.0, v182
	v_sub_f32_e32 v183, 1.0, v180
	v_fma_f32 v130, v130, v188, v171
	v_cmp_gt_f32_e32 vcc, s72, v130
	v_sub_f32_e32 v181, 1.0, v175
	v_sub_f32_e32 v174, 1.0, v173
	v_cndmask_b32_e64 v131, 0, 32, vcc
	v_ldexp_f32 v130, v130, v131
	v_log_f32_e32 v130, v130
	v_readlane_b32 s2, v252, 60
	v_readlane_b32 s3, v252, 61
	v_mul_f32_e32 v131, 0x3f317217, v130
	v_fma_f32 v131, v130, s73, -v131
	v_fmac_f32_e32 v131, 0x3377d1cf, v130
	v_fmac_f32_e32 v131, 0x3f317217, v130
	v_cmp_lt_f32_e64 s[0:1], |v130|, s11
	s_nop 1
	v_cndmask_b32_e64 v130, v130, v131, s[0:1]
	v_cndmask_b32_e32 v131, 0, v243, vcc
	v_sub_f32_e32 v130, v130, v131
	v_max_f32_e32 v131, v127, v127
	v_max_f32_e32 v131, 0xc2a00000, v131
	v_mul_f32_e32 v131, 0xbfb8aa3b, v131
	v_exp_f32_e32 v131, v131
	s_nop 0
	v_add_f32_e32 v131, 1.0, v131
	v_rcp_f32_e32 v131, v131
	s_nop 0
	v_fma_f32 v131, v131, v187, v170
	v_cmp_gt_f32_e32 vcc, s72, v131
	s_nop 1
	v_cndmask_b32_e64 v132, 0, 32, vcc
	v_ldexp_f32 v131, v131, v132
	v_log_f32_e32 v131, v131
	s_nop 0
	v_mul_f32_e32 v132, 0x3f317217, v131
	v_fma_f32 v132, v131, s73, -v132
	v_fmac_f32_e32 v132, 0x3377d1cf, v131
	v_fmac_f32_e32 v132, 0x3f317217, v131
	v_cmp_lt_f32_e64 s[0:1], |v131|, s11
	s_nop 1
	v_cndmask_b32_e64 v131, v131, v132, s[0:1]
	v_cndmask_b32_e32 v132, 0, v243, vcc
	v_sub_f32_e32 v131, v131, v132
	v_max_f32_e32 v132, v128, v128
	v_max_f32_e32 v132, 0xc2a00000, v132
	v_mul_f32_e32 v132, 0xbfb8aa3b, v132
	v_exp_f32_e32 v132, v132
	s_nop 0
	v_add_f32_e32 v132, 1.0, v132
	v_rcp_f32_e32 v132, v132
	s_nop 0
	v_fma_f32 v132, v132, v186, v8
	v_cmp_gt_f32_e32 vcc, s72, v132
	s_nop 1
	v_cndmask_b32_e64 v133, 0, 32, vcc
	v_ldexp_f32 v132, v132, v133
	v_log_f32_e32 v132, v132
	s_nop 0
	v_mul_f32_e32 v133, 0x3f317217, v132
	v_fma_f32 v133, v132, s73, -v133
	v_fmac_f32_e32 v133, 0x3377d1cf, v132
	v_fmac_f32_e32 v133, 0x3f317217, v132
	v_cmp_lt_f32_e64 s[0:1], |v132|, s11
	s_nop 1
	v_cndmask_b32_e64 v132, v132, v133, s[0:1]
	v_cndmask_b32_e32 v133, 0, v243, vcc
	v_sub_f32_e32 v132, v132, v133
	v_max_f32_e32 v133, v129, v129
	v_max_f32_e32 v133, 0xc2a00000, v133
	v_mul_f32_e32 v133, 0xbfb8aa3b, v133
	v_exp_f32_e32 v133, v133
	s_nop 0
	v_add_f32_e32 v133, 1.0, v133
	v_rcp_f32_e32 v133, v133
	s_nop 0
	v_fma_f32 v133, v133, v185, v172
	v_cmp_gt_f32_e32 vcc, s72, v133
	s_nop 1
	v_cndmask_b32_e64 v134, 0, 32, vcc
	v_ldexp_f32 v133, v133, v134
	v_log_f32_e32 v133, v133
	s_nop 0
	v_mul_f32_e32 v134, 0x3f317217, v133
	v_fma_f32 v134, v133, s73, -v134
	v_fmac_f32_e32 v134, 0x3377d1cf, v133
	v_fmac_f32_e32 v134, 0x3f317217, v133
	v_cmp_lt_f32_e64 s[0:1], |v133|, s11
	s_nop 1
	v_cndmask_b32_e64 v133, v133, v134, s[0:1]
	v_cndmask_b32_e32 v134, 0, v243, vcc
	v_sub_f32_e32 v133, v133, v134
	v_max_f32_e32 v134, v122, v122
	v_max_f32_e32 v134, 0xc2a00000, v134
	v_mul_f32_e32 v134, 0xbfb8aa3b, v134
	v_exp_f32_e32 v134, v134
	s_nop 0
	v_add_f32_e32 v134, 1.0, v134
	v_rcp_f32_e32 v134, v134
	s_nop 0
	v_fma_f32 v134, v134, v184, v182
	v_cmp_gt_f32_e32 vcc, s72, v134
	s_nop 1
	v_cndmask_b32_e64 v135, 0, 32, vcc
	v_ldexp_f32 v134, v134, v135
	v_log_f32_e32 v134, v134
	s_nop 0
	v_mul_f32_e32 v135, 0x3f317217, v134
	v_fma_f32 v135, v134, s73, -v135
	v_fmac_f32_e32 v135, 0x3377d1cf, v134
	v_fmac_f32_e32 v135, 0x3f317217, v134
	v_cmp_lt_f32_e64 s[0:1], |v134|, s11
	s_nop 1
	v_cndmask_b32_e64 v134, v134, v135, s[0:1]
	v_cndmask_b32_e32 v135, 0, v243, vcc
	v_sub_f32_e32 v134, v134, v135
	v_max_f32_e32 v135, v123, v123
	v_max_f32_e32 v135, 0xc2a00000, v135
	v_mul_f32_e32 v135, 0xbfb8aa3b, v135
	v_exp_f32_e32 v135, v135
	s_nop 0
	v_add_f32_e32 v135, 1.0, v135
	v_rcp_f32_e32 v135, v135
	s_nop 0
	v_fma_f32 v135, v135, v183, v180
	v_cmp_gt_f32_e32 vcc, s72, v135
	s_nop 1
	v_cndmask_b32_e64 v136, 0, 32, vcc
	v_ldexp_f32 v135, v135, v136
	v_log_f32_e32 v135, v135
	s_nop 0
	v_mul_f32_e32 v136, 0x3f317217, v135
	v_fma_f32 v136, v135, s73, -v136
	v_fmac_f32_e32 v136, 0x3377d1cf, v135
	v_fmac_f32_e32 v136, 0x3f317217, v135
	v_cmp_lt_f32_e64 s[0:1], |v135|, s11
	s_nop 1
	v_cndmask_b32_e64 v135, v135, v136, s[0:1]
	v_cndmask_b32_e32 v136, 0, v243, vcc
	v_sub_f32_e32 v135, v135, v136
	v_max_f32_e32 v136, v124, v124
	v_max_f32_e32 v136, 0xc2a00000, v136
	v_mul_f32_e32 v136, 0xbfb8aa3b, v136
	v_exp_f32_e32 v136, v136
	s_nop 0
	v_add_f32_e32 v136, 1.0, v136
	v_rcp_f32_e32 v136, v136
	s_nop 0
	v_fma_f32 v136, v136, v181, v175
	v_cmp_gt_f32_e32 vcc, s72, v136
	s_nop 1
	v_cndmask_b32_e64 v137, 0, 32, vcc
	v_ldexp_f32 v136, v136, v137
	v_log_f32_e32 v136, v136
	s_nop 0
	v_mul_f32_e32 v137, 0x3f317217, v136
	v_fma_f32 v137, v136, s73, -v137
	v_fmac_f32_e32 v137, 0x3377d1cf, v136
	v_fmac_f32_e32 v137, 0x3f317217, v136
	v_cmp_lt_f32_e64 s[0:1], |v136|, s11
	s_nop 1
	v_cndmask_b32_e64 v136, v136, v137, s[0:1]
	v_cndmask_b32_e32 v137, 0, v243, vcc
	v_sub_f32_e32 v136, v136, v137
	v_max_f32_e32 v137, v125, v125
	v_max_f32_e32 v137, 0xc2a00000, v137
	v_mul_f32_e32 v137, 0xbfb8aa3b, v137
	v_exp_f32_e32 v137, v137
	s_nop 0
	v_add_f32_e32 v137, 1.0, v137
	v_rcp_f32_e32 v137, v137
	s_nop 0
	v_fma_f32 v137, v137, v174, v173
	v_cmp_gt_f32_e32 vcc, s72, v137
	s_nop 1
	v_cndmask_b32_e64 v151, 0, 32, vcc
	v_ldexp_f32 v137, v137, v151
	v_log_f32_e32 v137, v137
	s_nop 0
	v_mul_f32_e32 v151, 0x3f317217, v137
	v_fma_f32 v151, v137, s73, -v151
	v_fmac_f32_e32 v151, 0x3377d1cf, v137
; __device__ __forceinline__ float lbound(float h0, float h1) { return 1.f / (1.f + expf(h0 - h1)); }
; __device__ __forceinline__ float logf_gate(float x, float lb) {
;     const float t = __expf(-fmaxf(x, -80.f));
;     return __logf(lb + (1.f - lb) * __builtin_amdgcn_rcpf(1.f + t));
; }
;     __device__ __forceinline__ void operator()(EPI_ARGS) const {
;     ...
;         } else if (seg == 8) {
; #pragma unroll
;             for (int bj = 0; bj < 2; ++bj) { const int c0 = colt + bj * 128 - 8192;
;                 f32x4 lb0 = (f32x4){0.f, 0.f, 0.f, 0.f}, lb1 = lb0;
;                 if (layer != 0) { const f32x4 a0 = *(const f32x4*)(hlb + c0), a1 = *(const f32x4*)(hlb + c0 + 4), b0 = *(const f32x4*)(hlb + WMIX + c0), b1 = *(const f32x4*)(hlb + WMIX + c0 + 4);
;                     lb0 = (f32x4){lbound(a0[0], b0[0]), lbound(a0[1], b0[1]), lbound(a0[2], b0[2]), lbound(a0[3], b0[3])};
;                     lb1 = (f32x4){lbound(a1[0], b1[0]), lbound(a1[1], b1[1]), lbound(a1[2], b1[2]), lbound(a1[3], b1[3])}; }
; #pragma unroll
;                 for (int ai = 0; ai < 2; ++ai)
; #pragma unroll
;                     for (int m = 0; m < 4; ++m) { const int row = row0 + ai * 128 + m * 16;
;                         const f32x4 v0 = acc[ai][bj][m][0], v1 = acc[ai][bj][m][1];
;                         const f32x4 o0 = (f32x4){logf_gate(v0[0], lb0[0]), logf_gate(v0[1], lb0[1]), logf_gate(v0[2], lb0[2]), logf_gate(v0[3], lb0[3])};
;                         const f32x4 o1 = (f32x4){logf_gate(v1[0], lb1[0]), logf_gate(v1[1], lb1[1]), logf_gate(v1[2], lb1[2]), logf_gate(v1[3], lb1[3])};
;                         float* p = lf_out + (size_t)row * WMIX + c0;
;                         *(f32x4*)p = o0; *(f32x4*)(p + 4) = o1; } }
	v_fmac_f32_e32 v151, 0x3f317217, v137
	v_cmp_lt_f32_e64 s[0:1], |v137|, s11
	s_nop 1
	v_cndmask_b32_e64 v137, v137, v151, s[0:1]
	v_cndmask_b32_e32 v151, 0, v243, vcc
	v_sub_f32_e32 v137, v137, v151
	v_ashrrev_i32_e32 v151, 31, v150
	v_lshlrev_b64 v[154:155], 12, v[150:151]
	v_lshl_add_u64 v[154:155], s[2:3], 0, v[154:155]
	v_lshl_add_u64 v[156:157], v[154:155], 0, v[158:159]
	global_store_dwordx4 v[156:157], v[130:133], off sc1
	global_store_dwordx4 v[156:157], v[134:137], off offset:16 sc1
	v_or_b32_e32 v156, 16, v150
	v_max_f32_e32 v130, v110, v110
	v_max_f32_e32 v130, 0xc2a00000, v130
	v_mul_f32_e32 v130, 0xbfb8aa3b, v130
	v_exp_f32_e32 v130, v130
	v_ashrrev_i32_e32 v157, 31, v156
	v_lshlrev_b64 v[156:157], 12, v[156:157]
	v_lshl_add_u64 v[156:157], s[2:3], 0, v[156:157]
	v_add_f32_e32 v130, 1.0, v130
	v_rcp_f32_e32 v130, v130
	v_lshl_add_u64 v[160:161], v[156:157], 0, v[158:159]
	v_fma_f32 v130, v130, v188, v171
	v_cmp_gt_f32_e32 vcc, s72, v130
	s_nop 1
	v_cndmask_b32_e64 v131, 0, 32, vcc
	v_ldexp_f32 v130, v130, v131
	v_log_f32_e32 v130, v130
	s_nop 0
	v_mul_f32_e32 v131, 0x3f317217, v130
	v_fma_f32 v131, v130, s73, -v131
	v_fmac_f32_e32 v131, 0x3377d1cf, v130
	v_fmac_f32_e32 v131, 0x3f317217, v130
	v_cmp_lt_f32_e64 s[0:1], |v130|, s11
	s_nop 1
	v_cndmask_b32_e64 v130, v130, v131, s[0:1]
	v_cndmask_b32_e32 v131, 0, v243, vcc
	v_sub_f32_e32 v130, v130, v131
	v_max_f32_e32 v131, v111, v111
	v_max_f32_e32 v131, 0xc2a00000, v131
	v_mul_f32_e32 v131, 0xbfb8aa3b, v131
	v_exp_f32_e32 v131, v131
	s_nop 0
	v_add_f32_e32 v131, 1.0, v131
	v_rcp_f32_e32 v131, v131
	s_nop 0
	v_fma_f32 v131, v131, v187, v170
	v_cmp_gt_f32_e32 vcc, s72, v131
	s_nop 1
	v_cndmask_b32_e64 v132, 0, 32, vcc
	v_ldexp_f32 v131, v131, v132
	v_log_f32_e32 v131, v131
	s_nop 0
	v_mul_f32_e32 v132, 0x3f317217, v131
	v_fma_f32 v132, v131, s73, -v132
	v_fmac_f32_e32 v132, 0x3377d1cf, v131
	v_fmac_f32_e32 v132, 0x3f317217, v131
	v_cmp_lt_f32_e64 s[0:1], |v131|, s11
	s_nop 1
	v_cndmask_b32_e64 v131, v131, v132, s[0:1]
	v_cndmask_b32_e32 v132, 0, v243, vcc
	v_sub_f32_e32 v131, v131, v132
	v_max_f32_e32 v132, v112, v112
	v_max_f32_e32 v132, 0xc2a00000, v132
	v_mul_f32_e32 v132, 0xbfb8aa3b, v132
	v_exp_f32_e32 v132, v132
	s_nop 0
	v_add_f32_e32 v132, 1.0, v132
	v_rcp_f32_e32 v132, v132
	s_nop 0
	v_fma_f32 v132, v132, v186, v8
	v_cmp_gt_f32_e32 vcc, s72, v132
	s_nop 1
	v_cndmask_b32_e64 v133, 0, 32, vcc
	v_ldexp_f32 v132, v132, v133
	v_log_f32_e32 v132, v132
	s_nop 0
	v_mul_f32_e32 v133, 0x3f317217, v132
	v_fma_f32 v133, v132, s73, -v133
	v_fmac_f32_e32 v133, 0x3377d1cf, v132
	v_fmac_f32_e32 v133, 0x3f317217, v132
	v_cmp_lt_f32_e64 s[0:1], |v132|, s11
	s_nop 1
	v_cndmask_b32_e64 v132, v132, v133, s[0:1]
	v_cndmask_b32_e32 v133, 0, v243, vcc
	v_sub_f32_e32 v132, v132, v133
	v_max_f32_e32 v133, v113, v113
	v_max_f32_e32 v133, 0xc2a00000, v133
	v_mul_f32_e32 v133, 0xbfb8aa3b, v133
	v_exp_f32_e32 v133, v133
	s_nop 0
	v_add_f32_e32 v133, 1.0, v133
	v_rcp_f32_e32 v133, v133
	s_nop 0
	v_fma_f32 v133, v133, v185, v172
	v_cmp_gt_f32_e32 vcc, s72, v133
	s_nop 1
	v_cndmask_b32_e64 v134, 0, 32, vcc
	v_ldexp_f32 v133, v133, v134
	v_log_f32_e32 v133, v133
	s_nop 0
	v_mul_f32_e32 v134, 0x3f317217, v133
	v_fma_f32 v134, v133, s73, -v134
	v_fmac_f32_e32 v134, 0x3377d1cf, v133
	v_fmac_f32_e32 v134, 0x3f317217, v133
	v_cmp_lt_f32_e64 s[0:1], |v133|, s11
	s_nop 1
	v_cndmask_b32_e64 v133, v133, v134, s[0:1]
	v_cndmask_b32_e32 v134, 0, v243, vcc
	v_sub_f32_e32 v133, v133, v134
	v_max_f32_e32 v134, v106, v106
	v_max_f32_e32 v134, 0xc2a00000, v134
	v_mul_f32_e32 v134, 0xbfb8aa3b, v134
	v_exp_f32_e32 v134, v134
	s_nop 0
	v_add_f32_e32 v134, 1.0, v134
	v_rcp_f32_e32 v134, v134
	s_nop 0
	v_fma_f32 v134, v134, v184, v182
	v_cmp_gt_f32_e32 vcc, s72, v134
	s_nop 1
	v_cndmask_b32_e64 v135, 0, 32, vcc
	v_ldexp_f32 v134, v134, v135
	v_log_f32_e32 v134, v134
	s_nop 0
	v_mul_f32_e32 v135, 0x3f317217, v134
	v_fma_f32 v135, v134, s73, -v135
	v_fmac_f32_e32 v135, 0x3377d1cf, v134
	v_fmac_f32_e32 v135, 0x3f317217, v134
	v_cmp_lt_f32_e64 s[0:1], |v134|, s11
	s_nop 1
	v_cndmask_b32_e64 v134, v134, v135, s[0:1]
	v_cndmask_b32_e32 v135, 0, v243, vcc
	v_sub_f32_e32 v134, v134, v135
	v_max_f32_e32 v135, v107, v107
	v_max_f32_e32 v135, 0xc2a00000, v135
	v_mul_f32_e32 v135, 0xbfb8aa3b, v135
	v_exp_f32_e32 v135, v135
	s_nop 0
	v_add_f32_e32 v135, 1.0, v135
	v_rcp_f32_e32 v135, v135
	s_nop 0
	v_fma_f32 v135, v135, v183, v180
	v_cmp_gt_f32_e32 vcc, s72, v135
	s_nop 1
	v_cndmask_b32_e64 v136, 0, 32, vcc
	v_ldexp_f32 v135, v135, v136
	v_log_f32_e32 v135, v135
	s_nop 0
	v_mul_f32_e32 v136, 0x3f317217, v135
	v_fma_f32 v136, v135, s73, -v136
	v_fmac_f32_e32 v136, 0x3377d1cf, v135
	v_fmac_f32_e32 v136, 0x3f317217, v135
	v_cmp_lt_f32_e64 s[0:1], |v135|, s11
	s_nop 1
	v_cndmask_b32_e64 v135, v135, v136, s[0:1]
	v_cndmask_b32_e32 v136, 0, v243, vcc
	v_sub_f32_e32 v135, v135, v136
	v_max_f32_e32 v136, v108, v108
	v_max_f32_e32 v136, 0xc2a00000, v136
	v_mul_f32_e32 v136, 0xbfb8aa3b, v136
	v_exp_f32_e32 v136, v136
	s_nop 0
	v_add_f32_e32 v136, 1.0, v136
	v_rcp_f32_e32 v136, v136
	s_nop 0
	v_fma_f32 v136, v136, v181, v175
	v_cmp_gt_f32_e32 vcc, s72, v136
	s_nop 1
	v_cndmask_b32_e64 v137, 0, 32, vcc
	v_ldexp_f32 v136, v136, v137
	v_log_f32_e32 v136, v136
	s_nop 0
	v_mul_f32_e32 v137, 0x3f317217, v136
	v_fma_f32 v137, v136, s73, -v137
	v_fmac_f32_e32 v137, 0x3377d1cf, v136
	v_fmac_f32_e32 v137, 0x3f317217, v136
	v_cmp_lt_f32_e64 s[0:1], |v136|, s11
	s_nop 1
	v_cndmask_b32_e64 v136, v136, v137, s[0:1]
	v_cndmask_b32_e32 v137, 0, v243, vcc
	v_sub_f32_e32 v136, v136, v137
	v_max_f32_e32 v137, v109, v109
	v_max_f32_e32 v137, 0xc2a00000, v137
; __device__ __forceinline__ float lbound(float h0, float h1) { return 1.f / (1.f + expf(h0 - h1)); }
; __device__ __forceinline__ float logf_gate(float x, float lb) {
;     const float t = __expf(-fmaxf(x, -80.f));
;     return __logf(lb + (1.f - lb) * __builtin_amdgcn_rcpf(1.f + t));
; }
;     __device__ __forceinline__ void operator()(EPI_ARGS) const {
;     ...
;         } else if (seg == 8) {
; #pragma unroll
;             for (int bj = 0; bj < 2; ++bj) { const int c0 = colt + bj * 128 - 8192;
;                 f32x4 lb0 = (f32x4){0.f, 0.f, 0.f, 0.f}, lb1 = lb0;
;                 if (layer != 0) { const f32x4 a0 = *(const f32x4*)(hlb + c0), a1 = *(const f32x4*)(hlb + c0 + 4), b0 = *(const f32x4*)(hlb + WMIX + c0), b1 = *(const f32x4*)(hlb + WMIX + c0 + 4);
;                     lb0 = (f32x4){lbound(a0[0], b0[0]), lbound(a0[1], b0[1]), lbound(a0[2], b0[2]), lbound(a0[3], b0[3])};
;                     lb1 = (f32x4){lbound(a1[0], b1[0]), lbound(a1[1], b1[1]), lbound(a1[2], b1[2]), lbound(a1[3], b1[3])}; }
; #pragma unroll
;                 for (int ai = 0; ai < 2; ++ai)
; #pragma unroll
;                     for (int m = 0; m < 4; ++m) { const int row = row0 + ai * 128 + m * 16;
;                         const f32x4 v0 = acc[ai][bj][m][0], v1 = acc[ai][bj][m][1];
;                         const f32x4 o0 = (f32x4){logf_gate(v0[0], lb0[0]), logf_gate(v0[1], lb0[1]), logf_gate(v0[2], lb0[2]), logf_gate(v0[3], lb0[3])};
;                         const f32x4 o1 = (f32x4){logf_gate(v1[0], lb1[0]), logf_gate(v1[1], lb1[1]), logf_gate(v1[2], lb1[2]), logf_gate(v1[3], lb1[3])};
;                         float* p = lf_out + (size_t)row * WMIX + c0;
;                         *(f32x4*)p = o0; *(f32x4*)(p + 4) = o1; } }
	v_mul_f32_e32 v137, 0xbfb8aa3b, v137
	v_exp_f32_e32 v137, v137
	s_nop 0
	v_add_f32_e32 v137, 1.0, v137
	v_rcp_f32_e32 v137, v137
	s_nop 0
	v_fma_f32 v137, v137, v174, v173
	v_cmp_gt_f32_e32 vcc, s72, v137
	s_nop 1
	v_cndmask_b32_e64 v151, 0, 32, vcc
	v_ldexp_f32 v137, v137, v151
	v_log_f32_e32 v137, v137
	s_nop 0
	v_mul_f32_e32 v151, 0x3f317217, v137
	v_fma_f32 v151, v137, s73, -v151
	v_fmac_f32_e32 v151, 0x3377d1cf, v137
	v_fmac_f32_e32 v151, 0x3f317217, v137
	v_cmp_lt_f32_e64 s[0:1], |v137|, s11
	s_nop 1
	v_cndmask_b32_e64 v137, v137, v151, s[0:1]
	v_cndmask_b32_e32 v151, 0, v243, vcc
	v_sub_f32_e32 v137, v137, v151
	global_store_dwordx4 v[160:161], v[130:133], off sc1
	global_store_dwordx4 v[160:161], v[134:137], off offset:16 sc1
	v_or_b32_e32 v160, 32, v150
	v_max_f32_e32 v130, v94, v94
	v_max_f32_e32 v130, 0xc2a00000, v130
	v_mul_f32_e32 v130, 0xbfb8aa3b, v130
	v_exp_f32_e32 v130, v130
	v_ashrrev_i32_e32 v161, 31, v160
	v_lshlrev_b64 v[160:161], 12, v[160:161]
	v_lshl_add_u64 v[160:161], s[2:3], 0, v[160:161]
	v_add_f32_e32 v130, 1.0, v130
	v_rcp_f32_e32 v130, v130
	v_lshl_add_u64 v[162:163], v[160:161], 0, v[158:159]
	v_fma_f32 v130, v130, v188, v171
	v_cmp_gt_f32_e32 vcc, s72, v130
	s_nop 1
	v_cndmask_b32_e64 v131, 0, 32, vcc
	v_ldexp_f32 v130, v130, v131
	v_log_f32_e32 v130, v130
	s_nop 0
	v_mul_f32_e32 v131, 0x3f317217, v130
	v_fma_f32 v131, v130, s73, -v131
	v_fmac_f32_e32 v131, 0x3377d1cf, v130
	v_fmac_f32_e32 v131, 0x3f317217, v130
	v_cmp_lt_f32_e64 s[0:1], |v130|, s11
	s_nop 1
	v_cndmask_b32_e64 v130, v130, v131, s[0:1]
	v_cndmask_b32_e32 v131, 0, v243, vcc
	v_sub_f32_e32 v130, v130, v131
	v_max_f32_e32 v131, v95, v95
	v_max_f32_e32 v131, 0xc2a00000, v131
	v_mul_f32_e32 v131, 0xbfb8aa3b, v131
	v_exp_f32_e32 v131, v131
	s_nop 0
	v_add_f32_e32 v131, 1.0, v131
	v_rcp_f32_e32 v131, v131
	s_nop 0
	v_fma_f32 v131, v131, v187, v170
	v_cmp_gt_f32_e32 vcc, s72, v131
	s_nop 1
	v_cndmask_b32_e64 v132, 0, 32, vcc
	v_ldexp_f32 v131, v131, v132
	v_log_f32_e32 v131, v131
	s_nop 0
	v_mul_f32_e32 v132, 0x3f317217, v131
	v_fma_f32 v132, v131, s73, -v132
	v_fmac_f32_e32 v132, 0x3377d1cf, v131
	v_fmac_f32_e32 v132, 0x3f317217, v131
	v_cmp_lt_f32_e64 s[0:1], |v131|, s11
	s_nop 1
	v_cndmask_b32_e64 v131, v131, v132, s[0:1]
	v_cndmask_b32_e32 v132, 0, v243, vcc
	v_sub_f32_e32 v131, v131, v132
	v_max_f32_e32 v132, v96, v96
	v_max_f32_e32 v132, 0xc2a00000, v132
	v_mul_f32_e32 v132, 0xbfb8aa3b, v132
	v_exp_f32_e32 v132, v132
	s_nop 0
	v_add_f32_e32 v132, 1.0, v132
	v_rcp_f32_e32 v132, v132
	s_nop 0
	v_fma_f32 v132, v132, v186, v8
	v_cmp_gt_f32_e32 vcc, s72, v132
	s_nop 1
	v_cndmask_b32_e64 v133, 0, 32, vcc
	v_ldexp_f32 v132, v132, v133
	v_log_f32_e32 v132, v132
	s_nop 0
	v_mul_f32_e32 v133, 0x3f317217, v132
	v_fma_f32 v133, v132, s73, -v133
	v_fmac_f32_e32 v133, 0x3377d1cf, v132
	v_fmac_f32_e32 v133, 0x3f317217, v132
	v_cmp_lt_f32_e64 s[0:1], |v132|, s11
	s_nop 1
	v_cndmask_b32_e64 v132, v132, v133, s[0:1]
	v_cndmask_b32_e32 v133, 0, v243, vcc
	v_sub_f32_e32 v132, v132, v133
	v_max_f32_e32 v133, v97, v97
	v_max_f32_e32 v133, 0xc2a00000, v133
	v_mul_f32_e32 v133, 0xbfb8aa3b, v133
	v_exp_f32_e32 v133, v133
	s_nop 0
	v_add_f32_e32 v133, 1.0, v133
	v_rcp_f32_e32 v133, v133
	s_nop 0
	v_fma_f32 v133, v133, v185, v172
	v_cmp_gt_f32_e32 vcc, s72, v133
	s_nop 1
	v_cndmask_b32_e64 v134, 0, 32, vcc
	v_ldexp_f32 v133, v133, v134
	v_log_f32_e32 v133, v133
	s_nop 0
	v_mul_f32_e32 v134, 0x3f317217, v133
	v_fma_f32 v134, v133, s73, -v134
	v_fmac_f32_e32 v134, 0x3377d1cf, v133
	v_fmac_f32_e32 v134, 0x3f317217, v133
	v_cmp_lt_f32_e64 s[0:1], |v133|, s11
	s_nop 1
	v_cndmask_b32_e64 v133, v133, v134, s[0:1]
	v_cndmask_b32_e32 v134, 0, v243, vcc
	v_sub_f32_e32 v133, v133, v134
	v_max_f32_e32 v134, v90, v90
	v_max_f32_e32 v134, 0xc2a00000, v134
	v_mul_f32_e32 v134, 0xbfb8aa3b, v134
	v_exp_f32_e32 v134, v134
	s_nop 0
	v_add_f32_e32 v134, 1.0, v134
	v_rcp_f32_e32 v134, v134
	s_nop 0
	v_fma_f32 v134, v134, v184, v182
	v_cmp_gt_f32_e32 vcc, s72, v134
	s_nop 1
	v_cndmask_b32_e64 v135, 0, 32, vcc
	v_ldexp_f32 v134, v134, v135
	v_log_f32_e32 v134, v134
	s_nop 0
	v_mul_f32_e32 v135, 0x3f317217, v134
	v_fma_f32 v135, v134, s73, -v135
	v_fmac_f32_e32 v135, 0x3377d1cf, v134
	v_fmac_f32_e32 v135, 0x3f317217, v134
	v_cmp_lt_f32_e64 s[0:1], |v134|, s11
	s_nop 1
	v_cndmask_b32_e64 v134, v134, v135, s[0:1]
	v_cndmask_b32_e32 v135, 0, v243, vcc
	v_sub_f32_e32 v134, v134, v135
	v_max_f32_e32 v135, v91, v91
	v_max_f32_e32 v135, 0xc2a00000, v135
	v_mul_f32_e32 v135, 0xbfb8aa3b, v135
	v_exp_f32_e32 v135, v135
	s_nop 0
	v_add_f32_e32 v135, 1.0, v135
	v_rcp_f32_e32 v135, v135
	s_nop 0
	v_fma_f32 v135, v135, v183, v180
	v_cmp_gt_f32_e32 vcc, s72, v135
	s_nop 1
	v_cndmask_b32_e64 v136, 0, 32, vcc
	v_ldexp_f32 v135, v135, v136
	v_log_f32_e32 v135, v135
	s_nop 0
	v_mul_f32_e32 v136, 0x3f317217, v135
	v_fma_f32 v136, v135, s73, -v136
	v_fmac_f32_e32 v136, 0x3377d1cf, v135
	v_fmac_f32_e32 v136, 0x3f317217, v135
	v_cmp_lt_f32_e64 s[0:1], |v135|, s11
	s_nop 1
	v_cndmask_b32_e64 v135, v135, v136, s[0:1]
	v_cndmask_b32_e32 v136, 0, v243, vcc
	v_sub_f32_e32 v135, v135, v136
	v_max_f32_e32 v136, v92, v92
	v_max_f32_e32 v136, 0xc2a00000, v136
	v_mul_f32_e32 v136, 0xbfb8aa3b, v136
	v_exp_f32_e32 v136, v136
	s_nop 0
	v_add_f32_e32 v136, 1.0, v136
	v_rcp_f32_e32 v136, v136
	s_nop 0
	v_fma_f32 v136, v136, v181, v175
	v_cmp_gt_f32_e32 vcc, s72, v136
	s_nop 1
	v_cndmask_b32_e64 v137, 0, 32, vcc
	v_ldexp_f32 v136, v136, v137
	v_log_f32_e32 v136, v136
	s_nop 0
	v_mul_f32_e32 v137, 0x3f317217, v136
	v_fma_f32 v137, v136, s73, -v137
	v_fmac_f32_e32 v137, 0x3377d1cf, v136
	v_fmac_f32_e32 v137, 0x3f317217, v136
; __device__ __forceinline__ float lbound(float h0, float h1) { return 1.f / (1.f + expf(h0 - h1)); }
; __device__ __forceinline__ float logf_gate(float x, float lb) {
;     const float t = __expf(-fmaxf(x, -80.f));
;     return __logf(lb + (1.f - lb) * __builtin_amdgcn_rcpf(1.f + t));
; }
;     __device__ __forceinline__ void operator()(EPI_ARGS) const {
;     ...
;         } else if (seg == 8) {
; #pragma unroll
;             for (int bj = 0; bj < 2; ++bj) { const int c0 = colt + bj * 128 - 8192;
;                 f32x4 lb0 = (f32x4){0.f, 0.f, 0.f, 0.f}, lb1 = lb0;
;                 if (layer != 0) { const f32x4 a0 = *(const f32x4*)(hlb + c0), a1 = *(const f32x4*)(hlb + c0 + 4), b0 = *(const f32x4*)(hlb + WMIX + c0), b1 = *(const f32x4*)(hlb + WMIX + c0 + 4);
;                     lb0 = (f32x4){lbound(a0[0], b0[0]), lbound(a0[1], b0[1]), lbound(a0[2], b0[2]), lbound(a0[3], b0[3])};
;                     lb1 = (f32x4){lbound(a1[0], b1[0]), lbound(a1[1], b1[1]), lbound(a1[2], b1[2]), lbound(a1[3], b1[3])}; }
; #pragma unroll
;                 for (int ai = 0; ai < 2; ++ai)
; #pragma unroll
;                     for (int m = 0; m < 4; ++m) { const int row = row0 + ai * 128 + m * 16;
;                         const f32x4 v0 = acc[ai][bj][m][0], v1 = acc[ai][bj][m][1];
;                         const f32x4 o0 = (f32x4){logf_gate(v0[0], lb0[0]), logf_gate(v0[1], lb0[1]), logf_gate(v0[2], lb0[2]), logf_gate(v0[3], lb0[3])};
;                         const f32x4 o1 = (f32x4){logf_gate(v1[0], lb1[0]), logf_gate(v1[1], lb1[1]), logf_gate(v1[2], lb1[2]), logf_gate(v1[3], lb1[3])};
;                         float* p = lf_out + (size_t)row * WMIX + c0;
;                         *(f32x4*)p = o0; *(f32x4*)(p + 4) = o1; } }
	v_cmp_lt_f32_e64 s[0:1], |v136|, s11
	s_nop 1
	v_cndmask_b32_e64 v136, v136, v137, s[0:1]
	v_cndmask_b32_e32 v137, 0, v243, vcc
	v_sub_f32_e32 v136, v136, v137
	v_max_f32_e32 v137, v93, v93
	v_max_f32_e32 v137, 0xc2a00000, v137
	v_mul_f32_e32 v137, 0xbfb8aa3b, v137
	v_exp_f32_e32 v137, v137
	s_nop 0
	v_add_f32_e32 v137, 1.0, v137
	v_rcp_f32_e32 v137, v137
	s_nop 0
	v_fma_f32 v137, v137, v174, v173
	v_cmp_gt_f32_e32 vcc, s72, v137
	s_nop 1
	v_cndmask_b32_e64 v151, 0, 32, vcc
	v_ldexp_f32 v137, v137, v151
	v_log_f32_e32 v137, v137
	s_nop 0
	v_mul_f32_e32 v151, 0x3f317217, v137
	v_fma_f32 v151, v137, s73, -v151
	v_fmac_f32_e32 v151, 0x3377d1cf, v137
	v_fmac_f32_e32 v151, 0x3f317217, v137
	v_cmp_lt_f32_e64 s[0:1], |v137|, s11
	s_nop 1
	v_cndmask_b32_e64 v137, v137, v151, s[0:1]
	v_cndmask_b32_e32 v151, 0, v243, vcc
	v_sub_f32_e32 v137, v137, v151
	global_store_dwordx4 v[162:163], v[130:133], off sc1
	global_store_dwordx4 v[162:163], v[134:137], off offset:16 sc1
	v_or_b32_e32 v162, 48, v150
	v_max_f32_e32 v130, v78, v78
	v_max_f32_e32 v130, 0xc2a00000, v130
	v_mul_f32_e32 v130, 0xbfb8aa3b, v130
	v_exp_f32_e32 v130, v130
	v_ashrrev_i32_e32 v163, 31, v162
	v_lshlrev_b64 v[162:163], 12, v[162:163]
	v_lshl_add_u64 v[162:163], s[2:3], 0, v[162:163]
	v_add_f32_e32 v130, 1.0, v130
	v_rcp_f32_e32 v130, v130
	v_lshl_add_u64 v[164:165], v[162:163], 0, v[158:159]
	v_fma_f32 v130, v130, v188, v171
	v_cmp_gt_f32_e32 vcc, s72, v130
	s_nop 1
	v_cndmask_b32_e64 v131, 0, 32, vcc
	v_ldexp_f32 v130, v130, v131
	v_log_f32_e32 v130, v130
	s_nop 0
	v_mul_f32_e32 v131, 0x3f317217, v130
	v_fma_f32 v131, v130, s73, -v131
	v_fmac_f32_e32 v131, 0x3377d1cf, v130
	v_fmac_f32_e32 v131, 0x3f317217, v130
	v_cmp_lt_f32_e64 s[0:1], |v130|, s11
	s_nop 1
	v_cndmask_b32_e64 v130, v130, v131, s[0:1]
	v_cndmask_b32_e32 v131, 0, v243, vcc
	v_sub_f32_e32 v130, v130, v131
	v_max_f32_e32 v131, v79, v79
	v_max_f32_e32 v131, 0xc2a00000, v131
	v_mul_f32_e32 v131, 0xbfb8aa3b, v131
	v_exp_f32_e32 v131, v131
	s_nop 0
	v_add_f32_e32 v131, 1.0, v131
	v_rcp_f32_e32 v131, v131
	s_nop 0
	v_fma_f32 v131, v131, v187, v170
	v_cmp_gt_f32_e32 vcc, s72, v131
	s_nop 1
	v_cndmask_b32_e64 v132, 0, 32, vcc
	v_ldexp_f32 v131, v131, v132
	v_log_f32_e32 v131, v131
	s_nop 0
	v_mul_f32_e32 v132, 0x3f317217, v131
	v_fma_f32 v132, v131, s73, -v132
	v_fmac_f32_e32 v132, 0x3377d1cf, v131
	v_fmac_f32_e32 v132, 0x3f317217, v131
	v_cmp_lt_f32_e64 s[0:1], |v131|, s11
	s_nop 1
	v_cndmask_b32_e64 v131, v131, v132, s[0:1]
	v_cndmask_b32_e32 v132, 0, v243, vcc
	v_sub_f32_e32 v131, v131, v132
	v_max_f32_e32 v132, v80, v80
	v_max_f32_e32 v132, 0xc2a00000, v132
	v_mul_f32_e32 v132, 0xbfb8aa3b, v132
	v_exp_f32_e32 v132, v132
	s_nop 0
	v_add_f32_e32 v132, 1.0, v132
	v_rcp_f32_e32 v132, v132
	s_nop 0
	v_fma_f32 v132, v132, v186, v8
	v_cmp_gt_f32_e32 vcc, s72, v132
	s_nop 1
	v_cndmask_b32_e64 v133, 0, 32, vcc
	v_ldexp_f32 v132, v132, v133
	v_log_f32_e32 v132, v132
	s_nop 0
	v_mul_f32_e32 v133, 0x3f317217, v132
	v_fma_f32 v133, v132, s73, -v133
	v_fmac_f32_e32 v133, 0x3377d1cf, v132
	v_fmac_f32_e32 v133, 0x3f317217, v132
	v_cmp_lt_f32_e64 s[0:1], |v132|, s11
	s_nop 1
	v_cndmask_b32_e64 v132, v132, v133, s[0:1]
	v_cndmask_b32_e32 v133, 0, v243, vcc
	v_sub_f32_e32 v132, v132, v133
	v_max_f32_e32 v133, v81, v81
	v_max_f32_e32 v133, 0xc2a00000, v133
	v_mul_f32_e32 v133, 0xbfb8aa3b, v133
	v_exp_f32_e32 v133, v133
	s_nop 0
	v_add_f32_e32 v133, 1.0, v133
	v_rcp_f32_e32 v133, v133
	s_nop 0
	v_fma_f32 v133, v133, v185, v172
	v_cmp_gt_f32_e32 vcc, s72, v133
	s_nop 1
	v_cndmask_b32_e64 v134, 0, 32, vcc
	v_ldexp_f32 v133, v133, v134
	v_log_f32_e32 v133, v133
	s_nop 0
	v_mul_f32_e32 v134, 0x3f317217, v133
	v_fma_f32 v134, v133, s73, -v134
	v_fmac_f32_e32 v134, 0x3377d1cf, v133
	v_fmac_f32_e32 v134, 0x3f317217, v133
	v_cmp_lt_f32_e64 s[0:1], |v133|, s11
	s_nop 1
	v_cndmask_b32_e64 v133, v133, v134, s[0:1]
	v_cndmask_b32_e32 v134, 0, v243, vcc
	v_sub_f32_e32 v133, v133, v134
	v_max_f32_e32 v134, v74, v74
	v_max_f32_e32 v134, 0xc2a00000, v134
	v_mul_f32_e32 v134, 0xbfb8aa3b, v134
	v_exp_f32_e32 v134, v134
	s_nop 0
	v_add_f32_e32 v134, 1.0, v134
	v_rcp_f32_e32 v134, v134
	s_nop 0
	v_fma_f32 v134, v134, v184, v182
	v_cmp_gt_f32_e32 vcc, s72, v134
	s_nop 1
	v_cndmask_b32_e64 v135, 0, 32, vcc
	v_ldexp_f32 v134, v134, v135
	v_log_f32_e32 v134, v134
	s_nop 0
	v_mul_f32_e32 v135, 0x3f317217, v134
	v_fma_f32 v135, v134, s73, -v135
	v_fmac_f32_e32 v135, 0x3377d1cf, v134
	v_fmac_f32_e32 v135, 0x3f317217, v134
	v_cmp_lt_f32_e64 s[0:1], |v134|, s11
	s_nop 1
	v_cndmask_b32_e64 v134, v134, v135, s[0:1]
	v_cndmask_b32_e32 v135, 0, v243, vcc
	v_sub_f32_e32 v134, v134, v135
	v_max_f32_e32 v135, v75, v75
	v_max_f32_e32 v135, 0xc2a00000, v135
	v_mul_f32_e32 v135, 0xbfb8aa3b, v135
	v_exp_f32_e32 v135, v135
	s_nop 0
	v_add_f32_e32 v135, 1.0, v135
	v_rcp_f32_e32 v135, v135
	s_nop 0
	v_fma_f32 v135, v135, v183, v180
	v_cmp_gt_f32_e32 vcc, s72, v135
	s_nop 1
	v_cndmask_b32_e64 v136, 0, 32, vcc
	v_ldexp_f32 v135, v135, v136
	v_log_f32_e32 v135, v135
	s_nop 0
	v_mul_f32_e32 v136, 0x3f317217, v135
	v_fma_f32 v136, v135, s73, -v136
	v_fmac_f32_e32 v136, 0x3377d1cf, v135
	v_fmac_f32_e32 v136, 0x3f317217, v135
	v_cmp_lt_f32_e64 s[0:1], |v135|, s11
	s_nop 1
	v_cndmask_b32_e64 v135, v135, v136, s[0:1]
	v_cndmask_b32_e32 v136, 0, v243, vcc
	v_sub_f32_e32 v135, v135, v136
	v_max_f32_e32 v136, v76, v76
	v_max_f32_e32 v136, 0xc2a00000, v136
	v_mul_f32_e32 v136, 0xbfb8aa3b, v136
	v_exp_f32_e32 v136, v136
	s_nop 0
	v_add_f32_e32 v136, 1.0, v136
	v_rcp_f32_e32 v136, v136
	s_nop 0
	v_fma_f32 v136, v136, v181, v175
	v_cmp_gt_f32_e32 vcc, s72, v136
	s_nop 1
	v_cndmask_b32_e64 v137, 0, 32, vcc
; __device__ __forceinline__ float lbound(float h0, float h1) { return 1.f / (1.f + expf(h0 - h1)); }
; __device__ __forceinline__ float logf_gate(float x, float lb) {
;     const float t = __expf(-fmaxf(x, -80.f));
;     return __logf(lb + (1.f - lb) * __builtin_amdgcn_rcpf(1.f + t));
; }
;     __device__ __forceinline__ void operator()(EPI_ARGS) const {
;     ...
;         } else if (seg == 8) {
; #pragma unroll
;             for (int bj = 0; bj < 2; ++bj) { const int c0 = colt + bj * 128 - 8192;
;                 f32x4 lb0 = (f32x4){0.f, 0.f, 0.f, 0.f}, lb1 = lb0;
;                 if (layer != 0) { const f32x4 a0 = *(const f32x4*)(hlb + c0), a1 = *(const f32x4*)(hlb + c0 + 4), b0 = *(const f32x4*)(hlb + WMIX + c0), b1 = *(const f32x4*)(hlb + WMIX + c0 + 4);
;                     lb0 = (f32x4){lbound(a0[0], b0[0]), lbound(a0[1], b0[1]), lbound(a0[2], b0[2]), lbound(a0[3], b0[3])};
;                     lb1 = (f32x4){lbound(a1[0], b1[0]), lbound(a1[1], b1[1]), lbound(a1[2], b1[2]), lbound(a1[3], b1[3])}; }
; #pragma unroll
;                 for (int ai = 0; ai < 2; ++ai)
; #pragma unroll
;                     for (int m = 0; m < 4; ++m) { const int row = row0 + ai * 128 + m * 16;
;                         const f32x4 v0 = acc[ai][bj][m][0], v1 = acc[ai][bj][m][1];
;                         const f32x4 o0 = (f32x4){logf_gate(v0[0], lb0[0]), logf_gate(v0[1], lb0[1]), logf_gate(v0[2], lb0[2]), logf_gate(v0[3], lb0[3])};
;                         const f32x4 o1 = (f32x4){logf_gate(v1[0], lb1[0]), logf_gate(v1[1], lb1[1]), logf_gate(v1[2], lb1[2]), logf_gate(v1[3], lb1[3])};
;                         float* p = lf_out + (size_t)row * WMIX + c0;
;                         *(f32x4*)p = o0; *(f32x4*)(p + 4) = o1; } }
	v_ldexp_f32 v136, v136, v137
	v_log_f32_e32 v136, v136
	s_nop 0
	v_mul_f32_e32 v137, 0x3f317217, v136
	v_fma_f32 v137, v136, s73, -v137
	v_fmac_f32_e32 v137, 0x3377d1cf, v136
	v_fmac_f32_e32 v137, 0x3f317217, v136
	v_cmp_lt_f32_e64 s[0:1], |v136|, s11
	s_nop 1
	v_cndmask_b32_e64 v136, v136, v137, s[0:1]
	v_cndmask_b32_e32 v137, 0, v243, vcc
	v_sub_f32_e32 v136, v136, v137
	v_max_f32_e32 v137, v77, v77
	v_max_f32_e32 v137, 0xc2a00000, v137
	v_mul_f32_e32 v137, 0xbfb8aa3b, v137
	v_exp_f32_e32 v137, v137
	s_nop 0
	v_add_f32_e32 v137, 1.0, v137
	v_rcp_f32_e32 v137, v137
	s_nop 0
	v_fma_f32 v137, v137, v174, v173
	v_cmp_gt_f32_e32 vcc, s72, v137
	s_nop 1
	v_cndmask_b32_e64 v151, 0, 32, vcc
	v_ldexp_f32 v137, v137, v151
	v_log_f32_e32 v137, v137
	s_nop 0
	v_mul_f32_e32 v151, 0x3f317217, v137
	v_fma_f32 v151, v137, s73, -v151
	v_fmac_f32_e32 v151, 0x3377d1cf, v137
	v_fmac_f32_e32 v151, 0x3f317217, v137
	v_cmp_lt_f32_e64 s[0:1], |v137|, s11
	s_nop 1
	v_cndmask_b32_e64 v137, v137, v151, s[0:1]
	v_cndmask_b32_e32 v151, 0, v243, vcc
	v_sub_f32_e32 v137, v137, v151
	global_store_dwordx4 v[164:165], v[130:133], off sc1
	global_store_dwordx4 v[164:165], v[134:137], off offset:16 sc1
	s_nop 0
	v_max_f32_e32 v130, v62, v62
	v_max_f32_e32 v130, 0xc2a00000, v130
	v_mul_f32_e32 v130, 0xbfb8aa3b, v130
	v_exp_f32_e32 v130, v130
	s_nop 0
	v_add_f32_e32 v130, 1.0, v130
	v_rcp_f32_e32 v130, v130
	s_nop 0
	v_fma_f32 v130, v130, v188, v171
	v_cmp_gt_f32_e32 vcc, s72, v130
	s_nop 1
	v_cndmask_b32_e64 v131, 0, 32, vcc
	v_ldexp_f32 v130, v130, v131
	v_log_f32_e32 v130, v130
	s_nop 0
	v_mul_f32_e32 v131, 0x3f317217, v130
	v_fma_f32 v131, v130, s73, -v131
	v_fmac_f32_e32 v131, 0x3377d1cf, v130
	v_fmac_f32_e32 v131, 0x3f317217, v130
	v_cmp_lt_f32_e64 s[0:1], |v130|, s11
	s_nop 1
	v_cndmask_b32_e64 v130, v130, v131, s[0:1]
	v_cndmask_b32_e32 v131, 0, v243, vcc
	v_sub_f32_e32 v130, v130, v131
	v_max_f32_e32 v131, v63, v63
	v_max_f32_e32 v131, 0xc2a00000, v131
	v_mul_f32_e32 v131, 0xbfb8aa3b, v131
	v_exp_f32_e32 v131, v131
	s_nop 0
	v_add_f32_e32 v131, 1.0, v131
	v_rcp_f32_e32 v131, v131
	s_nop 0
	v_fma_f32 v131, v131, v187, v170
	v_cmp_gt_f32_e32 vcc, s72, v131
	s_nop 1
	v_cndmask_b32_e64 v132, 0, 32, vcc
	v_ldexp_f32 v131, v131, v132
	v_log_f32_e32 v131, v131
	s_nop 0
	v_mul_f32_e32 v132, 0x3f317217, v131
	v_fma_f32 v132, v131, s73, -v132
	v_fmac_f32_e32 v132, 0x3377d1cf, v131
	v_fmac_f32_e32 v132, 0x3f317217, v131
	v_cmp_lt_f32_e64 s[0:1], |v131|, s11
	s_nop 1
	v_cndmask_b32_e64 v131, v131, v132, s[0:1]
	v_cndmask_b32_e32 v132, 0, v243, vcc
	v_sub_f32_e32 v131, v131, v132
	v_max_f32_e32 v132, v64, v64
	v_max_f32_e32 v132, 0xc2a00000, v132
	v_mul_f32_e32 v132, 0xbfb8aa3b, v132
	v_exp_f32_e32 v132, v132
	s_nop 0
	v_add_f32_e32 v132, 1.0, v132
	v_rcp_f32_e32 v132, v132
	s_nop 0
	v_fma_f32 v132, v132, v186, v8
	v_cmp_gt_f32_e32 vcc, s72, v132
	s_nop 1
	v_cndmask_b32_e64 v133, 0, 32, vcc
	v_ldexp_f32 v132, v132, v133
	v_log_f32_e32 v132, v132
	s_nop 0
	v_mul_f32_e32 v133, 0x3f317217, v132
	v_fma_f32 v133, v132, s73, -v133
	v_fmac_f32_e32 v133, 0x3377d1cf, v132
	v_fmac_f32_e32 v133, 0x3f317217, v132
	v_cmp_lt_f32_e64 s[0:1], |v132|, s11
	s_nop 1
	v_cndmask_b32_e64 v132, v132, v133, s[0:1]
	v_cndmask_b32_e32 v133, 0, v243, vcc
	v_sub_f32_e32 v132, v132, v133
	v_max_f32_e32 v133, v65, v65
	v_max_f32_e32 v133, 0xc2a00000, v133
	v_mul_f32_e32 v133, 0xbfb8aa3b, v133
	v_exp_f32_e32 v133, v133
	s_nop 0
	v_add_f32_e32 v133, 1.0, v133
	v_rcp_f32_e32 v133, v133
	s_nop 0
	v_fma_f32 v133, v133, v185, v172
	v_cmp_gt_f32_e32 vcc, s72, v133
	s_nop 1
	v_cndmask_b32_e64 v134, 0, 32, vcc
	v_ldexp_f32 v133, v133, v134
	v_log_f32_e32 v133, v133
	s_nop 0
	v_mul_f32_e32 v134, 0x3f317217, v133
	v_fma_f32 v134, v133, s73, -v134
	v_fmac_f32_e32 v134, 0x3377d1cf, v133
	v_fmac_f32_e32 v134, 0x3f317217, v133
	v_cmp_lt_f32_e64 s[0:1], |v133|, s11
	s_nop 1
	v_cndmask_b32_e64 v133, v133, v134, s[0:1]
	v_cndmask_b32_e32 v134, 0, v243, vcc
	v_sub_f32_e32 v133, v133, v134
	v_max_f32_e32 v134, v58, v58
	v_max_f32_e32 v134, 0xc2a00000, v134
	v_mul_f32_e32 v134, 0xbfb8aa3b, v134
	v_exp_f32_e32 v134, v134
	s_nop 0
	v_add_f32_e32 v134, 1.0, v134
	v_rcp_f32_e32 v134, v134
	s_nop 0
	v_fma_f32 v134, v134, v184, v182
	v_cmp_gt_f32_e32 vcc, s72, v134
	s_nop 1
	v_cndmask_b32_e64 v135, 0, 32, vcc
	v_ldexp_f32 v134, v134, v135
	v_log_f32_e32 v134, v134
	s_nop 0
	v_mul_f32_e32 v135, 0x3f317217, v134
	v_fma_f32 v135, v134, s73, -v135
	v_fmac_f32_e32 v135, 0x3377d1cf, v134
	v_fmac_f32_e32 v135, 0x3f317217, v134
	v_cmp_lt_f32_e64 s[0:1], |v134|, s11
	s_nop 1
	v_cndmask_b32_e64 v134, v134, v135, s[0:1]
	v_cndmask_b32_e32 v135, 0, v243, vcc
	v_sub_f32_e32 v134, v134, v135
	v_max_f32_e32 v135, v59, v59
	v_max_f32_e32 v135, 0xc2a00000, v135
	v_mul_f32_e32 v135, 0xbfb8aa3b, v135
	v_exp_f32_e32 v135, v135
	s_nop 0
	v_add_f32_e32 v135, 1.0, v135
	v_rcp_f32_e32 v135, v135
	s_nop 0
	v_fma_f32 v135, v135, v183, v180
	v_cmp_gt_f32_e32 vcc, s72, v135
	s_nop 1
	v_cndmask_b32_e64 v136, 0, 32, vcc
	v_ldexp_f32 v135, v135, v136
	v_log_f32_e32 v135, v135
	s_nop 0
	v_mul_f32_e32 v136, 0x3f317217, v135
	v_fma_f32 v136, v135, s73, -v136
	v_fmac_f32_e32 v136, 0x3377d1cf, v135
	v_fmac_f32_e32 v136, 0x3f317217, v135
	v_cmp_lt_f32_e64 s[0:1], |v135|, s11
	s_nop 1
	v_cndmask_b32_e64 v135, v135, v136, s[0:1]
	v_cndmask_b32_e32 v136, 0, v243, vcc
	v_sub_f32_e32 v135, v135, v136
	v_max_f32_e32 v136, v60, v60
	v_max_f32_e32 v136, 0xc2a00000, v136
	v_mul_f32_e32 v136, 0xbfb8aa3b, v136
	v_exp_f32_e32 v136, v136
	s_nop 0
	v_add_f32_e32 v136, 1.0, v136
	v_rcp_f32_e32 v136, v136
	s_nop 0
	v_fma_f32 v136, v136, v181, v175
	v_cmp_gt_f32_e32 vcc, s72, v136
; __device__ __forceinline__ float lbound(float h0, float h1) { return 1.f / (1.f + expf(h0 - h1)); }
; __device__ __forceinline__ float logf_gate(float x, float lb) {
;     const float t = __expf(-fmaxf(x, -80.f));
;     return __logf(lb + (1.f - lb) * __builtin_amdgcn_rcpf(1.f + t));
; }
;     __device__ __forceinline__ void operator()(EPI_ARGS) const {
;     ...
;         } else if (seg == 8) {
; #pragma unroll
;             for (int bj = 0; bj < 2; ++bj) { const int c0 = colt + bj * 128 - 8192;
;                 f32x4 lb0 = (f32x4){0.f, 0.f, 0.f, 0.f}, lb1 = lb0;
;                 if (layer != 0) { const f32x4 a0 = *(const f32x4*)(hlb + c0), a1 = *(const f32x4*)(hlb + c0 + 4), b0 = *(const f32x4*)(hlb + WMIX + c0), b1 = *(const f32x4*)(hlb + WMIX + c0 + 4);
;                     lb0 = (f32x4){lbound(a0[0], b0[0]), lbound(a0[1], b0[1]), lbound(a0[2], b0[2]), lbound(a0[3], b0[3])};
;                     lb1 = (f32x4){lbound(a1[0], b1[0]), lbound(a1[1], b1[1]), lbound(a1[2], b1[2]), lbound(a1[3], b1[3])}; }
; #pragma unroll
;                 for (int ai = 0; ai < 2; ++ai)
; #pragma unroll
;                     for (int m = 0; m < 4; ++m) { const int row = row0 + ai * 128 + m * 16;
;                         const f32x4 v0 = acc[ai][bj][m][0], v1 = acc[ai][bj][m][1];
;                         const f32x4 o0 = (f32x4){logf_gate(v0[0], lb0[0]), logf_gate(v0[1], lb0[1]), logf_gate(v0[2], lb0[2]), logf_gate(v0[3], lb0[3])};
;                         const f32x4 o1 = (f32x4){logf_gate(v1[0], lb1[0]), logf_gate(v1[1], lb1[1]), logf_gate(v1[2], lb1[2]), logf_gate(v1[3], lb1[3])};
;                         float* p = lf_out + (size_t)row * WMIX + c0;
;                         *(f32x4*)p = o0; *(f32x4*)(p + 4) = o1; } }
	s_nop 1
	v_cndmask_b32_e64 v137, 0, 32, vcc
	v_ldexp_f32 v136, v136, v137
	v_log_f32_e32 v136, v136
	s_nop 0
	v_mul_f32_e32 v137, 0x3f317217, v136
	v_fma_f32 v137, v136, s73, -v137
	v_fmac_f32_e32 v137, 0x3377d1cf, v136
	v_fmac_f32_e32 v137, 0x3f317217, v136
	v_cmp_lt_f32_e64 s[0:1], |v136|, s11
	s_nop 1
	v_cndmask_b32_e64 v136, v136, v137, s[0:1]
	v_cndmask_b32_e32 v137, 0, v243, vcc
	v_sub_f32_e32 v136, v136, v137
	v_max_f32_e32 v137, v61, v61
	v_max_f32_e32 v137, 0xc2a00000, v137
	v_mul_f32_e32 v137, 0xbfb8aa3b, v137
	v_exp_f32_e32 v137, v137
	s_nop 0
	v_add_f32_e32 v137, 1.0, v137
	v_rcp_f32_e32 v137, v137
	s_nop 0
	v_fma_f32 v137, v137, v174, v173
	v_cmp_gt_f32_e32 vcc, s72, v137
	s_nop 1
	v_cndmask_b32_e64 v151, 0, 32, vcc
	v_ldexp_f32 v137, v137, v151
	v_log_f32_e32 v137, v137
	s_nop 0
	v_mul_f32_e32 v151, 0x3f317217, v137
	v_fma_f32 v151, v137, s73, -v151
	v_fmac_f32_e32 v151, 0x3377d1cf, v137
	v_fmac_f32_e32 v151, 0x3f317217, v137
	v_cmp_lt_f32_e64 s[0:1], |v137|, s11
	s_nop 1
	v_cndmask_b32_e64 v137, v137, v151, s[0:1]
	s_mov_b64 s[0:1], 0x80000
	v_lshl_add_u64 v[164:165], v[154:155], 0, s[0:1]
	v_cndmask_b32_e32 v151, 0, v243, vcc
	v_lshl_add_u64 v[166:167], v[164:165], 0, v[158:159]
	v_sub_f32_e32 v137, v137, v151
	global_store_dwordx4 v[166:167], v[130:133], off sc1
	global_store_dwordx4 v[166:167], v[134:137], off offset:16 sc1
	s_nop 0
	v_max_f32_e32 v130, v46, v46
	v_max_f32_e32 v130, 0xc2a00000, v130
	v_mul_f32_e32 v130, 0xbfb8aa3b, v130
	v_exp_f32_e32 v130, v130
	s_nop 0
	v_add_f32_e32 v130, 1.0, v130
	v_rcp_f32_e32 v130, v130
	s_nop 0
	v_fma_f32 v130, v130, v188, v171
	v_cmp_gt_f32_e32 vcc, s72, v130
	s_nop 1
	v_cndmask_b32_e64 v131, 0, 32, vcc
	v_ldexp_f32 v130, v130, v131
	v_log_f32_e32 v130, v130
	s_nop 0
	v_mul_f32_e32 v131, 0x3f317217, v130
	v_fma_f32 v131, v130, s73, -v131
	v_fmac_f32_e32 v131, 0x3377d1cf, v130
	v_fmac_f32_e32 v131, 0x3f317217, v130
	v_cmp_lt_f32_e64 s[0:1], |v130|, s11
	s_nop 1
	v_cndmask_b32_e64 v130, v130, v131, s[0:1]
	v_cndmask_b32_e32 v131, 0, v243, vcc
	v_sub_f32_e32 v130, v130, v131
	v_max_f32_e32 v131, v47, v47
	v_max_f32_e32 v131, 0xc2a00000, v131
	v_mul_f32_e32 v131, 0xbfb8aa3b, v131
	v_exp_f32_e32 v131, v131
	s_nop 0
	v_add_f32_e32 v131, 1.0, v131
	v_rcp_f32_e32 v131, v131
	s_nop 0
	v_fma_f32 v131, v131, v187, v170
	v_cmp_gt_f32_e32 vcc, s72, v131
	s_nop 1
	v_cndmask_b32_e64 v132, 0, 32, vcc
	v_ldexp_f32 v131, v131, v132
	v_log_f32_e32 v131, v131
	s_nop 0
	v_mul_f32_e32 v132, 0x3f317217, v131
	v_fma_f32 v132, v131, s73, -v132
	v_fmac_f32_e32 v132, 0x3377d1cf, v131
	v_fmac_f32_e32 v132, 0x3f317217, v131
	v_cmp_lt_f32_e64 s[0:1], |v131|, s11
	s_nop 1
	v_cndmask_b32_e64 v131, v131, v132, s[0:1]
	v_cndmask_b32_e32 v132, 0, v243, vcc
	v_sub_f32_e32 v131, v131, v132
	v_max_f32_e32 v132, v48, v48
	v_max_f32_e32 v132, 0xc2a00000, v132
	v_mul_f32_e32 v132, 0xbfb8aa3b, v132
	v_exp_f32_e32 v132, v132
	s_nop 0
	v_add_f32_e32 v132, 1.0, v132
	v_rcp_f32_e32 v132, v132
	s_nop 0
	v_fma_f32 v132, v132, v186, v8
	v_cmp_gt_f32_e32 vcc, s72, v132
	s_nop 1
	v_cndmask_b32_e64 v133, 0, 32, vcc
	v_ldexp_f32 v132, v132, v133
	v_log_f32_e32 v132, v132
	s_nop 0
	v_mul_f32_e32 v133, 0x3f317217, v132
	v_fma_f32 v133, v132, s73, -v133
	v_fmac_f32_e32 v133, 0x3377d1cf, v132
	v_fmac_f32_e32 v133, 0x3f317217, v132
	v_cmp_lt_f32_e64 s[0:1], |v132|, s11
	s_nop 1
	v_cndmask_b32_e64 v132, v132, v133, s[0:1]
	v_cndmask_b32_e32 v133, 0, v243, vcc
	v_sub_f32_e32 v132, v132, v133
	v_max_f32_e32 v133, v49, v49
	v_max_f32_e32 v133, 0xc2a00000, v133
	v_mul_f32_e32 v133, 0xbfb8aa3b, v133
	v_exp_f32_e32 v133, v133
	s_nop 0
	v_add_f32_e32 v133, 1.0, v133
	v_rcp_f32_e32 v133, v133
	s_nop 0
	v_fma_f32 v133, v133, v185, v172
	v_cmp_gt_f32_e32 vcc, s72, v133
	s_nop 1
	v_cndmask_b32_e64 v134, 0, 32, vcc
	v_ldexp_f32 v133, v133, v134
	v_log_f32_e32 v133, v133
	s_nop 0
	v_mul_f32_e32 v134, 0x3f317217, v133
	v_fma_f32 v134, v133, s73, -v134
	v_fmac_f32_e32 v134, 0x3377d1cf, v133
	v_fmac_f32_e32 v134, 0x3f317217, v133
	v_cmp_lt_f32_e64 s[0:1], |v133|, s11
	s_nop 1
	v_cndmask_b32_e64 v133, v133, v134, s[0:1]
	v_cndmask_b32_e32 v134, 0, v243, vcc
	v_sub_f32_e32 v133, v133, v134
	v_max_f32_e32 v134, v42, v42
	v_max_f32_e32 v134, 0xc2a00000, v134
	v_mul_f32_e32 v134, 0xbfb8aa3b, v134
	v_exp_f32_e32 v134, v134
	s_nop 0
	v_add_f32_e32 v134, 1.0, v134
	v_rcp_f32_e32 v134, v134
	s_nop 0
	v_fma_f32 v134, v134, v184, v182
	v_cmp_gt_f32_e32 vcc, s72, v134
	s_nop 1
	v_cndmask_b32_e64 v135, 0, 32, vcc
	v_ldexp_f32 v134, v134, v135
	v_log_f32_e32 v134, v134
	s_nop 0
	v_mul_f32_e32 v135, 0x3f317217, v134
	v_fma_f32 v135, v134, s73, -v135
	v_fmac_f32_e32 v135, 0x3377d1cf, v134
	v_fmac_f32_e32 v135, 0x3f317217, v134
	v_cmp_lt_f32_e64 s[0:1], |v134|, s11
	s_nop 1
	v_cndmask_b32_e64 v134, v134, v135, s[0:1]
	v_cndmask_b32_e32 v135, 0, v243, vcc
	v_sub_f32_e32 v134, v134, v135
	v_max_f32_e32 v135, v43, v43
	v_max_f32_e32 v135, 0xc2a00000, v135
	v_mul_f32_e32 v135, 0xbfb8aa3b, v135
	v_exp_f32_e32 v135, v135
	s_nop 0
	v_add_f32_e32 v135, 1.0, v135
	v_rcp_f32_e32 v135, v135
	s_nop 0
	v_fma_f32 v135, v135, v183, v180
	v_cmp_gt_f32_e32 vcc, s72, v135
	s_nop 1
	v_cndmask_b32_e64 v136, 0, 32, vcc
	v_ldexp_f32 v135, v135, v136
	v_log_f32_e32 v135, v135
	s_nop 0
	v_mul_f32_e32 v136, 0x3f317217, v135
	v_fma_f32 v136, v135, s73, -v136
	v_fmac_f32_e32 v136, 0x3377d1cf, v135
	v_fmac_f32_e32 v136, 0x3f317217, v135
	v_cmp_lt_f32_e64 s[0:1], |v135|, s11
	s_nop 1
	v_cndmask_b32_e64 v135, v135, v136, s[0:1]
	v_cndmask_b32_e32 v136, 0, v243, vcc
	v_sub_f32_e32 v135, v135, v136
	v_max_f32_e32 v136, v44, v44
	v_max_f32_e32 v136, 0xc2a00000, v136
	v_mul_f32_e32 v136, 0xbfb8aa3b, v136
; __device__ __forceinline__ float lbound(float h0, float h1) { return 1.f / (1.f + expf(h0 - h1)); }
; __device__ __forceinline__ float logf_gate(float x, float lb) {
;     const float t = __expf(-fmaxf(x, -80.f));
;     return __logf(lb + (1.f - lb) * __builtin_amdgcn_rcpf(1.f + t));
; }
;     __device__ __forceinline__ void operator()(EPI_ARGS) const {
;     ...
;         } else if (seg == 8) {
; #pragma unroll
;             for (int bj = 0; bj < 2; ++bj) { const int c0 = colt + bj * 128 - 8192;
;                 f32x4 lb0 = (f32x4){0.f, 0.f, 0.f, 0.f}, lb1 = lb0;
;                 if (layer != 0) { const f32x4 a0 = *(const f32x4*)(hlb + c0), a1 = *(const f32x4*)(hlb + c0 + 4), b0 = *(const f32x4*)(hlb + WMIX + c0), b1 = *(const f32x4*)(hlb + WMIX + c0 + 4);
;                     lb0 = (f32x4){lbound(a0[0], b0[0]), lbound(a0[1], b0[1]), lbound(a0[2], b0[2]), lbound(a0[3], b0[3])};
;                     lb1 = (f32x4){lbound(a1[0], b1[0]), lbound(a1[1], b1[1]), lbound(a1[2], b1[2]), lbound(a1[3], b1[3])}; }
; #pragma unroll
;                 for (int ai = 0; ai < 2; ++ai)
; #pragma unroll
;                     for (int m = 0; m < 4; ++m) { const int row = row0 + ai * 128 + m * 16;
;                         const f32x4 v0 = acc[ai][bj][m][0], v1 = acc[ai][bj][m][1];
;                         const f32x4 o0 = (f32x4){logf_gate(v0[0], lb0[0]), logf_gate(v0[1], lb0[1]), logf_gate(v0[2], lb0[2]), logf_gate(v0[3], lb0[3])};
;                         const f32x4 o1 = (f32x4){logf_gate(v1[0], lb1[0]), logf_gate(v1[1], lb1[1]), logf_gate(v1[2], lb1[2]), logf_gate(v1[3], lb1[3])};
;                         float* p = lf_out + (size_t)row * WMIX + c0;
;                         *(f32x4*)p = o0; *(f32x4*)(p + 4) = o1; } }
	v_exp_f32_e32 v136, v136
	s_nop 0
	v_add_f32_e32 v136, 1.0, v136
	v_rcp_f32_e32 v136, v136
	s_nop 0
	v_fma_f32 v136, v136, v181, v175
	v_cmp_gt_f32_e32 vcc, s72, v136
	s_nop 1
	v_cndmask_b32_e64 v137, 0, 32, vcc
	v_ldexp_f32 v136, v136, v137
	v_log_f32_e32 v136, v136
	s_nop 0
	v_mul_f32_e32 v137, 0x3f317217, v136
	v_fma_f32 v137, v136, s73, -v137
	v_fmac_f32_e32 v137, 0x3377d1cf, v136
	v_fmac_f32_e32 v137, 0x3f317217, v136
	v_cmp_lt_f32_e64 s[0:1], |v136|, s11
	s_nop 1
	v_cndmask_b32_e64 v136, v136, v137, s[0:1]
	v_cndmask_b32_e32 v137, 0, v243, vcc
	v_sub_f32_e32 v136, v136, v137
	v_max_f32_e32 v137, v45, v45
	v_max_f32_e32 v137, 0xc2a00000, v137
	v_mul_f32_e32 v137, 0xbfb8aa3b, v137
	v_exp_f32_e32 v137, v137
	s_nop 0
	v_add_f32_e32 v137, 1.0, v137
	v_rcp_f32_e32 v137, v137
	s_nop 0
	v_fma_f32 v137, v137, v174, v173
	v_cmp_gt_f32_e32 vcc, s72, v137
	s_nop 1
	v_cndmask_b32_e64 v151, 0, 32, vcc
	v_ldexp_f32 v137, v137, v151
	v_log_f32_e32 v137, v137
	s_nop 0
	v_mul_f32_e32 v151, 0x3f317217, v137
	v_fma_f32 v151, v137, s73, -v151
	v_fmac_f32_e32 v151, 0x3377d1cf, v137
	v_fmac_f32_e32 v151, 0x3f317217, v137
	v_cmp_lt_f32_e64 s[0:1], |v137|, s11
	s_nop 1
	v_cndmask_b32_e64 v137, v137, v151, s[0:1]
	s_mov_b64 s[0:1], 0x90000
	v_lshl_add_u64 v[166:167], v[154:155], 0, s[0:1]
	v_cndmask_b32_e32 v151, 0, v243, vcc
	v_lshl_add_u64 v[168:169], v[166:167], 0, v[158:159]
	v_sub_f32_e32 v137, v137, v151
	global_store_dwordx4 v[168:169], v[130:133], off sc1
	global_store_dwordx4 v[168:169], v[134:137], off offset:16 sc1
	s_nop 0
	v_max_f32_e32 v130, v30, v30
	v_max_f32_e32 v130, 0xc2a00000, v130
	v_mul_f32_e32 v130, 0xbfb8aa3b, v130
	v_exp_f32_e32 v130, v130
	s_nop 0
	v_add_f32_e32 v130, 1.0, v130
	v_rcp_f32_e32 v130, v130
	s_nop 0
	v_fma_f32 v130, v130, v188, v171
	v_cmp_gt_f32_e32 vcc, s72, v130
	s_nop 1
	v_cndmask_b32_e64 v131, 0, 32, vcc
	v_ldexp_f32 v130, v130, v131
	v_log_f32_e32 v130, v130
	s_nop 0
	v_mul_f32_e32 v131, 0x3f317217, v130
	v_fma_f32 v131, v130, s73, -v131
	v_fmac_f32_e32 v131, 0x3377d1cf, v130
	v_fmac_f32_e32 v131, 0x3f317217, v130
	v_cmp_lt_f32_e64 s[0:1], |v130|, s11
	s_nop 1
	v_cndmask_b32_e64 v130, v130, v131, s[0:1]
	v_cndmask_b32_e32 v131, 0, v243, vcc
	v_sub_f32_e32 v130, v130, v131
	v_max_f32_e32 v131, v31, v31
	v_max_f32_e32 v131, 0xc2a00000, v131
	v_mul_f32_e32 v131, 0xbfb8aa3b, v131
	v_exp_f32_e32 v131, v131
	s_nop 0
	v_add_f32_e32 v131, 1.0, v131
	v_rcp_f32_e32 v131, v131
	s_nop 0
	v_fma_f32 v131, v131, v187, v170
	v_cmp_gt_f32_e32 vcc, s72, v131
	s_nop 1
	v_cndmask_b32_e64 v132, 0, 32, vcc
	v_ldexp_f32 v131, v131, v132
	v_log_f32_e32 v131, v131
	s_nop 0
	v_mul_f32_e32 v132, 0x3f317217, v131
	v_fma_f32 v132, v131, s73, -v132
	v_fmac_f32_e32 v132, 0x3377d1cf, v131
	v_fmac_f32_e32 v132, 0x3f317217, v131
	v_cmp_lt_f32_e64 s[0:1], |v131|, s11
	s_nop 1
	v_cndmask_b32_e64 v131, v131, v132, s[0:1]
	v_cndmask_b32_e32 v132, 0, v243, vcc
	v_sub_f32_e32 v131, v131, v132
	v_max_f32_e32 v132, v32, v32
	v_max_f32_e32 v132, 0xc2a00000, v132
	v_mul_f32_e32 v132, 0xbfb8aa3b, v132
	v_exp_f32_e32 v132, v132
	s_nop 0
	v_add_f32_e32 v132, 1.0, v132
	v_rcp_f32_e32 v132, v132
	s_nop 0
	v_fma_f32 v132, v132, v186, v8
	v_cmp_gt_f32_e32 vcc, s72, v132
	s_nop 1
	v_cndmask_b32_e64 v133, 0, 32, vcc
	v_ldexp_f32 v132, v132, v133
	v_log_f32_e32 v132, v132
	s_nop 0
	v_mul_f32_e32 v133, 0x3f317217, v132
	v_fma_f32 v133, v132, s73, -v133
	v_fmac_f32_e32 v133, 0x3377d1cf, v132
	v_fmac_f32_e32 v133, 0x3f317217, v132
	v_cmp_lt_f32_e64 s[0:1], |v132|, s11
	s_nop 1
	v_cndmask_b32_e64 v132, v132, v133, s[0:1]
	v_cndmask_b32_e32 v133, 0, v243, vcc
	v_sub_f32_e32 v132, v132, v133
	v_max_f32_e32 v133, v33, v33
	v_max_f32_e32 v133, 0xc2a00000, v133
	v_mul_f32_e32 v133, 0xbfb8aa3b, v133
	v_exp_f32_e32 v133, v133
	s_nop 0
	v_add_f32_e32 v133, 1.0, v133
	v_rcp_f32_e32 v133, v133
	s_nop 0
	v_fma_f32 v133, v133, v185, v172
	v_cmp_gt_f32_e32 vcc, s72, v133
	s_nop 1
	v_cndmask_b32_e64 v134, 0, 32, vcc
	v_ldexp_f32 v133, v133, v134
	v_log_f32_e32 v133, v133
	s_nop 0
	v_mul_f32_e32 v134, 0x3f317217, v133
	v_fma_f32 v134, v133, s73, -v134
	v_fmac_f32_e32 v134, 0x3377d1cf, v133
	v_fmac_f32_e32 v134, 0x3f317217, v133
	v_cmp_lt_f32_e64 s[0:1], |v133|, s11
	s_nop 1
	v_cndmask_b32_e64 v133, v133, v134, s[0:1]
	v_cndmask_b32_e32 v134, 0, v243, vcc
	v_sub_f32_e32 v133, v133, v134
	v_max_f32_e32 v134, v26, v26
	v_max_f32_e32 v134, 0xc2a00000, v134
	v_mul_f32_e32 v134, 0xbfb8aa3b, v134
	v_exp_f32_e32 v134, v134
	s_nop 0
	v_add_f32_e32 v134, 1.0, v134
	v_rcp_f32_e32 v134, v134
	s_nop 0
	v_fma_f32 v134, v134, v184, v182
	v_cmp_gt_f32_e32 vcc, s72, v134
	s_nop 1
	v_cndmask_b32_e64 v135, 0, 32, vcc
	v_ldexp_f32 v134, v134, v135
	v_log_f32_e32 v134, v134
	s_nop 0
	v_mul_f32_e32 v135, 0x3f317217, v134
	v_fma_f32 v135, v134, s73, -v135
	v_fmac_f32_e32 v135, 0x3377d1cf, v134
	v_fmac_f32_e32 v135, 0x3f317217, v134
	v_cmp_lt_f32_e64 s[0:1], |v134|, s11
	s_nop 1
	v_cndmask_b32_e64 v134, v134, v135, s[0:1]
	v_cndmask_b32_e32 v135, 0, v243, vcc
	v_sub_f32_e32 v134, v134, v135
	v_max_f32_e32 v135, v27, v27
	v_max_f32_e32 v135, 0xc2a00000, v135
	v_mul_f32_e32 v135, 0xbfb8aa3b, v135
	v_exp_f32_e32 v135, v135
	s_nop 0
	v_add_f32_e32 v135, 1.0, v135
	v_rcp_f32_e32 v135, v135
	s_nop 0
	v_fma_f32 v135, v135, v183, v180
	v_cmp_gt_f32_e32 vcc, s72, v135
	s_nop 1
	v_cndmask_b32_e64 v136, 0, 32, vcc
	v_ldexp_f32 v135, v135, v136
	v_log_f32_e32 v135, v135
	s_nop 0
	v_mul_f32_e32 v136, 0x3f317217, v135
	v_fma_f32 v136, v135, s73, -v136
	v_fmac_f32_e32 v136, 0x3377d1cf, v135
	v_fmac_f32_e32 v136, 0x3f317217, v135
	v_cmp_lt_f32_e64 s[0:1], |v135|, s11
	s_nop 1
	v_cndmask_b32_e64 v135, v135, v136, s[0:1]
; __device__ __forceinline__ float lbound(float h0, float h1) { return 1.f / (1.f + expf(h0 - h1)); }
; __device__ __forceinline__ float logf_gate(float x, float lb) {
;     const float t = __expf(-fmaxf(x, -80.f));
;     return __logf(lb + (1.f - lb) * __builtin_amdgcn_rcpf(1.f + t));
; }
;     __device__ __forceinline__ void operator()(EPI_ARGS) const {
;     ...
;         } else if (seg == 8) {
; #pragma unroll
;             for (int bj = 0; bj < 2; ++bj) { const int c0 = colt + bj * 128 - 8192;
;                 f32x4 lb0 = (f32x4){0.f, 0.f, 0.f, 0.f}, lb1 = lb0;
;                 if (layer != 0) { const f32x4 a0 = *(const f32x4*)(hlb + c0), a1 = *(const f32x4*)(hlb + c0 + 4), b0 = *(const f32x4*)(hlb + WMIX + c0), b1 = *(const f32x4*)(hlb + WMIX + c0 + 4);
;                     lb0 = (f32x4){lbound(a0[0], b0[0]), lbound(a0[1], b0[1]), lbound(a0[2], b0[2]), lbound(a0[3], b0[3])};
;                     lb1 = (f32x4){lbound(a1[0], b1[0]), lbound(a1[1], b1[1]), lbound(a1[2], b1[2]), lbound(a1[3], b1[3])}; }
; #pragma unroll
;                 for (int ai = 0; ai < 2; ++ai)
; #pragma unroll
;                     for (int m = 0; m < 4; ++m) { const int row = row0 + ai * 128 + m * 16;
;                         const f32x4 v0 = acc[ai][bj][m][0], v1 = acc[ai][bj][m][1];
;                         const f32x4 o0 = (f32x4){logf_gate(v0[0], lb0[0]), logf_gate(v0[1], lb0[1]), logf_gate(v0[2], lb0[2]), logf_gate(v0[3], lb0[3])};
;                         const f32x4 o1 = (f32x4){logf_gate(v1[0], lb1[0]), logf_gate(v1[1], lb1[1]), logf_gate(v1[2], lb1[2]), logf_gate(v1[3], lb1[3])};
;                         float* p = lf_out + (size_t)row * WMIX + c0;
;                         *(f32x4*)p = o0; *(f32x4*)(p + 4) = o1; } }
	v_cndmask_b32_e32 v136, 0, v243, vcc
	v_sub_f32_e32 v135, v135, v136
	v_max_f32_e32 v136, v28, v28
	v_max_f32_e32 v136, 0xc2a00000, v136
	v_mul_f32_e32 v136, 0xbfb8aa3b, v136
	v_exp_f32_e32 v136, v136
	s_nop 0
	v_add_f32_e32 v136, 1.0, v136
	v_rcp_f32_e32 v136, v136
	s_nop 0
	v_fma_f32 v136, v136, v181, v175
	v_cmp_gt_f32_e32 vcc, s72, v136
	s_nop 1
	v_cndmask_b32_e64 v137, 0, 32, vcc
	v_ldexp_f32 v136, v136, v137
	v_log_f32_e32 v136, v136
	s_nop 0
	v_mul_f32_e32 v137, 0x3f317217, v136
	v_fma_f32 v137, v136, s73, -v137
	v_fmac_f32_e32 v137, 0x3377d1cf, v136
	v_fmac_f32_e32 v137, 0x3f317217, v136
	v_cmp_lt_f32_e64 s[0:1], |v136|, s11
	s_nop 1
	v_cndmask_b32_e64 v136, v136, v137, s[0:1]
	v_cndmask_b32_e32 v137, 0, v243, vcc
	v_sub_f32_e32 v136, v136, v137
	v_max_f32_e32 v137, v29, v29
	v_max_f32_e32 v137, 0xc2a00000, v137
	v_mul_f32_e32 v137, 0xbfb8aa3b, v137
	v_exp_f32_e32 v137, v137
	s_nop 0
	v_add_f32_e32 v137, 1.0, v137
	v_rcp_f32_e32 v137, v137
	s_nop 0
	v_fma_f32 v137, v137, v174, v173
	v_cmp_gt_f32_e32 vcc, s72, v137
	s_nop 1
	v_cndmask_b32_e64 v151, 0, 32, vcc
	v_ldexp_f32 v137, v137, v151
	v_log_f32_e32 v137, v137
	s_nop 0
	v_mul_f32_e32 v151, 0x3f317217, v137
	v_fma_f32 v151, v137, s73, -v151
	v_fmac_f32_e32 v151, 0x3377d1cf, v137
	v_fmac_f32_e32 v151, 0x3f317217, v137
	v_cmp_lt_f32_e64 s[0:1], |v137|, s11
	s_nop 1
	v_cndmask_b32_e64 v137, v137, v151, s[0:1]
	s_mov_b64 s[0:1], 0xa0000
	v_lshl_add_u64 v[168:169], v[154:155], 0, s[0:1]
	v_cndmask_b32_e32 v151, 0, v243, vcc
	v_lshl_add_u64 v[190:191], v[168:169], 0, v[158:159]
	v_sub_f32_e32 v137, v137, v151
	global_store_dwordx4 v[190:191], v[130:133], off sc1
	global_store_dwordx4 v[190:191], v[134:137], off offset:16 sc1
	v_mov_b32_e32 v151, 0
	v_max_f32_e32 v130, v14, v14
	v_max_f32_e32 v130, 0xc2a00000, v130
	v_mul_f32_e32 v130, 0xbfb8aa3b, v130
	v_exp_f32_e32 v130, v130
	s_nop 0
	v_add_f32_e32 v130, 1.0, v130
	v_rcp_f32_e32 v130, v130
	s_nop 0
	v_fmac_f32_e32 v171, v130, v188
	v_cmp_gt_f32_e32 vcc, s72, v171
	s_nop 1
	v_cndmask_b32_e64 v130, 0, 32, vcc
	v_ldexp_f32 v130, v171, v130
	v_log_f32_e32 v130, v130
	s_nop 0
	v_mul_f32_e32 v131, 0x3f317217, v130
	v_fma_f32 v131, v130, s73, -v131
	v_fmac_f32_e32 v131, 0x3377d1cf, v130
	v_fmac_f32_e32 v131, 0x3f317217, v130
	v_cmp_lt_f32_e64 s[0:1], |v130|, s11
	s_nop 1
	v_cndmask_b32_e64 v130, v130, v131, s[0:1]
	v_cndmask_b32_e32 v131, 0, v243, vcc
	v_sub_f32_e32 v130, v130, v131
	v_max_f32_e32 v131, v15, v15
	v_max_f32_e32 v131, 0xc2a00000, v131
	v_mul_f32_e32 v131, 0xbfb8aa3b, v131
	v_exp_f32_e32 v131, v131
	s_nop 0
	v_add_f32_e32 v131, 1.0, v131
	v_rcp_f32_e32 v131, v131
	s_nop 0
	v_fmac_f32_e32 v170, v131, v187
	v_cmp_gt_f32_e32 vcc, s72, v170
	s_nop 1
	v_cndmask_b32_e64 v131, 0, 32, vcc
	v_ldexp_f32 v131, v170, v131
	v_log_f32_e32 v131, v131
	s_nop 0
	v_mul_f32_e32 v132, 0x3f317217, v131
	v_fma_f32 v132, v131, s73, -v132
	v_fmac_f32_e32 v132, 0x3377d1cf, v131
	v_fmac_f32_e32 v132, 0x3f317217, v131
	v_cmp_lt_f32_e64 s[0:1], |v131|, s11
	s_nop 1
	v_cndmask_b32_e64 v131, v131, v132, s[0:1]
	v_cndmask_b32_e32 v132, 0, v243, vcc
	v_sub_f32_e32 v131, v131, v132
	v_max_f32_e32 v132, v16, v16
	v_max_f32_e32 v132, 0xc2a00000, v132
	v_mul_f32_e32 v132, 0xbfb8aa3b, v132
	v_exp_f32_e32 v132, v132
	s_nop 0
	v_add_f32_e32 v132, 1.0, v132
	v_rcp_f32_e32 v132, v132
	s_nop 0
	v_fmac_f32_e32 v8, v132, v186
	v_cmp_gt_f32_e32 vcc, s72, v8
	s_nop 1
	v_cndmask_b32_e64 v132, 0, 32, vcc
	v_ldexp_f32 v8, v8, v132
	v_log_f32_e32 v8, v8
	s_nop 0
	v_mul_f32_e32 v132, 0x3f317217, v8
	v_fma_f32 v132, v8, s73, -v132
	v_fmac_f32_e32 v132, 0x3377d1cf, v8
	v_fmac_f32_e32 v132, 0x3f317217, v8
	v_cmp_lt_f32_e64 s[0:1], |v8|, s11
	s_nop 1
	v_cndmask_b32_e64 v8, v8, v132, s[0:1]
	v_cndmask_b32_e32 v132, 0, v243, vcc
	v_sub_f32_e32 v132, v8, v132
	v_max_f32_e32 v8, v17, v17
	v_max_f32_e32 v8, 0xc2a00000, v8
	v_mul_f32_e32 v8, 0xbfb8aa3b, v8
	v_exp_f32_e32 v8, v8
	s_nop 0
	v_add_f32_e32 v8, 1.0, v8
	v_rcp_f32_e32 v8, v8
	s_nop 0
	v_fmac_f32_e32 v172, v8, v185
	v_cmp_gt_f32_e32 vcc, s72, v172
	s_nop 1
	v_cndmask_b32_e64 v8, 0, 32, vcc
	v_ldexp_f32 v8, v172, v8
	v_log_f32_e32 v8, v8
	v_mov_b32_e32 v172, 0
	v_mul_f32_e32 v133, 0x3f317217, v8
	v_fma_f32 v133, v8, s73, -v133
	v_fmac_f32_e32 v133, 0x3377d1cf, v8
	v_fmac_f32_e32 v133, 0x3f317217, v8
	v_cmp_lt_f32_e64 s[0:1], |v8|, s11
	s_nop 1
	v_cndmask_b32_e64 v8, v8, v133, s[0:1]
	v_cndmask_b32_e32 v133, 0, v243, vcc
	v_sub_f32_e32 v133, v8, v133
	v_max_f32_e32 v8, v10, v10
	v_max_f32_e32 v8, 0xc2a00000, v8
	v_mul_f32_e32 v8, 0xbfb8aa3b, v8
	v_exp_f32_e32 v8, v8
	s_nop 0
	v_add_f32_e32 v8, 1.0, v8
	v_rcp_f32_e32 v8, v8
	s_nop 0
	v_fmac_f32_e32 v182, v8, v184
	v_cmp_gt_f32_e32 vcc, s72, v182
	s_nop 1
	v_cndmask_b32_e64 v8, 0, 32, vcc
	v_ldexp_f32 v8, v182, v8
	v_log_f32_e32 v8, v8
	s_nop 0
	v_mul_f32_e32 v134, 0x3f317217, v8
	v_fma_f32 v134, v8, s73, -v134
	v_fmac_f32_e32 v134, 0x3377d1cf, v8
	v_fmac_f32_e32 v134, 0x3f317217, v8
	v_cmp_lt_f32_e64 s[0:1], |v8|, s11
	s_nop 1
	v_cndmask_b32_e64 v8, v8, v134, s[0:1]
	v_cndmask_b32_e32 v134, 0, v243, vcc
	v_sub_f32_e32 v134, v8, v134
	v_max_f32_e32 v8, v11, v11
	v_max_f32_e32 v8, 0xc2a00000, v8
	v_mul_f32_e32 v8, 0xbfb8aa3b, v8
	v_exp_f32_e32 v8, v8
	s_nop 0
	v_add_f32_e32 v8, 1.0, v8
	v_rcp_f32_e32 v8, v8
	s_nop 0
	v_fmac_f32_e32 v180, v8, v183
	v_cmp_gt_f32_e32 vcc, s72, v180
	s_nop 1
	v_cndmask_b32_e64 v8, 0, 32, vcc
	v_ldexp_f32 v8, v180, v8
	v_log_f32_e32 v8, v8
	v_mov_b32_e32 v180, 0
	v_mul_f32_e32 v135, 0x3f317217, v8
	v_fma_f32 v135, v8, s73, -v135
	v_fmac_f32_e32 v135, 0x3377d1cf, v8
	v_fmac_f32_e32 v135, 0x3f317217, v8
	v_cmp_lt_f32_e64 s[0:1], |v8|, s11
	s_nop 1
; __device__ __forceinline__ float lbound(float h0, float h1) { return 1.f / (1.f + expf(h0 - h1)); }
;     __device__ __forceinline__ void operator()(EPI_ARGS) const {
;     ...
;         } else if (seg == 8) {
; #pragma unroll
;             for (int bj = 0; bj < 2; ++bj) { const int c0 = colt + bj * 128 - 8192;
;                 f32x4 lb0 = (f32x4){0.f, 0.f, 0.f, 0.f}, lb1 = lb0;
;                 if (layer != 0) { const f32x4 a0 = *(const f32x4*)(hlb + c0), a1 = *(const f32x4*)(hlb + c0 + 4), b0 = *(const f32x4*)(hlb + WMIX + c0), b1 = *(const f32x4*)(hlb + WMIX + c0 + 4);
;                     lb0 = (f32x4){lbound(a0[0], b0[0]), lbound(a0[1], b0[1]), lbound(a0[2], b0[2]), lbound(a0[3], b0[3])};
;                     lb1 = (f32x4){lbound(a1[0], b1[0]), lbound(a1[1], b1[1]), lbound(a1[2], b1[2]), lbound(a1[3], b1[3])}; }
; #pragma unroll
;                 for (int ai = 0; ai < 2; ++ai)
; #pragma unroll
;                     for (int m = 0; m < 4; ++m) { const int row = row0 + ai * 128 + m * 16;
;                         const f32x4 v0 = acc[ai][bj][m][0], v1 = acc[ai][bj][m][1];
;                         const f32x4 o0 = (f32x4){logf_gate(v0[0], lb0[0]), logf_gate(v0[1], lb0[1]), logf_gate(v0[2], lb0[2]), logf_gate(v0[3], lb0[3])};
;                         const f32x4 o1 = (f32x4){logf_gate(v1[0], lb1[0]), logf_gate(v1[1], lb1[1]), logf_gate(v1[2], lb1[2]), logf_gate(v1[3], lb1[3])};
;                         float* p = lf_out + (size_t)row * WMIX + c0;
;                         *(f32x4*)p = o0; *(f32x4*)(p + 4) = o1; } }
	v_cndmask_b32_e64 v8, v8, v135, s[0:1]
	v_cndmask_b32_e32 v135, 0, v243, vcc
	v_sub_f32_e32 v135, v8, v135
	v_max_f32_e32 v8, v12, v12
	v_max_f32_e32 v8, 0xc2a00000, v8
	v_mul_f32_e32 v8, 0xbfb8aa3b, v8
	v_exp_f32_e32 v8, v8
	s_nop 0
	v_add_f32_e32 v8, 1.0, v8
	v_rcp_f32_e32 v8, v8
	s_nop 0
	v_fmac_f32_e32 v175, v8, v181
	v_cmp_gt_f32_e32 vcc, s72, v175
	v_mov_b32_e32 v181, 0
	s_nop 0
	v_cndmask_b32_e64 v8, 0, 32, vcc
	v_ldexp_f32 v8, v175, v8
	v_log_f32_e32 v8, v8
	s_nop 0
	v_mul_f32_e32 v136, 0x3f317217, v8
	v_fma_f32 v136, v8, s73, -v136
	v_fmac_f32_e32 v136, 0x3377d1cf, v8
	v_fmac_f32_e32 v136, 0x3f317217, v8
	v_cmp_lt_f32_e64 s[0:1], |v8|, s11
	s_nop 1
	v_cndmask_b32_e64 v8, v8, v136, s[0:1]
	v_cndmask_b32_e32 v136, 0, v243, vcc
	v_sub_f32_e32 v136, v8, v136
	v_max_f32_e32 v8, v13, v13
	v_max_f32_e32 v8, 0xc2a00000, v8
	v_mul_f32_e32 v8, 0xbfb8aa3b, v8
	v_exp_f32_e32 v8, v8
	s_nop 0
	v_add_f32_e32 v8, 1.0, v8
	v_rcp_f32_e32 v8, v8
	s_nop 0
	v_fmac_f32_e32 v173, v8, v174
	v_cmp_gt_f32_e32 vcc, s72, v173
	v_mov_b32_e32 v174, 0
	s_nop 0
	v_cndmask_b32_e64 v8, 0, 32, vcc
	v_ldexp_f32 v8, v173, v8
	v_log_f32_e32 v8, v8
	v_mov_b32_e32 v173, 0
	v_mul_f32_e32 v137, 0x3f317217, v8
	v_fma_f32 v137, v8, s73, -v137
	v_fmac_f32_e32 v137, 0x3377d1cf, v8
	v_fmac_f32_e32 v137, 0x3f317217, v8
	v_cmp_lt_f32_e64 s[0:1], |v8|, s11
	s_nop 1
	v_cndmask_b32_e64 v8, v8, v137, s[0:1]
	s_mov_b64 s[0:1], 0xb0000
	v_cndmask_b32_e32 v137, 0, v243, vcc
	v_lshl_add_u64 v[170:171], v[154:155], 0, s[0:1]
	v_sub_f32_e32 v137, v8, v137
	v_lshl_add_u64 v[158:159], v[170:171], 0, v[158:159]
	v_add_u32_e32 v8, 0xffffe080, v152
	global_store_dwordx4 v[158:159], v[130:133], off sc1
	global_store_dwordx4 v[158:159], v[134:137], off offset:16 sc1
	s_and_b64 vcc, exec, s[38:39]
	v_lshlrev_b64 v[158:159], 2, v[8:9]
	v_mov_b32_e32 v8, 0
	s_cbranch_vccnz .LBB0_180
	v_readlane_b32 s56, v252, 16
	v_readlane_b32 s0, v253, 1
	v_readlane_b32 s68, v252, 28
	v_readlane_b32 s69, v252, 29
	v_readlane_b32 s1, v253, 2
	s_mov_b32 s2, 0x3fb8aa3b
	v_lshl_add_u64 v[134:135], s[68:69], 0, v[158:159]
	v_lshl_add_u64 v[180:181], s[0:1], 0, v[158:159]
	global_load_dwordx4 v[130:133], v[134:135], off offset:16
	global_load_dwordx4 v[172:175], v[134:135], off
	s_nop 0
	global_load_dwordx4 v[134:137], v[180:181], off offset:16
	s_nop 0
	global_load_dwordx4 v[180:183], v[180:181], off
	s_mov_b32 s3, 0xc2ce8ed0
	s_mov_b32 s4, 0x42b17218
	v_readlane_b32 s57, v252, 17
	v_readlane_b32 s58, v252, 18
	v_readlane_b32 s59, v252, 19
	v_readlane_b32 s60, v252, 20
	v_readlane_b32 s61, v252, 21
	v_readlane_b32 s62, v252, 22
	v_readlane_b32 s63, v252, 23
	v_readlane_b32 s64, v252, 24
	v_readlane_b32 s65, v252, 25
	v_readlane_b32 s66, v252, 26
	v_readlane_b32 s67, v252, 27
	v_readlane_b32 s70, v252, 30
	v_readlane_b32 s71, v252, 31
	s_waitcnt vmcnt(0)
	v_sub_f32_e32 v130, v130, v134
	v_sub_f32_e32 v8, v172, v180
	v_mul_f32_e32 v151, 0x3fb8aa3b, v8
	v_fma_f32 v153, v8, s2, -v151
	v_rndne_f32_e32 v172, v151
	v_fmac_f32_e32 v153, 0x32a5705f, v8
	v_sub_f32_e32 v151, v151, v172
	v_add_f32_e32 v151, v151, v153
	v_exp_f32_e32 v151, v151
	v_cvt_i32_f32_e32 v153, v172
	v_cmp_ngt_f32_e32 vcc, s3, v8
	v_mul_f32_e32 v134, 0x3fb8aa3b, v130
	v_sub_f32_e32 v131, v131, v135
	v_ldexp_f32 v151, v151, v153
	v_cndmask_b32_e32 v151, 0, v151, vcc
	v_cmp_nlt_f32_e32 vcc, s4, v8
	v_sub_f32_e32 v8, v173, v181
	v_sub_f32_e32 v132, v132, v136
	v_cndmask_b32_e32 v172, v242, v151, vcc
	v_mul_f32_e32 v151, 0x3fb8aa3b, v8
	v_fma_f32 v153, v8, s2, -v151
	v_rndne_f32_e32 v173, v151
	v_fmac_f32_e32 v153, 0x32a5705f, v8
	v_sub_f32_e32 v151, v151, v173
	v_add_f32_e32 v151, v151, v153
	v_exp_f32_e32 v151, v151
	v_cvt_i32_f32_e32 v153, v173
	v_cmp_ngt_f32_e32 vcc, s3, v8
	v_sub_f32_e32 v133, v133, v137
	v_ldexp_f32 v151, v151, v153
	v_cndmask_b32_e32 v151, 0, v151, vcc
	v_cmp_nlt_f32_e32 vcc, s4, v8
	v_sub_f32_e32 v8, v174, v182
	s_nop 0
	v_cndmask_b32_e32 v173, v242, v151, vcc
	v_mul_f32_e32 v151, 0x3fb8aa3b, v8
	v_fma_f32 v153, v8, s2, -v151
	v_rndne_f32_e32 v174, v151
	v_fmac_f32_e32 v153, 0x32a5705f, v8
	v_sub_f32_e32 v151, v151, v174
	v_add_f32_e32 v151, v151, v153
	v_exp_f32_e32 v151, v151
	v_cvt_i32_f32_e32 v153, v174
	v_cmp_ngt_f32_e32 vcc, s3, v8
	v_pk_add_f32 v[172:173], v[172:173], 1.0 op_sel_hi:[1,0]
	v_ldexp_f32 v151, v151, v153
	v_cndmask_b32_e32 v151, 0, v151, vcc
	v_cmp_nlt_f32_e32 vcc, s4, v8
	v_sub_f32_e32 v8, v175, v183
	s_nop 0
	v_cndmask_b32_e32 v174, v242, v151, vcc
	v_mul_f32_e32 v151, 0x3fb8aa3b, v8
	v_fma_f32 v153, v8, s2, -v151
	v_rndne_f32_e32 v175, v151
	v_fmac_f32_e32 v153, 0x32a5705f, v8
	v_sub_f32_e32 v151, v151, v175
	v_add_f32_e32 v151, v151, v153
	v_exp_f32_e32 v151, v151
	v_cvt_i32_f32_e32 v153, v175
	v_cmp_ngt_f32_e32 vcc, s3, v8
	v_ldexp_f32 v151, v151, v153
	s_nop 0
	v_cndmask_b32_e32 v151, 0, v151, vcc
	v_cmp_nlt_f32_e32 vcc, s4, v8
	v_div_scale_f32 v8, s[0:1], v172, v172, 1.0
	s_nop 0
	v_cndmask_b32_e32 v175, v242, v151, vcc
	v_rcp_f32_e32 v151, v8
	v_pk_add_f32 v[174:175], v[174:175], 1.0 op_sel_hi:[1,0]
	v_fma_f32 v153, -v8, v151, 1.0
	v_fmac_f32_e32 v151, v153, v151
	v_div_scale_f32 v153, vcc, 1.0, v172, 1.0
	v_mul_f32_e32 v180, v153, v151
	v_fma_f32 v181, -v8, v180, v153
	v_fmac_f32_e32 v180, v181, v151
	v_fma_f32 v8, -v8, v180, v153
	v_div_fmas_f32 v8, v8, v151, v180
	v_div_fixup_f32 v172, v8, v172, 1.0
	v_div_scale_f32 v8, s[0:1], v173, v173, 1.0
	v_rcp_f32_e32 v151, v8
	s_nop 0
	v_fma_f32 v153, -v8, v151, 1.0
	v_fmac_f32_e32 v151, v153, v151
	v_div_scale_f32 v153, vcc, 1.0, v173, 1.0
	v_mul_f32_e32 v180, v153, v151
	v_fma_f32 v181, -v8, v180, v153
	v_fmac_f32_e32 v180, v181, v151
	v_fma_f32 v8, -v8, v180, v153
; __device__ __forceinline__ float lbound(float h0, float h1) { return 1.f / (1.f + expf(h0 - h1)); }
;     __device__ __forceinline__ void operator()(EPI_ARGS) const {
;     ...
;                 if (layer != 0) { const f32x4 a0 = *(const f32x4*)(hlb + c0), a1 = *(const f32x4*)(hlb + c0 + 4), b0 = *(const f32x4*)(hlb + WMIX + c0), b1 = *(const f32x4*)(hlb + WMIX + c0 + 4);
;                     lb0 = (f32x4){lbound(a0[0], b0[0]), lbound(a0[1], b0[1]), lbound(a0[2], b0[2]), lbound(a0[3], b0[3])};
;                     lb1 = (f32x4){lbound(a1[0], b1[0]), lbound(a1[1], b1[1]), lbound(a1[2], b1[2]), lbound(a1[3], b1[3])}; }
	v_div_fmas_f32 v8, v8, v151, v180
	v_div_fixup_f32 v151, v8, v173, 1.0
	v_div_scale_f32 v8, s[0:1], v174, v174, 1.0
	v_rcp_f32_e32 v153, v8
	s_nop 0
	v_fma_f32 v173, -v8, v153, 1.0
	v_fmac_f32_e32 v153, v173, v153
	v_div_scale_f32 v173, vcc, 1.0, v174, 1.0
	v_mul_f32_e32 v180, v173, v153
	v_fma_f32 v181, -v8, v180, v173
	v_fmac_f32_e32 v180, v181, v153
	v_fma_f32 v8, -v8, v180, v173
	v_div_fmas_f32 v8, v8, v153, v180
	v_div_scale_f32 v153, s[0:1], v175, v175, 1.0
	v_rcp_f32_e32 v173, v153
	v_div_fixup_f32 v8, v8, v174, 1.0
	v_fma_f32 v174, -v153, v173, 1.0
	v_fmac_f32_e32 v173, v174, v173
	v_div_scale_f32 v174, vcc, 1.0, v175, 1.0
	v_mul_f32_e32 v180, v174, v173
	v_fma_f32 v181, -v153, v180, v174
	v_fmac_f32_e32 v180, v181, v173
	v_fma_f32 v153, -v153, v180, v174
	v_div_fmas_f32 v153, v153, v173, v180
	v_div_fixup_f32 v173, v153, v175, 1.0
	v_fma_f32 v153, v130, s2, -v134
	v_rndne_f32_e32 v174, v134
	v_fmac_f32_e32 v153, 0x32a5705f, v130
	v_sub_f32_e32 v134, v134, v174
	v_add_f32_e32 v134, v134, v153
	v_exp_f32_e32 v134, v134
	v_cvt_i32_f32_e32 v153, v174
	v_cmp_ngt_f32_e32 vcc, s3, v130
	v_ldexp_f32 v134, v134, v153
	s_nop 0
	v_cndmask_b32_e32 v134, 0, v134, vcc
	v_cmp_nlt_f32_e32 vcc, s4, v130
	s_nop 1
	v_cndmask_b32_e32 v130, v242, v134, vcc
	v_mul_f32_e32 v134, 0x3fb8aa3b, v131
	v_fma_f32 v135, v131, s2, -v134
	v_rndne_f32_e32 v153, v134
	v_fmac_f32_e32 v135, 0x32a5705f, v131
	v_sub_f32_e32 v134, v134, v153
	v_add_f32_e32 v134, v134, v135
	v_exp_f32_e32 v134, v134
	v_cvt_i32_f32_e32 v135, v153
	v_cmp_ngt_f32_e32 vcc, s3, v131
	v_ldexp_f32 v134, v134, v135
	s_nop 0
	v_cndmask_b32_e32 v134, 0, v134, vcc
	v_cmp_nlt_f32_e32 vcc, s4, v131
	s_nop 1
	v_cndmask_b32_e32 v131, v242, v134, vcc
	v_mul_f32_e32 v134, 0x3fb8aa3b, v132
	v_fma_f32 v135, v132, s2, -v134
	v_rndne_f32_e32 v136, v134
	v_fmac_f32_e32 v135, 0x32a5705f, v132
	v_sub_f32_e32 v134, v134, v136
	v_add_f32_e32 v134, v134, v135
	v_exp_f32_e32 v134, v134
	v_cvt_i32_f32_e32 v135, v136
	v_cmp_ngt_f32_e32 vcc, s3, v132
	v_pk_add_f32 v[130:131], v[130:131], 1.0 op_sel_hi:[1,0]
	v_ldexp_f32 v134, v134, v135
	v_cndmask_b32_e32 v134, 0, v134, vcc
	v_cmp_nlt_f32_e32 vcc, s4, v132
	s_nop 1
	v_cndmask_b32_e32 v132, v242, v134, vcc
	v_mul_f32_e32 v134, 0x3fb8aa3b, v133
	v_fma_f32 v135, v133, s2, -v134
	v_rndne_f32_e32 v136, v134
	v_fmac_f32_e32 v135, 0x32a5705f, v133
	v_sub_f32_e32 v134, v134, v136
	v_add_f32_e32 v134, v134, v135
	v_exp_f32_e32 v134, v134
	v_cvt_i32_f32_e32 v135, v136
	v_cmp_ngt_f32_e32 vcc, s3, v133
	v_ldexp_f32 v134, v134, v135
	s_nop 0
	v_cndmask_b32_e32 v134, 0, v134, vcc
	v_cmp_nlt_f32_e32 vcc, s4, v133
	s_nop 1
	v_cndmask_b32_e32 v133, v242, v134, vcc
	v_div_scale_f32 v134, s[0:1], v130, v130, 1.0
	v_rcp_f32_e32 v135, v134
	v_pk_add_f32 v[132:133], v[132:133], 1.0 op_sel_hi:[1,0]
	v_fma_f32 v136, -v134, v135, 1.0
	v_fmac_f32_e32 v135, v136, v135
	v_div_scale_f32 v136, vcc, 1.0, v130, 1.0
	v_mul_f32_e32 v137, v136, v135
	v_fma_f32 v153, -v134, v137, v136
	v_fmac_f32_e32 v137, v153, v135
	v_fma_f32 v134, -v134, v137, v136
	v_div_fmas_f32 v134, v134, v135, v137
	v_div_fixup_f32 v153, v134, v130, 1.0
	v_div_scale_f32 v130, s[0:1], v131, v131, 1.0
	v_rcp_f32_e32 v134, v130
	s_nop 0
	v_fma_f32 v135, -v130, v134, 1.0
	v_fmac_f32_e32 v134, v135, v134
	v_div_scale_f32 v135, vcc, 1.0, v131, 1.0
	v_mul_f32_e32 v136, v135, v134
	v_fma_f32 v137, -v130, v136, v135
	v_fmac_f32_e32 v136, v137, v134
	v_fma_f32 v130, -v130, v136, v135
	v_div_fmas_f32 v130, v130, v134, v136
	v_div_fixup_f32 v181, v130, v131, 1.0
	v_div_scale_f32 v130, s[0:1], v132, v132, 1.0
	v_rcp_f32_e32 v131, v130
	s_nop 0
	v_fma_f32 v134, -v130, v131, 1.0
	v_fmac_f32_e32 v131, v134, v131
	v_div_scale_f32 v134, vcc, 1.0, v132, 1.0
	v_mul_f32_e32 v135, v134, v131
	v_fma_f32 v136, -v130, v135, v134
	v_fmac_f32_e32 v135, v136, v131
	v_fma_f32 v130, -v130, v135, v134
	v_div_fmas_f32 v130, v130, v131, v135
	v_div_fixup_f32 v180, v130, v132, 1.0
	v_div_scale_f32 v130, s[0:1], v133, v133, 1.0
	v_rcp_f32_e32 v131, v130
	s_nop 0
	v_fma_f32 v132, -v130, v131, 1.0
	v_fmac_f32_e32 v131, v132, v131
	v_div_scale_f32 v132, vcc, 1.0, v133, 1.0
	v_mul_f32_e32 v134, v132, v131
	v_fma_f32 v135, -v130, v134, v132
	v_fmac_f32_e32 v134, v135, v131
	v_fma_f32 v130, -v130, v134, v132
	v_div_fmas_f32 v130, v130, v131, v134
	v_div_fixup_f32 v174, v130, v133, 1.0
; __device__ __forceinline__ float lbound(float h0, float h1) { return 1.f / (1.f + expf(h0 - h1)); }
; __device__ __forceinline__ float logf_gate(float x, float lb) {
;     const float t = __expf(-fmaxf(x, -80.f));
;     return __logf(lb + (1.f - lb) * __builtin_amdgcn_rcpf(1.f + t));
; }
;     __device__ __forceinline__ void operator()(EPI_ARGS) const {
;     ...
;         } else if (seg == 8) {
; #pragma unroll
;             for (int bj = 0; bj < 2; ++bj) { const int c0 = colt + bj * 128 - 8192;
;                 f32x4 lb0 = (f32x4){0.f, 0.f, 0.f, 0.f}, lb1 = lb0;
;                 if (layer != 0) { const f32x4 a0 = *(const f32x4*)(hlb + c0), a1 = *(const f32x4*)(hlb + c0 + 4), b0 = *(const f32x4*)(hlb + WMIX + c0), b1 = *(const f32x4*)(hlb + WMIX + c0 + 4);
;                     lb0 = (f32x4){lbound(a0[0], b0[0]), lbound(a0[1], b0[1]), lbound(a0[2], b0[2]), lbound(a0[3], b0[3])};
;                     lb1 = (f32x4){lbound(a1[0], b1[0]), lbound(a1[1], b1[1]), lbound(a1[2], b1[2]), lbound(a1[3], b1[3])}; }
; #pragma unroll
;                 for (int ai = 0; ai < 2; ++ai)
; #pragma unroll
;                     for (int m = 0; m < 4; ++m) { const int row = row0 + ai * 128 + m * 16;
;                         const f32x4 v0 = acc[ai][bj][m][0], v1 = acc[ai][bj][m][1];
;                         const f32x4 o0 = (f32x4){logf_gate(v0[0], lb0[0]), logf_gate(v0[1], lb0[1]), logf_gate(v0[2], lb0[2]), logf_gate(v0[3], lb0[3])};
;                         const f32x4 o1 = (f32x4){logf_gate(v1[0], lb1[0]), logf_gate(v1[1], lb1[1]), logf_gate(v1[2], lb1[2]), logf_gate(v1[3], lb1[3])};
;                         float* p = lf_out + (size_t)row * WMIX + c0;
;                         *(f32x4*)p = o0; *(f32x4*)(p + 4) = o1; } }
.LBB0_180:
	v_max_f32_e32 v130, v118, v118
	v_max_f32_e32 v130, 0xc2a00000, v130
	v_mul_f32_e32 v130, 0xbfb8aa3b, v130
	v_exp_f32_e32 v130, v130
	v_sub_f32_e32 v188, 1.0, v172
	v_sub_f32_e32 v187, 1.0, v151
	v_sub_f32_e32 v186, 1.0, v8
	v_add_f32_e32 v130, 1.0, v130
	v_rcp_f32_e32 v130, v130
	v_sub_f32_e32 v185, 1.0, v173
	v_sub_f32_e32 v184, 1.0, v153
	v_sub_f32_e32 v183, 1.0, v181
	v_fma_f32 v130, v130, v188, v172
	v_cmp_gt_f32_e32 vcc, s72, v130
	v_sub_f32_e32 v182, 1.0, v180
	v_sub_f32_e32 v175, 1.0, v174
	v_cndmask_b32_e64 v131, 0, 32, vcc
	v_ldexp_f32 v130, v130, v131
	v_log_f32_e32 v130, v130
	v_lshl_add_u64 v[154:155], v[154:155], 0, v[158:159]
	v_mul_f32_e32 v131, 0x3f317217, v130
	v_fma_f32 v131, v130, s73, -v131
	v_fmac_f32_e32 v131, 0x3377d1cf, v130
	v_fmac_f32_e32 v131, 0x3f317217, v130
	v_cmp_lt_f32_e64 s[0:1], |v130|, s11
	s_nop 1
	v_cndmask_b32_e64 v130, v130, v131, s[0:1]
	v_cndmask_b32_e32 v131, 0, v243, vcc
	v_sub_f32_e32 v130, v130, v131
	v_max_f32_e32 v131, v119, v119
	v_max_f32_e32 v131, 0xc2a00000, v131
	v_mul_f32_e32 v131, 0xbfb8aa3b, v131
	v_exp_f32_e32 v131, v131
	s_nop 0
	v_add_f32_e32 v131, 1.0, v131
	v_rcp_f32_e32 v131, v131
	s_nop 0
	v_fma_f32 v131, v131, v187, v151
	v_cmp_gt_f32_e32 vcc, s72, v131
	s_nop 1
	v_cndmask_b32_e64 v132, 0, 32, vcc
	v_ldexp_f32 v131, v131, v132
	v_log_f32_e32 v131, v131
	s_nop 0
	v_mul_f32_e32 v132, 0x3f317217, v131
	v_fma_f32 v132, v131, s73, -v132
	v_fmac_f32_e32 v132, 0x3377d1cf, v131
	v_fmac_f32_e32 v132, 0x3f317217, v131
	v_cmp_lt_f32_e64 s[0:1], |v131|, s11
	s_nop 1
	v_cndmask_b32_e64 v131, v131, v132, s[0:1]
	v_cndmask_b32_e32 v132, 0, v243, vcc
	v_sub_f32_e32 v131, v131, v132
	v_max_f32_e32 v132, v120, v120
	v_max_f32_e32 v132, 0xc2a00000, v132
	v_mul_f32_e32 v132, 0xbfb8aa3b, v132
	v_exp_f32_e32 v132, v132
	s_nop 0
	v_add_f32_e32 v132, 1.0, v132
	v_rcp_f32_e32 v132, v132
	s_nop 0
	v_fma_f32 v132, v132, v186, v8
	v_cmp_gt_f32_e32 vcc, s72, v132
	s_nop 1
	v_cndmask_b32_e64 v133, 0, 32, vcc
	v_ldexp_f32 v132, v132, v133
	v_log_f32_e32 v132, v132
	s_nop 0
	v_mul_f32_e32 v133, 0x3f317217, v132
	v_fma_f32 v133, v132, s73, -v133
	v_fmac_f32_e32 v133, 0x3377d1cf, v132
	v_fmac_f32_e32 v133, 0x3f317217, v132
	v_cmp_lt_f32_e64 s[0:1], |v132|, s11
	s_nop 1
	v_cndmask_b32_e64 v132, v132, v133, s[0:1]
	v_cndmask_b32_e32 v133, 0, v243, vcc
	v_sub_f32_e32 v132, v132, v133
	v_max_f32_e32 v133, v121, v121
	v_max_f32_e32 v133, 0xc2a00000, v133
	v_mul_f32_e32 v133, 0xbfb8aa3b, v133
	v_exp_f32_e32 v133, v133
	s_nop 0
	v_add_f32_e32 v133, 1.0, v133
	v_rcp_f32_e32 v133, v133
	s_nop 0
	v_fma_f32 v133, v133, v185, v173
	v_cmp_gt_f32_e32 vcc, s72, v133
	s_nop 1
	v_cndmask_b32_e64 v134, 0, 32, vcc
	v_ldexp_f32 v133, v133, v134
	v_log_f32_e32 v133, v133
	s_nop 0
	v_mul_f32_e32 v134, 0x3f317217, v133
	v_fma_f32 v134, v133, s73, -v134
	v_fmac_f32_e32 v134, 0x3377d1cf, v133
	v_fmac_f32_e32 v134, 0x3f317217, v133
	v_cmp_lt_f32_e64 s[0:1], |v133|, s11
	s_nop 1
	v_cndmask_b32_e64 v133, v133, v134, s[0:1]
	v_cndmask_b32_e32 v134, 0, v243, vcc
	v_sub_f32_e32 v133, v133, v134
	v_max_f32_e32 v134, v114, v114
	v_max_f32_e32 v134, 0xc2a00000, v134
	v_mul_f32_e32 v134, 0xbfb8aa3b, v134
	v_exp_f32_e32 v134, v134
	s_nop 0
	v_add_f32_e32 v134, 1.0, v134
	v_rcp_f32_e32 v134, v134
	s_nop 0
	v_fma_f32 v134, v134, v184, v153
	v_cmp_gt_f32_e32 vcc, s72, v134
	s_nop 1
	v_cndmask_b32_e64 v135, 0, 32, vcc
	v_ldexp_f32 v134, v134, v135
	v_log_f32_e32 v134, v134
	s_nop 0
	v_mul_f32_e32 v135, 0x3f317217, v134
	v_fma_f32 v135, v134, s73, -v135
	v_fmac_f32_e32 v135, 0x3377d1cf, v134
	v_fmac_f32_e32 v135, 0x3f317217, v134
	v_cmp_lt_f32_e64 s[0:1], |v134|, s11
	s_nop 1
	v_cndmask_b32_e64 v134, v134, v135, s[0:1]
	v_cndmask_b32_e32 v135, 0, v243, vcc
	v_sub_f32_e32 v134, v134, v135
	v_max_f32_e32 v135, v115, v115
	v_max_f32_e32 v135, 0xc2a00000, v135
	v_mul_f32_e32 v135, 0xbfb8aa3b, v135
	v_exp_f32_e32 v135, v135
	s_nop 0
	v_add_f32_e32 v135, 1.0, v135
	v_rcp_f32_e32 v135, v135
	s_nop 0
	v_fma_f32 v135, v135, v183, v181
	v_cmp_gt_f32_e32 vcc, s72, v135
	s_nop 1
	v_cndmask_b32_e64 v136, 0, 32, vcc
	v_ldexp_f32 v135, v135, v136
	v_log_f32_e32 v135, v135
	s_nop 0
	v_mul_f32_e32 v136, 0x3f317217, v135
	v_fma_f32 v136, v135, s73, -v136
	v_fmac_f32_e32 v136, 0x3377d1cf, v135
	v_fmac_f32_e32 v136, 0x3f317217, v135
	v_cmp_lt_f32_e64 s[0:1], |v135|, s11
	s_nop 1
	v_cndmask_b32_e64 v135, v135, v136, s[0:1]
	v_cndmask_b32_e32 v136, 0, v243, vcc
	v_sub_f32_e32 v135, v135, v136
	v_max_f32_e32 v136, v116, v116
	v_max_f32_e32 v136, 0xc2a00000, v136
	v_mul_f32_e32 v136, 0xbfb8aa3b, v136
	v_exp_f32_e32 v136, v136
	s_nop 0
	v_add_f32_e32 v136, 1.0, v136
	v_rcp_f32_e32 v136, v136
	s_nop 0
	v_fma_f32 v136, v136, v182, v180
	v_cmp_gt_f32_e32 vcc, s72, v136
	s_nop 1
	v_cndmask_b32_e64 v137, 0, 32, vcc
	v_ldexp_f32 v136, v136, v137
	v_log_f32_e32 v136, v136
	s_nop 0
	v_mul_f32_e32 v137, 0x3f317217, v136
	v_fma_f32 v137, v136, s73, -v137
	v_fmac_f32_e32 v137, 0x3377d1cf, v136
	v_fmac_f32_e32 v137, 0x3f317217, v136
	v_cmp_lt_f32_e64 s[0:1], |v136|, s11
	s_nop 1
	v_cndmask_b32_e64 v136, v136, v137, s[0:1]
	v_cndmask_b32_e32 v137, 0, v243, vcc
	v_sub_f32_e32 v136, v136, v137
	v_max_f32_e32 v137, v117, v117
	v_max_f32_e32 v137, 0xc2a00000, v137
	v_mul_f32_e32 v137, 0xbfb8aa3b, v137
	v_exp_f32_e32 v137, v137
	s_nop 0
	v_add_f32_e32 v137, 1.0, v137
	v_rcp_f32_e32 v137, v137
	s_nop 0
	v_fma_f32 v137, v137, v175, v174
	v_cmp_gt_f32_e32 vcc, s72, v137
	s_nop 1
	v_cndmask_b32_e64 v189, 0, 32, vcc
	v_ldexp_f32 v137, v137, v189
	v_log_f32_e32 v137, v137
	s_nop 0
	v_mul_f32_e32 v189, 0x3f317217, v137
	v_fma_f32 v189, v137, s73, -v189
	v_fmac_f32_e32 v189, 0x3377d1cf, v137
; __device__ __forceinline__ float lbound(float h0, float h1) { return 1.f / (1.f + expf(h0 - h1)); }
; __device__ __forceinline__ float logf_gate(float x, float lb) {
;     const float t = __expf(-fmaxf(x, -80.f));
;     return __logf(lb + (1.f - lb) * __builtin_amdgcn_rcpf(1.f + t));
; }
;     __device__ __forceinline__ void operator()(EPI_ARGS) const {
;     ...
;         } else if (seg == 8) {
; #pragma unroll
;             for (int bj = 0; bj < 2; ++bj) { const int c0 = colt + bj * 128 - 8192;
;                 f32x4 lb0 = (f32x4){0.f, 0.f, 0.f, 0.f}, lb1 = lb0;
;                 if (layer != 0) { const f32x4 a0 = *(const f32x4*)(hlb + c0), a1 = *(const f32x4*)(hlb + c0 + 4), b0 = *(const f32x4*)(hlb + WMIX + c0), b1 = *(const f32x4*)(hlb + WMIX + c0 + 4);
;                     lb0 = (f32x4){lbound(a0[0], b0[0]), lbound(a0[1], b0[1]), lbound(a0[2], b0[2]), lbound(a0[3], b0[3])};
;                     lb1 = (f32x4){lbound(a1[0], b1[0]), lbound(a1[1], b1[1]), lbound(a1[2], b1[2]), lbound(a1[3], b1[3])}; }
; #pragma unroll
;                 for (int ai = 0; ai < 2; ++ai)
; #pragma unroll
;                     for (int m = 0; m < 4; ++m) { const int row = row0 + ai * 128 + m * 16;
;                         const f32x4 v0 = acc[ai][bj][m][0], v1 = acc[ai][bj][m][1];
;                         const f32x4 o0 = (f32x4){logf_gate(v0[0], lb0[0]), logf_gate(v0[1], lb0[1]), logf_gate(v0[2], lb0[2]), logf_gate(v0[3], lb0[3])};
;                         const f32x4 o1 = (f32x4){logf_gate(v1[0], lb1[0]), logf_gate(v1[1], lb1[1]), logf_gate(v1[2], lb1[2]), logf_gate(v1[3], lb1[3])};
;                         float* p = lf_out + (size_t)row * WMIX + c0;
;                         *(f32x4*)p = o0; *(f32x4*)(p + 4) = o1; } }
	v_fmac_f32_e32 v189, 0x3f317217, v137
	v_cmp_lt_f32_e64 s[0:1], |v137|, s11
	s_nop 1
	v_cndmask_b32_e64 v137, v137, v189, s[0:1]
	v_cndmask_b32_e32 v189, 0, v243, vcc
	v_sub_f32_e32 v137, v137, v189
	global_store_dwordx4 v[154:155], v[130:133], off sc1
	global_store_dwordx4 v[154:155], v[134:137], off offset:16 sc1
	s_nop 0
	v_max_f32_e32 v130, v102, v102
	v_max_f32_e32 v130, 0xc2a00000, v130
	v_mul_f32_e32 v130, 0xbfb8aa3b, v130
	v_exp_f32_e32 v130, v130
	s_nop 0
	v_add_f32_e32 v130, 1.0, v130
	v_rcp_f32_e32 v130, v130
	s_nop 0
	v_fma_f32 v130, v130, v188, v172
	v_cmp_gt_f32_e32 vcc, s72, v130
	s_nop 1
	v_cndmask_b32_e64 v131, 0, 32, vcc
	v_ldexp_f32 v130, v130, v131
	v_log_f32_e32 v130, v130
	s_nop 0
	v_mul_f32_e32 v131, 0x3f317217, v130
	v_fma_f32 v131, v130, s73, -v131
	v_fmac_f32_e32 v131, 0x3377d1cf, v130
	v_fmac_f32_e32 v131, 0x3f317217, v130
	v_cmp_lt_f32_e64 s[0:1], |v130|, s11
	s_nop 1
	v_cndmask_b32_e64 v130, v130, v131, s[0:1]
	v_cndmask_b32_e32 v131, 0, v243, vcc
	v_sub_f32_e32 v130, v130, v131
	v_max_f32_e32 v131, v103, v103
	v_max_f32_e32 v131, 0xc2a00000, v131
	v_mul_f32_e32 v131, 0xbfb8aa3b, v131
	v_exp_f32_e32 v131, v131
	s_nop 0
	v_add_f32_e32 v131, 1.0, v131
	v_rcp_f32_e32 v131, v131
	s_nop 0
	v_fma_f32 v131, v131, v187, v151
	v_cmp_gt_f32_e32 vcc, s72, v131
	s_nop 1
	v_cndmask_b32_e64 v132, 0, 32, vcc
	v_ldexp_f32 v131, v131, v132
	v_log_f32_e32 v131, v131
	s_nop 0
	v_mul_f32_e32 v132, 0x3f317217, v131
	v_fma_f32 v132, v131, s73, -v132
	v_fmac_f32_e32 v132, 0x3377d1cf, v131
	v_fmac_f32_e32 v132, 0x3f317217, v131
	v_cmp_lt_f32_e64 s[0:1], |v131|, s11
	s_nop 1
	v_cndmask_b32_e64 v131, v131, v132, s[0:1]
	v_cndmask_b32_e32 v132, 0, v243, vcc
	v_sub_f32_e32 v131, v131, v132
	v_max_f32_e32 v132, v104, v104
	v_max_f32_e32 v132, 0xc2a00000, v132
	v_mul_f32_e32 v132, 0xbfb8aa3b, v132
	v_exp_f32_e32 v132, v132
	s_nop 0
	v_add_f32_e32 v132, 1.0, v132
	v_rcp_f32_e32 v132, v132
	s_nop 0
	v_fma_f32 v132, v132, v186, v8
	v_cmp_gt_f32_e32 vcc, s72, v132
	s_nop 1
	v_cndmask_b32_e64 v133, 0, 32, vcc
	v_ldexp_f32 v132, v132, v133
	v_log_f32_e32 v132, v132
	s_nop 0
	v_mul_f32_e32 v133, 0x3f317217, v132
	v_fma_f32 v133, v132, s73, -v133
	v_fmac_f32_e32 v133, 0x3377d1cf, v132
	v_fmac_f32_e32 v133, 0x3f317217, v132
	v_cmp_lt_f32_e64 s[0:1], |v132|, s11
	s_nop 1
	v_cndmask_b32_e64 v132, v132, v133, s[0:1]
	v_cndmask_b32_e32 v133, 0, v243, vcc
	v_sub_f32_e32 v132, v132, v133
	v_max_f32_e32 v133, v105, v105
	v_max_f32_e32 v133, 0xc2a00000, v133
	v_mul_f32_e32 v133, 0xbfb8aa3b, v133
	v_exp_f32_e32 v133, v133
	s_nop 0
	v_add_f32_e32 v133, 1.0, v133
	v_rcp_f32_e32 v133, v133
	s_nop 0
	v_fma_f32 v133, v133, v185, v173
	v_cmp_gt_f32_e32 vcc, s72, v133
	s_nop 1
	v_cndmask_b32_e64 v134, 0, 32, vcc
	v_ldexp_f32 v133, v133, v134
	v_log_f32_e32 v133, v133
	s_nop 0
	v_mul_f32_e32 v134, 0x3f317217, v133
	v_fma_f32 v134, v133, s73, -v134
	v_fmac_f32_e32 v134, 0x3377d1cf, v133
	v_fmac_f32_e32 v134, 0x3f317217, v133
	v_cmp_lt_f32_e64 s[0:1], |v133|, s11
	s_nop 1
	v_cndmask_b32_e64 v133, v133, v134, s[0:1]
	v_cndmask_b32_e32 v134, 0, v243, vcc
	v_sub_f32_e32 v133, v133, v134
	v_max_f32_e32 v134, v98, v98
	v_max_f32_e32 v134, 0xc2a00000, v134
	v_mul_f32_e32 v134, 0xbfb8aa3b, v134
	v_exp_f32_e32 v134, v134
	s_nop 0
	v_add_f32_e32 v134, 1.0, v134
	v_rcp_f32_e32 v134, v134
	s_nop 0
	v_fma_f32 v134, v134, v184, v153
	v_cmp_gt_f32_e32 vcc, s72, v134
	s_nop 1
	v_cndmask_b32_e64 v135, 0, 32, vcc
	v_ldexp_f32 v134, v134, v135
	v_log_f32_e32 v134, v134
	s_nop 0
	v_mul_f32_e32 v135, 0x3f317217, v134
	v_fma_f32 v135, v134, s73, -v135
	v_fmac_f32_e32 v135, 0x3377d1cf, v134
	v_fmac_f32_e32 v135, 0x3f317217, v134
	v_cmp_lt_f32_e64 s[0:1], |v134|, s11
	s_nop 1
	v_cndmask_b32_e64 v134, v134, v135, s[0:1]
	v_cndmask_b32_e32 v135, 0, v243, vcc
	v_sub_f32_e32 v134, v134, v135
	v_max_f32_e32 v135, v99, v99
	v_max_f32_e32 v135, 0xc2a00000, v135
	v_mul_f32_e32 v135, 0xbfb8aa3b, v135
	v_exp_f32_e32 v135, v135
	s_nop 0
	v_add_f32_e32 v135, 1.0, v135
	v_rcp_f32_e32 v135, v135
	s_nop 0
	v_fma_f32 v135, v135, v183, v181
	v_cmp_gt_f32_e32 vcc, s72, v135
	s_nop 1
	v_cndmask_b32_e64 v136, 0, 32, vcc
	v_ldexp_f32 v135, v135, v136
	v_log_f32_e32 v135, v135
	s_nop 0
	v_mul_f32_e32 v136, 0x3f317217, v135
	v_fma_f32 v136, v135, s73, -v136
	v_fmac_f32_e32 v136, 0x3377d1cf, v135
	v_fmac_f32_e32 v136, 0x3f317217, v135
	v_cmp_lt_f32_e64 s[0:1], |v135|, s11
	s_nop 1
	v_cndmask_b32_e64 v135, v135, v136, s[0:1]
	v_cndmask_b32_e32 v136, 0, v243, vcc
	v_sub_f32_e32 v135, v135, v136
	v_max_f32_e32 v136, v100, v100
	v_max_f32_e32 v136, 0xc2a00000, v136
	v_mul_f32_e32 v136, 0xbfb8aa3b, v136
	v_exp_f32_e32 v136, v136
	s_nop 0
	v_add_f32_e32 v136, 1.0, v136
	v_rcp_f32_e32 v136, v136
	s_nop 0
	v_fma_f32 v136, v136, v182, v180
	v_cmp_gt_f32_e32 vcc, s72, v136
	s_nop 1
	v_cndmask_b32_e64 v137, 0, 32, vcc
	v_ldexp_f32 v136, v136, v137
	v_log_f32_e32 v136, v136
	s_nop 0
	v_mul_f32_e32 v137, 0x3f317217, v136
	v_fma_f32 v137, v136, s73, -v137
	v_fmac_f32_e32 v137, 0x3377d1cf, v136
	v_fmac_f32_e32 v137, 0x3f317217, v136
	v_cmp_lt_f32_e64 s[0:1], |v136|, s11
	s_nop 1
	v_cndmask_b32_e64 v136, v136, v137, s[0:1]
	v_cndmask_b32_e32 v137, 0, v243, vcc
	v_sub_f32_e32 v136, v136, v137
	v_max_f32_e32 v137, v101, v101
	v_max_f32_e32 v137, 0xc2a00000, v137
	v_mul_f32_e32 v137, 0xbfb8aa3b, v137
	v_exp_f32_e32 v137, v137
	s_nop 0
	v_add_f32_e32 v137, 1.0, v137
	v_rcp_f32_e32 v137, v137
	s_nop 0
	v_fma_f32 v137, v137, v175, v174
	v_cmp_gt_f32_e32 vcc, s72, v137
	s_nop 1
	v_cndmask_b32_e64 v154, 0, 32, vcc
	v_ldexp_f32 v137, v137, v154
	v_log_f32_e32 v137, v137
	s_nop 0
	v_mul_f32_e32 v154, 0x3f317217, v137
; __device__ __forceinline__ float lbound(float h0, float h1) { return 1.f / (1.f + expf(h0 - h1)); }
; __device__ __forceinline__ float logf_gate(float x, float lb) {
;     const float t = __expf(-fmaxf(x, -80.f));
;     return __logf(lb + (1.f - lb) * __builtin_amdgcn_rcpf(1.f + t));
; }
;     __device__ __forceinline__ void operator()(EPI_ARGS) const {
;     ...
;         } else if (seg == 8) {
; #pragma unroll
;             for (int bj = 0; bj < 2; ++bj) { const int c0 = colt + bj * 128 - 8192;
;                 f32x4 lb0 = (f32x4){0.f, 0.f, 0.f, 0.f}, lb1 = lb0;
;                 if (layer != 0) { const f32x4 a0 = *(const f32x4*)(hlb + c0), a1 = *(const f32x4*)(hlb + c0 + 4), b0 = *(const f32x4*)(hlb + WMIX + c0), b1 = *(const f32x4*)(hlb + WMIX + c0 + 4);
;                     lb0 = (f32x4){lbound(a0[0], b0[0]), lbound(a0[1], b0[1]), lbound(a0[2], b0[2]), lbound(a0[3], b0[3])};
;                     lb1 = (f32x4){lbound(a1[0], b1[0]), lbound(a1[1], b1[1]), lbound(a1[2], b1[2]), lbound(a1[3], b1[3])}; }
; #pragma unroll
;                 for (int ai = 0; ai < 2; ++ai)
; #pragma unroll
;                     for (int m = 0; m < 4; ++m) { const int row = row0 + ai * 128 + m * 16;
;                         const f32x4 v0 = acc[ai][bj][m][0], v1 = acc[ai][bj][m][1];
;                         const f32x4 o0 = (f32x4){logf_gate(v0[0], lb0[0]), logf_gate(v0[1], lb0[1]), logf_gate(v0[2], lb0[2]), logf_gate(v0[3], lb0[3])};
;                         const f32x4 o1 = (f32x4){logf_gate(v1[0], lb1[0]), logf_gate(v1[1], lb1[1]), logf_gate(v1[2], lb1[2]), logf_gate(v1[3], lb1[3])};
;                         float* p = lf_out + (size_t)row * WMIX + c0;
;                         *(f32x4*)p = o0; *(f32x4*)(p + 4) = o1; } }
	v_fma_f32 v154, v137, s73, -v154
	v_fmac_f32_e32 v154, 0x3377d1cf, v137
	v_fmac_f32_e32 v154, 0x3f317217, v137
	v_cmp_lt_f32_e64 s[0:1], |v137|, s11
	s_nop 1
	v_cndmask_b32_e64 v137, v137, v154, s[0:1]
	v_cndmask_b32_e32 v154, 0, v243, vcc
	v_sub_f32_e32 v137, v137, v154
	v_lshl_add_u64 v[154:155], v[156:157], 0, v[158:159]
	global_store_dwordx4 v[154:155], v[130:133], off sc1
	global_store_dwordx4 v[154:155], v[134:137], off offset:16 sc1
	s_nop 0
	v_max_f32_e32 v130, v86, v86
	v_max_f32_e32 v130, 0xc2a00000, v130
	v_mul_f32_e32 v130, 0xbfb8aa3b, v130
	v_exp_f32_e32 v130, v130
	s_nop 0
	v_add_f32_e32 v130, 1.0, v130
	v_rcp_f32_e32 v130, v130
	s_nop 0
	v_fma_f32 v130, v130, v188, v172
	v_cmp_gt_f32_e32 vcc, s72, v130
	s_nop 1
	v_cndmask_b32_e64 v131, 0, 32, vcc
	v_ldexp_f32 v130, v130, v131
	v_log_f32_e32 v130, v130
	s_nop 0
	v_mul_f32_e32 v131, 0x3f317217, v130
	v_fma_f32 v131, v130, s73, -v131
	v_fmac_f32_e32 v131, 0x3377d1cf, v130
	v_fmac_f32_e32 v131, 0x3f317217, v130
	v_cmp_lt_f32_e64 s[0:1], |v130|, s11
	s_nop 1
	v_cndmask_b32_e64 v130, v130, v131, s[0:1]
	v_cndmask_b32_e32 v131, 0, v243, vcc
	v_sub_f32_e32 v130, v130, v131
	v_max_f32_e32 v131, v87, v87
	v_max_f32_e32 v131, 0xc2a00000, v131
	v_mul_f32_e32 v131, 0xbfb8aa3b, v131
	v_exp_f32_e32 v131, v131
	s_nop 0
	v_add_f32_e32 v131, 1.0, v131
	v_rcp_f32_e32 v131, v131
	s_nop 0
	v_fma_f32 v131, v131, v187, v151
	v_cmp_gt_f32_e32 vcc, s72, v131
	s_nop 1
	v_cndmask_b32_e64 v132, 0, 32, vcc
	v_ldexp_f32 v131, v131, v132
	v_log_f32_e32 v131, v131
	s_nop 0
	v_mul_f32_e32 v132, 0x3f317217, v131
	v_fma_f32 v132, v131, s73, -v132
	v_fmac_f32_e32 v132, 0x3377d1cf, v131
	v_fmac_f32_e32 v132, 0x3f317217, v131
	v_cmp_lt_f32_e64 s[0:1], |v131|, s11
	s_nop 1
	v_cndmask_b32_e64 v131, v131, v132, s[0:1]
	v_cndmask_b32_e32 v132, 0, v243, vcc
	v_sub_f32_e32 v131, v131, v132
	v_max_f32_e32 v132, v88, v88
	v_max_f32_e32 v132, 0xc2a00000, v132
	v_mul_f32_e32 v132, 0xbfb8aa3b, v132
	v_exp_f32_e32 v132, v132
	s_nop 0
	v_add_f32_e32 v132, 1.0, v132
	v_rcp_f32_e32 v132, v132
	s_nop 0
	v_fma_f32 v132, v132, v186, v8
	v_cmp_gt_f32_e32 vcc, s72, v132
	s_nop 1
	v_cndmask_b32_e64 v133, 0, 32, vcc
	v_ldexp_f32 v132, v132, v133
	v_log_f32_e32 v132, v132
	s_nop 0
	v_mul_f32_e32 v133, 0x3f317217, v132
	v_fma_f32 v133, v132, s73, -v133
	v_fmac_f32_e32 v133, 0x3377d1cf, v132
	v_fmac_f32_e32 v133, 0x3f317217, v132
	v_cmp_lt_f32_e64 s[0:1], |v132|, s11
	s_nop 1
	v_cndmask_b32_e64 v132, v132, v133, s[0:1]
	v_cndmask_b32_e32 v133, 0, v243, vcc
	v_sub_f32_e32 v132, v132, v133
	v_max_f32_e32 v133, v89, v89
	v_max_f32_e32 v133, 0xc2a00000, v133
	v_mul_f32_e32 v133, 0xbfb8aa3b, v133
	v_exp_f32_e32 v133, v133
	s_nop 0
	v_add_f32_e32 v133, 1.0, v133
	v_rcp_f32_e32 v133, v133
	s_nop 0
	v_fma_f32 v133, v133, v185, v173
	v_cmp_gt_f32_e32 vcc, s72, v133
	s_nop 1
	v_cndmask_b32_e64 v134, 0, 32, vcc
	v_ldexp_f32 v133, v133, v134
	v_log_f32_e32 v133, v133
	s_nop 0
	v_mul_f32_e32 v134, 0x3f317217, v133
	v_fma_f32 v134, v133, s73, -v134
	v_fmac_f32_e32 v134, 0x3377d1cf, v133
	v_fmac_f32_e32 v134, 0x3f317217, v133
	v_cmp_lt_f32_e64 s[0:1], |v133|, s11
	s_nop 1
	v_cndmask_b32_e64 v133, v133, v134, s[0:1]
	v_cndmask_b32_e32 v134, 0, v243, vcc
	v_sub_f32_e32 v133, v133, v134
	v_max_f32_e32 v134, v82, v82
	v_max_f32_e32 v134, 0xc2a00000, v134
	v_mul_f32_e32 v134, 0xbfb8aa3b, v134
	v_exp_f32_e32 v134, v134
	s_nop 0
	v_add_f32_e32 v134, 1.0, v134
	v_rcp_f32_e32 v134, v134
	s_nop 0
	v_fma_f32 v134, v134, v184, v153
	v_cmp_gt_f32_e32 vcc, s72, v134
	s_nop 1
	v_cndmask_b32_e64 v135, 0, 32, vcc
	v_ldexp_f32 v134, v134, v135
	v_log_f32_e32 v134, v134
	s_nop 0
	v_mul_f32_e32 v135, 0x3f317217, v134
	v_fma_f32 v135, v134, s73, -v135
	v_fmac_f32_e32 v135, 0x3377d1cf, v134
	v_fmac_f32_e32 v135, 0x3f317217, v134
	v_cmp_lt_f32_e64 s[0:1], |v134|, s11
	s_nop 1
	v_cndmask_b32_e64 v134, v134, v135, s[0:1]
	v_cndmask_b32_e32 v135, 0, v243, vcc
	v_sub_f32_e32 v134, v134, v135
	v_max_f32_e32 v135, v83, v83
	v_max_f32_e32 v135, 0xc2a00000, v135
	v_mul_f32_e32 v135, 0xbfb8aa3b, v135
	v_exp_f32_e32 v135, v135
	s_nop 0
	v_add_f32_e32 v135, 1.0, v135
	v_rcp_f32_e32 v135, v135
	s_nop 0
	v_fma_f32 v135, v135, v183, v181
	v_cmp_gt_f32_e32 vcc, s72, v135
	s_nop 1
	v_cndmask_b32_e64 v136, 0, 32, vcc
	v_ldexp_f32 v135, v135, v136
	v_log_f32_e32 v135, v135
	s_nop 0
	v_mul_f32_e32 v136, 0x3f317217, v135
	v_fma_f32 v136, v135, s73, -v136
	v_fmac_f32_e32 v136, 0x3377d1cf, v135
	v_fmac_f32_e32 v136, 0x3f317217, v135
	v_cmp_lt_f32_e64 s[0:1], |v135|, s11
	s_nop 1
	v_cndmask_b32_e64 v135, v135, v136, s[0:1]
	v_cndmask_b32_e32 v136, 0, v243, vcc
	v_sub_f32_e32 v135, v135, v136
	v_max_f32_e32 v136, v84, v84
	v_max_f32_e32 v136, 0xc2a00000, v136
	v_mul_f32_e32 v136, 0xbfb8aa3b, v136
	v_exp_f32_e32 v136, v136
	s_nop 0
	v_add_f32_e32 v136, 1.0, v136
	v_rcp_f32_e32 v136, v136
	s_nop 0
	v_fma_f32 v136, v136, v182, v180
	v_cmp_gt_f32_e32 vcc, s72, v136
	s_nop 1
	v_cndmask_b32_e64 v137, 0, 32, vcc
	v_ldexp_f32 v136, v136, v137
	v_log_f32_e32 v136, v136
	s_nop 0
	v_mul_f32_e32 v137, 0x3f317217, v136
	v_fma_f32 v137, v136, s73, -v137
	v_fmac_f32_e32 v137, 0x3377d1cf, v136
	v_fmac_f32_e32 v137, 0x3f317217, v136
	v_cmp_lt_f32_e64 s[0:1], |v136|, s11
	s_nop 1
	v_cndmask_b32_e64 v136, v136, v137, s[0:1]
	v_cndmask_b32_e32 v137, 0, v243, vcc
	v_sub_f32_e32 v136, v136, v137
	v_max_f32_e32 v137, v85, v85
	v_max_f32_e32 v137, 0xc2a00000, v137
	v_mul_f32_e32 v137, 0xbfb8aa3b, v137
	v_exp_f32_e32 v137, v137
	s_nop 0
	v_add_f32_e32 v137, 1.0, v137
	v_rcp_f32_e32 v137, v137
	s_nop 0
	v_fma_f32 v137, v137, v175, v174
	v_cmp_gt_f32_e32 vcc, s72, v137
	s_nop 1
	v_cndmask_b32_e64 v154, 0, 32, vcc
; __device__ __forceinline__ float lbound(float h0, float h1) { return 1.f / (1.f + expf(h0 - h1)); }
; __device__ __forceinline__ float logf_gate(float x, float lb) {
;     const float t = __expf(-fmaxf(x, -80.f));
;     return __logf(lb + (1.f - lb) * __builtin_amdgcn_rcpf(1.f + t));
; }
;     __device__ __forceinline__ void operator()(EPI_ARGS) const {
;     ...
;         } else if (seg == 8) {
; #pragma unroll
;             for (int bj = 0; bj < 2; ++bj) { const int c0 = colt + bj * 128 - 8192;
;                 f32x4 lb0 = (f32x4){0.f, 0.f, 0.f, 0.f}, lb1 = lb0;
;                 if (layer != 0) { const f32x4 a0 = *(const f32x4*)(hlb + c0), a1 = *(const f32x4*)(hlb + c0 + 4), b0 = *(const f32x4*)(hlb + WMIX + c0), b1 = *(const f32x4*)(hlb + WMIX + c0 + 4);
;                     lb0 = (f32x4){lbound(a0[0], b0[0]), lbound(a0[1], b0[1]), lbound(a0[2], b0[2]), lbound(a0[3], b0[3])};
;                     lb1 = (f32x4){lbound(a1[0], b1[0]), lbound(a1[1], b1[1]), lbound(a1[2], b1[2]), lbound(a1[3], b1[3])}; }
; #pragma unroll
;                 for (int ai = 0; ai < 2; ++ai)
; #pragma unroll
;                     for (int m = 0; m < 4; ++m) { const int row = row0 + ai * 128 + m * 16;
;                         const f32x4 v0 = acc[ai][bj][m][0], v1 = acc[ai][bj][m][1];
;                         const f32x4 o0 = (f32x4){logf_gate(v0[0], lb0[0]), logf_gate(v0[1], lb0[1]), logf_gate(v0[2], lb0[2]), logf_gate(v0[3], lb0[3])};
;                         const f32x4 o1 = (f32x4){logf_gate(v1[0], lb1[0]), logf_gate(v1[1], lb1[1]), logf_gate(v1[2], lb1[2]), logf_gate(v1[3], lb1[3])};
;                         float* p = lf_out + (size_t)row * WMIX + c0;
;                         *(f32x4*)p = o0; *(f32x4*)(p + 4) = o1; } }
	v_ldexp_f32 v137, v137, v154
	v_log_f32_e32 v137, v137
	s_nop 0
	v_mul_f32_e32 v154, 0x3f317217, v137
	v_fma_f32 v154, v137, s73, -v154
	v_fmac_f32_e32 v154, 0x3377d1cf, v137
	v_fmac_f32_e32 v154, 0x3f317217, v137
	v_cmp_lt_f32_e64 s[0:1], |v137|, s11
	s_nop 1
	v_cndmask_b32_e64 v137, v137, v154, s[0:1]
	v_cndmask_b32_e32 v154, 0, v243, vcc
	v_sub_f32_e32 v137, v137, v154
	v_lshl_add_u64 v[154:155], v[160:161], 0, v[158:159]
	global_store_dwordx4 v[154:155], v[130:133], off sc1
	global_store_dwordx4 v[154:155], v[134:137], off offset:16 sc1
	s_nop 0
	v_max_f32_e32 v130, v70, v70
	v_max_f32_e32 v130, 0xc2a00000, v130
	v_mul_f32_e32 v130, 0xbfb8aa3b, v130
	v_exp_f32_e32 v130, v130
	s_nop 0
	v_add_f32_e32 v130, 1.0, v130
	v_rcp_f32_e32 v130, v130
	s_nop 0
	v_fma_f32 v130, v130, v188, v172
	v_cmp_gt_f32_e32 vcc, s72, v130
	s_nop 1
	v_cndmask_b32_e64 v131, 0, 32, vcc
	v_ldexp_f32 v130, v130, v131
	v_log_f32_e32 v130, v130
	s_nop 0
	v_mul_f32_e32 v131, 0x3f317217, v130
	v_fma_f32 v131, v130, s73, -v131
	v_fmac_f32_e32 v131, 0x3377d1cf, v130
	v_fmac_f32_e32 v131, 0x3f317217, v130
	v_cmp_lt_f32_e64 s[0:1], |v130|, s11
	s_nop 1
	v_cndmask_b32_e64 v130, v130, v131, s[0:1]
	v_cndmask_b32_e32 v131, 0, v243, vcc
	v_sub_f32_e32 v130, v130, v131
	v_max_f32_e32 v131, v71, v71
	v_max_f32_e32 v131, 0xc2a00000, v131
	v_mul_f32_e32 v131, 0xbfb8aa3b, v131
	v_exp_f32_e32 v131, v131
	s_nop 0
	v_add_f32_e32 v131, 1.0, v131
	v_rcp_f32_e32 v131, v131
	s_nop 0
	v_fma_f32 v131, v131, v187, v151
	v_cmp_gt_f32_e32 vcc, s72, v131
	s_nop 1
	v_cndmask_b32_e64 v132, 0, 32, vcc
	v_ldexp_f32 v131, v131, v132
	v_log_f32_e32 v131, v131
	s_nop 0
	v_mul_f32_e32 v132, 0x3f317217, v131
	v_fma_f32 v132, v131, s73, -v132
	v_fmac_f32_e32 v132, 0x3377d1cf, v131
	v_fmac_f32_e32 v132, 0x3f317217, v131
	v_cmp_lt_f32_e64 s[0:1], |v131|, s11
	s_nop 1
	v_cndmask_b32_e64 v131, v131, v132, s[0:1]
	v_cndmask_b32_e32 v132, 0, v243, vcc
	v_sub_f32_e32 v131, v131, v132
	v_max_f32_e32 v132, v72, v72
	v_max_f32_e32 v132, 0xc2a00000, v132
	v_mul_f32_e32 v132, 0xbfb8aa3b, v132
	v_exp_f32_e32 v132, v132
	s_nop 0
	v_add_f32_e32 v132, 1.0, v132
	v_rcp_f32_e32 v132, v132
	s_nop 0
	v_fma_f32 v132, v132, v186, v8
	v_cmp_gt_f32_e32 vcc, s72, v132
	s_nop 1
	v_cndmask_b32_e64 v133, 0, 32, vcc
	v_ldexp_f32 v132, v132, v133
	v_log_f32_e32 v132, v132
	s_nop 0
	v_mul_f32_e32 v133, 0x3f317217, v132
	v_fma_f32 v133, v132, s73, -v133
	v_fmac_f32_e32 v133, 0x3377d1cf, v132
	v_fmac_f32_e32 v133, 0x3f317217, v132
	v_cmp_lt_f32_e64 s[0:1], |v132|, s11
	s_nop 1
	v_cndmask_b32_e64 v132, v132, v133, s[0:1]
	v_cndmask_b32_e32 v133, 0, v243, vcc
	v_sub_f32_e32 v132, v132, v133
	v_max_f32_e32 v133, v73, v73
	v_max_f32_e32 v133, 0xc2a00000, v133
	v_mul_f32_e32 v133, 0xbfb8aa3b, v133
	v_exp_f32_e32 v133, v133
	s_nop 0
	v_add_f32_e32 v133, 1.0, v133
	v_rcp_f32_e32 v133, v133
	s_nop 0
	v_fma_f32 v133, v133, v185, v173
	v_cmp_gt_f32_e32 vcc, s72, v133
	s_nop 1
	v_cndmask_b32_e64 v134, 0, 32, vcc
	v_ldexp_f32 v133, v133, v134
	v_log_f32_e32 v133, v133
	s_nop 0
	v_mul_f32_e32 v134, 0x3f317217, v133
	v_fma_f32 v134, v133, s73, -v134
	v_fmac_f32_e32 v134, 0x3377d1cf, v133
	v_fmac_f32_e32 v134, 0x3f317217, v133
	v_cmp_lt_f32_e64 s[0:1], |v133|, s11
	s_nop 1
	v_cndmask_b32_e64 v133, v133, v134, s[0:1]
	v_cndmask_b32_e32 v134, 0, v243, vcc
	v_sub_f32_e32 v133, v133, v134
	v_max_f32_e32 v134, v66, v66
	v_max_f32_e32 v134, 0xc2a00000, v134
	v_mul_f32_e32 v134, 0xbfb8aa3b, v134
	v_exp_f32_e32 v134, v134
	s_nop 0
	v_add_f32_e32 v134, 1.0, v134
	v_rcp_f32_e32 v134, v134
	s_nop 0
	v_fma_f32 v134, v134, v184, v153
	v_cmp_gt_f32_e32 vcc, s72, v134
	s_nop 1
	v_cndmask_b32_e64 v135, 0, 32, vcc
	v_ldexp_f32 v134, v134, v135
	v_log_f32_e32 v134, v134
	s_nop 0
	v_mul_f32_e32 v135, 0x3f317217, v134
	v_fma_f32 v135, v134, s73, -v135
	v_fmac_f32_e32 v135, 0x3377d1cf, v134
	v_fmac_f32_e32 v135, 0x3f317217, v134
	v_cmp_lt_f32_e64 s[0:1], |v134|, s11
	s_nop 1
	v_cndmask_b32_e64 v134, v134, v135, s[0:1]
	v_cndmask_b32_e32 v135, 0, v243, vcc
	v_sub_f32_e32 v134, v134, v135
	v_max_f32_e32 v135, v67, v67
	v_max_f32_e32 v135, 0xc2a00000, v135
	v_mul_f32_e32 v135, 0xbfb8aa3b, v135
	v_exp_f32_e32 v135, v135
	s_nop 0
	v_add_f32_e32 v135, 1.0, v135
	v_rcp_f32_e32 v135, v135
	s_nop 0
	v_fma_f32 v135, v135, v183, v181
	v_cmp_gt_f32_e32 vcc, s72, v135
	s_nop 1
	v_cndmask_b32_e64 v136, 0, 32, vcc
	v_ldexp_f32 v135, v135, v136
	v_log_f32_e32 v135, v135
	s_nop 0
	v_mul_f32_e32 v136, 0x3f317217, v135
	v_fma_f32 v136, v135, s73, -v136
	v_fmac_f32_e32 v136, 0x3377d1cf, v135
	v_fmac_f32_e32 v136, 0x3f317217, v135
	v_cmp_lt_f32_e64 s[0:1], |v135|, s11
	s_nop 1
	v_cndmask_b32_e64 v135, v135, v136, s[0:1]
	v_cndmask_b32_e32 v136, 0, v243, vcc
	v_sub_f32_e32 v135, v135, v136
	v_max_f32_e32 v136, v68, v68
	v_max_f32_e32 v136, 0xc2a00000, v136
	v_mul_f32_e32 v136, 0xbfb8aa3b, v136
	v_exp_f32_e32 v136, v136
	s_nop 0
	v_add_f32_e32 v136, 1.0, v136
	v_rcp_f32_e32 v136, v136
	s_nop 0
	v_fma_f32 v136, v136, v182, v180
	v_cmp_gt_f32_e32 vcc, s72, v136
	s_nop 1
	v_cndmask_b32_e64 v137, 0, 32, vcc
	v_ldexp_f32 v136, v136, v137
	v_log_f32_e32 v136, v136
	s_nop 0
	v_mul_f32_e32 v137, 0x3f317217, v136
	v_fma_f32 v137, v136, s73, -v137
	v_fmac_f32_e32 v137, 0x3377d1cf, v136
	v_fmac_f32_e32 v137, 0x3f317217, v136
	v_cmp_lt_f32_e64 s[0:1], |v136|, s11
	s_nop 1
	v_cndmask_b32_e64 v136, v136, v137, s[0:1]
	v_cndmask_b32_e32 v137, 0, v243, vcc
	v_sub_f32_e32 v136, v136, v137
	v_max_f32_e32 v137, v69, v69
	v_max_f32_e32 v137, 0xc2a00000, v137
	v_mul_f32_e32 v137, 0xbfb8aa3b, v137
	v_exp_f32_e32 v137, v137
	s_nop 0
	v_add_f32_e32 v137, 1.0, v137
	v_rcp_f32_e32 v137, v137
	s_nop 0
; __device__ __forceinline__ float lbound(float h0, float h1) { return 1.f / (1.f + expf(h0 - h1)); }
; __device__ __forceinline__ float logf_gate(float x, float lb) {
;     const float t = __expf(-fmaxf(x, -80.f));
;     return __logf(lb + (1.f - lb) * __builtin_amdgcn_rcpf(1.f + t));
; }
;     __device__ __forceinline__ void operator()(EPI_ARGS) const {
;     ...
;         } else if (seg == 8) {
; #pragma unroll
;             for (int bj = 0; bj < 2; ++bj) { const int c0 = colt + bj * 128 - 8192;
;                 f32x4 lb0 = (f32x4){0.f, 0.f, 0.f, 0.f}, lb1 = lb0;
;                 if (layer != 0) { const f32x4 a0 = *(const f32x4*)(hlb + c0), a1 = *(const f32x4*)(hlb + c0 + 4), b0 = *(const f32x4*)(hlb + WMIX + c0), b1 = *(const f32x4*)(hlb + WMIX + c0 + 4);
;                     lb0 = (f32x4){lbound(a0[0], b0[0]), lbound(a0[1], b0[1]), lbound(a0[2], b0[2]), lbound(a0[3], b0[3])};
;                     lb1 = (f32x4){lbound(a1[0], b1[0]), lbound(a1[1], b1[1]), lbound(a1[2], b1[2]), lbound(a1[3], b1[3])}; }
; #pragma unroll
;                 for (int ai = 0; ai < 2; ++ai)
; #pragma unroll
;                     for (int m = 0; m < 4; ++m) { const int row = row0 + ai * 128 + m * 16;
;                         const f32x4 v0 = acc[ai][bj][m][0], v1 = acc[ai][bj][m][1];
;                         const f32x4 o0 = (f32x4){logf_gate(v0[0], lb0[0]), logf_gate(v0[1], lb0[1]), logf_gate(v0[2], lb0[2]), logf_gate(v0[3], lb0[3])};
;                         const f32x4 o1 = (f32x4){logf_gate(v1[0], lb1[0]), logf_gate(v1[1], lb1[1]), logf_gate(v1[2], lb1[2]), logf_gate(v1[3], lb1[3])};
;                         float* p = lf_out + (size_t)row * WMIX + c0;
;                         *(f32x4*)p = o0; *(f32x4*)(p + 4) = o1; } }
	v_fma_f32 v137, v137, v175, v174
	v_cmp_gt_f32_e32 vcc, s72, v137
	s_nop 1
	v_cndmask_b32_e64 v154, 0, 32, vcc
	v_ldexp_f32 v137, v137, v154
	v_log_f32_e32 v137, v137
	s_nop 0
	v_mul_f32_e32 v154, 0x3f317217, v137
	v_fma_f32 v154, v137, s73, -v154
	v_fmac_f32_e32 v154, 0x3377d1cf, v137
	v_fmac_f32_e32 v154, 0x3f317217, v137
	v_cmp_lt_f32_e64 s[0:1], |v137|, s11
	s_nop 1
	v_cndmask_b32_e64 v137, v137, v154, s[0:1]
	v_cndmask_b32_e32 v154, 0, v243, vcc
	v_sub_f32_e32 v137, v137, v154
	v_lshl_add_u64 v[154:155], v[162:163], 0, v[158:159]
	global_store_dwordx4 v[154:155], v[130:133], off sc1
	global_store_dwordx4 v[154:155], v[134:137], off offset:16 sc1
	s_nop 0
	v_max_f32_e32 v130, v54, v54
	v_max_f32_e32 v130, 0xc2a00000, v130
	v_mul_f32_e32 v130, 0xbfb8aa3b, v130
	v_exp_f32_e32 v130, v130
	s_nop 0
	v_add_f32_e32 v130, 1.0, v130
	v_rcp_f32_e32 v130, v130
	s_nop 0
	v_fma_f32 v130, v130, v188, v172
	v_cmp_gt_f32_e32 vcc, s72, v130
	s_nop 1
	v_cndmask_b32_e64 v131, 0, 32, vcc
	v_ldexp_f32 v130, v130, v131
	v_log_f32_e32 v130, v130
	s_nop 0
	v_mul_f32_e32 v131, 0x3f317217, v130
	v_fma_f32 v131, v130, s73, -v131
	v_fmac_f32_e32 v131, 0x3377d1cf, v130
	v_fmac_f32_e32 v131, 0x3f317217, v130
	v_cmp_lt_f32_e64 s[0:1], |v130|, s11
	s_nop 1
	v_cndmask_b32_e64 v130, v130, v131, s[0:1]
	v_cndmask_b32_e32 v131, 0, v243, vcc
	v_sub_f32_e32 v130, v130, v131
	v_max_f32_e32 v131, v55, v55
	v_max_f32_e32 v131, 0xc2a00000, v131
	v_mul_f32_e32 v131, 0xbfb8aa3b, v131
	v_exp_f32_e32 v131, v131
	s_nop 0
	v_add_f32_e32 v131, 1.0, v131
	v_rcp_f32_e32 v131, v131
	s_nop 0
	v_fma_f32 v131, v131, v187, v151
	v_cmp_gt_f32_e32 vcc, s72, v131
	s_nop 1
	v_cndmask_b32_e64 v132, 0, 32, vcc
	v_ldexp_f32 v131, v131, v132
	v_log_f32_e32 v131, v131
	s_nop 0
	v_mul_f32_e32 v132, 0x3f317217, v131
	v_fma_f32 v132, v131, s73, -v132
	v_fmac_f32_e32 v132, 0x3377d1cf, v131
	v_fmac_f32_e32 v132, 0x3f317217, v131
	v_cmp_lt_f32_e64 s[0:1], |v131|, s11
	s_nop 1
	v_cndmask_b32_e64 v131, v131, v132, s[0:1]
	v_cndmask_b32_e32 v132, 0, v243, vcc
	v_sub_f32_e32 v131, v131, v132
	v_max_f32_e32 v132, v56, v56
	v_max_f32_e32 v132, 0xc2a00000, v132
	v_mul_f32_e32 v132, 0xbfb8aa3b, v132
	v_exp_f32_e32 v132, v132
	s_nop 0
	v_add_f32_e32 v132, 1.0, v132
	v_rcp_f32_e32 v132, v132
	s_nop 0
	v_fma_f32 v132, v132, v186, v8
	v_cmp_gt_f32_e32 vcc, s72, v132
	s_nop 1
	v_cndmask_b32_e64 v133, 0, 32, vcc
	v_ldexp_f32 v132, v132, v133
	v_log_f32_e32 v132, v132
	s_nop 0
	v_mul_f32_e32 v133, 0x3f317217, v132
	v_fma_f32 v133, v132, s73, -v133
	v_fmac_f32_e32 v133, 0x3377d1cf, v132
	v_fmac_f32_e32 v133, 0x3f317217, v132
	v_cmp_lt_f32_e64 s[0:1], |v132|, s11
	s_nop 1
	v_cndmask_b32_e64 v132, v132, v133, s[0:1]
	v_cndmask_b32_e32 v133, 0, v243, vcc
	v_sub_f32_e32 v132, v132, v133
	v_max_f32_e32 v133, v57, v57
	v_max_f32_e32 v133, 0xc2a00000, v133
	v_mul_f32_e32 v133, 0xbfb8aa3b, v133
	v_exp_f32_e32 v133, v133
	s_nop 0
	v_add_f32_e32 v133, 1.0, v133
	v_rcp_f32_e32 v133, v133
	s_nop 0
	v_fma_f32 v133, v133, v185, v173
	v_cmp_gt_f32_e32 vcc, s72, v133
	s_nop 1
	v_cndmask_b32_e64 v134, 0, 32, vcc
	v_ldexp_f32 v133, v133, v134
	v_log_f32_e32 v133, v133
	s_nop 0
	v_mul_f32_e32 v134, 0x3f317217, v133
	v_fma_f32 v134, v133, s73, -v134
	v_fmac_f32_e32 v134, 0x3377d1cf, v133
	v_fmac_f32_e32 v134, 0x3f317217, v133
	v_cmp_lt_f32_e64 s[0:1], |v133|, s11
	s_nop 1
	v_cndmask_b32_e64 v133, v133, v134, s[0:1]
	v_cndmask_b32_e32 v134, 0, v243, vcc
	v_sub_f32_e32 v133, v133, v134
	v_max_f32_e32 v134, v50, v50
	v_max_f32_e32 v134, 0xc2a00000, v134
	v_mul_f32_e32 v134, 0xbfb8aa3b, v134
	v_exp_f32_e32 v134, v134
	s_nop 0
	v_add_f32_e32 v134, 1.0, v134
	v_rcp_f32_e32 v134, v134
	s_nop 0
	v_fma_f32 v134, v134, v184, v153
	v_cmp_gt_f32_e32 vcc, s72, v134
	s_nop 1
	v_cndmask_b32_e64 v135, 0, 32, vcc
	v_ldexp_f32 v134, v134, v135
	v_log_f32_e32 v134, v134
	s_nop 0
	v_mul_f32_e32 v135, 0x3f317217, v134
	v_fma_f32 v135, v134, s73, -v135
	v_fmac_f32_e32 v135, 0x3377d1cf, v134
	v_fmac_f32_e32 v135, 0x3f317217, v134
	v_cmp_lt_f32_e64 s[0:1], |v134|, s11
	s_nop 1
	v_cndmask_b32_e64 v134, v134, v135, s[0:1]
	v_cndmask_b32_e32 v135, 0, v243, vcc
	v_sub_f32_e32 v134, v134, v135
	v_max_f32_e32 v135, v51, v51
	v_max_f32_e32 v135, 0xc2a00000, v135
	v_mul_f32_e32 v135, 0xbfb8aa3b, v135
	v_exp_f32_e32 v135, v135
	s_nop 0
	v_add_f32_e32 v135, 1.0, v135
	v_rcp_f32_e32 v135, v135
	s_nop 0
	v_fma_f32 v135, v135, v183, v181
	v_cmp_gt_f32_e32 vcc, s72, v135
	s_nop 1
	v_cndmask_b32_e64 v136, 0, 32, vcc
	v_ldexp_f32 v135, v135, v136
	v_log_f32_e32 v135, v135
	s_nop 0
	v_mul_f32_e32 v136, 0x3f317217, v135
	v_fma_f32 v136, v135, s73, -v136
	v_fmac_f32_e32 v136, 0x3377d1cf, v135
	v_fmac_f32_e32 v136, 0x3f317217, v135
	v_cmp_lt_f32_e64 s[0:1], |v135|, s11
	s_nop 1
	v_cndmask_b32_e64 v135, v135, v136, s[0:1]
	v_cndmask_b32_e32 v136, 0, v243, vcc
	v_sub_f32_e32 v135, v135, v136
	v_max_f32_e32 v136, v52, v52
	v_max_f32_e32 v136, 0xc2a00000, v136
	v_mul_f32_e32 v136, 0xbfb8aa3b, v136
	v_exp_f32_e32 v136, v136
	s_nop 0
	v_add_f32_e32 v136, 1.0, v136
	v_rcp_f32_e32 v136, v136
	s_nop 0
	v_fma_f32 v136, v136, v182, v180
	v_cmp_gt_f32_e32 vcc, s72, v136
	s_nop 1
	v_cndmask_b32_e64 v137, 0, 32, vcc
	v_ldexp_f32 v136, v136, v137
	v_log_f32_e32 v136, v136
	s_nop 0
	v_mul_f32_e32 v137, 0x3f317217, v136
	v_fma_f32 v137, v136, s73, -v137
	v_fmac_f32_e32 v137, 0x3377d1cf, v136
	v_fmac_f32_e32 v137, 0x3f317217, v136
	v_cmp_lt_f32_e64 s[0:1], |v136|, s11
	s_nop 1
	v_cndmask_b32_e64 v136, v136, v137, s[0:1]
	v_cndmask_b32_e32 v137, 0, v243, vcc
	v_sub_f32_e32 v136, v136, v137
	v_max_f32_e32 v137, v53, v53
	v_max_f32_e32 v137, 0xc2a00000, v137
	v_mul_f32_e32 v137, 0xbfb8aa3b, v137
; __device__ __forceinline__ float lbound(float h0, float h1) { return 1.f / (1.f + expf(h0 - h1)); }
; __device__ __forceinline__ float logf_gate(float x, float lb) {
;     const float t = __expf(-fmaxf(x, -80.f));
;     return __logf(lb + (1.f - lb) * __builtin_amdgcn_rcpf(1.f + t));
; }
;     __device__ __forceinline__ void operator()(EPI_ARGS) const {
;     ...
;         } else if (seg == 8) {
; #pragma unroll
;             for (int bj = 0; bj < 2; ++bj) { const int c0 = colt + bj * 128 - 8192;
;                 f32x4 lb0 = (f32x4){0.f, 0.f, 0.f, 0.f}, lb1 = lb0;
;                 if (layer != 0) { const f32x4 a0 = *(const f32x4*)(hlb + c0), a1 = *(const f32x4*)(hlb + c0 + 4), b0 = *(const f32x4*)(hlb + WMIX + c0), b1 = *(const f32x4*)(hlb + WMIX + c0 + 4);
;                     lb0 = (f32x4){lbound(a0[0], b0[0]), lbound(a0[1], b0[1]), lbound(a0[2], b0[2]), lbound(a0[3], b0[3])};
;                     lb1 = (f32x4){lbound(a1[0], b1[0]), lbound(a1[1], b1[1]), lbound(a1[2], b1[2]), lbound(a1[3], b1[3])}; }
; #pragma unroll
;                 for (int ai = 0; ai < 2; ++ai)
; #pragma unroll
;                     for (int m = 0; m < 4; ++m) { const int row = row0 + ai * 128 + m * 16;
;                         const f32x4 v0 = acc[ai][bj][m][0], v1 = acc[ai][bj][m][1];
;                         const f32x4 o0 = (f32x4){logf_gate(v0[0], lb0[0]), logf_gate(v0[1], lb0[1]), logf_gate(v0[2], lb0[2]), logf_gate(v0[3], lb0[3])};
;                         const f32x4 o1 = (f32x4){logf_gate(v1[0], lb1[0]), logf_gate(v1[1], lb1[1]), logf_gate(v1[2], lb1[2]), logf_gate(v1[3], lb1[3])};
;                         float* p = lf_out + (size_t)row * WMIX + c0;
;                         *(f32x4*)p = o0; *(f32x4*)(p + 4) = o1; } }
	v_exp_f32_e32 v137, v137
	s_nop 0
	v_add_f32_e32 v137, 1.0, v137
	v_rcp_f32_e32 v137, v137
	s_nop 0
	v_fma_f32 v137, v137, v175, v174
	v_cmp_gt_f32_e32 vcc, s72, v137
	s_nop 1
	v_cndmask_b32_e64 v154, 0, 32, vcc
	v_ldexp_f32 v137, v137, v154
	v_log_f32_e32 v137, v137
	s_nop 0
	v_mul_f32_e32 v154, 0x3f317217, v137
	v_fma_f32 v154, v137, s73, -v154
	v_fmac_f32_e32 v154, 0x3377d1cf, v137
	v_fmac_f32_e32 v154, 0x3f317217, v137
	v_cmp_lt_f32_e64 s[0:1], |v137|, s11
	s_nop 1
	v_cndmask_b32_e64 v137, v137, v154, s[0:1]
	v_cndmask_b32_e32 v154, 0, v243, vcc
	v_sub_f32_e32 v137, v137, v154
	v_lshl_add_u64 v[154:155], v[164:165], 0, v[158:159]
	global_store_dwordx4 v[154:155], v[130:133], off sc1
	global_store_dwordx4 v[154:155], v[134:137], off offset:16 sc1
	s_nop 0
	v_max_f32_e32 v130, v38, v38
	v_max_f32_e32 v130, 0xc2a00000, v130
	v_mul_f32_e32 v130, 0xbfb8aa3b, v130
	v_exp_f32_e32 v130, v130
	s_nop 0
	v_add_f32_e32 v130, 1.0, v130
	v_rcp_f32_e32 v130, v130
	s_nop 0
	v_fma_f32 v130, v130, v188, v172
	v_cmp_gt_f32_e32 vcc, s72, v130
	s_nop 1
	v_cndmask_b32_e64 v131, 0, 32, vcc
	v_ldexp_f32 v130, v130, v131
	v_log_f32_e32 v130, v130
	s_nop 0
	v_mul_f32_e32 v131, 0x3f317217, v130
	v_fma_f32 v131, v130, s73, -v131
	v_fmac_f32_e32 v131, 0x3377d1cf, v130
	v_fmac_f32_e32 v131, 0x3f317217, v130
	v_cmp_lt_f32_e64 s[0:1], |v130|, s11
	s_nop 1
	v_cndmask_b32_e64 v130, v130, v131, s[0:1]
	v_cndmask_b32_e32 v131, 0, v243, vcc
	v_sub_f32_e32 v130, v130, v131
	v_max_f32_e32 v131, v39, v39
	v_max_f32_e32 v131, 0xc2a00000, v131
	v_mul_f32_e32 v131, 0xbfb8aa3b, v131
	v_exp_f32_e32 v131, v131
	s_nop 0
	v_add_f32_e32 v131, 1.0, v131
	v_rcp_f32_e32 v131, v131
	s_nop 0
	v_fma_f32 v131, v131, v187, v151
	v_cmp_gt_f32_e32 vcc, s72, v131
	s_nop 1
	v_cndmask_b32_e64 v132, 0, 32, vcc
	v_ldexp_f32 v131, v131, v132
	v_log_f32_e32 v131, v131
	s_nop 0
	v_mul_f32_e32 v132, 0x3f317217, v131
	v_fma_f32 v132, v131, s73, -v132
	v_fmac_f32_e32 v132, 0x3377d1cf, v131
	v_fmac_f32_e32 v132, 0x3f317217, v131
	v_cmp_lt_f32_e64 s[0:1], |v131|, s11
	s_nop 1
	v_cndmask_b32_e64 v131, v131, v132, s[0:1]
	v_cndmask_b32_e32 v132, 0, v243, vcc
	v_sub_f32_e32 v131, v131, v132
	v_max_f32_e32 v132, v40, v40
	v_max_f32_e32 v132, 0xc2a00000, v132
	v_mul_f32_e32 v132, 0xbfb8aa3b, v132
	v_exp_f32_e32 v132, v132
	s_nop 0
	v_add_f32_e32 v132, 1.0, v132
	v_rcp_f32_e32 v132, v132
	s_nop 0
	v_fma_f32 v132, v132, v186, v8
	v_cmp_gt_f32_e32 vcc, s72, v132
	s_nop 1
	v_cndmask_b32_e64 v133, 0, 32, vcc
	v_ldexp_f32 v132, v132, v133
	v_log_f32_e32 v132, v132
	s_nop 0
	v_mul_f32_e32 v133, 0x3f317217, v132
	v_fma_f32 v133, v132, s73, -v133
	v_fmac_f32_e32 v133, 0x3377d1cf, v132
	v_fmac_f32_e32 v133, 0x3f317217, v132
	v_cmp_lt_f32_e64 s[0:1], |v132|, s11
	s_nop 1
	v_cndmask_b32_e64 v132, v132, v133, s[0:1]
	v_cndmask_b32_e32 v133, 0, v243, vcc
	v_sub_f32_e32 v132, v132, v133
	v_max_f32_e32 v133, v41, v41
	v_max_f32_e32 v133, 0xc2a00000, v133
	v_mul_f32_e32 v133, 0xbfb8aa3b, v133
	v_exp_f32_e32 v133, v133
	s_nop 0
	v_add_f32_e32 v133, 1.0, v133
	v_rcp_f32_e32 v133, v133
	s_nop 0
	v_fma_f32 v133, v133, v185, v173
	v_cmp_gt_f32_e32 vcc, s72, v133
	s_nop 1
	v_cndmask_b32_e64 v134, 0, 32, vcc
	v_ldexp_f32 v133, v133, v134
	v_log_f32_e32 v133, v133
	s_nop 0
	v_mul_f32_e32 v134, 0x3f317217, v133
	v_fma_f32 v134, v133, s73, -v134
	v_fmac_f32_e32 v134, 0x3377d1cf, v133
	v_fmac_f32_e32 v134, 0x3f317217, v133
	v_cmp_lt_f32_e64 s[0:1], |v133|, s11
	s_nop 1
	v_cndmask_b32_e64 v133, v133, v134, s[0:1]
	v_cndmask_b32_e32 v134, 0, v243, vcc
	v_sub_f32_e32 v133, v133, v134
	v_max_f32_e32 v134, v34, v34
	v_max_f32_e32 v134, 0xc2a00000, v134
	v_mul_f32_e32 v134, 0xbfb8aa3b, v134
	v_exp_f32_e32 v134, v134
	s_nop 0
	v_add_f32_e32 v134, 1.0, v134
	v_rcp_f32_e32 v134, v134
	s_nop 0
	v_fma_f32 v134, v134, v184, v153
	v_cmp_gt_f32_e32 vcc, s72, v134
	s_nop 1
	v_cndmask_b32_e64 v135, 0, 32, vcc
	v_ldexp_f32 v134, v134, v135
	v_log_f32_e32 v134, v134
	s_nop 0
	v_mul_f32_e32 v135, 0x3f317217, v134
	v_fma_f32 v135, v134, s73, -v135
	v_fmac_f32_e32 v135, 0x3377d1cf, v134
	v_fmac_f32_e32 v135, 0x3f317217, v134
	v_cmp_lt_f32_e64 s[0:1], |v134|, s11
	s_nop 1
	v_cndmask_b32_e64 v134, v134, v135, s[0:1]
	v_cndmask_b32_e32 v135, 0, v243, vcc
	v_sub_f32_e32 v134, v134, v135
	v_max_f32_e32 v135, v35, v35
	v_max_f32_e32 v135, 0xc2a00000, v135
	v_mul_f32_e32 v135, 0xbfb8aa3b, v135
	v_exp_f32_e32 v135, v135
	s_nop 0
	v_add_f32_e32 v135, 1.0, v135
	v_rcp_f32_e32 v135, v135
	s_nop 0
	v_fma_f32 v135, v135, v183, v181
	v_cmp_gt_f32_e32 vcc, s72, v135
	s_nop 1
	v_cndmask_b32_e64 v136, 0, 32, vcc
	v_ldexp_f32 v135, v135, v136
	v_log_f32_e32 v135, v135
	s_nop 0
	v_mul_f32_e32 v136, 0x3f317217, v135
	v_fma_f32 v136, v135, s73, -v136
	v_fmac_f32_e32 v136, 0x3377d1cf, v135
	v_fmac_f32_e32 v136, 0x3f317217, v135
	v_cmp_lt_f32_e64 s[0:1], |v135|, s11
	s_nop 1
	v_cndmask_b32_e64 v135, v135, v136, s[0:1]
	v_cndmask_b32_e32 v136, 0, v243, vcc
	v_sub_f32_e32 v135, v135, v136
	v_max_f32_e32 v136, v36, v36
	v_max_f32_e32 v136, 0xc2a00000, v136
	v_mul_f32_e32 v136, 0xbfb8aa3b, v136
	v_exp_f32_e32 v136, v136
	s_nop 0
	v_add_f32_e32 v136, 1.0, v136
	v_rcp_f32_e32 v136, v136
	s_nop 0
	v_fma_f32 v136, v136, v182, v180
	v_cmp_gt_f32_e32 vcc, s72, v136
	s_nop 1
	v_cndmask_b32_e64 v137, 0, 32, vcc
	v_ldexp_f32 v136, v136, v137
	v_log_f32_e32 v136, v136
	s_nop 0
	v_mul_f32_e32 v137, 0x3f317217, v136
	v_fma_f32 v137, v136, s73, -v137
	v_fmac_f32_e32 v137, 0x3377d1cf, v136
	v_fmac_f32_e32 v137, 0x3f317217, v136
	v_cmp_lt_f32_e64 s[0:1], |v136|, s11
	s_nop 1
	v_cndmask_b32_e64 v136, v136, v137, s[0:1]
	v_cndmask_b32_e32 v137, 0, v243, vcc
	v_sub_f32_e32 v136, v136, v137
; __device__ __forceinline__ float lbound(float h0, float h1) { return 1.f / (1.f + expf(h0 - h1)); }
; __device__ __forceinline__ float logf_gate(float x, float lb) {
;     const float t = __expf(-fmaxf(x, -80.f));
;     return __logf(lb + (1.f - lb) * __builtin_amdgcn_rcpf(1.f + t));
; }
;     __device__ __forceinline__ void operator()(EPI_ARGS) const {
;     ...
;         } else if (seg == 8) {
; #pragma unroll
;             for (int bj = 0; bj < 2; ++bj) { const int c0 = colt + bj * 128 - 8192;
;                 f32x4 lb0 = (f32x4){0.f, 0.f, 0.f, 0.f}, lb1 = lb0;
;                 if (layer != 0) { const f32x4 a0 = *(const f32x4*)(hlb + c0), a1 = *(const f32x4*)(hlb + c0 + 4), b0 = *(const f32x4*)(hlb + WMIX + c0), b1 = *(const f32x4*)(hlb + WMIX + c0 + 4);
;                     lb0 = (f32x4){lbound(a0[0], b0[0]), lbound(a0[1], b0[1]), lbound(a0[2], b0[2]), lbound(a0[3], b0[3])};
;                     lb1 = (f32x4){lbound(a1[0], b1[0]), lbound(a1[1], b1[1]), lbound(a1[2], b1[2]), lbound(a1[3], b1[3])}; }
; #pragma unroll
;                 for (int ai = 0; ai < 2; ++ai)
; #pragma unroll
;                     for (int m = 0; m < 4; ++m) { const int row = row0 + ai * 128 + m * 16;
;                         const f32x4 v0 = acc[ai][bj][m][0], v1 = acc[ai][bj][m][1];
;                         const f32x4 o0 = (f32x4){logf_gate(v0[0], lb0[0]), logf_gate(v0[1], lb0[1]), logf_gate(v0[2], lb0[2]), logf_gate(v0[3], lb0[3])};
;                         const f32x4 o1 = (f32x4){logf_gate(v1[0], lb1[0]), logf_gate(v1[1], lb1[1]), logf_gate(v1[2], lb1[2]), logf_gate(v1[3], lb1[3])};
;                         float* p = lf_out + (size_t)row * WMIX + c0;
;                         *(f32x4*)p = o0; *(f32x4*)(p + 4) = o1; } }
	v_max_f32_e32 v137, v37, v37
	v_max_f32_e32 v137, 0xc2a00000, v137
	v_mul_f32_e32 v137, 0xbfb8aa3b, v137
	v_exp_f32_e32 v137, v137
	s_nop 0
	v_add_f32_e32 v137, 1.0, v137
	v_rcp_f32_e32 v137, v137
	s_nop 0
	v_fma_f32 v137, v137, v175, v174
	v_cmp_gt_f32_e32 vcc, s72, v137
	s_nop 1
	v_cndmask_b32_e64 v154, 0, 32, vcc
	v_ldexp_f32 v137, v137, v154
	v_log_f32_e32 v137, v137
	s_nop 0
	v_mul_f32_e32 v154, 0x3f317217, v137
	v_fma_f32 v154, v137, s73, -v154
	v_fmac_f32_e32 v154, 0x3377d1cf, v137
	v_fmac_f32_e32 v154, 0x3f317217, v137
	v_cmp_lt_f32_e64 s[0:1], |v137|, s11
	s_nop 1
	v_cndmask_b32_e64 v137, v137, v154, s[0:1]
	v_cndmask_b32_e32 v154, 0, v243, vcc
	v_sub_f32_e32 v137, v137, v154
	v_lshl_add_u64 v[154:155], v[166:167], 0, v[158:159]
	global_store_dwordx4 v[154:155], v[130:133], off sc1
	global_store_dwordx4 v[154:155], v[134:137], off offset:16 sc1
	s_nop 0
	v_max_f32_e32 v130, v22, v22
	v_max_f32_e32 v130, 0xc2a00000, v130
	v_mul_f32_e32 v130, 0xbfb8aa3b, v130
	v_exp_f32_e32 v130, v130
	s_nop 0
	v_add_f32_e32 v130, 1.0, v130
	v_rcp_f32_e32 v130, v130
	s_nop 0
	v_fma_f32 v130, v130, v188, v172
	v_cmp_gt_f32_e32 vcc, s72, v130
	s_nop 1
	v_cndmask_b32_e64 v131, 0, 32, vcc
	v_ldexp_f32 v130, v130, v131
	v_log_f32_e32 v130, v130
	s_nop 0
	v_mul_f32_e32 v131, 0x3f317217, v130
	v_fma_f32 v131, v130, s73, -v131
	v_fmac_f32_e32 v131, 0x3377d1cf, v130
	v_fmac_f32_e32 v131, 0x3f317217, v130
	v_cmp_lt_f32_e64 s[0:1], |v130|, s11
	s_nop 1
	v_cndmask_b32_e64 v130, v130, v131, s[0:1]
	v_cndmask_b32_e32 v131, 0, v243, vcc
	v_sub_f32_e32 v130, v130, v131
	v_max_f32_e32 v131, v23, v23
	v_max_f32_e32 v131, 0xc2a00000, v131
	v_mul_f32_e32 v131, 0xbfb8aa3b, v131
	v_exp_f32_e32 v131, v131
	s_nop 0
	v_add_f32_e32 v131, 1.0, v131
	v_rcp_f32_e32 v131, v131
	s_nop 0
	v_fma_f32 v131, v131, v187, v151
	v_cmp_gt_f32_e32 vcc, s72, v131
	s_nop 1
	v_cndmask_b32_e64 v132, 0, 32, vcc
	v_ldexp_f32 v131, v131, v132
	v_log_f32_e32 v131, v131
	s_nop 0
	v_mul_f32_e32 v132, 0x3f317217, v131
	v_fma_f32 v132, v131, s73, -v132
	v_fmac_f32_e32 v132, 0x3377d1cf, v131
	v_fmac_f32_e32 v132, 0x3f317217, v131
	v_cmp_lt_f32_e64 s[0:1], |v131|, s11
	s_nop 1
	v_cndmask_b32_e64 v131, v131, v132, s[0:1]
	v_cndmask_b32_e32 v132, 0, v243, vcc
	v_sub_f32_e32 v131, v131, v132
	v_max_f32_e32 v132, v24, v24
	v_max_f32_e32 v132, 0xc2a00000, v132
	v_mul_f32_e32 v132, 0xbfb8aa3b, v132
	v_exp_f32_e32 v132, v132
	s_nop 0
	v_add_f32_e32 v132, 1.0, v132
	v_rcp_f32_e32 v132, v132
	s_nop 0
	v_fma_f32 v132, v132, v186, v8
	v_cmp_gt_f32_e32 vcc, s72, v132
	s_nop 1
	v_cndmask_b32_e64 v133, 0, 32, vcc
	v_ldexp_f32 v132, v132, v133
	v_log_f32_e32 v132, v132
	s_nop 0
	v_mul_f32_e32 v133, 0x3f317217, v132
	v_fma_f32 v133, v132, s73, -v133
	v_fmac_f32_e32 v133, 0x3377d1cf, v132
	v_fmac_f32_e32 v133, 0x3f317217, v132
	v_cmp_lt_f32_e64 s[0:1], |v132|, s11
	s_nop 1
	v_cndmask_b32_e64 v132, v132, v133, s[0:1]
	v_cndmask_b32_e32 v133, 0, v243, vcc
	v_sub_f32_e32 v132, v132, v133
	v_max_f32_e32 v133, v25, v25
	v_max_f32_e32 v133, 0xc2a00000, v133
	v_mul_f32_e32 v133, 0xbfb8aa3b, v133
	v_exp_f32_e32 v133, v133
	s_nop 0
	v_add_f32_e32 v133, 1.0, v133
	v_rcp_f32_e32 v133, v133
	s_nop 0
	v_fma_f32 v133, v133, v185, v173
	v_cmp_gt_f32_e32 vcc, s72, v133
	s_nop 1
	v_cndmask_b32_e64 v134, 0, 32, vcc
	v_ldexp_f32 v133, v133, v134
	v_log_f32_e32 v133, v133
	s_nop 0
	v_mul_f32_e32 v134, 0x3f317217, v133
	v_fma_f32 v134, v133, s73, -v134
	v_fmac_f32_e32 v134, 0x3377d1cf, v133
	v_fmac_f32_e32 v134, 0x3f317217, v133
	v_cmp_lt_f32_e64 s[0:1], |v133|, s11
	s_nop 1
	v_cndmask_b32_e64 v133, v133, v134, s[0:1]
	v_cndmask_b32_e32 v134, 0, v243, vcc
	v_sub_f32_e32 v133, v133, v134
	v_max_f32_e32 v134, v18, v18
	v_max_f32_e32 v134, 0xc2a00000, v134
	v_mul_f32_e32 v134, 0xbfb8aa3b, v134
	v_exp_f32_e32 v134, v134
	s_nop 0
	v_add_f32_e32 v134, 1.0, v134
	v_rcp_f32_e32 v134, v134
	s_nop 0
	v_fma_f32 v134, v134, v184, v153
	v_cmp_gt_f32_e32 vcc, s72, v134
	s_nop 1
	v_cndmask_b32_e64 v135, 0, 32, vcc
	v_ldexp_f32 v134, v134, v135
	v_log_f32_e32 v134, v134
	s_nop 0
	v_mul_f32_e32 v135, 0x3f317217, v134
	v_fma_f32 v135, v134, s73, -v135
	v_fmac_f32_e32 v135, 0x3377d1cf, v134
	v_fmac_f32_e32 v135, 0x3f317217, v134
	v_cmp_lt_f32_e64 s[0:1], |v134|, s11
	s_nop 1
	v_cndmask_b32_e64 v134, v134, v135, s[0:1]
	v_cndmask_b32_e32 v135, 0, v243, vcc
	v_sub_f32_e32 v134, v134, v135
	v_max_f32_e32 v135, v19, v19
	v_max_f32_e32 v135, 0xc2a00000, v135
	v_mul_f32_e32 v135, 0xbfb8aa3b, v135
	v_exp_f32_e32 v135, v135
	s_nop 0
	v_add_f32_e32 v135, 1.0, v135
	v_rcp_f32_e32 v135, v135
	s_nop 0
	v_fma_f32 v135, v135, v183, v181
	v_cmp_gt_f32_e32 vcc, s72, v135
	s_nop 1
	v_cndmask_b32_e64 v136, 0, 32, vcc
	v_ldexp_f32 v135, v135, v136
	v_log_f32_e32 v135, v135
	s_nop 0
	v_mul_f32_e32 v136, 0x3f317217, v135
	v_fma_f32 v136, v135, s73, -v136
	v_fmac_f32_e32 v136, 0x3377d1cf, v135
	v_fmac_f32_e32 v136, 0x3f317217, v135
	v_cmp_lt_f32_e64 s[0:1], |v135|, s11
	s_nop 1
	v_cndmask_b32_e64 v135, v135, v136, s[0:1]
	v_cndmask_b32_e32 v136, 0, v243, vcc
	v_sub_f32_e32 v135, v135, v136
	v_max_f32_e32 v136, v20, v20
	v_max_f32_e32 v136, 0xc2a00000, v136
	v_mul_f32_e32 v136, 0xbfb8aa3b, v136
	v_exp_f32_e32 v136, v136
	s_nop 0
	v_add_f32_e32 v136, 1.0, v136
	v_rcp_f32_e32 v136, v136
	s_nop 0
	v_fma_f32 v136, v136, v182, v180
	v_cmp_gt_f32_e32 vcc, s72, v136
	s_nop 1
	v_cndmask_b32_e64 v137, 0, 32, vcc
	v_ldexp_f32 v136, v136, v137
	v_log_f32_e32 v136, v136
	s_nop 0
	v_mul_f32_e32 v137, 0x3f317217, v136
	v_fma_f32 v137, v136, s73, -v137
	v_fmac_f32_e32 v137, 0x3377d1cf, v136
	v_fmac_f32_e32 v137, 0x3f317217, v136
	v_cmp_lt_f32_e64 s[0:1], |v136|, s11
	s_nop 1
; __device__ __forceinline__ float lbound(float h0, float h1) { return 1.f / (1.f + expf(h0 - h1)); }
; __device__ __forceinline__ float logf_gate(float x, float lb) {
;     const float t = __expf(-fmaxf(x, -80.f));
;     return __logf(lb + (1.f - lb) * __builtin_amdgcn_rcpf(1.f + t));
; }
;     __device__ __forceinline__ void operator()(EPI_ARGS) const {
;     ...
;         } else if (seg == 8) {
; #pragma unroll
;             for (int bj = 0; bj < 2; ++bj) { const int c0 = colt + bj * 128 - 8192;
;                 f32x4 lb0 = (f32x4){0.f, 0.f, 0.f, 0.f}, lb1 = lb0;
;                 if (layer != 0) { const f32x4 a0 = *(const f32x4*)(hlb + c0), a1 = *(const f32x4*)(hlb + c0 + 4), b0 = *(const f32x4*)(hlb + WMIX + c0), b1 = *(const f32x4*)(hlb + WMIX + c0 + 4);
;                     lb0 = (f32x4){lbound(a0[0], b0[0]), lbound(a0[1], b0[1]), lbound(a0[2], b0[2]), lbound(a0[3], b0[3])};
;                     lb1 = (f32x4){lbound(a1[0], b1[0]), lbound(a1[1], b1[1]), lbound(a1[2], b1[2]), lbound(a1[3], b1[3])}; }
; #pragma unroll
;                 for (int ai = 0; ai < 2; ++ai)
; #pragma unroll
;                     for (int m = 0; m < 4; ++m) { const int row = row0 + ai * 128 + m * 16;
;                         const f32x4 v0 = acc[ai][bj][m][0], v1 = acc[ai][bj][m][1];
;                         const f32x4 o0 = (f32x4){logf_gate(v0[0], lb0[0]), logf_gate(v0[1], lb0[1]), logf_gate(v0[2], lb0[2]), logf_gate(v0[3], lb0[3])};
;                         const f32x4 o1 = (f32x4){logf_gate(v1[0], lb1[0]), logf_gate(v1[1], lb1[1]), logf_gate(v1[2], lb1[2]), logf_gate(v1[3], lb1[3])};
;                         float* p = lf_out + (size_t)row * WMIX + c0;
;                         *(f32x4*)p = o0; *(f32x4*)(p + 4) = o1; } }
	v_cndmask_b32_e64 v136, v136, v137, s[0:1]
	v_cndmask_b32_e32 v137, 0, v243, vcc
	v_sub_f32_e32 v136, v136, v137
	v_max_f32_e32 v137, v21, v21
	v_max_f32_e32 v137, 0xc2a00000, v137
	v_mul_f32_e32 v137, 0xbfb8aa3b, v137
	v_exp_f32_e32 v137, v137
	s_nop 0
	v_add_f32_e32 v137, 1.0, v137
	v_rcp_f32_e32 v137, v137
	s_nop 0
	v_fma_f32 v137, v137, v175, v174
	v_cmp_gt_f32_e32 vcc, s72, v137
	s_nop 1
	v_cndmask_b32_e64 v154, 0, 32, vcc
	v_ldexp_f32 v137, v137, v154
	v_log_f32_e32 v137, v137
	s_nop 0
	v_mul_f32_e32 v154, 0x3f317217, v137
	v_fma_f32 v154, v137, s73, -v154
	v_fmac_f32_e32 v154, 0x3377d1cf, v137
	v_fmac_f32_e32 v154, 0x3f317217, v137
	v_cmp_lt_f32_e64 s[0:1], |v137|, s11
	s_nop 1
	v_cndmask_b32_e64 v137, v137, v154, s[0:1]
	v_cndmask_b32_e32 v154, 0, v243, vcc
	v_sub_f32_e32 v137, v137, v154
	v_lshl_add_u64 v[154:155], v[168:169], 0, v[158:159]
	global_store_dwordx4 v[154:155], v[130:133], off sc1
	global_store_dwordx4 v[154:155], v[134:137], off offset:16 sc1
	v_lshl_add_u64 v[154:155], v[170:171], 0, v[158:159]
	v_max_f32_e32 v130, v4, v4
	v_max_f32_e32 v130, 0xc2a00000, v130
	v_mul_f32_e32 v130, 0xbfb8aa3b, v130
	v_exp_f32_e32 v130, v130
	s_nop 0
	v_add_f32_e32 v130, 1.0, v130
	v_rcp_f32_e32 v130, v130
	s_nop 0
	v_fmac_f32_e32 v172, v130, v188
	v_cmp_gt_f32_e32 vcc, s72, v172
	s_nop 1
	v_cndmask_b32_e64 v130, 0, 32, vcc
	v_ldexp_f32 v130, v172, v130
	v_log_f32_e32 v130, v130
	s_nop 0
	v_mul_f32_e32 v131, 0x3f317217, v130
	v_fma_f32 v131, v130, s73, -v131
	v_fmac_f32_e32 v131, 0x3377d1cf, v130
	v_fmac_f32_e32 v131, 0x3f317217, v130
	v_cmp_lt_f32_e64 s[0:1], |v130|, s11
	s_nop 1
	v_cndmask_b32_e64 v130, v130, v131, s[0:1]
	v_cndmask_b32_e32 v131, 0, v243, vcc
	v_sub_f32_e32 v130, v130, v131
	v_max_f32_e32 v131, v5, v5
	v_max_f32_e32 v131, 0xc2a00000, v131
	v_mul_f32_e32 v131, 0xbfb8aa3b, v131
	v_exp_f32_e32 v131, v131
	s_nop 0
	v_add_f32_e32 v131, 1.0, v131
	v_rcp_f32_e32 v131, v131
	s_nop 0
	v_fmac_f32_e32 v151, v131, v187
	v_cmp_gt_f32_e32 vcc, s72, v151
	s_nop 1
	v_cndmask_b32_e64 v131, 0, 32, vcc
	v_ldexp_f32 v131, v151, v131
	v_log_f32_e32 v131, v131
	s_nop 0
	v_mul_f32_e32 v132, 0x3f317217, v131
	v_fma_f32 v132, v131, s73, -v132
	v_fmac_f32_e32 v132, 0x3377d1cf, v131
	v_fmac_f32_e32 v132, 0x3f317217, v131
	v_cmp_lt_f32_e64 s[0:1], |v131|, s11
	s_nop 1
	v_cndmask_b32_e64 v131, v131, v132, s[0:1]
	v_cndmask_b32_e32 v132, 0, v243, vcc
	v_sub_f32_e32 v131, v131, v132
	v_max_f32_e32 v132, v6, v6
	v_max_f32_e32 v132, 0xc2a00000, v132
	v_mul_f32_e32 v132, 0xbfb8aa3b, v132
	v_exp_f32_e32 v132, v132
	s_nop 0
	v_add_f32_e32 v132, 1.0, v132
	v_rcp_f32_e32 v132, v132
	s_nop 0
	v_fmac_f32_e32 v8, v132, v186
	v_cmp_gt_f32_e32 vcc, s72, v8
	s_nop 1
	v_cndmask_b32_e64 v132, 0, 32, vcc
	v_ldexp_f32 v8, v8, v132
	v_log_f32_e32 v8, v8
	s_nop 0
	v_mul_f32_e32 v132, 0x3f317217, v8
	v_fma_f32 v132, v8, s73, -v132
	v_fmac_f32_e32 v132, 0x3377d1cf, v8
	v_fmac_f32_e32 v132, 0x3f317217, v8
	v_cmp_lt_f32_e64 s[0:1], |v8|, s11
	s_nop 1
	v_cndmask_b32_e64 v8, v8, v132, s[0:1]
	v_cndmask_b32_e32 v132, 0, v243, vcc
	v_sub_f32_e32 v132, v8, v132
	v_max_f32_e32 v8, v7, v7
	v_max_f32_e32 v8, 0xc2a00000, v8
	v_mul_f32_e32 v8, 0xbfb8aa3b, v8
	v_exp_f32_e32 v8, v8
	s_nop 0
	v_add_f32_e32 v8, 1.0, v8
	v_rcp_f32_e32 v8, v8
	s_nop 0
	v_fmac_f32_e32 v173, v8, v185
	v_cmp_gt_f32_e32 vcc, s72, v173
	s_nop 1
	v_cndmask_b32_e64 v8, 0, 32, vcc
	v_ldexp_f32 v8, v173, v8
	v_log_f32_e32 v8, v8
	s_nop 0
	v_mul_f32_e32 v133, 0x3f317217, v8
	v_fma_f32 v133, v8, s73, -v133
	v_fmac_f32_e32 v133, 0x3377d1cf, v8
	v_fmac_f32_e32 v133, 0x3f317217, v8
	v_cmp_lt_f32_e64 s[0:1], |v8|, s11
	s_nop 1
	v_cndmask_b32_e64 v8, v8, v133, s[0:1]
	v_cndmask_b32_e32 v133, 0, v243, vcc
	v_sub_f32_e32 v133, v8, v133
	v_max_f32_e32 v8, v0, v0
	v_max_f32_e32 v8, 0xc2a00000, v8
	v_mul_f32_e32 v8, 0xbfb8aa3b, v8
	v_exp_f32_e32 v8, v8
	s_nop 0
	v_add_f32_e32 v8, 1.0, v8
	v_rcp_f32_e32 v8, v8
	s_nop 0
	v_fmac_f32_e32 v153, v8, v184
	v_cmp_gt_f32_e32 vcc, s72, v153
	s_nop 1
	v_cndmask_b32_e64 v8, 0, 32, vcc
	v_ldexp_f32 v8, v153, v8
	v_log_f32_e32 v8, v8
	s_nop 0
	v_mul_f32_e32 v134, 0x3f317217, v8
	v_fma_f32 v134, v8, s73, -v134
	v_fmac_f32_e32 v134, 0x3377d1cf, v8
	v_fmac_f32_e32 v134, 0x3f317217, v8
	v_cmp_lt_f32_e64 s[0:1], |v8|, s11
	s_nop 1
	v_cndmask_b32_e64 v8, v8, v134, s[0:1]
	v_cndmask_b32_e32 v134, 0, v243, vcc
	v_sub_f32_e32 v134, v8, v134
	v_max_f32_e32 v8, v1, v1
	v_max_f32_e32 v8, 0xc2a00000, v8
	v_mul_f32_e32 v8, 0xbfb8aa3b, v8
	v_exp_f32_e32 v8, v8
	s_nop 0
	v_add_f32_e32 v8, 1.0, v8
	v_rcp_f32_e32 v8, v8
	s_nop 0
	v_fmac_f32_e32 v181, v8, v183
	v_cmp_gt_f32_e32 vcc, s72, v181
	s_nop 1
	v_cndmask_b32_e64 v8, 0, 32, vcc
	v_ldexp_f32 v8, v181, v8
	v_log_f32_e32 v8, v8
	s_nop 0
	v_mul_f32_e32 v135, 0x3f317217, v8
	v_fma_f32 v135, v8, s73, -v135
	v_fmac_f32_e32 v135, 0x3377d1cf, v8
	v_fmac_f32_e32 v135, 0x3f317217, v8
	v_cmp_lt_f32_e64 s[0:1], |v8|, s11
	s_nop 1
	v_cndmask_b32_e64 v8, v8, v135, s[0:1]
	v_cndmask_b32_e32 v135, 0, v243, vcc
	v_sub_f32_e32 v135, v8, v135
	v_max_f32_e32 v8, v2, v2
	v_max_f32_e32 v8, 0xc2a00000, v8
	v_mul_f32_e32 v8, 0xbfb8aa3b, v8
	v_exp_f32_e32 v8, v8
	s_nop 0
	v_add_f32_e32 v8, 1.0, v8
	v_rcp_f32_e32 v8, v8
	s_nop 0
	v_fmac_f32_e32 v180, v8, v182
	v_cmp_gt_f32_e32 vcc, s72, v180
	s_nop 1
	v_cndmask_b32_e64 v8, 0, 32, vcc
	v_ldexp_f32 v8, v180, v8
	v_log_f32_e32 v8, v8
	s_nop 0
	v_mul_f32_e32 v136, 0x3f317217, v8
	v_fma_f32 v136, v8, s73, -v136
	v_fmac_f32_e32 v136, 0x3377d1cf, v8
	v_fmac_f32_e32 v136, 0x3f317217, v8
	v_cmp_lt_f32_e64 s[0:1], |v8|, s11
	s_nop 1
	v_cndmask_b32_e64 v8, v8, v136, s[0:1]
	v_cndmask_b32_e32 v136, 0, v243, vcc
	v_sub_f32_e32 v136, v8, v136
	v_max_f32_e32 v8, v3, v3
	v_max_f32_e32 v8, 0xc2a00000, v8
	v_mul_f32_e32 v8, 0xbfb8aa3b, v8
	v_exp_f32_e32 v8, v8
	s_nop 0
	v_add_f32_e32 v8, 1.0, v8
	v_rcp_f32_e32 v8, v8
	s_nop 0
	v_fmac_f32_e32 v174, v8, v175
	v_cmp_gt_f32_e32 vcc, s72, v174
	s_nop 1
	v_cndmask_b32_e64 v8, 0, 32, vcc
	v_ldexp_f32 v8, v174, v8
	v_log_f32_e32 v8, v8
	s_nop 0
	v_mul_f32_e32 v137, 0x3f317217, v8
	v_fma_f32 v137, v8, s73, -v137
	v_fmac_f32_e32 v137, 0x3377d1cf, v8
	v_fmac_f32_e32 v137, 0x3f317217, v8
	v_cmp_lt_f32_e64 s[0:1], |v8|, s11
	s_nop 1
	v_cndmask_b32_e64 v8, v8, v137, s[0:1]
	v_cndmask_b32_e32 v137, 0, v243, vcc
	v_sub_f32_e32 v137, v8, v137
	global_store_dwordx4 v[154:155], v[130:133], off sc1
	global_store_dwordx4 v[154:155], v[134:137], off offset:16 sc1
	s_cbranch_execnz .LBB0_76
	s_branch .LBB0_182

; __device__ __forceinline__ unsigned pk2(float lo, float hi) { unsigned r; asm("v_cvt_pk_bf16_f32 %0, %1, %2" : "=v"(r) : "v"(lo), "v"(hi)); return r; }
; __device__ __forceinline__ float sigmoidf_(float x) { return 1.f / (1.f + __expf(-x)); }
;     __device__ __forceinline__ void operator()(EPI_ARGS) const {
;     ...
;         if (u.pn >= 44) {
; #pragma unroll
;             for (int ai = 0; ai < 2; ++ai)
; #pragma unroll
;                 for (int m = 0; m < 4; ++m) { const int row = row0 + ai * 128 + m * 16;
; #pragma unroll
;                     for (int bj = 0; bj < 2; ++bj) { const f32x4 v0 = acc[ai][bj][m][0], v1 = acc[ai][bj][m][1];
;                         u32x4 w; w.x = pk2(sigmoidf_(v0[0]), sigmoidf_(v0[1])); w.y = pk2(sigmoidf_(v0[2]), sigmoidf_(v0[3])); w.z = pk2(sigmoidf_(v1[0]), sigmoidf_(v1[1])); w.w = pk2(sigmoidf_(v1[2]), sigmoidf_(v1[3]));
;                         *(u32x4*)(gates + (size_t)row * NGATE + (colt + bj * 128 - NIN)) = w; } }
.LBB0_182:
	v_mul_f32_e32 v8, 0xbfb8aa3b, v126
	v_exp_f32_e32 v8, v8
	s_movk_i32 s2, 0x3000
	v_mov_b32_e32 v153, v9
	s_movk_i32 s3, 0xb000
	v_add_f32_e32 v8, 1.0, v8
	v_div_scale_f32 v126, s[0:1], v8, v8, 1.0
	v_rcp_f32_e32 v130, v126
	v_mul_f32_e32 v110, 0xbfb8aa3b, v110
	v_exp_f32_e32 v110, v110
	v_mul_f32_e32 v111, 0xbfb8aa3b, v111
	v_fma_f32 v131, -v126, v130, 1.0
	v_fmac_f32_e32 v130, v131, v130
	v_div_scale_f32 v131, vcc, 1.0, v8, 1.0
	v_mul_f32_e32 v132, v131, v130
	v_fma_f32 v133, -v126, v132, v131
	v_fmac_f32_e32 v132, v133, v130
	v_fma_f32 v126, -v126, v132, v131
	v_div_fmas_f32 v126, v126, v130, v132
	v_div_fixup_f32 v8, v126, v8, 1.0
	v_mul_f32_e32 v126, 0xbfb8aa3b, v127
	v_exp_f32_e32 v126, v126
	v_add_f32_e32 v110, 1.0, v110
	v_exp_f32_e32 v111, v111
	v_mul_f32_e32 v106, 0xbfb8aa3b, v106
	v_add_f32_e32 v126, 1.0, v126
	v_div_scale_f32 v127, s[0:1], v126, v126, 1.0
	v_rcp_f32_e32 v130, v127
	v_add_f32_e32 v111, 1.0, v111
	v_exp_f32_e32 v106, v106
	v_mul_f32_e32 v107, 0xbfb8aa3b, v107
	v_fma_f32 v131, -v127, v130, 1.0
	v_fmac_f32_e32 v130, v131, v130
	v_div_scale_f32 v131, vcc, 1.0, v126, 1.0
	v_mul_f32_e32 v132, v131, v130
	v_fma_f32 v133, -v127, v132, v131
	v_fmac_f32_e32 v132, v133, v130
	v_fma_f32 v127, -v127, v132, v131
	v_div_fmas_f32 v127, v127, v130, v132
	v_div_fixup_f32 v126, v127, v126, 1.0
	v_cvt_pk_bf16_f32 v126, v8, v126
	v_mul_f32_e32 v8, 0xbfb8aa3b, v128
	v_exp_f32_e32 v8, v8
	v_add_f32_e32 v106, 1.0, v106
	v_exp_f32_e32 v107, v107
	v_mul_f32_e32 v94, 0xbfb8aa3b, v94
	v_add_f32_e32 v8, 1.0, v8
	v_div_scale_f32 v127, s[0:1], v8, v8, 1.0
	v_rcp_f32_e32 v128, v127
	v_add_f32_e32 v107, 1.0, v107
	v_exp_f32_e32 v94, v94
	v_mul_f32_e32 v95, 0xbfb8aa3b, v95
	v_fma_f32 v130, -v127, v128, 1.0
	v_fmac_f32_e32 v128, v130, v128
	v_div_scale_f32 v130, vcc, 1.0, v8, 1.0
	v_mul_f32_e32 v131, v130, v128
	v_fma_f32 v132, -v127, v131, v130
	v_fmac_f32_e32 v131, v132, v128
	v_fma_f32 v127, -v127, v131, v130
	v_div_fmas_f32 v127, v127, v128, v131
	v_div_fixup_f32 v8, v127, v8, 1.0
	v_mul_f32_e32 v127, 0xbfb8aa3b, v129
	v_exp_f32_e32 v127, v127
	v_add_f32_e32 v94, 1.0, v94
	v_exp_f32_e32 v95, v95
	v_mul_f32_e32 v90, 0xbfb8aa3b, v90
	v_add_f32_e32 v127, 1.0, v127
	v_div_scale_f32 v128, s[0:1], v127, v127, 1.0
	v_rcp_f32_e32 v129, v128
	v_add_f32_e32 v95, 1.0, v95
	v_exp_f32_e32 v90, v90
	v_mul_f32_e32 v91, 0xbfb8aa3b, v91
	v_fma_f32 v130, -v128, v129, 1.0
	v_fmac_f32_e32 v129, v130, v129
	v_div_scale_f32 v130, vcc, 1.0, v127, 1.0
	v_mul_f32_e32 v131, v130, v129
	v_fma_f32 v132, -v128, v131, v130
	v_fmac_f32_e32 v131, v132, v129
	v_fma_f32 v128, -v128, v131, v130
	v_div_fmas_f32 v128, v128, v129, v131
	v_div_fixup_f32 v127, v128, v127, 1.0
	v_cvt_pk_bf16_f32 v127, v8, v127
	v_mul_f32_e32 v8, 0xbfb8aa3b, v122
	v_exp_f32_e32 v8, v8
	v_add_f32_e32 v90, 1.0, v90
	v_exp_f32_e32 v91, v91
	v_mul_f32_e32 v78, 0xbfb8aa3b, v78
	v_add_f32_e32 v8, 1.0, v8
	v_div_scale_f32 v122, s[0:1], v8, v8, 1.0
	v_rcp_f32_e32 v128, v122
	v_add_f32_e32 v91, 1.0, v91
	v_exp_f32_e32 v78, v78
	v_mul_f32_e32 v79, 0xbfb8aa3b, v79
	v_fma_f32 v129, -v122, v128, 1.0
	v_fmac_f32_e32 v128, v129, v128
	v_div_scale_f32 v129, vcc, 1.0, v8, 1.0
	v_mul_f32_e32 v130, v129, v128
	v_fma_f32 v131, -v122, v130, v129
	v_fmac_f32_e32 v130, v131, v128
	v_fma_f32 v122, -v122, v130, v129
	v_div_fmas_f32 v122, v122, v128, v130
	v_div_fixup_f32 v8, v122, v8, 1.0
	v_mul_f32_e32 v122, 0xbfb8aa3b, v123
	v_exp_f32_e32 v122, v122
	v_add_f32_e32 v78, 1.0, v78
	v_exp_f32_e32 v79, v79
	v_mul_f32_e32 v74, 0xbfb8aa3b, v74
	v_add_f32_e32 v122, 1.0, v122
	v_div_scale_f32 v123, s[0:1], v122, v122, 1.0
	v_rcp_f32_e32 v128, v123
	v_add_f32_e32 v79, 1.0, v79
	v_exp_f32_e32 v74, v74
	v_mul_f32_e32 v75, 0xbfb8aa3b, v75
	v_fma_f32 v129, -v123, v128, 1.0
	v_fmac_f32_e32 v128, v129, v128
	v_div_scale_f32 v129, vcc, 1.0, v122, 1.0
	v_mul_f32_e32 v130, v129, v128
	v_fma_f32 v131, -v123, v130, v129
	v_fmac_f32_e32 v130, v131, v128
	v_fma_f32 v123, -v123, v130, v129
	v_div_fmas_f32 v123, v123, v128, v130
	v_div_fixup_f32 v122, v123, v122, 1.0
	v_cvt_pk_bf16_f32 v128, v8, v122
	v_mul_f32_e32 v8, 0xbfb8aa3b, v124
	v_exp_f32_e32 v8, v8
	v_add_f32_e32 v74, 1.0, v74
	v_exp_f32_e32 v75, v75
	v_mul_f32_e32 v62, 0xbfb8aa3b, v62
	v_add_f32_e32 v8, 1.0, v8
	v_div_scale_f32 v122, s[0:1], v8, v8, 1.0
	v_rcp_f32_e32 v123, v122
	v_add_f32_e32 v75, 1.0, v75
	v_exp_f32_e32 v62, v62
	v_mul_f32_e32 v63, 0xbfb8aa3b, v63
	v_fma_f32 v124, -v122, v123, 1.0
	v_fmac_f32_e32 v123, v124, v123
	v_div_scale_f32 v124, vcc, 1.0, v8, 1.0
	v_mul_f32_e32 v129, v124, v123
	v_fma_f32 v130, -v122, v129, v124
	v_fmac_f32_e32 v129, v130, v123
	v_fma_f32 v122, -v122, v129, v124
	v_div_fmas_f32 v122, v122, v123, v129
	v_div_fixup_f32 v8, v122, v8, 1.0
	v_mul_f32_e32 v122, 0xbfb8aa3b, v125
	v_exp_f32_e32 v122, v122
	v_add_f32_e32 v62, 1.0, v62
	v_exp_f32_e32 v63, v63
	v_mul_f32_e32 v58, 0xbfb8aa3b, v58
	v_add_f32_e32 v122, 1.0, v122
	v_div_scale_f32 v123, s[0:1], v122, v122, 1.0
	v_rcp_f32_e32 v124, v123
	v_readlane_b32 s0, v252, 62
	v_readlane_b32 s1, v252, 63
	v_add_f32_e32 v63, 1.0, v63
	v_fma_f32 v125, -v123, v124, 1.0
	v_fmac_f32_e32 v124, v125, v124
	v_div_scale_f32 v125, vcc, 1.0, v122, 1.0
	v_mul_f32_e32 v129, v125, v124
	v_fma_f32 v130, -v123, v129, v125
	v_fmac_f32_e32 v129, v130, v124
	v_fma_f32 v123, -v123, v129, v125
	v_div_fmas_f32 v123, v123, v124, v129
	v_div_fixup_f32 v122, v123, v122, 1.0
	v_cvt_pk_bf16_f32 v129, v8, v122
	v_mul_f32_e32 v8, 0xbfb8aa3b, v118
	v_exp_f32_e32 v8, v8
	v_mov_b64_e32 v[122:123], s[0:1]
	v_mad_i64_i32 v[130:131], s[0:1], v150, s2, v[122:123]
	v_lshlrev_b64 v[124:125], 1, v[152:153]
; __device__ __forceinline__ unsigned pk2(float lo, float hi) { unsigned r; asm("v_cvt_pk_bf16_f32 %0, %1, %2" : "=v"(r) : "v"(lo), "v"(hi)); return r; }
; __device__ __forceinline__ float sigmoidf_(float x) { return 1.f / (1.f + __expf(-x)); }
;     __device__ __forceinline__ void operator()(EPI_ARGS) const {
;     ...
;         if (u.pn >= 44) {
; #pragma unroll
;             for (int ai = 0; ai < 2; ++ai)
; #pragma unroll
;                 for (int m = 0; m < 4; ++m) { const int row = row0 + ai * 128 + m * 16;
; #pragma unroll
;                     for (int bj = 0; bj < 2; ++bj) { const f32x4 v0 = acc[ai][bj][m][0], v1 = acc[ai][bj][m][1];
;                         u32x4 w; w.x = pk2(sigmoidf_(v0[0]), sigmoidf_(v0[1])); w.y = pk2(sigmoidf_(v0[2]), sigmoidf_(v0[3])); w.z = pk2(sigmoidf_(v1[0]), sigmoidf_(v1[1])); w.w = pk2(sigmoidf_(v1[2]), sigmoidf_(v1[3]));
;                         *(u32x4*)(gates + (size_t)row * NGATE + (colt + bj * 128 - NIN)) = w; } }
	v_lshl_add_u64 v[130:131], v[130:131], 0, v[124:125]
	v_add_co_u32_e32 v130, vcc, s3, v130
	v_add_f32_e32 v8, 1.0, v8
	s_nop 0
	v_addc_co_u32_e32 v131, vcc, -1, v131, vcc
	v_div_scale_f32 v118, s[0:1], v8, v8, 1.0
	global_store_dwordx4 v[130:131], v[126:129], off offset:-2048 sc1
	v_exp_f32_e32 v58, v58
	v_mul_f32_e32 v59, 0xbfb8aa3b, v59
	v_rcp_f32_e32 v126, v118
	v_exp_f32_e32 v59, v59
	v_add_f32_e32 v58, 1.0, v58
	v_mul_f32_e32 v46, 0xbfb8aa3b, v46
	v_fma_f32 v127, -v118, v126, 1.0
	v_fmac_f32_e32 v126, v127, v126
	v_div_scale_f32 v127, vcc, 1.0, v8, 1.0
	v_mul_f32_e32 v128, v127, v126
	v_fma_f32 v129, -v118, v128, v127
	v_fmac_f32_e32 v128, v129, v126
	v_fma_f32 v118, -v118, v128, v127
	v_div_fmas_f32 v118, v118, v126, v128
	v_div_fixup_f32 v8, v118, v8, 1.0
	v_mul_f32_e32 v118, 0xbfb8aa3b, v119
	v_exp_f32_e32 v118, v118
	v_add_f32_e32 v59, 1.0, v59
	v_exp_f32_e32 v46, v46
	v_mul_f32_e32 v47, 0xbfb8aa3b, v47
	v_add_f32_e32 v118, 1.0, v118
	v_div_scale_f32 v119, s[0:1], v118, v118, 1.0
	v_rcp_f32_e32 v126, v119
	v_add_f32_e32 v46, 1.0, v46
	v_exp_f32_e32 v47, v47
	v_mul_f32_e32 v42, 0xbfb8aa3b, v42
	v_fma_f32 v127, -v119, v126, 1.0
	v_fmac_f32_e32 v126, v127, v126
	v_div_scale_f32 v127, vcc, 1.0, v118, 1.0
	v_mul_f32_e32 v128, v127, v126
	v_fma_f32 v129, -v119, v128, v127
	v_fmac_f32_e32 v128, v129, v126
	v_fma_f32 v119, -v119, v128, v127
	v_div_fmas_f32 v119, v119, v126, v128
	v_div_fixup_f32 v118, v119, v118, 1.0
	v_cvt_pk_bf16_f32 v118, v8, v118
	v_mul_f32_e32 v8, 0xbfb8aa3b, v120
	v_exp_f32_e32 v8, v8
	v_add_f32_e32 v47, 1.0, v47
	v_exp_f32_e32 v42, v42
	v_mul_f32_e32 v43, 0xbfb8aa3b, v43
	v_add_f32_e32 v8, 1.0, v8
	v_div_scale_f32 v119, s[0:1], v8, v8, 1.0
	v_rcp_f32_e32 v120, v119
	v_add_f32_e32 v42, 1.0, v42
	v_exp_f32_e32 v43, v43
	v_mul_f32_e32 v30, 0xbfb8aa3b, v30
	v_fma_f32 v126, -v119, v120, 1.0
	v_fmac_f32_e32 v120, v126, v120
	v_div_scale_f32 v126, vcc, 1.0, v8, 1.0
	v_mul_f32_e32 v127, v126, v120
	v_fma_f32 v128, -v119, v127, v126
	v_fmac_f32_e32 v127, v128, v120
	v_fma_f32 v119, -v119, v127, v126
	v_div_fmas_f32 v119, v119, v120, v127
	v_div_fixup_f32 v8, v119, v8, 1.0
	v_mul_f32_e32 v119, 0xbfb8aa3b, v121
	v_exp_f32_e32 v119, v119
	v_add_f32_e32 v43, 1.0, v43
	v_exp_f32_e32 v30, v30
	v_mul_f32_e32 v31, 0xbfb8aa3b, v31
	v_add_f32_e32 v119, 1.0, v119
	v_div_scale_f32 v120, s[0:1], v119, v119, 1.0
	v_rcp_f32_e32 v121, v120
	v_add_f32_e32 v30, 1.0, v30
	v_exp_f32_e32 v31, v31
	v_mul_f32_e32 v26, 0xbfb8aa3b, v26
	v_fma_f32 v126, -v120, v121, 1.0
	v_fmac_f32_e32 v121, v126, v121
	v_div_scale_f32 v126, vcc, 1.0, v119, 1.0
	v_mul_f32_e32 v127, v126, v121
	v_fma_f32 v128, -v120, v127, v126
	v_fmac_f32_e32 v127, v128, v121
	v_fma_f32 v120, -v120, v127, v126
	v_div_fmas_f32 v120, v120, v121, v127
	v_div_fixup_f32 v119, v120, v119, 1.0
	v_cvt_pk_bf16_f32 v119, v8, v119
	v_mul_f32_e32 v8, 0xbfb8aa3b, v114
	v_exp_f32_e32 v8, v8
	v_add_f32_e32 v31, 1.0, v31
	v_exp_f32_e32 v26, v26
	v_mul_f32_e32 v27, 0xbfb8aa3b, v27
	v_add_f32_e32 v8, 1.0, v8
	v_div_scale_f32 v114, s[0:1], v8, v8, 1.0
	v_rcp_f32_e32 v120, v114
	v_add_f32_e32 v26, 1.0, v26
	v_exp_f32_e32 v27, v27
	v_mul_f32_e32 v14, 0xbfb8aa3b, v14
	v_fma_f32 v121, -v114, v120, 1.0
	v_fmac_f32_e32 v120, v121, v120
	v_div_scale_f32 v121, vcc, 1.0, v8, 1.0
	v_mul_f32_e32 v126, v121, v120
	v_fma_f32 v127, -v114, v126, v121
	v_fmac_f32_e32 v126, v127, v120
	v_fma_f32 v114, -v114, v126, v121
	v_div_fmas_f32 v114, v114, v120, v126
	v_div_fixup_f32 v8, v114, v8, 1.0
	v_mul_f32_e32 v114, 0xbfb8aa3b, v115
	v_exp_f32_e32 v114, v114
	v_add_f32_e32 v27, 1.0, v27
	v_exp_f32_e32 v14, v14
	v_mul_f32_e32 v15, 0xbfb8aa3b, v15
	v_add_f32_e32 v114, 1.0, v114
	v_div_scale_f32 v115, s[0:1], v114, v114, 1.0
	v_rcp_f32_e32 v120, v115
	v_add_f32_e32 v14, 1.0, v14
	v_exp_f32_e32 v15, v15
	v_mul_f32_e32 v10, 0xbfb8aa3b, v10
	v_fma_f32 v121, -v115, v120, 1.0
	v_fmac_f32_e32 v120, v121, v120
	v_div_scale_f32 v121, vcc, 1.0, v114, 1.0
	v_mul_f32_e32 v126, v121, v120
	v_fma_f32 v127, -v115, v126, v121
	v_fmac_f32_e32 v126, v127, v120
	v_fma_f32 v115, -v115, v126, v121
	v_div_fmas_f32 v115, v115, v120, v126
	v_div_fixup_f32 v114, v115, v114, 1.0
	v_cvt_pk_bf16_f32 v120, v8, v114
	v_mul_f32_e32 v8, 0xbfb8aa3b, v116
	v_exp_f32_e32 v8, v8
	v_add_f32_e32 v15, 1.0, v15
	v_exp_f32_e32 v10, v10
	v_mul_f32_e32 v11, 0xbfb8aa3b, v11
	v_add_f32_e32 v8, 1.0, v8
	v_div_scale_f32 v114, s[0:1], v8, v8, 1.0
	v_rcp_f32_e32 v115, v114
	v_add_f32_e32 v10, 1.0, v10
	v_exp_f32_e32 v11, v11
	v_mul_f32_e32 v4, 0xbfb8aa3b, v4
	v_fma_f32 v116, -v114, v115, 1.0
	v_fmac_f32_e32 v115, v116, v115
	v_div_scale_f32 v116, vcc, 1.0, v8, 1.0
	v_mul_f32_e32 v121, v116, v115
	v_fma_f32 v126, -v114, v121, v116
	v_fmac_f32_e32 v121, v126, v115
	v_fma_f32 v114, -v114, v121, v116
	v_div_fmas_f32 v114, v114, v115, v121
	v_div_fixup_f32 v8, v114, v8, 1.0
	v_mul_f32_e32 v114, 0xbfb8aa3b, v117
	v_exp_f32_e32 v114, v114
	v_add_f32_e32 v11, 1.0, v11
	v_exp_f32_e32 v4, v4
	v_mul_f32_e32 v5, 0xbfb8aa3b, v5
	v_add_f32_e32 v114, 1.0, v114
	v_div_scale_f32 v115, s[0:1], v114, v114, 1.0
	v_rcp_f32_e32 v116, v115
	v_add_f32_e32 v4, 1.0, v4
	v_exp_f32_e32 v5, v5
	v_mul_f32_e32 v0, 0xbfb8aa3b, v0
	v_fma_f32 v117, -v115, v116, 1.0
	v_fmac_f32_e32 v116, v117, v116
	v_div_scale_f32 v117, vcc, 1.0, v114, 1.0
	v_mul_f32_e32 v121, v117, v116
	v_fma_f32 v126, -v115, v121, v117
	v_fmac_f32_e32 v121, v126, v116
	v_fma_f32 v115, -v115, v121, v117
	v_div_fmas_f32 v115, v115, v116, v121
	v_div_fixup_f32 v114, v115, v114, 1.0
	v_cvt_pk_bf16_f32 v121, v8, v114
	v_div_scale_f32 v114, s[0:1], v110, v110, 1.0
	v_rcp_f32_e32 v115, v114
	global_store_dwordx4 v[130:131], v[118:121], off offset:-1792 sc1
; __device__ __forceinline__ unsigned pk2(float lo, float hi) { unsigned r; asm("v_cvt_pk_bf16_f32 %0, %1, %2" : "=v"(r) : "v"(lo), "v"(hi)); return r; }
; __device__ __forceinline__ float sigmoidf_(float x) { return 1.f / (1.f + __expf(-x)); }
;     __device__ __forceinline__ void operator()(EPI_ARGS) const {
;     ...
;         if (u.pn >= 44) {
; #pragma unroll
;             for (int ai = 0; ai < 2; ++ai)
; #pragma unroll
;                 for (int m = 0; m < 4; ++m) { const int row = row0 + ai * 128 + m * 16;
; #pragma unroll
;                     for (int bj = 0; bj < 2; ++bj) { const f32x4 v0 = acc[ai][bj][m][0], v1 = acc[ai][bj][m][1];
;                         u32x4 w; w.x = pk2(sigmoidf_(v0[0]), sigmoidf_(v0[1])); w.y = pk2(sigmoidf_(v0[2]), sigmoidf_(v0[3])); w.z = pk2(sigmoidf_(v1[0]), sigmoidf_(v1[1])); w.w = pk2(sigmoidf_(v1[2]), sigmoidf_(v1[3]));
;                         *(u32x4*)(gates + (size_t)row * NGATE + (colt + bj * 128 - NIN)) = w; } }
	v_or_b32_e32 v8, 16, v150
	v_add_f32_e32 v5, 1.0, v5
	v_fma_f32 v116, -v114, v115, 1.0
	v_fmac_f32_e32 v115, v116, v115
	v_div_scale_f32 v116, vcc, 1.0, v110, 1.0
	v_mul_f32_e32 v117, v116, v115
	v_fma_f32 v118, -v114, v117, v116
	v_fmac_f32_e32 v117, v118, v115
	v_fma_f32 v114, -v114, v117, v116
	v_div_fmas_f32 v114, v114, v115, v117
	v_div_fixup_f32 v110, v114, v110, 1.0
	v_div_scale_f32 v114, s[0:1], v111, v111, 1.0
	v_rcp_f32_e32 v115, v114
	v_exp_f32_e32 v0, v0
	v_mul_f32_e32 v1, 0xbfb8aa3b, v1
	v_exp_f32_e32 v1, v1
	v_fma_f32 v116, -v114, v115, 1.0
	v_fmac_f32_e32 v115, v116, v115
	v_div_scale_f32 v116, vcc, 1.0, v111, 1.0
	v_mul_f32_e32 v117, v116, v115
	v_fma_f32 v118, -v114, v117, v116
	v_fmac_f32_e32 v117, v118, v115
	v_fma_f32 v114, -v114, v117, v116
	v_div_fmas_f32 v114, v114, v115, v117
	v_div_fixup_f32 v111, v114, v111, 1.0
	v_cvt_pk_bf16_f32 v110, v110, v111
	v_mul_f32_e32 v111, 0xbfb8aa3b, v112
	v_exp_f32_e32 v111, v111
	v_add_f32_e32 v0, 1.0, v0
	v_add_f32_e32 v1, 1.0, v1
	v_add_f32_e32 v111, 1.0, v111
	v_div_scale_f32 v112, s[0:1], v111, v111, 1.0
	v_rcp_f32_e32 v114, v112
	s_nop 0
	v_fma_f32 v115, -v112, v114, 1.0
	v_fmac_f32_e32 v114, v115, v114
	v_div_scale_f32 v115, vcc, 1.0, v111, 1.0
	v_mul_f32_e32 v116, v115, v114
	v_fma_f32 v117, -v112, v116, v115
	v_fmac_f32_e32 v116, v117, v114
	v_fma_f32 v112, -v112, v116, v115
	v_div_fmas_f32 v112, v112, v114, v116
	v_div_fixup_f32 v111, v112, v111, 1.0
	v_mul_f32_e32 v112, 0xbfb8aa3b, v113
	v_exp_f32_e32 v112, v112
	s_nop 0
	v_add_f32_e32 v112, 1.0, v112
	v_div_scale_f32 v113, s[0:1], v112, v112, 1.0
	v_rcp_f32_e32 v114, v113
	s_nop 0
	v_fma_f32 v115, -v113, v114, 1.0
	v_fmac_f32_e32 v114, v115, v114
	v_div_scale_f32 v115, vcc, 1.0, v112, 1.0
	v_mul_f32_e32 v116, v115, v114
	v_fma_f32 v117, -v113, v116, v115
	v_fmac_f32_e32 v116, v117, v114
	v_fma_f32 v113, -v113, v116, v115
	v_div_fmas_f32 v113, v113, v114, v116
	v_div_fixup_f32 v112, v113, v112, 1.0
	v_cvt_pk_bf16_f32 v111, v111, v112
	v_div_scale_f32 v112, s[0:1], v106, v106, 1.0
	v_rcp_f32_e32 v113, v112
	s_nop 0
	v_fma_f32 v114, -v112, v113, 1.0
	v_fmac_f32_e32 v113, v114, v113
	v_div_scale_f32 v114, vcc, 1.0, v106, 1.0
	v_mul_f32_e32 v115, v114, v113
	v_fma_f32 v116, -v112, v115, v114
	v_fmac_f32_e32 v115, v116, v113
	v_fma_f32 v112, -v112, v115, v114
	v_div_fmas_f32 v112, v112, v113, v115
	v_div_fixup_f32 v106, v112, v106, 1.0
	v_div_scale_f32 v112, s[0:1], v107, v107, 1.0
	v_rcp_f32_e32 v113, v112
	s_nop 0
	v_fma_f32 v114, -v112, v113, 1.0
	v_fmac_f32_e32 v113, v114, v113
	v_div_scale_f32 v114, vcc, 1.0, v107, 1.0
	v_mul_f32_e32 v115, v114, v113
	v_fma_f32 v116, -v112, v115, v114
	v_fmac_f32_e32 v115, v116, v113
	v_fma_f32 v112, -v112, v115, v114
	v_div_fmas_f32 v112, v112, v113, v115
	v_div_fixup_f32 v107, v112, v107, 1.0
	v_cvt_pk_bf16_f32 v112, v106, v107
	v_mul_f32_e32 v106, 0xbfb8aa3b, v108
	v_exp_f32_e32 v106, v106
	s_nop 0
	v_add_f32_e32 v106, 1.0, v106
	v_div_scale_f32 v107, s[0:1], v106, v106, 1.0
	v_rcp_f32_e32 v108, v107
	s_nop 0
	v_fma_f32 v113, -v107, v108, 1.0
	v_fmac_f32_e32 v108, v113, v108
	v_div_scale_f32 v113, vcc, 1.0, v106, 1.0
	v_mul_f32_e32 v114, v113, v108
	v_fma_f32 v115, -v107, v114, v113
	v_fmac_f32_e32 v114, v115, v108
	v_fma_f32 v107, -v107, v114, v113
	v_div_fmas_f32 v107, v107, v108, v114
	v_div_fixup_f32 v106, v107, v106, 1.0
	v_mul_f32_e32 v107, 0xbfb8aa3b, v109
	v_exp_f32_e32 v107, v107
	s_nop 0
	v_add_f32_e32 v107, 1.0, v107
	v_div_scale_f32 v108, s[0:1], v107, v107, 1.0
	v_rcp_f32_e32 v109, v108
	s_nop 0
	v_fma_f32 v113, -v108, v109, 1.0
	v_fmac_f32_e32 v109, v113, v109
	v_div_scale_f32 v113, vcc, 1.0, v107, 1.0
	v_mul_f32_e32 v114, v113, v109
	v_fma_f32 v115, -v108, v114, v113
	v_fmac_f32_e32 v114, v115, v109
	v_fma_f32 v108, -v108, v114, v113
	v_div_fmas_f32 v108, v108, v109, v114
	v_div_fixup_f32 v107, v108, v107, 1.0
	v_cvt_pk_bf16_f32 v113, v106, v107
	v_mad_i64_i32 v[106:107], s[0:1], v8, s2, v[122:123]
	v_mul_f32_e32 v8, 0xbfb8aa3b, v102
	v_exp_f32_e32 v8, v8
	v_lshl_add_u64 v[106:107], v[106:107], 0, v[124:125]
	v_add_co_u32_e32 v106, vcc, s3, v106
	v_add_f32_e32 v8, 1.0, v8
	v_div_scale_f32 v102, s[0:1], v8, v8, 1.0
	v_rcp_f32_e32 v108, v102
	v_addc_co_u32_e32 v107, vcc, -1, v107, vcc
	global_store_dwordx4 v[106:107], v[110:113], off offset:-2048 sc1
	v_fma_f32 v109, -v102, v108, 1.0
	v_fmac_f32_e32 v108, v109, v108
	v_div_scale_f32 v109, vcc, 1.0, v8, 1.0
	v_mul_f32_e32 v110, v109, v108
	v_fma_f32 v111, -v102, v110, v109
	v_fmac_f32_e32 v110, v111, v108
	v_fma_f32 v102, -v102, v110, v109
	v_div_fmas_f32 v102, v102, v108, v110
	v_div_fixup_f32 v8, v102, v8, 1.0
	v_mul_f32_e32 v102, 0xbfb8aa3b, v103
	v_exp_f32_e32 v102, v102
	s_nop 0
	v_add_f32_e32 v102, 1.0, v102
	v_div_scale_f32 v103, s[0:1], v102, v102, 1.0
	v_rcp_f32_e32 v108, v103
	s_nop 0
	v_fma_f32 v109, -v103, v108, 1.0
	v_fmac_f32_e32 v108, v109, v108
	v_div_scale_f32 v109, vcc, 1.0, v102, 1.0
	v_mul_f32_e32 v110, v109, v108
	v_fma_f32 v111, -v103, v110, v109
	v_fmac_f32_e32 v110, v111, v108
	v_fma_f32 v103, -v103, v110, v109
	v_div_fmas_f32 v103, v103, v108, v110
	v_div_fixup_f32 v102, v103, v102, 1.0
	v_cvt_pk_bf16_f32 v102, v8, v102
	v_mul_f32_e32 v8, 0xbfb8aa3b, v104
	v_exp_f32_e32 v8, v8
	s_nop 0
	v_add_f32_e32 v8, 1.0, v8
	v_div_scale_f32 v103, s[0:1], v8, v8, 1.0
	v_rcp_f32_e32 v104, v103
	s_nop 0
	v_fma_f32 v108, -v103, v104, 1.0
	v_fmac_f32_e32 v104, v108, v104
	v_div_scale_f32 v108, vcc, 1.0, v8, 1.0
	v_mul_f32_e32 v109, v108, v104
	v_fma_f32 v110, -v103, v109, v108
	v_fmac_f32_e32 v109, v110, v104
	v_fma_f32 v103, -v103, v109, v108
	v_div_fmas_f32 v103, v103, v104, v109
	v_div_fixup_f32 v8, v103, v8, 1.0
	v_mul_f32_e32 v103, 0xbfb8aa3b, v105
	v_exp_f32_e32 v103, v103
	s_nop 0
	v_add_f32_e32 v103, 1.0, v103
	v_div_scale_f32 v104, s[0:1], v103, v103, 1.0
	v_rcp_f32_e32 v105, v104
	s_nop 0
	v_fma_f32 v108, -v104, v105, 1.0
	v_fmac_f32_e32 v105, v108, v105
	v_div_scale_f32 v108, vcc, 1.0, v103, 1.0
	v_mul_f32_e32 v109, v108, v105
	v_fma_f32 v110, -v104, v109, v108
	v_fmac_f32_e32 v109, v110, v105
	v_fma_f32 v104, -v104, v109, v108
	v_div_fmas_f32 v104, v104, v105, v109
	v_div_fixup_f32 v103, v104, v103, 1.0
	v_cvt_pk_bf16_f32 v103, v8, v103
	v_mul_f32_e32 v8, 0xbfb8aa3b, v98
	v_exp_f32_e32 v8, v8
	s_nop 0
	v_add_f32_e32 v8, 1.0, v8
	v_div_scale_f32 v98, s[0:1], v8, v8, 1.0
	v_rcp_f32_e32 v104, v98
	s_nop 0
	v_fma_f32 v105, -v98, v104, 1.0
	v_fmac_f32_e32 v104, v105, v104
	v_div_scale_f32 v105, vcc, 1.0, v8, 1.0
	v_mul_f32_e32 v108, v105, v104
	v_fma_f32 v109, -v98, v108, v105
	v_fmac_f32_e32 v108, v109, v104
	v_fma_f32 v98, -v98, v108, v105
	v_div_fmas_f32 v98, v98, v104, v108
	v_div_fixup_f32 v8, v98, v8, 1.0
	v_mul_f32_e32 v98, 0xbfb8aa3b, v99
	v_exp_f32_e32 v98, v98
	s_nop 0
	v_add_f32_e32 v98, 1.0, v98
	v_div_scale_f32 v99, s[0:1], v98, v98, 1.0
	v_rcp_f32_e32 v104, v99
	s_nop 0
	v_fma_f32 v105, -v99, v104, 1.0
	v_fmac_f32_e32 v104, v105, v104
	v_div_scale_f32 v105, vcc, 1.0, v98, 1.0
	v_mul_f32_e32 v108, v105, v104
	v_fma_f32 v109, -v99, v108, v105
	v_fmac_f32_e32 v108, v109, v104
	v_fma_f32 v99, -v99, v108, v105
	v_div_fmas_f32 v99, v99, v104, v108
	v_div_fixup_f32 v98, v99, v98, 1.0
	v_cvt_pk_bf16_f32 v104, v8, v98
	v_mul_f32_e32 v8, 0xbfb8aa3b, v100
	v_exp_f32_e32 v8, v8
	s_nop 0
	v_add_f32_e32 v8, 1.0, v8
	v_div_scale_f32 v98, s[0:1], v8, v8, 1.0
	v_rcp_f32_e32 v99, v98
	s_nop 0
	v_fma_f32 v100, -v98, v99, 1.0
	v_fmac_f32_e32 v99, v100, v99
	v_div_scale_f32 v100, vcc, 1.0, v8, 1.0
	v_mul_f32_e32 v105, v100, v99
	v_fma_f32 v108, -v98, v105, v100
	v_fmac_f32_e32 v105, v108, v99
	v_fma_f32 v98, -v98, v105, v100
	v_div_fmas_f32 v98, v98, v99, v105
	v_div_fixup_f32 v8, v98, v8, 1.0
	v_mul_f32_e32 v98, 0xbfb8aa3b, v101
	v_exp_f32_e32 v98, v98
	s_nop 0
	v_add_f32_e32 v98, 1.0, v98
	v_div_scale_f32 v99, s[0:1], v98, v98, 1.0
	v_rcp_f32_e32 v100, v99
	s_nop 0
	v_fma_f32 v101, -v99, v100, 1.0
	v_fmac_f32_e32 v100, v101, v100
	v_div_scale_f32 v101, vcc, 1.0, v98, 1.0
	v_mul_f32_e32 v105, v101, v100
	v_fma_f32 v108, -v99, v105, v101
	v_fmac_f32_e32 v105, v108, v100
	v_fma_f32 v99, -v99, v105, v101
	v_div_fmas_f32 v99, v99, v100, v105
	v_div_fixup_f32 v98, v99, v98, 1.0
	v_cvt_pk_bf16_f32 v105, v8, v98
	v_div_scale_f32 v98, s[0:1], v94, v94, 1.0
	v_rcp_f32_e32 v99, v98
	global_store_dwordx4 v[106:107], v[102:105], off offset:-1792 sc1
	v_or_b32_e32 v8, 32, v150
	v_fma_f32 v100, -v98, v99, 1.0
	v_fmac_f32_e32 v99, v100, v99
	v_div_scale_f32 v100, vcc, 1.0, v94, 1.0
	v_mul_f32_e32 v101, v100, v99
	v_fma_f32 v102, -v98, v101, v100
	v_fmac_f32_e32 v101, v102, v99
	v_fma_f32 v98, -v98, v101, v100
	v_div_fmas_f32 v98, v98, v99, v101
	v_div_fixup_f32 v94, v98, v94, 1.0
	v_div_scale_f32 v98, s[0:1], v95, v95, 1.0
	v_rcp_f32_e32 v99, v98
	s_nop 0
	v_fma_f32 v100, -v98, v99, 1.0
	v_fmac_f32_e32 v99, v100, v99
	v_div_scale_f32 v100, vcc, 1.0, v95, 1.0
	v_mul_f32_e32 v101, v100, v99
	v_fma_f32 v102, -v98, v101, v100
	v_fmac_f32_e32 v101, v102, v99
	v_fma_f32 v98, -v98, v101, v100
	v_div_fmas_f32 v98, v98, v99, v101
	v_div_fixup_f32 v95, v98, v95, 1.0
	v_cvt_pk_bf16_f32 v94, v94, v95
	v_mul_f32_e32 v95, 0xbfb8aa3b, v96
	v_exp_f32_e32 v95, v95
	s_nop 0
	v_add_f32_e32 v95, 1.0, v95
	v_div_scale_f32 v96, s[0:1], v95, v95, 1.0
	v_rcp_f32_e32 v98, v96
	s_nop 0
	v_fma_f32 v99, -v96, v98, 1.0
	v_fmac_f32_e32 v98, v99, v98
	v_div_scale_f32 v99, vcc, 1.0, v95, 1.0
	v_mul_f32_e32 v100, v99, v98
	v_fma_f32 v101, -v96, v100, v99
	v_fmac_f32_e32 v100, v101, v98
	v_fma_f32 v96, -v96, v100, v99
	v_div_fmas_f32 v96, v96, v98, v100
	v_div_fixup_f32 v95, v96, v95, 1.0
	v_mul_f32_e32 v96, 0xbfb8aa3b, v97
	v_exp_f32_e32 v96, v96
	s_nop 0
	v_add_f32_e32 v96, 1.0, v96
	v_div_scale_f32 v97, s[0:1], v96, v96, 1.0
	v_rcp_f32_e32 v98, v97
	s_nop 0
	v_fma_f32 v99, -v97, v98, 1.0
	v_fmac_f32_e32 v98, v99, v98
	v_div_scale_f32 v99, vcc, 1.0, v96, 1.0
	v_mul_f32_e32 v100, v99, v98
	v_fma_f32 v101, -v97, v100, v99
	v_fmac_f32_e32 v100, v101, v98
	v_fma_f32 v97, -v97, v100, v99
	v_div_fmas_f32 v97, v97, v98, v100
	v_div_fixup_f32 v96, v97, v96, 1.0
	v_cvt_pk_bf16_f32 v95, v95, v96
	v_div_scale_f32 v96, s[0:1], v90, v90, 1.0
	v_rcp_f32_e32 v97, v96
	s_nop 0
	v_fma_f32 v98, -v96, v97, 1.0
	v_fmac_f32_e32 v97, v98, v97
	v_div_scale_f32 v98, vcc, 1.0, v90, 1.0
	v_mul_f32_e32 v99, v98, v97
	v_fma_f32 v100, -v96, v99, v98
	v_fmac_f32_e32 v99, v100, v97
	v_fma_f32 v96, -v96, v99, v98
	v_div_fmas_f32 v96, v96, v97, v99
	v_div_fixup_f32 v90, v96, v90, 1.0
	v_div_scale_f32 v96, s[0:1], v91, v91, 1.0
	v_rcp_f32_e32 v97, v96
	s_nop 0
	v_fma_f32 v98, -v96, v97, 1.0
	v_fmac_f32_e32 v97, v98, v97
	v_div_scale_f32 v98, vcc, 1.0, v91, 1.0
	v_mul_f32_e32 v99, v98, v97
	v_fma_f32 v100, -v96, v99, v98
	v_fmac_f32_e32 v99, v100, v97
	v_fma_f32 v96, -v96, v99, v98
	v_div_fmas_f32 v96, v96, v97, v99
	v_div_fixup_f32 v91, v96, v91, 1.0
	v_cvt_pk_bf16_f32 v96, v90, v91
	v_mul_f32_e32 v90, 0xbfb8aa3b, v92
	v_exp_f32_e32 v90, v90
	s_nop 0
	v_add_f32_e32 v90, 1.0, v90
	v_div_scale_f32 v91, s[0:1], v90, v90, 1.0
	v_rcp_f32_e32 v92, v91
	s_nop 0
	v_fma_f32 v97, -v91, v92, 1.0
	v_fmac_f32_e32 v92, v97, v92
	v_div_scale_f32 v97, vcc, 1.0, v90, 1.0
	v_mul_f32_e32 v98, v97, v92
	v_fma_f32 v99, -v91, v98, v97
	v_fmac_f32_e32 v98, v99, v92
	v_fma_f32 v91, -v91, v98, v97
	v_div_fmas_f32 v91, v91, v92, v98
	v_div_fixup_f32 v90, v91, v90, 1.0
	v_mul_f32_e32 v91, 0xbfb8aa3b, v93
	v_exp_f32_e32 v91, v91
	s_nop 0
	v_add_f32_e32 v91, 1.0, v91
	v_div_scale_f32 v92, s[0:1], v91, v91, 1.0
	v_rcp_f32_e32 v93, v92
	s_nop 0
	v_fma_f32 v97, -v92, v93, 1.0
	v_fmac_f32_e32 v93, v97, v93
	v_div_scale_f32 v97, vcc, 1.0, v91, 1.0
	v_mul_f32_e32 v98, v97, v93
	v_fma_f32 v99, -v92, v98, v97
	v_fmac_f32_e32 v98, v99, v93
	v_fma_f32 v92, -v92, v98, v97
	v_div_fmas_f32 v92, v92, v93, v98
	v_div_fixup_f32 v91, v92, v91, 1.0
	v_cvt_pk_bf16_f32 v97, v90, v91
	v_mad_i64_i32 v[90:91], s[0:1], v8, s2, v[122:123]
	v_mul_f32_e32 v8, 0xbfb8aa3b, v86
	v_exp_f32_e32 v8, v8
	v_lshl_add_u64 v[90:91], v[90:91], 0, v[124:125]
	v_add_co_u32_e32 v90, vcc, s3, v90
	v_add_f32_e32 v8, 1.0, v8
	v_div_scale_f32 v86, s[0:1], v8, v8, 1.0
	v_rcp_f32_e32 v92, v86
	v_addc_co_u32_e32 v91, vcc, -1, v91, vcc
	global_store_dwordx4 v[90:91], v[94:97], off offset:-2048 sc1
	v_fma_f32 v93, -v86, v92, 1.0
	v_fmac_f32_e32 v92, v93, v92
	v_div_scale_f32 v93, vcc, 1.0, v8, 1.0
	v_mul_f32_e32 v94, v93, v92
	v_fma_f32 v95, -v86, v94, v93
	v_fmac_f32_e32 v94, v95, v92
	v_fma_f32 v86, -v86, v94, v93
	v_div_fmas_f32 v86, v86, v92, v94
	v_div_fixup_f32 v8, v86, v8, 1.0
	v_mul_f32_e32 v86, 0xbfb8aa3b, v87
	v_exp_f32_e32 v86, v86
	s_nop 0
	v_add_f32_e32 v86, 1.0, v86
	v_div_scale_f32 v87, s[0:1], v86, v86, 1.0
	v_rcp_f32_e32 v92, v87
	s_nop 0
	v_fma_f32 v93, -v87, v92, 1.0
	v_fmac_f32_e32 v92, v93, v92
	v_div_scale_f32 v93, vcc, 1.0, v86, 1.0
	v_mul_f32_e32 v94, v93, v92
	v_fma_f32 v95, -v87, v94, v93
	v_fmac_f32_e32 v94, v95, v92
	v_fma_f32 v87, -v87, v94, v93
	v_div_fmas_f32 v87, v87, v92, v94
	v_div_fixup_f32 v86, v87, v86, 1.0
	v_cvt_pk_bf16_f32 v86, v8, v86
	v_mul_f32_e32 v8, 0xbfb8aa3b, v88
	v_exp_f32_e32 v8, v8
	s_nop 0
	v_add_f32_e32 v8, 1.0, v8
	v_div_scale_f32 v87, s[0:1], v8, v8, 1.0
	v_rcp_f32_e32 v88, v87
	s_nop 0
	v_fma_f32 v92, -v87, v88, 1.0
	v_fmac_f32_e32 v88, v92, v88
	v_div_scale_f32 v92, vcc, 1.0, v8, 1.0
	v_mul_f32_e32 v93, v92, v88
	v_fma_f32 v94, -v87, v93, v92
	v_fmac_f32_e32 v93, v94, v88
	v_fma_f32 v87, -v87, v93, v92
	v_div_fmas_f32 v87, v87, v88, v93
	v_div_fixup_f32 v8, v87, v8, 1.0
	v_mul_f32_e32 v87, 0xbfb8aa3b, v89
	v_exp_f32_e32 v87, v87
	s_nop 0
	v_add_f32_e32 v87, 1.0, v87
	v_div_scale_f32 v88, s[0:1], v87, v87, 1.0
	v_rcp_f32_e32 v89, v88
	s_nop 0
	v_fma_f32 v92, -v88, v89, 1.0
	v_fmac_f32_e32 v89, v92, v89
	v_div_scale_f32 v92, vcc, 1.0, v87, 1.0
	v_mul_f32_e32 v93, v92, v89
	v_fma_f32 v94, -v88, v93, v92
	v_fmac_f32_e32 v93, v94, v89
	v_fma_f32 v88, -v88, v93, v92
	v_div_fmas_f32 v88, v88, v89, v93
	v_div_fixup_f32 v87, v88, v87, 1.0
	v_cvt_pk_bf16_f32 v87, v8, v87
	v_mul_f32_e32 v8, 0xbfb8aa3b, v82
	v_exp_f32_e32 v8, v8
	s_nop 0
	v_add_f32_e32 v8, 1.0, v8
	v_div_scale_f32 v82, s[0:1], v8, v8, 1.0
	v_rcp_f32_e32 v88, v82
	s_nop 0
	v_fma_f32 v89, -v82, v88, 1.0
	v_fmac_f32_e32 v88, v89, v88
	v_div_scale_f32 v89, vcc, 1.0, v8, 1.0
	v_mul_f32_e32 v92, v89, v88
	v_fma_f32 v93, -v82, v92, v89
	v_fmac_f32_e32 v92, v93, v88
	v_fma_f32 v82, -v82, v92, v89
	v_div_fmas_f32 v82, v82, v88, v92
	v_div_fixup_f32 v8, v82, v8, 1.0
	v_mul_f32_e32 v82, 0xbfb8aa3b, v83
	v_exp_f32_e32 v82, v82
	s_nop 0
	v_add_f32_e32 v82, 1.0, v82
	v_div_scale_f32 v83, s[0:1], v82, v82, 1.0
	v_rcp_f32_e32 v88, v83
	s_nop 0
	v_fma_f32 v89, -v83, v88, 1.0
	v_fmac_f32_e32 v88, v89, v88
	v_div_scale_f32 v89, vcc, 1.0, v82, 1.0
	v_mul_f32_e32 v92, v89, v88
	v_fma_f32 v93, -v83, v92, v89
	v_fmac_f32_e32 v92, v93, v88
	v_fma_f32 v83, -v83, v92, v89
	v_div_fmas_f32 v83, v83, v88, v92
	v_div_fixup_f32 v82, v83, v82, 1.0
	v_cvt_pk_bf16_f32 v88, v8, v82
	v_mul_f32_e32 v8, 0xbfb8aa3b, v84
	v_exp_f32_e32 v8, v8
	s_nop 0
	v_add_f32_e32 v8, 1.0, v8
	v_div_scale_f32 v82, s[0:1], v8, v8, 1.0
	v_rcp_f32_e32 v83, v82
	s_nop 0
	v_fma_f32 v84, -v82, v83, 1.0
	v_fmac_f32_e32 v83, v84, v83
	v_div_scale_f32 v84, vcc, 1.0, v8, 1.0
	v_mul_f32_e32 v89, v84, v83
	v_fma_f32 v92, -v82, v89, v84
	v_fmac_f32_e32 v89, v92, v83
	v_fma_f32 v82, -v82, v89, v84
	v_div_fmas_f32 v82, v82, v83, v89
	v_div_fixup_f32 v8, v82, v8, 1.0
	v_mul_f32_e32 v82, 0xbfb8aa3b, v85
	v_exp_f32_e32 v82, v82
	s_nop 0
	v_add_f32_e32 v82, 1.0, v82
	v_div_scale_f32 v83, s[0:1], v82, v82, 1.0
	v_rcp_f32_e32 v84, v83
	s_nop 0
	v_fma_f32 v85, -v83, v84, 1.0
	v_fmac_f32_e32 v84, v85, v84
	v_div_scale_f32 v85, vcc, 1.0, v82, 1.0
	v_mul_f32_e32 v89, v85, v84
	v_fma_f32 v92, -v83, v89, v85
	v_fmac_f32_e32 v89, v92, v84
	v_fma_f32 v83, -v83, v89, v85
	v_div_fmas_f32 v83, v83, v84, v89
	v_div_fixup_f32 v82, v83, v82, 1.0
	v_cvt_pk_bf16_f32 v89, v8, v82
	v_div_scale_f32 v82, s[0:1], v78, v78, 1.0
	v_rcp_f32_e32 v83, v82
	global_store_dwordx4 v[90:91], v[86:89], off offset:-1792 sc1
	v_or_b32_e32 v8, 48, v150
	v_fma_f32 v84, -v82, v83, 1.0
	v_fmac_f32_e32 v83, v84, v83
	v_div_scale_f32 v84, vcc, 1.0, v78, 1.0
	v_mul_f32_e32 v85, v84, v83
	v_fma_f32 v86, -v82, v85, v84
	v_fmac_f32_e32 v85, v86, v83
	v_fma_f32 v82, -v82, v85, v84
	v_div_fmas_f32 v82, v82, v83, v85
	v_div_fixup_f32 v78, v82, v78, 1.0
	v_div_scale_f32 v82, s[0:1], v79, v79, 1.0
	v_rcp_f32_e32 v83, v82
	s_nop 0
	v_fma_f32 v84, -v82, v83, 1.0
	v_fmac_f32_e32 v83, v84, v83
	v_div_scale_f32 v84, vcc, 1.0, v79, 1.0
	v_mul_f32_e32 v85, v84, v83
	v_fma_f32 v86, -v82, v85, v84
	v_fmac_f32_e32 v85, v86, v83
	v_fma_f32 v82, -v82, v85, v84
	v_div_fmas_f32 v82, v82, v83, v85
	v_div_fixup_f32 v79, v82, v79, 1.0
	v_cvt_pk_bf16_f32 v78, v78, v79
	v_mul_f32_e32 v79, 0xbfb8aa3b, v80
	v_exp_f32_e32 v79, v79
	s_nop 0
	v_add_f32_e32 v79, 1.0, v79
	v_div_scale_f32 v80, s[0:1], v79, v79, 1.0
	v_rcp_f32_e32 v82, v80
	s_nop 0
	v_fma_f32 v83, -v80, v82, 1.0
	v_fmac_f32_e32 v82, v83, v82
	v_div_scale_f32 v83, vcc, 1.0, v79, 1.0
	v_mul_f32_e32 v84, v83, v82
	v_fma_f32 v85, -v80, v84, v83
	v_fmac_f32_e32 v84, v85, v82
	v_fma_f32 v80, -v80, v84, v83
	v_div_fmas_f32 v80, v80, v82, v84
	v_div_fixup_f32 v79, v80, v79, 1.0
	v_mul_f32_e32 v80, 0xbfb8aa3b, v81
	v_exp_f32_e32 v80, v80
	s_nop 0
	v_add_f32_e32 v80, 1.0, v80
	v_div_scale_f32 v81, s[0:1], v80, v80, 1.0
	v_rcp_f32_e32 v82, v81
	s_nop 0
	v_fma_f32 v83, -v81, v82, 1.0
	v_fmac_f32_e32 v82, v83, v82
	v_div_scale_f32 v83, vcc, 1.0, v80, 1.0
	v_mul_f32_e32 v84, v83, v82
	v_fma_f32 v85, -v81, v84, v83
	v_fmac_f32_e32 v84, v85, v82
	v_fma_f32 v81, -v81, v84, v83
	v_div_fmas_f32 v81, v81, v82, v84
	v_div_fixup_f32 v80, v81, v80, 1.0
	v_cvt_pk_bf16_f32 v79, v79, v80
	v_div_scale_f32 v80, s[0:1], v74, v74, 1.0
	v_rcp_f32_e32 v81, v80
	s_nop 0
	v_fma_f32 v82, -v80, v81, 1.0
	v_fmac_f32_e32 v81, v82, v81
	v_div_scale_f32 v82, vcc, 1.0, v74, 1.0
	v_mul_f32_e32 v83, v82, v81
	v_fma_f32 v84, -v80, v83, v82
	v_fmac_f32_e32 v83, v84, v81
	v_fma_f32 v80, -v80, v83, v82
	v_div_fmas_f32 v80, v80, v81, v83
	v_div_fixup_f32 v74, v80, v74, 1.0
	v_div_scale_f32 v80, s[0:1], v75, v75, 1.0
	v_rcp_f32_e32 v81, v80
	s_nop 0
	v_fma_f32 v82, -v80, v81, 1.0
	v_fmac_f32_e32 v81, v82, v81
	v_div_scale_f32 v82, vcc, 1.0, v75, 1.0
	v_mul_f32_e32 v83, v82, v81
	v_fma_f32 v84, -v80, v83, v82
	v_fmac_f32_e32 v83, v84, v81
	v_fma_f32 v80, -v80, v83, v82
	v_div_fmas_f32 v80, v80, v81, v83
	v_div_fixup_f32 v75, v80, v75, 1.0
	v_cvt_pk_bf16_f32 v80, v74, v75
	v_mul_f32_e32 v74, 0xbfb8aa3b, v76
	v_exp_f32_e32 v74, v74
	s_nop 0
	v_add_f32_e32 v74, 1.0, v74
	v_div_scale_f32 v75, s[0:1], v74, v74, 1.0
	v_rcp_f32_e32 v76, v75
	s_nop 0
	v_fma_f32 v81, -v75, v76, 1.0
	v_fmac_f32_e32 v76, v81, v76
	v_div_scale_f32 v81, vcc, 1.0, v74, 1.0
	v_mul_f32_e32 v82, v81, v76
	v_fma_f32 v83, -v75, v82, v81
	v_fmac_f32_e32 v82, v83, v76
	v_fma_f32 v75, -v75, v82, v81
	v_div_fmas_f32 v75, v75, v76, v82
	v_div_fixup_f32 v74, v75, v74, 1.0
	v_mul_f32_e32 v75, 0xbfb8aa3b, v77
	v_exp_f32_e32 v75, v75
	s_nop 0
	v_add_f32_e32 v75, 1.0, v75
	v_div_scale_f32 v76, s[0:1], v75, v75, 1.0
	v_rcp_f32_e32 v77, v76
	s_nop 0
	v_fma_f32 v81, -v76, v77, 1.0
	v_fmac_f32_e32 v77, v81, v77
	v_div_scale_f32 v81, vcc, 1.0, v75, 1.0
	v_mul_f32_e32 v82, v81, v77
	v_fma_f32 v83, -v76, v82, v81
	v_fmac_f32_e32 v82, v83, v77
	v_fma_f32 v76, -v76, v82, v81
	v_div_fmas_f32 v76, v76, v77, v82
	v_div_fixup_f32 v75, v76, v75, 1.0
	v_cvt_pk_bf16_f32 v81, v74, v75
	v_mad_i64_i32 v[74:75], s[0:1], v8, s2, v[122:123]
	v_mul_f32_e32 v8, 0xbfb8aa3b, v70
	v_exp_f32_e32 v8, v8
	v_lshl_add_u64 v[74:75], v[74:75], 0, v[124:125]
	v_add_co_u32_e32 v74, vcc, s3, v74
	v_add_f32_e32 v8, 1.0, v8
	v_div_scale_f32 v70, s[0:1], v8, v8, 1.0
	v_rcp_f32_e32 v76, v70
	v_addc_co_u32_e32 v75, vcc, -1, v75, vcc
	global_store_dwordx4 v[74:75], v[78:81], off offset:-2048 sc1
	v_fma_f32 v77, -v70, v76, 1.0
	v_fmac_f32_e32 v76, v77, v76
	v_div_scale_f32 v77, vcc, 1.0, v8, 1.0
	v_mul_f32_e32 v78, v77, v76
	v_fma_f32 v79, -v70, v78, v77
	v_fmac_f32_e32 v78, v79, v76
	v_fma_f32 v70, -v70, v78, v77
	v_div_fmas_f32 v70, v70, v76, v78
	v_div_fixup_f32 v8, v70, v8, 1.0
	v_mul_f32_e32 v70, 0xbfb8aa3b, v71
	v_exp_f32_e32 v70, v70
	s_nop 0
	v_add_f32_e32 v70, 1.0, v70
	v_div_scale_f32 v71, s[0:1], v70, v70, 1.0
	v_rcp_f32_e32 v76, v71
	s_nop 0
	v_fma_f32 v77, -v71, v76, 1.0
	v_fmac_f32_e32 v76, v77, v76
	v_div_scale_f32 v77, vcc, 1.0, v70, 1.0
	v_mul_f32_e32 v78, v77, v76
	v_fma_f32 v79, -v71, v78, v77
	v_fmac_f32_e32 v78, v79, v76
	v_fma_f32 v71, -v71, v78, v77
	v_div_fmas_f32 v71, v71, v76, v78
	v_div_fixup_f32 v70, v71, v70, 1.0
	v_cvt_pk_bf16_f32 v70, v8, v70
	v_mul_f32_e32 v8, 0xbfb8aa3b, v72
	v_exp_f32_e32 v8, v8
	s_nop 0
	v_add_f32_e32 v8, 1.0, v8
	v_div_scale_f32 v71, s[0:1], v8, v8, 1.0
	v_rcp_f32_e32 v72, v71
	s_nop 0
	v_fma_f32 v76, -v71, v72, 1.0
	v_fmac_f32_e32 v72, v76, v72
	v_div_scale_f32 v76, vcc, 1.0, v8, 1.0
	v_mul_f32_e32 v77, v76, v72
	v_fma_f32 v78, -v71, v77, v76
	v_fmac_f32_e32 v77, v78, v72
	v_fma_f32 v71, -v71, v77, v76
	v_div_fmas_f32 v71, v71, v72, v77
	v_div_fixup_f32 v8, v71, v8, 1.0
	v_mul_f32_e32 v71, 0xbfb8aa3b, v73
	v_exp_f32_e32 v71, v71
	s_nop 0
	v_add_f32_e32 v71, 1.0, v71
	v_div_scale_f32 v72, s[0:1], v71, v71, 1.0
	v_rcp_f32_e32 v73, v72
	s_nop 0
	v_fma_f32 v76, -v72, v73, 1.0
	v_fmac_f32_e32 v73, v76, v73
	v_div_scale_f32 v76, vcc, 1.0, v71, 1.0
	v_mul_f32_e32 v77, v76, v73
	v_fma_f32 v78, -v72, v77, v76
	v_fmac_f32_e32 v77, v78, v73
	v_fma_f32 v72, -v72, v77, v76
	v_div_fmas_f32 v72, v72, v73, v77
	v_div_fixup_f32 v71, v72, v71, 1.0
	v_cvt_pk_bf16_f32 v71, v8, v71
	v_mul_f32_e32 v8, 0xbfb8aa3b, v66
	v_exp_f32_e32 v8, v8
	s_nop 0
	v_add_f32_e32 v8, 1.0, v8
	v_div_scale_f32 v66, s[0:1], v8, v8, 1.0
	v_rcp_f32_e32 v72, v66
	s_nop 0
	v_fma_f32 v73, -v66, v72, 1.0
	v_fmac_f32_e32 v72, v73, v72
	v_div_scale_f32 v73, vcc, 1.0, v8, 1.0
	v_mul_f32_e32 v76, v73, v72
	v_fma_f32 v77, -v66, v76, v73
	v_fmac_f32_e32 v76, v77, v72
	v_fma_f32 v66, -v66, v76, v73
	v_div_fmas_f32 v66, v66, v72, v76
	v_div_fixup_f32 v8, v66, v8, 1.0
	v_mul_f32_e32 v66, 0xbfb8aa3b, v67
	v_exp_f32_e32 v66, v66
	s_nop 0
	v_add_f32_e32 v66, 1.0, v66
	v_div_scale_f32 v67, s[0:1], v66, v66, 1.0
	v_rcp_f32_e32 v72, v67
	s_nop 0
	v_fma_f32 v73, -v67, v72, 1.0
	v_fmac_f32_e32 v72, v73, v72
	v_div_scale_f32 v73, vcc, 1.0, v66, 1.0
	v_mul_f32_e32 v76, v73, v72
	v_fma_f32 v77, -v67, v76, v73
	v_fmac_f32_e32 v76, v77, v72
	v_fma_f32 v67, -v67, v76, v73
	v_div_fmas_f32 v67, v67, v72, v76
	v_div_fixup_f32 v66, v67, v66, 1.0
	v_cvt_pk_bf16_f32 v72, v8, v66
	v_mul_f32_e32 v8, 0xbfb8aa3b, v68
	v_exp_f32_e32 v8, v8
	s_nop 0
	v_add_f32_e32 v8, 1.0, v8
	v_div_scale_f32 v66, s[0:1], v8, v8, 1.0
	v_rcp_f32_e32 v67, v66
	s_nop 0
	v_fma_f32 v68, -v66, v67, 1.0
	v_fmac_f32_e32 v67, v68, v67
	v_div_scale_f32 v68, vcc, 1.0, v8, 1.0
	v_mul_f32_e32 v73, v68, v67
	v_fma_f32 v76, -v66, v73, v68
	v_fmac_f32_e32 v73, v76, v67
	v_fma_f32 v66, -v66, v73, v68
	v_div_fmas_f32 v66, v66, v67, v73
	v_div_fixup_f32 v8, v66, v8, 1.0
	v_mul_f32_e32 v66, 0xbfb8aa3b, v69
	v_exp_f32_e32 v66, v66
	s_nop 0
	v_add_f32_e32 v66, 1.0, v66
	v_div_scale_f32 v67, s[0:1], v66, v66, 1.0
	v_rcp_f32_e32 v68, v67
	s_nop 0
	v_fma_f32 v69, -v67, v68, 1.0
	v_fmac_f32_e32 v68, v69, v68
	v_div_scale_f32 v69, vcc, 1.0, v66, 1.0
	v_mul_f32_e32 v73, v69, v68
	v_fma_f32 v76, -v67, v73, v69
	v_fmac_f32_e32 v73, v76, v68
	v_fma_f32 v67, -v67, v73, v69
	v_div_fmas_f32 v67, v67, v68, v73
	v_div_fixup_f32 v66, v67, v66, 1.0
	v_cvt_pk_bf16_f32 v73, v8, v66
	v_div_scale_f32 v66, s[0:1], v62, v62, 1.0
	v_rcp_f32_e32 v67, v66
	global_store_dwordx4 v[74:75], v[70:73], off offset:-1792 sc1
	v_add_u32_e32 v8, 0x80, v150
	v_fma_f32 v68, -v66, v67, 1.0
	v_fmac_f32_e32 v67, v68, v67
	v_div_scale_f32 v68, vcc, 1.0, v62, 1.0
	v_mul_f32_e32 v69, v68, v67
	v_fma_f32 v70, -v66, v69, v68
	v_fmac_f32_e32 v69, v70, v67
	v_fma_f32 v66, -v66, v69, v68
	v_div_fmas_f32 v66, v66, v67, v69
	v_div_fixup_f32 v62, v66, v62, 1.0
	v_div_scale_f32 v66, s[0:1], v63, v63, 1.0
	v_rcp_f32_e32 v67, v66
	s_nop 0
	v_fma_f32 v68, -v66, v67, 1.0
	v_fmac_f32_e32 v67, v68, v67
	v_div_scale_f32 v68, vcc, 1.0, v63, 1.0
	v_mul_f32_e32 v69, v68, v67
	v_fma_f32 v70, -v66, v69, v68
	v_fmac_f32_e32 v69, v70, v67
	v_fma_f32 v66, -v66, v69, v68
	v_div_fmas_f32 v66, v66, v67, v69
	v_div_fixup_f32 v63, v66, v63, 1.0
	v_cvt_pk_bf16_f32 v62, v62, v63
	v_mul_f32_e32 v63, 0xbfb8aa3b, v64
	v_exp_f32_e32 v63, v63
	s_nop 0
	v_add_f32_e32 v63, 1.0, v63
	v_div_scale_f32 v64, s[0:1], v63, v63, 1.0
	v_rcp_f32_e32 v66, v64
	s_nop 0
	v_fma_f32 v67, -v64, v66, 1.0
	v_fmac_f32_e32 v66, v67, v66
	v_div_scale_f32 v67, vcc, 1.0, v63, 1.0
	v_mul_f32_e32 v68, v67, v66
	v_fma_f32 v69, -v64, v68, v67
	v_fmac_f32_e32 v68, v69, v66
	v_fma_f32 v64, -v64, v68, v67
	v_div_fmas_f32 v64, v64, v66, v68
	v_div_fixup_f32 v63, v64, v63, 1.0
	v_mul_f32_e32 v64, 0xbfb8aa3b, v65
	v_exp_f32_e32 v64, v64
	s_nop 0
	v_add_f32_e32 v64, 1.0, v64
	v_div_scale_f32 v65, s[0:1], v64, v64, 1.0
	v_rcp_f32_e32 v66, v65
	s_nop 0
	v_fma_f32 v67, -v65, v66, 1.0
	v_fmac_f32_e32 v66, v67, v66
	v_div_scale_f32 v67, vcc, 1.0, v64, 1.0
	v_mul_f32_e32 v68, v67, v66
	v_fma_f32 v69, -v65, v68, v67
	v_fmac_f32_e32 v68, v69, v66
	v_fma_f32 v65, -v65, v68, v67
	v_div_fmas_f32 v65, v65, v66, v68
	v_div_fixup_f32 v64, v65, v64, 1.0
	v_cvt_pk_bf16_f32 v63, v63, v64
	v_div_scale_f32 v64, s[0:1], v58, v58, 1.0
	v_rcp_f32_e32 v65, v64
	s_nop 0
	v_fma_f32 v66, -v64, v65, 1.0
	v_fmac_f32_e32 v65, v66, v65
	v_div_scale_f32 v66, vcc, 1.0, v58, 1.0
	v_mul_f32_e32 v67, v66, v65
	v_fma_f32 v68, -v64, v67, v66
	v_fmac_f32_e32 v67, v68, v65
	v_fma_f32 v64, -v64, v67, v66
	v_div_fmas_f32 v64, v64, v65, v67
	v_div_fixup_f32 v58, v64, v58, 1.0
	v_div_scale_f32 v64, s[0:1], v59, v59, 1.0
	v_rcp_f32_e32 v65, v64
	s_nop 0
	v_fma_f32 v66, -v64, v65, 1.0
	v_fmac_f32_e32 v65, v66, v65
	v_div_scale_f32 v66, vcc, 1.0, v59, 1.0
	v_mul_f32_e32 v67, v66, v65
	v_fma_f32 v68, -v64, v67, v66
	v_fmac_f32_e32 v67, v68, v65
	v_fma_f32 v64, -v64, v67, v66
	v_div_fmas_f32 v64, v64, v65, v67
	v_div_fixup_f32 v59, v64, v59, 1.0
	v_cvt_pk_bf16_f32 v64, v58, v59
	v_mul_f32_e32 v58, 0xbfb8aa3b, v60
	v_exp_f32_e32 v58, v58
	s_nop 0
	v_add_f32_e32 v58, 1.0, v58
	v_div_scale_f32 v59, s[0:1], v58, v58, 1.0
	v_rcp_f32_e32 v60, v59
	s_nop 0
	v_fma_f32 v65, -v59, v60, 1.0
	v_fmac_f32_e32 v60, v65, v60
	v_div_scale_f32 v65, vcc, 1.0, v58, 1.0
	v_mul_f32_e32 v66, v65, v60
	v_fma_f32 v67, -v59, v66, v65
	v_fmac_f32_e32 v66, v67, v60
	v_fma_f32 v59, -v59, v66, v65
	v_div_fmas_f32 v59, v59, v60, v66
	v_div_fixup_f32 v58, v59, v58, 1.0
	v_mul_f32_e32 v59, 0xbfb8aa3b, v61
	v_exp_f32_e32 v59, v59
	s_nop 0
	v_add_f32_e32 v59, 1.0, v59
	v_div_scale_f32 v60, s[0:1], v59, v59, 1.0
	v_rcp_f32_e32 v61, v60
	s_nop 0
	v_fma_f32 v65, -v60, v61, 1.0
	v_fmac_f32_e32 v61, v65, v61
	v_div_scale_f32 v65, vcc, 1.0, v59, 1.0
	v_mul_f32_e32 v66, v65, v61
	v_fma_f32 v67, -v60, v66, v65
	v_fmac_f32_e32 v66, v67, v61
	v_fma_f32 v60, -v60, v66, v65
	v_div_fmas_f32 v60, v60, v61, v66
	v_div_fixup_f32 v59, v60, v59, 1.0
	v_cvt_pk_bf16_f32 v65, v58, v59
	v_mad_i64_i32 v[58:59], s[0:1], v8, s2, v[122:123]
	v_mul_f32_e32 v8, 0xbfb8aa3b, v54
	v_exp_f32_e32 v8, v8
	v_lshl_add_u64 v[58:59], v[58:59], 0, v[124:125]
	v_add_co_u32_e32 v58, vcc, s3, v58
	v_add_f32_e32 v8, 1.0, v8
	v_div_scale_f32 v54, s[0:1], v8, v8, 1.0
	v_rcp_f32_e32 v60, v54
	v_addc_co_u32_e32 v59, vcc, -1, v59, vcc
	global_store_dwordx4 v[58:59], v[62:65], off offset:-2048 sc1
	v_fma_f32 v61, -v54, v60, 1.0
	v_fmac_f32_e32 v60, v61, v60
	v_div_scale_f32 v61, vcc, 1.0, v8, 1.0
	v_mul_f32_e32 v62, v61, v60
	v_fma_f32 v63, -v54, v62, v61
	v_fmac_f32_e32 v62, v63, v60
	v_fma_f32 v54, -v54, v62, v61
	v_div_fmas_f32 v54, v54, v60, v62
	v_div_fixup_f32 v8, v54, v8, 1.0
	v_mul_f32_e32 v54, 0xbfb8aa3b, v55
	v_exp_f32_e32 v54, v54
	s_nop 0
	v_add_f32_e32 v54, 1.0, v54
	v_div_scale_f32 v55, s[0:1], v54, v54, 1.0
	v_rcp_f32_e32 v60, v55
	s_nop 0
	v_fma_f32 v61, -v55, v60, 1.0
	v_fmac_f32_e32 v60, v61, v60
	v_div_scale_f32 v61, vcc, 1.0, v54, 1.0
	v_mul_f32_e32 v62, v61, v60
	v_fma_f32 v63, -v55, v62, v61
	v_fmac_f32_e32 v62, v63, v60
	v_fma_f32 v55, -v55, v62, v61
	v_div_fmas_f32 v55, v55, v60, v62
	v_div_fixup_f32 v54, v55, v54, 1.0
	v_cvt_pk_bf16_f32 v54, v8, v54
	v_mul_f32_e32 v8, 0xbfb8aa3b, v56
	v_exp_f32_e32 v8, v8
	s_nop 0
	v_add_f32_e32 v8, 1.0, v8
	v_div_scale_f32 v55, s[0:1], v8, v8, 1.0
	v_rcp_f32_e32 v56, v55
	s_nop 0
	v_fma_f32 v60, -v55, v56, 1.0
	v_fmac_f32_e32 v56, v60, v56
	v_div_scale_f32 v60, vcc, 1.0, v8, 1.0
	v_mul_f32_e32 v61, v60, v56
	v_fma_f32 v62, -v55, v61, v60
	v_fmac_f32_e32 v61, v62, v56
	v_fma_f32 v55, -v55, v61, v60
	v_div_fmas_f32 v55, v55, v56, v61
	v_div_fixup_f32 v8, v55, v8, 1.0
	v_mul_f32_e32 v55, 0xbfb8aa3b, v57
	v_exp_f32_e32 v55, v55
	s_nop 0
	v_add_f32_e32 v55, 1.0, v55
	v_div_scale_f32 v56, s[0:1], v55, v55, 1.0
	v_rcp_f32_e32 v57, v56
	s_nop 0
	v_fma_f32 v60, -v56, v57, 1.0
	v_fmac_f32_e32 v57, v60, v57
	v_div_scale_f32 v60, vcc, 1.0, v55, 1.0
	v_mul_f32_e32 v61, v60, v57
	v_fma_f32 v62, -v56, v61, v60
	v_fmac_f32_e32 v61, v62, v57
	v_fma_f32 v56, -v56, v61, v60
	v_div_fmas_f32 v56, v56, v57, v61
	v_div_fixup_f32 v55, v56, v55, 1.0
	v_cvt_pk_bf16_f32 v55, v8, v55
	v_mul_f32_e32 v8, 0xbfb8aa3b, v50
	v_exp_f32_e32 v8, v8
	s_nop 0
	v_add_f32_e32 v8, 1.0, v8
	v_div_scale_f32 v50, s[0:1], v8, v8, 1.0
	v_rcp_f32_e32 v56, v50
	s_nop 0
	v_fma_f32 v57, -v50, v56, 1.0
	v_fmac_f32_e32 v56, v57, v56
	v_div_scale_f32 v57, vcc, 1.0, v8, 1.0
	v_mul_f32_e32 v60, v57, v56
	v_fma_f32 v61, -v50, v60, v57
	v_fmac_f32_e32 v60, v61, v56
	v_fma_f32 v50, -v50, v60, v57
	v_div_fmas_f32 v50, v50, v56, v60
	v_div_fixup_f32 v8, v50, v8, 1.0
	v_mul_f32_e32 v50, 0xbfb8aa3b, v51
	v_exp_f32_e32 v50, v50
	s_nop 0
	v_add_f32_e32 v50, 1.0, v50
	v_div_scale_f32 v51, s[0:1], v50, v50, 1.0
	v_rcp_f32_e32 v56, v51
	s_nop 0
	v_fma_f32 v57, -v51, v56, 1.0
	v_fmac_f32_e32 v56, v57, v56
	v_div_scale_f32 v57, vcc, 1.0, v50, 1.0
	v_mul_f32_e32 v60, v57, v56
	v_fma_f32 v61, -v51, v60, v57
	v_fmac_f32_e32 v60, v61, v56
	v_fma_f32 v51, -v51, v60, v57
	v_div_fmas_f32 v51, v51, v56, v60
	v_div_fixup_f32 v50, v51, v50, 1.0
	v_cvt_pk_bf16_f32 v56, v8, v50
	v_mul_f32_e32 v8, 0xbfb8aa3b, v52
	v_exp_f32_e32 v8, v8
	s_nop 0
	v_add_f32_e32 v8, 1.0, v8
	v_div_scale_f32 v50, s[0:1], v8, v8, 1.0
	v_rcp_f32_e32 v51, v50
	s_nop 0
	v_fma_f32 v52, -v50, v51, 1.0
	v_fmac_f32_e32 v51, v52, v51
	v_div_scale_f32 v52, vcc, 1.0, v8, 1.0
	v_mul_f32_e32 v57, v52, v51
	v_fma_f32 v60, -v50, v57, v52
	v_fmac_f32_e32 v57, v60, v51
	v_fma_f32 v50, -v50, v57, v52
	v_div_fmas_f32 v50, v50, v51, v57
	v_div_fixup_f32 v8, v50, v8, 1.0
	v_mul_f32_e32 v50, 0xbfb8aa3b, v53
	v_exp_f32_e32 v50, v50
	s_nop 0
	v_add_f32_e32 v50, 1.0, v50
	v_div_scale_f32 v51, s[0:1], v50, v50, 1.0
	v_rcp_f32_e32 v52, v51
	s_nop 0
	v_fma_f32 v53, -v51, v52, 1.0
	v_fmac_f32_e32 v52, v53, v52
	v_div_scale_f32 v53, vcc, 1.0, v50, 1.0
	v_mul_f32_e32 v57, v53, v52
	v_fma_f32 v60, -v51, v57, v53
	v_fmac_f32_e32 v57, v60, v52
	v_fma_f32 v51, -v51, v57, v53
	v_div_fmas_f32 v51, v51, v52, v57
	v_div_fixup_f32 v50, v51, v50, 1.0
	v_cvt_pk_bf16_f32 v57, v8, v50
	v_div_scale_f32 v50, s[0:1], v46, v46, 1.0
	v_rcp_f32_e32 v51, v50
	global_store_dwordx4 v[58:59], v[54:57], off offset:-1792 sc1
	v_add_u32_e32 v8, 0x90, v150
	v_fma_f32 v52, -v50, v51, 1.0
	v_fmac_f32_e32 v51, v52, v51
	v_div_scale_f32 v52, vcc, 1.0, v46, 1.0
	v_mul_f32_e32 v53, v52, v51
	v_fma_f32 v54, -v50, v53, v52
	v_fmac_f32_e32 v53, v54, v51
	v_fma_f32 v50, -v50, v53, v52
	v_div_fmas_f32 v50, v50, v51, v53
	v_div_fixup_f32 v46, v50, v46, 1.0
	v_div_scale_f32 v50, s[0:1], v47, v47, 1.0
	v_rcp_f32_e32 v51, v50
	s_nop 0
	v_fma_f32 v52, -v50, v51, 1.0
	v_fmac_f32_e32 v51, v52, v51
	v_div_scale_f32 v52, vcc, 1.0, v47, 1.0
	v_mul_f32_e32 v53, v52, v51
	v_fma_f32 v54, -v50, v53, v52
	v_fmac_f32_e32 v53, v54, v51
	v_fma_f32 v50, -v50, v53, v52
	v_div_fmas_f32 v50, v50, v51, v53
	v_div_fixup_f32 v47, v50, v47, 1.0
	v_cvt_pk_bf16_f32 v46, v46, v47
	v_mul_f32_e32 v47, 0xbfb8aa3b, v48
	v_exp_f32_e32 v47, v47
	s_nop 0
	v_add_f32_e32 v47, 1.0, v47
	v_div_scale_f32 v48, s[0:1], v47, v47, 1.0
	v_rcp_f32_e32 v50, v48
	s_nop 0
	v_fma_f32 v51, -v48, v50, 1.0
	v_fmac_f32_e32 v50, v51, v50
	v_div_scale_f32 v51, vcc, 1.0, v47, 1.0
	v_mul_f32_e32 v52, v51, v50
	v_fma_f32 v53, -v48, v52, v51
	v_fmac_f32_e32 v52, v53, v50
	v_fma_f32 v48, -v48, v52, v51
	v_div_fmas_f32 v48, v48, v50, v52
	v_div_fixup_f32 v47, v48, v47, 1.0
	v_mul_f32_e32 v48, 0xbfb8aa3b, v49
	v_exp_f32_e32 v48, v48
	s_nop 0
	v_add_f32_e32 v48, 1.0, v48
	v_div_scale_f32 v49, s[0:1], v48, v48, 1.0
	v_rcp_f32_e32 v50, v49
	s_nop 0
	v_fma_f32 v51, -v49, v50, 1.0
	v_fmac_f32_e32 v50, v51, v50
	v_div_scale_f32 v51, vcc, 1.0, v48, 1.0
	v_mul_f32_e32 v52, v51, v50
	v_fma_f32 v53, -v49, v52, v51
	v_fmac_f32_e32 v52, v53, v50
	v_fma_f32 v49, -v49, v52, v51
	v_div_fmas_f32 v49, v49, v50, v52
	v_div_fixup_f32 v48, v49, v48, 1.0
	v_cvt_pk_bf16_f32 v47, v47, v48
	v_div_scale_f32 v48, s[0:1], v42, v42, 1.0
	v_rcp_f32_e32 v49, v48
	s_nop 0
	v_fma_f32 v50, -v48, v49, 1.0
	v_fmac_f32_e32 v49, v50, v49
	v_div_scale_f32 v50, vcc, 1.0, v42, 1.0
	v_mul_f32_e32 v51, v50, v49
	v_fma_f32 v52, -v48, v51, v50
	v_fmac_f32_e32 v51, v52, v49
	v_fma_f32 v48, -v48, v51, v50
	v_div_fmas_f32 v48, v48, v49, v51
	v_div_fixup_f32 v42, v48, v42, 1.0
	v_div_scale_f32 v48, s[0:1], v43, v43, 1.0
	v_rcp_f32_e32 v49, v48
	s_nop 0
	v_fma_f32 v50, -v48, v49, 1.0
	v_fmac_f32_e32 v49, v50, v49
	v_div_scale_f32 v50, vcc, 1.0, v43, 1.0
	v_mul_f32_e32 v51, v50, v49
	v_fma_f32 v52, -v48, v51, v50
	v_fmac_f32_e32 v51, v52, v49
	v_fma_f32 v48, -v48, v51, v50
	v_div_fmas_f32 v48, v48, v49, v51
	v_div_fixup_f32 v43, v48, v43, 1.0
	v_cvt_pk_bf16_f32 v48, v42, v43
	v_mul_f32_e32 v42, 0xbfb8aa3b, v44
	v_exp_f32_e32 v42, v42
	s_nop 0
	v_add_f32_e32 v42, 1.0, v42
	v_div_scale_f32 v43, s[0:1], v42, v42, 1.0
	v_rcp_f32_e32 v44, v43
	s_nop 0
	v_fma_f32 v49, -v43, v44, 1.0
	v_fmac_f32_e32 v44, v49, v44
	v_div_scale_f32 v49, vcc, 1.0, v42, 1.0
	v_mul_f32_e32 v50, v49, v44
	v_fma_f32 v51, -v43, v50, v49
	v_fmac_f32_e32 v50, v51, v44
	v_fma_f32 v43, -v43, v50, v49
	v_div_fmas_f32 v43, v43, v44, v50
	v_div_fixup_f32 v42, v43, v42, 1.0
	v_mul_f32_e32 v43, 0xbfb8aa3b, v45
	v_exp_f32_e32 v43, v43
	s_nop 0
	v_add_f32_e32 v43, 1.0, v43
	v_div_scale_f32 v44, s[0:1], v43, v43, 1.0
	v_rcp_f32_e32 v45, v44
	s_nop 0
	v_fma_f32 v49, -v44, v45, 1.0
	v_fmac_f32_e32 v45, v49, v45
	v_div_scale_f32 v49, vcc, 1.0, v43, 1.0
	v_mul_f32_e32 v50, v49, v45
	v_fma_f32 v51, -v44, v50, v49
	v_fmac_f32_e32 v50, v51, v45
	v_fma_f32 v44, -v44, v50, v49
	v_div_fmas_f32 v44, v44, v45, v50
	v_div_fixup_f32 v43, v44, v43, 1.0
	v_cvt_pk_bf16_f32 v49, v42, v43
	v_mad_i64_i32 v[42:43], s[0:1], v8, s2, v[122:123]
	v_mul_f32_e32 v8, 0xbfb8aa3b, v38
	v_exp_f32_e32 v8, v8
	v_lshl_add_u64 v[42:43], v[42:43], 0, v[124:125]
	v_add_co_u32_e32 v42, vcc, s3, v42
	v_add_f32_e32 v8, 1.0, v8
	v_div_scale_f32 v38, s[0:1], v8, v8, 1.0
	v_rcp_f32_e32 v44, v38
	v_addc_co_u32_e32 v43, vcc, -1, v43, vcc
	global_store_dwordx4 v[42:43], v[46:49], off offset:-2048 sc1
	v_fma_f32 v45, -v38, v44, 1.0
	v_fmac_f32_e32 v44, v45, v44
	v_div_scale_f32 v45, vcc, 1.0, v8, 1.0
	v_mul_f32_e32 v46, v45, v44
	v_fma_f32 v47, -v38, v46, v45
	v_fmac_f32_e32 v46, v47, v44
	v_fma_f32 v38, -v38, v46, v45
	v_div_fmas_f32 v38, v38, v44, v46
	v_div_fixup_f32 v8, v38, v8, 1.0
	v_mul_f32_e32 v38, 0xbfb8aa3b, v39
	v_exp_f32_e32 v38, v38
	s_nop 0
	v_add_f32_e32 v38, 1.0, v38
	v_div_scale_f32 v39, s[0:1], v38, v38, 1.0
	v_rcp_f32_e32 v44, v39
	s_nop 0
	v_fma_f32 v45, -v39, v44, 1.0
	v_fmac_f32_e32 v44, v45, v44
	v_div_scale_f32 v45, vcc, 1.0, v38, 1.0
	v_mul_f32_e32 v46, v45, v44
	v_fma_f32 v47, -v39, v46, v45
	v_fmac_f32_e32 v46, v47, v44
	v_fma_f32 v39, -v39, v46, v45
	v_div_fmas_f32 v39, v39, v44, v46
	v_div_fixup_f32 v38, v39, v38, 1.0
	v_cvt_pk_bf16_f32 v38, v8, v38
	v_mul_f32_e32 v8, 0xbfb8aa3b, v40
	v_exp_f32_e32 v8, v8
	s_nop 0
	v_add_f32_e32 v8, 1.0, v8
	v_div_scale_f32 v39, s[0:1], v8, v8, 1.0
	v_rcp_f32_e32 v40, v39
	s_nop 0
	v_fma_f32 v44, -v39, v40, 1.0
	v_fmac_f32_e32 v40, v44, v40
	v_div_scale_f32 v44, vcc, 1.0, v8, 1.0
	v_mul_f32_e32 v45, v44, v40
	v_fma_f32 v46, -v39, v45, v44
	v_fmac_f32_e32 v45, v46, v40
	v_fma_f32 v39, -v39, v45, v44
	v_div_fmas_f32 v39, v39, v40, v45
	v_div_fixup_f32 v8, v39, v8, 1.0
	v_mul_f32_e32 v39, 0xbfb8aa3b, v41
	v_exp_f32_e32 v39, v39
	s_nop 0
	v_add_f32_e32 v39, 1.0, v39
	v_div_scale_f32 v40, s[0:1], v39, v39, 1.0
	v_rcp_f32_e32 v41, v40
	s_nop 0
	v_fma_f32 v44, -v40, v41, 1.0
	v_fmac_f32_e32 v41, v44, v41
	v_div_scale_f32 v44, vcc, 1.0, v39, 1.0
	v_mul_f32_e32 v45, v44, v41
	v_fma_f32 v46, -v40, v45, v44
	v_fmac_f32_e32 v45, v46, v41
	v_fma_f32 v40, -v40, v45, v44
	v_div_fmas_f32 v40, v40, v41, v45
	v_div_fixup_f32 v39, v40, v39, 1.0
	v_cvt_pk_bf16_f32 v39, v8, v39
	v_mul_f32_e32 v8, 0xbfb8aa3b, v34
	v_exp_f32_e32 v8, v8
	s_nop 0
	v_add_f32_e32 v8, 1.0, v8
	v_div_scale_f32 v34, s[0:1], v8, v8, 1.0
	v_rcp_f32_e32 v40, v34
	s_nop 0
	v_fma_f32 v41, -v34, v40, 1.0
	v_fmac_f32_e32 v40, v41, v40
	v_div_scale_f32 v41, vcc, 1.0, v8, 1.0
	v_mul_f32_e32 v44, v41, v40
	v_fma_f32 v45, -v34, v44, v41
	v_fmac_f32_e32 v44, v45, v40
	v_fma_f32 v34, -v34, v44, v41
	v_div_fmas_f32 v34, v34, v40, v44
	v_div_fixup_f32 v8, v34, v8, 1.0
	v_mul_f32_e32 v34, 0xbfb8aa3b, v35
	v_exp_f32_e32 v34, v34
	s_nop 0
	v_add_f32_e32 v34, 1.0, v34
	v_div_scale_f32 v35, s[0:1], v34, v34, 1.0
	v_rcp_f32_e32 v40, v35
	s_nop 0
	v_fma_f32 v41, -v35, v40, 1.0
	v_fmac_f32_e32 v40, v41, v40
	v_div_scale_f32 v41, vcc, 1.0, v34, 1.0
	v_mul_f32_e32 v44, v41, v40
	v_fma_f32 v45, -v35, v44, v41
	v_fmac_f32_e32 v44, v45, v40
	v_fma_f32 v35, -v35, v44, v41
	v_div_fmas_f32 v35, v35, v40, v44
	v_div_fixup_f32 v34, v35, v34, 1.0
	v_cvt_pk_bf16_f32 v40, v8, v34
	v_mul_f32_e32 v8, 0xbfb8aa3b, v36
	v_exp_f32_e32 v8, v8
	s_nop 0
	v_add_f32_e32 v8, 1.0, v8
	v_div_scale_f32 v34, s[0:1], v8, v8, 1.0
	v_rcp_f32_e32 v35, v34
	s_nop 0
	v_fma_f32 v36, -v34, v35, 1.0
	v_fmac_f32_e32 v35, v36, v35
	v_div_scale_f32 v36, vcc, 1.0, v8, 1.0
	v_mul_f32_e32 v41, v36, v35
	v_fma_f32 v44, -v34, v41, v36
	v_fmac_f32_e32 v41, v44, v35
	v_fma_f32 v34, -v34, v41, v36
	v_div_fmas_f32 v34, v34, v35, v41
	v_div_fixup_f32 v8, v34, v8, 1.0
	v_mul_f32_e32 v34, 0xbfb8aa3b, v37
	v_exp_f32_e32 v34, v34
	s_nop 0
	v_add_f32_e32 v34, 1.0, v34
	v_div_scale_f32 v35, s[0:1], v34, v34, 1.0
	v_rcp_f32_e32 v36, v35
	s_nop 0
	v_fma_f32 v37, -v35, v36, 1.0
	v_fmac_f32_e32 v36, v37, v36
	v_div_scale_f32 v37, vcc, 1.0, v34, 1.0
	v_mul_f32_e32 v41, v37, v36
	v_fma_f32 v44, -v35, v41, v37
	v_fmac_f32_e32 v41, v44, v36
	v_fma_f32 v35, -v35, v41, v37
	v_div_fmas_f32 v35, v35, v36, v41
	v_div_fixup_f32 v34, v35, v34, 1.0
	v_cvt_pk_bf16_f32 v41, v8, v34
	v_div_scale_f32 v34, s[0:1], v30, v30, 1.0
	v_rcp_f32_e32 v35, v34
	global_store_dwordx4 v[42:43], v[38:41], off offset:-1792 sc1
	v_add_u32_e32 v8, 0xa0, v150
	v_fma_f32 v36, -v34, v35, 1.0
	v_fmac_f32_e32 v35, v36, v35
	v_div_scale_f32 v36, vcc, 1.0, v30, 1.0
	v_mul_f32_e32 v37, v36, v35
	v_fma_f32 v38, -v34, v37, v36
	v_fmac_f32_e32 v37, v38, v35
	v_fma_f32 v34, -v34, v37, v36
	v_div_fmas_f32 v34, v34, v35, v37
	v_div_fixup_f32 v30, v34, v30, 1.0
	v_div_scale_f32 v34, s[0:1], v31, v31, 1.0
	v_rcp_f32_e32 v35, v34
	s_nop 0
	v_fma_f32 v36, -v34, v35, 1.0
	v_fmac_f32_e32 v35, v36, v35
	v_div_scale_f32 v36, vcc, 1.0, v31, 1.0
	v_mul_f32_e32 v37, v36, v35
	v_fma_f32 v38, -v34, v37, v36
	v_fmac_f32_e32 v37, v38, v35
	v_fma_f32 v34, -v34, v37, v36
	v_div_fmas_f32 v34, v34, v35, v37
	v_div_fixup_f32 v31, v34, v31, 1.0
	v_cvt_pk_bf16_f32 v30, v30, v31
	v_mul_f32_e32 v31, 0xbfb8aa3b, v32
	v_exp_f32_e32 v31, v31
	s_nop 0
	v_add_f32_e32 v31, 1.0, v31
	v_div_scale_f32 v32, s[0:1], v31, v31, 1.0
	v_rcp_f32_e32 v34, v32
	s_nop 0
	v_fma_f32 v35, -v32, v34, 1.0
	v_fmac_f32_e32 v34, v35, v34
	v_div_scale_f32 v35, vcc, 1.0, v31, 1.0
	v_mul_f32_e32 v36, v35, v34
	v_fma_f32 v37, -v32, v36, v35
	v_fmac_f32_e32 v36, v37, v34
	v_fma_f32 v32, -v32, v36, v35
	v_div_fmas_f32 v32, v32, v34, v36
	v_div_fixup_f32 v31, v32, v31, 1.0
	v_mul_f32_e32 v32, 0xbfb8aa3b, v33
	v_exp_f32_e32 v32, v32
	s_nop 0
	v_add_f32_e32 v32, 1.0, v32
	v_div_scale_f32 v33, s[0:1], v32, v32, 1.0
	v_rcp_f32_e32 v34, v33
	s_nop 0
	v_fma_f32 v35, -v33, v34, 1.0
	v_fmac_f32_e32 v34, v35, v34
	v_div_scale_f32 v35, vcc, 1.0, v32, 1.0
	v_mul_f32_e32 v36, v35, v34
	v_fma_f32 v37, -v33, v36, v35
	v_fmac_f32_e32 v36, v37, v34
	v_fma_f32 v33, -v33, v36, v35
	v_div_fmas_f32 v33, v33, v34, v36
	v_div_fixup_f32 v32, v33, v32, 1.0
	v_cvt_pk_bf16_f32 v31, v31, v32
	v_div_scale_f32 v32, s[0:1], v26, v26, 1.0
	v_rcp_f32_e32 v33, v32
	s_nop 0
	v_fma_f32 v34, -v32, v33, 1.0
	v_fmac_f32_e32 v33, v34, v33
	v_div_scale_f32 v34, vcc, 1.0, v26, 1.0
	v_mul_f32_e32 v35, v34, v33
	v_fma_f32 v36, -v32, v35, v34
	v_fmac_f32_e32 v35, v36, v33
	v_fma_f32 v32, -v32, v35, v34
	v_div_fmas_f32 v32, v32, v33, v35
	v_div_fixup_f32 v26, v32, v26, 1.0
	v_div_scale_f32 v32, s[0:1], v27, v27, 1.0
	v_rcp_f32_e32 v33, v32
	s_nop 0
	v_fma_f32 v34, -v32, v33, 1.0
	v_fmac_f32_e32 v33, v34, v33
	v_div_scale_f32 v34, vcc, 1.0, v27, 1.0
	v_mul_f32_e32 v35, v34, v33
	v_fma_f32 v36, -v32, v35, v34
	v_fmac_f32_e32 v35, v36, v33
	v_fma_f32 v32, -v32, v35, v34
	v_div_fmas_f32 v32, v32, v33, v35
	v_div_fixup_f32 v27, v32, v27, 1.0
	v_cvt_pk_bf16_f32 v32, v26, v27
	v_mul_f32_e32 v26, 0xbfb8aa3b, v28
	v_exp_f32_e32 v26, v26
	s_nop 0
	v_add_f32_e32 v26, 1.0, v26
	v_div_scale_f32 v27, s[0:1], v26, v26, 1.0
	v_rcp_f32_e32 v28, v27
	s_nop 0
	v_fma_f32 v33, -v27, v28, 1.0
	v_fmac_f32_e32 v28, v33, v28
	v_div_scale_f32 v33, vcc, 1.0, v26, 1.0
	v_mul_f32_e32 v34, v33, v28
	v_fma_f32 v35, -v27, v34, v33
	v_fmac_f32_e32 v34, v35, v28
	v_fma_f32 v27, -v27, v34, v33
	v_div_fmas_f32 v27, v27, v28, v34
	v_div_fixup_f32 v26, v27, v26, 1.0
	v_mul_f32_e32 v27, 0xbfb8aa3b, v29
	v_exp_f32_e32 v27, v27
	s_nop 0
	v_add_f32_e32 v27, 1.0, v27
	v_div_scale_f32 v28, s[0:1], v27, v27, 1.0
	v_rcp_f32_e32 v29, v28
	s_nop 0
	v_fma_f32 v33, -v28, v29, 1.0
	v_fmac_f32_e32 v29, v33, v29
	v_div_scale_f32 v33, vcc, 1.0, v27, 1.0
	v_mul_f32_e32 v34, v33, v29
	v_fma_f32 v35, -v28, v34, v33
	v_fmac_f32_e32 v34, v35, v29
	v_fma_f32 v28, -v28, v34, v33
	v_div_fmas_f32 v28, v28, v29, v34
	v_div_fixup_f32 v27, v28, v27, 1.0
	v_cvt_pk_bf16_f32 v33, v26, v27
	v_mad_i64_i32 v[26:27], s[0:1], v8, s2, v[122:123]
	v_mul_f32_e32 v8, 0xbfb8aa3b, v22
	v_exp_f32_e32 v8, v8
	v_lshl_add_u64 v[26:27], v[26:27], 0, v[124:125]
	v_add_co_u32_e32 v26, vcc, s3, v26
	v_add_f32_e32 v8, 1.0, v8
	v_div_scale_f32 v22, s[0:1], v8, v8, 1.0
	v_rcp_f32_e32 v28, v22
	v_addc_co_u32_e32 v27, vcc, -1, v27, vcc
	global_store_dwordx4 v[26:27], v[30:33], off offset:-2048 sc1
	v_fma_f32 v29, -v22, v28, 1.0
	v_fmac_f32_e32 v28, v29, v28
	v_div_scale_f32 v29, vcc, 1.0, v8, 1.0
	v_mul_f32_e32 v30, v29, v28
	v_fma_f32 v31, -v22, v30, v29
	v_fmac_f32_e32 v30, v31, v28
	v_fma_f32 v22, -v22, v30, v29
	v_div_fmas_f32 v22, v22, v28, v30
	v_div_fixup_f32 v8, v22, v8, 1.0
	v_mul_f32_e32 v22, 0xbfb8aa3b, v23
	v_exp_f32_e32 v22, v22
	s_nop 0
	v_add_f32_e32 v22, 1.0, v22
	v_div_scale_f32 v23, s[0:1], v22, v22, 1.0
	v_rcp_f32_e32 v28, v23
	s_nop 0
	v_fma_f32 v29, -v23, v28, 1.0
	v_fmac_f32_e32 v28, v29, v28
	v_div_scale_f32 v29, vcc, 1.0, v22, 1.0
	v_mul_f32_e32 v30, v29, v28
	v_fma_f32 v31, -v23, v30, v29
	v_fmac_f32_e32 v30, v31, v28
	v_fma_f32 v23, -v23, v30, v29
	v_div_fmas_f32 v23, v23, v28, v30
	v_div_fixup_f32 v22, v23, v22, 1.0
	v_cvt_pk_bf16_f32 v22, v8, v22
	v_mul_f32_e32 v8, 0xbfb8aa3b, v24
	v_exp_f32_e32 v8, v8
	s_nop 0
	v_add_f32_e32 v8, 1.0, v8
	v_div_scale_f32 v23, s[0:1], v8, v8, 1.0
	v_rcp_f32_e32 v24, v23
	s_nop 0
	v_fma_f32 v28, -v23, v24, 1.0
	v_fmac_f32_e32 v24, v28, v24
	v_div_scale_f32 v28, vcc, 1.0, v8, 1.0
	v_mul_f32_e32 v29, v28, v24
	v_fma_f32 v30, -v23, v29, v28
	v_fmac_f32_e32 v29, v30, v24
	v_fma_f32 v23, -v23, v29, v28
	v_div_fmas_f32 v23, v23, v24, v29
	v_div_fixup_f32 v8, v23, v8, 1.0
	v_mul_f32_e32 v23, 0xbfb8aa3b, v25
	v_exp_f32_e32 v23, v23
	s_nop 0
	v_add_f32_e32 v23, 1.0, v23
	v_div_scale_f32 v24, s[0:1], v23, v23, 1.0
	v_rcp_f32_e32 v25, v24
	s_nop 0
	v_fma_f32 v28, -v24, v25, 1.0
	v_fmac_f32_e32 v25, v28, v25
	v_div_scale_f32 v28, vcc, 1.0, v23, 1.0
	v_mul_f32_e32 v29, v28, v25
	v_fma_f32 v30, -v24, v29, v28
	v_fmac_f32_e32 v29, v30, v25
	v_fma_f32 v24, -v24, v29, v28
	v_div_fmas_f32 v24, v24, v25, v29
	v_div_fixup_f32 v23, v24, v23, 1.0
	v_cvt_pk_bf16_f32 v23, v8, v23
	v_mul_f32_e32 v8, 0xbfb8aa3b, v18
	v_exp_f32_e32 v8, v8
	s_nop 0
	v_add_f32_e32 v8, 1.0, v8
	v_div_scale_f32 v18, s[0:1], v8, v8, 1.0
	v_rcp_f32_e32 v24, v18
	s_nop 0
	v_fma_f32 v25, -v18, v24, 1.0
	v_fmac_f32_e32 v24, v25, v24
	v_div_scale_f32 v25, vcc, 1.0, v8, 1.0
	v_mul_f32_e32 v28, v25, v24
	v_fma_f32 v29, -v18, v28, v25
	v_fmac_f32_e32 v28, v29, v24
	v_fma_f32 v18, -v18, v28, v25
	v_div_fmas_f32 v18, v18, v24, v28
	v_div_fixup_f32 v8, v18, v8, 1.0
	v_mul_f32_e32 v18, 0xbfb8aa3b, v19
	v_exp_f32_e32 v18, v18
	s_nop 0
	v_add_f32_e32 v18, 1.0, v18
	v_div_scale_f32 v19, s[0:1], v18, v18, 1.0
	v_rcp_f32_e32 v24, v19
	s_nop 0
	v_fma_f32 v25, -v19, v24, 1.0
	v_fmac_f32_e32 v24, v25, v24
	v_div_scale_f32 v25, vcc, 1.0, v18, 1.0
	v_mul_f32_e32 v28, v25, v24
	v_fma_f32 v29, -v19, v28, v25
	v_fmac_f32_e32 v28, v29, v24
	v_fma_f32 v19, -v19, v28, v25
	v_div_fmas_f32 v19, v19, v24, v28
	v_div_fixup_f32 v18, v19, v18, 1.0
	v_cvt_pk_bf16_f32 v24, v8, v18
	v_mul_f32_e32 v8, 0xbfb8aa3b, v20
	v_exp_f32_e32 v8, v8
	s_nop 0
	v_add_f32_e32 v8, 1.0, v8
	v_div_scale_f32 v18, s[0:1], v8, v8, 1.0
	v_rcp_f32_e32 v19, v18
	s_nop 0
	v_fma_f32 v20, -v18, v19, 1.0
	v_fmac_f32_e32 v19, v20, v19
	v_div_scale_f32 v20, vcc, 1.0, v8, 1.0
	v_mul_f32_e32 v25, v20, v19
	v_fma_f32 v28, -v18, v25, v20
	v_fmac_f32_e32 v25, v28, v19
	v_fma_f32 v18, -v18, v25, v20
	v_div_fmas_f32 v18, v18, v19, v25
	v_div_fixup_f32 v8, v18, v8, 1.0
	v_mul_f32_e32 v18, 0xbfb8aa3b, v21
	v_exp_f32_e32 v18, v18
	s_nop 0
	v_add_f32_e32 v18, 1.0, v18
	v_div_scale_f32 v19, s[0:1], v18, v18, 1.0
	v_rcp_f32_e32 v20, v19
	s_nop 0
	v_fma_f32 v21, -v19, v20, 1.0
	v_fmac_f32_e32 v20, v21, v20
	v_div_scale_f32 v21, vcc, 1.0, v18, 1.0
	v_mul_f32_e32 v25, v21, v20
	v_fma_f32 v28, -v19, v25, v21
	v_fmac_f32_e32 v25, v28, v20
	v_fma_f32 v19, -v19, v25, v21
	v_div_fmas_f32 v19, v19, v20, v25
	v_div_fixup_f32 v18, v19, v18, 1.0
	v_cvt_pk_bf16_f32 v25, v8, v18
	v_div_scale_f32 v18, s[0:1], v14, v14, 1.0
	v_rcp_f32_e32 v19, v18
	global_store_dwordx4 v[26:27], v[22:25], off offset:-1792 sc1
	v_add_u32_e32 v8, 0xb0, v150
	v_fma_f32 v20, -v18, v19, 1.0
	v_fmac_f32_e32 v19, v20, v19
	v_div_scale_f32 v20, vcc, 1.0, v14, 1.0
	v_mul_f32_e32 v21, v20, v19
	v_fma_f32 v22, -v18, v21, v20
	v_fmac_f32_e32 v21, v22, v19
	v_fma_f32 v18, -v18, v21, v20
	v_div_fmas_f32 v18, v18, v19, v21
	v_div_fixup_f32 v14, v18, v14, 1.0
	v_div_scale_f32 v18, s[0:1], v15, v15, 1.0
	v_rcp_f32_e32 v19, v18
	s_nop 0
	v_fma_f32 v20, -v18, v19, 1.0
	v_fmac_f32_e32 v19, v20, v19
	v_div_scale_f32 v20, vcc, 1.0, v15, 1.0
	v_mul_f32_e32 v21, v20, v19
	v_fma_f32 v22, -v18, v21, v20
	v_fmac_f32_e32 v21, v22, v19
	v_fma_f32 v18, -v18, v21, v20
	v_div_fmas_f32 v18, v18, v19, v21
	v_div_fixup_f32 v15, v18, v15, 1.0
	v_cvt_pk_bf16_f32 v14, v14, v15
	v_mul_f32_e32 v15, 0xbfb8aa3b, v16
	v_exp_f32_e32 v15, v15
	s_nop 0
	v_add_f32_e32 v15, 1.0, v15
	v_div_scale_f32 v16, s[0:1], v15, v15, 1.0
	v_rcp_f32_e32 v18, v16
	s_nop 0
	v_fma_f32 v19, -v16, v18, 1.0
	v_fmac_f32_e32 v18, v19, v18
	v_div_scale_f32 v19, vcc, 1.0, v15, 1.0
	v_mul_f32_e32 v20, v19, v18
	v_fma_f32 v21, -v16, v20, v19
	v_fmac_f32_e32 v20, v21, v18
	v_fma_f32 v16, -v16, v20, v19
	v_div_fmas_f32 v16, v16, v18, v20
	v_div_fixup_f32 v15, v16, v15, 1.0
	v_mul_f32_e32 v16, 0xbfb8aa3b, v17
	v_exp_f32_e32 v16, v16
	s_nop 0
	v_add_f32_e32 v16, 1.0, v16
	v_div_scale_f32 v17, s[0:1], v16, v16, 1.0
	v_rcp_f32_e32 v18, v17
	s_nop 0
	v_fma_f32 v19, -v17, v18, 1.0
	v_fmac_f32_e32 v18, v19, v18
	v_div_scale_f32 v19, vcc, 1.0, v16, 1.0
	v_mul_f32_e32 v20, v19, v18
	v_fma_f32 v21, -v17, v20, v19
	v_fmac_f32_e32 v20, v21, v18
	v_fma_f32 v17, -v17, v20, v19
	v_div_fmas_f32 v17, v17, v18, v20
	v_div_fixup_f32 v16, v17, v16, 1.0
	v_cvt_pk_bf16_f32 v15, v15, v16
	v_div_scale_f32 v16, s[0:1], v10, v10, 1.0
	v_rcp_f32_e32 v17, v16
	s_nop 0
	v_fma_f32 v18, -v16, v17, 1.0
	v_fmac_f32_e32 v17, v18, v17
	v_div_scale_f32 v18, vcc, 1.0, v10, 1.0
	v_mul_f32_e32 v19, v18, v17
	v_fma_f32 v20, -v16, v19, v18
	v_fmac_f32_e32 v19, v20, v17
	v_fma_f32 v16, -v16, v19, v18
	v_div_fmas_f32 v16, v16, v17, v19
	v_div_fixup_f32 v10, v16, v10, 1.0
	v_div_scale_f32 v16, s[0:1], v11, v11, 1.0
	v_rcp_f32_e32 v17, v16
	s_nop 0
	v_fma_f32 v18, -v16, v17, 1.0
	v_fmac_f32_e32 v17, v18, v17
	v_div_scale_f32 v18, vcc, 1.0, v11, 1.0
	v_mul_f32_e32 v19, v18, v17
	v_fma_f32 v20, -v16, v19, v18
	v_fmac_f32_e32 v19, v20, v17
	v_fma_f32 v16, -v16, v19, v18
	v_div_fmas_f32 v16, v16, v17, v19
	v_div_fixup_f32 v11, v16, v11, 1.0
	v_cvt_pk_bf16_f32 v16, v10, v11
	v_mul_f32_e32 v10, 0xbfb8aa3b, v12
	v_exp_f32_e32 v10, v10
	s_nop 0
	v_add_f32_e32 v10, 1.0, v10
	v_div_scale_f32 v11, s[0:1], v10, v10, 1.0
	v_rcp_f32_e32 v12, v11
	s_nop 0
	v_fma_f32 v17, -v11, v12, 1.0
	v_fmac_f32_e32 v12, v17, v12
	v_div_scale_f32 v17, vcc, 1.0, v10, 1.0
	v_mul_f32_e32 v18, v17, v12
	v_fma_f32 v19, -v11, v18, v17
	v_fmac_f32_e32 v18, v19, v12
	v_fma_f32 v11, -v11, v18, v17
	v_div_fmas_f32 v11, v11, v12, v18
	v_div_fixup_f32 v10, v11, v10, 1.0
	v_mul_f32_e32 v11, 0xbfb8aa3b, v13
	v_exp_f32_e32 v11, v11
	s_nop 0
	v_add_f32_e32 v11, 1.0, v11
	v_div_scale_f32 v12, s[0:1], v11, v11, 1.0
	v_rcp_f32_e32 v13, v12
	s_nop 0
	v_fma_f32 v17, -v12, v13, 1.0
	v_fmac_f32_e32 v13, v17, v13
	v_div_scale_f32 v17, vcc, 1.0, v11, 1.0
	v_mul_f32_e32 v18, v17, v13
	v_fma_f32 v19, -v12, v18, v17
	v_fmac_f32_e32 v18, v19, v13
	v_fma_f32 v12, -v12, v18, v17
	v_div_fmas_f32 v12, v12, v13, v18
	v_div_fixup_f32 v11, v12, v11, 1.0
	v_cvt_pk_bf16_f32 v17, v10, v11
	v_mad_i64_i32 v[10:11], s[0:1], v8, s2, v[122:123]
	v_div_scale_f32 v8, s[0:1], v4, v4, 1.0
	v_rcp_f32_e32 v12, v8
	v_lshl_add_u64 v[10:11], v[10:11], 0, v[124:125]
	v_add_co_u32_e32 v10, vcc, s3, v10
	v_fma_f32 v13, -v8, v12, 1.0
	s_nop 0
	v_addc_co_u32_e32 v11, vcc, -1, v11, vcc
	v_fmac_f32_e32 v12, v13, v12
	v_div_scale_f32 v13, vcc, 1.0, v4, 1.0
	global_store_dwordx4 v[10:11], v[14:17], off offset:-2048 sc1
	s_nop 1
	v_mul_f32_e32 v14, v13, v12
	v_fma_f32 v15, -v8, v14, v13
	v_fmac_f32_e32 v14, v15, v12
	v_fma_f32 v8, -v8, v14, v13
	v_div_fmas_f32 v8, v8, v12, v14
	v_div_fixup_f32 v4, v8, v4, 1.0
	v_div_scale_f32 v8, s[0:1], v5, v5, 1.0
	v_rcp_f32_e32 v12, v8
	s_nop 0
	v_fma_f32 v13, -v8, v12, 1.0
	v_fmac_f32_e32 v12, v13, v12
	v_div_scale_f32 v13, vcc, 1.0, v5, 1.0
	v_mul_f32_e32 v14, v13, v12
	v_fma_f32 v15, -v8, v14, v13
	v_fmac_f32_e32 v14, v15, v12
	v_fma_f32 v8, -v8, v14, v13
	v_div_fmas_f32 v8, v8, v12, v14
	v_div_fixup_f32 v5, v8, v5, 1.0
	v_cvt_pk_bf16_f32 v4, v4, v5
	v_mul_f32_e32 v5, 0xbfb8aa3b, v6
	v_exp_f32_e32 v5, v5
	s_nop 0
	v_add_f32_e32 v5, 1.0, v5
	v_div_scale_f32 v6, s[0:1], v5, v5, 1.0
	v_rcp_f32_e32 v8, v6
	s_nop 0
	v_fma_f32 v12, -v6, v8, 1.0
	v_fmac_f32_e32 v8, v12, v8
	v_div_scale_f32 v12, vcc, 1.0, v5, 1.0
	v_mul_f32_e32 v13, v12, v8
	v_fma_f32 v14, -v6, v13, v12
	v_fmac_f32_e32 v13, v14, v8
	v_fma_f32 v6, -v6, v13, v12
	v_div_fmas_f32 v6, v6, v8, v13
	v_div_fixup_f32 v5, v6, v5, 1.0
	v_mul_f32_e32 v6, 0xbfb8aa3b, v7
	v_exp_f32_e32 v6, v6
	s_nop 0
	v_add_f32_e32 v6, 1.0, v6
	v_div_scale_f32 v7, s[0:1], v6, v6, 1.0
	v_rcp_f32_e32 v8, v7
	s_nop 0
	v_fma_f32 v12, -v7, v8, 1.0
	v_fmac_f32_e32 v8, v12, v8
	v_div_scale_f32 v12, vcc, 1.0, v6, 1.0
	v_mul_f32_e32 v13, v12, v8
	v_fma_f32 v14, -v7, v13, v12
	v_fmac_f32_e32 v13, v14, v8
	v_fma_f32 v7, -v7, v13, v12
	v_div_fmas_f32 v7, v7, v8, v13
	v_div_fixup_f32 v6, v7, v6, 1.0
	v_cvt_pk_bf16_f32 v5, v5, v6
	v_div_scale_f32 v6, s[0:1], v0, v0, 1.0
	v_rcp_f32_e32 v7, v6
	s_nop 0
	v_fma_f32 v8, -v6, v7, 1.0
	v_fmac_f32_e32 v7, v8, v7
	v_div_scale_f32 v8, vcc, 1.0, v0, 1.0
	v_mul_f32_e32 v12, v8, v7
	v_fma_f32 v13, -v6, v12, v8
	v_fmac_f32_e32 v12, v13, v7
	v_fma_f32 v6, -v6, v12, v8
	v_div_fmas_f32 v6, v6, v7, v12
	v_div_fixup_f32 v0, v6, v0, 1.0
	v_div_scale_f32 v6, s[0:1], v1, v1, 1.0
	v_rcp_f32_e32 v7, v6
	s_nop 0
	v_fma_f32 v8, -v6, v7, 1.0
	v_fmac_f32_e32 v7, v8, v7
	v_div_scale_f32 v8, vcc, 1.0, v1, 1.0
	v_mul_f32_e32 v12, v8, v7
	v_fma_f32 v13, -v6, v12, v8
	v_fmac_f32_e32 v12, v13, v7
	v_fma_f32 v6, -v6, v12, v8
	v_div_fmas_f32 v6, v6, v7, v12
	v_div_fixup_f32 v1, v6, v1, 1.0
	v_cvt_pk_bf16_f32 v6, v0, v1
	v_mul_f32_e32 v0, 0xbfb8aa3b, v2
	v_exp_f32_e32 v0, v0
	s_nop 0
	v_add_f32_e32 v0, 1.0, v0
	v_div_scale_f32 v1, s[0:1], v0, v0, 1.0
	v_rcp_f32_e32 v2, v1
	s_nop 0
	v_fma_f32 v7, -v1, v2, 1.0
	v_fmac_f32_e32 v2, v7, v2
	v_div_scale_f32 v7, vcc, 1.0, v0, 1.0
	v_mul_f32_e32 v8, v7, v2
	v_fma_f32 v12, -v1, v8, v7
	v_fmac_f32_e32 v8, v12, v2
	v_fma_f32 v1, -v1, v8, v7
	v_div_fmas_f32 v1, v1, v2, v8
	v_div_fixup_f32 v0, v1, v0, 1.0
	v_mul_f32_e32 v1, 0xbfb8aa3b, v3
	v_exp_f32_e32 v1, v1
	s_nop 0
	v_add_f32_e32 v1, 1.0, v1
	v_div_scale_f32 v2, s[0:1], v1, v1, 1.0
	v_rcp_f32_e32 v3, v2
	s_nop 0
	v_fma_f32 v7, -v2, v3, 1.0
	v_fmac_f32_e32 v3, v7, v3
	v_div_scale_f32 v7, vcc, 1.0, v1, 1.0
	v_mul_f32_e32 v8, v7, v3
	v_fma_f32 v12, -v2, v8, v7
	v_fmac_f32_e32 v8, v12, v3
	v_fma_f32 v2, -v2, v8, v7
	v_div_fmas_f32 v2, v2, v3, v8
	v_div_fixup_f32 v1, v2, v1, 1.0
	v_cvt_pk_bf16_f32 v7, v0, v1
	global_store_dwordx4 v[10:11], v[4:7], off offset:-1792 sc1
	s_andn2_b64 vcc, exec, s[36:37]
	s_mov_b64 s[0:1], -1
	s_cbranch_vccnz .LBB0_63

.LBB0_675:
	v_lshl_add_u32 v132, s44, 8, v208
	v_mad_i64_i32 v[134:135], s[0:1], v132, s56, 0
	v_ashrrev_i32_e32 v131, 31, v130
	v_ashrrev_i32_e32 v133, 31, v132
	s_mov_b64 s[18:19], -1
	s_mov_b64 s[0:1], 0
	s_cmp_lt_i32 s42, 1
	s_mov_b64 s[14:15], 0
	s_cbranch_scc1 .LBB0_679
	s_cmp_eq_u32 s42, 1
	s_mov_b64 s[14:15], -1
	s_cbranch_scc0 .LBB0_678
	v_readlane_b32 s14, v252, 62
	v_readlane_b32 s15, v252, 63
	v_lshlrev_b64 v[140:141], 1, v[130:131]
	s_mov_b64 s[48:49], 0x1000
	v_lshl_add_u64 v[142:143], s[14:15], 0, v[134:135]
	v_lshl_add_u64 v[142:143], v[142:143], 0, v[140:141]
	s_waitcnt lgkmcnt(0)
	v_add_co_u32_e32 v168, vcc, 0x1000, v142
	v_lshl_add_u64 v[152:153], v[142:143], 0, s[48:49]
	s_nop 0
	v_addc_co_u32_e32 v169, vcc, 0, v143, vcc
	v_or_b32_e32 v160, 16, v132
	v_mov_b64_e32 v[142:143], s[14:15]
	s_movk_i32 s9, 0x3000
	v_readlane_b32 s18, v254, 20
	v_mad_i64_i32 v[162:163], s[14:15], v160, s9, v[142:143]
	v_lshlrev_b64 v[136:137], 2, v[130:131]
	v_readlane_b32 s19, v254, 21
	v_ashrrev_i32_e32 v161, 31, v160
	v_lshl_add_u64 v[162:163], v[162:163], 0, v[140:141]
	s_movk_i32 s20, 0x1000
	v_lshl_add_u64 v[138:139], s[18:19], 0, v[136:137]
	v_lshlrev_b64 v[176:177], 13, v[132:133]
	v_lshlrev_b64 v[184:185], 13, v[160:161]
	v_add_co_u32_e32 v160, vcc, s20, v162
	v_lshl_add_u64 v[156:157], v[138:139], 0, v[176:177]
	v_lshl_add_u64 v[170:171], v[162:163], 0, s[48:49]
	v_lshl_add_u64 v[172:173], v[138:139], 0, v[184:185]
	v_addc_co_u32_e32 v161, vcc, 0, v163, vcc
	global_load_dwordx4 v[144:147], v[156:157], off
	global_load_dwordx4 v[148:151], v[156:157], off offset:64
	global_load_dwordx2 v[178:179], v[152:153], off offset:32
	global_load_dwordx2 v[180:181], v[152:153], off offset:256
	global_load_dwordx2 v[182:183], v[152:153], off offset:288
	s_nop 0
	global_load_dwordx4 v[152:155], v[156:157], off offset:512
	s_nop 0
	global_load_dwordx4 v[156:159], v[156:157], off offset:576
	s_nop 0
	global_load_dwordx2 v[186:187], v[160:161], off
	s_nop 0
	global_load_dwordx4 v[160:163], v[172:173], off
	global_load_dwordx4 v[164:167], v[172:173], off offset:64
	global_load_dwordx2 v[188:189], v[168:169], off
	global_load_dwordx2 v[190:191], v[170:171], off offset:32
	global_load_dwordx2 v[192:193], v[170:171], off offset:256
	global_load_dwordx2 v[230:231], v[170:171], off offset:288
	s_nop 0
	global_load_dwordx4 v[168:171], v[172:173], off offset:512
	s_nop 0
	global_load_dwordx4 v[172:175], v[172:173], off offset:576
	s_waitcnt vmcnt(0)
	v_lshlrev_b32_e32 v232, 16, v188
	v_and_b32_e32 v233, 0xffff0000, v188
	v_lshlrev_b32_e32 v188, 16, v189
	v_and_b32_e32 v189, 0xffff0000, v189
	v_lshl_add_u64 v[176:177], s[18:19], 0, v[176:177]
	v_pk_fma_f32 v[146:147], v[108:109], v[188:189], v[146:147]
	v_pk_fma_f32 v[144:145], v[106:107], v[232:233], v[144:145]
	v_lshl_add_u64 v[176:177], v[176:177], 0, v[136:137]
	global_store_dwordx4 v[176:177], v[144:147], off sc1
	s_nop 1
	v_lshlrev_b32_e32 v144, 16, v178
	v_and_b32_e32 v145, 0xffff0000, v178
	v_lshlrev_b32_e32 v146, 16, v179
	v_and_b32_e32 v147, 0xffff0000, v179
	v_pk_fma_f32 v[146:147], v[100:101], v[146:147], v[150:151]
	v_pk_fma_f32 v[144:145], v[98:99], v[144:145], v[148:149]
	global_store_dwordx4 v[176:177], v[144:147], off offset:64 sc1
	v_lshl_add_u64 v[148:149], s[18:19], 0, v[184:185]
	v_lshl_add_u64 v[148:149], v[148:149], 0, v[136:137]
	v_lshlrev_b32_e32 v144, 16, v180
	v_and_b32_e32 v145, 0xffff0000, v180
	v_lshlrev_b32_e32 v146, 16, v181
	v_and_b32_e32 v147, 0xffff0000, v181
	v_pk_fma_f32 v[146:147], v[84:85], v[146:147], v[154:155]
	v_pk_fma_f32 v[144:145], v[82:83], v[144:145], v[152:153]
	global_store_dwordx4 v[176:177], v[144:147], off offset:512 sc1
	s_nop 1
	v_lshlrev_b32_e32 v144, 16, v182
	v_and_b32_e32 v145, 0xffff0000, v182
	v_lshlrev_b32_e32 v146, 16, v183
	v_and_b32_e32 v147, 0xffff0000, v183
	v_pk_fma_f32 v[146:147], v[76:77], v[146:147], v[158:159]
	v_pk_fma_f32 v[144:145], v[74:75], v[144:145], v[156:157]
	global_store_dwordx4 v[176:177], v[144:147], off offset:576 sc1
	s_nop 1
	v_lshlrev_b32_e32 v144, 16, v186
	v_and_b32_e32 v145, 0xffff0000, v186
	v_lshlrev_b32_e32 v146, 16, v187
	v_and_b32_e32 v147, 0xffff0000, v187
	v_pk_fma_f32 v[146:147], v[88:89], v[146:147], v[162:163]
	v_pk_fma_f32 v[144:145], v[86:87], v[144:145], v[160:161]
	global_store_dwordx4 v[148:149], v[144:147], off sc1
	v_or_b32_e32 v160, 48, v132
	v_mad_i64_i32 v[162:163], s[14:15], v160, s9, v[142:143]
	v_lshlrev_b32_e32 v144, 16, v190
	v_and_b32_e32 v145, 0xffff0000, v190
	v_lshlrev_b32_e32 v146, 16, v191
	v_and_b32_e32 v147, 0xffff0000, v191
	v_pk_fma_f32 v[146:147], v[80:81], v[146:147], v[166:167]
	v_pk_fma_f32 v[144:145], v[78:79], v[144:145], v[164:165]
	global_store_dwordx4 v[148:149], v[144:147], off offset:64 sc1
	v_ashrrev_i32_e32 v161, 31, v160
	v_lshl_add_u64 v[162:163], v[162:163], 0, v[140:141]
	v_lshlrev_b32_e32 v144, 16, v192
	v_and_b32_e32 v145, 0xffff0000, v192
	v_lshlrev_b32_e32 v146, 16, v193
	v_and_b32_e32 v147, 0xffff0000, v193
	v_pk_fma_f32 v[146:147], v[64:65], v[146:147], v[170:171]
	v_pk_fma_f32 v[144:145], v[62:63], v[144:145], v[168:169]
	global_store_dwordx4 v[148:149], v[144:147], off offset:512 sc1
	v_lshlrev_b64 v[184:185], 13, v[160:161]
	v_lshl_add_u64 v[170:171], v[162:163], 0, s[48:49]
	v_lshlrev_b32_e32 v144, 16, v230
	v_and_b32_e32 v145, 0xffff0000, v230
	v_lshlrev_b32_e32 v146, 16, v231
	v_and_b32_e32 v147, 0xffff0000, v231
	v_pk_fma_f32 v[146:147], v[56:57], v[146:147], v[174:175]
	v_pk_fma_f32 v[144:145], v[54:55], v[144:145], v[172:173]
	global_store_dwordx4 v[148:149], v[144:147], off offset:576 sc1
	v_lshl_add_u64 v[172:173], v[138:139], 0, v[184:185]
	s_nop 0
	v_or_b32_e32 v144, 32, v132
	v_mad_i64_i32 v[146:147], s[14:15], v144, s9, v[142:143]
	v_lshl_add_u64 v[146:147], v[146:147], 0, v[140:141]
	v_add_co_u32_e32 v168, vcc, s20, v146
	v_ashrrev_i32_e32 v145, 31, v144
	s_nop 0
	v_addc_co_u32_e32 v169, vcc, 0, v147, vcc
	v_lshlrev_b64 v[176:177], 13, v[144:145]
	v_add_co_u32_e32 v160, vcc, s20, v162
	v_lshl_add_u64 v[152:153], v[146:147], 0, s[48:49]
	v_lshl_add_u64 v[156:157], v[138:139], 0, v[176:177]
	v_addc_co_u32_e32 v161, vcc, 0, v163, vcc
	global_load_dwordx4 v[144:147], v[156:157], off
	global_load_dwordx4 v[148:151], v[156:157], off offset:64
	global_load_dwordx2 v[178:179], v[152:153], off offset:32
	global_load_dwordx2 v[180:181], v[152:153], off offset:256
	global_load_dwordx2 v[182:183], v[152:153], off offset:288
	s_nop 0
	global_load_dwordx4 v[152:155], v[156:157], off offset:512
	s_nop 0
	global_load_dwordx4 v[156:159], v[156:157], off offset:576
	s_nop 0
	global_load_dwordx2 v[186:187], v[160:161], off
	s_nop 0
	global_load_dwordx4 v[160:163], v[172:173], off
	global_load_dwordx4 v[164:167], v[172:173], off offset:64
	global_load_dwordx2 v[188:189], v[168:169], off
	global_load_dwordx2 v[190:191], v[170:171], off offset:32
	global_load_dwordx2 v[192:193], v[170:171], off offset:256
	global_load_dwordx2 v[230:231], v[170:171], off offset:288
	s_nop 0
	global_load_dwordx4 v[168:171], v[172:173], off offset:512
	s_nop 0
	global_load_dwordx4 v[172:175], v[172:173], off offset:576
	s_waitcnt vmcnt(5)
	v_lshlrev_b32_e32 v232, 16, v188
	v_and_b32_e32 v233, 0xffff0000, v188
	v_lshlrev_b32_e32 v188, 16, v189
	v_and_b32_e32 v189, 0xffff0000, v189
	v_lshl_add_u64 v[176:177], s[18:19], 0, v[176:177]
	v_pk_fma_f32 v[146:147], v[32:33], v[188:189], v[146:147]
	v_pk_fma_f32 v[144:145], v[30:31], v[232:233], v[144:145]
	v_lshl_add_u64 v[176:177], v[176:177], 0, v[136:137]
	global_store_dwordx4 v[176:177], v[144:147], off sc1
	s_nop 1
	v_lshlrev_b32_e32 v144, 16, v178
	v_and_b32_e32 v145, 0xffff0000, v178
	v_lshlrev_b32_e32 v146, 16, v179
	v_and_b32_e32 v147, 0xffff0000, v179
	v_pk_fma_f32 v[146:147], v[28:29], v[146:147], v[150:151]
	v_pk_fma_f32 v[144:145], v[26:27], v[144:145], v[148:149]
	global_store_dwordx4 v[176:177], v[144:147], off offset:64 sc1
	v_lshl_add_u64 v[148:149], s[18:19], 0, v[184:185]
	v_lshl_add_u64 v[148:149], v[148:149], 0, v[136:137]
	v_lshlrev_b32_e32 v144, 16, v180
	v_and_b32_e32 v145, 0xffff0000, v180
	v_lshlrev_b32_e32 v146, 16, v181
	v_and_b32_e32 v147, 0xffff0000, v181
	v_pk_fma_f32 v[146:147], v[24:25], v[146:147], v[154:155]
	v_pk_fma_f32 v[144:145], v[22:23], v[144:145], v[152:153]
	global_store_dwordx4 v[176:177], v[144:147], off offset:512 sc1
	s_nop 1
	v_lshlrev_b32_e32 v144, 16, v182
	v_and_b32_e32 v145, 0xffff0000, v182
	v_lshlrev_b32_e32 v146, 16, v183
	v_and_b32_e32 v147, 0xffff0000, v183
	v_pk_fma_f32 v[146:147], v[16:17], v[146:147], v[158:159]
	v_pk_fma_f32 v[144:145], v[14:15], v[144:145], v[156:157]
	global_store_dwordx4 v[176:177], v[144:147], off offset:576 sc1
	s_nop 1
	v_lshlrev_b32_e32 v144, 16, v186
	v_and_b32_e32 v145, 0xffff0000, v186
	v_lshlrev_b32_e32 v146, 16, v187
	v_and_b32_e32 v147, 0xffff0000, v187
	v_pk_fma_f32 v[146:147], v[20:21], v[146:147], v[162:163]
	v_pk_fma_f32 v[144:145], v[18:19], v[144:145], v[160:161]
	global_store_dwordx4 v[148:149], v[144:147], off sc1
	v_add_u32_e32 v160, 0x90, v132
	v_mad_i64_i32 v[162:163], s[14:15], v160, s9, v[142:143]
	s_waitcnt vmcnt(9)
	v_lshlrev_b32_e32 v144, 16, v190
	v_and_b32_e32 v145, 0xffff0000, v190
	v_lshlrev_b32_e32 v146, 16, v191
	v_and_b32_e32 v147, 0xffff0000, v191
	v_pk_fma_f32 v[146:147], v[12:13], v[146:147], v[166:167]
	v_pk_fma_f32 v[144:145], v[10:11], v[144:145], v[164:165]
	global_store_dwordx4 v[148:149], v[144:147], off offset:64 sc1
	v_ashrrev_i32_e32 v161, 31, v160
	v_lshl_add_u64 v[162:163], v[162:163], 0, v[140:141]
	s_waitcnt vmcnt(9)
	v_lshlrev_b32_e32 v144, 16, v192
	v_and_b32_e32 v145, 0xffff0000, v192
	v_lshlrev_b32_e32 v146, 16, v193
	v_and_b32_e32 v147, 0xffff0000, v193
	s_waitcnt vmcnt(7)
	v_pk_fma_f32 v[146:147], v[6:7], v[146:147], v[170:171]
	v_pk_fma_f32 v[144:145], v[4:5], v[144:145], v[168:169]
	global_store_dwordx4 v[148:149], v[144:147], off offset:512 sc1
	v_lshlrev_b64 v[184:185], 13, v[160:161]
	v_lshl_add_u64 v[170:171], v[162:163], 0, s[48:49]
	v_lshlrev_b32_e32 v144, 16, v230
	v_and_b32_e32 v145, 0xffff0000, v230
	v_lshlrev_b32_e32 v146, 16, v231
	v_and_b32_e32 v147, 0xffff0000, v231
	s_waitcnt vmcnt(7)
	v_pk_fma_f32 v[146:147], v[2:3], v[146:147], v[174:175]
	v_pk_fma_f32 v[144:145], v[0:1], v[144:145], v[172:173]
	global_store_dwordx4 v[148:149], v[144:147], off offset:576 sc1
	v_lshl_add_u64 v[172:173], v[138:139], 0, v[184:185]
	s_nop 0
	v_add_u32_e32 v144, 0x80, v132
	v_mad_i64_i32 v[146:147], s[14:15], v144, s9, v[142:143]
	v_lshl_add_u64 v[146:147], v[146:147], 0, v[140:141]
	v_add_co_u32_e32 v168, vcc, s20, v146
	v_ashrrev_i32_e32 v145, 31, v144
	s_nop 0
	v_addc_co_u32_e32 v169, vcc, 0, v147, vcc
	v_lshlrev_b64 v[176:177], 13, v[144:145]
	v_add_co_u32_e32 v160, vcc, s20, v162
	v_lshl_add_u64 v[152:153], v[146:147], 0, s[48:49]
	v_lshl_add_u64 v[156:157], v[138:139], 0, v[176:177]
	v_addc_co_u32_e32 v161, vcc, 0, v163, vcc
	global_load_dwordx4 v[144:147], v[156:157], off
	global_load_dwordx4 v[148:151], v[156:157], off offset:64
	global_load_dwordx2 v[178:179], v[152:153], off offset:32
	global_load_dwordx2 v[180:181], v[152:153], off offset:256
	global_load_dwordx2 v[182:183], v[152:153], off offset:288
	s_nop 0
	global_load_dwordx4 v[152:155], v[156:157], off offset:512
	s_nop 0
	global_load_dwordx4 v[156:159], v[156:157], off offset:576
	s_nop 0
	global_load_dwordx2 v[186:187], v[160:161], off
	s_nop 0
	global_load_dwordx4 v[160:163], v[172:173], off
	global_load_dwordx4 v[164:167], v[172:173], off offset:64
	global_load_dwordx2 v[188:189], v[168:169], off
	global_load_dwordx2 v[190:191], v[170:171], off offset:32
	global_load_dwordx2 v[192:193], v[170:171], off offset:256
	global_load_dwordx2 v[230:231], v[170:171], off offset:288
	s_nop 0
	global_load_dwordx4 v[168:171], v[172:173], off offset:512
	s_nop 0
	global_load_dwordx4 v[172:175], v[172:173], off offset:576
	s_waitcnt vmcnt(5)
	v_lshlrev_b32_e32 v232, 16, v188
	v_and_b32_e32 v233, 0xffff0000, v188
	v_lshlrev_b32_e32 v188, 16, v189
	v_and_b32_e32 v189, 0xffff0000, v189
	v_lshl_add_u64 v[176:177], s[18:19], 0, v[176:177]
	v_pk_fma_f32 v[146:147], v[128:129], v[188:189], v[146:147]
	v_pk_fma_f32 v[144:145], v[126:127], v[232:233], v[144:145]
	v_lshl_add_u64 v[176:177], v[176:177], 0, v[136:137]
	global_store_dwordx4 v[176:177], v[144:147], off sc1
	s_movk_i32 s56, 0x3000
	s_nop 0
	v_lshlrev_b32_e32 v144, 16, v178
	v_and_b32_e32 v145, 0xffff0000, v178
	v_lshlrev_b32_e32 v146, 16, v179
	v_and_b32_e32 v147, 0xffff0000, v179
	v_pk_fma_f32 v[146:147], v[124:125], v[146:147], v[150:151]
	v_pk_fma_f32 v[144:145], v[122:123], v[144:145], v[148:149]
	global_store_dwordx4 v[176:177], v[144:147], off offset:64 sc1
	v_lshl_add_u64 v[148:149], s[18:19], 0, v[184:185]
	v_lshl_add_u64 v[148:149], v[148:149], 0, v[136:137]
	v_lshlrev_b32_e32 v144, 16, v180
	v_and_b32_e32 v145, 0xffff0000, v180
	v_lshlrev_b32_e32 v146, 16, v181
	v_and_b32_e32 v147, 0xffff0000, v181
	v_pk_fma_f32 v[146:147], v[120:121], v[146:147], v[154:155]
	v_pk_fma_f32 v[144:145], v[118:119], v[144:145], v[152:153]
	global_store_dwordx4 v[176:177], v[144:147], off offset:512 sc1
	s_nop 1
	v_lshlrev_b32_e32 v144, 16, v182
	v_and_b32_e32 v145, 0xffff0000, v182
	v_lshlrev_b32_e32 v146, 16, v183
	v_and_b32_e32 v147, 0xffff0000, v183
	v_pk_fma_f32 v[146:147], v[116:117], v[146:147], v[158:159]
	v_pk_fma_f32 v[144:145], v[114:115], v[144:145], v[156:157]
	global_store_dwordx4 v[176:177], v[144:147], off offset:576 sc1
	s_nop 1
	v_lshlrev_b32_e32 v144, 16, v186
	v_and_b32_e32 v145, 0xffff0000, v186
	v_lshlrev_b32_e32 v146, 16, v187
	v_and_b32_e32 v147, 0xffff0000, v187
	v_pk_fma_f32 v[146:147], v[112:113], v[146:147], v[162:163]
	v_pk_fma_f32 v[144:145], v[110:111], v[144:145], v[160:161]
	global_store_dwordx4 v[148:149], v[144:147], off sc1
	v_add_u32_e32 v160, 0xb0, v132
	v_ashrrev_i32_e32 v161, 31, v160
	s_waitcnt vmcnt(9)
	v_lshlrev_b32_e32 v144, 16, v190
	v_and_b32_e32 v145, 0xffff0000, v190
	v_lshlrev_b32_e32 v146, 16, v191
	v_and_b32_e32 v147, 0xffff0000, v191
	v_pk_fma_f32 v[146:147], v[104:105], v[146:147], v[166:167]
	v_pk_fma_f32 v[144:145], v[102:103], v[144:145], v[164:165]
	global_store_dwordx4 v[148:149], v[144:147], off offset:64 sc1
	v_lshlrev_b64 v[180:181], 13, v[160:161]
	s_waitcnt vmcnt(9)
	v_lshlrev_b32_e32 v144, 16, v192
	v_and_b32_e32 v145, 0xffff0000, v192
	v_lshlrev_b32_e32 v146, 16, v193
	v_and_b32_e32 v147, 0xffff0000, v193
	s_waitcnt vmcnt(7)
	v_pk_fma_f32 v[146:147], v[96:97], v[146:147], v[170:171]
	v_pk_fma_f32 v[144:145], v[94:95], v[144:145], v[168:169]
	global_store_dwordx4 v[148:149], v[144:147], off offset:512 sc1
	v_lshl_add_u64 v[168:169], v[138:139], 0, v[180:181]
	s_nop 0
	v_lshlrev_b32_e32 v144, 16, v230
	v_and_b32_e32 v145, 0xffff0000, v230
	v_lshlrev_b32_e32 v146, 16, v231
	v_and_b32_e32 v147, 0xffff0000, v231
	s_waitcnt vmcnt(7)
	v_pk_fma_f32 v[146:147], v[92:93], v[146:147], v[174:175]
	v_pk_fma_f32 v[144:145], v[90:91], v[144:145], v[172:173]
	global_store_dwordx4 v[148:149], v[144:147], off offset:576 sc1
	s_nop 1
	v_add_u32_e32 v144, 0xa0, v132
	v_mad_i64_i32 v[146:147], s[14:15], v144, s9, v[142:143]
	v_lshl_add_u64 v[146:147], v[146:147], 0, v[140:141]
	v_ashrrev_i32_e32 v145, 31, v144
	v_add_co_u32_e32 v164, vcc, s20, v146
	v_mad_i64_i32 v[142:143], s[14:15], v160, s9, v[142:143]
	v_lshlrev_b64 v[172:173], 13, v[144:145]
	v_addc_co_u32_e32 v165, vcc, 0, v147, vcc
	v_lshl_add_u64 v[140:141], v[142:143], 0, v[140:141]
	v_lshl_add_u64 v[156:157], v[138:139], 0, v[172:173]
	v_add_co_u32_e32 v138, vcc, s20, v140
	v_lshl_add_u64 v[152:153], v[146:147], 0, s[48:49]
	s_nop 0
	v_addc_co_u32_e32 v139, vcc, 0, v141, vcc
	global_load_dwordx4 v[144:147], v[156:157], off
	global_load_dwordx4 v[148:151], v[156:157], off offset:64
	global_load_dwordx2 v[174:175], v[152:153], off offset:32
	global_load_dwordx2 v[176:177], v[152:153], off offset:256
	global_load_dwordx2 v[178:179], v[152:153], off offset:288
	s_nop 0
	global_load_dwordx4 v[152:155], v[156:157], off offset:512
	s_nop 0
	global_load_dwordx4 v[156:159], v[156:157], off offset:576
	v_lshl_add_u64 v[142:143], v[140:141], 0, s[48:49]
	global_load_dwordx2 v[182:183], v[138:139], off
	s_nop 0
	global_load_dwordx4 v[138:141], v[168:169], off
	global_load_dwordx4 v[160:163], v[168:169], off offset:64
	global_load_dwordx2 v[184:185], v[164:165], off
	global_load_dwordx2 v[186:187], v[142:143], off offset:32
	global_load_dwordx2 v[188:189], v[142:143], off offset:256
	global_load_dwordx2 v[190:191], v[142:143], off offset:288
	s_nop 0
	global_load_dwordx4 v[164:167], v[168:169], off offset:512
	s_nop 0
	global_load_dwordx4 v[168:171], v[168:169], off offset:576
	s_waitcnt vmcnt(5)
	v_lshlrev_b32_e32 v142, 16, v184
	v_and_b32_e32 v143, 0xffff0000, v184
	v_lshlrev_b32_e32 v184, 16, v185
	v_and_b32_e32 v185, 0xffff0000, v185
	v_pk_fma_f32 v[144:145], v[70:71], v[142:143], v[144:145]
	v_lshl_add_u64 v[142:143], s[18:19], 0, v[172:173]
	v_pk_fma_f32 v[146:147], v[72:73], v[184:185], v[146:147]
	v_lshl_add_u64 v[172:173], v[142:143], 0, v[136:137]
	global_store_dwordx4 v[172:173], v[144:147], off sc1
	v_lshlrev_b32_e32 v142, 16, v174
	v_and_b32_e32 v143, 0xffff0000, v174
	v_lshlrev_b32_e32 v144, 16, v175
	v_and_b32_e32 v145, 0xffff0000, v175
	v_pk_fma_f32 v[144:145], v[68:69], v[144:145], v[150:151]
	v_pk_fma_f32 v[142:143], v[66:67], v[142:143], v[148:149]
	global_store_dwordx4 v[172:173], v[142:145], off offset:64 sc1
	s_mov_b64 s[14:15], 0
	s_nop 0
	v_lshlrev_b32_e32 v142, 16, v176
	v_and_b32_e32 v143, 0xffff0000, v176
	v_lshlrev_b32_e32 v144, 16, v177
	v_and_b32_e32 v145, 0xffff0000, v177
	v_pk_fma_f32 v[144:145], v[60:61], v[144:145], v[154:155]
	v_pk_fma_f32 v[142:143], v[58:59], v[142:143], v[152:153]
	global_store_dwordx4 v[172:173], v[142:145], off offset:512 sc1
	s_nop 1
	v_lshlrev_b32_e32 v142, 16, v178
	v_and_b32_e32 v143, 0xffff0000, v178
	v_lshlrev_b32_e32 v144, 16, v179
	v_and_b32_e32 v145, 0xffff0000, v179
	v_pk_fma_f32 v[144:145], v[52:53], v[144:145], v[158:159]
	v_pk_fma_f32 v[142:143], v[50:51], v[142:143], v[156:157]
	global_store_dwordx4 v[172:173], v[142:145], off offset:576 sc1
	s_nop 1
	v_lshlrev_b32_e32 v142, 16, v182
	v_and_b32_e32 v143, 0xffff0000, v182
	v_lshlrev_b32_e32 v144, 16, v183
	v_and_b32_e32 v145, 0xffff0000, v183
	v_pk_fma_f32 v[138:139], v[46:47], v[142:143], v[138:139]
	v_lshl_add_u64 v[142:143], s[18:19], 0, v[180:181]
	v_pk_fma_f32 v[140:141], v[48:49], v[144:145], v[140:141]
	v_lshl_add_u64 v[142:143], v[142:143], 0, v[136:137]
	global_store_dwordx4 v[142:143], v[138:141], off sc1
	s_waitcnt vmcnt(9)
	v_lshlrev_b32_e32 v136, 16, v186
	v_and_b32_e32 v137, 0xffff0000, v186
	v_lshlrev_b32_e32 v138, 16, v187
	v_and_b32_e32 v139, 0xffff0000, v187
	v_pk_fma_f32 v[138:139], v[44:45], v[138:139], v[162:163]
	v_pk_fma_f32 v[136:137], v[42:43], v[136:137], v[160:161]
	global_store_dwordx4 v[142:143], v[136:139], off offset:64 sc1
	s_waitcnt vmcnt(9)
	s_nop 0
	v_lshlrev_b32_e32 v136, 16, v188
	v_and_b32_e32 v137, 0xffff0000, v188
	v_lshlrev_b32_e32 v138, 16, v189
	v_and_b32_e32 v139, 0xffff0000, v189
	s_waitcnt vmcnt(7)
	v_pk_fma_f32 v[138:139], v[40:41], v[138:139], v[166:167]
	v_pk_fma_f32 v[136:137], v[38:39], v[136:137], v[164:165]
	global_store_dwordx4 v[142:143], v[136:139], off offset:512 sc1
	s_nop 1
	v_lshlrev_b32_e32 v136, 16, v190
	v_and_b32_e32 v137, 0xffff0000, v190
	v_lshlrev_b32_e32 v138, 16, v191
	v_and_b32_e32 v139, 0xffff0000, v191
	s_waitcnt vmcnt(7)
	v_pk_fma_f32 v[138:139], v[36:37], v[138:139], v[170:171]
	v_pk_fma_f32 v[136:137], v[34:35], v[136:137], v[168:169]
	global_store_dwordx4 v[142:143], v[136:139], off offset:576 sc1

.LBB0_681:
	s_andn2_b64 vcc, exec, s[14:15]
	v_lshlrev_b64 v[146:147], 13, v[132:133]
	v_or_b32_e32 v144, 16, v132
	v_or_b32_e32 v142, 32, v132
	v_or_b32_e32 v140, 48, v132
	v_add_u32_e32 v138, 0x80, v132
	v_add_u32_e32 v136, 0x90, v132
	s_cbranch_vccnz .LBB0_683
	v_readlane_b32 s0, v254, 20
	v_readlane_b32 s1, v254, 21
	v_lshlrev_b64 v[148:149], 1, v[130:131]
	s_mov_b64 s[20:21], 0x2000
	v_lshl_add_u64 v[150:151], v[130:131], 2, s[0:1]
	v_readlane_b32 s0, v252, 62
	v_readlane_b32 s1, v252, 63
	s_movk_i32 s18, 0x3000
	v_ashrrev_i32_e32 v145, 31, v144
	v_lshl_add_u64 v[152:153], s[0:1], 0, v[134:135]
	v_lshl_add_u64 v[152:153], v[152:153], 0, v[148:149]
	s_waitcnt lgkmcnt(0)
	v_add_co_u32_e32 v178, vcc, 0x2000, v152
	v_lshl_add_u64 v[162:163], v[152:153], 0, s[20:21]
	s_nop 0
	v_addc_co_u32_e32 v179, vcc, 0, v153, vcc
	v_mov_b64_e32 v[152:153], s[0:1]
	v_mad_i64_i32 v[170:171], s[0:1], v144, s18, v[152:153]
	v_lshl_add_u64 v[170:171], v[170:171], 0, v[148:149]
	s_movk_i32 s9, 0x2000
	v_lshl_add_u64 v[180:181], v[170:171], 0, s[20:21]
	v_lshlrev_b64 v[172:173], 13, v[144:145]
	v_add_co_u32_e32 v170, vcc, s9, v170
	v_lshl_add_u64 v[166:167], v[150:151], 0, v[146:147]
	v_lshl_add_u64 v[182:183], v[150:151], 0, v[172:173]
	v_addc_co_u32_e32 v171, vcc, 0, v171, vcc
	global_load_dwordx4 v[154:157], v[166:167], off
	global_load_dwordx4 v[158:161], v[166:167], off offset:64
	global_load_dwordx2 v[186:187], v[162:163], off offset:32
	global_load_dwordx2 v[188:189], v[162:163], off offset:256
	global_load_dwordx2 v[190:191], v[162:163], off offset:288
	s_nop 0
	global_load_dwordx4 v[162:165], v[166:167], off offset:512
	s_nop 0
	global_load_dwordx4 v[166:169], v[166:167], off offset:576
	s_nop 0
	global_load_dwordx2 v[192:193], v[170:171], off
	s_nop 0
	global_load_dwordx4 v[170:173], v[182:183], off
	global_load_dwordx4 v[174:177], v[182:183], off offset:64
	global_load_dwordx2 v[230:231], v[178:179], off
	global_load_dwordx2 v[232:233], v[180:181], off offset:32
	global_load_dwordx2 v[234:235], v[180:181], off offset:256
	global_load_dwordx2 v[236:237], v[180:181], off offset:288
	s_nop 0
	global_load_dwordx4 v[178:181], v[182:183], off offset:512
	s_nop 0
	global_load_dwordx4 v[182:185], v[182:183], off offset:576
	s_waitcnt vmcnt(0)
	v_lshlrev_b32_e32 v194, 16, v230
	v_and_b32_e32 v195, 0xffff0000, v230
	v_lshlrev_b32_e32 v230, 16, v231
	v_and_b32_e32 v231, 0xffff0000, v231
	v_readlane_b32 s14, v252, 60
	v_lshlrev_b64 v[250:251], 12, v[132:133]
	v_pk_fma_f32 v[156:157], v[108:109], v[230:231], v[156:157]
	v_pk_fma_f32 v[154:155], v[106:107], v[194:195], v[154:155]
	v_readlane_b32 s15, v252, 61
	v_cvt_pk_bf16_f32 v154, v154, v155
	v_cvt_pk_bf16_f32 v155, v156, v157
	v_ashrrev_i32_e32 v143, 31, v142
	v_ashrrev_i32_e32 v141, 31, v140
	v_lshl_add_u64 v[156:157], s[14:15], 0, v[250:251]
	v_lshl_add_u64 v[156:157], v[156:157], 0, v[148:149]
	global_store_dwordx2 v[156:157], v[154:155], off sc1
	v_lshlrev_b32_e32 v154, 16, v186
	v_and_b32_e32 v155, 0xffff0000, v186
	v_lshlrev_b32_e32 v186, 16, v187
	v_and_b32_e32 v187, 0xffff0000, v187
	v_pk_fma_f32 v[154:155], v[98:99], v[154:155], v[158:159]
	v_pk_fma_f32 v[160:161], v[100:101], v[186:187], v[160:161]
	v_cvt_pk_bf16_f32 v154, v154, v155
	v_lshlrev_b32_e32 v158, 16, v189
	v_cvt_pk_bf16_f32 v155, v160, v161
	global_store_dwordx2 v[156:157], v[154:155], off offset:32 sc1
	v_lshlrev_b32_e32 v154, 16, v188
	v_and_b32_e32 v155, 0xffff0000, v188
	v_and_b32_e32 v159, 0xffff0000, v189
	v_pk_fma_f32 v[154:155], v[82:83], v[154:155], v[162:163]
	v_pk_fma_f32 v[158:159], v[84:85], v[158:159], v[164:165]
	v_cvt_pk_bf16_f32 v154, v154, v155
	s_nop 0
	v_cvt_pk_bf16_f32 v155, v158, v159
	global_store_dwordx2 v[156:157], v[154:155], off offset:256 sc1
	v_lshlrev_b32_e32 v154, 16, v190
	v_and_b32_e32 v155, 0xffff0000, v190
	v_lshlrev_b32_e32 v158, 16, v191
	v_and_b32_e32 v159, 0xffff0000, v191
	v_pk_fma_f32 v[154:155], v[74:75], v[154:155], v[166:167]
	v_pk_fma_f32 v[158:159], v[76:77], v[158:159], v[168:169]
	v_cvt_pk_bf16_f32 v154, v154, v155
	s_nop 0
	v_cvt_pk_bf16_f32 v155, v158, v159
	global_store_dwordx2 v[156:157], v[154:155], off offset:288 sc1
	v_lshlrev_b64 v[154:155], 12, v[144:145]
	v_lshlrev_b32_e32 v156, 16, v192
	v_and_b32_e32 v157, 0xffff0000, v192
	v_lshlrev_b32_e32 v158, 16, v193
	v_and_b32_e32 v159, 0xffff0000, v193
	v_pk_fma_f32 v[156:157], v[86:87], v[156:157], v[170:171]
	v_lshl_add_u64 v[154:155], s[14:15], 0, v[154:155]
	v_pk_fma_f32 v[158:159], v[88:89], v[158:159], v[172:173]
	v_cvt_pk_bf16_f32 v156, v156, v157
	v_lshl_add_u64 v[154:155], v[154:155], 0, v[148:149]
	v_cvt_pk_bf16_f32 v157, v158, v159
	global_store_dwordx2 v[154:155], v[156:157], off sc1
	v_lshlrev_b32_e32 v156, 16, v232
	v_and_b32_e32 v157, 0xffff0000, v232
	v_lshlrev_b32_e32 v158, 16, v233
	v_and_b32_e32 v159, 0xffff0000, v233
	v_pk_fma_f32 v[156:157], v[78:79], v[156:157], v[174:175]
	v_pk_fma_f32 v[158:159], v[80:81], v[158:159], v[176:177]
	v_cvt_pk_bf16_f32 v156, v156, v157
	v_mad_i64_i32 v[170:171], s[0:1], v140, s18, v[152:153]
	v_cvt_pk_bf16_f32 v157, v158, v159
	global_store_dwordx2 v[154:155], v[156:157], off offset:32 sc1
	v_lshlrev_b32_e32 v156, 16, v234
	v_and_b32_e32 v157, 0xffff0000, v234
	v_lshlrev_b32_e32 v158, 16, v235
	v_and_b32_e32 v159, 0xffff0000, v235
	v_pk_fma_f32 v[156:157], v[62:63], v[156:157], v[178:179]
	v_pk_fma_f32 v[158:159], v[64:65], v[158:159], v[180:181]
	v_cvt_pk_bf16_f32 v156, v156, v157
	v_lshl_add_u64 v[170:171], v[170:171], 0, v[148:149]
	v_cvt_pk_bf16_f32 v157, v158, v159
	global_store_dwordx2 v[154:155], v[156:157], off offset:256 sc1
	v_lshlrev_b32_e32 v156, 16, v236
	v_and_b32_e32 v157, 0xffff0000, v236
	v_lshlrev_b32_e32 v158, 16, v237
	v_and_b32_e32 v159, 0xffff0000, v237
	v_pk_fma_f32 v[156:157], v[54:55], v[156:157], v[182:183]
	v_pk_fma_f32 v[158:159], v[56:57], v[158:159], v[184:185]
	v_cvt_pk_bf16_f32 v156, v156, v157
	v_lshl_add_u64 v[180:181], v[170:171], 0, s[20:21]
	v_cvt_pk_bf16_f32 v157, v158, v159
	global_store_dwordx2 v[154:155], v[156:157], off offset:288 sc1
	v_mad_i64_i32 v[154:155], s[0:1], v142, s18, v[152:153]
	v_lshl_add_u64 v[154:155], v[154:155], 0, v[148:149]
	v_add_co_u32_e32 v178, vcc, s9, v154
	v_lshlrev_b64 v[156:157], 13, v[142:143]
	s_nop 0
	v_addc_co_u32_e32 v179, vcc, 0, v155, vcc
	v_lshlrev_b64 v[172:173], 13, v[140:141]
	v_add_co_u32_e32 v170, vcc, s9, v170
	v_lshl_add_u64 v[162:163], v[154:155], 0, s[20:21]
	v_lshl_add_u64 v[166:167], v[150:151], 0, v[156:157]
	v_lshl_add_u64 v[182:183], v[150:151], 0, v[172:173]
	v_addc_co_u32_e32 v171, vcc, 0, v171, vcc
	global_load_dwordx4 v[154:157], v[166:167], off
	global_load_dwordx4 v[158:161], v[166:167], off offset:64
	global_load_dwordx2 v[186:187], v[162:163], off offset:32
	global_load_dwordx2 v[188:189], v[162:163], off offset:256
	global_load_dwordx2 v[190:191], v[162:163], off offset:288
	s_nop 0
	global_load_dwordx4 v[162:165], v[166:167], off offset:512
	s_nop 0
	global_load_dwordx4 v[166:169], v[166:167], off offset:576
	s_nop 0
	global_load_dwordx2 v[192:193], v[170:171], off
	s_nop 0
	global_load_dwordx4 v[170:173], v[182:183], off
	global_load_dwordx4 v[174:177], v[182:183], off offset:64
	global_load_dwordx2 v[194:195], v[178:179], off
	global_load_dwordx2 v[230:231], v[180:181], off offset:32
	global_load_dwordx2 v[232:233], v[180:181], off offset:256
	global_load_dwordx2 v[234:235], v[180:181], off offset:288
	s_nop 0
	global_load_dwordx4 v[178:181], v[182:183], off offset:512
	s_nop 0
	global_load_dwordx4 v[182:185], v[182:183], off offset:576
	s_waitcnt vmcnt(5)
	v_lshlrev_b32_e32 v250, 16, v194
	v_and_b32_e32 v251, 0xffff0000, v194
	v_lshlrev_b32_e32 v194, 16, v195
	v_and_b32_e32 v195, 0xffff0000, v195
	v_lshlrev_b64 v[236:237], 12, v[142:143]
	v_pk_fma_f32 v[156:157], v[32:33], v[194:195], v[156:157]
	v_pk_fma_f32 v[154:155], v[30:31], v[250:251], v[154:155]
	v_ashrrev_i32_e32 v139, 31, v138
	v_cvt_pk_bf16_f32 v154, v154, v155
	v_cvt_pk_bf16_f32 v155, v156, v157
	v_lshl_add_u64 v[156:157], s[14:15], 0, v[236:237]
	v_lshl_add_u64 v[156:157], v[156:157], 0, v[148:149]
	global_store_dwordx2 v[156:157], v[154:155], off sc1
	v_lshlrev_b32_e32 v154, 16, v186
	v_and_b32_e32 v155, 0xffff0000, v186
	v_lshlrev_b32_e32 v186, 16, v187
	v_and_b32_e32 v187, 0xffff0000, v187
	v_pk_fma_f32 v[154:155], v[26:27], v[154:155], v[158:159]
	v_pk_fma_f32 v[160:161], v[28:29], v[186:187], v[160:161]
	v_cvt_pk_bf16_f32 v154, v154, v155
	v_lshlrev_b32_e32 v158, 16, v189
	v_cvt_pk_bf16_f32 v155, v160, v161
	global_store_dwordx2 v[156:157], v[154:155], off offset:32 sc1
	v_lshlrev_b32_e32 v154, 16, v188
	v_and_b32_e32 v155, 0xffff0000, v188
	v_and_b32_e32 v159, 0xffff0000, v189
	v_pk_fma_f32 v[154:155], v[22:23], v[154:155], v[162:163]
	v_pk_fma_f32 v[158:159], v[24:25], v[158:159], v[164:165]
	v_cvt_pk_bf16_f32 v154, v154, v155
	v_ashrrev_i32_e32 v137, 31, v136
	v_cvt_pk_bf16_f32 v155, v158, v159
	global_store_dwordx2 v[156:157], v[154:155], off offset:256 sc1
	v_lshlrev_b32_e32 v154, 16, v190
	v_and_b32_e32 v155, 0xffff0000, v190
	v_lshlrev_b32_e32 v158, 16, v191
	v_and_b32_e32 v159, 0xffff0000, v191
	v_pk_fma_f32 v[154:155], v[14:15], v[154:155], v[166:167]
	v_pk_fma_f32 v[158:159], v[16:17], v[158:159], v[168:169]
	v_cvt_pk_bf16_f32 v154, v154, v155
	s_nop 0
	v_cvt_pk_bf16_f32 v155, v158, v159
	global_store_dwordx2 v[156:157], v[154:155], off offset:288 sc1
	v_lshlrev_b64 v[154:155], 12, v[140:141]
	v_lshlrev_b32_e32 v156, 16, v192
	v_and_b32_e32 v157, 0xffff0000, v192
	v_lshlrev_b32_e32 v158, 16, v193
	v_and_b32_e32 v159, 0xffff0000, v193
	v_pk_fma_f32 v[156:157], v[18:19], v[156:157], v[170:171]
	v_lshl_add_u64 v[154:155], s[14:15], 0, v[154:155]
	v_pk_fma_f32 v[158:159], v[20:21], v[158:159], v[172:173]
	v_cvt_pk_bf16_f32 v156, v156, v157
	v_lshl_add_u64 v[154:155], v[154:155], 0, v[148:149]
	v_cvt_pk_bf16_f32 v157, v158, v159
	global_store_dwordx2 v[154:155], v[156:157], off sc1
	s_waitcnt vmcnt(9)
	v_lshlrev_b32_e32 v156, 16, v230
	v_and_b32_e32 v157, 0xffff0000, v230
	v_lshlrev_b32_e32 v158, 16, v231
	v_and_b32_e32 v159, 0xffff0000, v231
	v_pk_fma_f32 v[156:157], v[10:11], v[156:157], v[174:175]
	v_pk_fma_f32 v[158:159], v[12:13], v[158:159], v[176:177]
	v_cvt_pk_bf16_f32 v156, v156, v157
	v_mad_i64_i32 v[170:171], s[0:1], v136, s18, v[152:153]
	v_cvt_pk_bf16_f32 v157, v158, v159
	global_store_dwordx2 v[154:155], v[156:157], off offset:32 sc1
	s_waitcnt vmcnt(9)
	v_lshlrev_b32_e32 v156, 16, v232
	v_and_b32_e32 v157, 0xffff0000, v232
	v_lshlrev_b32_e32 v158, 16, v233
	v_and_b32_e32 v159, 0xffff0000, v233
	s_waitcnt vmcnt(7)
	v_pk_fma_f32 v[156:157], v[4:5], v[156:157], v[178:179]
	v_pk_fma_f32 v[158:159], v[6:7], v[158:159], v[180:181]
	v_cvt_pk_bf16_f32 v156, v156, v157
	v_lshl_add_u64 v[170:171], v[170:171], 0, v[148:149]
	v_cvt_pk_bf16_f32 v157, v158, v159
	global_store_dwordx2 v[154:155], v[156:157], off offset:256 sc1
	v_lshlrev_b32_e32 v156, 16, v234
	v_and_b32_e32 v157, 0xffff0000, v234
	v_lshlrev_b32_e32 v158, 16, v235
	v_and_b32_e32 v159, 0xffff0000, v235
	s_waitcnt vmcnt(7)
	v_pk_fma_f32 v[156:157], v[0:1], v[156:157], v[182:183]
	v_pk_fma_f32 v[158:159], v[2:3], v[158:159], v[184:185]
	v_cvt_pk_bf16_f32 v156, v156, v157
	v_lshl_add_u64 v[180:181], v[170:171], 0, s[20:21]
	v_cvt_pk_bf16_f32 v157, v158, v159
	global_store_dwordx2 v[154:155], v[156:157], off offset:288 sc1
	v_mad_i64_i32 v[154:155], s[0:1], v138, s18, v[152:153]
	v_lshl_add_u64 v[154:155], v[154:155], 0, v[148:149]
	v_add_co_u32_e32 v178, vcc, s9, v154
	v_lshlrev_b64 v[156:157], 13, v[138:139]
	s_nop 0
	v_addc_co_u32_e32 v179, vcc, 0, v155, vcc
	v_lshlrev_b64 v[172:173], 13, v[136:137]
	v_add_co_u32_e32 v170, vcc, s9, v170
	v_lshl_add_u64 v[162:163], v[154:155], 0, s[20:21]
	v_lshl_add_u64 v[166:167], v[150:151], 0, v[156:157]
	v_lshl_add_u64 v[182:183], v[150:151], 0, v[172:173]
	v_addc_co_u32_e32 v171, vcc, 0, v171, vcc
	global_load_dwordx4 v[154:157], v[166:167], off
	global_load_dwordx4 v[158:161], v[166:167], off offset:64
	global_load_dwordx2 v[186:187], v[162:163], off offset:32
	global_load_dwordx2 v[188:189], v[162:163], off offset:256
	global_load_dwordx2 v[190:191], v[162:163], off offset:288
	s_nop 0
	global_load_dwordx4 v[162:165], v[166:167], off offset:512
	s_nop 0
	global_load_dwordx4 v[166:169], v[166:167], off offset:576
	s_nop 0
	global_load_dwordx2 v[192:193], v[170:171], off
	s_nop 0
	global_load_dwordx4 v[170:173], v[182:183], off
	global_load_dwordx4 v[174:177], v[182:183], off offset:64
	global_load_dwordx2 v[194:195], v[178:179], off
	global_load_dwordx2 v[230:231], v[180:181], off offset:32
	global_load_dwordx2 v[232:233], v[180:181], off offset:256
	global_load_dwordx2 v[234:235], v[180:181], off offset:288
	s_nop 0
	global_load_dwordx4 v[178:181], v[182:183], off offset:512
	s_nop 0
	global_load_dwordx4 v[182:185], v[182:183], off offset:576
	s_waitcnt vmcnt(5)
	v_lshlrev_b32_e32 v250, 16, v194
	v_and_b32_e32 v251, 0xffff0000, v194
	v_lshlrev_b32_e32 v194, 16, v195
	v_and_b32_e32 v195, 0xffff0000, v195
	v_lshlrev_b64 v[236:237], 12, v[138:139]
	v_pk_fma_f32 v[156:157], v[128:129], v[194:195], v[156:157]
	v_pk_fma_f32 v[154:155], v[126:127], v[250:251], v[154:155]
	s_movk_i32 s56, 0x3000
	v_cvt_pk_bf16_f32 v154, v154, v155
	v_cvt_pk_bf16_f32 v155, v156, v157
	v_lshl_add_u64 v[156:157], s[14:15], 0, v[236:237]
	v_lshl_add_u64 v[156:157], v[156:157], 0, v[148:149]
	global_store_dwordx2 v[156:157], v[154:155], off sc1
	v_lshlrev_b32_e32 v154, 16, v186
	v_and_b32_e32 v155, 0xffff0000, v186
	v_lshlrev_b32_e32 v186, 16, v187
	v_and_b32_e32 v187, 0xffff0000, v187
	v_pk_fma_f32 v[154:155], v[122:123], v[154:155], v[158:159]
	v_pk_fma_f32 v[160:161], v[124:125], v[186:187], v[160:161]
	v_cvt_pk_bf16_f32 v154, v154, v155
	v_lshlrev_b32_e32 v158, 16, v189
	v_cvt_pk_bf16_f32 v155, v160, v161
	global_store_dwordx2 v[156:157], v[154:155], off offset:32 sc1
	v_lshlrev_b32_e32 v154, 16, v188
	v_and_b32_e32 v155, 0xffff0000, v188
	v_and_b32_e32 v159, 0xffff0000, v189
	v_pk_fma_f32 v[154:155], v[118:119], v[154:155], v[162:163]
	v_pk_fma_f32 v[158:159], v[120:121], v[158:159], v[164:165]
	v_cvt_pk_bf16_f32 v154, v154, v155
	s_movk_i32 s77, 0x2000
	v_cvt_pk_bf16_f32 v155, v158, v159
	global_store_dwordx2 v[156:157], v[154:155], off offset:256 sc1
	v_lshlrev_b32_e32 v154, 16, v190
	v_and_b32_e32 v155, 0xffff0000, v190
	v_lshlrev_b32_e32 v158, 16, v191
	v_and_b32_e32 v159, 0xffff0000, v191
	v_pk_fma_f32 v[154:155], v[114:115], v[154:155], v[166:167]
	v_pk_fma_f32 v[158:159], v[116:117], v[158:159], v[168:169]
	v_cvt_pk_bf16_f32 v154, v154, v155
	v_add_u32_e32 v190, 0xb0, v132
	v_cvt_pk_bf16_f32 v155, v158, v159
	global_store_dwordx2 v[156:157], v[154:155], off offset:288 sc1
	v_lshlrev_b64 v[154:155], 12, v[136:137]
	v_lshlrev_b32_e32 v156, 16, v192
	v_and_b32_e32 v157, 0xffff0000, v192
	v_lshlrev_b32_e32 v158, 16, v193
	v_and_b32_e32 v159, 0xffff0000, v193
	v_pk_fma_f32 v[156:157], v[110:111], v[156:157], v[170:171]
	v_lshl_add_u64 v[154:155], s[14:15], 0, v[154:155]
	v_pk_fma_f32 v[158:159], v[112:113], v[158:159], v[172:173]
	v_cvt_pk_bf16_f32 v156, v156, v157
	v_lshl_add_u64 v[154:155], v[154:155], 0, v[148:149]
	v_cvt_pk_bf16_f32 v157, v158, v159
	global_store_dwordx2 v[154:155], v[156:157], off sc1
	s_waitcnt vmcnt(9)
	v_lshlrev_b32_e32 v156, 16, v230
	v_and_b32_e32 v157, 0xffff0000, v230
	v_lshlrev_b32_e32 v158, 16, v231
	v_and_b32_e32 v159, 0xffff0000, v231
	v_pk_fma_f32 v[156:157], v[102:103], v[156:157], v[174:175]
	v_pk_fma_f32 v[158:159], v[104:105], v[158:159], v[176:177]
	v_cvt_pk_bf16_f32 v156, v156, v157
	v_ashrrev_i32_e32 v191, 31, v190
	v_cvt_pk_bf16_f32 v157, v158, v159
	global_store_dwordx2 v[154:155], v[156:157], off offset:32 sc1
	s_waitcnt vmcnt(9)
	v_lshlrev_b32_e32 v156, 16, v232
	v_and_b32_e32 v157, 0xffff0000, v232
	v_lshlrev_b32_e32 v158, 16, v233
	v_and_b32_e32 v159, 0xffff0000, v233
	s_waitcnt vmcnt(7)
	v_pk_fma_f32 v[156:157], v[94:95], v[156:157], v[178:179]
	v_pk_fma_f32 v[158:159], v[96:97], v[158:159], v[180:181]
	v_cvt_pk_bf16_f32 v156, v156, v157
	v_lshlrev_b64 v[170:171], 13, v[190:191]
	v_cvt_pk_bf16_f32 v157, v158, v159
	global_store_dwordx2 v[154:155], v[156:157], off offset:256 sc1
	v_lshlrev_b32_e32 v156, 16, v234
	v_and_b32_e32 v157, 0xffff0000, v234
	v_lshlrev_b32_e32 v158, 16, v235
	v_and_b32_e32 v159, 0xffff0000, v235
	s_waitcnt vmcnt(7)
	v_pk_fma_f32 v[156:157], v[90:91], v[156:157], v[182:183]
	v_add_u32_e32 v182, 0xa0, v132
	v_pk_fma_f32 v[158:159], v[92:93], v[158:159], v[184:185]
	v_cvt_pk_bf16_f32 v156, v156, v157
	v_ashrrev_i32_e32 v183, 31, v182
	v_cvt_pk_bf16_f32 v157, v158, v159
	global_store_dwordx2 v[154:155], v[156:157], off offset:288 sc1
	v_mad_i64_i32 v[154:155], s[0:1], v182, s18, v[152:153]
	v_lshl_add_u64 v[154:155], v[154:155], 0, v[148:149]
	v_add_co_u32_e32 v174, vcc, s9, v154
	v_mad_i64_i32 v[152:153], s[0:1], v190, s18, v[152:153]
	v_lshlrev_b64 v[156:157], 13, v[182:183]
	v_addc_co_u32_e32 v175, vcc, 0, v155, vcc
	v_lshl_add_u64 v[152:153], v[152:153], 0, v[148:149]
	v_lshl_add_u64 v[166:167], v[150:151], 0, v[156:157]
	v_lshl_add_u64 v[178:179], v[150:151], 0, v[170:171]
	v_add_co_u32_e32 v150, vcc, s9, v152
	v_lshl_add_u64 v[162:163], v[154:155], 0, s[20:21]
	v_lshl_add_u64 v[176:177], v[152:153], 0, s[20:21]
	v_addc_co_u32_e32 v151, vcc, 0, v153, vcc
	global_load_dwordx4 v[154:157], v[166:167], off
	global_load_dwordx4 v[158:161], v[166:167], off offset:64
	global_load_dwordx2 v[184:185], v[162:163], off offset:32
	global_load_dwordx2 v[186:187], v[162:163], off offset:256
	global_load_dwordx2 v[188:189], v[162:163], off offset:288
	s_nop 0
	global_load_dwordx4 v[162:165], v[166:167], off offset:512
	s_nop 0
	global_load_dwordx4 v[166:169], v[166:167], off offset:576
	s_nop 0
	global_load_dwordx2 v[192:193], v[150:151], off
	s_nop 0
	global_load_dwordx4 v[150:153], v[178:179], off
	global_load_dwordx4 v[170:173], v[178:179], off offset:64
	global_load_dwordx2 v[194:195], v[174:175], off
	global_load_dwordx2 v[230:231], v[176:177], off offset:32
	global_load_dwordx2 v[232:233], v[176:177], off offset:256
	global_load_dwordx2 v[234:235], v[176:177], off offset:288
	s_nop 0
	global_load_dwordx4 v[174:177], v[178:179], off offset:512
	s_nop 0
	global_load_dwordx4 v[178:181], v[178:179], off offset:576
	s_waitcnt vmcnt(5)
	v_lshlrev_b32_e32 v236, 16, v194
	v_and_b32_e32 v237, 0xffff0000, v194
	v_lshlrev_b32_e32 v194, 16, v195
	v_and_b32_e32 v195, 0xffff0000, v195
	v_lshlrev_b64 v[182:183], 12, v[182:183]
	v_pk_fma_f32 v[156:157], v[72:73], v[194:195], v[156:157]
	v_pk_fma_f32 v[154:155], v[70:71], v[236:237], v[154:155]
	s_mov_b64 s[0:1], 0
	v_cvt_pk_bf16_f32 v154, v154, v155
	v_cvt_pk_bf16_f32 v155, v156, v157
	v_lshl_add_u64 v[156:157], s[14:15], 0, v[182:183]
	v_lshl_add_u64 v[156:157], v[156:157], 0, v[148:149]
	global_store_dwordx2 v[156:157], v[154:155], off sc1
	v_lshlrev_b32_e32 v154, 16, v184
	v_and_b32_e32 v155, 0xffff0000, v184
	v_lshlrev_b32_e32 v182, 16, v185
	v_and_b32_e32 v183, 0xffff0000, v185
	v_pk_fma_f32 v[154:155], v[66:67], v[154:155], v[158:159]
	v_pk_fma_f32 v[160:161], v[68:69], v[182:183], v[160:161]
	v_cvt_pk_bf16_f32 v154, v154, v155
	v_lshlrev_b32_e32 v158, 16, v187
	v_cvt_pk_bf16_f32 v155, v160, v161
	global_store_dwordx2 v[156:157], v[154:155], off offset:32 sc1
	v_lshlrev_b32_e32 v154, 16, v186
	v_and_b32_e32 v155, 0xffff0000, v186
	v_and_b32_e32 v159, 0xffff0000, v187
	v_pk_fma_f32 v[154:155], v[58:59], v[154:155], v[162:163]
	v_pk_fma_f32 v[158:159], v[60:61], v[158:159], v[164:165]
	v_cvt_pk_bf16_f32 v154, v154, v155
	s_nop 0
	v_cvt_pk_bf16_f32 v155, v158, v159
	global_store_dwordx2 v[156:157], v[154:155], off offset:256 sc1
	v_lshlrev_b32_e32 v154, 16, v188
	v_and_b32_e32 v155, 0xffff0000, v188
	v_lshlrev_b32_e32 v158, 16, v189
	v_and_b32_e32 v159, 0xffff0000, v189
	v_pk_fma_f32 v[158:159], v[52:53], v[158:159], v[168:169]
	v_pk_fma_f32 v[154:155], v[50:51], v[154:155], v[166:167]
	s_nop 0
	v_cvt_pk_bf16_f32 v154, v154, v155
	v_cvt_pk_bf16_f32 v155, v158, v159
	global_store_dwordx2 v[156:157], v[154:155], off offset:288 sc1
	v_lshlrev_b32_e32 v156, 16, v192
	v_and_b32_e32 v157, 0xffff0000, v192
	v_lshlrev_b32_e32 v158, 16, v193
	v_and_b32_e32 v159, 0xffff0000, v193
	v_lshlrev_b64 v[154:155], 12, v[190:191]
	v_pk_fma_f32 v[152:153], v[48:49], v[158:159], v[152:153]
	v_pk_fma_f32 v[150:151], v[46:47], v[156:157], v[150:151]
	s_nop 0
	v_cvt_pk_bf16_f32 v150, v150, v151
	v_cvt_pk_bf16_f32 v151, v152, v153
	v_lshl_add_u64 v[152:153], s[14:15], 0, v[154:155]
	v_lshl_add_u64 v[148:149], v[152:153], 0, v[148:149]
	global_store_dwordx2 v[148:149], v[150:151], off sc1
	s_waitcnt vmcnt(9)
	v_lshlrev_b32_e32 v150, 16, v230
	v_and_b32_e32 v151, 0xffff0000, v230
	v_lshlrev_b32_e32 v152, 16, v231
	v_and_b32_e32 v153, 0xffff0000, v231
	v_pk_fma_f32 v[150:151], v[42:43], v[150:151], v[170:171]
	v_pk_fma_f32 v[152:153], v[44:45], v[152:153], v[172:173]
	v_cvt_pk_bf16_f32 v150, v150, v151
	s_nop 0
	v_cvt_pk_bf16_f32 v151, v152, v153
	global_store_dwordx2 v[148:149], v[150:151], off offset:32 sc1
	s_waitcnt vmcnt(9)
	v_lshlrev_b32_e32 v150, 16, v232
	v_and_b32_e32 v151, 0xffff0000, v232
	v_lshlrev_b32_e32 v152, 16, v233
	v_and_b32_e32 v153, 0xffff0000, v233
	s_waitcnt vmcnt(7)
	v_pk_fma_f32 v[150:151], v[38:39], v[150:151], v[174:175]
	v_pk_fma_f32 v[152:153], v[40:41], v[152:153], v[176:177]
	v_cvt_pk_bf16_f32 v150, v150, v151
	s_nop 0
	v_cvt_pk_bf16_f32 v151, v152, v153
	global_store_dwordx2 v[148:149], v[150:151], off offset:256 sc1
	v_lshlrev_b32_e32 v150, 16, v234
	v_and_b32_e32 v151, 0xffff0000, v234
	v_lshlrev_b32_e32 v152, 16, v235
	v_and_b32_e32 v153, 0xffff0000, v235
	s_waitcnt vmcnt(7)
	v_pk_fma_f32 v[150:151], v[34:35], v[150:151], v[178:179]
	v_pk_fma_f32 v[152:153], v[36:37], v[152:153], v[180:181]
	v_cvt_pk_bf16_f32 v150, v150, v151
	s_nop 0
	v_cvt_pk_bf16_f32 v151, v152, v153
	global_store_dwordx2 v[148:149], v[150:151], off offset:288 sc1
.LBB0_683:
	s_andn2_b64 vcc, exec, s[0:1]
	s_cbranch_vccnz .LBB0_685
	v_readlane_b32 s0, v252, 62
	v_readlane_b32 s1, v252, 63
	s_movk_i32 s9, 0x3000
	v_ashrrev_i32_e32 v145, 31, v144
	v_lshl_add_u64 v[148:149], v[130:131], 1, s[0:1]
	v_lshl_add_u64 v[134:135], v[148:149], 0, v[134:135]
	global_load_dwordx2 v[152:153], v[134:135], off
	global_load_dwordx2 v[154:155], v[134:135], off offset:32
	global_load_dwordx2 v[156:157], v[134:135], off offset:256
	global_load_dwordx2 v[158:159], v[134:135], off offset:288
	v_mad_i64_i32 v[134:135], s[0:1], v144, s9, v[148:149]
	global_load_dwordx2 v[160:161], v[134:135], off
	s_waitcnt lgkmcnt(0)
	global_load_dwordx2 v[162:163], v[134:135], off offset:32
	global_load_dwordx2 v[164:165], v[134:135], off offset:256
	global_load_dwordx2 v[166:167], v[134:135], off offset:288
	s_waitcnt vmcnt(0)
	v_lshlrev_b32_e32 v134, 16, v152
	v_and_b32_e32 v135, 0xffff0000, v152
	v_readlane_b32 s14, v254, 20
	v_pk_mul_f32 v[150:151], v[106:107], v[134:135]
	v_lshlrev_b32_e32 v134, 16, v153
	v_and_b32_e32 v135, 0xffff0000, v153
	v_readlane_b32 s15, v254, 21
	v_pk_mul_f32 v[152:153], v[108:109], v[134:135]
	v_lshlrev_b64 v[134:135], 2, v[130:131]
	v_lshl_add_u64 v[146:147], s[14:15], 0, v[146:147]
	v_lshl_add_u64 v[146:147], v[146:147], 0, v[134:135]
	global_store_dwordx4 v[146:147], v[150:153], off sc1
	v_ashrrev_i32_e32 v143, 31, v142
	v_ashrrev_i32_e32 v141, 31, v140
	v_lshlrev_b32_e32 v150, 16, v154
	v_and_b32_e32 v151, 0xffff0000, v154
	v_lshlrev_b32_e32 v152, 16, v155
	v_and_b32_e32 v153, 0xffff0000, v155
	v_pk_mul_f32 v[150:151], v[98:99], v[150:151]
	v_pk_mul_f32 v[152:153], v[100:101], v[152:153]
	global_store_dwordx4 v[146:147], v[150:153], off offset:64 sc1
	s_nop 1
	v_lshlrev_b32_e32 v150, 16, v156
	v_and_b32_e32 v151, 0xffff0000, v156
	v_lshlrev_b32_e32 v152, 16, v157
	v_and_b32_e32 v153, 0xffff0000, v157
	v_pk_mul_f32 v[150:151], v[82:83], v[150:151]
	v_pk_mul_f32 v[152:153], v[84:85], v[152:153]
	global_store_dwordx4 v[146:147], v[150:153], off offset:512 sc1
	s_nop 1
	v_lshlrev_b32_e32 v150, 16, v158
	v_and_b32_e32 v151, 0xffff0000, v158
	v_lshlrev_b32_e32 v152, 16, v159
	v_and_b32_e32 v153, 0xffff0000, v159
	v_pk_mul_f32 v[150:151], v[74:75], v[150:151]
	v_pk_mul_f32 v[152:153], v[76:77], v[152:153]
	global_store_dwordx4 v[146:147], v[150:153], off offset:576 sc1
	v_lshlrev_b32_e32 v146, 16, v161
	v_and_b32_e32 v147, 0xffff0000, v161
	v_lshlrev_b64 v[150:151], 13, v[144:145]
	v_lshlrev_b32_e32 v144, 16, v160
	v_and_b32_e32 v145, 0xffff0000, v160
	v_lshl_add_u64 v[150:151], s[14:15], 0, v[150:151]
	v_pk_mul_f32 v[144:145], v[86:87], v[144:145]
	v_pk_mul_f32 v[146:147], v[88:89], v[146:147]
	v_lshl_add_u64 v[150:151], v[150:151], 0, v[134:135]
	global_store_dwordx4 v[150:151], v[144:147], off sc1
	s_nop 1
	v_lshlrev_b32_e32 v144, 16, v162
	v_and_b32_e32 v145, 0xffff0000, v162
	v_lshlrev_b32_e32 v146, 16, v163
	v_and_b32_e32 v147, 0xffff0000, v163
	v_pk_mul_f32 v[144:145], v[78:79], v[144:145]
	v_pk_mul_f32 v[146:147], v[80:81], v[146:147]
	global_store_dwordx4 v[150:151], v[144:147], off offset:64 sc1
	s_nop 1
	v_lshlrev_b32_e32 v144, 16, v164
	v_and_b32_e32 v145, 0xffff0000, v164
	v_lshlrev_b32_e32 v146, 16, v165
	v_and_b32_e32 v147, 0xffff0000, v165
	v_pk_mul_f32 v[144:145], v[62:63], v[144:145]
	v_pk_mul_f32 v[146:147], v[64:65], v[146:147]
	global_store_dwordx4 v[150:151], v[144:147], off offset:512 sc1
	s_nop 1
	v_lshlrev_b32_e32 v144, 16, v166
	v_and_b32_e32 v145, 0xffff0000, v166
	v_lshlrev_b32_e32 v146, 16, v167
	v_and_b32_e32 v147, 0xffff0000, v167
	v_pk_mul_f32 v[144:145], v[54:55], v[144:145]
	v_pk_mul_f32 v[146:147], v[56:57], v[146:147]
	global_store_dwordx4 v[150:151], v[144:147], off offset:576 sc1
	s_nop 1
	v_mad_i64_i32 v[144:145], s[0:1], v142, s9, v[148:149]
	global_load_dwordx2 v[146:147], v[144:145], off
	global_load_dwordx2 v[150:151], v[144:145], off offset:32
	global_load_dwordx2 v[152:153], v[144:145], off offset:256
	global_load_dwordx2 v[154:155], v[144:145], off offset:288
	v_mad_i64_i32 v[144:145], s[0:1], v140, s9, v[148:149]
	global_load_dwordx2 v[156:157], v[144:145], off
	global_load_dwordx2 v[158:159], v[144:145], off offset:32
	global_load_dwordx2 v[160:161], v[144:145], off offset:256
	global_load_dwordx2 v[162:163], v[144:145], off offset:288
	v_lshlrev_b64 v[164:165], 13, v[142:143]
	s_waitcnt vmcnt(7)
	v_lshlrev_b32_e32 v142, 16, v146
	v_and_b32_e32 v143, 0xffff0000, v146
	v_lshlrev_b32_e32 v144, 16, v147
	v_and_b32_e32 v145, 0xffff0000, v147
	v_lshl_add_u64 v[146:147], s[14:15], 0, v[164:165]
	v_pk_mul_f32 v[142:143], v[30:31], v[142:143]
	v_pk_mul_f32 v[144:145], v[32:33], v[144:145]
	v_lshl_add_u64 v[146:147], v[146:147], 0, v[134:135]
	global_store_dwordx4 v[146:147], v[142:145], off sc1
	v_ashrrev_i32_e32 v139, 31, v138
	v_ashrrev_i32_e32 v137, 31, v136
	s_waitcnt vmcnt(7)
	v_lshlrev_b32_e32 v142, 16, v150
	v_and_b32_e32 v143, 0xffff0000, v150
	v_lshlrev_b32_e32 v144, 16, v151
	v_and_b32_e32 v145, 0xffff0000, v151
	v_pk_mul_f32 v[142:143], v[26:27], v[142:143]
	v_pk_mul_f32 v[144:145], v[28:29], v[144:145]
	global_store_dwordx4 v[146:147], v[142:145], off offset:64 sc1
	v_mad_i64_i32 v[150:151], s[0:1], v136, s9, v[148:149]
	s_waitcnt vmcnt(7)
	v_lshlrev_b32_e32 v142, 16, v152
	v_and_b32_e32 v143, 0xffff0000, v152
	v_lshlrev_b32_e32 v144, 16, v153
	v_and_b32_e32 v145, 0xffff0000, v153
	v_pk_mul_f32 v[142:143], v[22:23], v[142:143]
	v_pk_mul_f32 v[144:145], v[24:25], v[144:145]
	global_store_dwordx4 v[146:147], v[142:145], off offset:512 sc1
	s_waitcnt vmcnt(7)
	s_nop 0
	v_lshlrev_b32_e32 v142, 16, v154
	v_and_b32_e32 v143, 0xffff0000, v154
	v_lshlrev_b32_e32 v144, 16, v155
	v_and_b32_e32 v145, 0xffff0000, v155
	v_pk_mul_f32 v[142:143], v[14:15], v[142:143]
	v_pk_mul_f32 v[144:145], v[16:17], v[144:145]
	global_store_dwordx4 v[146:147], v[142:145], off offset:576 sc1
	s_nop 1
	v_lshlrev_b64 v[144:145], 13, v[140:141]
	s_waitcnt vmcnt(7)
	v_lshlrev_b32_e32 v140, 16, v156
	v_and_b32_e32 v141, 0xffff0000, v156
	v_lshlrev_b32_e32 v142, 16, v157
	v_and_b32_e32 v143, 0xffff0000, v157
	v_lshl_add_u64 v[144:145], s[14:15], 0, v[144:145]
	v_pk_mul_f32 v[140:141], v[18:19], v[140:141]
	v_pk_mul_f32 v[142:143], v[20:21], v[142:143]
	v_lshl_add_u64 v[144:145], v[144:145], 0, v[134:135]
	global_store_dwordx4 v[144:145], v[140:143], off sc1
	s_waitcnt vmcnt(7)
	s_nop 0
	v_lshlrev_b32_e32 v140, 16, v158
	v_and_b32_e32 v141, 0xffff0000, v158
	v_lshlrev_b32_e32 v142, 16, v159
	v_and_b32_e32 v143, 0xffff0000, v159
	v_pk_mul_f32 v[140:141], v[10:11], v[140:141]
	v_pk_mul_f32 v[142:143], v[12:13], v[142:143]
	global_store_dwordx4 v[144:145], v[140:143], off offset:64 sc1
	s_waitcnt vmcnt(7)
	s_nop 0
	v_lshlrev_b32_e32 v140, 16, v160
	v_and_b32_e32 v141, 0xffff0000, v160
	v_lshlrev_b32_e32 v142, 16, v161
	v_and_b32_e32 v143, 0xffff0000, v161
	v_pk_mul_f32 v[140:141], v[4:5], v[140:141]
	v_pk_mul_f32 v[142:143], v[6:7], v[142:143]
	global_store_dwordx4 v[144:145], v[140:143], off offset:512 sc1
	s_waitcnt vmcnt(7)
	s_nop 0
	v_lshlrev_b32_e32 v140, 16, v162
	v_and_b32_e32 v141, 0xffff0000, v162
	v_lshlrev_b32_e32 v142, 16, v163
	v_and_b32_e32 v143, 0xffff0000, v163
	v_pk_mul_f32 v[140:141], v[0:1], v[140:141]
	v_pk_mul_f32 v[142:143], v[2:3], v[142:143]
	global_store_dwordx4 v[144:145], v[140:143], off offset:576 sc1
	s_nop 1
	v_mad_i64_i32 v[140:141], s[0:1], v138, s9, v[148:149]
	global_load_dwordx2 v[142:143], v[140:141], off
	global_load_dwordx2 v[144:145], v[140:141], off offset:32
	global_load_dwordx2 v[146:147], v[140:141], off offset:256
	s_nop 0
	global_load_dwordx2 v[140:141], v[140:141], off offset:288
	s_nop 0
	global_load_dwordx2 v[152:153], v[150:151], off
	global_load_dwordx2 v[154:155], v[150:151], off offset:32
	global_load_dwordx2 v[156:157], v[150:151], off offset:256
	s_nop 0
	global_load_dwordx2 v[150:151], v[150:151], off offset:288
	v_lshlrev_b64 v[138:139], 13, v[138:139]
	s_waitcnt vmcnt(7)
	v_lshlrev_b32_e32 v158, 16, v142
	v_and_b32_e32 v159, 0xffff0000, v142
	v_lshlrev_b32_e32 v142, 16, v143
	v_and_b32_e32 v143, 0xffff0000, v143
	v_lshl_add_u64 v[138:139], s[14:15], 0, v[138:139]
	v_pk_mul_f32 v[126:127], v[126:127], v[158:159]
	v_pk_mul_f32 v[128:129], v[128:129], v[142:143]
	v_lshl_add_u64 v[138:139], v[138:139], 0, v[134:135]
	global_store_dwordx4 v[138:139], v[126:129], off sc1
	s_movk_i32 s56, 0x3000
	s_waitcnt vmcnt(7)
	v_lshlrev_b32_e32 v126, 16, v144
	v_and_b32_e32 v127, 0xffff0000, v144
	v_pk_mul_f32 v[122:123], v[122:123], v[126:127]
	v_lshlrev_b32_e32 v126, 16, v145
	v_and_b32_e32 v127, 0xffff0000, v145
	v_pk_mul_f32 v[124:125], v[124:125], v[126:127]
	global_store_dwordx4 v[138:139], v[122:125], off offset:64 sc1
	s_waitcnt vmcnt(7)
	s_nop 0
	v_lshlrev_b32_e32 v122, 16, v146
	v_and_b32_e32 v123, 0xffff0000, v146
	v_pk_mul_f32 v[118:119], v[118:119], v[122:123]
	v_lshlrev_b32_e32 v122, 16, v147
	v_and_b32_e32 v123, 0xffff0000, v147
	v_pk_mul_f32 v[120:121], v[120:121], v[122:123]
	global_store_dwordx4 v[138:139], v[118:121], off offset:512 sc1
	s_waitcnt vmcnt(7)
	s_nop 0
	v_lshlrev_b32_e32 v118, 16, v140
	v_and_b32_e32 v119, 0xffff0000, v140
	v_pk_mul_f32 v[114:115], v[114:115], v[118:119]
	v_lshlrev_b32_e32 v118, 16, v141
	v_and_b32_e32 v119, 0xffff0000, v141
	v_pk_mul_f32 v[116:117], v[116:117], v[118:119]
	global_store_dwordx4 v[138:139], v[114:117], off offset:576 sc1
	s_nop 1
	v_lshlrev_b64 v[114:115], 13, v[136:137]
	s_waitcnt vmcnt(7)
	v_lshlrev_b32_e32 v116, 16, v152
	v_and_b32_e32 v117, 0xffff0000, v152
	v_pk_mul_f32 v[110:111], v[110:111], v[116:117]
	v_lshlrev_b32_e32 v116, 16, v153
	v_and_b32_e32 v117, 0xffff0000, v153
	v_lshl_add_u64 v[114:115], s[14:15], 0, v[114:115]
	v_pk_mul_f32 v[112:113], v[112:113], v[116:117]
	v_lshl_add_u64 v[114:115], v[114:115], 0, v[134:135]
	global_store_dwordx4 v[114:115], v[110:113], off sc1
	s_waitcnt vmcnt(7)
	s_nop 0
	v_lshlrev_b32_e32 v110, 16, v154
	v_and_b32_e32 v111, 0xffff0000, v154
	v_pk_mul_f32 v[102:103], v[102:103], v[110:111]
	v_lshlrev_b32_e32 v110, 16, v155
	v_and_b32_e32 v111, 0xffff0000, v155
	v_pk_mul_f32 v[104:105], v[104:105], v[110:111]
	global_store_dwordx4 v[114:115], v[102:105], off offset:64 sc1
	s_waitcnt vmcnt(7)
	s_nop 0
	v_lshlrev_b32_e32 v102, 16, v156
	v_and_b32_e32 v103, 0xffff0000, v156
	v_pk_mul_f32 v[94:95], v[94:95], v[102:103]
	v_lshlrev_b32_e32 v102, 16, v157
	v_and_b32_e32 v103, 0xffff0000, v157
	v_pk_mul_f32 v[96:97], v[96:97], v[102:103]
	global_store_dwordx4 v[114:115], v[94:97], off offset:512 sc1
	v_add_u32_e32 v104, 0xb0, v132
	v_mad_i64_i32 v[110:111], s[0:1], v104, s9, v[148:149]
	s_waitcnt vmcnt(7)
	v_lshlrev_b32_e32 v94, 16, v150
	v_and_b32_e32 v95, 0xffff0000, v150
	v_pk_mul_f32 v[90:91], v[90:91], v[94:95]
	v_lshlrev_b32_e32 v94, 16, v151
	v_and_b32_e32 v95, 0xffff0000, v151
	v_pk_mul_f32 v[92:93], v[92:93], v[94:95]
	global_store_dwordx4 v[114:115], v[90:93], off offset:576 sc1
	v_ashrrev_i32_e32 v105, 31, v104
	s_nop 0
	v_add_u32_e32 v90, 0xa0, v132
	v_mad_i64_i32 v[92:93], s[0:1], v90, s9, v[148:149]
	global_load_dwordx2 v[94:95], v[92:93], off
	global_load_dwordx2 v[96:97], v[92:93], off offset:32
	global_load_dwordx2 v[102:103], v[92:93], off offset:256
	s_nop 0
	global_load_dwordx2 v[92:93], v[92:93], off offset:288
	s_nop 0
	global_load_dwordx2 v[112:113], v[110:111], off
	global_load_dwordx2 v[114:115], v[110:111], off offset:32
	global_load_dwordx2 v[116:117], v[110:111], off offset:256
	s_nop 0
	global_load_dwordx2 v[110:111], v[110:111], off offset:288
	v_ashrrev_i32_e32 v91, 31, v90
	v_lshlrev_b64 v[90:91], 13, v[90:91]
	s_waitcnt vmcnt(7)
	v_lshlrev_b32_e32 v118, 16, v94
	v_and_b32_e32 v119, 0xffff0000, v94
	v_lshlrev_b32_e32 v94, 16, v95
	v_and_b32_e32 v95, 0xffff0000, v95
	v_lshl_add_u64 v[90:91], s[14:15], 0, v[90:91]
	v_pk_mul_f32 v[70:71], v[70:71], v[118:119]
	v_pk_mul_f32 v[72:73], v[72:73], v[94:95]
	v_lshl_add_u64 v[90:91], v[90:91], 0, v[134:135]
	global_store_dwordx4 v[90:91], v[70:73], off sc1
	s_waitcnt vmcnt(7)
	s_nop 0
	v_lshlrev_b32_e32 v70, 16, v96
	v_and_b32_e32 v71, 0xffff0000, v96
	v_pk_mul_f32 v[66:67], v[66:67], v[70:71]
	v_lshlrev_b32_e32 v70, 16, v97
	v_and_b32_e32 v71, 0xffff0000, v97
	v_pk_mul_f32 v[68:69], v[68:69], v[70:71]
	global_store_dwordx4 v[90:91], v[66:69], off offset:64 sc1
	s_waitcnt vmcnt(7)
	s_nop 0
	v_lshlrev_b32_e32 v66, 16, v102
	v_and_b32_e32 v67, 0xffff0000, v102
	v_pk_mul_f32 v[58:59], v[58:59], v[66:67]
	v_lshlrev_b32_e32 v66, 16, v103
	v_and_b32_e32 v67, 0xffff0000, v103
	v_pk_mul_f32 v[60:61], v[60:61], v[66:67]
	global_store_dwordx4 v[90:91], v[58:61], off offset:512 sc1
	s_waitcnt vmcnt(7)
	s_nop 0
	v_lshlrev_b32_e32 v58, 16, v92
	v_and_b32_e32 v59, 0xffff0000, v92
	v_pk_mul_f32 v[50:51], v[50:51], v[58:59]
	v_lshlrev_b32_e32 v58, 16, v93
	v_and_b32_e32 v59, 0xffff0000, v93
	v_pk_mul_f32 v[52:53], v[52:53], v[58:59]
	global_store_dwordx4 v[90:91], v[50:53], off offset:576 sc1
	s_nop 1
	v_lshlrev_b64 v[50:51], 13, v[104:105]
	s_waitcnt vmcnt(7)
	v_lshlrev_b32_e32 v52, 16, v112
	v_and_b32_e32 v53, 0xffff0000, v112
	v_pk_mul_f32 v[46:47], v[46:47], v[52:53]
	v_lshlrev_b32_e32 v52, 16, v113
	v_and_b32_e32 v53, 0xffff0000, v113
	v_lshl_add_u64 v[50:51], s[14:15], 0, v[50:51]
	v_pk_mul_f32 v[48:49], v[48:49], v[52:53]
	v_lshl_add_u64 v[50:51], v[50:51], 0, v[134:135]
	global_store_dwordx4 v[50:51], v[46:49], off sc1
	s_waitcnt vmcnt(7)
	s_nop 0
	v_lshlrev_b32_e32 v46, 16, v114
	v_and_b32_e32 v47, 0xffff0000, v114
	v_pk_mul_f32 v[42:43], v[42:43], v[46:47]
	v_lshlrev_b32_e32 v46, 16, v115
	v_and_b32_e32 v47, 0xffff0000, v115
	v_pk_mul_f32 v[44:45], v[44:45], v[46:47]
	global_store_dwordx4 v[50:51], v[42:45], off offset:64 sc1
	s_waitcnt vmcnt(7)
	s_nop 0
	v_lshlrev_b32_e32 v42, 16, v116
	v_and_b32_e32 v43, 0xffff0000, v116
	v_pk_mul_f32 v[38:39], v[38:39], v[42:43]
	v_lshlrev_b32_e32 v42, 16, v117
	v_and_b32_e32 v43, 0xffff0000, v117
	v_pk_mul_f32 v[40:41], v[40:41], v[42:43]
	global_store_dwordx4 v[50:51], v[38:41], off offset:512 sc1
	s_waitcnt vmcnt(7)
	s_nop 0
	v_lshlrev_b32_e32 v38, 16, v110
	v_and_b32_e32 v39, 0xffff0000, v110
	v_pk_mul_f32 v[34:35], v[34:35], v[38:39]
	v_lshlrev_b32_e32 v38, 16, v111
	v_and_b32_e32 v39, 0xffff0000, v111
	v_pk_mul_f32 v[36:37], v[36:37], v[38:39]
	global_store_dwordx4 v[50:51], v[34:37], off offset:576 sc1

.LBB0_686:
	s_lshl_b32 s0, s42, 11
	s_ashr_i32 s1, s0, 31
	s_lshl_b64 s[0:1], s[0:1], 1
	v_readlane_b32 s14, v252, 62
	v_ashrrev_i32_e32 v131, 31, v130
	v_readlane_b32 s15, v252, 63
	s_add_u32 s0, s14, s0
	s_addc_u32 s1, s15, s1
	v_lshlrev_b64 v[34:35], 1, v[130:131]
	v_lshl_add_u64 v[36:37], s[0:1], 0, v[34:35]
	v_lshl_add_u64 v[38:39], v[36:37], 0, v[210:211]
	v_lshl_add_u64 v[46:47], v[36:37], 0, v[212:213]
	global_load_dwordx2 v[40:41], v[38:39], off
	global_load_dwordx2 v[42:43], v[38:39], off offset:32
	global_load_dwordx2 v[44:45], v[38:39], off offset:256
	s_nop 0
	global_load_dwordx2 v[38:39], v[38:39], off offset:288
	s_nop 0
	global_load_dwordx2 v[48:49], v[46:47], off
	global_load_dwordx2 v[50:51], v[46:47], off offset:32
	global_load_dwordx2 v[52:53], v[46:47], off offset:256
	s_nop 0
	global_load_dwordx2 v[46:47], v[46:47], off offset:288
	s_ashr_i32 s43, s42, 31
	s_lshl_b64 s[0:1], s[42:43], 19
	v_readlane_b32 s9, v254, 26
	s_waitcnt vmcnt(0)
	v_lshlrev_b32_e32 v58, 16, v41
	v_and_b32_e32 v41, 0xffff0000, v41
	s_add_u32 s0, s9, s0
	v_readlane_b32 s9, v254, 27
	v_lshlrev_b32_e32 v8, 16, v40
	v_and_b32_e32 v40, 0xffff0000, v40
	v_mul_f32_e32 v58, v108, v58
	v_mul_f32_e32 v41, v109, v41
	s_addc_u32 s1, s9, s1
	v_mul_f32_e32 v40, v107, v40
	v_cvt_pk_bf16_f32 v41, v58, v41
	v_lshl_add_u64 v[58:59], s[0:1], 0, v[214:215]
	v_mul_f32_e32 v8, v106, v8
	v_cvt_pk_bf16_f32 v40, v8, v40
	v_lshl_add_u64 v[58:59], v[58:59], 0, v[34:35]
	global_store_dwordx2 v[58:59], v[40:41], off sc1
	v_and_b32_e32 v40, 0xffff0000, v42
	v_lshlrev_b32_e32 v8, 16, v42
	v_mul_f32_e32 v40, v99, v40
	v_lshlrev_b32_e32 v41, 16, v43
	v_mul_f32_e32 v8, v98, v8
	v_mul_f32_e32 v41, v100, v41
	v_and_b32_e32 v42, 0xffff0000, v43
	v_cvt_pk_bf16_f32 v40, v8, v40
	v_mul_f32_e32 v42, v101, v42
	v_cvt_pk_bf16_f32 v41, v41, v42
	global_store_dwordx2 v[58:59], v[40:41], off offset:32 sc1
	v_and_b32_e32 v40, 0xffff0000, v44
	v_lshlrev_b32_e32 v8, 16, v44
	v_mul_f32_e32 v40, v83, v40
	v_lshlrev_b32_e32 v41, 16, v45
	v_mul_f32_e32 v8, v82, v8
	v_mul_f32_e32 v41, v84, v41
	v_and_b32_e32 v42, 0xffff0000, v45
	v_cvt_pk_bf16_f32 v40, v8, v40
	v_mul_f32_e32 v42, v85, v42
	v_cvt_pk_bf16_f32 v41, v41, v42
	global_store_dwordx2 v[58:59], v[40:41], off offset:256 sc1
	v_lshlrev_b32_e32 v40, 16, v39
	v_and_b32_e32 v39, 0xffff0000, v39
	v_lshlrev_b32_e32 v8, 16, v38
	v_and_b32_e32 v38, 0xffff0000, v38
	v_mul_f32_e32 v39, v77, v39
	v_mul_f32_e32 v38, v75, v38
	v_mul_f32_e32 v40, v76, v40
	v_cvt_pk_bf16_f32 v39, v40, v39
	v_mul_f32_e32 v8, v74, v8
	v_cvt_pk_bf16_f32 v38, v8, v38
	global_store_dwordx2 v[58:59], v[38:39], off offset:288 sc1
	v_lshlrev_b32_e32 v39, 16, v49
	v_and_b32_e32 v40, 0xffff0000, v49
	v_and_b32_e32 v38, 0xffff0000, v48
	v_mul_f32_e32 v39, v88, v39
	v_mul_f32_e32 v40, v89, v40
	v_lshlrev_b32_e32 v8, 16, v48
	v_mul_f32_e32 v38, v87, v38
	v_cvt_pk_bf16_f32 v39, v39, v40
	v_lshl_add_u64 v[40:41], s[0:1], 0, v[216:217]
	v_mul_f32_e32 v8, v86, v8
	v_cvt_pk_bf16_f32 v38, v8, v38
	v_lshl_add_u64 v[40:41], v[40:41], 0, v[34:35]
	global_store_dwordx2 v[40:41], v[38:39], off sc1
	v_and_b32_e32 v38, 0xffff0000, v50
	v_lshlrev_b32_e32 v39, 16, v51
	v_lshlrev_b32_e32 v8, 16, v50
	v_mul_f32_e32 v38, v79, v38
	v_mul_f32_e32 v39, v80, v39
	v_and_b32_e32 v42, 0xffff0000, v51
	v_mul_f32_e32 v8, v78, v8
	v_mul_f32_e32 v42, v81, v42
	v_cvt_pk_bf16_f32 v38, v8, v38
	v_cvt_pk_bf16_f32 v39, v39, v42
	global_store_dwordx2 v[40:41], v[38:39], off offset:32 sc1
	v_and_b32_e32 v38, 0xffff0000, v52
	v_lshlrev_b32_e32 v39, 16, v53
	v_lshlrev_b32_e32 v8, 16, v52
	v_mul_f32_e32 v38, v63, v38
	v_mul_f32_e32 v39, v64, v39
	v_and_b32_e32 v42, 0xffff0000, v53
	v_mul_f32_e32 v8, v62, v8
	v_mul_f32_e32 v42, v65, v42
	v_cvt_pk_bf16_f32 v38, v8, v38
	v_cvt_pk_bf16_f32 v39, v39, v42
	global_store_dwordx2 v[40:41], v[38:39], off offset:256 sc1
	v_and_b32_e32 v38, 0xffff0000, v46
	v_lshlrev_b32_e32 v39, 16, v47
	v_lshlrev_b32_e32 v8, 16, v46
	v_mul_f32_e32 v38, v55, v38
	v_mul_f32_e32 v39, v56, v39
	v_and_b32_e32 v42, 0xffff0000, v47
	v_mul_f32_e32 v8, v54, v8
	v_mul_f32_e32 v42, v57, v42
	v_cvt_pk_bf16_f32 v38, v8, v38
	v_cvt_pk_bf16_f32 v39, v39, v42
	global_store_dwordx2 v[40:41], v[38:39], off offset:288 sc1
	v_lshl_add_u64 v[38:39], v[36:37], 0, v[218:219]
	v_lshl_add_u64 v[36:37], v[36:37], 0, v[220:221]
	global_load_dwordx2 v[50:51], v[38:39], off
	global_load_dwordx2 v[48:49], v[38:39], off offset:32
	global_load_dwordx2 v[46:47], v[38:39], off offset:256
	global_load_dwordx2 v[44:45], v[38:39], off offset:288
	global_load_dwordx2 v[42:43], v[36:37], off
	global_load_dwordx2 v[40:41], v[36:37], off offset:32
	s_nop 0
	global_load_dwordx2 v[38:39], v[36:37], off offset:256
	s_nop 0
	global_load_dwordx2 v[36:37], v[36:37], off offset:288
	s_waitcnt vmcnt(0)
	v_lshlrev_b32_e32 v8, 16, v50
	v_mul_f32_e32 v8, v30, v8
	v_and_b32_e32 v30, 0xffff0000, v50
	v_mul_f32_e32 v30, v31, v30
	v_cvt_pk_bf16_f32 v30, v8, v30
	v_lshlrev_b32_e32 v8, 16, v48
	v_mul_f32_e32 v8, v26, v8
	v_and_b32_e32 v26, 0xffff0000, v48
	v_mul_f32_e32 v26, v27, v26
	v_cvt_pk_bf16_f32 v26, v8, v26
	v_lshlrev_b32_e32 v8, 16, v46
	v_mul_f32_e32 v8, v22, v8
	v_and_b32_e32 v22, 0xffff0000, v46
	v_lshlrev_b32_e32 v31, 16, v51
	v_mul_f32_e32 v22, v23, v22
	v_mul_f32_e32 v31, v32, v31
	v_and_b32_e32 v32, 0xffff0000, v51
	v_cvt_pk_bf16_f32 v22, v8, v22
	v_lshlrev_b32_e32 v8, 16, v44
	v_mul_f32_e32 v32, v33, v32
	v_mul_f32_e32 v8, v14, v8
	v_and_b32_e32 v14, 0xffff0000, v44
	v_cvt_pk_bf16_f32 v31, v31, v32
	v_lshl_add_u64 v[32:33], s[0:1], 0, v[222:223]
	v_mul_f32_e32 v14, v15, v14
	v_lshlrev_b32_e32 v15, 16, v45
	v_lshl_add_u64 v[32:33], v[32:33], 0, v[34:35]
	v_mul_f32_e32 v15, v16, v15
	v_and_b32_e32 v16, 0xffff0000, v45
	v_cvt_pk_bf16_f32 v14, v8, v14
	v_mul_f32_e32 v16, v17, v16
	v_cvt_pk_bf16_f32 v15, v15, v16
	global_store_dwordx2 v[32:33], v[14:15], off offset:288 sc1
	v_lshlrev_b32_e32 v8, 16, v42
	v_and_b32_e32 v14, 0xffff0000, v42
	v_mul_f32_e32 v8, v18, v8
	v_mul_f32_e32 v14, v19, v14
	v_cvt_pk_bf16_f32 v14, v8, v14
	v_lshlrev_b32_e32 v8, 16, v40
	v_mul_f32_e32 v8, v10, v8
	v_and_b32_e32 v10, 0xffff0000, v40
	v_mul_f32_e32 v10, v11, v10
	v_lshlrev_b32_e32 v15, 16, v43
	v_and_b32_e32 v16, 0xffff0000, v43
	v_cvt_pk_bf16_f32 v10, v8, v10
	v_lshlrev_b32_e32 v8, 16, v38
	v_mul_f32_e32 v15, v20, v15
	v_mul_f32_e32 v16, v21, v16
	v_mul_f32_e32 v4, v4, v8
	v_and_b32_e32 v8, 0xffff0000, v38
	v_cvt_pk_bf16_f32 v15, v15, v16
	v_lshl_add_u64 v[16:17], s[0:1], 0, v[224:225]
	v_mul_f32_e32 v5, v5, v8
	v_lshlrev_b32_e32 v8, 16, v39
	v_lshl_add_u64 v[16:17], v[16:17], 0, v[34:35]
	v_mul_f32_e32 v6, v6, v8
	v_and_b32_e32 v8, 0xffff0000, v39
	v_cvt_pk_bf16_f32 v4, v4, v5
	v_mul_f32_e32 v7, v7, v8
	v_cvt_pk_bf16_f32 v5, v6, v7
	global_store_dwordx2 v[16:17], v[4:5], off offset:256 sc1
	v_lshlrev_b32_e32 v4, 16, v36
	v_mul_f32_e32 v0, v0, v4
	v_and_b32_e32 v4, 0xffff0000, v36
	v_lshlrev_b32_e32 v27, 16, v49
	v_lshlrev_b32_e32 v23, 16, v47
	v_lshlrev_b32_e32 v11, 16, v41
	v_mul_f32_e32 v1, v1, v4
	v_lshlrev_b32_e32 v4, 16, v37
	v_mul_f32_e32 v27, v28, v27
	v_and_b32_e32 v28, 0xffff0000, v49
	v_mul_f32_e32 v23, v24, v23
	v_and_b32_e32 v24, 0xffff0000, v47
	v_mul_f32_e32 v11, v12, v11
	v_and_b32_e32 v12, 0xffff0000, v41
	v_mul_f32_e32 v2, v2, v4
	v_and_b32_e32 v4, 0xffff0000, v37
	global_store_dwordx2 v[32:33], v[30:31], off sc1
	v_mul_f32_e32 v28, v29, v28
	v_cvt_pk_bf16_f32 v27, v27, v28
	global_store_dwordx2 v[32:33], v[26:27], off offset:32 sc1
	v_mul_f32_e32 v24, v25, v24
	v_cvt_pk_bf16_f32 v23, v23, v24
	global_store_dwordx2 v[32:33], v[22:23], off offset:256 sc1
	global_store_dwordx2 v[16:17], v[14:15], off sc1
	v_mul_f32_e32 v12, v13, v12
	v_cvt_pk_bf16_f32 v11, v11, v12
	global_store_dwordx2 v[16:17], v[10:11], off offset:32 sc1
	v_mul_f32_e32 v3, v3, v4
	v_cvt_pk_bf16_f32 v0, v0, v1
	v_cvt_pk_bf16_f32 v1, v2, v3
	global_store_dwordx2 v[16:17], v[0:1], off offset:288 sc1
	s_and_b64 vcc, exec, s[36:37]
	s_mov_b64 s[0:1], -1
	s_cbranch_vccnz .LBB0_648

;     __device__ __forceinline__ void operator()(EPI_ARGS) const {
;         const int col0 = u.pn * 256 + wc * 32 + 4 * fq;
;         if (u.pm == 32) {
;             float* pb = srow + (size_t)u.pc * 128 * ldc;
; #pragma unroll
;             for (int m = 0; m < 4; ++m) { float* rowp = pb + (size_t)(wr * 64 + fr + m * 16) * ldc + col0;
; #pragma unroll
;                 for (int bj = 0; bj < 2; ++bj)
; #pragma unroll
;                     for (int n = 0; n < 2; ++n) *(f32x4*)(rowp + bj * 128 + n * 16) = acc[0][bj][m][n]; }
;         } else {
;             const int row0 = u.pm * 256 + wr * 64 + fr;
; #pragma unroll
;             for (int ai = 0; ai < 2; ++ai)
; #pragma unroll
;                 for (int m = 0; m < 4; ++m) { float* rowp = C + (size_t)(row0 + ai * 128 + m * 16) * ldc + col0;
; #pragma unroll
;                     for (int bj = 0; bj < 2; ++bj)
; #pragma unroll
;                         for (int n = 0; n < 2; ++n) *(f32x4*)(rowp + bj * 128 + n * 16) = acc[ai][bj][m][n]; }
;         }
;     }
.LBB0_800:
	v_lshl_or_b32 v146, s36, 8, v133
	s_mov_b64 s[14:15], -1
	s_cmp_lg_u32 s25, 32
	v_ashrrev_i32_e32 v147, 31, v146
	s_cbranch_scc0 .LBB0_802
	v_lshl_add_u32 v148, s25, 8, v132
	v_or_b32_e32 v156, 16, v148
	v_ashrrev_i32_e32 v149, 31, v148
	v_readlane_b32 s14, v252, 62
	v_ashrrev_i32_e32 v157, 31, v156
	v_lshlrev_b64 v[152:153], 13, v[148:149]
	v_readlane_b32 s15, v252, 63
	v_lshlrev_b64 v[156:157], 13, v[156:157]
	v_lshlrev_b64 v[154:155], 2, v[146:147]
	v_lshl_add_u64 v[152:153], s[14:15], 0, v[152:153]
	v_lshl_add_u64 v[156:157], s[14:15], 0, v[156:157]
	v_lshl_add_u64 v[152:153], v[152:153], 0, v[154:155]
	v_lshl_add_u64 v[156:157], v[156:157], 0, v[154:155]
	global_store_dwordx4 v[152:153], v[118:121], off sc1
	global_store_dwordx4 v[152:153], v[110:113], off offset:64 sc1
	global_store_dwordx4 v[152:153], v[74:77], off offset:512 sc1
	global_store_dwordx4 v[152:153], v[62:65], off offset:576 sc1
	global_store_dwordx4 v[156:157], v[98:101], off sc1
	global_store_dwordx4 v[156:157], v[90:93], off offset:64 sc1
	global_store_dwordx4 v[156:157], v[50:53], off offset:512 sc1
	global_store_dwordx4 v[156:157], v[42:45], off offset:576 sc1
	v_or_b32_e32 v156, 32, v148
	v_or_b32_e32 v148, 48, v148
	v_ashrrev_i32_e32 v157, 31, v156
	v_ashrrev_i32_e32 v149, 31, v148
	v_lshlrev_b64 v[156:157], 13, v[156:157]
	v_lshlrev_b64 v[148:149], 13, v[148:149]
	v_lshl_add_u64 v[156:157], s[14:15], 0, v[156:157]
	v_lshl_add_u64 v[148:149], s[14:15], 0, v[148:149]
	v_lshl_add_u64 v[156:157], v[156:157], 0, v[154:155]
	v_lshl_add_u64 v[148:149], v[148:149], 0, v[154:155]
	s_mov_b64 s[14:15], 0x100000
	global_store_dwordx4 v[156:157], v[82:85], off sc1
	global_store_dwordx4 v[156:157], v[70:73], off offset:64 sc1
	global_store_dwordx4 v[156:157], v[34:37], off offset:512 sc1
	global_store_dwordx4 v[156:157], v[26:29], off offset:576 sc1
	global_store_dwordx4 v[148:149], v[54:57], off sc1
	global_store_dwordx4 v[148:149], v[10:13], off offset:64 sc1
	global_store_dwordx4 v[148:149], v[4:7], off offset:512 sc1
	global_store_dwordx4 v[148:149], v[0:3], off offset:576 sc1
	v_lshl_add_u64 v[148:149], v[152:153], 0, s[14:15]
	s_mov_b32 s14, 0x100000
	v_add_co_u32_e32 v154, vcc, s14, v152
	s_mov_b64 s[14:15], 0x120000
	s_nop 0
	v_addc_co_u32_e32 v155, vcc, 0, v153, vcc
	global_store_dwordx4 v[154:155], v[126:129], off sc1
	global_store_dwordx4 v[148:149], v[122:125], off offset:64 sc1
	global_store_dwordx4 v[148:149], v[102:105], off offset:512 sc1
	global_store_dwordx4 v[148:149], v[94:97], off offset:576 sc1
	s_nop 1
	v_lshl_add_u64 v[94:95], v[152:153], 0, s[14:15]
	s_mov_b32 s14, 0x120000
	v_add_co_u32_e32 v96, vcc, s14, v152
	s_mov_b64 s[14:15], 0x140000
	s_nop 0
	v_addc_co_u32_e32 v97, vcc, 0, v153, vcc
	global_store_dwordx4 v[96:97], v[114:117], off sc1
	global_store_dwordx4 v[94:95], v[106:109], off offset:64 sc1
	global_store_dwordx4 v[94:95], v[66:69], off offset:512 sc1
	global_store_dwordx4 v[94:95], v[58:61], off offset:576 sc1
	s_nop 1
	v_add_co_u32_e32 v60, vcc, 0x140000, v152
	v_lshl_add_u64 v[58:59], v[152:153], 0, s[14:15]
	s_nop 0
	v_addc_co_u32_e32 v61, vcc, 0, v153, vcc
	global_store_dwordx4 v[60:61], v[86:89], off sc1
	global_store_dwordx4 v[58:59], v[78:81], off offset:64 sc1
	global_store_dwordx4 v[58:59], v[38:41], off offset:512 sc1
	global_store_dwordx4 v[58:59], v[30:33], off offset:576 sc1
	s_mov_b64 s[14:15], 0x160000
	v_lshl_add_u64 v[148:149], v[152:153], 0, s[14:15]
	v_add_co_u32_e32 v30, vcc, 0x160000, v152
	s_mov_b64 s[14:15], 0
	s_nop 0
	v_addc_co_u32_e32 v31, vcc, 0, v153, vcc
	global_store_dwordx4 v[30:31], v[46:49], off sc1
.LBB0_802:
	s_andn2_b64 vcc, exec, s[14:15]
	s_cbranch_vccnz .LBB0_804
	s_ashr_i32 s35, s34, 31
	s_lshl_b64 s[14:15], s[34:35], 20
	v_readlane_b32 s18, v254, 34
	v_readlane_b32 s19, v254, 35
	s_add_u32 s14, s18, s14
	s_addc_u32 s15, s19, s15
	v_lshl_add_u64 v[14:15], v[146:147], 2, s[14:15]
	v_lshl_add_u64 v[16:17], v[14:15], 0, v[134:135]
	global_store_dwordx4 v[16:17], v[118:121], off sc1
	global_store_dwordx4 v[16:17], v[110:113], off offset:64 sc1
	global_store_dwordx4 v[16:17], v[74:77], off offset:512 sc1
	global_store_dwordx4 v[16:17], v[62:65], off offset:576 sc1
	v_lshl_add_u64 v[16:17], v[14:15], 0, v[136:137]
	global_store_dwordx4 v[16:17], v[98:101], off sc1
	global_store_dwordx4 v[16:17], v[90:93], off offset:64 sc1
	global_store_dwordx4 v[16:17], v[50:53], off offset:512 sc1
	global_store_dwordx4 v[16:17], v[42:45], off offset:576 sc1
	v_lshl_add_u64 v[16:17], v[14:15], 0, v[138:139]
	global_store_dwordx4 v[16:17], v[82:85], off sc1
	global_store_dwordx4 v[16:17], v[70:73], off offset:64 sc1
	global_store_dwordx4 v[16:17], v[34:37], off offset:512 sc1
	global_store_dwordx4 v[16:17], v[26:29], off offset:576 sc1
	v_lshl_add_u64 v[148:149], v[14:15], 0, v[140:141]
	v_mov_b64_e32 v[16:17], v[2:3]
	v_mov_b64_e32 v[20:21], v[6:7]
	v_mov_b64_e32 v[24:25], v[12:13]
	v_mov_b64_e32 v[14:15], v[0:1]
	v_mov_b64_e32 v[18:19], v[4:5]
	v_mov_b64_e32 v[22:23], v[10:11]
	global_store_dwordx4 v[148:149], v[54:57], off sc1
.LBB0_804:
	s_and_b64 vcc, exec, s[0:1]
	s_mov_b64 s[0:1], -1
	global_store_dwordx4 v[148:149], v[22:25], off offset:64 sc1
	global_store_dwordx4 v[148:149], v[18:21], off offset:512 sc1
	global_store_dwordx4 v[148:149], v[14:17], off offset:576 sc1
	s_cbranch_vccnz .LBB0_779
	s_andn2_b64 vcc, exec, s[38:39]
	s_cbranch_vccnz .LBB0_778
	s_barrier
	s_branch .LBB0_778

; __device__ __forceinline__ unsigned pk2(float lo, float hi) { unsigned r; asm("v_cvt_pk_bf16_f32 %0, %1, %2" : "=v"(r) : "v"(lo), "v"(hi)); return r; }
;     __device__ __forceinline__ void operator()(EPI_ARGS) const {
;         const int row0 = u.pm * 256 + wr * 64 + fr, colt = u.pn * 256 + wc * 32 + 8 * fq;
; #pragma unroll
;         for (int ai = 0; ai < 2; ++ai)
; #pragma unroll
;             for (int m = 0; m < 4; ++m) { const int row = row0 + ai * 128 + m * 16;
; #pragma unroll
;                 for (int bj = 0; bj < 2; ++bj) { const f32x4 v0 = acc[ai][bj][m][0], v1 = acc[ai][bj][m][1]; const int col = colt + bj * 128;
;                     u32x4 w; w.x = pk2(v0[0], v0[1]); w.y = pk2(v0[2], v0[3]); w.z = pk2(v1[0], v1[1]); w.w = pk2(v1[2], v1[3]);
;                     *(u32x4*)(up + (size_t)row * DFF + col) = w;
;                     float* dst = nullptr;
;                     if (row == TP - 2 || row == TP - 1) dst = out + OFF_CP + ((size_t)layer * 2 + (row - (TP - 2))) * DFF + col;
;                     else if (row >= TP && row < MROWS && ((row - TP) & 15) >= 14) { const int s = (row - TP) >> 4, j = ((row - TP) & 15) - 14; dst = out + OFF_CS + (((size_t)layer * 8 + s) * 2 + j) * DFF + col; }
;                     if (dst) { *(f32x4*)dst = v0; *(f32x4*)(dst + 4) = v1; } } }
.LBB0_971:
	s_lshl_b32 s1, s42, 8
	s_add_i32 s1, s1, s46
	v_lshl_or_b32 v144, s0, 8, v153
	s_and_b32 s0, s1, 0xffffff80
	s_cmpk_eq_i32 s0, 0x2000
	v_or_b32_e32 v155, s1, v150
	s_cselect_b64 s[0:1], -1, 0
	v_mov_b64_e32 v[146:147], s[30:31]
	s_and_b64 s[42:43], s[0:1], s[36:37]
	v_mad_i64_i32 v[146:147], s[0:1], v155, s76, v[146:147]
	v_ashrrev_i32_e32 v145, 31, v144
	v_lshl_add_u64 v[148:149], v[144:145], 1, v[146:147]
	v_lshl_add_u64 v[146:147], v[144:145], 2, v[138:139]
	v_cvt_pk_bf16_f32 v156, v126, v127
	v_cvt_pk_bf16_f32 v157, v128, v129
	v_cvt_pk_bf16_f32 v158, v122, v123
	v_cvt_pk_bf16_f32 v159, v124, v125
	global_store_dwordx4 v[148:149], v[156:159], off sc1
	s_and_saveexec_b64 s[0:1], s[42:43]
	s_cbranch_execz .LBB0_973
	global_store_dwordx4 v[146:147], v[126:129], off sc1
	global_store_dwordx4 v[146:147], v[122:125], off offset:16 sc1
.LBB0_973:
	s_or_b64 exec, exec, s[0:1]
	s_nop 0
	v_cvt_pk_bf16_f32 v122, v118, v119
	v_cvt_pk_bf16_f32 v123, v120, v121
	v_cvt_pk_bf16_f32 v124, v114, v115
	v_cvt_pk_bf16_f32 v125, v116, v117
	global_store_dwordx4 v[148:149], v[122:125], off offset:256 sc1
	s_and_saveexec_b64 s[0:1], s[42:43]
	s_cbranch_execz .LBB0_975
	global_store_dwordx4 v[146:147], v[118:121], off offset:512 sc1
	global_store_dwordx4 v[146:147], v[114:117], off offset:528 sc1
.LBB0_975:
	s_or_b64 exec, exec, s[0:1]
	s_nop 0
	v_or_b32_e32 v116, 16, v155
	v_lshrrev_b32_e32 v8, 3, v116
	v_mov_b64_e32 v[114:115], s[30:31]
	v_and_b32_e32 v8, 10, v8
	v_mad_i64_i32 v[114:115], s[0:1], v116, s76, v[114:115]
	v_add_u32_e32 v8, v8, v152
	v_cvt_pk_bf16_f32 v118, v110, v111
	v_cvt_pk_bf16_f32 v119, v112, v113
	v_lshl_add_u64 v[116:117], v[144:145], 1, v[114:115]
	v_cvt_pk_bf16_f32 v120, v106, v107
	v_cvt_pk_bf16_f32 v121, v108, v109
	global_store_dwordx4 v[116:117], v[118:121], off sc1
	v_lshl_add_u64 v[114:115], v[8:9], 0, s[82:83]
	s_nop 0
	v_mov_b64_e32 v[118:119], 0
	s_and_saveexec_b64 s[0:1], s[42:43]
	s_cbranch_execz .LBB0_977
	v_readlane_b32 s14, v254, 38
	v_readlane_b32 s15, v254, 39
	s_nop 1
	v_mov_b64_e32 v[118:119], s[14:15]
	v_mad_u64_u32 v[118:119], s[14:15], v114, s13, v[118:119]
	v_mad_u32_u24 v119, v115, s13, v119
	v_lshl_add_u64 v[118:119], v[144:145], 2, v[118:119]
.LBB0_977:
	s_or_b64 exec, exec, s[0:1]
	v_cmp_ne_u64_e32 vcc, 0, v[118:119]
	s_and_saveexec_b64 s[0:1], vcc
	s_cbranch_execz .LBB0_979
	global_store_dwordx4 v[118:119], v[110:113], off sc1
	global_store_dwordx4 v[118:119], v[106:109], off offset:16 sc1
.LBB0_979:
	s_or_b64 exec, exec, s[0:1]
	s_nop 0
	v_cvt_pk_bf16_f32 v106, v102, v103
	v_cvt_pk_bf16_f32 v107, v104, v105
	v_cvt_pk_bf16_f32 v108, v98, v99
	v_cvt_pk_bf16_f32 v109, v100, v101
	global_store_dwordx4 v[116:117], v[106:109], off offset:256 sc1
	s_nop 1
	v_mov_b64_e32 v[106:107], 0
	s_and_saveexec_b64 s[0:1], s[42:43]
	s_cbranch_execz .LBB0_981
	v_readlane_b32 s14, v254, 38
	v_readlane_b32 s15, v254, 39
	s_nop 1
	v_mov_b64_e32 v[106:107], s[14:15]
	v_mad_u64_u32 v[106:107], s[14:15], v114, s13, v[106:107]
	v_mad_u32_u24 v107, v115, s13, v107
	v_lshl_add_u64 v[106:107], v[144:145], 2, v[106:107]
	s_mov_b64 s[14:15], 0x200
	v_lshl_add_u64 v[106:107], v[106:107], 0, s[14:15]
.LBB0_981:
	s_or_b64 exec, exec, s[0:1]
	v_cmp_ne_u64_e32 vcc, 0, v[106:107]
	s_and_saveexec_b64 s[0:1], vcc
	s_cbranch_execz .LBB0_983
	global_store_dwordx4 v[106:107], v[102:105], off sc1
	global_store_dwordx4 v[106:107], v[98:101], off offset:16 sc1
.LBB0_983:
	s_or_b64 exec, exec, s[0:1]
	s_nop 0
	v_or_b32_e32 v100, 32, v155
	v_lshrrev_b32_e32 v8, 3, v100
	v_mov_b64_e32 v[98:99], s[30:31]
	v_and_b32_e32 v8, 12, v8
	v_mad_i64_i32 v[98:99], s[0:1], v100, s76, v[98:99]
	v_add_u32_e32 v8, v8, v152
	v_cvt_pk_bf16_f32 v102, v94, v95
	v_cvt_pk_bf16_f32 v103, v96, v97
	v_lshl_add_u64 v[100:101], v[144:145], 1, v[98:99]
	v_cvt_pk_bf16_f32 v104, v90, v91
	v_cvt_pk_bf16_f32 v105, v92, v93
	global_store_dwordx4 v[100:101], v[102:105], off sc1
	v_lshl_add_u64 v[98:99], v[8:9], 0, s[82:83]
	s_nop 0
	v_mov_b64_e32 v[102:103], 0
	s_and_saveexec_b64 s[0:1], s[42:43]
	s_cbranch_execz .LBB0_985
	v_readlane_b32 s14, v254, 38
	v_readlane_b32 s15, v254, 39
	s_nop 1
	v_mov_b64_e32 v[102:103], s[14:15]
	v_mad_u64_u32 v[102:103], s[14:15], v98, s13, v[102:103]
	v_mad_u32_u24 v103, v99, s13, v103
	v_lshl_add_u64 v[102:103], v[144:145], 2, v[102:103]
.LBB0_985:
	s_or_b64 exec, exec, s[0:1]
	v_cmp_ne_u64_e32 vcc, 0, v[102:103]
	s_and_saveexec_b64 s[0:1], vcc
	s_cbranch_execz .LBB0_987
	global_store_dwordx4 v[102:103], v[94:97], off sc1
	global_store_dwordx4 v[102:103], v[90:93], off offset:16 sc1
.LBB0_987:
	s_or_b64 exec, exec, s[0:1]
	s_nop 0
	v_cvt_pk_bf16_f32 v90, v86, v87
	v_cvt_pk_bf16_f32 v91, v88, v89
	v_cvt_pk_bf16_f32 v92, v82, v83
	v_cvt_pk_bf16_f32 v93, v84, v85
	global_store_dwordx4 v[100:101], v[90:93], off offset:256 sc1
	s_nop 1
	v_mov_b64_e32 v[90:91], 0
	s_and_saveexec_b64 s[0:1], s[42:43]
	s_cbranch_execz .LBB0_989
	v_readlane_b32 s14, v254, 38
	v_readlane_b32 s15, v254, 39
	s_nop 1
	v_mov_b64_e32 v[90:91], s[14:15]
	v_mad_u64_u32 v[90:91], s[14:15], v98, s13, v[90:91]
	v_mad_u32_u24 v91, v99, s13, v91
	v_lshl_add_u64 v[90:91], v[144:145], 2, v[90:91]
	s_mov_b64 s[14:15], 0x200
	v_lshl_add_u64 v[90:91], v[90:91], 0, s[14:15]
.LBB0_989:
	s_or_b64 exec, exec, s[0:1]
	v_cmp_ne_u64_e32 vcc, 0, v[90:91]
	s_and_saveexec_b64 s[0:1], vcc
	s_cbranch_execz .LBB0_991
	global_store_dwordx4 v[90:91], v[86:89], off sc1
	global_store_dwordx4 v[90:91], v[82:85], off offset:16 sc1
.LBB0_991:
	s_or_b64 exec, exec, s[0:1]
	v_or_b32_e32 v88, 48, v155
	v_bitop3_b32 v8, v155, -2, 48 bitop3:0xc8
	s_movk_i32 s0, 0x1ffe
	v_cmp_ne_u32_e32 vcc, s0, v8
	v_lshrrev_b32_e32 v8, 3, v88
	v_mov_b64_e32 v[82:83], s[30:31]
	v_and_b32_e32 v8, 14, v8
	v_mad_i64_i32 v[82:83], s[0:1], v88, s76, v[82:83]
	v_add_u32_e32 v8, v8, v152
	v_cvt_pk_bf16_f32 v84, v78, v79
	v_cvt_pk_bf16_f32 v85, v80, v81
	v_lshl_add_u64 v[82:83], v[144:145], 1, v[82:83]
	v_cvt_pk_bf16_f32 v86, v74, v75
	v_cvt_pk_bf16_f32 v87, v76, v77
	global_store_dwordx4 v[82:83], v[84:87], off sc1
	s_and_saveexec_b64 s[0:1], vcc
	s_xor_b64 s[0:1], exec, s[0:1]
	s_cbranch_execz .LBB0_995
	v_mov_b64_e32 v[84:85], 0
	s_and_saveexec_b64 s[14:15], s[42:43]
	s_cbranch_execz .LBB0_994
	v_readlane_b32 s18, v254, 38
	v_readlane_b32 s19, v254, 39
	v_lshl_add_u64 v[84:85], v[8:9], 0, s[82:83]
	s_nop 0
	v_mov_b64_e32 v[86:87], s[18:19]
	v_mad_u64_u32 v[86:87], s[18:19], v84, s13, v[86:87]
	v_mad_u32_u24 v87, v85, s13, v87
	v_lshl_add_u64 v[84:85], v[144:145], 2, v[86:87]

; __device__ __forceinline__ unsigned pk2(float lo, float hi) { unsigned r; asm("v_cvt_pk_bf16_f32 %0, %1, %2" : "=v"(r) : "v"(lo), "v"(hi)); return r; }
;     __device__ __forceinline__ void operator()(EPI_ARGS) const {
;     ...
;                 for (int bj = 0; bj < 2; ++bj) { const f32x4 v0 = acc[ai][bj][m][0], v1 = acc[ai][bj][m][1]; const int col = colt + bj * 128;
;                     u32x4 w; w.x = pk2(v0[0], v0[1]); w.y = pk2(v0[2], v0[3]); w.z = pk2(v1[0], v1[1]); w.w = pk2(v1[2], v1[3]);
;                     *(u32x4*)(up + (size_t)row * DFF + col) = w;
;                     float* dst = nullptr;
;                     if (row == TP - 2 || row == TP - 1) dst = out + OFF_CP + ((size_t)layer * 2 + (row - (TP - 2))) * DFF + col;
;                     else if (row >= TP && row < MROWS && ((row - TP) & 15) >= 14) { const int s = (row - TP) >> 4, j = ((row - TP) & 15) - 14; dst = out + OFF_CS + (((size_t)layer * 8 + s) * 2 + j) * DFF + col; }
;                     if (dst) { *(f32x4*)dst = v0; *(f32x4*)(dst + 4) = v1; } } }
.LBB0_997:
	s_or_b64 exec, exec, s[0:1]
	v_cmp_ne_u64_e64 s[0:1], 0, v[84:85]
	s_and_saveexec_b64 s[14:15], s[0:1]
	s_cbranch_execz .LBB0_999
	global_store_dwordx4 v[84:85], v[78:81], off sc1
	global_store_dwordx4 v[84:85], v[74:77], off offset:16 sc1
.LBB0_999:
	s_or_b64 exec, exec, s[14:15]
	s_nop 0
	v_cvt_pk_bf16_f32 v74, v70, v71
	v_cvt_pk_bf16_f32 v75, v72, v73
	v_cvt_pk_bf16_f32 v76, v66, v67
	v_cvt_pk_bf16_f32 v77, v68, v69
	global_store_dwordx4 v[82:83], v[74:77], off offset:256 sc1
	s_and_saveexec_b64 s[0:1], vcc
	s_xor_b64 s[0:1], exec, s[0:1]
	s_cbranch_execnz .LBB0_1035
	s_andn2_saveexec_b64 s[0:1], s[0:1]
	s_cbranch_execnz .LBB0_1038

; __device__ __forceinline__ unsigned pk2(float lo, float hi) { unsigned r; asm("v_cvt_pk_bf16_f32 %0, %1, %2" : "=v"(r) : "v"(lo), "v"(hi)); return r; }
;     __device__ __forceinline__ void operator()(EPI_ARGS) const {
;     ...
;                 for (int bj = 0; bj < 2; ++bj) { const f32x4 v0 = acc[ai][bj][m][0], v1 = acc[ai][bj][m][1]; const int col = colt + bj * 128;
;                     u32x4 w; w.x = pk2(v0[0], v0[1]); w.y = pk2(v0[2], v0[3]); w.z = pk2(v1[0], v1[1]); w.w = pk2(v1[2], v1[3]);
;                     *(u32x4*)(up + (size_t)row * DFF + col) = w;
;                     float* dst = nullptr;
;                     if (row == TP - 2 || row == TP - 1) dst = out + OFF_CP + ((size_t)layer * 2 + (row - (TP - 2))) * DFF + col;
;                     else if (row >= TP && row < MROWS && ((row - TP) & 15) >= 14) { const int s = (row - TP) >> 4, j = ((row - TP) & 15) - 14; dst = out + OFF_CS + (((size_t)layer * 8 + s) * 2 + j) * DFF + col; }
;                     if (dst) { *(f32x4*)dst = v0; *(f32x4*)(dst + 4) = v1; } } }
.LBB0_1002:
	global_store_dwordx4 v[74:75], v[70:73], off sc1
	global_store_dwordx4 v[74:75], v[66:69], off offset:16 sc1
.LBB0_1003:
	s_or_b64 exec, exec, s[0:1]
	v_add_u32_e32 v8, 0x80, v155
	v_and_b32_e32 v66, 0xffffff80, v8
	v_cmp_eq_u32_e32 vcc, s77, v66
	v_mov_b64_e32 v[66:67], s[30:31]
	v_mad_i64_i32 v[66:67], s[0:1], v8, s76, v[66:67]
	s_and_b64 s[14:15], vcc, s[36:37]
	v_lshl_add_u64 v[66:67], v[144:145], 1, v[66:67]
	v_cvt_pk_bf16_f32 v68, v62, v63
	v_cvt_pk_bf16_f32 v69, v64, v65
	v_cvt_pk_bf16_f32 v70, v58, v59
	v_cvt_pk_bf16_f32 v71, v60, v61
	global_store_dwordx4 v[66:67], v[68:71], off sc1
	s_and_saveexec_b64 s[0:1], s[14:15]
	s_cbranch_execz .LBB0_1005
	global_store_dwordx4 v[146:147], v[62:65], off sc1
	global_store_dwordx4 v[146:147], v[58:61], off offset:16 sc1
.LBB0_1005:
	s_or_b64 exec, exec, s[0:1]
	s_nop 0
	v_cvt_pk_bf16_f32 v58, v54, v55
	v_cvt_pk_bf16_f32 v59, v56, v57
	v_cvt_pk_bf16_f32 v60, v50, v51
	v_cvt_pk_bf16_f32 v61, v52, v53
	global_store_dwordx4 v[66:67], v[58:61], off offset:256 sc1
	s_and_saveexec_b64 s[0:1], s[14:15]
	s_cbranch_execz .LBB0_1007
	global_store_dwordx4 v[146:147], v[54:57], off offset:512 sc1
	global_store_dwordx4 v[146:147], v[50:53], off offset:528 sc1
.LBB0_1007:
	s_or_b64 exec, exec, s[0:1]
	s_nop 0
	v_add_u32_e32 v52, 0x90, v155
	v_lshrrev_b32_e32 v8, 3, v52
	v_mov_b64_e32 v[50:51], s[30:31]
	v_and_b32_e32 v8, 10, v8
	v_mad_i64_i32 v[50:51], s[0:1], v52, s76, v[50:51]
	v_add_u32_e32 v8, v8, v152
	v_cvt_pk_bf16_f32 v54, v46, v47
	v_cvt_pk_bf16_f32 v55, v48, v49
	v_lshl_add_u64 v[52:53], v[144:145], 1, v[50:51]
	v_cvt_pk_bf16_f32 v56, v42, v43
	v_cvt_pk_bf16_f32 v57, v44, v45
	global_store_dwordx4 v[52:53], v[54:57], off sc1
	v_lshl_add_u64 v[50:51], v[8:9], 0, s[82:83]
	s_nop 0
	v_mov_b64_e32 v[54:55], 0
	s_and_saveexec_b64 s[0:1], s[14:15]
	s_cbranch_execz .LBB0_1009
	v_readlane_b32 s18, v254, 38
	v_readlane_b32 s19, v254, 39
	s_nop 1
	v_mov_b64_e32 v[54:55], s[18:19]
	v_mad_u64_u32 v[54:55], s[18:19], v50, s13, v[54:55]
	v_mad_u32_u24 v55, v51, s13, v55
	v_lshl_add_u64 v[54:55], v[144:145], 2, v[54:55]
.LBB0_1009:
	s_or_b64 exec, exec, s[0:1]
	v_cmp_ne_u64_e32 vcc, 0, v[54:55]
	s_and_saveexec_b64 s[0:1], vcc
	s_cbranch_execz .LBB0_1011
	global_store_dwordx4 v[54:55], v[46:49], off sc1
	global_store_dwordx4 v[54:55], v[42:45], off offset:16 sc1
.LBB0_1011:
	s_or_b64 exec, exec, s[0:1]
	s_nop 0
	v_cvt_pk_bf16_f32 v42, v38, v39
	v_cvt_pk_bf16_f32 v43, v40, v41
	v_cvt_pk_bf16_f32 v44, v34, v35
	v_cvt_pk_bf16_f32 v45, v36, v37
	global_store_dwordx4 v[52:53], v[42:45], off offset:256 sc1
	s_nop 1
	v_mov_b64_e32 v[42:43], 0
	s_and_saveexec_b64 s[0:1], s[14:15]
	s_cbranch_execz .LBB0_1013
	v_readlane_b32 s18, v254, 38
	v_readlane_b32 s19, v254, 39
	s_nop 1
	v_mov_b64_e32 v[42:43], s[18:19]
	v_mad_u64_u32 v[42:43], s[18:19], v50, s13, v[42:43]
	v_mad_u32_u24 v43, v51, s13, v43
	v_lshl_add_u64 v[42:43], v[144:145], 2, v[42:43]
	s_mov_b64 s[18:19], 0x200
	v_lshl_add_u64 v[42:43], v[42:43], 0, s[18:19]
.LBB0_1013:
	s_or_b64 exec, exec, s[0:1]
	v_cmp_ne_u64_e32 vcc, 0, v[42:43]
	s_and_saveexec_b64 s[0:1], vcc
	s_cbranch_execz .LBB0_1015
	global_store_dwordx4 v[42:43], v[38:41], off sc1
	global_store_dwordx4 v[42:43], v[34:37], off offset:16 sc1
.LBB0_1015:
	s_or_b64 exec, exec, s[0:1]
	s_nop 0
	v_add_u32_e32 v36, 0xa0, v155
	v_lshrrev_b32_e32 v8, 3, v36
	v_mov_b64_e32 v[34:35], s[30:31]
	v_and_b32_e32 v8, 12, v8
	v_mad_i64_i32 v[34:35], s[0:1], v36, s76, v[34:35]
	v_add_u32_e32 v8, v8, v152
	v_cvt_pk_bf16_f32 v38, v30, v31
	v_cvt_pk_bf16_f32 v39, v32, v33
	v_lshl_add_u64 v[36:37], v[144:145], 1, v[34:35]
	v_cvt_pk_bf16_f32 v40, v26, v27
	v_cvt_pk_bf16_f32 v41, v28, v29
	global_store_dwordx4 v[36:37], v[38:41], off sc1
	v_lshl_add_u64 v[34:35], v[8:9], 0, s[82:83]
	s_nop 0
	v_mov_b64_e32 v[38:39], 0
	s_and_saveexec_b64 s[0:1], s[14:15]
	s_cbranch_execz .LBB0_1017
	v_readlane_b32 s18, v254, 38
	v_readlane_b32 s19, v254, 39
	s_nop 1
	v_mov_b64_e32 v[38:39], s[18:19]
	v_mad_u64_u32 v[38:39], s[18:19], v34, s13, v[38:39]
	v_mad_u32_u24 v39, v35, s13, v39
	v_lshl_add_u64 v[38:39], v[144:145], 2, v[38:39]
.LBB0_1017:
	s_or_b64 exec, exec, s[0:1]
	v_cmp_ne_u64_e32 vcc, 0, v[38:39]
	s_and_saveexec_b64 s[0:1], vcc
	s_cbranch_execz .LBB0_1019
	global_store_dwordx4 v[38:39], v[30:33], off sc1
	global_store_dwordx4 v[38:39], v[26:29], off offset:16 sc1
.LBB0_1019:
	s_or_b64 exec, exec, s[0:1]
	s_nop 0
	v_cvt_pk_bf16_f32 v26, v22, v23
	v_cvt_pk_bf16_f32 v27, v24, v25
	v_cvt_pk_bf16_f32 v28, v18, v19
	v_cvt_pk_bf16_f32 v29, v20, v21
	global_store_dwordx4 v[36:37], v[26:29], off offset:256 sc1
	s_nop 1
	v_mov_b64_e32 v[26:27], 0
	s_and_saveexec_b64 s[0:1], s[14:15]
	s_cbranch_execz .LBB0_1021
	v_readlane_b32 s18, v254, 38
	v_readlane_b32 s19, v254, 39
	s_nop 1
	v_mov_b64_e32 v[26:27], s[18:19]
	v_mad_u64_u32 v[26:27], s[18:19], v34, s13, v[26:27]
	v_mad_u32_u24 v27, v35, s13, v27
	v_lshl_add_u64 v[26:27], v[144:145], 2, v[26:27]
	s_mov_b64 s[18:19], 0x200
	v_lshl_add_u64 v[26:27], v[26:27], 0, s[18:19]
.LBB0_1021:
	s_or_b64 exec, exec, s[0:1]
	v_cmp_ne_u64_e32 vcc, 0, v[26:27]
	s_and_saveexec_b64 s[0:1], vcc
	s_cbranch_execz .LBB0_1023
	global_store_dwordx4 v[26:27], v[22:25], off sc1
	global_store_dwordx4 v[26:27], v[18:21], off offset:16 sc1
.LBB0_1023:
	s_or_b64 exec, exec, s[0:1]
	v_add_u32_e32 v24, 0xb0, v155
	v_and_b32_e32 v8, -2, v24
	s_movk_i32 s0, 0x1ffe
	v_cmp_ne_u32_e32 vcc, s0, v8
	v_lshrrev_b32_e32 v8, 3, v24
	v_mov_b64_e32 v[18:19], s[30:31]
	v_and_b32_e32 v8, 14, v8
	v_mad_i64_i32 v[18:19], s[0:1], v24, s76, v[18:19]
	v_add_u32_e32 v8, v8, v152
	v_cvt_pk_bf16_f32 v20, v14, v15
	v_cvt_pk_bf16_f32 v21, v16, v17
	v_lshl_add_u64 v[18:19], v[144:145], 1, v[18:19]
	v_cvt_pk_bf16_f32 v22, v10, v11
	v_cvt_pk_bf16_f32 v23, v12, v13
	global_store_dwordx4 v[18:19], v[20:23], off sc1
	s_and_saveexec_b64 s[0:1], vcc
	s_xor_b64 s[0:1], exec, s[0:1]
	s_cbranch_execz .LBB0_1027
	v_mov_b64_e32 v[20:21], 0
	s_and_saveexec_b64 s[18:19], s[14:15]
	s_cbranch_execz .LBB0_1026
	v_readlane_b32 s20, v254, 38
	v_readlane_b32 s21, v254, 39
	v_lshl_add_u64 v[20:21], v[8:9], 0, s[82:83]
	s_nop 0
	v_mov_b64_e32 v[22:23], s[20:21]
	v_mad_u64_u32 v[22:23], s[20:21], v20, s13, v[22:23]
	v_mad_u32_u24 v23, v21, s13, v23
	v_lshl_add_u64 v[20:21], v[144:145], 2, v[22:23]

; __device__ __forceinline__ unsigned pk2(float lo, float hi) { unsigned r; asm("v_cvt_pk_bf16_f32 %0, %1, %2" : "=v"(r) : "v"(lo), "v"(hi)); return r; }
;     __device__ __forceinline__ void operator()(EPI_ARGS) const {
;     ...
;                 for (int bj = 0; bj < 2; ++bj) { const f32x4 v0 = acc[ai][bj][m][0], v1 = acc[ai][bj][m][1]; const int col = colt + bj * 128;
;                     u32x4 w; w.x = pk2(v0[0], v0[1]); w.y = pk2(v0[2], v0[3]); w.z = pk2(v1[0], v1[1]); w.w = pk2(v1[2], v1[3]);
;                     *(u32x4*)(up + (size_t)row * DFF + col) = w;
;                     float* dst = nullptr;
;                     if (row == TP - 2 || row == TP - 1) dst = out + OFF_CP + ((size_t)layer * 2 + (row - (TP - 2))) * DFF + col;
;                     else if (row >= TP && row < MROWS && ((row - TP) & 15) >= 14) { const int s = (row - TP) >> 4, j = ((row - TP) & 15) - 14; dst = out + OFF_CS + (((size_t)layer * 8 + s) * 2 + j) * DFF + col; }
;                     if (dst) { *(f32x4*)dst = v0; *(f32x4*)(dst + 4) = v1; } } }
.LBB0_1029:
	s_or_b64 exec, exec, s[0:1]
	v_cmp_ne_u64_e64 s[0:1], 0, v[20:21]
	s_and_saveexec_b64 s[18:19], s[0:1]
	s_cbranch_execz .LBB0_1031
	global_store_dwordx4 v[20:21], v[14:17], off sc1
	global_store_dwordx4 v[20:21], v[10:13], off offset:16 sc1
.LBB0_1031:
	s_or_b64 exec, exec, s[18:19]
	s_nop 0
	v_cvt_pk_bf16_f32 v10, v4, v5
	v_cvt_pk_bf16_f32 v11, v6, v7
	v_cvt_pk_bf16_f32 v12, v0, v1
	v_cvt_pk_bf16_f32 v13, v2, v3
	global_store_dwordx4 v[18:19], v[10:13], off offset:256 sc1
	s_and_saveexec_b64 s[0:1], vcc
	s_xor_b64 s[0:1], exec, s[0:1]
	s_cbranch_execnz .LBB0_1039
	s_andn2_saveexec_b64 s[0:1], s[0:1]
	s_cbranch_execnz .LBB0_1042

; #define PG8_BAR __builtin_amdgcn_s_barrier()
; template <bool HALFSKIP, bool SP2, bool ALIGN, class Epi>
; __device__ __forceinline__ void gemm_phase(LAS unsigned char* lds, const Gemm g, const StaticOrder& S, const Epi& E, const int wv) {
;     ...
;         if (!has_next) break;
; #pragma unroll
;         for (int a = 0; a < 2; ++a)
; #pragma unroll
;             for (int b = 0; b < 2; ++b)
; #pragma unroll
;                 for (int m = 0; m < 4; ++m)
; #pragma unroll
;                     for (int n = 0; n < 2; ++n) acc[a][b][m][n] = (f32x4){0.f, 0.f, 0.f, 0.f};
;         cur = nxt; cA = nA; cB = nB; ++ui;
;         if (ALIGN && wr == 1) PG8_BAR;
;     __device__ __forceinline__ void operator()(EPI_ARGS) const {
;     ...
;                     if (row == TP - 2 || row == TP - 1) dst = out + OFF_CP + ((size_t)layer * 2 + (row - (TP - 2))) * DFF + col;
;                     else if (row >= TP && row < MROWS && ((row - TP) & 15) >= 14) { const int s = (row - TP) >> 4, j = ((row - TP) & 15) - 14; dst = out + OFF_CS + (((size_t)layer * 8 + s) * 2 + j) * DFF + col; }
;                     if (dst) { *(f32x4*)dst = v0; *(f32x4*)(dst + 4) = v1; } } }
.LBB0_1043:
	global_store_dwordx4 v[10:11], v[4:7], off sc1
	global_store_dwordx4 v[10:11], v[0:3], off offset:16 sc1
	s_or_b64 exec, exec, s[0:1]
	s_andn2_b64 vcc, exec, s[38:39]
	s_mov_b64 s[0:1], -1
	s_cbranch_vccnz .LBB0_960

; __device__ __forceinline__ unsigned pk2(float lo, float hi) { unsigned r; asm("v_cvt_pk_bf16_f32 %0, %1, %2" : "=v"(r) : "v"(lo), "v"(hi)); return r; }
; __device__ __forceinline__ float gelu_f(float v) {
;     const float av = fabsf(v), d = av * 0.2316418882f + 1.0f;
;     const float t = __builtin_amdgcn_rcpf(d);
;     float q = t * 0.5307027145f + (-0.7265760135f); q = q * t + 0.7107068705f; q = q * t + (-0.142248368f); q = q * t + 0.127414796f; q = q * t;
;     const float e = __builtin_amdgcn_exp2f(v * v * (-0.72134752044f));
;     const float m = v * (q * e);
;     return v < 0.f ? m : v - m;
;     __device__ __forceinline__ void operator()(EPI_ARGS) const {
;     ...
;                     for (int t = 0; t < 1; ++t) { const int row = row0 + ai * 128 + (mp + t) * 16; const int r1 = row > 0 ? row - 1 : 0, r2 = row > 1 ? row - 2 : 0;
;                         q2[t] = *(const u32x4*)(up + (size_t)row * DFF + col); q1[t] = *(const u32x4*)(up + (size_t)r1 * DFF + col); q0[t] = *(const u32x4*)(up + (size_t)r2 * DFF + col); }
;                     __builtin_amdgcn_sched_barrier(0);
; #pragma unroll
;                     for (int t = 0; t < 1; ++t) { const int m = mp + t, row = row0 + ai * 128 + m * 16;
;                         const int i = row < TP ? row : ((row - TP) & 15); const int sidx = row < TP ? 0 : ((row - TP) >> 4);
;                         float x0[8], x1[8], x2[8]; unpack8(q0[t], x0); unpack8(q1[t], x1); unpack8(q2[t], x2);
;                         if (i < 2) {
;                             const bool smp = row >= TP; const float* p0 = cs + ((size_t)sidx * 2 + i) * DFF + col; const float* p1 = cs + ((size_t)sidx * 2 + 1) * DFF + col;
; #pragma unroll
;                             for (int e = 0; e < 8; ++e) { x0[e] = smp ? p0[e] : 0.f; if (i == 0) x1[e] = smp ? p1[e] : 0.f; } }
;                         float r[8];
; #pragma unroll
;                         for (int e = 0; e < 8; ++e) { const float cv = bb[e] + x0[e] * w0[e] + x1[e] * w1[e] + x2[e] * w2[e]; r[e] = gelu_f(cv) * acc[ai][bj][m][e >> 2][e & 3]; }
;                         u32x4 w; w.x = pk2(r[0], r[1]); w.y = pk2(r[2], r[3]); w.z = pk2(r[4], r[5]); w.w = pk2(r[6], r[7]);
;                         *(u32x4*)(act + (size_t)row * DFF + col) = w; } } } }
.LBB0_1173:
	s_or_b64 exec, exec, s[0:1]
	v_lshlrev_b32_e32 v194, 16, v170
	v_and_b32_e32 v170, 0xffff0000, v170
	v_lshlrev_b32_e32 v222, 16, v171
	v_and_b32_e32 v224, 0xffff0000, v171
	v_mov_b32_e32 v210, v166
	v_mov_b32_e32 v211, v106
	s_waitcnt vmcnt(0)
	v_add_u32_e32 v240, 16, v232
	v_mov_b64_e32 v[238:239], s[30:31]
	v_mad_i64_i32 v[238:239], s[0:1], v240, s76, v[238:239]
	v_lshl_add_u64 v[238:239], v[238:239], 0, v[186:187]
	global_load_dwordx4 v[196:199], v[238:239], off
	v_add_u32_e32 v240, -1, v240
	v_mov_b64_e32 v[246:247], s[30:31]
	v_mad_i64_i32 v[246:247], s[0:1], v240, s76, v[246:247]
	v_lshl_add_u64 v[246:247], v[246:247], 0, v[186:187]
	global_load_dwordx4 v[200:203], v[246:247], off
	v_add_u32_e32 v240, -1, v240
	v_mov_b64_e32 v[238:239], s[30:31]
	v_mad_i64_i32 v[238:239], s[0:1], v240, s76, v[238:239]
	v_lshl_add_u64 v[238:239], v[238:239], 0, v[186:187]
	global_load_dwordx4 v[242:245], v[238:239], off
	v_mov_b32_e32 v195, v0
	v_mov_b32_e32 v106, v167
	v_mov_b32_e32 v171, v1
	v_pk_mul_f32 v[194:195], v[210:211], v[194:195]
	v_pk_mul_f32 v[0:1], v[106:107], v[170:171]
	v_pk_fma_f32 v[166:167], v[102:103], v[212:213], v[110:111]
	v_mov_b32_e32 v170, v195
	v_mov_b32_e32 v171, v1
	v_pk_add_f32 v[166:167], v[170:171], v[166:167]
	v_mov_b32_e32 v195, v0
	v_pk_add_f32 v[0:1], v[194:195], v[166:167]
	v_lshlrev_b32_e32 v226, 16, v172
	v_fma_f32 v166, |v0|, s84, 1.0
	v_rcp_f32_e32 v167, v166
	v_and_b32_e32 v166, 0xffff0000, v172
	v_lshlrev_b32_e32 v170, 16, v173
	v_and_b32_e32 v194, 0xffff0000, v173
	v_pk_mul_f32 v[172:173], v[0:1], v[0:1]
	v_fmamk_f32 v171, v167, 0x3f07dc22, v241
	v_mul_f32_e32 v172, 0xbf38aa3b, v172
	v_fmaak_f32 v171, v167, v171, 0x3f35f0e3
	v_exp_f32_e32 v172, v172
	v_fmaak_f32 v171, v167, v171, 0xbe11a98e
	v_fmaak_f32 v171, v167, v171, 0x3e027906
	v_mul_f32_e32 v167, v167, v171
	v_mul_f32_e32 v167, v172, v167
	v_fma_f32 v172, |v1|, s84, 1.0
	v_rcp_f32_e32 v172, v172
	v_mad_i64_i32 v[220:221], s[0:1], v232, s76, 0
	v_mul_f32_e32 v171, v0, v167
	v_fma_f32 v167, -v0, v167, v0
	v_cmp_gt_f32_e64 s[0:1], 0, v0
	v_mov_b32_e32 v223, v2
	v_mov_b32_e32 v225, v3
	v_cndmask_b32_e64 v0, v167, v171, s[0:1]
	v_mul_f32_e32 v233, v158, v0
	v_fmamk_f32 v0, v172, 0x3f07dc22, v241
	v_fmaak_f32 v0, v172, v0, 0x3f35f0e3
	v_fmaak_f32 v0, v172, v0, 0xbe11a98e
	v_fmaak_f32 v0, v172, v0, 0x3e027906
	v_mul_f32_e32 v158, 0xbf38aa3b, v173
	v_mul_f32_e32 v0, v172, v0
	v_mov_b32_e32 v172, v168
	v_mov_b32_e32 v173, v108
	v_mov_b32_e32 v108, v169
	v_pk_mul_f32 v[212:213], v[172:173], v[222:223]
	v_pk_mul_f32 v[2:3], v[108:109], v[224:225]
	v_pk_fma_f32 v[168:169], v[104:105], v[214:215], v[112:113]
	v_mov_b32_e32 v214, v213
	v_mov_b32_e32 v215, v3
	v_exp_f32_e32 v158, v158
	v_pk_add_f32 v[168:169], v[214:215], v[168:169]
	v_mov_b32_e32 v213, v2
	v_pk_add_f32 v[2:3], v[212:213], v[168:169]
	v_mul_f32_e32 v0, v158, v0
	v_fma_f32 v167, |v2|, s84, 1.0
	v_rcp_f32_e32 v167, v167
	v_mul_f32_e32 v158, v1, v0
	v_fma_f32 v0, -v1, v0, v1
	v_cmp_gt_f32_e64 s[0:1], 0, v1
	v_mov_b32_e32 v212, v162
	v_mov_b32_e32 v213, v94
	v_cndmask_b32_e64 v0, v0, v158, s[0:1]
	v_mul_f32_e32 v168, v159, v0
	v_fmamk_f32 v0, v167, 0x3f07dc22, v241
	v_fmaak_f32 v158, v167, v0, 0x3f35f0e3
	v_pk_mul_f32 v[0:1], v[2:3], v[2:3]
	v_fmaak_f32 v158, v167, v158, 0xbe11a98e
	v_mul_f32_e32 v0, 0xbf38aa3b, v0
	v_exp_f32_e32 v0, v0
	v_fmaak_f32 v158, v167, v158, 0x3e027906
	v_fma_f32 v159, |v3|, s84, 1.0
	v_mul_f32_e32 v158, v167, v158
	v_rcp_f32_e32 v159, v159
	v_mul_f32_e32 v0, v0, v158
	v_mul_f32_e32 v158, v2, v0
	v_fma_f32 v0, -v2, v0, v2
	v_cmp_gt_f32_e64 s[0:1], 0, v2
	v_mul_f32_e32 v1, 0xbf38aa3b, v1
	v_exp_f32_e32 v1, v1
	v_cndmask_b32_e64 v0, v0, v158, s[0:1]
	v_mul_f32_e32 v160, v160, v0
	v_fmamk_f32 v0, v159, 0x3f07dc22, v241
	v_fmaak_f32 v0, v159, v0, 0x3f35f0e3
	v_fmaak_f32 v0, v159, v0, 0xbe11a98e
	v_fmaak_f32 v0, v159, v0, 0x3e027906
	v_mul_f32_e32 v0, v159, v0
	v_mul_f32_e32 v0, v1, v0
	v_mov_b32_e32 v227, v4
	v_mov_b32_e32 v94, v163
	v_mov_b32_e32 v167, v5
	v_mul_f32_e32 v2, v3, v0
	v_fma_f32 v169, -v3, v0, v3
	v_pk_mul_f32 v[0:1], v[212:213], v[226:227]
	v_pk_mul_f32 v[4:5], v[94:95], v[166:167]
	v_pk_fma_f32 v[158:159], v[90:91], v[216:217], v[98:99]
	v_mov_b32_e32 v162, v1
	v_mov_b32_e32 v163, v5
	v_pk_add_f32 v[158:159], v[162:163], v[158:159]
	v_mov_b32_e32 v1, v4
	v_pk_add_f32 v[0:1], v[0:1], v[158:159]
	v_cmp_gt_f32_e64 s[0:1], 0, v3
	v_fma_f32 v4, |v0|, s84, 1.0
	v_rcp_f32_e32 v4, v4
	v_cndmask_b32_e64 v2, v169, v2, s[0:1]
	v_mul_f32_e32 v161, v161, v2
	v_cmp_gt_f32_e64 s[0:1], 0, v0
	v_fmamk_f32 v2, v4, 0x3f07dc22, v241
; __device__ __forceinline__ unsigned pk2(float lo, float hi) { unsigned r; asm("v_cvt_pk_bf16_f32 %0, %1, %2" : "=v"(r) : "v"(lo), "v"(hi)); return r; }
;     static __device__ __forceinline__ void unpack8(const u32x4 q, float (&x)[8]) { x[0] = bflo(q.x); x[1] = bfhi(q.x); x[2] = bflo(q.y); x[3] = bfhi(q.y); x[4] = bflo(q.z); x[5] = bfhi(q.z); x[6] = bflo(q.w); x[7] = bfhi(q.w); }
;     __device__ __forceinline__ void operator()(EPI_ARGS) const {
;     ...
;                     for (int t = 0; t < 1; ++t) { const int row = row0 + ai * 128 + (mp + t) * 16; const int r1 = row > 0 ? row - 1 : 0, r2 = row > 1 ? row - 2 : 0;
;                         q2[t] = *(const u32x4*)(up + (size_t)row * DFF + col); q1[t] = *(const u32x4*)(up + (size_t)r1 * DFF + col); q0[t] = *(const u32x4*)(up + (size_t)r2 * DFF + col); }
;                     __builtin_amdgcn_sched_barrier(0);
; #pragma unroll
;                     for (int t = 0; t < 1; ++t) { const int m = mp + t, row = row0 + ai * 128 + m * 16;
;                         const int i = row < TP ? row : ((row - TP) & 15); const int sidx = row < TP ? 0 : ((row - TP) >> 4);
;                         float x0[8], x1[8], x2[8]; unpack8(q0[t], x0); unpack8(q1[t], x1); unpack8(q2[t], x2);
;                         if (i < 2) {
;                             const bool smp = row >= TP; const float* p0 = cs + ((size_t)sidx * 2 + i) * DFF + col; const float* p1 = cs + ((size_t)sidx * 2 + 1) * DFF + col;
; #pragma unroll
;                             for (int e = 0; e < 8; ++e) { x0[e] = smp ? p0[e] : 0.f; if (i == 0) x1[e] = smp ? p1[e] : 0.f; } }
;     ...
;                         for (int e = 0; e < 8; ++e) { const float cv = bb[e] + x0[e] * w0[e] + x1[e] * w1[e] + x2[e] * w2[e]; r[e] = gelu_f(cv) * acc[ai][bj][m][e >> 2][e & 3]; }
;                         u32x4 w; w.x = pk2(r[0], r[1]); w.y = pk2(r[2], r[3]); w.z = pk2(r[4], r[5]); w.w = pk2(r[6], r[7]);
;                         *(u32x4*)(act + (size_t)row * DFF + col) = w; } } } }
	v_fmaak_f32 v5, v4, v2, 0x3f35f0e3
	v_pk_mul_f32 v[2:3], v[0:1], v[0:1]
	v_fmaak_f32 v5, v4, v5, 0xbe11a98e
	v_mul_f32_e32 v2, 0xbf38aa3b, v2
	v_exp_f32_e32 v2, v2
	v_fmaak_f32 v5, v4, v5, 0x3e027906
	v_mul_f32_e32 v4, v4, v5
	v_fma_f32 v5, |v1|, s84, 1.0
	v_rcp_f32_e32 v5, v5
	v_mul_f32_e32 v2, v2, v4
	v_mul_f32_e32 v4, v0, v2
	v_fma_f32 v2, -v0, v2, v0
	v_cndmask_b32_e64 v0, v2, v4, s[0:1]
	v_mul_f32_e32 v154, v154, v0
	v_fmamk_f32 v0, v5, 0x3f07dc22, v241
	v_mul_f32_e32 v2, 0xbf38aa3b, v3
	v_fmaak_f32 v0, v5, v0, 0x3f35f0e3
	v_exp_f32_e32 v2, v2
	v_fmaak_f32 v0, v5, v0, 0xbe11a98e
	v_fmaak_f32 v0, v5, v0, 0x3e027906
	v_mul_f32_e32 v0, v5, v0
	v_mov_b32_e32 v214, v164
	v_mov_b32_e32 v215, v96
	v_mov_b32_e32 v171, v6
	v_mov_b32_e32 v96, v165
	v_mov_b32_e32 v195, v7
	v_mul_f32_e32 v0, v2, v0
	v_pk_mul_f32 v[2:3], v[214:215], v[170:171]
	v_pk_mul_f32 v[4:5], v[96:97], v[194:195]
	v_pk_fma_f32 v[6:7], v[92:93], v[218:219], v[100:101]
	v_mov_b32_e32 v158, v3
	v_mov_b32_e32 v159, v5
	v_pk_add_f32 v[6:7], v[158:159], v[6:7]
	v_mov_b32_e32 v3, v4
	v_pk_add_f32 v[2:3], v[2:3], v[6:7]
	v_mul_f32_e32 v162, v1, v0
	v_fma_f32 v4, |v2|, s84, 1.0
	v_rcp_f32_e32 v4, v4
	v_fma_f32 v0, -v1, v0, v1
	v_cmp_gt_f32_e64 s[0:1], 0, v1
	v_or_b32_e32 v224, 16, v232
	s_nop 0
	v_cndmask_b32_e64 v0, v0, v162, s[0:1]
	v_mul_f32_e32 v5, v155, v0
	v_fmamk_f32 v0, v4, 0x3f07dc22, v241
	v_fmaak_f32 v6, v4, v0, 0x3f35f0e3
	v_pk_mul_f32 v[0:1], v[2:3], v[2:3]
	v_fmaak_f32 v6, v4, v6, 0xbe11a98e
	v_mul_f32_e32 v0, 0xbf38aa3b, v0
	v_exp_f32_e32 v0, v0
	v_fmaak_f32 v6, v4, v6, 0x3e027906
	v_mul_f32_e32 v4, v4, v6
	v_fma_f32 v6, |v3|, s84, 1.0
	v_rcp_f32_e32 v6, v6
	v_mul_f32_e32 v0, v0, v4
	v_mul_f32_e32 v4, v2, v0
	v_fma_f32 v0, -v2, v0, v2
	v_cmp_gt_f32_e64 s[0:1], 0, v2
	v_mul_f32_e32 v1, 0xbf38aa3b, v1
	v_exp_f32_e32 v1, v1
	v_cndmask_b32_e64 v0, v0, v4, s[0:1]
	v_mul_f32_e32 v4, v156, v0
	v_fmamk_f32 v0, v6, 0x3f07dc22, v241
	v_fmaak_f32 v0, v6, v0, 0x3f35f0e3
	v_fmaak_f32 v0, v6, v0, 0xbe11a98e
	v_fmaak_f32 v0, v6, v0, 0x3e027906
	v_mul_f32_e32 v0, v6, v0
	v_mul_f32_e32 v0, v1, v0
	v_mul_f32_e32 v1, v3, v0
	v_fma_f32 v0, -v3, v0, v3
	v_cmp_gt_f32_e64 s[0:1], 0, v3
	v_cvt_pk_bf16_f32 v2, v154, v5
	s_nop 1
	v_cndmask_b32_e64 v0, v0, v1, s[0:1]
	v_mul_f32_e32 v3, v157, v0
	v_cvt_pk_bf16_f32 v3, v4, v3
	v_lshl_add_u64 v[4:5], s[80:81], 0, v[220:221]
	v_cvt_pk_bf16_f32 v0, v233, v168
	v_cvt_pk_bf16_f32 v1, v160, v161
	v_lshl_add_u64 v[160:161], v[4:5], 0, v[186:187]
	global_store_dwordx4 v[160:161], v[0:3], off sc1
	s_nop 1
	v_max_i32_e32 v0, 1, v224
	v_add_u32_e32 v4, -1, v0
	v_max_i32_e32 v0, 2, v224
	v_add_u32_e32 v158, -2, v0
	v_mov_b64_e32 v[0:1], s[30:31]
	v_mad_i64_i32 v[2:3], s[0:1], v224, s76, v[0:1]
	v_lshl_add_u64 v[162:163], v[2:3], 0, v[186:187]
	v_mad_u64_u32 v[2:3], s[0:1], v4, s76, v[0:1]
	v_mad_u64_u32 v[0:1], s[0:1], v158, s76, v[0:1]
	v_lshl_add_u64 v[166:167], v[0:1], 0, v[186:187]
	v_lshl_add_u64 v[164:165], v[2:3], 0, v[186:187]
	v_cmp_gt_i32_e64 s[54:55], s77, v224
	s_movk_i32 s0, 0x1fff
	s_waitcnt vmcnt(1)
	v_mov_b64_e32 v[154:155], v[196:197]
	v_mov_b64_e32 v[156:157], v[198:199]
	v_mov_b64_e32 v[4:5], v[200:201]
	v_mov_b64_e32 v[6:7], v[202:203]
	v_mov_b64_e32 v[0:1], v[242:243]
	v_mov_b64_e32 v[2:3], v[244:245]
	v_lshlrev_b32_e32 v168, 16, v0
	v_cndmask_b32_e64 v158, v228, v224, s[54:55]
	v_and_b32_e32 v169, 0xffff0000, v0
	v_lshlrev_b32_e32 v170, 16, v1
	v_and_b32_e32 v171, 0xffff0000, v1
	v_lshlrev_b32_e32 v216, 16, v2
	v_and_b32_e32 v217, 0xffff0000, v2
	v_lshlrev_b32_e32 v218, 16, v3
	v_and_b32_e32 v219, 0xffff0000, v3
	v_lshlrev_b32_e32 v0, 16, v4
	v_and_b32_e32 v1, 0xffff0000, v4
	v_lshlrev_b32_e32 v2, 16, v5
	v_and_b32_e32 v3, 0xffff0000, v5
	v_lshlrev_b32_e32 v4, 16, v6
	v_and_b32_e32 v5, 0xffff0000, v6
	v_lshlrev_b32_e32 v6, 16, v7
	v_and_b32_e32 v7, 0xffff0000, v7
	v_cmp_gt_i32_e64 s[60:61], 2, v158
	v_cmp_lt_i32_e64 s[40:41], s0, v224
	v_cmp_eq_u32_e64 s[42:43], 0, v158
	v_ashrrev_i32_e32 v159, 31, v158
	s_and_saveexec_b64 s[0:1], s[60:61]
	s_cbranch_execz .LBB0_1223
	s_add_i32 s8, s5, 0xffffe010
	s_ashr_i32 s8, s8, 4
	v_mov_b32_e32 v168, s8
	v_cndmask_b32_e64 v170, v168, 0, s[54:55]
	v_ashrrev_i32_e32 v171, 31, v170
	v_lshl_add_u64 v[168:169], v[170:171], 1, v[158:159]
	v_mov_b64_e32 v[194:195], s[68:69]
	v_mad_u64_u32 v[194:195], s[8:9], v168, s13, v[194:195]
	v_mad_i32_i24 v195, v169, s13, v195
	v_lshl_add_u64 v[222:223], v[184:185], 2, v[194:195]
	v_mov_b32_e32 v168, 0
	s_and_saveexec_b64 s[8:9], s[40:41]
	s_cbranch_execz .LBB0_1176
	global_load_dword v168, v[222:223], off

; __device__ __forceinline__ unsigned pk2(float lo, float hi) { unsigned r; asm("v_cvt_pk_bf16_f32 %0, %1, %2" : "=v"(r) : "v"(lo), "v"(hi)); return r; }
; __device__ __forceinline__ float gelu_f(float v) {
;     const float av = fabsf(v), d = av * 0.2316418882f + 1.0f;
;     const float t = __builtin_amdgcn_rcpf(d);
;     float q = t * 0.5307027145f + (-0.7265760135f); q = q * t + 0.7107068705f; q = q * t + (-0.142248368f); q = q * t + 0.127414796f; q = q * t;
;     const float e = __builtin_amdgcn_exp2f(v * v * (-0.72134752044f));
;     const float m = v * (q * e);
;     return v < 0.f ? m : v - m;
;     __device__ __forceinline__ void operator()(EPI_ARGS) const {
;     ...
;                     for (int t = 0; t < 1; ++t) { const int row = row0 + ai * 128 + (mp + t) * 16; const int r1 = row > 0 ? row - 1 : 0, r2 = row > 1 ? row - 2 : 0;
;                         q2[t] = *(const u32x4*)(up + (size_t)row * DFF + col); q1[t] = *(const u32x4*)(up + (size_t)r1 * DFF + col); q0[t] = *(const u32x4*)(up + (size_t)r2 * DFF + col); }
;                     __builtin_amdgcn_sched_barrier(0);
; #pragma unroll
;                     for (int t = 0; t < 1; ++t) { const int m = mp + t, row = row0 + ai * 128 + m * 16;
;                         const int i = row < TP ? row : ((row - TP) & 15); const int sidx = row < TP ? 0 : ((row - TP) >> 4);
;                         float x0[8], x1[8], x2[8]; unpack8(q0[t], x0); unpack8(q1[t], x1); unpack8(q2[t], x2);
;                         if (i < 2) {
;                             const bool smp = row >= TP; const float* p0 = cs + ((size_t)sidx * 2 + i) * DFF + col; const float* p1 = cs + ((size_t)sidx * 2 + 1) * DFF + col;
; #pragma unroll
;                             for (int e = 0; e < 8; ++e) { x0[e] = smp ? p0[e] : 0.f; if (i == 0) x1[e] = smp ? p1[e] : 0.f; } }
;                         float r[8];
; #pragma unroll
;                         for (int e = 0; e < 8; ++e) { const float cv = bb[e] + x0[e] * w0[e] + x1[e] * w1[e] + x2[e] * w2[e]; r[e] = gelu_f(cv) * acc[ai][bj][m][e >> 2][e & 3]; }
;                         u32x4 w; w.x = pk2(r[0], r[1]); w.y = pk2(r[2], r[3]); w.z = pk2(r[4], r[5]); w.w = pk2(r[6], r[7]);
;                         *(u32x4*)(act + (size_t)row * DFF + col) = w; } } } }
.LBB0_1223:
	s_or_b64 exec, exec, s[0:1]
	v_mad_i64_i32 v[220:221], s[0:1], v224, s76, 0
	v_lshlrev_b32_e32 v194, 16, v154
	v_and_b32_e32 v154, 0xffff0000, v154
	v_lshlrev_b32_e32 v222, 16, v155
	v_and_b32_e32 v224, 0xffff0000, v155
	s_waitcnt vmcnt(1)
	v_add_u32_e32 v240, 32, v232
	v_mov_b64_e32 v[238:239], s[30:31]
	v_mad_i64_i32 v[238:239], s[0:1], v240, s76, v[238:239]
	v_lshl_add_u64 v[238:239], v[238:239], 0, v[186:187]
	global_load_dwordx4 v[196:199], v[238:239], off
	v_add_u32_e32 v240, -1, v240
	v_mov_b64_e32 v[246:247], s[30:31]
	v_mad_i64_i32 v[246:247], s[0:1], v240, s76, v[246:247]
	v_lshl_add_u64 v[246:247], v[246:247], 0, v[186:187]
	global_load_dwordx4 v[200:203], v[246:247], off
	v_add_u32_e32 v240, -1, v240
	v_mov_b64_e32 v[238:239], s[30:31]
	v_mad_i64_i32 v[238:239], s[0:1], v240, s76, v[238:239]
	v_lshl_add_u64 v[238:239], v[238:239], 0, v[186:187]
	global_load_dwordx4 v[242:245], v[238:239], off
	v_mov_b32_e32 v195, v0
	v_mov_b32_e32 v155, v1
	v_pk_mul_f32 v[194:195], v[210:211], v[194:195]
	v_pk_mul_f32 v[0:1], v[106:107], v[154:155]
	v_pk_fma_f32 v[154:155], v[102:103], v[168:169], v[110:111]
	v_mov_b32_e32 v168, v195
	v_mov_b32_e32 v169, v1
	v_pk_add_f32 v[154:155], v[168:169], v[154:155]
	v_mov_b32_e32 v195, v0
	v_pk_add_f32 v[0:1], v[194:195], v[154:155]
	v_lshlrev_b32_e32 v226, 16, v156
	v_fma_f32 v154, |v0|, s84, 1.0
	v_rcp_f32_e32 v155, v154
	v_pk_mul_f32 v[194:195], v[0:1], v[0:1]
	v_and_b32_e32 v154, 0xffff0000, v156
	v_lshlrev_b32_e32 v156, 16, v157
	v_and_b32_e32 v168, 0xffff0000, v157
	v_fmamk_f32 v157, v155, 0x3f07dc22, v241
	v_mul_f32_e32 v169, 0xbf38aa3b, v194
	v_fmaak_f32 v157, v155, v157, 0x3f35f0e3
	v_exp_f32_e32 v169, v169
	v_fmaak_f32 v157, v155, v157, 0xbe11a98e
	v_fmaak_f32 v157, v155, v157, 0x3e027906
	v_mul_f32_e32 v155, v155, v157
	v_mul_f32_e32 v155, v169, v155
	v_fma_f32 v169, |v1|, s84, 1.0
	v_rcp_f32_e32 v169, v169
	v_mul_f32_e32 v157, v0, v155
	v_fma_f32 v155, -v0, v155, v0
	v_cmp_gt_f32_e64 s[0:1], 0, v0
	v_mov_b32_e32 v223, v2
	v_mov_b32_e32 v225, v3
	v_cndmask_b32_e64 v0, v155, v157, s[0:1]
	v_mul_f32_e32 v233, v150, v0
	v_mul_f32_e32 v150, 0xbf38aa3b, v195
	v_pk_mul_f32 v[194:195], v[172:173], v[222:223]
	v_pk_mul_f32 v[2:3], v[108:109], v[224:225]
	v_fmamk_f32 v0, v169, 0x3f07dc22, v241
	v_pk_fma_f32 v[170:171], v[104:105], v[170:171], v[112:113]
	v_mov_b32_e32 v222, v195
	v_mov_b32_e32 v223, v3
	v_fmaak_f32 v0, v169, v0, 0x3f35f0e3
	v_exp_f32_e32 v150, v150
	v_pk_add_f32 v[170:171], v[222:223], v[170:171]
	v_mov_b32_e32 v195, v2
	v_fmaak_f32 v0, v169, v0, 0xbe11a98e
	v_pk_add_f32 v[2:3], v[194:195], v[170:171]
	v_fmaak_f32 v0, v169, v0, 0x3e027906
	v_fma_f32 v155, |v2|, s84, 1.0
	v_mul_f32_e32 v0, v169, v0
	v_rcp_f32_e32 v155, v155
	v_mul_f32_e32 v0, v150, v0
	v_mul_f32_e32 v150, v1, v0
	v_fma_f32 v0, -v1, v0, v1
	v_cmp_gt_f32_e64 s[0:1], 0, v1
	v_mov_b32_e32 v227, v4
	v_mov_b32_e32 v169, v7
	v_cndmask_b32_e64 v0, v0, v150, s[0:1]
	v_mul_f32_e32 v170, v151, v0
	v_fmamk_f32 v0, v155, 0x3f07dc22, v241
	v_fmaak_f32 v150, v155, v0, 0x3f35f0e3
	v_pk_mul_f32 v[0:1], v[2:3], v[2:3]
	v_fmaak_f32 v150, v155, v150, 0xbe11a98e
	v_mul_f32_e32 v0, 0xbf38aa3b, v0
	v_exp_f32_e32 v0, v0
	v_fmaak_f32 v150, v155, v150, 0x3e027906
	v_fma_f32 v151, |v3|, s84, 1.0
	v_mul_f32_e32 v150, v155, v150
	v_rcp_f32_e32 v151, v151
	v_mul_f32_e32 v0, v0, v150
	v_mul_f32_e32 v150, v2, v0
	v_fma_f32 v0, -v2, v0, v2
	v_cmp_gt_f32_e64 s[0:1], 0, v2
	v_mul_f32_e32 v1, 0xbf38aa3b, v1
	v_exp_f32_e32 v1, v1
	v_cndmask_b32_e64 v0, v0, v150, s[0:1]
	v_mul_f32_e32 v152, v152, v0
	v_fmamk_f32 v0, v151, 0x3f07dc22, v241
	v_fmaak_f32 v0, v151, v0, 0x3f35f0e3
	v_fmaak_f32 v0, v151, v0, 0xbe11a98e
	v_fmaak_f32 v0, v151, v0, 0x3e027906
	v_mul_f32_e32 v0, v151, v0
	v_mul_f32_e32 v0, v1, v0
	v_mov_b32_e32 v155, v5
	v_mul_f32_e32 v2, v3, v0
	v_fma_f32 v157, -v3, v0, v3
	v_pk_mul_f32 v[0:1], v[212:213], v[226:227]
	v_pk_mul_f32 v[4:5], v[94:95], v[154:155]
	v_pk_fma_f32 v[150:151], v[90:91], v[216:217], v[98:99]
	v_mov_b32_e32 v154, v1
	v_mov_b32_e32 v155, v5
	v_pk_add_f32 v[150:151], v[154:155], v[150:151]
	v_mov_b32_e32 v1, v4
	v_pk_add_f32 v[0:1], v[0:1], v[150:151]
	v_cmp_gt_f32_e64 s[0:1], 0, v3
	v_fma_f32 v4, |v0|, s84, 1.0
	v_rcp_f32_e32 v4, v4
	v_cndmask_b32_e64 v2, v157, v2, s[0:1]
	v_mul_f32_e32 v153, v153, v2
	v_cmp_gt_f32_e64 s[0:1], 0, v0
	v_fmamk_f32 v2, v4, 0x3f07dc22, v241
	v_fmaak_f32 v5, v4, v2, 0x3f35f0e3
; __device__ __forceinline__ unsigned pk2(float lo, float hi) { unsigned r; asm("v_cvt_pk_bf16_f32 %0, %1, %2" : "=v"(r) : "v"(lo), "v"(hi)); return r; }
;     static __device__ __forceinline__ void unpack8(const u32x4 q, float (&x)[8]) { x[0] = bflo(q.x); x[1] = bfhi(q.x); x[2] = bflo(q.y); x[3] = bfhi(q.y); x[4] = bflo(q.z); x[5] = bfhi(q.z); x[6] = bflo(q.w); x[7] = bfhi(q.w); }
;     __device__ __forceinline__ void operator()(EPI_ARGS) const {
;     ...
;                     for (int t = 0; t < 1; ++t) { const int row = row0 + ai * 128 + (mp + t) * 16; const int r1 = row > 0 ? row - 1 : 0, r2 = row > 1 ? row - 2 : 0;
;                         q2[t] = *(const u32x4*)(up + (size_t)row * DFF + col); q1[t] = *(const u32x4*)(up + (size_t)r1 * DFF + col); q0[t] = *(const u32x4*)(up + (size_t)r2 * DFF + col); }
;                     __builtin_amdgcn_sched_barrier(0);
; #pragma unroll
;                     for (int t = 0; t < 1; ++t) { const int m = mp + t, row = row0 + ai * 128 + m * 16;
;                         const int i = row < TP ? row : ((row - TP) & 15); const int sidx = row < TP ? 0 : ((row - TP) >> 4);
;                         float x0[8], x1[8], x2[8]; unpack8(q0[t], x0); unpack8(q1[t], x1); unpack8(q2[t], x2);
;                         if (i < 2) {
;                             const bool smp = row >= TP; const float* p0 = cs + ((size_t)sidx * 2 + i) * DFF + col; const float* p1 = cs + ((size_t)sidx * 2 + 1) * DFF + col;
; #pragma unroll
;                             for (int e = 0; e < 8; ++e) { x0[e] = smp ? p0[e] : 0.f; if (i == 0) x1[e] = smp ? p1[e] : 0.f; } }
;     ...
;                         for (int e = 0; e < 8; ++e) { const float cv = bb[e] + x0[e] * w0[e] + x1[e] * w1[e] + x2[e] * w2[e]; r[e] = gelu_f(cv) * acc[ai][bj][m][e >> 2][e & 3]; }
;                         u32x4 w; w.x = pk2(r[0], r[1]); w.y = pk2(r[2], r[3]); w.z = pk2(r[4], r[5]); w.w = pk2(r[6], r[7]);
;                         *(u32x4*)(act + (size_t)row * DFF + col) = w; } } } }
	v_pk_mul_f32 v[2:3], v[0:1], v[0:1]
	v_fmaak_f32 v5, v4, v5, 0xbe11a98e
	v_mul_f32_e32 v2, 0xbf38aa3b, v2
	v_exp_f32_e32 v2, v2
	v_fmaak_f32 v5, v4, v5, 0x3e027906
	v_mul_f32_e32 v4, v4, v5
	v_fma_f32 v5, |v1|, s84, 1.0
	v_rcp_f32_e32 v5, v5
	v_mul_f32_e32 v2, v2, v4
	v_mul_f32_e32 v4, v0, v2
	v_fma_f32 v2, -v0, v2, v0
	v_cndmask_b32_e64 v0, v2, v4, s[0:1]
	v_mul_f32_e32 v146, v146, v0
	v_fmamk_f32 v0, v5, 0x3f07dc22, v241
	v_mul_f32_e32 v2, 0xbf38aa3b, v3
	v_fmaak_f32 v0, v5, v0, 0x3f35f0e3
	v_exp_f32_e32 v2, v2
	v_fmaak_f32 v0, v5, v0, 0xbe11a98e
	v_fmaak_f32 v0, v5, v0, 0x3e027906
	v_mul_f32_e32 v0, v5, v0
	v_mov_b32_e32 v157, v6
	v_mul_f32_e32 v0, v2, v0
	v_pk_mul_f32 v[2:3], v[214:215], v[156:157]
	v_pk_mul_f32 v[4:5], v[96:97], v[168:169]
	v_pk_fma_f32 v[6:7], v[92:93], v[218:219], v[100:101]
	v_mov_b32_e32 v150, v3
	v_mov_b32_e32 v151, v5
	v_pk_add_f32 v[6:7], v[150:151], v[6:7]
	v_mov_b32_e32 v3, v4
	v_pk_add_f32 v[2:3], v[2:3], v[6:7]
	v_mul_f32_e32 v154, v1, v0
	v_fma_f32 v4, |v2|, s84, 1.0
	v_rcp_f32_e32 v4, v4
	v_fma_f32 v0, -v1, v0, v1
	v_cmp_gt_f32_e64 s[0:1], 0, v1
	v_or_b32_e32 v226, 32, v232
	s_nop 0
	v_cndmask_b32_e64 v0, v0, v154, s[0:1]
	v_mul_f32_e32 v5, v147, v0
	v_fmamk_f32 v0, v4, 0x3f07dc22, v241
	v_fmaak_f32 v6, v4, v0, 0x3f35f0e3
	v_pk_mul_f32 v[0:1], v[2:3], v[2:3]
	v_fmaak_f32 v6, v4, v6, 0xbe11a98e
	v_mul_f32_e32 v0, 0xbf38aa3b, v0
	v_exp_f32_e32 v0, v0
	v_fmaak_f32 v6, v4, v6, 0x3e027906
	v_mul_f32_e32 v4, v4, v6
	v_fma_f32 v6, |v3|, s84, 1.0
	v_rcp_f32_e32 v6, v6
	v_mul_f32_e32 v0, v0, v4
	v_mul_f32_e32 v4, v2, v0
	v_fma_f32 v0, -v2, v0, v2
	v_cmp_gt_f32_e64 s[0:1], 0, v2
	v_mul_f32_e32 v1, 0xbf38aa3b, v1
	v_exp_f32_e32 v1, v1
	v_cndmask_b32_e64 v0, v0, v4, s[0:1]
	v_mul_f32_e32 v4, v148, v0
	v_fmamk_f32 v0, v6, 0x3f07dc22, v241
	v_fmaak_f32 v0, v6, v0, 0x3f35f0e3
	v_fmaak_f32 v0, v6, v0, 0xbe11a98e
	v_fmaak_f32 v0, v6, v0, 0x3e027906
	v_mul_f32_e32 v0, v6, v0
	v_mul_f32_e32 v0, v1, v0
	v_mul_f32_e32 v1, v3, v0
	v_fma_f32 v0, -v3, v0, v3
	v_cmp_gt_f32_e64 s[0:1], 0, v3
	v_cvt_pk_bf16_f32 v2, v146, v5
	s_nop 1
	v_cndmask_b32_e64 v0, v0, v1, s[0:1]
	v_mul_f32_e32 v3, v149, v0
	v_cvt_pk_bf16_f32 v3, v4, v3
	v_lshl_add_u64 v[4:5], s[80:81], 0, v[220:221]
	v_cvt_pk_bf16_f32 v0, v233, v170
	v_cvt_pk_bf16_f32 v1, v152, v153
	v_lshl_add_u64 v[152:153], v[4:5], 0, v[186:187]
	global_store_dwordx4 v[152:153], v[0:3], off sc1
	s_nop 1
	v_max_i32_e32 v0, 1, v226
	v_add_u32_e32 v4, -1, v0
	v_max_i32_e32 v0, 2, v226
	v_add_u32_e32 v150, -2, v0
	v_mov_b64_e32 v[0:1], s[30:31]
	v_mad_i64_i32 v[2:3], s[0:1], v226, s76, v[0:1]
	v_lshl_add_u64 v[154:155], v[2:3], 0, v[186:187]
	v_mad_u64_u32 v[2:3], s[0:1], v4, s76, v[0:1]
	v_mad_u64_u32 v[0:1], s[0:1], v150, s76, v[0:1]
	v_lshl_add_u64 v[168:169], v[0:1], 0, v[186:187]
	v_lshl_add_u64 v[156:157], v[2:3], 0, v[186:187]
	v_cmp_gt_i32_e64 s[58:59], s77, v226
	s_movk_i32 s0, 0x1fff
	s_waitcnt vmcnt(1)
	v_mov_b64_e32 v[146:147], v[196:197]
	v_mov_b64_e32 v[148:149], v[198:199]
	v_mov_b64_e32 v[4:5], v[200:201]
	v_mov_b64_e32 v[6:7], v[202:203]
	v_mov_b64_e32 v[0:1], v[242:243]
	v_mov_b64_e32 v[2:3], v[244:245]
	v_lshlrev_b32_e32 v170, 16, v0
	v_cndmask_b32_e64 v150, v228, v226, s[58:59]
	v_and_b32_e32 v171, 0xffff0000, v0
	v_lshlrev_b32_e32 v216, 16, v1
	v_and_b32_e32 v217, 0xffff0000, v1
	v_lshlrev_b32_e32 v218, 16, v2
	v_and_b32_e32 v219, 0xffff0000, v2
	v_lshlrev_b32_e32 v220, 16, v3
	v_and_b32_e32 v221, 0xffff0000, v3
	v_lshlrev_b32_e32 v0, 16, v4
	v_and_b32_e32 v1, 0xffff0000, v4
	v_lshlrev_b32_e32 v2, 16, v5
	v_and_b32_e32 v3, 0xffff0000, v5
	v_lshlrev_b32_e32 v4, 16, v6
	v_and_b32_e32 v5, 0xffff0000, v6
	v_lshlrev_b32_e32 v6, 16, v7
	v_and_b32_e32 v7, 0xffff0000, v7
	v_cmp_gt_i32_e64 s[64:65], 2, v150
	v_cmp_lt_i32_e64 s[44:45], s0, v226
	v_cmp_eq_u32_e64 s[46:47], 0, v150
	v_ashrrev_i32_e32 v151, 31, v150
	s_and_saveexec_b64 s[0:1], s[64:65]
	s_cbranch_execz .LBB0_1273
	s_add_i32 s8, s5, 0xffffe020
	s_ashr_i32 s8, s8, 4
	v_mov_b32_e32 v170, s8
	v_cndmask_b32_e64 v216, v170, 0, s[58:59]
	v_ashrrev_i32_e32 v217, 31, v216
	v_lshl_add_u64 v[170:171], v[216:217], 1, v[150:151]
	v_mov_b64_e32 v[194:195], s[68:69]
	v_mad_u64_u32 v[194:195], s[8:9], v170, s13, v[194:195]
	v_mad_i32_i24 v195, v171, s13, v195
	v_lshl_add_u64 v[224:225], v[184:185], 2, v[194:195]
	v_mov_b32_e32 v170, 0
	s_and_saveexec_b64 s[8:9], s[44:45]
	s_cbranch_execz .LBB0_1226
	global_load_dword v170, v[224:225], off

; __device__ __forceinline__ unsigned pk2(float lo, float hi) { unsigned r; asm("v_cvt_pk_bf16_f32 %0, %1, %2" : "=v"(r) : "v"(lo), "v"(hi)); return r; }
; __device__ __forceinline__ float gelu_f(float v) {
;     const float av = fabsf(v), d = av * 0.2316418882f + 1.0f;
;     const float t = __builtin_amdgcn_rcpf(d);
;     float q = t * 0.5307027145f + (-0.7265760135f); q = q * t + 0.7107068705f; q = q * t + (-0.142248368f); q = q * t + 0.127414796f; q = q * t;
;     const float e = __builtin_amdgcn_exp2f(v * v * (-0.72134752044f));
;     const float m = v * (q * e);
;     return v < 0.f ? m : v - m;
;     __device__ __forceinline__ void operator()(EPI_ARGS) const {
;     ...
;                     for (int t = 0; t < 1; ++t) { const int row = row0 + ai * 128 + (mp + t) * 16; const int r1 = row > 0 ? row - 1 : 0, r2 = row > 1 ? row - 2 : 0;
;                         q2[t] = *(const u32x4*)(up + (size_t)row * DFF + col); q1[t] = *(const u32x4*)(up + (size_t)r1 * DFF + col); q0[t] = *(const u32x4*)(up + (size_t)r2 * DFF + col); }
;                     __builtin_amdgcn_sched_barrier(0);
; #pragma unroll
;                     for (int t = 0; t < 1; ++t) { const int m = mp + t, row = row0 + ai * 128 + m * 16;
;                         const int i = row < TP ? row : ((row - TP) & 15); const int sidx = row < TP ? 0 : ((row - TP) >> 4);
;                         float x0[8], x1[8], x2[8]; unpack8(q0[t], x0); unpack8(q1[t], x1); unpack8(q2[t], x2);
;                         if (i < 2) {
;                             const bool smp = row >= TP; const float* p0 = cs + ((size_t)sidx * 2 + i) * DFF + col; const float* p1 = cs + ((size_t)sidx * 2 + 1) * DFF + col;
; #pragma unroll
;                             for (int e = 0; e < 8; ++e) { x0[e] = smp ? p0[e] : 0.f; if (i == 0) x1[e] = smp ? p1[e] : 0.f; } }
;                         float r[8];
; #pragma unroll
;                         for (int e = 0; e < 8; ++e) { const float cv = bb[e] + x0[e] * w0[e] + x1[e] * w1[e] + x2[e] * w2[e]; r[e] = gelu_f(cv) * acc[ai][bj][m][e >> 2][e & 3]; }
;                         u32x4 w; w.x = pk2(r[0], r[1]); w.y = pk2(r[2], r[3]); w.z = pk2(r[4], r[5]); w.w = pk2(r[6], r[7]);
;                         *(u32x4*)(act + (size_t)row * DFF + col) = w; } } } }
.LBB0_1273:
	s_or_b64 exec, exec, s[0:1]
	v_mad_i64_i32 v[222:223], s[0:1], v226, s76, 0
	v_lshlrev_b32_e32 v194, 16, v146
	v_and_b32_e32 v146, 0xffff0000, v146
	v_lshlrev_b32_e32 v224, 16, v147
	v_and_b32_e32 v226, 0xffff0000, v147
	s_waitcnt vmcnt(1)
	v_add_u32_e32 v240, 48, v232
	v_mov_b64_e32 v[238:239], s[30:31]
	v_mad_i64_i32 v[238:239], s[0:1], v240, s76, v[238:239]
	v_lshl_add_u64 v[238:239], v[238:239], 0, v[186:187]
	global_load_dwordx4 v[196:199], v[238:239], off
	v_add_u32_e32 v240, -1, v240
	v_mov_b64_e32 v[246:247], s[30:31]
	v_mad_i64_i32 v[246:247], s[0:1], v240, s76, v[246:247]
	v_lshl_add_u64 v[246:247], v[246:247], 0, v[186:187]
	global_load_dwordx4 v[200:203], v[246:247], off
	v_add_u32_e32 v240, -1, v240
	v_mov_b64_e32 v[238:239], s[30:31]
	v_mad_i64_i32 v[238:239], s[0:1], v240, s76, v[238:239]
	v_lshl_add_u64 v[238:239], v[238:239], 0, v[186:187]
	global_load_dwordx4 v[242:245], v[238:239], off
	v_mov_b32_e32 v195, v0
	v_mov_b32_e32 v147, v1
	v_pk_mul_f32 v[194:195], v[210:211], v[194:195]
	v_pk_mul_f32 v[0:1], v[106:107], v[146:147]
	v_pk_fma_f32 v[146:147], v[102:103], v[170:171], v[110:111]
	v_mov_b32_e32 v170, v195
	v_mov_b32_e32 v171, v1
	v_pk_add_f32 v[146:147], v[170:171], v[146:147]
	v_mov_b32_e32 v195, v0
	v_pk_add_f32 v[0:1], v[194:195], v[146:147]
	v_lshlrev_b32_e32 v234, 16, v148
	v_fma_f32 v146, |v0|, s84, 1.0
	v_rcp_f32_e32 v147, v146
	v_pk_mul_f32 v[194:195], v[0:1], v[0:1]
	v_and_b32_e32 v146, 0xffff0000, v148
	v_lshlrev_b32_e32 v148, 16, v149
	v_and_b32_e32 v170, 0xffff0000, v149
	v_fmamk_f32 v149, v147, 0x3f07dc22, v241
	v_mul_f32_e32 v171, 0xbf38aa3b, v194
	v_fmaak_f32 v149, v147, v149, 0x3f35f0e3
	v_exp_f32_e32 v171, v171
	v_fmaak_f32 v149, v147, v149, 0xbe11a98e
	v_fmaak_f32 v149, v147, v149, 0x3e027906
	v_mul_f32_e32 v147, v147, v149
	v_mul_f32_e32 v147, v171, v147
	v_fma_f32 v171, |v1|, s84, 1.0
	v_rcp_f32_e32 v171, v171
	v_mul_f32_e32 v149, v0, v147
	v_fma_f32 v147, -v0, v147, v0
	v_cmp_gt_f32_e64 s[0:1], 0, v0
	v_mov_b32_e32 v225, v2
	v_mov_b32_e32 v227, v3
	v_cndmask_b32_e64 v0, v147, v149, s[0:1]
	v_mul_f32_e32 v233, v142, v0
	v_mul_f32_e32 v142, 0xbf38aa3b, v195
	v_pk_mul_f32 v[194:195], v[172:173], v[224:225]
	v_pk_mul_f32 v[2:3], v[108:109], v[226:227]
	v_fmamk_f32 v0, v171, 0x3f07dc22, v241
	v_pk_fma_f32 v[216:217], v[104:105], v[216:217], v[112:113]
	v_mov_b32_e32 v224, v195
	v_mov_b32_e32 v225, v3
	v_fmaak_f32 v0, v171, v0, 0x3f35f0e3
	v_exp_f32_e32 v142, v142
	v_pk_add_f32 v[216:217], v[224:225], v[216:217]
	v_mov_b32_e32 v195, v2
	v_fmaak_f32 v0, v171, v0, 0xbe11a98e
	v_pk_add_f32 v[2:3], v[194:195], v[216:217]
	v_fmaak_f32 v0, v171, v0, 0x3e027906
	v_fma_f32 v147, |v2|, s84, 1.0
	v_mul_f32_e32 v0, v171, v0
	v_rcp_f32_e32 v147, v147
	v_mul_f32_e32 v0, v142, v0
	v_mul_f32_e32 v142, v1, v0
	v_fma_f32 v0, -v1, v0, v1
	v_cmp_gt_f32_e64 s[0:1], 0, v1
	v_mov_b32_e32 v235, v4
	v_mov_b32_e32 v171, v7
	v_cndmask_b32_e64 v0, v0, v142, s[0:1]
	v_mul_f32_e32 v194, v143, v0
	v_fmamk_f32 v0, v147, 0x3f07dc22, v241
	v_fmaak_f32 v142, v147, v0, 0x3f35f0e3
	v_pk_mul_f32 v[0:1], v[2:3], v[2:3]
	v_fmaak_f32 v142, v147, v142, 0xbe11a98e
	v_mul_f32_e32 v0, 0xbf38aa3b, v0
	v_exp_f32_e32 v0, v0
	v_fmaak_f32 v142, v147, v142, 0x3e027906
	v_fma_f32 v143, |v3|, s84, 1.0
	v_mul_f32_e32 v142, v147, v142
	v_rcp_f32_e32 v143, v143
	v_mul_f32_e32 v0, v0, v142
	v_mul_f32_e32 v142, v2, v0
	v_fma_f32 v0, -v2, v0, v2
	v_cmp_gt_f32_e64 s[0:1], 0, v2
	v_mul_f32_e32 v1, 0xbf38aa3b, v1
	v_exp_f32_e32 v1, v1
	v_cndmask_b32_e64 v0, v0, v142, s[0:1]
	v_mul_f32_e32 v144, v144, v0
	v_fmamk_f32 v0, v143, 0x3f07dc22, v241
	v_fmaak_f32 v0, v143, v0, 0x3f35f0e3
	v_fmaak_f32 v0, v143, v0, 0xbe11a98e
	v_fmaak_f32 v0, v143, v0, 0x3e027906
	v_mul_f32_e32 v0, v143, v0
	v_mul_f32_e32 v0, v1, v0
	v_mov_b32_e32 v147, v5
	v_mul_f32_e32 v2, v3, v0
	v_fma_f32 v149, -v3, v0, v3
	v_pk_mul_f32 v[0:1], v[212:213], v[234:235]
	v_pk_mul_f32 v[4:5], v[94:95], v[146:147]
	v_pk_fma_f32 v[142:143], v[90:91], v[218:219], v[98:99]
	v_mov_b32_e32 v146, v1
	v_mov_b32_e32 v147, v5
	v_pk_add_f32 v[142:143], v[146:147], v[142:143]
	v_mov_b32_e32 v1, v4
	v_pk_add_f32 v[0:1], v[0:1], v[142:143]
	v_cmp_gt_f32_e64 s[0:1], 0, v3
	v_fma_f32 v4, |v0|, s84, 1.0
	v_rcp_f32_e32 v4, v4
	v_cndmask_b32_e64 v2, v149, v2, s[0:1]
	v_mul_f32_e32 v145, v145, v2
	v_cmp_gt_f32_e64 s[0:1], 0, v0
	v_fmamk_f32 v2, v4, 0x3f07dc22, v241
	v_fmaak_f32 v5, v4, v2, 0x3f35f0e3
; __device__ __forceinline__ unsigned pk2(float lo, float hi) { unsigned r; asm("v_cvt_pk_bf16_f32 %0, %1, %2" : "=v"(r) : "v"(lo), "v"(hi)); return r; }
;     static __device__ __forceinline__ void unpack8(const u32x4 q, float (&x)[8]) { x[0] = bflo(q.x); x[1] = bfhi(q.x); x[2] = bflo(q.y); x[3] = bfhi(q.y); x[4] = bflo(q.z); x[5] = bfhi(q.z); x[6] = bflo(q.w); x[7] = bfhi(q.w); }
;     __device__ __forceinline__ void operator()(EPI_ARGS) const {
;     ...
;                     for (int t = 0; t < 1; ++t) { const int row = row0 + ai * 128 + (mp + t) * 16; const int r1 = row > 0 ? row - 1 : 0, r2 = row > 1 ? row - 2 : 0;
;                         q2[t] = *(const u32x4*)(up + (size_t)row * DFF + col); q1[t] = *(const u32x4*)(up + (size_t)r1 * DFF + col); q0[t] = *(const u32x4*)(up + (size_t)r2 * DFF + col); }
;                     __builtin_amdgcn_sched_barrier(0);
; #pragma unroll
;                     for (int t = 0; t < 1; ++t) { const int m = mp + t, row = row0 + ai * 128 + m * 16;
;                         const int i = row < TP ? row : ((row - TP) & 15); const int sidx = row < TP ? 0 : ((row - TP) >> 4);
;                         float x0[8], x1[8], x2[8]; unpack8(q0[t], x0); unpack8(q1[t], x1); unpack8(q2[t], x2);
;                         if (i < 2) {
;                             const bool smp = row >= TP; const float* p0 = cs + ((size_t)sidx * 2 + i) * DFF + col; const float* p1 = cs + ((size_t)sidx * 2 + 1) * DFF + col;
; #pragma unroll
;                             for (int e = 0; e < 8; ++e) { x0[e] = smp ? p0[e] : 0.f; if (i == 0) x1[e] = smp ? p1[e] : 0.f; } }
;     ...
;                         for (int e = 0; e < 8; ++e) { const float cv = bb[e] + x0[e] * w0[e] + x1[e] * w1[e] + x2[e] * w2[e]; r[e] = gelu_f(cv) * acc[ai][bj][m][e >> 2][e & 3]; }
;                         u32x4 w; w.x = pk2(r[0], r[1]); w.y = pk2(r[2], r[3]); w.z = pk2(r[4], r[5]); w.w = pk2(r[6], r[7]);
;                         *(u32x4*)(act + (size_t)row * DFF + col) = w; } } } }
	v_pk_mul_f32 v[2:3], v[0:1], v[0:1]
	v_fmaak_f32 v5, v4, v5, 0xbe11a98e
	v_mul_f32_e32 v2, 0xbf38aa3b, v2
	v_exp_f32_e32 v2, v2
	v_fmaak_f32 v5, v4, v5, 0x3e027906
	v_mul_f32_e32 v4, v4, v5
	v_fma_f32 v5, |v1|, s84, 1.0
	v_rcp_f32_e32 v5, v5
	v_mul_f32_e32 v2, v2, v4
	v_mul_f32_e32 v4, v0, v2
	v_fma_f32 v2, -v0, v2, v0
	v_cndmask_b32_e64 v0, v2, v4, s[0:1]
	v_mul_f32_e32 v138, v138, v0
	v_fmamk_f32 v0, v5, 0x3f07dc22, v241
	v_mul_f32_e32 v2, 0xbf38aa3b, v3
	v_fmaak_f32 v0, v5, v0, 0x3f35f0e3
	v_exp_f32_e32 v2, v2
	v_fmaak_f32 v0, v5, v0, 0xbe11a98e
	v_fmaak_f32 v0, v5, v0, 0x3e027906
	v_mul_f32_e32 v0, v5, v0
	v_mov_b32_e32 v149, v6
	v_mul_f32_e32 v0, v2, v0
	v_pk_mul_f32 v[2:3], v[214:215], v[148:149]
	v_pk_mul_f32 v[4:5], v[96:97], v[170:171]
	v_pk_fma_f32 v[6:7], v[92:93], v[220:221], v[100:101]
	v_mov_b32_e32 v142, v3
	v_mov_b32_e32 v143, v5
	v_pk_add_f32 v[6:7], v[142:143], v[6:7]
	v_mov_b32_e32 v3, v4
	v_pk_add_f32 v[2:3], v[2:3], v[6:7]
	v_mul_f32_e32 v146, v1, v0
	v_fma_f32 v4, |v2|, s84, 1.0
	v_rcp_f32_e32 v4, v4
	v_fma_f32 v0, -v1, v0, v1
	v_cmp_gt_f32_e64 s[0:1], 0, v1
	s_nop 1
	v_cndmask_b32_e64 v0, v0, v146, s[0:1]
	v_mul_f32_e32 v5, v139, v0
	v_fmamk_f32 v0, v4, 0x3f07dc22, v241
	v_fmaak_f32 v6, v4, v0, 0x3f35f0e3
	v_pk_mul_f32 v[0:1], v[2:3], v[2:3]
	v_fmaak_f32 v6, v4, v6, 0xbe11a98e
	v_mul_f32_e32 v0, 0xbf38aa3b, v0
	v_exp_f32_e32 v0, v0
	v_fmaak_f32 v6, v4, v6, 0x3e027906
	v_mul_f32_e32 v4, v4, v6
	v_fma_f32 v6, |v3|, s84, 1.0
	v_rcp_f32_e32 v6, v6
	v_mul_f32_e32 v0, v0, v4
	v_mul_f32_e32 v4, v2, v0
	v_fma_f32 v0, -v2, v0, v2
	v_cmp_gt_f32_e64 s[0:1], 0, v2
	v_mul_f32_e32 v1, 0xbf38aa3b, v1
	v_exp_f32_e32 v1, v1
	v_cndmask_b32_e64 v0, v0, v4, s[0:1]
	v_mul_f32_e32 v4, v140, v0
	v_fmamk_f32 v0, v6, 0x3f07dc22, v241
	v_fmaak_f32 v0, v6, v0, 0x3f35f0e3
	v_fmaak_f32 v0, v6, v0, 0xbe11a98e
	v_fmaak_f32 v0, v6, v0, 0x3e027906
	v_mul_f32_e32 v0, v6, v0
	v_mul_f32_e32 v0, v1, v0
	v_mul_f32_e32 v1, v3, v0
	v_fma_f32 v0, -v3, v0, v3
	v_cmp_gt_f32_e64 s[0:1], 0, v3
	v_cvt_pk_bf16_f32 v2, v138, v5
	s_nop 1
	v_cndmask_b32_e64 v0, v0, v1, s[0:1]
	v_mul_f32_e32 v3, v141, v0
	v_cvt_pk_bf16_f32 v3, v4, v3
	v_lshl_add_u64 v[4:5], s[80:81], 0, v[222:223]
	v_cvt_pk_bf16_f32 v0, v233, v194
	v_cvt_pk_bf16_f32 v1, v144, v145
	v_lshl_add_u64 v[144:145], v[4:5], 0, v[186:187]
	v_or_b32_e32 v233, 48, v232
	global_store_dwordx4 v[144:145], v[0:3], off sc1
	s_nop 1
	v_max_i32_e32 v0, 1, v233
	v_add_u32_e32 v4, -1, v0
	v_max_i32_e32 v0, 2, v233
	v_add_u32_e32 v142, -2, v0
	v_mov_b64_e32 v[0:1], s[30:31]
	v_mad_i64_i32 v[2:3], s[0:1], v233, s76, v[0:1]
	v_lshl_add_u64 v[146:147], v[2:3], 0, v[186:187]
	v_mad_u64_u32 v[2:3], s[0:1], v4, s76, v[0:1]
	v_mad_u64_u32 v[0:1], s[0:1], v142, s76, v[0:1]
	v_lshl_add_u64 v[170:171], v[0:1], 0, v[186:187]
	v_lshl_add_u64 v[148:149], v[2:3], 0, v[186:187]
	v_cmp_gt_i32_e64 s[62:63], s77, v233
	s_movk_i32 s0, 0x1fff
	s_waitcnt vmcnt(1)
	v_mov_b64_e32 v[138:139], v[196:197]
	v_mov_b64_e32 v[140:141], v[198:199]
	v_mov_b64_e32 v[4:5], v[200:201]
	v_mov_b64_e32 v[6:7], v[202:203]
	v_mov_b64_e32 v[0:1], v[242:243]
	v_mov_b64_e32 v[2:3], v[244:245]
	v_lshlrev_b32_e32 v216, 16, v0
	v_cndmask_b32_e64 v142, v228, v233, s[62:63]
	v_and_b32_e32 v217, 0xffff0000, v0
	v_lshlrev_b32_e32 v218, 16, v1
	v_and_b32_e32 v219, 0xffff0000, v1
	v_lshlrev_b32_e32 v220, 16, v2
	v_and_b32_e32 v221, 0xffff0000, v2
	v_lshlrev_b32_e32 v222, 16, v3
	v_and_b32_e32 v223, 0xffff0000, v3
	v_lshlrev_b32_e32 v0, 16, v4
	v_and_b32_e32 v1, 0xffff0000, v4
	v_lshlrev_b32_e32 v2, 16, v5
	v_and_b32_e32 v3, 0xffff0000, v5
	v_lshlrev_b32_e32 v4, 16, v6
	v_and_b32_e32 v5, 0xffff0000, v6
	v_lshlrev_b32_e32 v6, 16, v7
	v_and_b32_e32 v7, 0xffff0000, v7
	v_cmp_gt_i32_e64 s[66:67], 2, v142
	v_cmp_lt_i32_e64 s[48:49], s0, v233
	v_cmp_eq_u32_e64 s[50:51], 0, v142
	v_ashrrev_i32_e32 v143, 31, v142
	s_and_saveexec_b64 s[0:1], s[66:67]
	s_cbranch_execz .LBB0_1323
	s_add_i32 s8, s5, 0xffffe030
	s_ashr_i32 s8, s8, 4
	v_mov_b32_e32 v194, s8
	v_cndmask_b32_e64 v218, v194, 0, s[62:63]
	v_ashrrev_i32_e32 v219, 31, v218
	v_lshl_add_u64 v[194:195], v[218:219], 1, v[142:143]
	v_mov_b64_e32 v[216:217], s[68:69]
	v_mad_u64_u32 v[216:217], s[8:9], v194, s13, v[216:217]
	v_mad_i32_i24 v217, v195, s13, v217
	v_lshl_add_u64 v[226:227], v[184:185], 2, v[216:217]
	v_mov_b32_e32 v216, 0
	s_and_saveexec_b64 s[8:9], s[48:49]
	s_cbranch_execz .LBB0_1276
	global_load_dword v216, v[226:227], off

; __device__ __forceinline__ unsigned pk2(float lo, float hi) { unsigned r; asm("v_cvt_pk_bf16_f32 %0, %1, %2" : "=v"(r) : "v"(lo), "v"(hi)); return r; }
;     static __device__ __forceinline__ void unpack8(const u32x4 q, float (&x)[8]) { x[0] = bflo(q.x); x[1] = bfhi(q.x); x[2] = bflo(q.y); x[3] = bfhi(q.y); x[4] = bflo(q.z); x[5] = bfhi(q.z); x[6] = bflo(q.w); x[7] = bfhi(q.w); }
;     __device__ __forceinline__ void operator()(EPI_ARGS) const {
;     ...
;                 if (u.pm == 32 && ai == 1) continue;
;     ...
;                     for (int t = 0; t < 1; ++t) { const int row = row0 + ai * 128 + (mp + t) * 16; const int r1 = row > 0 ? row - 1 : 0, r2 = row > 1 ? row - 2 : 0;
;                         q2[t] = *(const u32x4*)(up + (size_t)row * DFF + col); q1[t] = *(const u32x4*)(up + (size_t)r1 * DFF + col); q0[t] = *(const u32x4*)(up + (size_t)r2 * DFF + col); }
;                     __builtin_amdgcn_sched_barrier(0);
; #pragma unroll
;                     for (int t = 0; t < 1; ++t) { const int m = mp + t, row = row0 + ai * 128 + m * 16;
;                         const int i = row < TP ? row : ((row - TP) & 15); const int sidx = row < TP ? 0 : ((row - TP) >> 4);
;                         float x0[8], x1[8], x2[8]; unpack8(q0[t], x0); unpack8(q1[t], x1); unpack8(q2[t], x2);
;                         if (i < 2) {
;                             const bool smp = row >= TP; const float* p0 = cs + ((size_t)sidx * 2 + i) * DFF + col; const float* p1 = cs + ((size_t)sidx * 2 + 1) * DFF + col;
; #pragma unroll
;                             for (int e = 0; e < 8; ++e) { x0[e] = smp ? p0[e] : 0.f; if (i == 0) x1[e] = smp ? p1[e] : 0.f; } }
;                         float r[8];
; #pragma unroll
;                         for (int e = 0; e < 8; ++e) { const float cv = bb[e] + x0[e] * w0[e] + x1[e] * w1[e] + x2[e] * w2[e]; r[e] = gelu_f(cv) * acc[ai][bj][m][e >> 2][e & 3]; }
;                         u32x4 w; w.x = pk2(r[0], r[1]); w.y = pk2(r[2], r[3]); w.z = pk2(r[4], r[5]); w.w = pk2(r[6], r[7]);
;                         *(u32x4*)(act + (size_t)row * DFF + col) = w; } } } }
.LBB0_1323:
	s_or_b64 exec, exec, s[0:1]
	v_lshlrev_b32_e32 v194, 16, v138
	v_and_b32_e32 v138, 0xffff0000, v138
	v_lshlrev_b32_e32 v226, 16, v139
	v_and_b32_e32 v234, 0xffff0000, v139
	s_waitcnt vmcnt(1)
	v_mov_b32_e32 v195, v0
	v_mov_b32_e32 v139, v1
	v_pk_mul_f32 v[194:195], v[210:211], v[194:195]
	v_pk_mul_f32 v[0:1], v[106:107], v[138:139]
	v_pk_fma_f32 v[138:139], v[102:103], v[216:217], v[110:111]
	v_mov_b32_e32 v216, v195
	v_mov_b32_e32 v217, v1
	v_pk_add_f32 v[138:139], v[216:217], v[138:139]
	v_mov_b32_e32 v195, v0
	v_pk_add_f32 v[0:1], v[194:195], v[138:139]
	v_lshlrev_b32_e32 v248, 16, v141
	v_fma_f32 v138, |v0|, s84, 1.0
	v_and_b32_e32 v250, 0xffff0000, v141
	v_rcp_f32_e32 v141, v138
	v_mad_i64_i32 v[224:225], s[0:1], v233, s76, 0
	v_cmp_gt_f32_e64 s[0:1], 0, v0
	v_fmamk_f32 v138, v141, 0x3f07dc22, v241
	v_fmaak_f32 v194, v141, v138, 0x3f35f0e3
	v_pk_mul_f32 v[138:139], v[0:1], v[0:1]
	v_fmaak_f32 v194, v141, v194, 0xbe11a98e
	v_mul_f32_e32 v138, 0xbf38aa3b, v138
	v_exp_f32_e32 v138, v138
	v_fmaak_f32 v194, v141, v194, 0x3e027906
	v_mul_f32_e32 v141, v141, v194
	v_fma_f32 v194, |v1|, s84, 1.0
	v_rcp_f32_e32 v194, v194
	v_mul_f32_e32 v138, v138, v141
	v_mul_f32_e32 v141, v0, v138
	v_fma_f32 v138, -v0, v138, v0
	v_cndmask_b32_e64 v0, v138, v141, s[0:1]
	v_mul_f32_e32 v233, v134, v0
	v_fmamk_f32 v0, v194, 0x3f07dc22, v241
	v_fmaak_f32 v0, v194, v0, 0x3f35f0e3
	v_fmaak_f32 v0, v194, v0, 0xbe11a98e
	v_mov_b32_e32 v227, v2
	v_mov_b32_e32 v235, v3
	v_mul_f32_e32 v134, 0xbf38aa3b, v139
	v_fmaak_f32 v0, v194, v0, 0x3e027906
	v_pk_mul_f32 v[138:139], v[172:173], v[226:227]
	v_pk_mul_f32 v[2:3], v[108:109], v[234:235]
	v_mul_f32_e32 v0, v194, v0
	v_pk_fma_f32 v[194:195], v[104:105], v[218:219], v[112:113]
	v_mov_b32_e32 v216, v139
	v_mov_b32_e32 v217, v3
	v_exp_f32_e32 v134, v134
	v_pk_add_f32 v[194:195], v[216:217], v[194:195]
	v_mov_b32_e32 v139, v2
	v_pk_add_f32 v[2:3], v[138:139], v[194:195]
	v_mul_f32_e32 v0, v134, v0
	v_fma_f32 v138, |v2|, s84, 1.0
	v_rcp_f32_e32 v138, v138
	v_mul_f32_e32 v134, v1, v0
	v_fma_f32 v0, -v1, v0, v1
	v_cmp_gt_f32_e64 s[0:1], 0, v1
	v_lshlrev_b32_e32 v236, 16, v140
	v_and_b32_e32 v140, 0xffff0000, v140
	v_cndmask_b32_e64 v0, v0, v134, s[0:1]
	v_mul_f32_e32 v194, v135, v0
	v_fmamk_f32 v0, v138, 0x3f07dc22, v241
	v_fmaak_f32 v134, v138, v0, 0x3f35f0e3
	v_pk_mul_f32 v[0:1], v[2:3], v[2:3]
	v_fmaak_f32 v134, v138, v134, 0xbe11a98e
	v_mul_f32_e32 v0, 0xbf38aa3b, v0
	v_exp_f32_e32 v0, v0
	v_fmaak_f32 v134, v138, v134, 0x3e027906
	v_fma_f32 v135, |v3|, s84, 1.0
	v_mul_f32_e32 v134, v138, v134
	v_rcp_f32_e32 v135, v135
	v_mul_f32_e32 v0, v0, v134
	v_mul_f32_e32 v134, v2, v0
	v_fma_f32 v0, -v2, v0, v2
	v_cmp_gt_f32_e64 s[0:1], 0, v2
	v_mul_f32_e32 v1, 0xbf38aa3b, v1
	v_exp_f32_e32 v1, v1
	v_cndmask_b32_e64 v0, v0, v134, s[0:1]
	v_mul_f32_e32 v136, v136, v0
	v_fmamk_f32 v0, v135, 0x3f07dc22, v241
	v_fmaak_f32 v0, v135, v0, 0x3f35f0e3
	v_fmaak_f32 v0, v135, v0, 0xbe11a98e
	v_fmaak_f32 v0, v135, v0, 0x3e027906
	v_mul_f32_e32 v0, v135, v0
	v_mul_f32_e32 v0, v1, v0
	v_mov_b32_e32 v237, v4
	v_mov_b32_e32 v141, v5
	v_mul_f32_e32 v2, v3, v0
	v_fma_f32 v195, -v3, v0, v3
	v_pk_mul_f32 v[0:1], v[212:213], v[236:237]
	v_pk_mul_f32 v[4:5], v[94:95], v[140:141]
	v_pk_fma_f32 v[134:135], v[90:91], v[220:221], v[98:99]
	v_mov_b32_e32 v138, v1
	v_mov_b32_e32 v139, v5
	v_pk_add_f32 v[134:135], v[138:139], v[134:135]
	v_mov_b32_e32 v1, v4
	v_pk_add_f32 v[0:1], v[0:1], v[134:135]
	v_cmp_gt_f32_e64 s[0:1], 0, v3
	v_fma_f32 v4, |v0|, s84, 1.0
	v_rcp_f32_e32 v4, v4
	v_cndmask_b32_e64 v2, v195, v2, s[0:1]
	v_mul_f32_e32 v137, v137, v2
	v_cmp_gt_f32_e64 s[0:1], 0, v0
	v_fmamk_f32 v2, v4, 0x3f07dc22, v241
	v_fmaak_f32 v5, v4, v2, 0x3f35f0e3
	v_pk_mul_f32 v[2:3], v[0:1], v[0:1]
	v_fmaak_f32 v5, v4, v5, 0xbe11a98e
	v_mul_f32_e32 v2, 0xbf38aa3b, v2
	v_exp_f32_e32 v2, v2
	v_fmaak_f32 v5, v4, v5, 0x3e027906
	v_mul_f32_e32 v4, v4, v5
	v_fma_f32 v5, |v1|, s84, 1.0
	v_rcp_f32_e32 v5, v5
	v_mul_f32_e32 v2, v2, v4
	v_mul_f32_e32 v4, v0, v2
	v_fma_f32 v2, -v0, v2, v0
	v_cndmask_b32_e64 v0, v2, v4, s[0:1]
	v_mul_f32_e32 v130, v130, v0
	v_fmamk_f32 v0, v5, 0x3f07dc22, v241
	v_mul_f32_e32 v2, 0xbf38aa3b, v3
	v_fmaak_f32 v0, v5, v0, 0x3f35f0e3
	v_exp_f32_e32 v2, v2
	v_fmaak_f32 v0, v5, v0, 0xbe11a98e
	v_fmaak_f32 v0, v5, v0, 0x3e027906
	v_mul_f32_e32 v0, v5, v0
	v_mov_b32_e32 v249, v6
	v_mov_b32_e32 v251, v7
	v_mul_f32_e32 v0, v2, v0
	v_pk_mul_f32 v[2:3], v[214:215], v[248:249]
	v_pk_mul_f32 v[4:5], v[96:97], v[250:251]
	v_pk_fma_f32 v[6:7], v[92:93], v[222:223], v[100:101]
	v_mov_b32_e32 v134, v3
	v_mov_b32_e32 v135, v5
	v_pk_add_f32 v[6:7], v[134:135], v[6:7]
	v_mov_b32_e32 v3, v4
	v_pk_add_f32 v[2:3], v[2:3], v[6:7]
	v_mul_f32_e32 v138, v1, v0
	v_fma_f32 v4, |v2|, s84, 1.0
	v_rcp_f32_e32 v4, v4
	v_fma_f32 v0, -v1, v0, v1
	v_cmp_gt_f32_e64 s[0:1], 0, v1
	s_cmp_lg_u32 s70, 32
	s_cselect_b64 s[8:9], -1, 0
	v_cndmask_b32_e64 v0, v0, v138, s[0:1]
	v_mul_f32_e32 v5, v131, v0
	v_fmamk_f32 v0, v4, 0x3f07dc22, v241
	v_fmaak_f32 v6, v4, v0, 0x3f35f0e3
	v_pk_mul_f32 v[0:1], v[2:3], v[2:3]
	v_fmaak_f32 v6, v4, v6, 0xbe11a98e
	v_mul_f32_e32 v0, 0xbf38aa3b, v0
	v_exp_f32_e32 v0, v0
	v_fmaak_f32 v6, v4, v6, 0x3e027906
	v_mul_f32_e32 v4, v4, v6
	v_fma_f32 v6, |v3|, s84, 1.0
	v_rcp_f32_e32 v6, v6
	v_mul_f32_e32 v0, v0, v4
	v_mul_f32_e32 v4, v2, v0
	v_fma_f32 v0, -v2, v0, v2
	v_cmp_gt_f32_e64 s[0:1], 0, v2
	v_mul_f32_e32 v1, 0xbf38aa3b, v1
	v_exp_f32_e32 v1, v1
	v_cndmask_b32_e64 v0, v0, v4, s[0:1]
	v_mul_f32_e32 v4, v132, v0
	v_fmamk_f32 v0, v6, 0x3f07dc22, v241
	v_fmaak_f32 v0, v6, v0, 0x3f35f0e3
	v_fmaak_f32 v0, v6, v0, 0xbe11a98e
	v_fmaak_f32 v0, v6, v0, 0x3e027906
	v_mul_f32_e32 v0, v6, v0
	v_mul_f32_e32 v0, v1, v0
	v_mul_f32_e32 v1, v3, v0
	v_fma_f32 v0, -v3, v0, v3
	v_cmp_gt_f32_e64 s[0:1], 0, v3
	v_cvt_pk_bf16_f32 v2, v130, v5
	s_cmp_eq_u32 s70, 32
	s_nop 0
	v_cndmask_b32_e64 v0, v0, v1, s[0:1]
	v_mul_f32_e32 v3, v133, v0
	v_cvt_pk_bf16_f32 v3, v4, v3
	v_lshl_add_u64 v[4:5], s[80:81], 0, v[224:225]
	v_add_u32_e32 v224, 0x80, v232
	s_movk_i32 s0, 0x1f80
	v_lshl_add_u64 v[134:135], v[184:185], 1, v[4:5]
	v_cmp_gt_i32_e64 s[70:71], s0, v232
	v_max_i32_e32 v225, 1, v224
	v_max_i32_e32 v226, 2, v224
	v_cvt_pk_bf16_f32 v0, v233, v194
	v_cvt_pk_bf16_f32 v1, v136, v137
	global_store_dwordx4 v[134:135], v[0:3], off sc1
	s_cbranch_scc1 .LBB0_1525
;     static __device__ __forceinline__ void unpack8(const u32x4 q, float (&x)[8]) { x[0] = bflo(q.x); x[1] = bfhi(q.x); x[2] = bflo(q.y); x[3] = bfhi(q.y); x[4] = bflo(q.z); x[5] = bfhi(q.z); x[6] = bflo(q.w); x[7] = bfhi(q.w); }
;     __device__ __forceinline__ void operator()(EPI_ARGS) const {
;     ...
;                     for (int t = 0; t < 1; ++t) { const int row = row0 + ai * 128 + (mp + t) * 16; const int r1 = row > 0 ? row - 1 : 0, r2 = row > 1 ? row - 2 : 0;
;                         q2[t] = *(const u32x4*)(up + (size_t)row * DFF + col); q1[t] = *(const u32x4*)(up + (size_t)r1 * DFF + col); q0[t] = *(const u32x4*)(up + (size_t)r2 * DFF + col); }
;                     __builtin_amdgcn_sched_barrier(0);
; #pragma unroll
;                     for (int t = 0; t < 1; ++t) { const int m = mp + t, row = row0 + ai * 128 + m * 16;
;                         const int i = row < TP ? row : ((row - TP) & 15); const int sidx = row < TP ? 0 : ((row - TP) >> 4);
;                         float x0[8], x1[8], x2[8]; unpack8(q0[t], x0); unpack8(q1[t], x1); unpack8(q2[t], x2);
;                         if (i < 2) {
;                             const bool smp = row >= TP; const float* p0 = cs + ((size_t)sidx * 2 + i) * DFF + col; const float* p1 = cs + ((size_t)sidx * 2 + 1) * DFF + col;
; #pragma unroll
;                             for (int e = 0; e < 8; ++e) { x0[e] = smp ? p0[e] : 0.f; if (i == 0) x1[e] = smp ? p1[e] : 0.f; } }
	v_add_u32_e32 v4, -1, v225
	v_add_u32_e32 v136, -2, v226
	v_mov_b64_e32 v[0:1], s[30:31]
	v_mad_i64_i32 v[2:3], s[0:1], v224, s76, v[0:1]
	v_mad_u64_u32 v[4:5], s[0:1], v4, s76, v[0:1]
	v_mad_u64_u32 v[0:1], s[0:1], v136, s76, v[0:1]
	v_lshl_add_u64 v[2:3], v[2:3], 0, v[186:187]
	v_lshl_add_u64 v[4:5], v[4:5], 0, v[186:187]
	v_lshl_add_u64 v[0:1], v[0:1], 0, v[186:187]
	global_load_dwordx4 v[130:133], v[2:3], off
	s_nop 0
	global_load_dwordx4 v[4:7], v[4:5], off
	s_nop 0
	global_load_dwordx4 v[0:3], v[0:1], off
	v_cndmask_b32_e64 v222, v228, v224, s[70:71]
	s_waitcnt vmcnt(0)
	v_lshlrev_b32_e32 v136, 16, v0
	v_and_b32_e32 v137, 0xffff0000, v0
	v_lshlrev_b32_e32 v138, 16, v1
	v_and_b32_e32 v139, 0xffff0000, v1
	v_lshlrev_b32_e32 v140, 16, v2
	v_and_b32_e32 v141, 0xffff0000, v2
	v_lshlrev_b32_e32 v216, 16, v3
	v_and_b32_e32 v217, 0xffff0000, v3
	v_lshlrev_b32_e32 v0, 16, v4
	v_and_b32_e32 v1, 0xffff0000, v4
	v_lshlrev_b32_e32 v2, 16, v5
	v_and_b32_e32 v3, 0xffff0000, v5
	v_lshlrev_b32_e32 v4, 16, v6
	v_and_b32_e32 v5, 0xffff0000, v6
	v_lshlrev_b32_e32 v6, 16, v7
	v_and_b32_e32 v7, 0xffff0000, v7
	v_cmp_gt_i32_e64 s[0:1], 2, v222
	s_and_saveexec_b64 s[14:15], s[0:1]
	s_cbranch_execz .LBB0_1374
	s_add_i32 s18, s5, 0xffffe080
	s_ashr_i32 s18, s18, 4
	v_mov_b32_e32 v136, s18
	v_cndmask_b32_e64 v138, v136, 0, s[70:71]
	v_ashrrev_i32_e32 v139, 31, v138
	v_ashrrev_i32_e32 v223, 31, v222
	v_lshl_add_u64 v[136:137], v[138:139], 1, v[222:223]
	v_mov_b64_e32 v[140:141], s[68:69]
	v_mad_u64_u32 v[140:141], s[18:19], v136, s13, v[140:141]
	s_movk_i32 s0, 0x1f7f
	v_mad_i32_i24 v141, v137, s13, v141
	v_cmp_lt_i32_e64 s[0:1], s0, v232
	v_lshl_add_u64 v[220:221], v[184:185], 2, v[140:141]
	v_mov_b32_e32 v136, 0
	s_and_saveexec_b64 s[18:19], s[0:1]
	s_cbranch_execz .LBB0_1327
	global_load_dword v136, v[220:221], off

; __device__ __forceinline__ unsigned pk2(float lo, float hi) { unsigned r; asm("v_cvt_pk_bf16_f32 %0, %1, %2" : "=v"(r) : "v"(lo), "v"(hi)); return r; }
; __device__ __forceinline__ float gelu_f(float v) {
;     const float av = fabsf(v), d = av * 0.2316418882f + 1.0f;
;     const float t = __builtin_amdgcn_rcpf(d);
;     float q = t * 0.5307027145f + (-0.7265760135f); q = q * t + 0.7107068705f; q = q * t + (-0.142248368f); q = q * t + 0.127414796f; q = q * t;
;     const float e = __builtin_amdgcn_exp2f(v * v * (-0.72134752044f));
;     const float m = v * (q * e);
;     return v < 0.f ? m : v - m;
;     __device__ __forceinline__ void operator()(EPI_ARGS) const {
;     ...
;                     for (int t = 0; t < 1; ++t) { const int row = row0 + ai * 128 + (mp + t) * 16; const int r1 = row > 0 ? row - 1 : 0, r2 = row > 1 ? row - 2 : 0;
;                         q2[t] = *(const u32x4*)(up + (size_t)row * DFF + col); q1[t] = *(const u32x4*)(up + (size_t)r1 * DFF + col); q0[t] = *(const u32x4*)(up + (size_t)r2 * DFF + col); }
;                     __builtin_amdgcn_sched_barrier(0);
; #pragma unroll
;                     for (int t = 0; t < 1; ++t) { const int m = mp + t, row = row0 + ai * 128 + m * 16;
;                         const int i = row < TP ? row : ((row - TP) & 15); const int sidx = row < TP ? 0 : ((row - TP) >> 4);
;                         float x0[8], x1[8], x2[8]; unpack8(q0[t], x0); unpack8(q1[t], x1); unpack8(q2[t], x2);
;                         if (i < 2) {
;                             const bool smp = row >= TP; const float* p0 = cs + ((size_t)sidx * 2 + i) * DFF + col; const float* p1 = cs + ((size_t)sidx * 2 + 1) * DFF + col;
; #pragma unroll
;                             for (int e = 0; e < 8; ++e) { x0[e] = smp ? p0[e] : 0.f; if (i == 0) x1[e] = smp ? p1[e] : 0.f; } }
;                         float r[8];
; #pragma unroll
;                         for (int e = 0; e < 8; ++e) { const float cv = bb[e] + x0[e] * w0[e] + x1[e] * w1[e] + x2[e] * w2[e]; r[e] = gelu_f(cv) * acc[ai][bj][m][e >> 2][e & 3]; }
;                         u32x4 w; w.x = pk2(r[0], r[1]); w.y = pk2(r[2], r[3]); w.z = pk2(r[4], r[5]); w.w = pk2(r[6], r[7]);
;                         *(u32x4*)(act + (size_t)row * DFF + col) = w; } } } }
.LBB0_1374:
	s_or_b64 exec, exec, s[14:15]
	v_lshlrev_b32_e32 v194, 16, v130
	v_and_b32_e32 v130, 0xffff0000, v130
	v_lshlrev_b32_e32 v220, 16, v131
	v_and_b32_e32 v222, 0xffff0000, v131
	s_waitcnt vmcnt(0)
	v_add_u32_e32 v240, 144, v232
	v_mov_b64_e32 v[238:239], s[30:31]
	v_mad_i64_i32 v[238:239], s[0:1], v240, s76, v[238:239]
	v_lshl_add_u64 v[238:239], v[238:239], 0, v[186:187]
	global_load_dwordx4 v[196:199], v[238:239], off
	v_add_u32_e32 v240, -1, v240
	v_mov_b64_e32 v[246:247], s[30:31]
	v_mad_i64_i32 v[246:247], s[0:1], v240, s76, v[246:247]
	v_lshl_add_u64 v[246:247], v[246:247], 0, v[186:187]
	global_load_dwordx4 v[200:203], v[246:247], off
	v_add_u32_e32 v240, -1, v240
	v_mov_b64_e32 v[238:239], s[30:31]
	v_mad_i64_i32 v[238:239], s[0:1], v240, s76, v[238:239]
	v_lshl_add_u64 v[238:239], v[238:239], 0, v[186:187]
	global_load_dwordx4 v[242:245], v[238:239], off
	v_mov_b32_e32 v195, v0
	v_mov_b32_e32 v131, v1
	v_pk_mul_f32 v[194:195], v[210:211], v[194:195]
	v_pk_mul_f32 v[0:1], v[106:107], v[130:131]
	v_pk_fma_f32 v[130:131], v[102:103], v[136:137], v[110:111]
	v_mov_b32_e32 v136, v195
	v_mov_b32_e32 v137, v1
	v_pk_add_f32 v[130:131], v[136:137], v[130:131]
	v_mov_b32_e32 v195, v0
	v_pk_add_f32 v[0:1], v[194:195], v[130:131]
	v_lshlrev_b32_e32 v234, 16, v132
	v_fma_f32 v130, |v0|, s84, 1.0
	v_rcp_f32_e32 v131, v130
	v_pk_mul_f32 v[194:195], v[0:1], v[0:1]
	v_and_b32_e32 v130, 0xffff0000, v132
	v_lshlrev_b32_e32 v132, 16, v133
	v_and_b32_e32 v136, 0xffff0000, v133
	v_fmamk_f32 v133, v131, 0x3f07dc22, v241
	v_mul_f32_e32 v137, 0xbf38aa3b, v194
	v_fmaak_f32 v133, v131, v133, 0x3f35f0e3
	v_exp_f32_e32 v137, v137
	v_fmaak_f32 v133, v131, v133, 0xbe11a98e
	v_fmaak_f32 v133, v131, v133, 0x3e027906
	v_mul_f32_e32 v131, v131, v133
	v_mul_f32_e32 v131, v137, v131
	v_fma_f32 v137, |v1|, s84, 1.0
	v_mad_i64_i32 v[218:219], s[0:1], v224, s76, 0
	v_rcp_f32_e32 v137, v137
	v_mul_f32_e32 v133, v0, v131
	v_fma_f32 v131, -v0, v131, v0
	v_cmp_gt_f32_e64 s[0:1], 0, v0
	v_mov_b32_e32 v221, v2
	v_mov_b32_e32 v223, v3
	v_cndmask_b32_e64 v0, v131, v133, s[0:1]
	v_mul_f32_e32 v227, v126, v0
	v_mul_f32_e32 v126, 0xbf38aa3b, v195
	v_pk_mul_f32 v[194:195], v[172:173], v[220:221]
	v_pk_mul_f32 v[2:3], v[108:109], v[222:223]
	v_fmamk_f32 v0, v137, 0x3f07dc22, v241
	v_pk_fma_f32 v[138:139], v[104:105], v[138:139], v[112:113]
	v_mov_b32_e32 v220, v195
	v_mov_b32_e32 v221, v3
	v_fmaak_f32 v0, v137, v0, 0x3f35f0e3
	v_exp_f32_e32 v126, v126
	v_pk_add_f32 v[138:139], v[220:221], v[138:139]
	v_mov_b32_e32 v195, v2
	v_fmaak_f32 v0, v137, v0, 0xbe11a98e
	v_pk_add_f32 v[2:3], v[194:195], v[138:139]
	v_fmaak_f32 v0, v137, v0, 0x3e027906
	v_fma_f32 v131, |v2|, s84, 1.0
	v_mul_f32_e32 v0, v137, v0
	v_rcp_f32_e32 v131, v131
	v_mul_f32_e32 v0, v126, v0
	v_mul_f32_e32 v126, v1, v0
	v_fma_f32 v0, -v1, v0, v1
	v_cmp_gt_f32_e64 s[0:1], 0, v1
	v_mov_b32_e32 v235, v4
	v_mov_b32_e32 v137, v7
	v_cndmask_b32_e64 v0, v0, v126, s[0:1]
	v_mul_f32_e32 v138, v127, v0
	v_fmamk_f32 v0, v131, 0x3f07dc22, v241
	v_fmaak_f32 v126, v131, v0, 0x3f35f0e3
	v_pk_mul_f32 v[0:1], v[2:3], v[2:3]
	v_fmaak_f32 v126, v131, v126, 0xbe11a98e
	v_mul_f32_e32 v0, 0xbf38aa3b, v0
	v_exp_f32_e32 v0, v0
	v_fmaak_f32 v126, v131, v126, 0x3e027906
	v_fma_f32 v127, |v3|, s84, 1.0
	v_mul_f32_e32 v126, v131, v126
	v_rcp_f32_e32 v127, v127
	v_mul_f32_e32 v0, v0, v126
	v_mul_f32_e32 v126, v2, v0
	v_fma_f32 v0, -v2, v0, v2
	v_cmp_gt_f32_e64 s[0:1], 0, v2
	v_mul_f32_e32 v1, 0xbf38aa3b, v1
	v_exp_f32_e32 v1, v1
	v_cndmask_b32_e64 v0, v0, v126, s[0:1]
	v_mul_f32_e32 v128, v128, v0
	v_fmamk_f32 v0, v127, 0x3f07dc22, v241
	v_fmaak_f32 v0, v127, v0, 0x3f35f0e3
	v_fmaak_f32 v0, v127, v0, 0xbe11a98e
	v_fmaak_f32 v0, v127, v0, 0x3e027906
	v_mul_f32_e32 v0, v127, v0
	v_mul_f32_e32 v0, v1, v0
	v_mov_b32_e32 v131, v5
	v_mul_f32_e32 v2, v3, v0
	v_fma_f32 v133, -v3, v0, v3
	v_pk_mul_f32 v[0:1], v[212:213], v[234:235]
	v_pk_mul_f32 v[4:5], v[94:95], v[130:131]
	v_pk_fma_f32 v[126:127], v[90:91], v[140:141], v[98:99]
	v_mov_b32_e32 v130, v1
	v_mov_b32_e32 v131, v5
	v_pk_add_f32 v[126:127], v[130:131], v[126:127]
	v_mov_b32_e32 v1, v4
	v_pk_add_f32 v[0:1], v[0:1], v[126:127]
	v_cmp_gt_f32_e64 s[0:1], 0, v3
	v_fma_f32 v4, |v0|, s84, 1.0
	v_rcp_f32_e32 v4, v4
	v_cndmask_b32_e64 v2, v133, v2, s[0:1]
	v_mul_f32_e32 v129, v129, v2
	v_cmp_gt_f32_e64 s[0:1], 0, v0
	v_fmamk_f32 v2, v4, 0x3f07dc22, v241
	v_fmaak_f32 v5, v4, v2, 0x3f35f0e3
; __device__ __forceinline__ unsigned pk2(float lo, float hi) { unsigned r; asm("v_cvt_pk_bf16_f32 %0, %1, %2" : "=v"(r) : "v"(lo), "v"(hi)); return r; }
;     static __device__ __forceinline__ void unpack8(const u32x4 q, float (&x)[8]) { x[0] = bflo(q.x); x[1] = bfhi(q.x); x[2] = bflo(q.y); x[3] = bfhi(q.y); x[4] = bflo(q.z); x[5] = bfhi(q.z); x[6] = bflo(q.w); x[7] = bfhi(q.w); }
;     __device__ __forceinline__ void operator()(EPI_ARGS) const {
;     ...
;                     for (int t = 0; t < 1; ++t) { const int row = row0 + ai * 128 + (mp + t) * 16; const int r1 = row > 0 ? row - 1 : 0, r2 = row > 1 ? row - 2 : 0;
;                         q2[t] = *(const u32x4*)(up + (size_t)row * DFF + col); q1[t] = *(const u32x4*)(up + (size_t)r1 * DFF + col); q0[t] = *(const u32x4*)(up + (size_t)r2 * DFF + col); }
;                     __builtin_amdgcn_sched_barrier(0);
; #pragma unroll
;                     for (int t = 0; t < 1; ++t) { const int m = mp + t, row = row0 + ai * 128 + m * 16;
;                         const int i = row < TP ? row : ((row - TP) & 15); const int sidx = row < TP ? 0 : ((row - TP) >> 4);
;                         float x0[8], x1[8], x2[8]; unpack8(q0[t], x0); unpack8(q1[t], x1); unpack8(q2[t], x2);
;                         if (i < 2) {
;                             const bool smp = row >= TP; const float* p0 = cs + ((size_t)sidx * 2 + i) * DFF + col; const float* p1 = cs + ((size_t)sidx * 2 + 1) * DFF + col;
; #pragma unroll
;                             for (int e = 0; e < 8; ++e) { x0[e] = smp ? p0[e] : 0.f; if (i == 0) x1[e] = smp ? p1[e] : 0.f; } }
;     ...
;                         for (int e = 0; e < 8; ++e) { const float cv = bb[e] + x0[e] * w0[e] + x1[e] * w1[e] + x2[e] * w2[e]; r[e] = gelu_f(cv) * acc[ai][bj][m][e >> 2][e & 3]; }
;                         u32x4 w; w.x = pk2(r[0], r[1]); w.y = pk2(r[2], r[3]); w.z = pk2(r[4], r[5]); w.w = pk2(r[6], r[7]);
;                         *(u32x4*)(act + (size_t)row * DFF + col) = w; } } } }
	v_pk_mul_f32 v[2:3], v[0:1], v[0:1]
	v_fmaak_f32 v5, v4, v5, 0xbe11a98e
	v_mul_f32_e32 v2, 0xbf38aa3b, v2
	v_exp_f32_e32 v2, v2
	v_fmaak_f32 v5, v4, v5, 0x3e027906
	v_mul_f32_e32 v4, v4, v5
	v_fma_f32 v5, |v1|, s84, 1.0
	v_rcp_f32_e32 v5, v5
	v_mul_f32_e32 v2, v2, v4
	v_mul_f32_e32 v4, v0, v2
	v_fma_f32 v2, -v0, v2, v0
	v_cndmask_b32_e64 v0, v2, v4, s[0:1]
	v_mul_f32_e32 v122, v122, v0
	v_fmamk_f32 v0, v5, 0x3f07dc22, v241
	v_mul_f32_e32 v2, 0xbf38aa3b, v3
	v_fmaak_f32 v0, v5, v0, 0x3f35f0e3
	v_exp_f32_e32 v2, v2
	v_fmaak_f32 v0, v5, v0, 0xbe11a98e
	v_fmaak_f32 v0, v5, v0, 0x3e027906
	v_mul_f32_e32 v0, v5, v0
	v_mov_b32_e32 v133, v6
	v_mul_f32_e32 v0, v2, v0
	v_pk_mul_f32 v[2:3], v[214:215], v[132:133]
	v_pk_mul_f32 v[4:5], v[96:97], v[136:137]
	v_pk_fma_f32 v[6:7], v[92:93], v[216:217], v[100:101]
	v_mov_b32_e32 v126, v3
	v_mov_b32_e32 v127, v5
	v_pk_add_f32 v[6:7], v[126:127], v[6:7]
	v_mov_b32_e32 v3, v4
	v_pk_add_f32 v[2:3], v[2:3], v[6:7]
	v_mul_f32_e32 v130, v1, v0
	v_fma_f32 v4, |v2|, s84, 1.0
	v_rcp_f32_e32 v4, v4
	v_fma_f32 v0, -v1, v0, v1
	v_cmp_gt_f32_e64 s[0:1], 0, v1
	v_add_u32_e32 v216, 0x90, v232
	s_nop 0
	v_cndmask_b32_e64 v0, v0, v130, s[0:1]
	v_mul_f32_e32 v5, v123, v0
	v_fmamk_f32 v0, v4, 0x3f07dc22, v241
	v_fmaak_f32 v6, v4, v0, 0x3f35f0e3
	v_pk_mul_f32 v[0:1], v[2:3], v[2:3]
	v_fmaak_f32 v6, v4, v6, 0xbe11a98e
	v_mul_f32_e32 v0, 0xbf38aa3b, v0
	v_exp_f32_e32 v0, v0
	v_fmaak_f32 v6, v4, v6, 0x3e027906
	v_mul_f32_e32 v4, v4, v6
	v_fma_f32 v6, |v3|, s84, 1.0
	v_rcp_f32_e32 v6, v6
	v_mul_f32_e32 v0, v0, v4
	v_mul_f32_e32 v4, v2, v0
	v_fma_f32 v0, -v2, v0, v2
	v_cmp_gt_f32_e64 s[0:1], 0, v2
	v_mul_f32_e32 v1, 0xbf38aa3b, v1
	v_exp_f32_e32 v1, v1
	v_cndmask_b32_e64 v0, v0, v4, s[0:1]
	v_mul_f32_e32 v4, v124, v0
	v_fmamk_f32 v0, v6, 0x3f07dc22, v241
	v_fmaak_f32 v0, v6, v0, 0x3f35f0e3
	v_fmaak_f32 v0, v6, v0, 0xbe11a98e
	v_fmaak_f32 v0, v6, v0, 0x3e027906
	v_mul_f32_e32 v0, v6, v0
	v_mul_f32_e32 v0, v1, v0
	v_mul_f32_e32 v1, v3, v0
	v_fma_f32 v0, -v3, v0, v3
	v_cmp_gt_f32_e64 s[0:1], 0, v3
	v_cvt_pk_bf16_f32 v2, v122, v5
	s_nop 1
	v_cndmask_b32_e64 v0, v0, v1, s[0:1]
	v_mul_f32_e32 v3, v125, v0
	v_cvt_pk_bf16_f32 v3, v4, v3
	v_lshl_add_u64 v[4:5], s[80:81], 0, v[218:219]
	v_cvt_pk_bf16_f32 v0, v227, v138
	v_lshl_add_u64 v[4:5], v[4:5], 0, v[186:187]
	v_cvt_pk_bf16_f32 v1, v128, v129
	global_store_dwordx4 v[4:5], v[0:3], off sc1
	s_nop 1
	v_max_i32_e32 v0, 1, v216
	v_add_u32_e32 v4, -1, v0
	v_max_i32_e32 v0, 2, v216
	v_add_u32_e32 v126, -2, v0
	v_mov_b64_e32 v[0:1], s[30:31]
	v_mad_i64_i32 v[2:3], s[0:1], v216, s76, v[0:1]
	v_mad_u64_u32 v[4:5], s[0:1], v4, s76, v[0:1]
	v_mad_u64_u32 v[0:1], s[0:1], v126, s76, v[0:1]
	v_lshl_add_u64 v[2:3], v[2:3], 0, v[186:187]
	v_lshl_add_u64 v[4:5], v[4:5], 0, v[186:187]
	v_lshl_add_u64 v[0:1], v[0:1], 0, v[186:187]
	s_movk_i32 s0, 0x1f70
	v_cmp_gt_i32_e64 s[70:71], s0, v232
	s_waitcnt vmcnt(1)
	v_mov_b64_e32 v[122:123], v[196:197]
	v_mov_b64_e32 v[124:125], v[198:199]
	v_mov_b64_e32 v[4:5], v[200:201]
	v_mov_b64_e32 v[6:7], v[202:203]
	v_mov_b64_e32 v[0:1], v[242:243]
	v_mov_b64_e32 v[2:3], v[244:245]
	v_lshlrev_b32_e32 v126, 16, v0
	v_and_b32_e32 v127, 0xffff0000, v0
	v_cndmask_b32_e64 v140, v228, v216, s[70:71]
	v_lshlrev_b32_e32 v128, 16, v1
	v_and_b32_e32 v129, 0xffff0000, v1
	v_lshlrev_b32_e32 v130, 16, v2
	v_and_b32_e32 v131, 0xffff0000, v2
	v_lshlrev_b32_e32 v132, 16, v3
	v_and_b32_e32 v133, 0xffff0000, v3
	v_lshlrev_b32_e32 v0, 16, v4
	v_and_b32_e32 v1, 0xffff0000, v4
	v_lshlrev_b32_e32 v2, 16, v5
	v_and_b32_e32 v3, 0xffff0000, v5
	v_lshlrev_b32_e32 v4, 16, v6
	v_and_b32_e32 v5, 0xffff0000, v6
	v_lshlrev_b32_e32 v6, 16, v7
	v_and_b32_e32 v7, 0xffff0000, v7
	v_cmp_gt_i32_e64 s[0:1], 2, v140
	s_and_saveexec_b64 s[14:15], s[0:1]
	s_cbranch_execz .LBB0_1424
	s_add_i32 s18, s5, 0xffffe090
	s_ashr_i32 s18, s18, 4
	v_mov_b32_e32 v126, s18
	v_cndmask_b32_e64 v128, v126, 0, s[70:71]
	v_ashrrev_i32_e32 v129, 31, v128
	v_ashrrev_i32_e32 v141, 31, v140
	v_lshl_add_u64 v[126:127], v[128:129], 1, v[140:141]
	v_mov_b64_e32 v[130:131], s[68:69]
	v_mad_u64_u32 v[130:131], s[18:19], v126, s13, v[130:131]
	s_movk_i32 s0, 0x1f6f
	v_mad_i32_i24 v131, v127, s13, v131
	v_cmp_lt_i32_e64 s[0:1], s0, v232
	v_lshl_add_u64 v[138:139], v[184:185], 2, v[130:131]
	v_mov_b32_e32 v126, 0
	s_and_saveexec_b64 s[18:19], s[0:1]
	s_cbranch_execz .LBB0_1377
	global_load_dword v126, v[138:139], off

; __device__ __forceinline__ unsigned pk2(float lo, float hi) { unsigned r; asm("v_cvt_pk_bf16_f32 %0, %1, %2" : "=v"(r) : "v"(lo), "v"(hi)); return r; }
; __device__ __forceinline__ float gelu_f(float v) {
;     const float av = fabsf(v), d = av * 0.2316418882f + 1.0f;
;     const float t = __builtin_amdgcn_rcpf(d);
;     float q = t * 0.5307027145f + (-0.7265760135f); q = q * t + 0.7107068705f; q = q * t + (-0.142248368f); q = q * t + 0.127414796f; q = q * t;
;     const float e = __builtin_amdgcn_exp2f(v * v * (-0.72134752044f));
;     const float m = v * (q * e);
;     return v < 0.f ? m : v - m;
;     __device__ __forceinline__ void operator()(EPI_ARGS) const {
;     ...
;                     for (int t = 0; t < 1; ++t) { const int row = row0 + ai * 128 + (mp + t) * 16; const int r1 = row > 0 ? row - 1 : 0, r2 = row > 1 ? row - 2 : 0;
;                         q2[t] = *(const u32x4*)(up + (size_t)row * DFF + col); q1[t] = *(const u32x4*)(up + (size_t)r1 * DFF + col); q0[t] = *(const u32x4*)(up + (size_t)r2 * DFF + col); }
;                     __builtin_amdgcn_sched_barrier(0);
; #pragma unroll
;                     for (int t = 0; t < 1; ++t) { const int m = mp + t, row = row0 + ai * 128 + m * 16;
;                         const int i = row < TP ? row : ((row - TP) & 15); const int sidx = row < TP ? 0 : ((row - TP) >> 4);
;                         float x0[8], x1[8], x2[8]; unpack8(q0[t], x0); unpack8(q1[t], x1); unpack8(q2[t], x2);
;                         if (i < 2) {
;                             const bool smp = row >= TP; const float* p0 = cs + ((size_t)sidx * 2 + i) * DFF + col; const float* p1 = cs + ((size_t)sidx * 2 + 1) * DFF + col;
; #pragma unroll
;                             for (int e = 0; e < 8; ++e) { x0[e] = smp ? p0[e] : 0.f; if (i == 0) x1[e] = smp ? p1[e] : 0.f; } }
;                         float r[8];
; #pragma unroll
;                         for (int e = 0; e < 8; ++e) { const float cv = bb[e] + x0[e] * w0[e] + x1[e] * w1[e] + x2[e] * w2[e]; r[e] = gelu_f(cv) * acc[ai][bj][m][e >> 2][e & 3]; }
;                         u32x4 w; w.x = pk2(r[0], r[1]); w.y = pk2(r[2], r[3]); w.z = pk2(r[4], r[5]); w.w = pk2(r[6], r[7]);
;                         *(u32x4*)(act + (size_t)row * DFF + col) = w; } } } }
.LBB0_1424:
	s_or_b64 exec, exec, s[14:15]
	v_lshlrev_b32_e32 v138, 16, v122
	v_and_b32_e32 v122, 0xffff0000, v122
	v_lshlrev_b32_e32 v140, 16, v123
	v_and_b32_e32 v194, 0xffff0000, v123
	s_waitcnt vmcnt(1)
	v_add_u32_e32 v240, 160, v232
	v_mov_b64_e32 v[238:239], s[30:31]
	v_mad_i64_i32 v[238:239], s[0:1], v240, s76, v[238:239]
	v_lshl_add_u64 v[238:239], v[238:239], 0, v[186:187]
	global_load_dwordx4 v[196:199], v[238:239], off
	v_add_u32_e32 v240, -1, v240
	v_mov_b64_e32 v[246:247], s[30:31]
	v_mad_i64_i32 v[246:247], s[0:1], v240, s76, v[246:247]
	v_lshl_add_u64 v[246:247], v[246:247], 0, v[186:187]
	global_load_dwordx4 v[200:203], v[246:247], off
	v_add_u32_e32 v240, -1, v240
	v_mov_b64_e32 v[238:239], s[30:31]
	v_mad_i64_i32 v[238:239], s[0:1], v240, s76, v[238:239]
	v_lshl_add_u64 v[238:239], v[238:239], 0, v[186:187]
	global_load_dwordx4 v[242:245], v[238:239], off
	v_mov_b32_e32 v139, v0
	v_mov_b32_e32 v123, v1
	v_pk_mul_f32 v[138:139], v[210:211], v[138:139]
	v_pk_mul_f32 v[0:1], v[106:107], v[122:123]
	v_pk_fma_f32 v[122:123], v[102:103], v[126:127], v[110:111]
	v_mov_b32_e32 v126, v139
	v_mov_b32_e32 v127, v1
	v_pk_add_f32 v[122:123], v[126:127], v[122:123]
	v_mov_b32_e32 v139, v0
	v_pk_add_f32 v[0:1], v[138:139], v[122:123]
	v_mad_i64_i32 v[136:137], s[0:1], v216, s76, 0
	v_fma_f32 v122, |v0|, s84, 1.0
	v_rcp_f32_e32 v123, v122
	v_pk_mul_f32 v[138:139], v[0:1], v[0:1]
	v_lshlrev_b32_e32 v216, 16, v124
	v_and_b32_e32 v122, 0xffff0000, v124
	v_lshlrev_b32_e32 v124, 16, v125
	v_and_b32_e32 v126, 0xffff0000, v125
	v_fmamk_f32 v125, v123, 0x3f07dc22, v241
	v_mul_f32_e32 v127, 0xbf38aa3b, v138
	v_fmaak_f32 v125, v123, v125, 0x3f35f0e3
	v_exp_f32_e32 v127, v127
	v_fmaak_f32 v125, v123, v125, 0xbe11a98e
	v_fmaak_f32 v125, v123, v125, 0x3e027906
	v_mul_f32_e32 v123, v123, v125
	v_mul_f32_e32 v123, v127, v123
	v_fma_f32 v127, |v1|, s84, 1.0
	v_rcp_f32_e32 v127, v127
	v_mul_f32_e32 v125, v0, v123
	v_fma_f32 v123, -v0, v123, v0
	v_cmp_gt_f32_e64 s[0:1], 0, v0
	v_mov_b32_e32 v141, v2
	v_mov_b32_e32 v195, v3
	v_cndmask_b32_e64 v0, v123, v125, s[0:1]
	v_mul_f32_e32 v218, v118, v0
	v_mul_f32_e32 v118, 0xbf38aa3b, v139
	v_pk_mul_f32 v[138:139], v[172:173], v[140:141]
	v_pk_mul_f32 v[2:3], v[108:109], v[194:195]
	v_fmamk_f32 v0, v127, 0x3f07dc22, v241
	v_pk_fma_f32 v[128:129], v[104:105], v[128:129], v[112:113]
	v_mov_b32_e32 v140, v139
	v_mov_b32_e32 v141, v3
	v_fmaak_f32 v0, v127, v0, 0x3f35f0e3
	v_exp_f32_e32 v118, v118
	v_pk_add_f32 v[128:129], v[140:141], v[128:129]
	v_mov_b32_e32 v139, v2
	v_fmaak_f32 v0, v127, v0, 0xbe11a98e
	v_pk_add_f32 v[2:3], v[138:139], v[128:129]
	v_fmaak_f32 v0, v127, v0, 0x3e027906
	v_fma_f32 v123, |v2|, s84, 1.0
	v_mul_f32_e32 v0, v127, v0
	v_rcp_f32_e32 v123, v123
	v_mul_f32_e32 v0, v118, v0
	v_mul_f32_e32 v118, v1, v0
	v_fma_f32 v0, -v1, v0, v1
	v_cmp_gt_f32_e64 s[0:1], 0, v1
	v_mov_b32_e32 v217, v4
	v_mov_b32_e32 v127, v7
	v_cndmask_b32_e64 v0, v0, v118, s[0:1]
	v_mul_f32_e32 v128, v119, v0
	v_fmamk_f32 v0, v123, 0x3f07dc22, v241
	v_fmaak_f32 v118, v123, v0, 0x3f35f0e3
	v_pk_mul_f32 v[0:1], v[2:3], v[2:3]
	v_fmaak_f32 v118, v123, v118, 0xbe11a98e
	v_mul_f32_e32 v0, 0xbf38aa3b, v0
	v_exp_f32_e32 v0, v0
	v_fmaak_f32 v118, v123, v118, 0x3e027906
	v_fma_f32 v119, |v3|, s84, 1.0
	v_mul_f32_e32 v118, v123, v118
	v_rcp_f32_e32 v119, v119
	v_mul_f32_e32 v0, v0, v118
	v_mul_f32_e32 v118, v2, v0
	v_fma_f32 v0, -v2, v0, v2
	v_cmp_gt_f32_e64 s[0:1], 0, v2
	v_mul_f32_e32 v1, 0xbf38aa3b, v1
	v_exp_f32_e32 v1, v1
	v_cndmask_b32_e64 v0, v0, v118, s[0:1]
	v_mul_f32_e32 v120, v120, v0
	v_fmamk_f32 v0, v119, 0x3f07dc22, v241
	v_fmaak_f32 v0, v119, v0, 0x3f35f0e3
	v_fmaak_f32 v0, v119, v0, 0xbe11a98e
	v_fmaak_f32 v0, v119, v0, 0x3e027906
	v_mul_f32_e32 v0, v119, v0
	v_mul_f32_e32 v0, v1, v0
	v_mov_b32_e32 v123, v5
	v_mul_f32_e32 v2, v3, v0
	v_fma_f32 v125, -v3, v0, v3
	v_pk_mul_f32 v[0:1], v[212:213], v[216:217]
	v_pk_mul_f32 v[4:5], v[94:95], v[122:123]
	v_pk_fma_f32 v[118:119], v[90:91], v[130:131], v[98:99]
	v_mov_b32_e32 v122, v1
	v_mov_b32_e32 v123, v5
	v_pk_add_f32 v[118:119], v[122:123], v[118:119]
	v_mov_b32_e32 v1, v4
	v_pk_add_f32 v[0:1], v[0:1], v[118:119]
	v_cmp_gt_f32_e64 s[0:1], 0, v3
	v_fma_f32 v4, |v0|, s84, 1.0
	v_rcp_f32_e32 v4, v4
	v_cndmask_b32_e64 v2, v125, v2, s[0:1]
	v_mul_f32_e32 v121, v121, v2
	v_cmp_gt_f32_e64 s[0:1], 0, v0
	v_fmamk_f32 v2, v4, 0x3f07dc22, v241
	v_fmaak_f32 v5, v4, v2, 0x3f35f0e3
; __device__ __forceinline__ unsigned pk2(float lo, float hi) { unsigned r; asm("v_cvt_pk_bf16_f32 %0, %1, %2" : "=v"(r) : "v"(lo), "v"(hi)); return r; }
;     static __device__ __forceinline__ void unpack8(const u32x4 q, float (&x)[8]) { x[0] = bflo(q.x); x[1] = bfhi(q.x); x[2] = bflo(q.y); x[3] = bfhi(q.y); x[4] = bflo(q.z); x[5] = bfhi(q.z); x[6] = bflo(q.w); x[7] = bfhi(q.w); }
;     __device__ __forceinline__ void operator()(EPI_ARGS) const {
;     ...
;                     for (int t = 0; t < 1; ++t) { const int row = row0 + ai * 128 + (mp + t) * 16; const int r1 = row > 0 ? row - 1 : 0, r2 = row > 1 ? row - 2 : 0;
;                         q2[t] = *(const u32x4*)(up + (size_t)row * DFF + col); q1[t] = *(const u32x4*)(up + (size_t)r1 * DFF + col); q0[t] = *(const u32x4*)(up + (size_t)r2 * DFF + col); }
;                     __builtin_amdgcn_sched_barrier(0);
; #pragma unroll
;                     for (int t = 0; t < 1; ++t) { const int m = mp + t, row = row0 + ai * 128 + m * 16;
;                         const int i = row < TP ? row : ((row - TP) & 15); const int sidx = row < TP ? 0 : ((row - TP) >> 4);
;                         float x0[8], x1[8], x2[8]; unpack8(q0[t], x0); unpack8(q1[t], x1); unpack8(q2[t], x2);
;                         if (i < 2) {
;                             const bool smp = row >= TP; const float* p0 = cs + ((size_t)sidx * 2 + i) * DFF + col; const float* p1 = cs + ((size_t)sidx * 2 + 1) * DFF + col;
; #pragma unroll
;                             for (int e = 0; e < 8; ++e) { x0[e] = smp ? p0[e] : 0.f; if (i == 0) x1[e] = smp ? p1[e] : 0.f; } }
;     ...
;                         for (int e = 0; e < 8; ++e) { const float cv = bb[e] + x0[e] * w0[e] + x1[e] * w1[e] + x2[e] * w2[e]; r[e] = gelu_f(cv) * acc[ai][bj][m][e >> 2][e & 3]; }
;                         u32x4 w; w.x = pk2(r[0], r[1]); w.y = pk2(r[2], r[3]); w.z = pk2(r[4], r[5]); w.w = pk2(r[6], r[7]);
;                         *(u32x4*)(act + (size_t)row * DFF + col) = w; } } } }
	v_pk_mul_f32 v[2:3], v[0:1], v[0:1]
	v_fmaak_f32 v5, v4, v5, 0xbe11a98e
	v_mul_f32_e32 v2, 0xbf38aa3b, v2
	v_exp_f32_e32 v2, v2
	v_fmaak_f32 v5, v4, v5, 0x3e027906
	v_mul_f32_e32 v4, v4, v5
	v_fma_f32 v5, |v1|, s84, 1.0
	v_rcp_f32_e32 v5, v5
	v_mul_f32_e32 v2, v2, v4
	v_mul_f32_e32 v4, v0, v2
	v_fma_f32 v2, -v0, v2, v0
	v_cndmask_b32_e64 v0, v2, v4, s[0:1]
	v_mul_f32_e32 v114, v114, v0
	v_fmamk_f32 v0, v5, 0x3f07dc22, v241
	v_mul_f32_e32 v2, 0xbf38aa3b, v3
	v_fmaak_f32 v0, v5, v0, 0x3f35f0e3
	v_exp_f32_e32 v2, v2
	v_fmaak_f32 v0, v5, v0, 0xbe11a98e
	v_fmaak_f32 v0, v5, v0, 0x3e027906
	v_mul_f32_e32 v0, v5, v0
	v_mov_b32_e32 v125, v6
	v_mul_f32_e32 v0, v2, v0
	v_pk_mul_f32 v[2:3], v[214:215], v[124:125]
	v_pk_mul_f32 v[4:5], v[96:97], v[126:127]
	v_pk_fma_f32 v[6:7], v[92:93], v[132:133], v[100:101]
	v_mov_b32_e32 v118, v3
	v_mov_b32_e32 v119, v5
	v_pk_add_f32 v[6:7], v[118:119], v[6:7]
	v_mov_b32_e32 v3, v4
	v_pk_add_f32 v[2:3], v[2:3], v[6:7]
	v_mul_f32_e32 v122, v1, v0
	v_fma_f32 v4, |v2|, s84, 1.0
	v_rcp_f32_e32 v4, v4
	v_fma_f32 v0, -v1, v0, v1
	v_cmp_gt_f32_e64 s[0:1], 0, v1
	v_add_u32_e32 v132, 0xa0, v232
	s_nop 0
	v_cndmask_b32_e64 v0, v0, v122, s[0:1]
	v_mul_f32_e32 v5, v115, v0
	v_fmamk_f32 v0, v4, 0x3f07dc22, v241
	v_fmaak_f32 v6, v4, v0, 0x3f35f0e3
	v_pk_mul_f32 v[0:1], v[2:3], v[2:3]
	v_fmaak_f32 v6, v4, v6, 0xbe11a98e
	v_mul_f32_e32 v0, 0xbf38aa3b, v0
	v_exp_f32_e32 v0, v0
	v_fmaak_f32 v6, v4, v6, 0x3e027906
	v_mul_f32_e32 v4, v4, v6
	v_fma_f32 v6, |v3|, s84, 1.0
	v_rcp_f32_e32 v6, v6
	v_mul_f32_e32 v0, v0, v4
	v_mul_f32_e32 v4, v2, v0
	v_fma_f32 v0, -v2, v0, v2
	v_cmp_gt_f32_e64 s[0:1], 0, v2
	v_mul_f32_e32 v1, 0xbf38aa3b, v1
	v_exp_f32_e32 v1, v1
	v_cndmask_b32_e64 v0, v0, v4, s[0:1]
	v_mul_f32_e32 v4, v116, v0
	v_fmamk_f32 v0, v6, 0x3f07dc22, v241
	v_fmaak_f32 v0, v6, v0, 0x3f35f0e3
	v_fmaak_f32 v0, v6, v0, 0xbe11a98e
	v_fmaak_f32 v0, v6, v0, 0x3e027906
	v_mul_f32_e32 v0, v6, v0
	v_mul_f32_e32 v0, v1, v0
	v_mul_f32_e32 v1, v3, v0
	v_fma_f32 v0, -v3, v0, v3
	v_cmp_gt_f32_e64 s[0:1], 0, v3
	v_cvt_pk_bf16_f32 v2, v114, v5
	s_nop 1
	v_cndmask_b32_e64 v0, v0, v1, s[0:1]
	v_mul_f32_e32 v3, v117, v0
	v_cvt_pk_bf16_f32 v3, v4, v3
	v_lshl_add_u64 v[4:5], s[80:81], 0, v[136:137]
	v_cvt_pk_bf16_f32 v0, v218, v128
	v_lshl_add_u64 v[4:5], v[4:5], 0, v[186:187]
	v_cvt_pk_bf16_f32 v1, v120, v121
	global_store_dwordx4 v[4:5], v[0:3], off sc1
	s_nop 1
	v_max_i32_e32 v0, 1, v132
	v_add_u32_e32 v4, -1, v0
	v_max_i32_e32 v0, 2, v132
	v_add_u32_e32 v118, -2, v0
	v_mov_b64_e32 v[0:1], s[30:31]
	v_mad_i64_i32 v[2:3], s[0:1], v132, s76, v[0:1]
	v_mad_u64_u32 v[4:5], s[0:1], v4, s76, v[0:1]
	v_mad_u64_u32 v[0:1], s[0:1], v118, s76, v[0:1]
	v_lshl_add_u64 v[2:3], v[2:3], 0, v[186:187]
	v_lshl_add_u64 v[4:5], v[4:5], 0, v[186:187]
	v_lshl_add_u64 v[0:1], v[0:1], 0, v[186:187]
	s_movk_i32 s0, 0x1f60
	v_cmp_gt_i32_e64 s[70:71], s0, v232
	s_waitcnt vmcnt(1)
	v_mov_b64_e32 v[114:115], v[196:197]
	v_mov_b64_e32 v[116:117], v[198:199]
	v_mov_b64_e32 v[4:5], v[200:201]
	v_mov_b64_e32 v[6:7], v[202:203]
	v_mov_b64_e32 v[0:1], v[242:243]
	v_mov_b64_e32 v[2:3], v[244:245]
	v_lshlrev_b32_e32 v118, 16, v0
	v_and_b32_e32 v119, 0xffff0000, v0
	v_cndmask_b32_e64 v130, v228, v132, s[70:71]
	v_lshlrev_b32_e32 v120, 16, v1
	v_and_b32_e32 v121, 0xffff0000, v1
	v_lshlrev_b32_e32 v122, 16, v2
	v_and_b32_e32 v123, 0xffff0000, v2
	v_lshlrev_b32_e32 v124, 16, v3
	v_and_b32_e32 v125, 0xffff0000, v3
	v_lshlrev_b32_e32 v0, 16, v4
	v_and_b32_e32 v1, 0xffff0000, v4
	v_lshlrev_b32_e32 v2, 16, v5
	v_and_b32_e32 v3, 0xffff0000, v5
	v_lshlrev_b32_e32 v4, 16, v6
	v_and_b32_e32 v5, 0xffff0000, v6
	v_lshlrev_b32_e32 v6, 16, v7
	v_and_b32_e32 v7, 0xffff0000, v7
	v_cmp_gt_i32_e64 s[0:1], 2, v130
	s_and_saveexec_b64 s[14:15], s[0:1]
	s_cbranch_execz .LBB0_1474
	s_add_i32 s18, s5, 0xffffe0a0
	s_ashr_i32 s18, s18, 4
	v_mov_b32_e32 v118, s18
	v_cndmask_b32_e64 v120, v118, 0, s[70:71]
	v_ashrrev_i32_e32 v121, 31, v120
	v_ashrrev_i32_e32 v131, 31, v130
	v_lshl_add_u64 v[118:119], v[120:121], 1, v[130:131]
	v_mov_b64_e32 v[122:123], s[68:69]
	v_mad_u64_u32 v[122:123], s[18:19], v118, s13, v[122:123]
	s_movk_i32 s0, 0x1f5f
	v_mad_i32_i24 v123, v119, s13, v123
	v_cmp_lt_i32_e64 s[0:1], s0, v232
	v_lshl_add_u64 v[128:129], v[184:185], 2, v[122:123]
	v_mov_b32_e32 v118, 0
	s_and_saveexec_b64 s[18:19], s[0:1]
	s_cbranch_execz .LBB0_1427
	global_load_dword v118, v[128:129], off

; __device__ __forceinline__ unsigned pk2(float lo, float hi) { unsigned r; asm("v_cvt_pk_bf16_f32 %0, %1, %2" : "=v"(r) : "v"(lo), "v"(hi)); return r; }
; __device__ __forceinline__ float gelu_f(float v) {
;     const float av = fabsf(v), d = av * 0.2316418882f + 1.0f;
;     const float t = __builtin_amdgcn_rcpf(d);
;     float q = t * 0.5307027145f + (-0.7265760135f); q = q * t + 0.7107068705f; q = q * t + (-0.142248368f); q = q * t + 0.127414796f; q = q * t;
;     const float e = __builtin_amdgcn_exp2f(v * v * (-0.72134752044f));
;     const float m = v * (q * e);
;     return v < 0.f ? m : v - m;
;     __device__ __forceinline__ void operator()(EPI_ARGS) const {
;     ...
;                     for (int t = 0; t < 1; ++t) { const int row = row0 + ai * 128 + (mp + t) * 16; const int r1 = row > 0 ? row - 1 : 0, r2 = row > 1 ? row - 2 : 0;
;                         q2[t] = *(const u32x4*)(up + (size_t)row * DFF + col); q1[t] = *(const u32x4*)(up + (size_t)r1 * DFF + col); q0[t] = *(const u32x4*)(up + (size_t)r2 * DFF + col); }
;                     __builtin_amdgcn_sched_barrier(0);
; #pragma unroll
;                     for (int t = 0; t < 1; ++t) { const int m = mp + t, row = row0 + ai * 128 + m * 16;
;                         const int i = row < TP ? row : ((row - TP) & 15); const int sidx = row < TP ? 0 : ((row - TP) >> 4);
;                         float x0[8], x1[8], x2[8]; unpack8(q0[t], x0); unpack8(q1[t], x1); unpack8(q2[t], x2);
;                         if (i < 2) {
;                             const bool smp = row >= TP; const float* p0 = cs + ((size_t)sidx * 2 + i) * DFF + col; const float* p1 = cs + ((size_t)sidx * 2 + 1) * DFF + col;
; #pragma unroll
;                             for (int e = 0; e < 8; ++e) { x0[e] = smp ? p0[e] : 0.f; if (i == 0) x1[e] = smp ? p1[e] : 0.f; } }
;                         float r[8];
; #pragma unroll
;                         for (int e = 0; e < 8; ++e) { const float cv = bb[e] + x0[e] * w0[e] + x1[e] * w1[e] + x2[e] * w2[e]; r[e] = gelu_f(cv) * acc[ai][bj][m][e >> 2][e & 3]; }
;                         u32x4 w; w.x = pk2(r[0], r[1]); w.y = pk2(r[2], r[3]); w.z = pk2(r[4], r[5]); w.w = pk2(r[6], r[7]);
;                         *(u32x4*)(act + (size_t)row * DFF + col) = w; } } } }
.LBB0_1474:
	s_or_b64 exec, exec, s[14:15]
	v_mad_i64_i32 v[126:127], s[0:1], v132, s76, 0
	v_lshlrev_b32_e32 v128, 16, v114
	v_and_b32_e32 v114, 0xffff0000, v114
	v_lshlrev_b32_e32 v130, 16, v115
	v_and_b32_e32 v132, 0xffff0000, v115
	s_waitcnt vmcnt(1)
	v_add_u32_e32 v240, 176, v232
	v_mov_b64_e32 v[238:239], s[30:31]
	v_mad_i64_i32 v[238:239], s[0:1], v240, s76, v[238:239]
	v_lshl_add_u64 v[238:239], v[238:239], 0, v[186:187]
	global_load_dwordx4 v[196:199], v[238:239], off
	v_add_u32_e32 v240, -1, v240
	v_mov_b64_e32 v[246:247], s[30:31]
	v_mad_i64_i32 v[246:247], s[0:1], v240, s76, v[246:247]
	v_lshl_add_u64 v[246:247], v[246:247], 0, v[186:187]
	global_load_dwordx4 v[200:203], v[246:247], off
	v_add_u32_e32 v240, -1, v240
	v_mov_b64_e32 v[238:239], s[30:31]
	v_mad_i64_i32 v[238:239], s[0:1], v240, s76, v[238:239]
	v_lshl_add_u64 v[238:239], v[238:239], 0, v[186:187]
	global_load_dwordx4 v[242:245], v[238:239], off
	v_mov_b32_e32 v129, v0
	v_mov_b32_e32 v115, v1
	v_pk_mul_f32 v[128:129], v[210:211], v[128:129]
	v_pk_mul_f32 v[0:1], v[106:107], v[114:115]
	v_pk_fma_f32 v[114:115], v[102:103], v[118:119], v[110:111]
	v_mov_b32_e32 v118, v129
	v_mov_b32_e32 v119, v1
	v_pk_add_f32 v[114:115], v[118:119], v[114:115]
	v_mov_b32_e32 v129, v0
	v_pk_add_f32 v[0:1], v[128:129], v[114:115]
	v_lshlrev_b32_e32 v136, 16, v116
	v_fma_f32 v114, |v0|, s84, 1.0
	v_rcp_f32_e32 v115, v114
	v_pk_mul_f32 v[128:129], v[0:1], v[0:1]
	v_and_b32_e32 v114, 0xffff0000, v116
	v_lshlrev_b32_e32 v116, 16, v117
	v_and_b32_e32 v118, 0xffff0000, v117
	v_fmamk_f32 v117, v115, 0x3f07dc22, v241
	v_mul_f32_e32 v119, 0xbf38aa3b, v128
	v_fmaak_f32 v117, v115, v117, 0x3f35f0e3
	v_exp_f32_e32 v119, v119
	v_fmaak_f32 v117, v115, v117, 0xbe11a98e
	v_fmaak_f32 v117, v115, v117, 0x3e027906
	v_mul_f32_e32 v115, v115, v117
	v_mul_f32_e32 v115, v119, v115
	v_fma_f32 v119, |v1|, s84, 1.0
	v_rcp_f32_e32 v119, v119
	v_mul_f32_e32 v117, v0, v115
	v_fma_f32 v115, -v0, v115, v0
	v_cmp_gt_f32_e64 s[0:1], 0, v0
	v_mov_b32_e32 v131, v2
	v_mov_b32_e32 v133, v3
	v_cndmask_b32_e64 v0, v115, v117, s[0:1]
	v_mul_f32_e32 v138, v86, v0
	v_mul_f32_e32 v86, 0xbf38aa3b, v129
	v_pk_mul_f32 v[128:129], v[172:173], v[130:131]
	v_pk_mul_f32 v[2:3], v[108:109], v[132:133]
	v_fmamk_f32 v0, v119, 0x3f07dc22, v241
	v_pk_fma_f32 v[120:121], v[104:105], v[120:121], v[112:113]
	v_mov_b32_e32 v130, v129
	v_mov_b32_e32 v131, v3
	v_fmaak_f32 v0, v119, v0, 0x3f35f0e3
	v_exp_f32_e32 v86, v86
	v_pk_add_f32 v[120:121], v[130:131], v[120:121]
	v_mov_b32_e32 v129, v2
	v_fmaak_f32 v0, v119, v0, 0xbe11a98e
	v_pk_add_f32 v[2:3], v[128:129], v[120:121]
	v_fmaak_f32 v0, v119, v0, 0x3e027906
	v_fma_f32 v115, |v2|, s84, 1.0
	v_mul_f32_e32 v0, v119, v0
	v_rcp_f32_e32 v115, v115
	v_mul_f32_e32 v0, v86, v0
	v_mul_f32_e32 v86, v1, v0
	v_fma_f32 v0, -v1, v0, v1
	v_cmp_gt_f32_e64 s[0:1], 0, v1
	v_mov_b32_e32 v137, v4
	v_mov_b32_e32 v119, v7
	v_cndmask_b32_e64 v0, v0, v86, s[0:1]
	v_mul_f32_e32 v120, v87, v0
	v_fmamk_f32 v0, v115, 0x3f07dc22, v241
	v_fmaak_f32 v86, v115, v0, 0x3f35f0e3
	v_pk_mul_f32 v[0:1], v[2:3], v[2:3]
	v_fmaak_f32 v86, v115, v86, 0xbe11a98e
	v_mul_f32_e32 v0, 0xbf38aa3b, v0
	v_exp_f32_e32 v0, v0
	v_fmaak_f32 v86, v115, v86, 0x3e027906
	v_fma_f32 v87, |v3|, s84, 1.0
	v_mul_f32_e32 v86, v115, v86
	v_rcp_f32_e32 v87, v87
	v_mul_f32_e32 v0, v0, v86
	v_mul_f32_e32 v86, v2, v0
	v_fma_f32 v0, -v2, v0, v2
	v_cmp_gt_f32_e64 s[0:1], 0, v2
	v_mul_f32_e32 v1, 0xbf38aa3b, v1
	v_exp_f32_e32 v1, v1
	v_cndmask_b32_e64 v0, v0, v86, s[0:1]
	v_mul_f32_e32 v88, v88, v0
	v_fmamk_f32 v0, v87, 0x3f07dc22, v241
	v_fmaak_f32 v0, v87, v0, 0x3f35f0e3
	v_fmaak_f32 v0, v87, v0, 0xbe11a98e
	v_fmaak_f32 v0, v87, v0, 0x3e027906
	v_mul_f32_e32 v0, v87, v0
	v_mul_f32_e32 v0, v1, v0
	v_mov_b32_e32 v115, v5
	v_mul_f32_e32 v2, v3, v0
	v_fma_f32 v117, -v3, v0, v3
	v_pk_mul_f32 v[0:1], v[212:213], v[136:137]
	v_pk_mul_f32 v[4:5], v[94:95], v[114:115]
	v_pk_fma_f32 v[86:87], v[90:91], v[122:123], v[98:99]
	v_mov_b32_e32 v114, v1
	v_mov_b32_e32 v115, v5
	v_pk_add_f32 v[86:87], v[114:115], v[86:87]
	v_mov_b32_e32 v1, v4
	v_pk_add_f32 v[0:1], v[0:1], v[86:87]
	v_cmp_gt_f32_e64 s[0:1], 0, v3
	v_fma_f32 v4, |v0|, s84, 1.0
	v_rcp_f32_e32 v4, v4
	v_cndmask_b32_e64 v2, v117, v2, s[0:1]
	v_mul_f32_e32 v89, v89, v2
	v_cmp_gt_f32_e64 s[0:1], 0, v0
	v_fmamk_f32 v2, v4, 0x3f07dc22, v241
	v_fmaak_f32 v5, v4, v2, 0x3f35f0e3
; __device__ __forceinline__ unsigned pk2(float lo, float hi) { unsigned r; asm("v_cvt_pk_bf16_f32 %0, %1, %2" : "=v"(r) : "v"(lo), "v"(hi)); return r; }
;     static __device__ __forceinline__ void unpack8(const u32x4 q, float (&x)[8]) { x[0] = bflo(q.x); x[1] = bfhi(q.x); x[2] = bflo(q.y); x[3] = bfhi(q.y); x[4] = bflo(q.z); x[5] = bfhi(q.z); x[6] = bflo(q.w); x[7] = bfhi(q.w); }
;     __device__ __forceinline__ void operator()(EPI_ARGS) const {
;     ...
;                     for (int t = 0; t < 1; ++t) { const int row = row0 + ai * 128 + (mp + t) * 16; const int r1 = row > 0 ? row - 1 : 0, r2 = row > 1 ? row - 2 : 0;
;                         q2[t] = *(const u32x4*)(up + (size_t)row * DFF + col); q1[t] = *(const u32x4*)(up + (size_t)r1 * DFF + col); q0[t] = *(const u32x4*)(up + (size_t)r2 * DFF + col); }
;                     __builtin_amdgcn_sched_barrier(0);
; #pragma unroll
;                     for (int t = 0; t < 1; ++t) { const int m = mp + t, row = row0 + ai * 128 + m * 16;
;                         const int i = row < TP ? row : ((row - TP) & 15); const int sidx = row < TP ? 0 : ((row - TP) >> 4);
;                         float x0[8], x1[8], x2[8]; unpack8(q0[t], x0); unpack8(q1[t], x1); unpack8(q2[t], x2);
;                         if (i < 2) {
;                             const bool smp = row >= TP; const float* p0 = cs + ((size_t)sidx * 2 + i) * DFF + col; const float* p1 = cs + ((size_t)sidx * 2 + 1) * DFF + col;
; #pragma unroll
;                             for (int e = 0; e < 8; ++e) { x0[e] = smp ? p0[e] : 0.f; if (i == 0) x1[e] = smp ? p1[e] : 0.f; } }
;     ...
;                         for (int e = 0; e < 8; ++e) { const float cv = bb[e] + x0[e] * w0[e] + x1[e] * w1[e] + x2[e] * w2[e]; r[e] = gelu_f(cv) * acc[ai][bj][m][e >> 2][e & 3]; }
;                         u32x4 w; w.x = pk2(r[0], r[1]); w.y = pk2(r[2], r[3]); w.z = pk2(r[4], r[5]); w.w = pk2(r[6], r[7]);
;                         *(u32x4*)(act + (size_t)row * DFF + col) = w; } } } }
	v_pk_mul_f32 v[2:3], v[0:1], v[0:1]
	v_fmaak_f32 v5, v4, v5, 0xbe11a98e
	v_mul_f32_e32 v2, 0xbf38aa3b, v2
	v_exp_f32_e32 v2, v2
	v_fmaak_f32 v5, v4, v5, 0x3e027906
	v_mul_f32_e32 v4, v4, v5
	v_fma_f32 v5, |v1|, s84, 1.0
	v_rcp_f32_e32 v5, v5
	v_mul_f32_e32 v2, v2, v4
	v_mul_f32_e32 v4, v0, v2
	v_fma_f32 v2, -v0, v2, v0
	v_cndmask_b32_e64 v0, v2, v4, s[0:1]
	v_mul_f32_e32 v82, v82, v0
	v_fmamk_f32 v0, v5, 0x3f07dc22, v241
	v_mul_f32_e32 v2, 0xbf38aa3b, v3
	v_fmaak_f32 v0, v5, v0, 0x3f35f0e3
	v_exp_f32_e32 v2, v2
	v_fmaak_f32 v0, v5, v0, 0xbe11a98e
	v_fmaak_f32 v0, v5, v0, 0x3e027906
	v_mul_f32_e32 v0, v5, v0
	v_mov_b32_e32 v117, v6
	v_mul_f32_e32 v0, v2, v0
	v_pk_mul_f32 v[2:3], v[214:215], v[116:117]
	v_pk_mul_f32 v[4:5], v[96:97], v[118:119]
	v_pk_fma_f32 v[6:7], v[92:93], v[124:125], v[100:101]
	v_mov_b32_e32 v86, v3
	v_mov_b32_e32 v87, v5
	v_pk_add_f32 v[6:7], v[86:87], v[6:7]
	v_mov_b32_e32 v3, v4
	v_pk_add_f32 v[2:3], v[2:3], v[6:7]
	v_mul_f32_e32 v114, v1, v0
	v_fma_f32 v4, |v2|, s84, 1.0
	v_rcp_f32_e32 v4, v4
	v_fma_f32 v0, -v1, v0, v1
	v_cmp_gt_f32_e64 s[0:1], 0, v1
	v_add_u32_e32 v124, 0xb0, v232
	s_nop 0
	v_cndmask_b32_e64 v0, v0, v114, s[0:1]
	v_mul_f32_e32 v5, v83, v0
	v_fmamk_f32 v0, v4, 0x3f07dc22, v241
	v_fmaak_f32 v6, v4, v0, 0x3f35f0e3
	v_pk_mul_f32 v[0:1], v[2:3], v[2:3]
	v_fmaak_f32 v6, v4, v6, 0xbe11a98e
	v_mul_f32_e32 v0, 0xbf38aa3b, v0
	v_exp_f32_e32 v0, v0
	v_fmaak_f32 v6, v4, v6, 0x3e027906
	v_mul_f32_e32 v4, v4, v6
	v_fma_f32 v6, |v3|, s84, 1.0
	v_rcp_f32_e32 v6, v6
	v_mul_f32_e32 v0, v0, v4
	v_mul_f32_e32 v4, v2, v0
	v_fma_f32 v0, -v2, v0, v2
	v_cmp_gt_f32_e64 s[0:1], 0, v2
	v_mul_f32_e32 v1, 0xbf38aa3b, v1
	v_exp_f32_e32 v1, v1
	v_cndmask_b32_e64 v0, v0, v4, s[0:1]
	v_mul_f32_e32 v4, v84, v0
	v_fmamk_f32 v0, v6, 0x3f07dc22, v241
	v_fmaak_f32 v0, v6, v0, 0x3f35f0e3
	v_fmaak_f32 v0, v6, v0, 0xbe11a98e
	v_fmaak_f32 v0, v6, v0, 0x3e027906
	v_mul_f32_e32 v0, v6, v0
	v_mul_f32_e32 v0, v1, v0
	v_mul_f32_e32 v1, v3, v0
	v_fma_f32 v0, -v3, v0, v3
	v_cmp_gt_f32_e64 s[0:1], 0, v3
	v_cvt_pk_bf16_f32 v2, v82, v5
	s_nop 1
	v_cndmask_b32_e64 v0, v0, v1, s[0:1]
	v_mul_f32_e32 v3, v85, v0
	v_cvt_pk_bf16_f32 v3, v4, v3
	v_lshl_add_u64 v[4:5], s[80:81], 0, v[126:127]
	v_cvt_pk_bf16_f32 v0, v138, v120
	v_lshl_add_u64 v[4:5], v[4:5], 0, v[186:187]
	v_cvt_pk_bf16_f32 v1, v88, v89
	global_store_dwordx4 v[4:5], v[0:3], off sc1
	s_nop 1
	v_max_i32_e32 v0, 1, v124
	v_add_u32_e32 v4, -1, v0
	v_max_i32_e32 v0, 2, v124
	v_add_u32_e32 v86, -2, v0
	v_mov_b64_e32 v[0:1], s[30:31]
	v_mad_i64_i32 v[2:3], s[0:1], v124, s76, v[0:1]
	v_mad_u64_u32 v[4:5], s[0:1], v4, s76, v[0:1]
	v_mad_u64_u32 v[0:1], s[0:1], v86, s76, v[0:1]
	v_lshl_add_u64 v[2:3], v[2:3], 0, v[186:187]
	v_lshl_add_u64 v[4:5], v[4:5], 0, v[186:187]
	v_lshl_add_u64 v[0:1], v[0:1], 0, v[186:187]
	s_movk_i32 s0, 0x1f50
	v_cmp_gt_i32_e64 s[70:71], s0, v232
	s_waitcnt vmcnt(1)
	v_mov_b64_e32 v[82:83], v[196:197]
	v_mov_b64_e32 v[84:85], v[198:199]
	v_mov_b64_e32 v[4:5], v[200:201]
	v_mov_b64_e32 v[6:7], v[202:203]
	v_mov_b64_e32 v[0:1], v[242:243]
	v_mov_b64_e32 v[2:3], v[244:245]
	v_lshlrev_b32_e32 v86, 16, v0
	v_and_b32_e32 v87, 0xffff0000, v0
	v_cndmask_b32_e64 v122, v228, v124, s[70:71]
	v_lshlrev_b32_e32 v88, 16, v1
	v_and_b32_e32 v89, 0xffff0000, v1
	v_lshlrev_b32_e32 v114, 16, v2
	v_and_b32_e32 v115, 0xffff0000, v2
	v_lshlrev_b32_e32 v116, 16, v3
	v_and_b32_e32 v117, 0xffff0000, v3
	v_lshlrev_b32_e32 v0, 16, v4
	v_and_b32_e32 v1, 0xffff0000, v4
	v_lshlrev_b32_e32 v2, 16, v5
	v_and_b32_e32 v3, 0xffff0000, v5
	v_lshlrev_b32_e32 v4, 16, v6
	v_and_b32_e32 v5, 0xffff0000, v6
	v_lshlrev_b32_e32 v6, 16, v7
	v_and_b32_e32 v7, 0xffff0000, v7
	v_cmp_gt_i32_e64 s[0:1], 2, v122
	s_and_saveexec_b64 s[14:15], s[0:1]
	s_cbranch_execz .LBB0_1524
	s_add_i32 s18, s5, 0xffffe0b0
	s_ashr_i32 s18, s18, 4
	v_mov_b32_e32 v86, s18
	v_cndmask_b32_e64 v88, v86, 0, s[70:71]
	v_ashrrev_i32_e32 v89, 31, v88
	v_ashrrev_i32_e32 v123, 31, v122
	v_lshl_add_u64 v[86:87], v[88:89], 1, v[122:123]
	v_mov_b64_e32 v[114:115], s[68:69]
	v_mad_u64_u32 v[114:115], s[18:19], v86, s13, v[114:115]
	s_movk_i32 s0, 0x1f4f
	v_mad_i32_i24 v115, v87, s13, v115
	v_cmp_lt_i32_e64 s[0:1], s0, v232
	v_lshl_add_u64 v[120:121], v[184:185], 2, v[114:115]
	v_mov_b32_e32 v86, 0
	s_and_saveexec_b64 s[18:19], s[0:1]
	s_cbranch_execz .LBB0_1477
	global_load_dword v86, v[120:121], off

; __device__ __forceinline__ unsigned pk2(float lo, float hi) { unsigned r; asm("v_cvt_pk_bf16_f32 %0, %1, %2" : "=v"(r) : "v"(lo), "v"(hi)); return r; }
; __device__ __forceinline__ float gelu_f(float v) {
;     const float av = fabsf(v), d = av * 0.2316418882f + 1.0f;
;     const float t = __builtin_amdgcn_rcpf(d);
;     float q = t * 0.5307027145f + (-0.7265760135f); q = q * t + 0.7107068705f; q = q * t + (-0.142248368f); q = q * t + 0.127414796f; q = q * t;
;     const float e = __builtin_amdgcn_exp2f(v * v * (-0.72134752044f));
;     const float m = v * (q * e);
;     return v < 0.f ? m : v - m;
;     __device__ __forceinline__ void operator()(EPI_ARGS) const {
;     ...
;                     for (int t = 0; t < 1; ++t) { const int row = row0 + ai * 128 + (mp + t) * 16; const int r1 = row > 0 ? row - 1 : 0, r2 = row > 1 ? row - 2 : 0;
;                         q2[t] = *(const u32x4*)(up + (size_t)row * DFF + col); q1[t] = *(const u32x4*)(up + (size_t)r1 * DFF + col); q0[t] = *(const u32x4*)(up + (size_t)r2 * DFF + col); }
;                     __builtin_amdgcn_sched_barrier(0);
; #pragma unroll
;                     for (int t = 0; t < 1; ++t) { const int m = mp + t, row = row0 + ai * 128 + m * 16;
;                         const int i = row < TP ? row : ((row - TP) & 15); const int sidx = row < TP ? 0 : ((row - TP) >> 4);
;                         float x0[8], x1[8], x2[8]; unpack8(q0[t], x0); unpack8(q1[t], x1); unpack8(q2[t], x2);
;                         if (i < 2) {
;                             const bool smp = row >= TP; const float* p0 = cs + ((size_t)sidx * 2 + i) * DFF + col; const float* p1 = cs + ((size_t)sidx * 2 + 1) * DFF + col;
; #pragma unroll
;                             for (int e = 0; e < 8; ++e) { x0[e] = smp ? p0[e] : 0.f; if (i == 0) x1[e] = smp ? p1[e] : 0.f; } }
;                         float r[8];
; #pragma unroll
;                         for (int e = 0; e < 8; ++e) { const float cv = bb[e] + x0[e] * w0[e] + x1[e] * w1[e] + x2[e] * w2[e]; r[e] = gelu_f(cv) * acc[ai][bj][m][e >> 2][e & 3]; }
;                         u32x4 w; w.x = pk2(r[0], r[1]); w.y = pk2(r[2], r[3]); w.z = pk2(r[4], r[5]); w.w = pk2(r[6], r[7]);
;                         *(u32x4*)(act + (size_t)row * DFF + col) = w; } } } }
.LBB0_1524:
	s_or_b64 exec, exec, s[14:15]
	v_mad_i64_i32 v[118:119], s[0:1], v124, s76, 0
	v_lshlrev_b32_e32 v120, 16, v82
	v_and_b32_e32 v82, 0xffff0000, v82
	v_lshlrev_b32_e32 v122, 16, v83
	v_and_b32_e32 v124, 0xffff0000, v83
	s_waitcnt vmcnt(1)
	v_mov_b32_e32 v121, v0
	v_mov_b32_e32 v83, v1
	v_pk_mul_f32 v[120:121], v[210:211], v[120:121]
	v_pk_mul_f32 v[0:1], v[106:107], v[82:83]
	v_pk_fma_f32 v[82:83], v[102:103], v[86:87], v[110:111]
	v_mov_b32_e32 v86, v121
	v_mov_b32_e32 v87, v1
	v_pk_add_f32 v[82:83], v[86:87], v[82:83]
	v_mov_b32_e32 v121, v0
	v_pk_add_f32 v[0:1], v[120:121], v[82:83]
	v_lshlrev_b32_e32 v126, 16, v84
	v_fma_f32 v82, |v0|, s84, 1.0
	v_rcp_f32_e32 v83, v82
	v_pk_mul_f32 v[102:103], v[0:1], v[0:1]
	v_and_b32_e32 v82, 0xffff0000, v84
	v_lshlrev_b32_e32 v84, 16, v85
	v_and_b32_e32 v86, 0xffff0000, v85
	v_fmamk_f32 v85, v83, 0x3f07dc22, v241
	v_mul_f32_e32 v87, 0xbf38aa3b, v102
	v_fmaak_f32 v85, v83, v85, 0x3f35f0e3
	v_exp_f32_e32 v87, v87
	v_fmaak_f32 v85, v83, v85, 0xbe11a98e
	v_fmaak_f32 v85, v83, v85, 0x3e027906
	v_mul_f32_e32 v83, v83, v85
	v_mul_f32_e32 v83, v87, v83
	v_fma_f32 v87, |v1|, s84, 1.0
	v_rcp_f32_e32 v87, v87
	v_mul_f32_e32 v85, v0, v83
	v_fma_f32 v83, -v0, v83, v0
	v_cmp_gt_f32_e64 s[0:1], 0, v0
	v_mov_b32_e32 v123, v2
	v_mov_b32_e32 v125, v3
	v_cndmask_b32_e64 v0, v83, v85, s[0:1]
	v_mul_f32_e32 v106, v78, v0
	v_mul_f32_e32 v78, 0xbf38aa3b, v103
	v_pk_mul_f32 v[102:103], v[172:173], v[122:123]
	v_pk_mul_f32 v[2:3], v[108:109], v[124:125]
	v_fmamk_f32 v0, v87, 0x3f07dc22, v241
	v_pk_fma_f32 v[88:89], v[104:105], v[88:89], v[112:113]
	v_mov_b32_e32 v104, v103
	v_mov_b32_e32 v105, v3
	v_fmaak_f32 v0, v87, v0, 0x3f35f0e3
	v_exp_f32_e32 v78, v78
	v_pk_add_f32 v[88:89], v[104:105], v[88:89]
	v_mov_b32_e32 v103, v2
	v_fmaak_f32 v0, v87, v0, 0xbe11a98e
	v_pk_add_f32 v[2:3], v[102:103], v[88:89]
	v_fmaak_f32 v0, v87, v0, 0x3e027906
	v_fma_f32 v83, |v2|, s84, 1.0
	v_mul_f32_e32 v0, v87, v0
	v_rcp_f32_e32 v83, v83
	v_mul_f32_e32 v0, v78, v0
	v_mul_f32_e32 v78, v1, v0
	v_fma_f32 v0, -v1, v0, v1
	v_cmp_gt_f32_e64 s[0:1], 0, v1
	v_mov_b32_e32 v127, v4
	v_mov_b32_e32 v87, v7
	v_cndmask_b32_e64 v0, v0, v78, s[0:1]
	v_mul_f32_e32 v88, v79, v0
	v_fmamk_f32 v0, v83, 0x3f07dc22, v241
	v_fmaak_f32 v78, v83, v0, 0x3f35f0e3
	v_pk_mul_f32 v[0:1], v[2:3], v[2:3]
	v_fmaak_f32 v78, v83, v78, 0xbe11a98e
	v_mul_f32_e32 v0, 0xbf38aa3b, v0
	v_exp_f32_e32 v0, v0
	v_fmaak_f32 v78, v83, v78, 0x3e027906
	v_fma_f32 v79, |v3|, s84, 1.0
	v_mul_f32_e32 v78, v83, v78
	v_rcp_f32_e32 v79, v79
	v_mul_f32_e32 v0, v0, v78
	v_mul_f32_e32 v78, v2, v0
	v_fma_f32 v0, -v2, v0, v2
	v_cmp_gt_f32_e64 s[0:1], 0, v2
	v_mul_f32_e32 v1, 0xbf38aa3b, v1
	v_exp_f32_e32 v1, v1
	v_cndmask_b32_e64 v0, v0, v78, s[0:1]
	v_mul_f32_e32 v80, v80, v0
	v_fmamk_f32 v0, v79, 0x3f07dc22, v241
	v_fmaak_f32 v0, v79, v0, 0x3f35f0e3
	v_fmaak_f32 v0, v79, v0, 0xbe11a98e
	v_fmaak_f32 v0, v79, v0, 0x3e027906
	v_mul_f32_e32 v0, v79, v0
	v_mul_f32_e32 v0, v1, v0
	v_mov_b32_e32 v83, v5
	v_mul_f32_e32 v2, v3, v0
	v_fma_f32 v85, -v3, v0, v3
	v_pk_mul_f32 v[0:1], v[212:213], v[126:127]
	v_pk_mul_f32 v[4:5], v[94:95], v[82:83]
	v_pk_fma_f32 v[78:79], v[90:91], v[114:115], v[98:99]
	v_mov_b32_e32 v82, v1
	v_mov_b32_e32 v83, v5
	v_pk_add_f32 v[78:79], v[82:83], v[78:79]
	v_mov_b32_e32 v1, v4
	v_pk_add_f32 v[0:1], v[0:1], v[78:79]
	v_cmp_gt_f32_e64 s[0:1], 0, v3
	v_fma_f32 v4, |v0|, s84, 1.0
	v_rcp_f32_e32 v4, v4
	v_cndmask_b32_e64 v2, v85, v2, s[0:1]
	v_mul_f32_e32 v81, v81, v2
	v_cmp_gt_f32_e64 s[0:1], 0, v0
	v_fmamk_f32 v2, v4, 0x3f07dc22, v241
	v_fmaak_f32 v5, v4, v2, 0x3f35f0e3
	v_pk_mul_f32 v[2:3], v[0:1], v[0:1]
	v_fmaak_f32 v5, v4, v5, 0xbe11a98e
	v_mul_f32_e32 v2, 0xbf38aa3b, v2
	v_exp_f32_e32 v2, v2
	v_fmaak_f32 v5, v4, v5, 0x3e027906
	v_mul_f32_e32 v4, v4, v5
	v_fma_f32 v5, |v1|, s84, 1.0
	v_rcp_f32_e32 v5, v5
	v_mul_f32_e32 v2, v2, v4
	v_mul_f32_e32 v4, v0, v2
	v_fma_f32 v2, -v0, v2, v0
	v_cndmask_b32_e64 v0, v2, v4, s[0:1]
	v_mul_f32_e32 v74, v74, v0
	v_fmamk_f32 v0, v5, 0x3f07dc22, v241
	v_mul_f32_e32 v2, 0xbf38aa3b, v3
	v_fmaak_f32 v0, v5, v0, 0x3f35f0e3
	v_exp_f32_e32 v2, v2
	v_fmaak_f32 v0, v5, v0, 0xbe11a98e
	v_fmaak_f32 v0, v5, v0, 0x3e027906
	v_mul_f32_e32 v0, v5, v0
	v_mov_b32_e32 v85, v6
	v_mul_f32_e32 v0, v2, v0
	v_pk_mul_f32 v[2:3], v[214:215], v[84:85]
	v_pk_mul_f32 v[4:5], v[96:97], v[86:87]
	v_pk_fma_f32 v[6:7], v[92:93], v[116:117], v[100:101]
	v_mov_b32_e32 v78, v3
	v_mov_b32_e32 v79, v5
	v_pk_add_f32 v[6:7], v[78:79], v[6:7]
	v_mov_b32_e32 v3, v4
	v_pk_add_f32 v[2:3], v[2:3], v[6:7]
	v_mul_f32_e32 v82, v1, v0
	v_fma_f32 v4, |v2|, s84, 1.0
	v_rcp_f32_e32 v4, v4
	v_fma_f32 v0, -v1, v0, v1
	v_cmp_gt_f32_e64 s[0:1], 0, v1
	s_nop 1
	v_cndmask_b32_e64 v0, v0, v82, s[0:1]
	v_mul_f32_e32 v5, v75, v0
	v_fmamk_f32 v0, v4, 0x3f07dc22, v241
	v_fmaak_f32 v6, v4, v0, 0x3f35f0e3
	v_pk_mul_f32 v[0:1], v[2:3], v[2:3]
	v_fmaak_f32 v6, v4, v6, 0xbe11a98e
	v_mul_f32_e32 v0, 0xbf38aa3b, v0
	v_exp_f32_e32 v0, v0
	v_fmaak_f32 v6, v4, v6, 0x3e027906
	v_mul_f32_e32 v4, v4, v6
	v_fma_f32 v6, |v3|, s84, 1.0
	v_rcp_f32_e32 v6, v6
	v_mul_f32_e32 v0, v0, v4
	v_mul_f32_e32 v4, v2, v0
	v_fma_f32 v0, -v2, v0, v2
	v_cmp_gt_f32_e64 s[0:1], 0, v2
	v_mul_f32_e32 v1, 0xbf38aa3b, v1
	v_exp_f32_e32 v1, v1
	v_cndmask_b32_e64 v0, v0, v4, s[0:1]
	v_mul_f32_e32 v4, v76, v0
	v_fmamk_f32 v0, v6, 0x3f07dc22, v241
	v_fmaak_f32 v0, v6, v0, 0x3f35f0e3
	v_fmaak_f32 v0, v6, v0, 0xbe11a98e
	v_fmaak_f32 v0, v6, v0, 0x3e027906
	v_mul_f32_e32 v0, v6, v0
	v_mul_f32_e32 v0, v1, v0
	v_mul_f32_e32 v1, v3, v0
	v_fma_f32 v0, -v3, v0, v3
	v_cmp_gt_f32_e64 s[0:1], 0, v3
	v_cvt_pk_bf16_f32 v2, v74, v5
	s_nop 1
	v_cndmask_b32_e64 v0, v0, v1, s[0:1]
	v_mul_f32_e32 v3, v77, v0
	v_cvt_pk_bf16_f32 v3, v4, v3
	v_lshl_add_u64 v[4:5], s[80:81], 0, v[118:119]
	v_lshl_add_u64 v[4:5], v[184:185], 1, v[4:5]
	v_cvt_pk_bf16_f32 v0, v106, v88
	v_cvt_pk_bf16_f32 v1, v80, v81
	global_store_dwordx4 v[4:5], v[0:3], off sc1

; __device__ __forceinline__ unsigned pk2(float lo, float hi) { unsigned r; asm("v_cvt_pk_bf16_f32 %0, %1, %2" : "=v"(r) : "v"(lo), "v"(hi)); return r; }
; __device__ __forceinline__ float gelu_f(float v) {
;     const float av = fabsf(v), d = av * 0.2316418882f + 1.0f;
;     const float t = __builtin_amdgcn_rcpf(d);
;     float q = t * 0.5307027145f + (-0.7265760135f); q = q * t + 0.7107068705f; q = q * t + (-0.142248368f); q = q * t + 0.127414796f; q = q * t;
;     const float e = __builtin_amdgcn_exp2f(v * v * (-0.72134752044f));
;     const float m = v * (q * e);
;     return v < 0.f ? m : v - m;
;     __device__ __forceinline__ void operator()(EPI_ARGS) const {
;     ...
;                     for (int t = 0; t < 1; ++t) { const int row = row0 + ai * 128 + (mp + t) * 16; const int r1 = row > 0 ? row - 1 : 0, r2 = row > 1 ? row - 2 : 0;
;                         q2[t] = *(const u32x4*)(up + (size_t)row * DFF + col); q1[t] = *(const u32x4*)(up + (size_t)r1 * DFF + col); q0[t] = *(const u32x4*)(up + (size_t)r2 * DFF + col); }
;                     __builtin_amdgcn_sched_barrier(0);
; #pragma unroll
;                     for (int t = 0; t < 1; ++t) { const int m = mp + t, row = row0 + ai * 128 + m * 16;
;                         const int i = row < TP ? row : ((row - TP) & 15); const int sidx = row < TP ? 0 : ((row - TP) >> 4);
;                         float x0[8], x1[8], x2[8]; unpack8(q0[t], x0); unpack8(q1[t], x1); unpack8(q2[t], x2);
;                         if (i < 2) {
;                             const bool smp = row >= TP; const float* p0 = cs + ((size_t)sidx * 2 + i) * DFF + col; const float* p1 = cs + ((size_t)sidx * 2 + 1) * DFF + col;
; #pragma unroll
;                             for (int e = 0; e < 8; ++e) { x0[e] = smp ? p0[e] : 0.f; if (i == 0) x1[e] = smp ? p1[e] : 0.f; } }
;                         float r[8];
; #pragma unroll
;                         for (int e = 0; e < 8; ++e) { const float cv = bb[e] + x0[e] * w0[e] + x1[e] * w1[e] + x2[e] * w2[e]; r[e] = gelu_f(cv) * acc[ai][bj][m][e >> 2][e & 3]; }
;                         u32x4 w; w.x = pk2(r[0], r[1]); w.y = pk2(r[2], r[3]); w.z = pk2(r[4], r[5]); w.w = pk2(r[6], r[7]);
;                         *(u32x4*)(act + (size_t)row * DFF + col) = w; } } } }
.LBB0_1575:
	s_or_b64 exec, exec, s[0:1]
	v_lshlrev_b32_e32 v120, 16, v106
	v_and_b32_e32 v122, 0xffff0000, v106
	v_lshlrev_b32_e32 v124, 16, v107
	v_and_b32_e32 v126, 0xffff0000, v107
	v_mov_b32_e32 v106, v102
	v_mov_b32_e32 v107, v90
	s_waitcnt vmcnt(0)
	v_add_u32_e32 v240, 16, v232
	v_mov_b64_e32 v[238:239], s[30:31]
	v_mad_i64_i32 v[238:239], s[0:1], v240, s76, v[238:239]
	v_lshl_add_u64 v[238:239], v[238:239], 0, v[186:187]
	global_load_dwordx4 v[196:199], v[238:239], off offset:256
	v_add_u32_e32 v240, -1, v240
	v_mov_b64_e32 v[246:247], s[30:31]
	v_mad_i64_i32 v[246:247], s[0:1], v240, s76, v[246:247]
	v_lshl_add_u64 v[246:247], v[246:247], 0, v[186:187]
	global_load_dwordx4 v[200:203], v[246:247], off offset:256
	v_add_u32_e32 v240, -1, v240
	v_mov_b64_e32 v[238:239], s[30:31]
	v_mad_i64_i32 v[238:239], s[0:1], v240, s76, v[238:239]
	v_lshl_add_u64 v[238:239], v[238:239], 0, v[186:187]
	global_load_dwordx4 v[242:245], v[238:239], off offset:256
	v_mov_b32_e32 v121, v0
	v_mov_b32_e32 v90, v103
	v_mov_b32_e32 v123, v1
	v_pk_mul_f32 v[120:121], v[106:107], v[120:121]
	v_pk_mul_f32 v[0:1], v[90:91], v[122:123]
	v_pk_fma_f32 v[102:103], v[86:87], v[112:113], v[94:95]
	v_mov_b32_e32 v112, v121
	v_mov_b32_e32 v113, v1
	v_pk_add_f32 v[102:103], v[112:113], v[102:103]
	v_mov_b32_e32 v121, v0
	v_pk_add_f32 v[0:1], v[120:121], v[102:103]
	v_lshlrev_b32_e32 v112, 16, v109
	v_fma_f32 v102, |v0|, s84, 1.0
	v_rcp_f32_e32 v113, v102
	v_and_b32_e32 v120, 0xffff0000, v109
	v_cmp_gt_f32_e32 vcc, 0, v0
	v_mov_b32_e32 v125, v2
	v_fmamk_f32 v102, v113, 0x3f07dc22, v241
	v_fmaak_f32 v109, v113, v102, 0x3f35f0e3
	v_pk_mul_f32 v[102:103], v[0:1], v[0:1]
	v_fmaak_f32 v109, v113, v109, 0xbe11a98e
	v_mul_f32_e32 v102, 0xbf38aa3b, v102
	v_exp_f32_e32 v102, v102
	v_fmaak_f32 v109, v113, v109, 0x3e027906
	v_mul_f32_e32 v109, v113, v109
	v_fma_f32 v113, |v1|, s84, 1.0
	v_mul_f32_e32 v102, v102, v109
	v_mul_f32_e32 v109, v0, v102
	v_fma_f32 v102, -v0, v102, v0
	v_rcp_f32_e32 v113, v113
	v_cndmask_b32_e32 v0, v102, v109, vcc
	v_mul_f32_e32 v130, v70, v0
	v_mul_f32_e32 v70, 0xbf38aa3b, v103
	v_mov_b32_e32 v102, v104
	v_mov_b32_e32 v103, v92
	v_mov_b32_e32 v92, v105
	v_mov_b32_e32 v127, v3
	v_pk_mul_f32 v[122:123], v[102:103], v[124:125]
	v_pk_mul_f32 v[2:3], v[92:93], v[126:127]
	v_fmamk_f32 v0, v113, 0x3f07dc22, v241
	v_pk_fma_f32 v[104:105], v[88:89], v[114:115], v[96:97]
	v_mov_b32_e32 v114, v123
	v_mov_b32_e32 v115, v3
	v_fmaak_f32 v0, v113, v0, 0x3f35f0e3
	v_exp_f32_e32 v70, v70
	v_pk_add_f32 v[104:105], v[114:115], v[104:105]
	v_mov_b32_e32 v123, v2
	v_fmaak_f32 v0, v113, v0, 0xbe11a98e
	v_pk_add_f32 v[2:3], v[122:123], v[104:105]
	v_fmaak_f32 v0, v113, v0, 0x3e027906
	v_fma_f32 v104, |v2|, s84, 1.0
	v_mul_f32_e32 v0, v113, v0
	v_rcp_f32_e32 v104, v104
	v_mul_f32_e32 v0, v70, v0
	v_mul_f32_e32 v70, v1, v0
	v_fma_f32 v0, -v1, v0, v1
	v_cmp_gt_f32_e32 vcc, 0, v1
	v_lshlrev_b32_e32 v128, 16, v108
	v_and_b32_e32 v108, 0xffff0000, v108
	v_cndmask_b32_e32 v0, v0, v70, vcc
	v_mul_f32_e32 v114, v71, v0
	v_fmamk_f32 v0, v104, 0x3f07dc22, v241
	v_fmaak_f32 v70, v104, v0, 0x3f35f0e3
	v_pk_mul_f32 v[0:1], v[2:3], v[2:3]
	v_fmaak_f32 v70, v104, v70, 0xbe11a98e
	v_mul_f32_e32 v0, 0xbf38aa3b, v0
	v_exp_f32_e32 v0, v0
	v_fmaak_f32 v70, v104, v70, 0x3e027906
	v_fma_f32 v71, |v3|, s84, 1.0
	v_mul_f32_e32 v70, v104, v70
	v_rcp_f32_e32 v71, v71
	v_mul_f32_e32 v0, v0, v70
	v_mul_f32_e32 v70, v2, v0
	v_fma_f32 v0, -v2, v0, v2
	v_cmp_gt_f32_e32 vcc, 0, v2
	v_mul_f32_e32 v1, 0xbf38aa3b, v1
	v_exp_f32_e32 v1, v1
	v_cndmask_b32_e32 v0, v0, v70, vcc
	v_mul_f32_e32 v115, v72, v0
	v_fmamk_f32 v0, v71, 0x3f07dc22, v241
	v_fmaak_f32 v0, v71, v0, 0x3f35f0e3
	v_fmaak_f32 v0, v71, v0, 0xbe11a98e
	v_fmaak_f32 v0, v71, v0, 0x3e027906
	v_mul_f32_e32 v0, v71, v0
	v_mul_f32_e32 v0, v1, v0
	v_mov_b32_e32 v70, v98
	v_mov_b32_e32 v71, v78
	v_mov_b32_e32 v129, v4
	v_mov_b32_e32 v78, v99
	v_mov_b32_e32 v109, v5
	v_mul_f32_e32 v2, v3, v0
	v_fma_f32 v72, -v3, v0, v3
	v_pk_mul_f32 v[0:1], v[70:71], v[128:129]
	v_pk_mul_f32 v[4:5], v[78:79], v[108:109]
	v_pk_fma_f32 v[98:99], v[74:75], v[116:117], v[82:83]
	v_mov_b32_e32 v104, v1
	v_mov_b32_e32 v105, v5
	v_pk_add_f32 v[98:99], v[104:105], v[98:99]
	v_mov_b32_e32 v1, v4
	v_pk_add_f32 v[0:1], v[0:1], v[98:99]
	v_cmp_gt_f32_e32 vcc, 0, v3
	v_fma_f32 v4, |v0|, s84, 1.0
	v_rcp_f32_e32 v4, v4
	v_cndmask_b32_e32 v2, v72, v2, vcc
	v_mul_f32_e32 v104, v73, v2
	v_cmp_gt_f32_e32 vcc, 0, v0
	v_fmamk_f32 v2, v4, 0x3f07dc22, v241
	v_fmaak_f32 v5, v4, v2, 0x3f35f0e3
	v_pk_mul_f32 v[2:3], v[0:1], v[0:1]
	v_fmaak_f32 v5, v4, v5, 0xbe11a98e
	v_mul_f32_e32 v2, 0xbf38aa3b, v2
	v_exp_f32_e32 v2, v2
	v_fmaak_f32 v5, v4, v5, 0x3e027906
	v_mul_f32_e32 v4, v4, v5
	v_fma_f32 v5, |v1|, s84, 1.0
	v_rcp_f32_e32 v5, v5
	v_mul_f32_e32 v2, v2, v4
	v_mul_f32_e32 v4, v0, v2
	v_fma_f32 v2, -v0, v2, v0
	v_cndmask_b32_e32 v0, v2, v4, vcc
	v_mul_f32_e32 v66, v66, v0
	v_fmamk_f32 v0, v5, 0x3f07dc22, v241
	v_mul_f32_e32 v2, 0xbf38aa3b, v3
	v_fmaak_f32 v0, v5, v0, 0x3f35f0e3
	v_exp_f32_e32 v2, v2
	v_fmaak_f32 v0, v5, v0, 0xbe11a98e
	v_fmaak_f32 v0, v5, v0, 0x3e027906
	v_mul_f32_e32 v0, v5, v0
	v_mov_b32_e32 v72, v100
	v_mov_b32_e32 v73, v80
	v_mov_b32_e32 v113, v6
	v_mov_b32_e32 v80, v101
	v_mov_b32_e32 v121, v7
	v_mul_f32_e32 v0, v2, v0
	v_pk_mul_f32 v[2:3], v[72:73], v[112:113]
	v_pk_mul_f32 v[4:5], v[80:81], v[120:121]
	v_pk_fma_f32 v[6:7], v[76:77], v[118:119], v[84:85]
	v_mov_b32_e32 v98, v3
	v_mov_b32_e32 v99, v5
	v_pk_add_f32 v[6:7], v[98:99], v[6:7]
	v_mov_b32_e32 v3, v4
	v_pk_add_f32 v[2:3], v[2:3], v[6:7]
	v_mul_f32_e32 v105, v1, v0
	v_fma_f32 v4, |v2|, s84, 1.0
	v_rcp_f32_e32 v4, v4
	v_fma_f32 v0, -v1, v0, v1
	v_cmp_gt_f32_e32 vcc, 0, v1
	s_nop 1
	v_cndmask_b32_e32 v0, v0, v105, vcc
	v_mul_f32_e32 v5, v67, v0
	v_fmamk_f32 v0, v4, 0x3f07dc22, v241
	v_fmaak_f32 v6, v4, v0, 0x3f35f0e3
	v_pk_mul_f32 v[0:1], v[2:3], v[2:3]
	v_fmaak_f32 v6, v4, v6, 0xbe11a98e
	v_mul_f32_e32 v0, 0xbf38aa3b, v0
	v_exp_f32_e32 v0, v0
	v_fmaak_f32 v6, v4, v6, 0x3e027906
	v_mul_f32_e32 v4, v4, v6
	v_fma_f32 v6, |v3|, s84, 1.0
	v_rcp_f32_e32 v6, v6
	v_mul_f32_e32 v0, v0, v4
	v_mul_f32_e32 v4, v2, v0
	v_fma_f32 v0, -v2, v0, v2
	v_cmp_gt_f32_e32 vcc, 0, v2
	v_mul_f32_e32 v1, 0xbf38aa3b, v1
	v_exp_f32_e32 v1, v1
	v_cndmask_b32_e32 v0, v0, v4, vcc
	v_mul_f32_e32 v4, v68, v0
	v_fmamk_f32 v0, v6, 0x3f07dc22, v241
	v_fmaak_f32 v0, v6, v0, 0x3f35f0e3
	v_fmaak_f32 v0, v6, v0, 0xbe11a98e
	v_fmaak_f32 v0, v6, v0, 0x3e027906
	v_mul_f32_e32 v0, v6, v0
	v_mul_f32_e32 v0, v1, v0
	v_mul_f32_e32 v1, v3, v0
	v_fma_f32 v0, -v3, v0, v3
	v_cmp_gt_f32_e32 vcc, 0, v3
	v_cvt_pk_bf16_f32 v2, v66, v5
	s_nop 1
	v_cndmask_b32_e32 v0, v0, v1, vcc
	v_mul_f32_e32 v3, v69, v0
	v_cvt_pk_bf16_f32 v0, v130, v114
	v_cvt_pk_bf16_f32 v1, v115, v104
	v_cvt_pk_bf16_f32 v3, v4, v3
	global_store_dwordx4 v[160:161], v[0:3], off offset:256 sc1
	s_waitcnt vmcnt(1)
;     static __device__ __forceinline__ void unpack8(const u32x4 q, float (&x)[8]) { x[0] = bflo(q.x); x[1] = bfhi(q.x); x[2] = bflo(q.y); x[3] = bfhi(q.y); x[4] = bflo(q.z); x[5] = bfhi(q.z); x[6] = bflo(q.w); x[7] = bfhi(q.w); }
;     __device__ __forceinline__ void operator()(EPI_ARGS) const {
;     ...
;                     for (int t = 0; t < 1; ++t) { const int row = row0 + ai * 128 + (mp + t) * 16; const int r1 = row > 0 ? row - 1 : 0, r2 = row > 1 ? row - 2 : 0;
;                         q2[t] = *(const u32x4*)(up + (size_t)row * DFF + col); q1[t] = *(const u32x4*)(up + (size_t)r1 * DFF + col); q0[t] = *(const u32x4*)(up + (size_t)r2 * DFF + col); }
;                     __builtin_amdgcn_sched_barrier(0);
; #pragma unroll
;                     for (int t = 0; t < 1; ++t) { const int m = mp + t, row = row0 + ai * 128 + m * 16;
;                         const int i = row < TP ? row : ((row - TP) & 15); const int sidx = row < TP ? 0 : ((row - TP) >> 4);
;                         float x0[8], x1[8], x2[8]; unpack8(q0[t], x0); unpack8(q1[t], x1); unpack8(q2[t], x2);
;                         if (i < 2) {
;                             const bool smp = row >= TP; const float* p0 = cs + ((size_t)sidx * 2 + i) * DFF + col; const float* p1 = cs + ((size_t)sidx * 2 + 1) * DFF + col;
; #pragma unroll
;                             for (int e = 0; e < 8; ++e) { x0[e] = smp ? p0[e] : 0.f; if (i == 0) x1[e] = smp ? p1[e] : 0.f; } }
	v_mov_b64_e32 v[66:67], v[196:197]
	v_mov_b64_e32 v[68:69], v[198:199]
	v_mov_b64_e32 v[4:5], v[200:201]
	v_mov_b64_e32 v[6:7], v[202:203]
	v_mov_b64_e32 v[0:1], v[242:243]
	v_mov_b64_e32 v[2:3], v[244:245]
	v_lshlrev_b32_e32 v98, 16, v0
	v_and_b32_e32 v99, 0xffff0000, v0
	v_lshlrev_b32_e32 v100, 16, v1
	v_and_b32_e32 v101, 0xffff0000, v1
	v_lshlrev_b32_e32 v104, 16, v2
	v_and_b32_e32 v105, 0xffff0000, v2
	v_lshlrev_b32_e32 v108, 16, v3
	v_and_b32_e32 v109, 0xffff0000, v3
	v_lshlrev_b32_e32 v0, 16, v4
	v_and_b32_e32 v1, 0xffff0000, v4
	v_lshlrev_b32_e32 v2, 16, v5
	v_and_b32_e32 v3, 0xffff0000, v5
	v_lshlrev_b32_e32 v4, 16, v6
	v_and_b32_e32 v5, 0xffff0000, v6
	v_lshlrev_b32_e32 v6, 16, v7
	v_and_b32_e32 v7, 0xffff0000, v7
	s_and_saveexec_b64 s[0:1], s[60:61]
	s_cbranch_execz .LBB0_1625
	s_add_i32 s14, s5, 0xffffe010
	s_ashr_i32 s14, s14, 4
	v_mov_b32_e32 v98, s14
	v_cndmask_b32_e64 v100, v98, 0, s[54:55]
	v_ashrrev_i32_e32 v101, 31, v100
	v_lshl_add_u64 v[98:99], v[100:101], 1, v[158:159]
	v_mov_b64_e32 v[104:105], s[68:69]
	v_mad_u64_u32 v[104:105], s[14:15], v98, s13, v[104:105]
	v_mad_i32_i24 v105, v99, s13, v105
	v_lshl_add_u64 v[114:115], v[184:185], 2, v[104:105]
	v_mov_b32_e32 v98, 0
	s_and_saveexec_b64 s[14:15], s[40:41]
	s_cbranch_execz .LBB0_1578
	global_load_dword v98, v[114:115], off offset:512

; __device__ __forceinline__ unsigned pk2(float lo, float hi) { unsigned r; asm("v_cvt_pk_bf16_f32 %0, %1, %2" : "=v"(r) : "v"(lo), "v"(hi)); return r; }
; __device__ __forceinline__ float gelu_f(float v) {
;     const float av = fabsf(v), d = av * 0.2316418882f + 1.0f;
;     const float t = __builtin_amdgcn_rcpf(d);
;     float q = t * 0.5307027145f + (-0.7265760135f); q = q * t + 0.7107068705f; q = q * t + (-0.142248368f); q = q * t + 0.127414796f; q = q * t;
;     const float e = __builtin_amdgcn_exp2f(v * v * (-0.72134752044f));
;     const float m = v * (q * e);
;     return v < 0.f ? m : v - m;
;     __device__ __forceinline__ void operator()(EPI_ARGS) const {
;     ...
;                     for (int t = 0; t < 1; ++t) { const int row = row0 + ai * 128 + (mp + t) * 16; const int r1 = row > 0 ? row - 1 : 0, r2 = row > 1 ? row - 2 : 0;
;                         q2[t] = *(const u32x4*)(up + (size_t)row * DFF + col); q1[t] = *(const u32x4*)(up + (size_t)r1 * DFF + col); q0[t] = *(const u32x4*)(up + (size_t)r2 * DFF + col); }
;                     __builtin_amdgcn_sched_barrier(0);
; #pragma unroll
;                     for (int t = 0; t < 1; ++t) { const int m = mp + t, row = row0 + ai * 128 + m * 16;
;                         const int i = row < TP ? row : ((row - TP) & 15); const int sidx = row < TP ? 0 : ((row - TP) >> 4);
;                         float x0[8], x1[8], x2[8]; unpack8(q0[t], x0); unpack8(q1[t], x1); unpack8(q2[t], x2);
;                         if (i < 2) {
;                             const bool smp = row >= TP; const float* p0 = cs + ((size_t)sidx * 2 + i) * DFF + col; const float* p1 = cs + ((size_t)sidx * 2 + 1) * DFF + col;
; #pragma unroll
;                             for (int e = 0; e < 8; ++e) { x0[e] = smp ? p0[e] : 0.f; if (i == 0) x1[e] = smp ? p1[e] : 0.f; } }
;                         float r[8];
; #pragma unroll
;                         for (int e = 0; e < 8; ++e) { const float cv = bb[e] + x0[e] * w0[e] + x1[e] * w1[e] + x2[e] * w2[e]; r[e] = gelu_f(cv) * acc[ai][bj][m][e >> 2][e & 3]; }
;                         u32x4 w; w.x = pk2(r[0], r[1]); w.y = pk2(r[2], r[3]); w.z = pk2(r[4], r[5]); w.w = pk2(r[6], r[7]);
;                         *(u32x4*)(act + (size_t)row * DFF + col) = w; } } } }
.LBB0_1625:
	s_or_b64 exec, exec, s[0:1]
	v_lshlrev_b32_e32 v112, 16, v66
	v_and_b32_e32 v66, 0xffff0000, v66
	v_lshlrev_b32_e32 v114, 16, v67
	v_and_b32_e32 v116, 0xffff0000, v67
	s_waitcnt vmcnt(1)
	v_add_u32_e32 v240, 32, v232
	v_mov_b64_e32 v[238:239], s[30:31]
	v_mad_i64_i32 v[238:239], s[0:1], v240, s76, v[238:239]
	v_lshl_add_u64 v[238:239], v[238:239], 0, v[186:187]
	global_load_dwordx4 v[196:199], v[238:239], off offset:256
	v_add_u32_e32 v240, -1, v240
	v_mov_b64_e32 v[246:247], s[30:31]
	v_mad_i64_i32 v[246:247], s[0:1], v240, s76, v[246:247]
	v_lshl_add_u64 v[246:247], v[246:247], 0, v[186:187]
	global_load_dwordx4 v[200:203], v[246:247], off offset:256
	v_add_u32_e32 v240, -1, v240
	v_mov_b64_e32 v[238:239], s[30:31]
	v_mad_i64_i32 v[238:239], s[0:1], v240, s76, v[238:239]
	v_lshl_add_u64 v[238:239], v[238:239], 0, v[186:187]
	global_load_dwordx4 v[242:245], v[238:239], off offset:256
	v_mov_b32_e32 v113, v0
	v_mov_b32_e32 v67, v1
	v_pk_mul_f32 v[112:113], v[106:107], v[112:113]
	v_pk_mul_f32 v[0:1], v[90:91], v[66:67]
	v_pk_fma_f32 v[66:67], v[86:87], v[98:99], v[94:95]
	v_mov_b32_e32 v98, v113
	v_mov_b32_e32 v99, v1
	v_pk_add_f32 v[66:67], v[98:99], v[66:67]
	v_mov_b32_e32 v113, v0
	v_pk_add_f32 v[0:1], v[112:113], v[66:67]
	v_lshlrev_b32_e32 v118, 16, v68
	v_fma_f32 v66, |v0|, s84, 1.0
	v_rcp_f32_e32 v67, v66
	v_pk_mul_f32 v[112:113], v[0:1], v[0:1]
	v_and_b32_e32 v66, 0xffff0000, v68
	v_lshlrev_b32_e32 v68, 16, v69
	v_and_b32_e32 v98, 0xffff0000, v69
	v_fmamk_f32 v69, v67, 0x3f07dc22, v241
	v_mul_f32_e32 v99, 0xbf38aa3b, v112
	v_fmaak_f32 v69, v67, v69, 0x3f35f0e3
	v_exp_f32_e32 v99, v99
	v_fmaak_f32 v69, v67, v69, 0xbe11a98e
	v_fmaak_f32 v69, v67, v69, 0x3e027906
	v_mul_f32_e32 v67, v67, v69
	v_mul_f32_e32 v67, v99, v67
	v_fma_f32 v99, |v1|, s84, 1.0
	v_rcp_f32_e32 v99, v99
	v_mul_f32_e32 v69, v0, v67
	v_fma_f32 v67, -v0, v67, v0
	v_cmp_gt_f32_e32 vcc, 0, v0
	v_mov_b32_e32 v115, v2
	v_mov_b32_e32 v117, v3
	v_cndmask_b32_e32 v0, v67, v69, vcc
	v_mul_f32_e32 v120, v62, v0
	v_mul_f32_e32 v62, 0xbf38aa3b, v113
	v_pk_mul_f32 v[112:113], v[102:103], v[114:115]
	v_pk_mul_f32 v[2:3], v[92:93], v[116:117]
	v_fmamk_f32 v0, v99, 0x3f07dc22, v241
	v_pk_fma_f32 v[100:101], v[88:89], v[100:101], v[96:97]
	v_mov_b32_e32 v114, v113
	v_mov_b32_e32 v115, v3
	v_fmaak_f32 v0, v99, v0, 0x3f35f0e3
	v_exp_f32_e32 v62, v62
	v_pk_add_f32 v[100:101], v[114:115], v[100:101]
	v_mov_b32_e32 v113, v2
	v_fmaak_f32 v0, v99, v0, 0xbe11a98e
	v_pk_add_f32 v[2:3], v[112:113], v[100:101]
	v_fmaak_f32 v0, v99, v0, 0x3e027906
	v_fma_f32 v67, |v2|, s84, 1.0
	v_mul_f32_e32 v0, v99, v0
	v_rcp_f32_e32 v67, v67
	v_mul_f32_e32 v0, v62, v0
	v_mul_f32_e32 v62, v1, v0
	v_fma_f32 v0, -v1, v0, v1
	v_cmp_gt_f32_e32 vcc, 0, v1
	v_mov_b32_e32 v119, v4
	v_mov_b32_e32 v99, v7
	v_cndmask_b32_e32 v0, v0, v62, vcc
	v_mul_f32_e32 v100, v63, v0
	v_fmamk_f32 v0, v67, 0x3f07dc22, v241
	v_fmaak_f32 v62, v67, v0, 0x3f35f0e3
	v_pk_mul_f32 v[0:1], v[2:3], v[2:3]
	v_fmaak_f32 v62, v67, v62, 0xbe11a98e
	v_mul_f32_e32 v0, 0xbf38aa3b, v0
	v_exp_f32_e32 v0, v0
	v_fmaak_f32 v62, v67, v62, 0x3e027906
	v_fma_f32 v63, |v3|, s84, 1.0
	v_mul_f32_e32 v62, v67, v62
	v_rcp_f32_e32 v63, v63
	v_mul_f32_e32 v0, v0, v62
	v_mul_f32_e32 v62, v2, v0
	v_fma_f32 v0, -v2, v0, v2
	v_cmp_gt_f32_e32 vcc, 0, v2
	v_mul_f32_e32 v1, 0xbf38aa3b, v1
	v_exp_f32_e32 v1, v1
	v_cndmask_b32_e32 v0, v0, v62, vcc
	v_mul_f32_e32 v64, v64, v0
	v_fmamk_f32 v0, v63, 0x3f07dc22, v241
	v_fmaak_f32 v0, v63, v0, 0x3f35f0e3
	v_fmaak_f32 v0, v63, v0, 0xbe11a98e
	v_fmaak_f32 v0, v63, v0, 0x3e027906
	v_mul_f32_e32 v0, v63, v0
	v_mul_f32_e32 v0, v1, v0
	v_mov_b32_e32 v67, v5
	v_mul_f32_e32 v2, v3, v0
	v_fma_f32 v69, -v3, v0, v3
	v_pk_mul_f32 v[0:1], v[70:71], v[118:119]
	v_pk_mul_f32 v[4:5], v[78:79], v[66:67]
	v_pk_fma_f32 v[62:63], v[74:75], v[104:105], v[82:83]
	v_mov_b32_e32 v66, v1
	v_mov_b32_e32 v67, v5
	v_pk_add_f32 v[62:63], v[66:67], v[62:63]
	v_mov_b32_e32 v1, v4
	v_pk_add_f32 v[0:1], v[0:1], v[62:63]
	v_cmp_gt_f32_e32 vcc, 0, v3
	v_fma_f32 v4, |v0|, s84, 1.0
	v_rcp_f32_e32 v4, v4
	v_cndmask_b32_e32 v2, v69, v2, vcc
	v_mul_f32_e32 v65, v65, v2
	v_cmp_gt_f32_e32 vcc, 0, v0
	v_fmamk_f32 v2, v4, 0x3f07dc22, v241
	v_fmaak_f32 v5, v4, v2, 0x3f35f0e3
	v_pk_mul_f32 v[2:3], v[0:1], v[0:1]
	v_fmaak_f32 v5, v4, v5, 0xbe11a98e
	v_mul_f32_e32 v2, 0xbf38aa3b, v2
	v_exp_f32_e32 v2, v2
	v_fmaak_f32 v5, v4, v5, 0x3e027906
	v_mul_f32_e32 v4, v4, v5
	v_fma_f32 v5, |v1|, s84, 1.0
	v_rcp_f32_e32 v5, v5
	v_mul_f32_e32 v2, v2, v4
	v_mul_f32_e32 v4, v0, v2
	v_fma_f32 v2, -v0, v2, v0
	v_cndmask_b32_e32 v0, v2, v4, vcc
	v_mul_f32_e32 v58, v58, v0
	v_fmamk_f32 v0, v5, 0x3f07dc22, v241
	v_mul_f32_e32 v2, 0xbf38aa3b, v3
	v_fmaak_f32 v0, v5, v0, 0x3f35f0e3
	v_exp_f32_e32 v2, v2
	v_fmaak_f32 v0, v5, v0, 0xbe11a98e
	v_fmaak_f32 v0, v5, v0, 0x3e027906
	v_mul_f32_e32 v0, v5, v0
	v_mov_b32_e32 v69, v6
	v_mul_f32_e32 v0, v2, v0
	v_pk_mul_f32 v[2:3], v[72:73], v[68:69]
	v_pk_mul_f32 v[4:5], v[80:81], v[98:99]
	v_pk_fma_f32 v[6:7], v[76:77], v[108:109], v[84:85]
	v_mov_b32_e32 v62, v3
	v_mov_b32_e32 v63, v5
	v_pk_add_f32 v[6:7], v[62:63], v[6:7]
	v_mov_b32_e32 v3, v4
	v_pk_add_f32 v[2:3], v[2:3], v[6:7]
	v_mul_f32_e32 v66, v1, v0
	v_fma_f32 v4, |v2|, s84, 1.0
	v_rcp_f32_e32 v4, v4
	v_fma_f32 v0, -v1, v0, v1
	v_cmp_gt_f32_e32 vcc, 0, v1
	s_nop 1
	v_cndmask_b32_e32 v0, v0, v66, vcc
	v_mul_f32_e32 v5, v59, v0
	v_fmamk_f32 v0, v4, 0x3f07dc22, v241
	v_fmaak_f32 v6, v4, v0, 0x3f35f0e3
	v_pk_mul_f32 v[0:1], v[2:3], v[2:3]
	v_fmaak_f32 v6, v4, v6, 0xbe11a98e
	v_mul_f32_e32 v0, 0xbf38aa3b, v0
	v_exp_f32_e32 v0, v0
	v_fmaak_f32 v6, v4, v6, 0x3e027906
	v_mul_f32_e32 v4, v4, v6
	v_fma_f32 v6, |v3|, s84, 1.0
	v_rcp_f32_e32 v6, v6
	v_mul_f32_e32 v0, v0, v4
	v_mul_f32_e32 v4, v2, v0
	v_fma_f32 v0, -v2, v0, v2
	v_cmp_gt_f32_e32 vcc, 0, v2
	v_mul_f32_e32 v1, 0xbf38aa3b, v1
	v_exp_f32_e32 v1, v1
	v_cndmask_b32_e32 v0, v0, v4, vcc
	v_mul_f32_e32 v4, v60, v0
	v_fmamk_f32 v0, v6, 0x3f07dc22, v241
	v_fmaak_f32 v0, v6, v0, 0x3f35f0e3
	v_fmaak_f32 v0, v6, v0, 0xbe11a98e
	v_fmaak_f32 v0, v6, v0, 0x3e027906
	v_mul_f32_e32 v0, v6, v0
	v_mul_f32_e32 v0, v1, v0
	v_mul_f32_e32 v1, v3, v0
	v_fma_f32 v0, -v3, v0, v3
	v_cmp_gt_f32_e32 vcc, 0, v3
	v_cvt_pk_bf16_f32 v2, v58, v5
	s_nop 1
	v_cndmask_b32_e32 v0, v0, v1, vcc
	v_mul_f32_e32 v3, v61, v0
	v_cvt_pk_bf16_f32 v0, v120, v100
	v_cvt_pk_bf16_f32 v1, v64, v65
	v_cvt_pk_bf16_f32 v3, v4, v3
	global_store_dwordx4 v[152:153], v[0:3], off offset:256 sc1
	s_waitcnt vmcnt(1)
;     static __device__ __forceinline__ void unpack8(const u32x4 q, float (&x)[8]) { x[0] = bflo(q.x); x[1] = bfhi(q.x); x[2] = bflo(q.y); x[3] = bfhi(q.y); x[4] = bflo(q.z); x[5] = bfhi(q.z); x[6] = bflo(q.w); x[7] = bfhi(q.w); }
;     __device__ __forceinline__ void operator()(EPI_ARGS) const {
;     ...
;                     for (int t = 0; t < 1; ++t) { const int row = row0 + ai * 128 + (mp + t) * 16; const int r1 = row > 0 ? row - 1 : 0, r2 = row > 1 ? row - 2 : 0;
;                         q2[t] = *(const u32x4*)(up + (size_t)row * DFF + col); q1[t] = *(const u32x4*)(up + (size_t)r1 * DFF + col); q0[t] = *(const u32x4*)(up + (size_t)r2 * DFF + col); }
;                     __builtin_amdgcn_sched_barrier(0);
; #pragma unroll
;                     for (int t = 0; t < 1; ++t) { const int m = mp + t, row = row0 + ai * 128 + m * 16;
;                         const int i = row < TP ? row : ((row - TP) & 15); const int sidx = row < TP ? 0 : ((row - TP) >> 4);
;                         float x0[8], x1[8], x2[8]; unpack8(q0[t], x0); unpack8(q1[t], x1); unpack8(q2[t], x2);
;                         if (i < 2) {
;                             const bool smp = row >= TP; const float* p0 = cs + ((size_t)sidx * 2 + i) * DFF + col; const float* p1 = cs + ((size_t)sidx * 2 + 1) * DFF + col;
; #pragma unroll
;                             for (int e = 0; e < 8; ++e) { x0[e] = smp ? p0[e] : 0.f; if (i == 0) x1[e] = smp ? p1[e] : 0.f; } }
	v_mov_b64_e32 v[58:59], v[196:197]
	v_mov_b64_e32 v[60:61], v[198:199]
	v_mov_b64_e32 v[4:5], v[200:201]
	v_mov_b64_e32 v[6:7], v[202:203]
	v_mov_b64_e32 v[0:1], v[242:243]
	v_mov_b64_e32 v[2:3], v[244:245]
	v_lshlrev_b32_e32 v62, 16, v0
	v_and_b32_e32 v63, 0xffff0000, v0
	v_lshlrev_b32_e32 v64, 16, v1
	v_and_b32_e32 v65, 0xffff0000, v1
	v_lshlrev_b32_e32 v66, 16, v2
	v_and_b32_e32 v67, 0xffff0000, v2
	v_lshlrev_b32_e32 v68, 16, v3
	v_and_b32_e32 v69, 0xffff0000, v3
	v_lshlrev_b32_e32 v0, 16, v4
	v_and_b32_e32 v1, 0xffff0000, v4
	v_lshlrev_b32_e32 v2, 16, v5
	v_and_b32_e32 v3, 0xffff0000, v5
	v_lshlrev_b32_e32 v4, 16, v6
	v_and_b32_e32 v5, 0xffff0000, v6
	v_lshlrev_b32_e32 v6, 16, v7
	v_and_b32_e32 v7, 0xffff0000, v7
	s_and_saveexec_b64 s[0:1], s[64:65]
	s_mov_b32 s97, 0x7f807f81
	s_movk_i32 s90, 0xfeff
	s_movk_i32 s42, 0x410
	s_cbranch_execz .LBB0_1675
	s_add_i32 s14, s5, 0xffffe020
	s_ashr_i32 s14, s14, 4
	v_mov_b32_e32 v62, s14
	v_cndmask_b32_e64 v64, v62, 0, s[58:59]
	v_ashrrev_i32_e32 v65, 31, v64
	v_lshl_add_u64 v[62:63], v[64:65], 1, v[150:151]
	v_mov_b64_e32 v[66:67], s[68:69]
	v_mad_u64_u32 v[66:67], s[14:15], v62, s13, v[66:67]
	v_mad_i32_i24 v67, v63, s13, v67
	v_lshl_add_u64 v[100:101], v[184:185], 2, v[66:67]
	v_mov_b32_e32 v62, 0
	s_and_saveexec_b64 s[14:15], s[44:45]
	s_cbranch_execz .LBB0_1628
	global_load_dword v62, v[100:101], off offset:512

; __device__ __forceinline__ unsigned pk2(float lo, float hi) { unsigned r; asm("v_cvt_pk_bf16_f32 %0, %1, %2" : "=v"(r) : "v"(lo), "v"(hi)); return r; }
; __device__ __forceinline__ float gelu_f(float v) {
;     const float av = fabsf(v), d = av * 0.2316418882f + 1.0f;
;     const float t = __builtin_amdgcn_rcpf(d);
;     float q = t * 0.5307027145f + (-0.7265760135f); q = q * t + 0.7107068705f; q = q * t + (-0.142248368f); q = q * t + 0.127414796f; q = q * t;
;     const float e = __builtin_amdgcn_exp2f(v * v * (-0.72134752044f));
;     const float m = v * (q * e);
;     return v < 0.f ? m : v - m;
;     __device__ __forceinline__ void operator()(EPI_ARGS) const {
;     ...
;                     for (int t = 0; t < 1; ++t) { const int row = row0 + ai * 128 + (mp + t) * 16; const int r1 = row > 0 ? row - 1 : 0, r2 = row > 1 ? row - 2 : 0;
;                         q2[t] = *(const u32x4*)(up + (size_t)row * DFF + col); q1[t] = *(const u32x4*)(up + (size_t)r1 * DFF + col); q0[t] = *(const u32x4*)(up + (size_t)r2 * DFF + col); }
;                     __builtin_amdgcn_sched_barrier(0);
; #pragma unroll
;                     for (int t = 0; t < 1; ++t) { const int m = mp + t, row = row0 + ai * 128 + m * 16;
;                         const int i = row < TP ? row : ((row - TP) & 15); const int sidx = row < TP ? 0 : ((row - TP) >> 4);
;                         float x0[8], x1[8], x2[8]; unpack8(q0[t], x0); unpack8(q1[t], x1); unpack8(q2[t], x2);
;                         if (i < 2) {
;                             const bool smp = row >= TP; const float* p0 = cs + ((size_t)sidx * 2 + i) * DFF + col; const float* p1 = cs + ((size_t)sidx * 2 + 1) * DFF + col;
; #pragma unroll
;                             for (int e = 0; e < 8; ++e) { x0[e] = smp ? p0[e] : 0.f; if (i == 0) x1[e] = smp ? p1[e] : 0.f; } }
;                         float r[8];
; #pragma unroll
;                         for (int e = 0; e < 8; ++e) { const float cv = bb[e] + x0[e] * w0[e] + x1[e] * w1[e] + x2[e] * w2[e]; r[e] = gelu_f(cv) * acc[ai][bj][m][e >> 2][e & 3]; }
;                         u32x4 w; w.x = pk2(r[0], r[1]); w.y = pk2(r[2], r[3]); w.z = pk2(r[4], r[5]); w.w = pk2(r[6], r[7]);
;                         *(u32x4*)(act + (size_t)row * DFF + col) = w; } } } }
.LBB0_1675:
	s_or_b64 exec, exec, s[0:1]
	v_lshlrev_b32_e32 v98, 16, v58
	v_and_b32_e32 v58, 0xffff0000, v58
	v_lshlrev_b32_e32 v100, 16, v59
	v_and_b32_e32 v104, 0xffff0000, v59
	s_waitcnt vmcnt(1)
	v_add_u32_e32 v240, 48, v232
	v_mov_b64_e32 v[238:239], s[30:31]
	v_mad_i64_i32 v[238:239], s[0:1], v240, s76, v[238:239]
	v_lshl_add_u64 v[238:239], v[238:239], 0, v[186:187]
	global_load_dwordx4 v[196:199], v[238:239], off offset:256
	v_add_u32_e32 v240, -1, v240
	v_mov_b64_e32 v[246:247], s[30:31]
	v_mad_i64_i32 v[246:247], s[0:1], v240, s76, v[246:247]
	v_lshl_add_u64 v[246:247], v[246:247], 0, v[186:187]
	global_load_dwordx4 v[200:203], v[246:247], off offset:256
	v_add_u32_e32 v240, -1, v240
	v_mov_b64_e32 v[238:239], s[30:31]
	v_mad_i64_i32 v[238:239], s[0:1], v240, s76, v[238:239]
	v_lshl_add_u64 v[238:239], v[238:239], 0, v[186:187]
	global_load_dwordx4 v[242:245], v[238:239], off offset:256
	v_mov_b32_e32 v99, v0
	v_mov_b32_e32 v59, v1
	v_pk_mul_f32 v[98:99], v[106:107], v[98:99]
	v_pk_mul_f32 v[0:1], v[90:91], v[58:59]
	v_pk_fma_f32 v[58:59], v[86:87], v[62:63], v[94:95]
	v_mov_b32_e32 v62, v99
	v_mov_b32_e32 v63, v1
	v_pk_add_f32 v[58:59], v[62:63], v[58:59]
	v_mov_b32_e32 v99, v0
	v_pk_add_f32 v[0:1], v[98:99], v[58:59]
	v_lshlrev_b32_e32 v108, 16, v60
	v_fma_f32 v58, |v0|, s84, 1.0
	v_rcp_f32_e32 v59, v58
	v_pk_mul_f32 v[98:99], v[0:1], v[0:1]
	v_and_b32_e32 v58, 0xffff0000, v60
	v_lshlrev_b32_e32 v60, 16, v61
	v_and_b32_e32 v62, 0xffff0000, v61
	v_fmamk_f32 v61, v59, 0x3f07dc22, v241
	v_mul_f32_e32 v63, 0xbf38aa3b, v98
	v_fmaak_f32 v61, v59, v61, 0x3f35f0e3
	v_exp_f32_e32 v63, v63
	v_fmaak_f32 v61, v59, v61, 0xbe11a98e
	v_fmaak_f32 v61, v59, v61, 0x3e027906
	v_mul_f32_e32 v59, v59, v61
	v_mul_f32_e32 v59, v63, v59
	v_fma_f32 v63, |v1|, s84, 1.0
	v_rcp_f32_e32 v63, v63
	v_mul_f32_e32 v61, v0, v59
	v_fma_f32 v59, -v0, v59, v0
	v_cmp_gt_f32_e32 vcc, 0, v0
	v_mov_b32_e32 v101, v2
	v_mov_b32_e32 v105, v3
	v_cndmask_b32_e32 v0, v59, v61, vcc
	v_mul_f32_e32 v112, v54, v0
	v_mul_f32_e32 v54, 0xbf38aa3b, v99
	v_pk_mul_f32 v[98:99], v[102:103], v[100:101]
	v_pk_mul_f32 v[2:3], v[92:93], v[104:105]
	v_fmamk_f32 v0, v63, 0x3f07dc22, v241
	v_pk_fma_f32 v[64:65], v[88:89], v[64:65], v[96:97]
	v_mov_b32_e32 v100, v99
	v_mov_b32_e32 v101, v3
	v_fmaak_f32 v0, v63, v0, 0x3f35f0e3
	v_exp_f32_e32 v54, v54
	v_pk_add_f32 v[64:65], v[100:101], v[64:65]
	v_mov_b32_e32 v99, v2
	v_fmaak_f32 v0, v63, v0, 0xbe11a98e
	v_pk_add_f32 v[2:3], v[98:99], v[64:65]
	v_fmaak_f32 v0, v63, v0, 0x3e027906
	v_fma_f32 v59, |v2|, s84, 1.0
	v_mul_f32_e32 v0, v63, v0
	v_rcp_f32_e32 v59, v59
	v_mul_f32_e32 v0, v54, v0
	v_mul_f32_e32 v54, v1, v0
	v_fma_f32 v0, -v1, v0, v1
	v_cmp_gt_f32_e32 vcc, 0, v1
	v_mov_b32_e32 v109, v4
	v_mov_b32_e32 v63, v7
	v_cndmask_b32_e32 v0, v0, v54, vcc
	v_mul_f32_e32 v64, v55, v0
	v_fmamk_f32 v0, v59, 0x3f07dc22, v241
	v_fmaak_f32 v54, v59, v0, 0x3f35f0e3
	v_pk_mul_f32 v[0:1], v[2:3], v[2:3]
	v_fmaak_f32 v54, v59, v54, 0xbe11a98e
	v_mul_f32_e32 v0, 0xbf38aa3b, v0
	v_exp_f32_e32 v0, v0
	v_fmaak_f32 v54, v59, v54, 0x3e027906
	v_fma_f32 v55, |v3|, s84, 1.0
	v_mul_f32_e32 v54, v59, v54
	v_rcp_f32_e32 v55, v55
	v_mul_f32_e32 v0, v0, v54
	v_mul_f32_e32 v54, v2, v0
	v_fma_f32 v0, -v2, v0, v2
	v_cmp_gt_f32_e32 vcc, 0, v2
	v_mul_f32_e32 v1, 0xbf38aa3b, v1
	v_exp_f32_e32 v1, v1
	v_cndmask_b32_e32 v0, v0, v54, vcc
	v_mul_f32_e32 v56, v56, v0
	v_fmamk_f32 v0, v55, 0x3f07dc22, v241
	v_fmaak_f32 v0, v55, v0, 0x3f35f0e3
	v_fmaak_f32 v0, v55, v0, 0xbe11a98e
	v_fmaak_f32 v0, v55, v0, 0x3e027906
	v_mul_f32_e32 v0, v55, v0
	v_mul_f32_e32 v0, v1, v0
	v_mov_b32_e32 v59, v5
	v_mul_f32_e32 v2, v3, v0
	v_fma_f32 v61, -v3, v0, v3
	v_pk_mul_f32 v[0:1], v[70:71], v[108:109]
	v_pk_mul_f32 v[4:5], v[78:79], v[58:59]
	v_pk_fma_f32 v[54:55], v[74:75], v[66:67], v[82:83]
	v_mov_b32_e32 v58, v1
	v_mov_b32_e32 v59, v5
	v_pk_add_f32 v[54:55], v[58:59], v[54:55]
	v_mov_b32_e32 v1, v4
	v_pk_add_f32 v[0:1], v[0:1], v[54:55]
	v_cmp_gt_f32_e32 vcc, 0, v3
	v_fma_f32 v4, |v0|, s84, 1.0
	v_rcp_f32_e32 v4, v4
	v_cndmask_b32_e32 v2, v61, v2, vcc
	v_mul_f32_e32 v57, v57, v2
	v_cmp_gt_f32_e32 vcc, 0, v0
	v_fmamk_f32 v2, v4, 0x3f07dc22, v241
	v_fmaak_f32 v5, v4, v2, 0x3f35f0e3
	v_pk_mul_f32 v[2:3], v[0:1], v[0:1]
	v_fmaak_f32 v5, v4, v5, 0xbe11a98e
	v_mul_f32_e32 v2, 0xbf38aa3b, v2
	v_exp_f32_e32 v2, v2
	v_fmaak_f32 v5, v4, v5, 0x3e027906
	v_mul_f32_e32 v4, v4, v5
	v_fma_f32 v5, |v1|, s84, 1.0
	v_rcp_f32_e32 v5, v5
	v_mul_f32_e32 v2, v2, v4
	v_mul_f32_e32 v4, v0, v2
	v_fma_f32 v2, -v0, v2, v0
	v_cndmask_b32_e32 v0, v2, v4, vcc
	v_mul_f32_e32 v50, v50, v0
	v_fmamk_f32 v0, v5, 0x3f07dc22, v241
	v_mul_f32_e32 v2, 0xbf38aa3b, v3
	v_fmaak_f32 v0, v5, v0, 0x3f35f0e3
	v_exp_f32_e32 v2, v2
	v_fmaak_f32 v0, v5, v0, 0xbe11a98e
	v_fmaak_f32 v0, v5, v0, 0x3e027906
	v_mul_f32_e32 v0, v5, v0
	v_mov_b32_e32 v61, v6
	v_mul_f32_e32 v0, v2, v0
	v_pk_mul_f32 v[2:3], v[72:73], v[60:61]
	v_pk_mul_f32 v[4:5], v[80:81], v[62:63]
	v_pk_fma_f32 v[6:7], v[76:77], v[68:69], v[84:85]
	v_mov_b32_e32 v54, v3
	v_mov_b32_e32 v55, v5
	v_pk_add_f32 v[6:7], v[54:55], v[6:7]
	v_mov_b32_e32 v3, v4
	v_pk_add_f32 v[2:3], v[2:3], v[6:7]
	v_mul_f32_e32 v58, v1, v0
	v_fma_f32 v4, |v2|, s84, 1.0
	v_rcp_f32_e32 v4, v4
	v_fma_f32 v0, -v1, v0, v1
	v_cmp_gt_f32_e32 vcc, 0, v1
	s_nop 1
	v_cndmask_b32_e32 v0, v0, v58, vcc
	v_mul_f32_e32 v5, v51, v0
	v_fmamk_f32 v0, v4, 0x3f07dc22, v241
	v_fmaak_f32 v6, v4, v0, 0x3f35f0e3
	v_pk_mul_f32 v[0:1], v[2:3], v[2:3]
	v_fmaak_f32 v6, v4, v6, 0xbe11a98e
	v_mul_f32_e32 v0, 0xbf38aa3b, v0
	v_exp_f32_e32 v0, v0
	v_fmaak_f32 v6, v4, v6, 0x3e027906
	v_mul_f32_e32 v4, v4, v6
	v_fma_f32 v6, |v3|, s84, 1.0
	v_rcp_f32_e32 v6, v6
	v_mul_f32_e32 v0, v0, v4
	v_mul_f32_e32 v4, v2, v0
	v_fma_f32 v0, -v2, v0, v2
	v_cmp_gt_f32_e32 vcc, 0, v2
	v_mul_f32_e32 v1, 0xbf38aa3b, v1
	v_exp_f32_e32 v1, v1
	v_cndmask_b32_e32 v0, v0, v4, vcc
	v_mul_f32_e32 v4, v52, v0
	v_fmamk_f32 v0, v6, 0x3f07dc22, v241
	v_fmaak_f32 v0, v6, v0, 0x3f35f0e3
	v_fmaak_f32 v0, v6, v0, 0xbe11a98e
	v_fmaak_f32 v0, v6, v0, 0x3e027906
	v_mul_f32_e32 v0, v6, v0
	v_mul_f32_e32 v0, v1, v0
	v_mul_f32_e32 v1, v3, v0
	v_fma_f32 v0, -v3, v0, v3
	v_cmp_gt_f32_e32 vcc, 0, v3
	v_cvt_pk_bf16_f32 v2, v50, v5
	s_nop 1
	v_cndmask_b32_e32 v0, v0, v1, vcc
	v_mul_f32_e32 v3, v53, v0
	v_cvt_pk_bf16_f32 v0, v112, v64
	v_cvt_pk_bf16_f32 v1, v56, v57
	v_cvt_pk_bf16_f32 v3, v4, v3
	global_store_dwordx4 v[144:145], v[0:3], off offset:256 sc1
	s_waitcnt vmcnt(1)
;     static __device__ __forceinline__ void unpack8(const u32x4 q, float (&x)[8]) { x[0] = bflo(q.x); x[1] = bfhi(q.x); x[2] = bflo(q.y); x[3] = bfhi(q.y); x[4] = bflo(q.z); x[5] = bfhi(q.z); x[6] = bflo(q.w); x[7] = bfhi(q.w); }
;     __device__ __forceinline__ void operator()(EPI_ARGS) const {
;     ...
;                     for (int t = 0; t < 1; ++t) { const int row = row0 + ai * 128 + (mp + t) * 16; const int r1 = row > 0 ? row - 1 : 0, r2 = row > 1 ? row - 2 : 0;
;                         q2[t] = *(const u32x4*)(up + (size_t)row * DFF + col); q1[t] = *(const u32x4*)(up + (size_t)r1 * DFF + col); q0[t] = *(const u32x4*)(up + (size_t)r2 * DFF + col); }
;                     __builtin_amdgcn_sched_barrier(0);
; #pragma unroll
;                     for (int t = 0; t < 1; ++t) { const int m = mp + t, row = row0 + ai * 128 + m * 16;
;                         const int i = row < TP ? row : ((row - TP) & 15); const int sidx = row < TP ? 0 : ((row - TP) >> 4);
;                         float x0[8], x1[8], x2[8]; unpack8(q0[t], x0); unpack8(q1[t], x1); unpack8(q2[t], x2);
;                         if (i < 2) {
;                             const bool smp = row >= TP; const float* p0 = cs + ((size_t)sidx * 2 + i) * DFF + col; const float* p1 = cs + ((size_t)sidx * 2 + 1) * DFF + col;
; #pragma unroll
;                             for (int e = 0; e < 8; ++e) { x0[e] = smp ? p0[e] : 0.f; if (i == 0) x1[e] = smp ? p1[e] : 0.f; } }
	v_mov_b64_e32 v[50:51], v[196:197]
	v_mov_b64_e32 v[52:53], v[198:199]
	v_mov_b64_e32 v[4:5], v[200:201]
	v_mov_b64_e32 v[6:7], v[202:203]
	v_mov_b64_e32 v[0:1], v[242:243]
	v_mov_b64_e32 v[2:3], v[244:245]
	v_lshlrev_b32_e32 v54, 16, v0
	v_and_b32_e32 v55, 0xffff0000, v0
	v_lshlrev_b32_e32 v56, 16, v1
	v_and_b32_e32 v57, 0xffff0000, v1
	v_lshlrev_b32_e32 v58, 16, v2
	v_and_b32_e32 v59, 0xffff0000, v2
	v_lshlrev_b32_e32 v60, 16, v3
	v_and_b32_e32 v61, 0xffff0000, v3
	v_lshlrev_b32_e32 v0, 16, v4
	v_and_b32_e32 v1, 0xffff0000, v4
	v_lshlrev_b32_e32 v2, 16, v5
	v_and_b32_e32 v3, 0xffff0000, v5
	v_lshlrev_b32_e32 v4, 16, v6
	v_and_b32_e32 v5, 0xffff0000, v6
	v_lshlrev_b32_e32 v6, 16, v7
	v_and_b32_e32 v7, 0xffff0000, v7
	s_and_saveexec_b64 s[0:1], s[66:67]
	s_cbranch_execz .LBB0_1725
	s_add_i32 s14, s5, 0xffffe030
	s_ashr_i32 s14, s14, 4
	v_mov_b32_e32 v54, s14
	v_cndmask_b32_e64 v56, v54, 0, s[62:63]
	v_ashrrev_i32_e32 v57, 31, v56
	v_lshl_add_u64 v[54:55], v[56:57], 1, v[142:143]
	v_mov_b64_e32 v[58:59], s[68:69]
	v_mad_u64_u32 v[58:59], s[14:15], v54, s13, v[58:59]
	v_mad_i32_i24 v59, v55, s13, v59
	v_lshl_add_u64 v[64:65], v[184:185], 2, v[58:59]
	v_mov_b32_e32 v54, 0
	s_and_saveexec_b64 s[14:15], s[48:49]
	s_cbranch_execz .LBB0_1678
	global_load_dword v54, v[64:65], off offset:512

; __device__ __forceinline__ unsigned pk2(float lo, float hi) { unsigned r; asm("v_cvt_pk_bf16_f32 %0, %1, %2" : "=v"(r) : "v"(lo), "v"(hi)); return r; }
; __device__ __forceinline__ float gelu_f(float v) {
;     const float av = fabsf(v), d = av * 0.2316418882f + 1.0f;
;     const float t = __builtin_amdgcn_rcpf(d);
;     float q = t * 0.5307027145f + (-0.7265760135f); q = q * t + 0.7107068705f; q = q * t + (-0.142248368f); q = q * t + 0.127414796f; q = q * t;
;     const float e = __builtin_amdgcn_exp2f(v * v * (-0.72134752044f));
;     const float m = v * (q * e);
;     return v < 0.f ? m : v - m;
;     __device__ __forceinline__ void operator()(EPI_ARGS) const {
;     ...
;                     for (int t = 0; t < 1; ++t) { const int row = row0 + ai * 128 + (mp + t) * 16; const int r1 = row > 0 ? row - 1 : 0, r2 = row > 1 ? row - 2 : 0;
;                         q2[t] = *(const u32x4*)(up + (size_t)row * DFF + col); q1[t] = *(const u32x4*)(up + (size_t)r1 * DFF + col); q0[t] = *(const u32x4*)(up + (size_t)r2 * DFF + col); }
;                     __builtin_amdgcn_sched_barrier(0);
; #pragma unroll
;                     for (int t = 0; t < 1; ++t) { const int m = mp + t, row = row0 + ai * 128 + m * 16;
;                         const int i = row < TP ? row : ((row - TP) & 15); const int sidx = row < TP ? 0 : ((row - TP) >> 4);
;                         float x0[8], x1[8], x2[8]; unpack8(q0[t], x0); unpack8(q1[t], x1); unpack8(q2[t], x2);
;                         if (i < 2) {
;                             const bool smp = row >= TP; const float* p0 = cs + ((size_t)sidx * 2 + i) * DFF + col; const float* p1 = cs + ((size_t)sidx * 2 + 1) * DFF + col;
; #pragma unroll
;                             for (int e = 0; e < 8; ++e) { x0[e] = smp ? p0[e] : 0.f; if (i == 0) x1[e] = smp ? p1[e] : 0.f; } }
;                         float r[8];
; #pragma unroll
;                         for (int e = 0; e < 8; ++e) { const float cv = bb[e] + x0[e] * w0[e] + x1[e] * w1[e] + x2[e] * w2[e]; r[e] = gelu_f(cv) * acc[ai][bj][m][e >> 2][e & 3]; }
;                         u32x4 w; w.x = pk2(r[0], r[1]); w.y = pk2(r[2], r[3]); w.z = pk2(r[4], r[5]); w.w = pk2(r[6], r[7]);
;                         *(u32x4*)(act + (size_t)row * DFF + col) = w; } } } }
.LBB0_1725:
	s_or_b64 exec, exec, s[0:1]
	v_lshlrev_b32_e32 v62, 16, v50
	v_and_b32_e32 v50, 0xffff0000, v50
	v_lshlrev_b32_e32 v64, 16, v51
	v_and_b32_e32 v66, 0xffff0000, v51
	s_waitcnt vmcnt(1)
	v_mov_b32_e32 v63, v0
	v_mov_b32_e32 v51, v1
	v_pk_mul_f32 v[62:63], v[106:107], v[62:63]
	v_pk_mul_f32 v[0:1], v[90:91], v[50:51]
	v_pk_fma_f32 v[50:51], v[86:87], v[54:55], v[94:95]
	v_mov_b32_e32 v54, v63
	v_mov_b32_e32 v55, v1
	v_pk_add_f32 v[50:51], v[54:55], v[50:51]
	v_mov_b32_e32 v63, v0
	v_pk_add_f32 v[0:1], v[62:63], v[50:51]
	v_lshlrev_b32_e32 v68, 16, v52
	v_fma_f32 v50, |v0|, s84, 1.0
	v_rcp_f32_e32 v51, v50
	v_pk_mul_f32 v[62:63], v[0:1], v[0:1]
	v_and_b32_e32 v50, 0xffff0000, v52
	v_lshlrev_b32_e32 v52, 16, v53
	v_and_b32_e32 v54, 0xffff0000, v53
	v_fmamk_f32 v53, v51, 0x3f07dc22, v241
	v_mul_f32_e32 v55, 0xbf38aa3b, v62
	v_fmaak_f32 v53, v51, v53, 0x3f35f0e3
	v_exp_f32_e32 v55, v55
	v_fmaak_f32 v53, v51, v53, 0xbe11a98e
	v_fmaak_f32 v53, v51, v53, 0x3e027906
	v_mul_f32_e32 v51, v51, v53
	v_mul_f32_e32 v51, v55, v51
	v_fma_f32 v55, |v1|, s84, 1.0
	v_rcp_f32_e32 v55, v55
	v_mul_f32_e32 v53, v0, v51
	v_fma_f32 v51, -v0, v51, v0
	v_cmp_gt_f32_e32 vcc, 0, v0
	v_mov_b32_e32 v65, v2
	v_mov_b32_e32 v67, v3
	v_cndmask_b32_e32 v0, v51, v53, vcc
	v_mul_f32_e32 v98, v46, v0
	v_mul_f32_e32 v46, 0xbf38aa3b, v63
	v_pk_mul_f32 v[62:63], v[102:103], v[64:65]
	v_pk_mul_f32 v[2:3], v[92:93], v[66:67]
	v_fmamk_f32 v0, v55, 0x3f07dc22, v241
	v_pk_fma_f32 v[56:57], v[88:89], v[56:57], v[96:97]
	v_mov_b32_e32 v64, v63
	v_mov_b32_e32 v65, v3
	v_fmaak_f32 v0, v55, v0, 0x3f35f0e3
	v_exp_f32_e32 v46, v46
	v_pk_add_f32 v[56:57], v[64:65], v[56:57]
	v_mov_b32_e32 v63, v2
	v_fmaak_f32 v0, v55, v0, 0xbe11a98e
	v_pk_add_f32 v[2:3], v[62:63], v[56:57]
	v_fmaak_f32 v0, v55, v0, 0x3e027906
	v_fma_f32 v51, |v2|, s84, 1.0
	v_mul_f32_e32 v0, v55, v0
	v_rcp_f32_e32 v51, v51
	v_mul_f32_e32 v0, v46, v0
	v_mul_f32_e32 v46, v1, v0
	v_fma_f32 v0, -v1, v0, v1
	v_cmp_gt_f32_e32 vcc, 0, v1
	v_mov_b32_e32 v69, v4
	v_mov_b32_e32 v55, v7
	v_cndmask_b32_e32 v0, v0, v46, vcc
	v_mul_f32_e32 v56, v47, v0
	v_fmamk_f32 v0, v51, 0x3f07dc22, v241
	v_fmaak_f32 v46, v51, v0, 0x3f35f0e3
	v_pk_mul_f32 v[0:1], v[2:3], v[2:3]
	v_fmaak_f32 v46, v51, v46, 0xbe11a98e
	v_mul_f32_e32 v0, 0xbf38aa3b, v0
	v_exp_f32_e32 v0, v0
	v_fmaak_f32 v46, v51, v46, 0x3e027906
	v_fma_f32 v47, |v3|, s84, 1.0
	v_mul_f32_e32 v46, v51, v46
	v_rcp_f32_e32 v47, v47
	v_mul_f32_e32 v0, v0, v46
	v_mul_f32_e32 v46, v2, v0
	v_fma_f32 v0, -v2, v0, v2
	v_cmp_gt_f32_e32 vcc, 0, v2
	v_mul_f32_e32 v1, 0xbf38aa3b, v1
	v_exp_f32_e32 v1, v1
	v_cndmask_b32_e32 v0, v0, v46, vcc
	v_mul_f32_e32 v48, v48, v0
	v_fmamk_f32 v0, v47, 0x3f07dc22, v241
	v_fmaak_f32 v0, v47, v0, 0x3f35f0e3
	v_fmaak_f32 v0, v47, v0, 0xbe11a98e
	v_fmaak_f32 v0, v47, v0, 0x3e027906
	v_mul_f32_e32 v0, v47, v0
	v_mul_f32_e32 v0, v1, v0
	v_mov_b32_e32 v51, v5
	v_mul_f32_e32 v2, v3, v0
	v_fma_f32 v53, -v3, v0, v3
	v_pk_mul_f32 v[0:1], v[70:71], v[68:69]
	v_pk_mul_f32 v[4:5], v[78:79], v[50:51]
	v_pk_fma_f32 v[46:47], v[74:75], v[58:59], v[82:83]
	v_mov_b32_e32 v50, v1
	v_mov_b32_e32 v51, v5
	v_pk_add_f32 v[46:47], v[50:51], v[46:47]
	v_mov_b32_e32 v1, v4
	v_pk_add_f32 v[0:1], v[0:1], v[46:47]
	v_cmp_gt_f32_e32 vcc, 0, v3
	v_fma_f32 v4, |v0|, s84, 1.0
	v_rcp_f32_e32 v4, v4
	v_cndmask_b32_e32 v2, v53, v2, vcc
	v_mul_f32_e32 v49, v49, v2
	v_cmp_gt_f32_e32 vcc, 0, v0
	v_fmamk_f32 v2, v4, 0x3f07dc22, v241
	v_fmaak_f32 v5, v4, v2, 0x3f35f0e3
	v_pk_mul_f32 v[2:3], v[0:1], v[0:1]
	v_fmaak_f32 v5, v4, v5, 0xbe11a98e
	v_mul_f32_e32 v2, 0xbf38aa3b, v2
	v_exp_f32_e32 v2, v2
	v_fmaak_f32 v5, v4, v5, 0x3e027906
	v_mul_f32_e32 v4, v4, v5
	v_fma_f32 v5, |v1|, s84, 1.0
	v_rcp_f32_e32 v5, v5
	v_mul_f32_e32 v2, v2, v4
	v_mul_f32_e32 v4, v0, v2
	v_fma_f32 v2, -v0, v2, v0
	v_cndmask_b32_e32 v0, v2, v4, vcc
	v_mul_f32_e32 v42, v42, v0
	v_fmamk_f32 v0, v5, 0x3f07dc22, v241
	v_mul_f32_e32 v2, 0xbf38aa3b, v3
	v_fmaak_f32 v0, v5, v0, 0x3f35f0e3
	v_exp_f32_e32 v2, v2
	v_fmaak_f32 v0, v5, v0, 0xbe11a98e
	v_fmaak_f32 v0, v5, v0, 0x3e027906
	v_mul_f32_e32 v0, v5, v0
	v_mov_b32_e32 v53, v6
	v_mul_f32_e32 v0, v2, v0
	v_pk_mul_f32 v[2:3], v[72:73], v[52:53]
	v_pk_mul_f32 v[4:5], v[80:81], v[54:55]
	v_pk_fma_f32 v[6:7], v[76:77], v[60:61], v[84:85]
	v_mov_b32_e32 v46, v3
	v_mov_b32_e32 v47, v5
	v_pk_add_f32 v[6:7], v[46:47], v[6:7]
	v_mov_b32_e32 v3, v4
	v_pk_add_f32 v[2:3], v[2:3], v[6:7]
	v_mul_f32_e32 v50, v1, v0
	v_fma_f32 v4, |v2|, s84, 1.0
	v_rcp_f32_e32 v4, v4
	v_fma_f32 v0, -v1, v0, v1
	v_cmp_gt_f32_e32 vcc, 0, v1
	v_readlane_b32 s48, v252, 16
	v_readlane_b32 s49, v252, 17
	v_cndmask_b32_e32 v0, v0, v50, vcc
	v_mul_f32_e32 v5, v43, v0
	v_fmamk_f32 v0, v4, 0x3f07dc22, v241
	v_fmaak_f32 v6, v4, v0, 0x3f35f0e3
	v_pk_mul_f32 v[0:1], v[2:3], v[2:3]
	v_fmaak_f32 v6, v4, v6, 0xbe11a98e
	v_mul_f32_e32 v0, 0xbf38aa3b, v0
	v_exp_f32_e32 v0, v0
	v_fmaak_f32 v6, v4, v6, 0x3e027906
	v_mul_f32_e32 v4, v4, v6
	v_fma_f32 v6, |v3|, s84, 1.0
	v_rcp_f32_e32 v6, v6
	v_mul_f32_e32 v0, v0, v4
	v_mul_f32_e32 v4, v2, v0
	v_fma_f32 v0, -v2, v0, v2
	v_cmp_gt_f32_e32 vcc, 0, v2
	v_mul_f32_e32 v1, 0xbf38aa3b, v1
	v_exp_f32_e32 v1, v1
	v_cndmask_b32_e32 v0, v0, v4, vcc
	v_mul_f32_e32 v4, v44, v0
	v_fmamk_f32 v0, v6, 0x3f07dc22, v241
	v_fmaak_f32 v0, v6, v0, 0x3f35f0e3
	v_fmaak_f32 v0, v6, v0, 0xbe11a98e
	v_fmaak_f32 v0, v6, v0, 0x3e027906
	v_mul_f32_e32 v0, v6, v0
	v_mul_f32_e32 v0, v1, v0
	v_mul_f32_e32 v1, v3, v0
	v_fma_f32 v0, -v3, v0, v3
	v_cmp_gt_f32_e32 vcc, 0, v3
	v_readlane_b32 s50, v252, 18
	v_readlane_b32 s51, v252, 19
	v_cndmask_b32_e32 v0, v0, v1, vcc
	v_mul_f32_e32 v3, v45, v0
	s_andn2_b64 vcc, exec, s[8:9]
	v_readlane_b32 s52, v252, 20
	v_readlane_b32 s53, v252, 21
	v_readlane_b32 s56, v252, 24
	v_readlane_b32 s57, v252, 25
	v_readlane_b32 s58, v252, 26
	v_readlane_b32 s59, v252, 27
	v_readlane_b32 s60, v252, 28
	v_readlane_b32 s61, v252, 29
	v_readlane_b32 s62, v252, 30
	v_readlane_b32 s63, v252, 31
	v_cvt_pk_bf16_f32 v0, v98, v56
	v_cvt_pk_bf16_f32 v1, v48, v49
	v_cvt_pk_bf16_f32 v2, v42, v5
	v_cvt_pk_bf16_f32 v3, v4, v3
	global_store_dwordx4 v[134:135], v[0:3], off offset:256 sc1
	v_readlane_b32 s54, v252, 22
	v_readlane_b32 s55, v252, 23
	s_cbranch_vccnz .LBB0_1927
;     static __device__ __forceinline__ void unpack8(const u32x4 q, float (&x)[8]) { x[0] = bflo(q.x); x[1] = bfhi(q.x); x[2] = bflo(q.y); x[3] = bfhi(q.y); x[4] = bflo(q.z); x[5] = bfhi(q.z); x[6] = bflo(q.w); x[7] = bfhi(q.w); }
;     __device__ __forceinline__ void operator()(EPI_ARGS) const {
;     ...
;                     for (int t = 0; t < 1; ++t) { const int row = row0 + ai * 128 + (mp + t) * 16; const int r1 = row > 0 ? row - 1 : 0, r2 = row > 1 ? row - 2 : 0;
;                         q2[t] = *(const u32x4*)(up + (size_t)row * DFF + col); q1[t] = *(const u32x4*)(up + (size_t)r1 * DFF + col); q0[t] = *(const u32x4*)(up + (size_t)r2 * DFF + col); }
;                     __builtin_amdgcn_sched_barrier(0);
; #pragma unroll
;                     for (int t = 0; t < 1; ++t) { const int m = mp + t, row = row0 + ai * 128 + m * 16;
;                         const int i = row < TP ? row : ((row - TP) & 15); const int sidx = row < TP ? 0 : ((row - TP) >> 4);
;                         float x0[8], x1[8], x2[8]; unpack8(q0[t], x0); unpack8(q1[t], x1); unpack8(q2[t], x2);
;                         if (i < 2) {
;                             const bool smp = row >= TP; const float* p0 = cs + ((size_t)sidx * 2 + i) * DFF + col; const float* p1 = cs + ((size_t)sidx * 2 + 1) * DFF + col;
; #pragma unroll
;                             for (int e = 0; e < 8; ++e) { x0[e] = smp ? p0[e] : 0.f; if (i == 0) x1[e] = smp ? p1[e] : 0.f; } }
	v_add_u32_e32 v4, -1, v225
	v_add_u32_e32 v46, -2, v226
	v_mov_b64_e32 v[0:1], s[30:31]
	v_mad_i64_i32 v[2:3], s[0:1], v224, s76, v[0:1]
	v_mad_u64_u32 v[4:5], s[0:1], v4, s76, v[0:1]
	v_mad_u64_u32 v[0:1], s[0:1], v46, s76, v[0:1]
	v_lshl_add_u64 v[2:3], v[2:3], 0, v[186:187]
	v_lshl_add_u64 v[4:5], v[4:5], 0, v[186:187]
	v_lshl_add_u64 v[0:1], v[0:1], 0, v[186:187]
	global_load_dwordx4 v[42:45], v[2:3], off offset:256
	s_nop 0
	global_load_dwordx4 v[4:7], v[4:5], off offset:256
	s_nop 0
	global_load_dwordx4 v[0:3], v[0:1], off offset:256
	s_movk_i32 s0, 0x1f80
	v_cmp_gt_i32_e64 s[0:1], s0, v232
	s_waitcnt vmcnt(0)
	v_lshlrev_b32_e32 v46, 16, v0
	v_and_b32_e32 v47, 0xffff0000, v0
	v_cndmask_b32_e64 v58, v228, v224, s[0:1]
	v_lshlrev_b32_e32 v48, 16, v1
	v_and_b32_e32 v49, 0xffff0000, v1
	v_lshlrev_b32_e32 v50, 16, v2
	v_and_b32_e32 v51, 0xffff0000, v2
	v_lshlrev_b32_e32 v52, 16, v3
	v_and_b32_e32 v53, 0xffff0000, v3
	v_lshlrev_b32_e32 v0, 16, v4
	v_and_b32_e32 v1, 0xffff0000, v4
	v_lshlrev_b32_e32 v2, 16, v5
	v_and_b32_e32 v3, 0xffff0000, v5
	v_lshlrev_b32_e32 v4, 16, v6
	v_and_b32_e32 v5, 0xffff0000, v6
	v_lshlrev_b32_e32 v6, 16, v7
	v_and_b32_e32 v7, 0xffff0000, v7
	v_cmp_gt_i32_e32 vcc, 2, v58
	s_and_saveexec_b64 s[8:9], vcc
	s_cbranch_execz .LBB0_1776
	s_movk_i32 s14, 0x1f7f
	v_cmp_lt_i32_e32 vcc, s14, v232
	s_add_i32 s14, s5, 0xffffe080
	s_ashr_i32 s14, s14, 4
	v_mov_b32_e32 v46, s14
	v_cndmask_b32_e64 v48, v46, 0, s[0:1]
	v_ashrrev_i32_e32 v49, 31, v48
	v_ashrrev_i32_e32 v59, 31, v58
	v_lshl_add_u64 v[46:47], v[48:49], 1, v[58:59]
	v_mov_b64_e32 v[50:51], s[68:69]
	v_mad_u64_u32 v[50:51], s[0:1], v46, s13, v[50:51]
	v_mad_i32_i24 v51, v47, s13, v51
	v_lshl_add_u64 v[56:57], v[184:185], 2, v[50:51]
	v_mov_b32_e32 v46, 0
	s_and_saveexec_b64 s[0:1], vcc
	s_cbranch_execz .LBB0_1729
	global_load_dword v46, v[56:57], off offset:512

;     static __device__ __forceinline__ void unpack8(const u32x4 q, float (&x)[8]) { x[0] = bflo(q.x); x[1] = bfhi(q.x); x[2] = bflo(q.y); x[3] = bfhi(q.y); x[4] = bflo(q.z); x[5] = bfhi(q.z); x[6] = bflo(q.w); x[7] = bfhi(q.w); }
;     __device__ __forceinline__ void operator()(EPI_ARGS) const {
;     ...
;                         q2[t] = *(const u32x4*)(up + (size_t)row * DFF + col); q1[t] = *(const u32x4*)(up + (size_t)r1 * DFF + col); q0[t] = *(const u32x4*)(up + (size_t)r2 * DFF + col); }
;                     __builtin_amdgcn_sched_barrier(0);
; #pragma unroll
;                     for (int t = 0; t < 1; ++t) { const int m = mp + t, row = row0 + ai * 128 + m * 16;
;                         const int i = row < TP ? row : ((row - TP) & 15); const int sidx = row < TP ? 0 : ((row - TP) >> 4);
;                         float x0[8], x1[8], x2[8]; unpack8(q0[t], x0); unpack8(q1[t], x1); unpack8(q2[t], x2);
;                         if (i < 2) {
;                             const bool smp = row >= TP; const float* p0 = cs + ((size_t)sidx * 2 + i) * DFF + col; const float* p1 = cs + ((size_t)sidx * 2 + 1) * DFF + col;
; #pragma unroll
;                             for (int e = 0; e < 8; ++e) { x0[e] = smp ? p0[e] : 0.f; if (i == 0) x1[e] = smp ? p1[e] : 0.f; } }
;                         float r[8];
; #pragma unroll
;                         for (int e = 0; e < 8; ++e) { const float cv = bb[e] + x0[e] * w0[e] + x1[e] * w1[e] + x2[e] * w2[e]; r[e] = gelu_f(cv) * acc[ai][bj][m][e >> 2][e & 3]; }
.LBB0_1776:
	s_or_b64 exec, exec, s[8:9]
	v_lshlrev_b32_e32 v56, 16, v42
	v_and_b32_e32 v42, 0xffff0000, v42
	v_lshlrev_b32_e32 v58, 16, v43
	v_and_b32_e32 v60, 0xffff0000, v43
	s_waitcnt vmcnt(0)
	v_add_u32_e32 v240, 144, v232
	v_mov_b64_e32 v[238:239], s[30:31]
	v_mad_i64_i32 v[238:239], s[0:1], v240, s76, v[238:239]
	v_lshl_add_u64 v[238:239], v[238:239], 0, v[186:187]
	global_load_dwordx4 v[196:199], v[238:239], off offset:256
	v_add_u32_e32 v240, -1, v240
	v_mov_b64_e32 v[246:247], s[30:31]
	v_mad_i64_i32 v[246:247], s[0:1], v240, s76, v[246:247]
	v_lshl_add_u64 v[246:247], v[246:247], 0, v[186:187]
	global_load_dwordx4 v[200:203], v[246:247], off offset:256
	v_add_u32_e32 v240, -1, v240
	v_mov_b64_e32 v[238:239], s[30:31]
	v_mad_i64_i32 v[238:239], s[0:1], v240, s76, v[238:239]
	v_lshl_add_u64 v[238:239], v[238:239], 0, v[186:187]
	global_load_dwordx4 v[242:245], v[238:239], off offset:256
	v_mov_b32_e32 v57, v0
	v_mov_b32_e32 v43, v1
	v_pk_mul_f32 v[56:57], v[106:107], v[56:57]
	v_pk_mul_f32 v[0:1], v[90:91], v[42:43]
	v_pk_fma_f32 v[42:43], v[86:87], v[46:47], v[94:95]
	v_mov_b32_e32 v46, v57
	v_mov_b32_e32 v47, v1
	v_pk_add_f32 v[42:43], v[46:47], v[42:43]
	v_mov_b32_e32 v57, v0
	v_pk_add_f32 v[0:1], v[56:57], v[42:43]
	v_lshlrev_b32_e32 v62, 16, v44
	v_fma_f32 v42, |v0|, s84, 1.0
	v_rcp_f32_e32 v43, v42
	v_pk_mul_f32 v[56:57], v[0:1], v[0:1]
	v_and_b32_e32 v42, 0xffff0000, v44
	v_lshlrev_b32_e32 v44, 16, v45
	v_and_b32_e32 v46, 0xffff0000, v45
	v_fmamk_f32 v45, v43, 0x3f07dc22, v241
	v_mul_f32_e32 v47, 0xbf38aa3b, v56
	v_fmaak_f32 v45, v43, v45, 0x3f35f0e3
	v_exp_f32_e32 v47, v47
	v_fmaak_f32 v45, v43, v45, 0xbe11a98e
	v_fmaak_f32 v45, v43, v45, 0x3e027906
	v_mul_f32_e32 v43, v43, v45
	v_mul_f32_e32 v43, v47, v43
	v_fma_f32 v47, |v1|, s84, 1.0
	v_rcp_f32_e32 v47, v47
	v_mul_f32_e32 v45, v0, v43
	v_fma_f32 v43, -v0, v43, v0
	v_cmp_gt_f32_e32 vcc, 0, v0
	v_mov_b32_e32 v59, v2
	v_mov_b32_e32 v61, v3
	v_cndmask_b32_e32 v0, v43, v45, vcc
	v_mul_f32_e32 v64, v38, v0
	v_mul_f32_e32 v38, 0xbf38aa3b, v57
	v_pk_mul_f32 v[56:57], v[102:103], v[58:59]
	v_pk_mul_f32 v[2:3], v[92:93], v[60:61]
	v_fmamk_f32 v0, v47, 0x3f07dc22, v241
	v_pk_fma_f32 v[48:49], v[88:89], v[48:49], v[96:97]
	v_mov_b32_e32 v58, v57
	v_mov_b32_e32 v59, v3
	v_fmaak_f32 v0, v47, v0, 0x3f35f0e3
	v_exp_f32_e32 v38, v38
	v_pk_add_f32 v[48:49], v[58:59], v[48:49]
	v_mov_b32_e32 v57, v2
	v_fmaak_f32 v0, v47, v0, 0xbe11a98e
	v_pk_add_f32 v[2:3], v[56:57], v[48:49]
	v_fmaak_f32 v0, v47, v0, 0x3e027906
	v_fma_f32 v43, |v2|, s84, 1.0
	v_mul_f32_e32 v0, v47, v0
	v_rcp_f32_e32 v43, v43
	v_mul_f32_e32 v0, v38, v0
	v_mul_f32_e32 v38, v1, v0
	v_fma_f32 v0, -v1, v0, v1
	v_cmp_gt_f32_e32 vcc, 0, v1
	v_mov_b32_e32 v63, v4
	v_mov_b32_e32 v47, v7
	v_cndmask_b32_e32 v0, v0, v38, vcc
	v_mul_f32_e32 v48, v39, v0
	v_fmamk_f32 v0, v43, 0x3f07dc22, v241
	v_fmaak_f32 v38, v43, v0, 0x3f35f0e3
	v_pk_mul_f32 v[0:1], v[2:3], v[2:3]
	v_fmaak_f32 v38, v43, v38, 0xbe11a98e
	v_mul_f32_e32 v0, 0xbf38aa3b, v0
	v_exp_f32_e32 v0, v0
	v_fmaak_f32 v38, v43, v38, 0x3e027906
	v_fma_f32 v39, |v3|, s84, 1.0
	v_mul_f32_e32 v38, v43, v38
	v_rcp_f32_e32 v39, v39
	v_mul_f32_e32 v0, v0, v38
	v_mul_f32_e32 v38, v2, v0
	v_fma_f32 v0, -v2, v0, v2
	v_cmp_gt_f32_e32 vcc, 0, v2
	v_mul_f32_e32 v1, 0xbf38aa3b, v1
	v_exp_f32_e32 v1, v1
	v_cndmask_b32_e32 v0, v0, v38, vcc
	v_mul_f32_e32 v40, v40, v0
	v_fmamk_f32 v0, v39, 0x3f07dc22, v241
	v_fmaak_f32 v0, v39, v0, 0x3f35f0e3
	v_fmaak_f32 v0, v39, v0, 0xbe11a98e
	v_fmaak_f32 v0, v39, v0, 0x3e027906
	v_mul_f32_e32 v0, v39, v0
	v_mul_f32_e32 v0, v1, v0
	v_mov_b32_e32 v43, v5
	v_mul_f32_e32 v2, v3, v0
	v_fma_f32 v45, -v3, v0, v3
	v_pk_mul_f32 v[0:1], v[70:71], v[62:63]
	v_pk_mul_f32 v[4:5], v[78:79], v[42:43]
	v_pk_fma_f32 v[38:39], v[74:75], v[50:51], v[82:83]
	v_mov_b32_e32 v42, v1
	v_mov_b32_e32 v43, v5
	v_pk_add_f32 v[38:39], v[42:43], v[38:39]
	v_mov_b32_e32 v1, v4
	v_pk_add_f32 v[0:1], v[0:1], v[38:39]
	v_cmp_gt_f32_e32 vcc, 0, v3
	v_fma_f32 v4, |v0|, s84, 1.0
	v_rcp_f32_e32 v4, v4
	v_cndmask_b32_e32 v2, v45, v2, vcc
	v_mul_f32_e32 v41, v41, v2
	v_cmp_gt_f32_e32 vcc, 0, v0
	v_fmamk_f32 v2, v4, 0x3f07dc22, v241
	v_fmaak_f32 v5, v4, v2, 0x3f35f0e3
	v_pk_mul_f32 v[2:3], v[0:1], v[0:1]
	v_fmaak_f32 v5, v4, v5, 0xbe11a98e
; __device__ __forceinline__ unsigned pk2(float lo, float hi) { unsigned r; asm("v_cvt_pk_bf16_f32 %0, %1, %2" : "=v"(r) : "v"(lo), "v"(hi)); return r; }
;     static __device__ __forceinline__ void unpack8(const u32x4 q, float (&x)[8]) { x[0] = bflo(q.x); x[1] = bfhi(q.x); x[2] = bflo(q.y); x[3] = bfhi(q.y); x[4] = bflo(q.z); x[5] = bfhi(q.z); x[6] = bflo(q.w); x[7] = bfhi(q.w); }
;     __device__ __forceinline__ void operator()(EPI_ARGS) const {
;     ...
;                     for (int t = 0; t < 1; ++t) { const int row = row0 + ai * 128 + (mp + t) * 16; const int r1 = row > 0 ? row - 1 : 0, r2 = row > 1 ? row - 2 : 0;
;                         q2[t] = *(const u32x4*)(up + (size_t)row * DFF + col); q1[t] = *(const u32x4*)(up + (size_t)r1 * DFF + col); q0[t] = *(const u32x4*)(up + (size_t)r2 * DFF + col); }
;                     __builtin_amdgcn_sched_barrier(0);
; #pragma unroll
;                     for (int t = 0; t < 1; ++t) { const int m = mp + t, row = row0 + ai * 128 + m * 16;
;                         const int i = row < TP ? row : ((row - TP) & 15); const int sidx = row < TP ? 0 : ((row - TP) >> 4);
;                         float x0[8], x1[8], x2[8]; unpack8(q0[t], x0); unpack8(q1[t], x1); unpack8(q2[t], x2);
;                         if (i < 2) {
;                             const bool smp = row >= TP; const float* p0 = cs + ((size_t)sidx * 2 + i) * DFF + col; const float* p1 = cs + ((size_t)sidx * 2 + 1) * DFF + col;
; #pragma unroll
;                             for (int e = 0; e < 8; ++e) { x0[e] = smp ? p0[e] : 0.f; if (i == 0) x1[e] = smp ? p1[e] : 0.f; } }
;     ...
;                         for (int e = 0; e < 8; ++e) { const float cv = bb[e] + x0[e] * w0[e] + x1[e] * w1[e] + x2[e] * w2[e]; r[e] = gelu_f(cv) * acc[ai][bj][m][e >> 2][e & 3]; }
;                         u32x4 w; w.x = pk2(r[0], r[1]); w.y = pk2(r[2], r[3]); w.z = pk2(r[4], r[5]); w.w = pk2(r[6], r[7]);
;                         *(u32x4*)(act + (size_t)row * DFF + col) = w; } } } }
	v_mul_f32_e32 v2, 0xbf38aa3b, v2
	v_exp_f32_e32 v2, v2
	v_fmaak_f32 v5, v4, v5, 0x3e027906
	v_mul_f32_e32 v4, v4, v5
	v_fma_f32 v5, |v1|, s84, 1.0
	v_rcp_f32_e32 v5, v5
	v_mul_f32_e32 v2, v2, v4
	v_mul_f32_e32 v4, v0, v2
	v_fma_f32 v2, -v0, v2, v0
	v_cndmask_b32_e32 v0, v2, v4, vcc
	v_mul_f32_e32 v34, v34, v0
	v_fmamk_f32 v0, v5, 0x3f07dc22, v241
	v_mul_f32_e32 v2, 0xbf38aa3b, v3
	v_fmaak_f32 v0, v5, v0, 0x3f35f0e3
	v_exp_f32_e32 v2, v2
	v_fmaak_f32 v0, v5, v0, 0xbe11a98e
	v_fmaak_f32 v0, v5, v0, 0x3e027906
	v_mul_f32_e32 v0, v5, v0
	v_mov_b32_e32 v45, v6
	v_mul_f32_e32 v0, v2, v0
	v_pk_mul_f32 v[2:3], v[72:73], v[44:45]
	v_pk_mul_f32 v[4:5], v[80:81], v[46:47]
	v_pk_fma_f32 v[6:7], v[76:77], v[52:53], v[84:85]
	v_mov_b32_e32 v38, v3
	v_mov_b32_e32 v39, v5
	v_pk_add_f32 v[6:7], v[38:39], v[6:7]
	v_mov_b32_e32 v3, v4
	v_pk_add_f32 v[2:3], v[2:3], v[6:7]
	v_mul_f32_e32 v42, v1, v0
	v_fma_f32 v4, |v2|, s84, 1.0
	v_rcp_f32_e32 v4, v4
	v_fma_f32 v0, -v1, v0, v1
	v_cmp_gt_f32_e32 vcc, 0, v1
	v_mad_i64_i32 v[54:55], s[0:1], v224, s76, 0
	s_nop 0
	v_cndmask_b32_e32 v0, v0, v42, vcc
	v_mul_f32_e32 v5, v35, v0
	v_fmamk_f32 v0, v4, 0x3f07dc22, v241
	v_fmaak_f32 v6, v4, v0, 0x3f35f0e3
	v_pk_mul_f32 v[0:1], v[2:3], v[2:3]
	v_fmaak_f32 v6, v4, v6, 0xbe11a98e
	v_mul_f32_e32 v0, 0xbf38aa3b, v0
	v_exp_f32_e32 v0, v0
	v_fmaak_f32 v6, v4, v6, 0x3e027906
	v_mul_f32_e32 v4, v4, v6
	v_fma_f32 v6, |v3|, s84, 1.0
	v_rcp_f32_e32 v6, v6
	v_mul_f32_e32 v0, v0, v4
	v_mul_f32_e32 v4, v2, v0
	v_fma_f32 v0, -v2, v0, v2
	v_cmp_gt_f32_e32 vcc, 0, v2
	v_mul_f32_e32 v1, 0xbf38aa3b, v1
	v_exp_f32_e32 v1, v1
	v_cndmask_b32_e32 v0, v0, v4, vcc
	v_mul_f32_e32 v4, v36, v0
	v_fmamk_f32 v0, v6, 0x3f07dc22, v241
	v_fmaak_f32 v0, v6, v0, 0x3f35f0e3
	v_fmaak_f32 v0, v6, v0, 0xbe11a98e
	v_fmaak_f32 v0, v6, v0, 0x3e027906
	v_mul_f32_e32 v0, v6, v0
	v_mul_f32_e32 v0, v1, v0
	v_mul_f32_e32 v1, v3, v0
	v_fma_f32 v0, -v3, v0, v3
	v_cmp_gt_f32_e32 vcc, 0, v3
	v_cvt_pk_bf16_f32 v2, v34, v5
	v_add_u32_e32 v52, 0x90, v232
	s_nop 0
	v_cndmask_b32_e32 v0, v0, v1, vcc
	v_mul_f32_e32 v3, v37, v0
	v_cvt_pk_bf16_f32 v3, v4, v3
	v_lshl_add_u64 v[4:5], s[80:81], 0, v[54:55]
	v_cvt_pk_bf16_f32 v0, v64, v48
	v_lshl_add_u64 v[4:5], v[4:5], 0, v[186:187]
	v_cvt_pk_bf16_f32 v1, v40, v41
	global_store_dwordx4 v[4:5], v[0:3], off offset:256 sc1
	s_nop 1
	v_max_i32_e32 v0, 1, v52
	v_add_u32_e32 v4, -1, v0
	v_max_i32_e32 v0, 2, v52
	v_add_u32_e32 v38, -2, v0
	v_mov_b64_e32 v[0:1], s[30:31]
	v_mad_i64_i32 v[2:3], s[0:1], v52, s76, v[0:1]
	v_mad_u64_u32 v[4:5], s[0:1], v4, s76, v[0:1]
	v_mad_u64_u32 v[0:1], s[0:1], v38, s76, v[0:1]
	v_lshl_add_u64 v[2:3], v[2:3], 0, v[186:187]
	v_lshl_add_u64 v[4:5], v[4:5], 0, v[186:187]
	v_lshl_add_u64 v[0:1], v[0:1], 0, v[186:187]
	s_movk_i32 s0, 0x1f70
	v_cmp_gt_i32_e64 s[0:1], s0, v232
	s_waitcnt vmcnt(1)
	v_mov_b64_e32 v[34:35], v[196:197]
	v_mov_b64_e32 v[36:37], v[198:199]
	v_mov_b64_e32 v[4:5], v[200:201]
	v_mov_b64_e32 v[6:7], v[202:203]
	v_mov_b64_e32 v[0:1], v[242:243]
	v_mov_b64_e32 v[2:3], v[244:245]
	v_lshlrev_b32_e32 v38, 16, v0
	v_and_b32_e32 v39, 0xffff0000, v0
	v_cndmask_b32_e64 v50, v228, v52, s[0:1]
	v_lshlrev_b32_e32 v40, 16, v1
	v_and_b32_e32 v41, 0xffff0000, v1
	v_lshlrev_b32_e32 v42, 16, v2
	v_and_b32_e32 v43, 0xffff0000, v2
	v_lshlrev_b32_e32 v44, 16, v3
	v_and_b32_e32 v45, 0xffff0000, v3
	v_lshlrev_b32_e32 v0, 16, v4
	v_and_b32_e32 v1, 0xffff0000, v4
	v_lshlrev_b32_e32 v2, 16, v5
	v_and_b32_e32 v3, 0xffff0000, v5
	v_lshlrev_b32_e32 v4, 16, v6
	v_and_b32_e32 v5, 0xffff0000, v6
	v_lshlrev_b32_e32 v6, 16, v7
	v_and_b32_e32 v7, 0xffff0000, v7
	v_cmp_gt_i32_e32 vcc, 2, v50
	s_and_saveexec_b64 s[8:9], vcc
	s_cbranch_execz .LBB0_1826
	s_movk_i32 s14, 0x1f6f
	v_cmp_lt_i32_e32 vcc, s14, v232
	s_add_i32 s14, s5, 0xffffe090
	s_ashr_i32 s14, s14, 4
	v_mov_b32_e32 v38, s14
	v_cndmask_b32_e64 v40, v38, 0, s[0:1]
	v_ashrrev_i32_e32 v41, 31, v40
	v_ashrrev_i32_e32 v51, 31, v50
	v_lshl_add_u64 v[38:39], v[40:41], 1, v[50:51]
	v_mov_b64_e32 v[42:43], s[68:69]
	v_mad_u64_u32 v[42:43], s[0:1], v38, s13, v[42:43]
	v_mad_i32_i24 v43, v39, s13, v43
	v_lshl_add_u64 v[48:49], v[184:185], 2, v[42:43]
	v_mov_b32_e32 v38, 0
	s_and_saveexec_b64 s[0:1], vcc
	s_cbranch_execz .LBB0_1779
	global_load_dword v38, v[48:49], off offset:512

;     static __device__ __forceinline__ void unpack8(const u32x4 q, float (&x)[8]) { x[0] = bflo(q.x); x[1] = bfhi(q.x); x[2] = bflo(q.y); x[3] = bfhi(q.y); x[4] = bflo(q.z); x[5] = bfhi(q.z); x[6] = bflo(q.w); x[7] = bfhi(q.w); }
;     __device__ __forceinline__ void operator()(EPI_ARGS) const {
;     ...
;                         q2[t] = *(const u32x4*)(up + (size_t)row * DFF + col); q1[t] = *(const u32x4*)(up + (size_t)r1 * DFF + col); q0[t] = *(const u32x4*)(up + (size_t)r2 * DFF + col); }
;                     __builtin_amdgcn_sched_barrier(0);
; #pragma unroll
;                     for (int t = 0; t < 1; ++t) { const int m = mp + t, row = row0 + ai * 128 + m * 16;
;                         const int i = row < TP ? row : ((row - TP) & 15); const int sidx = row < TP ? 0 : ((row - TP) >> 4);
;                         float x0[8], x1[8], x2[8]; unpack8(q0[t], x0); unpack8(q1[t], x1); unpack8(q2[t], x2);
;                         if (i < 2) {
;                             const bool smp = row >= TP; const float* p0 = cs + ((size_t)sidx * 2 + i) * DFF + col; const float* p1 = cs + ((size_t)sidx * 2 + 1) * DFF + col;
; #pragma unroll
;                             for (int e = 0; e < 8; ++e) { x0[e] = smp ? p0[e] : 0.f; if (i == 0) x1[e] = smp ? p1[e] : 0.f; } }
;                         float r[8];
; #pragma unroll
;                         for (int e = 0; e < 8; ++e) { const float cv = bb[e] + x0[e] * w0[e] + x1[e] * w1[e] + x2[e] * w2[e]; r[e] = gelu_f(cv) * acc[ai][bj][m][e >> 2][e & 3]; }
.LBB0_1826:
	s_or_b64 exec, exec, s[8:9]
	v_mad_i64_i32 v[46:47], s[0:1], v52, s76, 0
	v_lshlrev_b32_e32 v48, 16, v34
	v_and_b32_e32 v34, 0xffff0000, v34
	v_lshlrev_b32_e32 v50, 16, v35
	v_and_b32_e32 v52, 0xffff0000, v35
	s_waitcnt vmcnt(1)
	v_add_u32_e32 v240, 160, v232
	v_mov_b64_e32 v[238:239], s[30:31]
	v_mad_i64_i32 v[238:239], s[0:1], v240, s76, v[238:239]
	v_lshl_add_u64 v[238:239], v[238:239], 0, v[186:187]
	global_load_dwordx4 v[196:199], v[238:239], off offset:256
	v_add_u32_e32 v240, -1, v240
	v_mov_b64_e32 v[246:247], s[30:31]
	v_mad_i64_i32 v[246:247], s[0:1], v240, s76, v[246:247]
	v_lshl_add_u64 v[246:247], v[246:247], 0, v[186:187]
	global_load_dwordx4 v[200:203], v[246:247], off offset:256
	v_add_u32_e32 v240, -1, v240
	v_mov_b64_e32 v[238:239], s[30:31]
	v_mad_i64_i32 v[238:239], s[0:1], v240, s76, v[238:239]
	v_lshl_add_u64 v[238:239], v[238:239], 0, v[186:187]
	global_load_dwordx4 v[242:245], v[238:239], off offset:256
	v_mov_b32_e32 v49, v0
	v_mov_b32_e32 v35, v1
	v_pk_mul_f32 v[48:49], v[106:107], v[48:49]
	v_pk_mul_f32 v[0:1], v[90:91], v[34:35]
	v_pk_fma_f32 v[34:35], v[86:87], v[38:39], v[94:95]
	v_mov_b32_e32 v38, v49
	v_mov_b32_e32 v39, v1
	v_pk_add_f32 v[34:35], v[38:39], v[34:35]
	v_mov_b32_e32 v49, v0
	v_pk_add_f32 v[0:1], v[48:49], v[34:35]
	v_lshlrev_b32_e32 v54, 16, v36
	v_fma_f32 v34, |v0|, s84, 1.0
	v_rcp_f32_e32 v35, v34
	v_pk_mul_f32 v[48:49], v[0:1], v[0:1]
	v_and_b32_e32 v34, 0xffff0000, v36
	v_lshlrev_b32_e32 v36, 16, v37
	v_and_b32_e32 v38, 0xffff0000, v37
	v_fmamk_f32 v37, v35, 0x3f07dc22, v241
	v_mul_f32_e32 v39, 0xbf38aa3b, v48
	v_fmaak_f32 v37, v35, v37, 0x3f35f0e3
	v_exp_f32_e32 v39, v39
	v_fmaak_f32 v37, v35, v37, 0xbe11a98e
	v_fmaak_f32 v37, v35, v37, 0x3e027906
	v_mul_f32_e32 v35, v35, v37
	v_mul_f32_e32 v35, v39, v35
	v_fma_f32 v39, |v1|, s84, 1.0
	v_rcp_f32_e32 v39, v39
	v_mul_f32_e32 v37, v0, v35
	v_fma_f32 v35, -v0, v35, v0
	v_cmp_gt_f32_e32 vcc, 0, v0
	v_mov_b32_e32 v51, v2
	v_mov_b32_e32 v53, v3
	v_cndmask_b32_e32 v0, v35, v37, vcc
	v_mul_f32_e32 v56, v30, v0
	v_mul_f32_e32 v30, 0xbf38aa3b, v49
	v_pk_mul_f32 v[48:49], v[102:103], v[50:51]
	v_pk_mul_f32 v[2:3], v[92:93], v[52:53]
	v_fmamk_f32 v0, v39, 0x3f07dc22, v241
	v_pk_fma_f32 v[40:41], v[88:89], v[40:41], v[96:97]
	v_mov_b32_e32 v50, v49
	v_mov_b32_e32 v51, v3
	v_fmaak_f32 v0, v39, v0, 0x3f35f0e3
	v_exp_f32_e32 v30, v30
	v_pk_add_f32 v[40:41], v[50:51], v[40:41]
	v_mov_b32_e32 v49, v2
	v_fmaak_f32 v0, v39, v0, 0xbe11a98e
	v_pk_add_f32 v[2:3], v[48:49], v[40:41]
	v_fmaak_f32 v0, v39, v0, 0x3e027906
	v_fma_f32 v35, |v2|, s84, 1.0
	v_mul_f32_e32 v0, v39, v0
	v_rcp_f32_e32 v35, v35
	v_mul_f32_e32 v0, v30, v0
	v_mul_f32_e32 v30, v1, v0
	v_fma_f32 v0, -v1, v0, v1
	v_cmp_gt_f32_e32 vcc, 0, v1
	v_mov_b32_e32 v55, v4
	v_mov_b32_e32 v39, v7
	v_cndmask_b32_e32 v0, v0, v30, vcc
	v_mul_f32_e32 v40, v31, v0
	v_fmamk_f32 v0, v35, 0x3f07dc22, v241
	v_fmaak_f32 v30, v35, v0, 0x3f35f0e3
	v_pk_mul_f32 v[0:1], v[2:3], v[2:3]
	v_fmaak_f32 v30, v35, v30, 0xbe11a98e
	v_mul_f32_e32 v0, 0xbf38aa3b, v0
	v_exp_f32_e32 v0, v0
	v_fmaak_f32 v30, v35, v30, 0x3e027906
	v_fma_f32 v31, |v3|, s84, 1.0
	v_mul_f32_e32 v30, v35, v30
	v_rcp_f32_e32 v31, v31
	v_mul_f32_e32 v0, v0, v30
	v_mul_f32_e32 v30, v2, v0
	v_fma_f32 v0, -v2, v0, v2
	v_cmp_gt_f32_e32 vcc, 0, v2
	v_mul_f32_e32 v1, 0xbf38aa3b, v1
	v_exp_f32_e32 v1, v1
	v_cndmask_b32_e32 v0, v0, v30, vcc
	v_mul_f32_e32 v32, v32, v0
	v_fmamk_f32 v0, v31, 0x3f07dc22, v241
	v_fmaak_f32 v0, v31, v0, 0x3f35f0e3
	v_fmaak_f32 v0, v31, v0, 0xbe11a98e
	v_fmaak_f32 v0, v31, v0, 0x3e027906
	v_mul_f32_e32 v0, v31, v0
	v_mul_f32_e32 v0, v1, v0
	v_mov_b32_e32 v35, v5
	v_mul_f32_e32 v2, v3, v0
	v_fma_f32 v37, -v3, v0, v3
	v_pk_mul_f32 v[0:1], v[70:71], v[54:55]
	v_pk_mul_f32 v[4:5], v[78:79], v[34:35]
	v_pk_fma_f32 v[30:31], v[74:75], v[42:43], v[82:83]
	v_mov_b32_e32 v34, v1
	v_mov_b32_e32 v35, v5
	v_pk_add_f32 v[30:31], v[34:35], v[30:31]
	v_mov_b32_e32 v1, v4
	v_pk_add_f32 v[0:1], v[0:1], v[30:31]
	v_cmp_gt_f32_e32 vcc, 0, v3
	v_fma_f32 v4, |v0|, s84, 1.0
	v_rcp_f32_e32 v4, v4
	v_cndmask_b32_e32 v2, v37, v2, vcc
	v_mul_f32_e32 v33, v33, v2
	v_cmp_gt_f32_e32 vcc, 0, v0
	v_fmamk_f32 v2, v4, 0x3f07dc22, v241
	v_fmaak_f32 v5, v4, v2, 0x3f35f0e3
	v_pk_mul_f32 v[2:3], v[0:1], v[0:1]
; __device__ __forceinline__ unsigned pk2(float lo, float hi) { unsigned r; asm("v_cvt_pk_bf16_f32 %0, %1, %2" : "=v"(r) : "v"(lo), "v"(hi)); return r; }
;     static __device__ __forceinline__ void unpack8(const u32x4 q, float (&x)[8]) { x[0] = bflo(q.x); x[1] = bfhi(q.x); x[2] = bflo(q.y); x[3] = bfhi(q.y); x[4] = bflo(q.z); x[5] = bfhi(q.z); x[6] = bflo(q.w); x[7] = bfhi(q.w); }
;     __device__ __forceinline__ void operator()(EPI_ARGS) const {
;     ...
;                     for (int t = 0; t < 1; ++t) { const int row = row0 + ai * 128 + (mp + t) * 16; const int r1 = row > 0 ? row - 1 : 0, r2 = row > 1 ? row - 2 : 0;
;                         q2[t] = *(const u32x4*)(up + (size_t)row * DFF + col); q1[t] = *(const u32x4*)(up + (size_t)r1 * DFF + col); q0[t] = *(const u32x4*)(up + (size_t)r2 * DFF + col); }
;                     __builtin_amdgcn_sched_barrier(0);
; #pragma unroll
;                     for (int t = 0; t < 1; ++t) { const int m = mp + t, row = row0 + ai * 128 + m * 16;
;                         const int i = row < TP ? row : ((row - TP) & 15); const int sidx = row < TP ? 0 : ((row - TP) >> 4);
;                         float x0[8], x1[8], x2[8]; unpack8(q0[t], x0); unpack8(q1[t], x1); unpack8(q2[t], x2);
;                         if (i < 2) {
;                             const bool smp = row >= TP; const float* p0 = cs + ((size_t)sidx * 2 + i) * DFF + col; const float* p1 = cs + ((size_t)sidx * 2 + 1) * DFF + col;
; #pragma unroll
;                             for (int e = 0; e < 8; ++e) { x0[e] = smp ? p0[e] : 0.f; if (i == 0) x1[e] = smp ? p1[e] : 0.f; } }
;     ...
;                         for (int e = 0; e < 8; ++e) { const float cv = bb[e] + x0[e] * w0[e] + x1[e] * w1[e] + x2[e] * w2[e]; r[e] = gelu_f(cv) * acc[ai][bj][m][e >> 2][e & 3]; }
;                         u32x4 w; w.x = pk2(r[0], r[1]); w.y = pk2(r[2], r[3]); w.z = pk2(r[4], r[5]); w.w = pk2(r[6], r[7]);
;                         *(u32x4*)(act + (size_t)row * DFF + col) = w; } } } }
	v_fmaak_f32 v5, v4, v5, 0xbe11a98e
	v_mul_f32_e32 v2, 0xbf38aa3b, v2
	v_exp_f32_e32 v2, v2
	v_fmaak_f32 v5, v4, v5, 0x3e027906
	v_mul_f32_e32 v4, v4, v5
	v_fma_f32 v5, |v1|, s84, 1.0
	v_rcp_f32_e32 v5, v5
	v_mul_f32_e32 v2, v2, v4
	v_mul_f32_e32 v4, v0, v2
	v_fma_f32 v2, -v0, v2, v0
	v_cndmask_b32_e32 v0, v2, v4, vcc
	v_mul_f32_e32 v26, v26, v0
	v_fmamk_f32 v0, v5, 0x3f07dc22, v241
	v_mul_f32_e32 v2, 0xbf38aa3b, v3
	v_fmaak_f32 v0, v5, v0, 0x3f35f0e3
	v_exp_f32_e32 v2, v2
	v_fmaak_f32 v0, v5, v0, 0xbe11a98e
	v_fmaak_f32 v0, v5, v0, 0x3e027906
	v_mul_f32_e32 v0, v5, v0
	v_mov_b32_e32 v37, v6
	v_mul_f32_e32 v0, v2, v0
	v_pk_mul_f32 v[2:3], v[72:73], v[36:37]
	v_pk_mul_f32 v[4:5], v[80:81], v[38:39]
	v_pk_fma_f32 v[6:7], v[76:77], v[44:45], v[84:85]
	v_mov_b32_e32 v30, v3
	v_mov_b32_e32 v31, v5
	v_pk_add_f32 v[6:7], v[30:31], v[6:7]
	v_mov_b32_e32 v3, v4
	v_pk_add_f32 v[2:3], v[2:3], v[6:7]
	v_mul_f32_e32 v34, v1, v0
	v_fma_f32 v4, |v2|, s84, 1.0
	v_rcp_f32_e32 v4, v4
	v_fma_f32 v0, -v1, v0, v1
	v_cmp_gt_f32_e32 vcc, 0, v1
	v_add_u32_e32 v44, 0xa0, v232
	s_nop 0
	v_cndmask_b32_e32 v0, v0, v34, vcc
	v_mul_f32_e32 v5, v27, v0
	v_fmamk_f32 v0, v4, 0x3f07dc22, v241
	v_fmaak_f32 v6, v4, v0, 0x3f35f0e3
	v_pk_mul_f32 v[0:1], v[2:3], v[2:3]
	v_fmaak_f32 v6, v4, v6, 0xbe11a98e
	v_mul_f32_e32 v0, 0xbf38aa3b, v0
	v_exp_f32_e32 v0, v0
	v_fmaak_f32 v6, v4, v6, 0x3e027906
	v_mul_f32_e32 v4, v4, v6
	v_fma_f32 v6, |v3|, s84, 1.0
	v_rcp_f32_e32 v6, v6
	v_mul_f32_e32 v0, v0, v4
	v_mul_f32_e32 v4, v2, v0
	v_fma_f32 v0, -v2, v0, v2
	v_cmp_gt_f32_e32 vcc, 0, v2
	v_mul_f32_e32 v1, 0xbf38aa3b, v1
	v_exp_f32_e32 v1, v1
	v_cndmask_b32_e32 v0, v0, v4, vcc
	v_mul_f32_e32 v4, v28, v0
	v_fmamk_f32 v0, v6, 0x3f07dc22, v241
	v_fmaak_f32 v0, v6, v0, 0x3f35f0e3
	v_fmaak_f32 v0, v6, v0, 0xbe11a98e
	v_fmaak_f32 v0, v6, v0, 0x3e027906
	v_mul_f32_e32 v0, v6, v0
	v_mul_f32_e32 v0, v1, v0
	v_mul_f32_e32 v1, v3, v0
	v_fma_f32 v0, -v3, v0, v3
	v_cmp_gt_f32_e32 vcc, 0, v3
	v_cvt_pk_bf16_f32 v2, v26, v5
	s_nop 1
	v_cndmask_b32_e32 v0, v0, v1, vcc
	v_mul_f32_e32 v3, v29, v0
	v_cvt_pk_bf16_f32 v3, v4, v3
	v_lshl_add_u64 v[4:5], s[80:81], 0, v[46:47]
	v_cvt_pk_bf16_f32 v0, v56, v40
	v_lshl_add_u64 v[4:5], v[4:5], 0, v[186:187]
	v_cvt_pk_bf16_f32 v1, v32, v33
	global_store_dwordx4 v[4:5], v[0:3], off offset:256 sc1
	s_nop 1
	v_max_i32_e32 v0, 1, v44
	v_add_u32_e32 v4, -1, v0
	v_max_i32_e32 v0, 2, v44
	v_add_u32_e32 v30, -2, v0
	v_mov_b64_e32 v[0:1], s[30:31]
	v_mad_i64_i32 v[2:3], s[0:1], v44, s76, v[0:1]
	v_mad_u64_u32 v[4:5], s[0:1], v4, s76, v[0:1]
	v_mad_u64_u32 v[0:1], s[0:1], v30, s76, v[0:1]
	v_lshl_add_u64 v[2:3], v[2:3], 0, v[186:187]
	v_lshl_add_u64 v[4:5], v[4:5], 0, v[186:187]
	v_lshl_add_u64 v[0:1], v[0:1], 0, v[186:187]
	s_movk_i32 s0, 0x1f60
	v_cmp_gt_i32_e64 s[0:1], s0, v232
	s_waitcnt vmcnt(1)
	v_mov_b64_e32 v[26:27], v[196:197]
	v_mov_b64_e32 v[28:29], v[198:199]
	v_mov_b64_e32 v[4:5], v[200:201]
	v_mov_b64_e32 v[6:7], v[202:203]
	v_mov_b64_e32 v[0:1], v[242:243]
	v_mov_b64_e32 v[2:3], v[244:245]
	v_lshlrev_b32_e32 v30, 16, v0
	v_and_b32_e32 v31, 0xffff0000, v0
	v_cndmask_b32_e64 v42, v228, v44, s[0:1]
	v_lshlrev_b32_e32 v32, 16, v1
	v_and_b32_e32 v33, 0xffff0000, v1
	v_lshlrev_b32_e32 v34, 16, v2
	v_and_b32_e32 v35, 0xffff0000, v2
	v_lshlrev_b32_e32 v36, 16, v3
	v_and_b32_e32 v37, 0xffff0000, v3
	v_lshlrev_b32_e32 v0, 16, v4
	v_and_b32_e32 v1, 0xffff0000, v4
	v_lshlrev_b32_e32 v2, 16, v5
	v_and_b32_e32 v3, 0xffff0000, v5
	v_lshlrev_b32_e32 v4, 16, v6
	v_and_b32_e32 v5, 0xffff0000, v6
	v_lshlrev_b32_e32 v6, 16, v7
	v_and_b32_e32 v7, 0xffff0000, v7
	v_cmp_gt_i32_e32 vcc, 2, v42
	s_and_saveexec_b64 s[8:9], vcc
	s_cbranch_execz .LBB0_1876
	s_movk_i32 s14, 0x1f5f
	v_cmp_lt_i32_e32 vcc, s14, v232
	s_add_i32 s14, s5, 0xffffe0a0
	s_ashr_i32 s14, s14, 4
	v_mov_b32_e32 v30, s14
	v_cndmask_b32_e64 v32, v30, 0, s[0:1]
	v_ashrrev_i32_e32 v33, 31, v32
	v_ashrrev_i32_e32 v43, 31, v42
	v_lshl_add_u64 v[30:31], v[32:33], 1, v[42:43]
	v_mov_b64_e32 v[34:35], s[68:69]
	v_mad_u64_u32 v[34:35], s[0:1], v30, s13, v[34:35]
	v_mad_i32_i24 v35, v31, s13, v35
	v_lshl_add_u64 v[40:41], v[184:185], 2, v[34:35]
	v_mov_b32_e32 v30, 0
	s_and_saveexec_b64 s[0:1], vcc
	s_cbranch_execz .LBB0_1829
	global_load_dword v30, v[40:41], off offset:512

;     static __device__ __forceinline__ void unpack8(const u32x4 q, float (&x)[8]) { x[0] = bflo(q.x); x[1] = bfhi(q.x); x[2] = bflo(q.y); x[3] = bfhi(q.y); x[4] = bflo(q.z); x[5] = bfhi(q.z); x[6] = bflo(q.w); x[7] = bfhi(q.w); }
;     __device__ __forceinline__ void operator()(EPI_ARGS) const {
;     ...
;                         q2[t] = *(const u32x4*)(up + (size_t)row * DFF + col); q1[t] = *(const u32x4*)(up + (size_t)r1 * DFF + col); q0[t] = *(const u32x4*)(up + (size_t)r2 * DFF + col); }
;                     __builtin_amdgcn_sched_barrier(0);
; #pragma unroll
;                     for (int t = 0; t < 1; ++t) { const int m = mp + t, row = row0 + ai * 128 + m * 16;
;                         const int i = row < TP ? row : ((row - TP) & 15); const int sidx = row < TP ? 0 : ((row - TP) >> 4);
;                         float x0[8], x1[8], x2[8]; unpack8(q0[t], x0); unpack8(q1[t], x1); unpack8(q2[t], x2);
;                         if (i < 2) {
;                             const bool smp = row >= TP; const float* p0 = cs + ((size_t)sidx * 2 + i) * DFF + col; const float* p1 = cs + ((size_t)sidx * 2 + 1) * DFF + col;
; #pragma unroll
;                             for (int e = 0; e < 8; ++e) { x0[e] = smp ? p0[e] : 0.f; if (i == 0) x1[e] = smp ? p1[e] : 0.f; } }
;                         float r[8];
; #pragma unroll
;                         for (int e = 0; e < 8; ++e) { const float cv = bb[e] + x0[e] * w0[e] + x1[e] * w1[e] + x2[e] * w2[e]; r[e] = gelu_f(cv) * acc[ai][bj][m][e >> 2][e & 3]; }
.LBB0_1876:
	s_or_b64 exec, exec, s[8:9]
	v_mad_i64_i32 v[38:39], s[0:1], v44, s76, 0
	v_lshlrev_b32_e32 v40, 16, v26
	v_and_b32_e32 v26, 0xffff0000, v26
	v_lshlrev_b32_e32 v42, 16, v27
	v_and_b32_e32 v44, 0xffff0000, v27
	s_waitcnt vmcnt(1)
	v_add_u32_e32 v240, 176, v232
	v_mov_b64_e32 v[238:239], s[30:31]
	v_mad_i64_i32 v[238:239], s[0:1], v240, s76, v[238:239]
	v_lshl_add_u64 v[238:239], v[238:239], 0, v[186:187]
	global_load_dwordx4 v[196:199], v[238:239], off offset:256
	v_add_u32_e32 v240, -1, v240
	v_mov_b64_e32 v[246:247], s[30:31]
	v_mad_i64_i32 v[246:247], s[0:1], v240, s76, v[246:247]
	v_lshl_add_u64 v[246:247], v[246:247], 0, v[186:187]
	global_load_dwordx4 v[200:203], v[246:247], off offset:256
	v_add_u32_e32 v240, -1, v240
	v_mov_b64_e32 v[238:239], s[30:31]
	v_mad_i64_i32 v[238:239], s[0:1], v240, s76, v[238:239]
	v_lshl_add_u64 v[238:239], v[238:239], 0, v[186:187]
	global_load_dwordx4 v[242:245], v[238:239], off offset:256
	v_mov_b32_e32 v41, v0
	v_mov_b32_e32 v27, v1
	v_pk_mul_f32 v[40:41], v[106:107], v[40:41]
	v_pk_mul_f32 v[0:1], v[90:91], v[26:27]
	v_pk_fma_f32 v[26:27], v[86:87], v[30:31], v[94:95]
	v_mov_b32_e32 v30, v41
	v_mov_b32_e32 v31, v1
	v_pk_add_f32 v[26:27], v[30:31], v[26:27]
	v_mov_b32_e32 v41, v0
	v_pk_add_f32 v[0:1], v[40:41], v[26:27]
	v_lshlrev_b32_e32 v46, 16, v28
	v_fma_f32 v26, |v0|, s84, 1.0
	v_rcp_f32_e32 v27, v26
	v_pk_mul_f32 v[40:41], v[0:1], v[0:1]
	v_and_b32_e32 v26, 0xffff0000, v28
	v_lshlrev_b32_e32 v28, 16, v29
	v_and_b32_e32 v30, 0xffff0000, v29
	v_fmamk_f32 v29, v27, 0x3f07dc22, v241
	v_mul_f32_e32 v31, 0xbf38aa3b, v40
	v_fmaak_f32 v29, v27, v29, 0x3f35f0e3
	v_exp_f32_e32 v31, v31
	v_fmaak_f32 v29, v27, v29, 0xbe11a98e
	v_fmaak_f32 v29, v27, v29, 0x3e027906
	v_mul_f32_e32 v27, v27, v29
	v_mul_f32_e32 v27, v31, v27
	v_fma_f32 v31, |v1|, s84, 1.0
	v_rcp_f32_e32 v31, v31
	v_mul_f32_e32 v29, v0, v27
	v_fma_f32 v27, -v0, v27, v0
	v_cmp_gt_f32_e32 vcc, 0, v0
	v_mov_b32_e32 v43, v2
	v_mov_b32_e32 v45, v3
	v_cndmask_b32_e32 v0, v27, v29, vcc
	v_mul_f32_e32 v48, v22, v0
	v_mul_f32_e32 v22, 0xbf38aa3b, v41
	v_pk_mul_f32 v[40:41], v[102:103], v[42:43]
	v_pk_mul_f32 v[2:3], v[92:93], v[44:45]
	v_fmamk_f32 v0, v31, 0x3f07dc22, v241
	v_pk_fma_f32 v[32:33], v[88:89], v[32:33], v[96:97]
	v_mov_b32_e32 v42, v41
	v_mov_b32_e32 v43, v3
	v_fmaak_f32 v0, v31, v0, 0x3f35f0e3
	v_exp_f32_e32 v22, v22
	v_pk_add_f32 v[32:33], v[42:43], v[32:33]
	v_mov_b32_e32 v41, v2
	v_fmaak_f32 v0, v31, v0, 0xbe11a98e
	v_pk_add_f32 v[2:3], v[40:41], v[32:33]
	v_fmaak_f32 v0, v31, v0, 0x3e027906
	v_fma_f32 v27, |v2|, s84, 1.0
	v_mul_f32_e32 v0, v31, v0
	v_rcp_f32_e32 v27, v27
	v_mul_f32_e32 v0, v22, v0
	v_mul_f32_e32 v22, v1, v0
	v_fma_f32 v0, -v1, v0, v1
	v_cmp_gt_f32_e32 vcc, 0, v1
	v_mov_b32_e32 v47, v4
	v_mov_b32_e32 v31, v7
	v_cndmask_b32_e32 v0, v0, v22, vcc
	v_mul_f32_e32 v32, v23, v0
	v_fmamk_f32 v0, v27, 0x3f07dc22, v241
	v_fmaak_f32 v22, v27, v0, 0x3f35f0e3
	v_pk_mul_f32 v[0:1], v[2:3], v[2:3]
	v_fmaak_f32 v22, v27, v22, 0xbe11a98e
	v_mul_f32_e32 v0, 0xbf38aa3b, v0
	v_exp_f32_e32 v0, v0
	v_fmaak_f32 v22, v27, v22, 0x3e027906
	v_fma_f32 v23, |v3|, s84, 1.0
	v_mul_f32_e32 v22, v27, v22
	v_rcp_f32_e32 v23, v23
	v_mul_f32_e32 v0, v0, v22
	v_mul_f32_e32 v22, v2, v0
	v_fma_f32 v0, -v2, v0, v2
	v_cmp_gt_f32_e32 vcc, 0, v2
	v_mul_f32_e32 v1, 0xbf38aa3b, v1
	v_exp_f32_e32 v1, v1
	v_cndmask_b32_e32 v0, v0, v22, vcc
	v_mul_f32_e32 v24, v24, v0
	v_fmamk_f32 v0, v23, 0x3f07dc22, v241
	v_fmaak_f32 v0, v23, v0, 0x3f35f0e3
	v_fmaak_f32 v0, v23, v0, 0xbe11a98e
	v_fmaak_f32 v0, v23, v0, 0x3e027906
	v_mul_f32_e32 v0, v23, v0
	v_mul_f32_e32 v0, v1, v0
	v_mov_b32_e32 v27, v5
	v_mul_f32_e32 v2, v3, v0
	v_fma_f32 v29, -v3, v0, v3
	v_pk_mul_f32 v[0:1], v[70:71], v[46:47]
	v_pk_mul_f32 v[4:5], v[78:79], v[26:27]
	v_pk_fma_f32 v[22:23], v[74:75], v[34:35], v[82:83]
	v_mov_b32_e32 v26, v1
	v_mov_b32_e32 v27, v5
	v_pk_add_f32 v[22:23], v[26:27], v[22:23]
	v_mov_b32_e32 v1, v4
	v_pk_add_f32 v[0:1], v[0:1], v[22:23]
	v_cmp_gt_f32_e32 vcc, 0, v3
	v_fma_f32 v4, |v0|, s84, 1.0
	v_rcp_f32_e32 v4, v4
	v_cndmask_b32_e32 v2, v29, v2, vcc
	v_mul_f32_e32 v25, v25, v2
	v_cmp_gt_f32_e32 vcc, 0, v0
	v_fmamk_f32 v2, v4, 0x3f07dc22, v241
	v_fmaak_f32 v5, v4, v2, 0x3f35f0e3
	v_pk_mul_f32 v[2:3], v[0:1], v[0:1]
; __device__ __forceinline__ unsigned pk2(float lo, float hi) { unsigned r; asm("v_cvt_pk_bf16_f32 %0, %1, %2" : "=v"(r) : "v"(lo), "v"(hi)); return r; }
;     static __device__ __forceinline__ void unpack8(const u32x4 q, float (&x)[8]) { x[0] = bflo(q.x); x[1] = bfhi(q.x); x[2] = bflo(q.y); x[3] = bfhi(q.y); x[4] = bflo(q.z); x[5] = bfhi(q.z); x[6] = bflo(q.w); x[7] = bfhi(q.w); }
;     __device__ __forceinline__ void operator()(EPI_ARGS) const {
;     ...
;                     for (int t = 0; t < 1; ++t) { const int row = row0 + ai * 128 + (mp + t) * 16; const int r1 = row > 0 ? row - 1 : 0, r2 = row > 1 ? row - 2 : 0;
;                         q2[t] = *(const u32x4*)(up + (size_t)row * DFF + col); q1[t] = *(const u32x4*)(up + (size_t)r1 * DFF + col); q0[t] = *(const u32x4*)(up + (size_t)r2 * DFF + col); }
;                     __builtin_amdgcn_sched_barrier(0);
; #pragma unroll
;                     for (int t = 0; t < 1; ++t) { const int m = mp + t, row = row0 + ai * 128 + m * 16;
;                         const int i = row < TP ? row : ((row - TP) & 15); const int sidx = row < TP ? 0 : ((row - TP) >> 4);
;                         float x0[8], x1[8], x2[8]; unpack8(q0[t], x0); unpack8(q1[t], x1); unpack8(q2[t], x2);
;                         if (i < 2) {
;                             const bool smp = row >= TP; const float* p0 = cs + ((size_t)sidx * 2 + i) * DFF + col; const float* p1 = cs + ((size_t)sidx * 2 + 1) * DFF + col;
; #pragma unroll
;                             for (int e = 0; e < 8; ++e) { x0[e] = smp ? p0[e] : 0.f; if (i == 0) x1[e] = smp ? p1[e] : 0.f; } }
;     ...
;                         for (int e = 0; e < 8; ++e) { const float cv = bb[e] + x0[e] * w0[e] + x1[e] * w1[e] + x2[e] * w2[e]; r[e] = gelu_f(cv) * acc[ai][bj][m][e >> 2][e & 3]; }
;                         u32x4 w; w.x = pk2(r[0], r[1]); w.y = pk2(r[2], r[3]); w.z = pk2(r[4], r[5]); w.w = pk2(r[6], r[7]);
;                         *(u32x4*)(act + (size_t)row * DFF + col) = w; } } } }
	v_fmaak_f32 v5, v4, v5, 0xbe11a98e
	v_mul_f32_e32 v2, 0xbf38aa3b, v2
	v_exp_f32_e32 v2, v2
	v_fmaak_f32 v5, v4, v5, 0x3e027906
	v_mul_f32_e32 v4, v4, v5
	v_fma_f32 v5, |v1|, s84, 1.0
	v_rcp_f32_e32 v5, v5
	v_mul_f32_e32 v2, v2, v4
	v_mul_f32_e32 v4, v0, v2
	v_fma_f32 v2, -v0, v2, v0
	v_cndmask_b32_e32 v0, v2, v4, vcc
	v_mul_f32_e32 v18, v18, v0
	v_fmamk_f32 v0, v5, 0x3f07dc22, v241
	v_mul_f32_e32 v2, 0xbf38aa3b, v3
	v_fmaak_f32 v0, v5, v0, 0x3f35f0e3
	v_exp_f32_e32 v2, v2
	v_fmaak_f32 v0, v5, v0, 0xbe11a98e
	v_fmaak_f32 v0, v5, v0, 0x3e027906
	v_mul_f32_e32 v0, v5, v0
	v_mov_b32_e32 v29, v6
	v_mul_f32_e32 v0, v2, v0
	v_pk_mul_f32 v[2:3], v[72:73], v[28:29]
	v_pk_mul_f32 v[4:5], v[80:81], v[30:31]
	v_pk_fma_f32 v[6:7], v[76:77], v[36:37], v[84:85]
	v_mov_b32_e32 v22, v3
	v_mov_b32_e32 v23, v5
	v_pk_add_f32 v[6:7], v[22:23], v[6:7]
	v_mov_b32_e32 v3, v4
	v_pk_add_f32 v[2:3], v[2:3], v[6:7]
	v_mul_f32_e32 v26, v1, v0
	v_fma_f32 v4, |v2|, s84, 1.0
	v_rcp_f32_e32 v4, v4
	v_fma_f32 v0, -v1, v0, v1
	v_cmp_gt_f32_e32 vcc, 0, v1
	v_add_u32_e32 v36, 0xb0, v232
	s_nop 0
	v_cndmask_b32_e32 v0, v0, v26, vcc
	v_mul_f32_e32 v5, v19, v0
	v_fmamk_f32 v0, v4, 0x3f07dc22, v241
	v_fmaak_f32 v6, v4, v0, 0x3f35f0e3
	v_pk_mul_f32 v[0:1], v[2:3], v[2:3]
	v_fmaak_f32 v6, v4, v6, 0xbe11a98e
	v_mul_f32_e32 v0, 0xbf38aa3b, v0
	v_exp_f32_e32 v0, v0
	v_fmaak_f32 v6, v4, v6, 0x3e027906
	v_mul_f32_e32 v4, v4, v6
	v_fma_f32 v6, |v3|, s84, 1.0
	v_rcp_f32_e32 v6, v6
	v_mul_f32_e32 v0, v0, v4
	v_mul_f32_e32 v4, v2, v0
	v_fma_f32 v0, -v2, v0, v2
	v_cmp_gt_f32_e32 vcc, 0, v2
	v_mul_f32_e32 v1, 0xbf38aa3b, v1
	v_exp_f32_e32 v1, v1
	v_cndmask_b32_e32 v0, v0, v4, vcc
	v_mul_f32_e32 v4, v20, v0
	v_fmamk_f32 v0, v6, 0x3f07dc22, v241
	v_fmaak_f32 v0, v6, v0, 0x3f35f0e3
	v_fmaak_f32 v0, v6, v0, 0xbe11a98e
	v_fmaak_f32 v0, v6, v0, 0x3e027906
	v_mul_f32_e32 v0, v6, v0
	v_mul_f32_e32 v0, v1, v0
	v_mul_f32_e32 v1, v3, v0
	v_fma_f32 v0, -v3, v0, v3
	v_cmp_gt_f32_e32 vcc, 0, v3
	v_cvt_pk_bf16_f32 v2, v18, v5
	s_nop 1
	v_cndmask_b32_e32 v0, v0, v1, vcc
	v_mul_f32_e32 v3, v21, v0
	v_cvt_pk_bf16_f32 v3, v4, v3
	v_lshl_add_u64 v[4:5], s[80:81], 0, v[38:39]
	v_cvt_pk_bf16_f32 v0, v48, v32
	v_lshl_add_u64 v[4:5], v[4:5], 0, v[186:187]
	v_cvt_pk_bf16_f32 v1, v24, v25
	global_store_dwordx4 v[4:5], v[0:3], off offset:256 sc1
	s_nop 1
	v_max_i32_e32 v0, 1, v36
	v_add_u32_e32 v4, -1, v0
	v_max_i32_e32 v0, 2, v36
	v_add_u32_e32 v22, -2, v0
	v_mov_b64_e32 v[0:1], s[30:31]
	v_mad_i64_i32 v[2:3], s[0:1], v36, s76, v[0:1]
	v_mad_u64_u32 v[4:5], s[0:1], v4, s76, v[0:1]
	v_mad_u64_u32 v[0:1], s[0:1], v22, s76, v[0:1]
	v_lshl_add_u64 v[2:3], v[2:3], 0, v[186:187]
	v_lshl_add_u64 v[4:5], v[4:5], 0, v[186:187]
	v_lshl_add_u64 v[0:1], v[0:1], 0, v[186:187]
	s_movk_i32 s0, 0x1f50
	v_cmp_gt_i32_e64 s[0:1], s0, v232
	s_waitcnt vmcnt(1)
	v_mov_b64_e32 v[18:19], v[196:197]
	v_mov_b64_e32 v[20:21], v[198:199]
	v_mov_b64_e32 v[4:5], v[200:201]
	v_mov_b64_e32 v[6:7], v[202:203]
	v_mov_b64_e32 v[0:1], v[242:243]
	v_mov_b64_e32 v[2:3], v[244:245]
	v_lshlrev_b32_e32 v22, 16, v0
	v_and_b32_e32 v23, 0xffff0000, v0
	v_cndmask_b32_e64 v34, v228, v36, s[0:1]
	v_lshlrev_b32_e32 v24, 16, v1
	v_and_b32_e32 v25, 0xffff0000, v1
	v_lshlrev_b32_e32 v26, 16, v2
	v_and_b32_e32 v27, 0xffff0000, v2
	v_lshlrev_b32_e32 v28, 16, v3
	v_and_b32_e32 v29, 0xffff0000, v3
	v_lshlrev_b32_e32 v0, 16, v4
	v_and_b32_e32 v1, 0xffff0000, v4
	v_lshlrev_b32_e32 v2, 16, v5
	v_and_b32_e32 v3, 0xffff0000, v5
	v_lshlrev_b32_e32 v4, 16, v6
	v_and_b32_e32 v5, 0xffff0000, v6
	v_lshlrev_b32_e32 v6, 16, v7
	v_and_b32_e32 v7, 0xffff0000, v7
	v_cmp_gt_i32_e32 vcc, 2, v34
	s_and_saveexec_b64 s[8:9], vcc
	s_cbranch_execz .LBB0_1926
	s_addk_i32 s5, 0xe0b0
	s_ashr_i32 s5, s5, 4
	v_mov_b32_e32 v22, s5
	v_cndmask_b32_e64 v24, v22, 0, s[0:1]
	v_ashrrev_i32_e32 v25, 31, v24
	v_ashrrev_i32_e32 v35, 31, v34
	v_lshl_add_u64 v[22:23], v[24:25], 1, v[34:35]
	v_mov_b64_e32 v[26:27], s[68:69]
	v_mad_u64_u32 v[26:27], s[0:1], v22, s13, v[26:27]
	s_movk_i32 s14, 0x1f4f
	v_mad_i32_i24 v27, v23, s13, v27
	v_cmp_lt_i32_e32 vcc, s14, v232
	v_lshl_add_u64 v[32:33], v[184:185], 2, v[26:27]
	v_mov_b32_e32 v22, 0
	s_and_saveexec_b64 s[0:1], vcc
	s_cbranch_execz .LBB0_1879
	global_load_dword v22, v[32:33], off offset:512

; __device__ __forceinline__ unsigned pk2(float lo, float hi) { unsigned r; asm("v_cvt_pk_bf16_f32 %0, %1, %2" : "=v"(r) : "v"(lo), "v"(hi)); return r; }
;     static __device__ __forceinline__ void unpack8(const u32x4 q, float (&x)[8]) { x[0] = bflo(q.x); x[1] = bfhi(q.x); x[2] = bflo(q.y); x[3] = bfhi(q.y); x[4] = bflo(q.z); x[5] = bfhi(q.z); x[6] = bflo(q.w); x[7] = bfhi(q.w); }
;     __device__ __forceinline__ void operator()(EPI_ARGS) const {
;     ...
;                     for (int t = 0; t < 1; ++t) { const int m = mp + t, row = row0 + ai * 128 + m * 16;
;                         const int i = row < TP ? row : ((row - TP) & 15); const int sidx = row < TP ? 0 : ((row - TP) >> 4);
;                         float x0[8], x1[8], x2[8]; unpack8(q0[t], x0); unpack8(q1[t], x1); unpack8(q2[t], x2);
;                         if (i < 2) {
;                             const bool smp = row >= TP; const float* p0 = cs + ((size_t)sidx * 2 + i) * DFF + col; const float* p1 = cs + ((size_t)sidx * 2 + 1) * DFF + col;
; #pragma unroll
;                             for (int e = 0; e < 8; ++e) { x0[e] = smp ? p0[e] : 0.f; if (i == 0) x1[e] = smp ? p1[e] : 0.f; } }
;                         float r[8];
; #pragma unroll
;                         for (int e = 0; e < 8; ++e) { const float cv = bb[e] + x0[e] * w0[e] + x1[e] * w1[e] + x2[e] * w2[e]; r[e] = gelu_f(cv) * acc[ai][bj][m][e >> 2][e & 3]; }
;                         u32x4 w; w.x = pk2(r[0], r[1]); w.y = pk2(r[2], r[3]); w.z = pk2(r[4], r[5]); w.w = pk2(r[6], r[7]);
;                         *(u32x4*)(act + (size_t)row * DFF + col) = w; } } } }
.LBB0_1926:
	s_or_b64 exec, exec, s[8:9]
	v_mad_i64_i32 v[30:31], s[0:1], v36, s76, 0
	v_lshlrev_b32_e32 v32, 16, v18
	v_and_b32_e32 v18, 0xffff0000, v18
	v_lshlrev_b32_e32 v34, 16, v19
	v_and_b32_e32 v36, 0xffff0000, v19
	s_waitcnt vmcnt(1)
	v_mov_b32_e32 v33, v0
	v_mov_b32_e32 v19, v1
	v_pk_mul_f32 v[32:33], v[106:107], v[32:33]
	v_pk_mul_f32 v[0:1], v[90:91], v[18:19]
	v_pk_fma_f32 v[18:19], v[86:87], v[22:23], v[94:95]
	v_mov_b32_e32 v22, v33
	v_mov_b32_e32 v23, v1
	v_pk_add_f32 v[18:19], v[22:23], v[18:19]
	v_mov_b32_e32 v33, v0
	v_pk_add_f32 v[0:1], v[32:33], v[18:19]
	v_lshlrev_b32_e32 v38, 16, v20
	v_fma_f32 v18, |v0|, s84, 1.0
	v_rcp_f32_e32 v19, v18
	v_pk_mul_f32 v[32:33], v[0:1], v[0:1]
	v_and_b32_e32 v18, 0xffff0000, v20
	v_lshlrev_b32_e32 v20, 16, v21
	v_and_b32_e32 v22, 0xffff0000, v21
	v_fmamk_f32 v21, v19, 0x3f07dc22, v241
	v_mul_f32_e32 v23, 0xbf38aa3b, v32
	v_fmaak_f32 v21, v19, v21, 0x3f35f0e3
	v_exp_f32_e32 v23, v23
	v_fmaak_f32 v21, v19, v21, 0xbe11a98e
	v_fmaak_f32 v21, v19, v21, 0x3e027906
	v_mul_f32_e32 v19, v19, v21
	v_mul_f32_e32 v19, v23, v19
	v_fma_f32 v23, |v1|, s84, 1.0
	v_rcp_f32_e32 v23, v23
	v_mul_f32_e32 v21, v0, v19
	v_fma_f32 v19, -v0, v19, v0
	v_cmp_gt_f32_e32 vcc, 0, v0
	v_mov_b32_e32 v35, v2
	v_mov_b32_e32 v37, v3
	v_cndmask_b32_e32 v0, v19, v21, vcc
	v_mul_f32_e32 v40, v14, v0
	v_mul_f32_e32 v14, 0xbf38aa3b, v33
	v_pk_mul_f32 v[32:33], v[102:103], v[34:35]
	v_pk_mul_f32 v[2:3], v[92:93], v[36:37]
	v_fmamk_f32 v0, v23, 0x3f07dc22, v241
	v_pk_fma_f32 v[24:25], v[88:89], v[24:25], v[96:97]
	v_mov_b32_e32 v34, v33
	v_mov_b32_e32 v35, v3
	v_fmaak_f32 v0, v23, v0, 0x3f35f0e3
	v_exp_f32_e32 v14, v14
	v_pk_add_f32 v[24:25], v[34:35], v[24:25]
	v_mov_b32_e32 v33, v2
	v_fmaak_f32 v0, v23, v0, 0xbe11a98e
	v_pk_add_f32 v[2:3], v[32:33], v[24:25]
	v_fmaak_f32 v0, v23, v0, 0x3e027906
	v_fma_f32 v19, |v2|, s84, 1.0
	v_mul_f32_e32 v0, v23, v0
	v_rcp_f32_e32 v19, v19
	v_mul_f32_e32 v0, v14, v0
	v_mul_f32_e32 v14, v1, v0
	v_fma_f32 v0, -v1, v0, v1
	v_cmp_gt_f32_e32 vcc, 0, v1
	v_mov_b32_e32 v39, v4
	v_mov_b32_e32 v23, v7
	v_cndmask_b32_e32 v0, v0, v14, vcc
	v_mul_f32_e32 v24, v15, v0
	v_fmamk_f32 v0, v19, 0x3f07dc22, v241
	v_fmaak_f32 v14, v19, v0, 0x3f35f0e3
	v_pk_mul_f32 v[0:1], v[2:3], v[2:3]
	v_fmaak_f32 v14, v19, v14, 0xbe11a98e
	v_mul_f32_e32 v0, 0xbf38aa3b, v0
	v_exp_f32_e32 v0, v0
	v_fmaak_f32 v14, v19, v14, 0x3e027906
	v_fma_f32 v15, |v3|, s84, 1.0
	v_mul_f32_e32 v14, v19, v14
	v_rcp_f32_e32 v15, v15
	v_mul_f32_e32 v0, v0, v14
	v_mul_f32_e32 v14, v2, v0
	v_fma_f32 v0, -v2, v0, v2
	v_cmp_gt_f32_e32 vcc, 0, v2
	v_mul_f32_e32 v1, 0xbf38aa3b, v1
	v_exp_f32_e32 v1, v1
	v_cndmask_b32_e32 v0, v0, v14, vcc
	v_mul_f32_e32 v16, v16, v0
	v_fmamk_f32 v0, v15, 0x3f07dc22, v241
	v_fmaak_f32 v0, v15, v0, 0x3f35f0e3
	v_fmaak_f32 v0, v15, v0, 0xbe11a98e
	v_fmaak_f32 v0, v15, v0, 0x3e027906
	v_mul_f32_e32 v0, v15, v0
	v_mul_f32_e32 v0, v1, v0
	v_mov_b32_e32 v19, v5
	v_mul_f32_e32 v2, v3, v0
	v_fma_f32 v21, -v3, v0, v3
	v_pk_mul_f32 v[0:1], v[70:71], v[38:39]
	v_pk_mul_f32 v[4:5], v[78:79], v[18:19]
	v_pk_fma_f32 v[14:15], v[74:75], v[26:27], v[82:83]
	v_mov_b32_e32 v18, v1
	v_mov_b32_e32 v19, v5
	v_pk_add_f32 v[14:15], v[18:19], v[14:15]
	v_mov_b32_e32 v1, v4
	v_pk_add_f32 v[0:1], v[0:1], v[14:15]
	v_cmp_gt_f32_e32 vcc, 0, v3
	v_fma_f32 v4, |v0|, s84, 1.0
	v_rcp_f32_e32 v4, v4
	v_cndmask_b32_e32 v2, v21, v2, vcc
	v_mul_f32_e32 v17, v17, v2
	v_cmp_gt_f32_e32 vcc, 0, v0
	v_fmamk_f32 v2, v4, 0x3f07dc22, v241
	v_fmaak_f32 v5, v4, v2, 0x3f35f0e3
	v_pk_mul_f32 v[2:3], v[0:1], v[0:1]
	v_fmaak_f32 v5, v4, v5, 0xbe11a98e
	v_mul_f32_e32 v2, 0xbf38aa3b, v2
	v_exp_f32_e32 v2, v2
	v_fmaak_f32 v5, v4, v5, 0x3e027906
	v_mul_f32_e32 v4, v4, v5
	v_fma_f32 v5, |v1|, s84, 1.0
	v_rcp_f32_e32 v5, v5
	v_mul_f32_e32 v2, v2, v4
	v_mul_f32_e32 v4, v0, v2
	v_fma_f32 v2, -v0, v2, v0
	v_cndmask_b32_e32 v0, v2, v4, vcc
	v_mul_f32_e32 v10, v10, v0
	v_fmamk_f32 v0, v5, 0x3f07dc22, v241
	v_mul_f32_e32 v2, 0xbf38aa3b, v3
	v_fmaak_f32 v0, v5, v0, 0x3f35f0e3
	v_exp_f32_e32 v2, v2
	v_fmaak_f32 v0, v5, v0, 0xbe11a98e
	v_fmaak_f32 v0, v5, v0, 0x3e027906
	v_mul_f32_e32 v0, v5, v0
	v_mov_b32_e32 v21, v6
	v_mul_f32_e32 v0, v2, v0
	v_pk_mul_f32 v[2:3], v[72:73], v[20:21]
	v_pk_mul_f32 v[4:5], v[80:81], v[22:23]
	v_pk_fma_f32 v[6:7], v[76:77], v[28:29], v[84:85]
	v_mov_b32_e32 v14, v3
	v_mov_b32_e32 v15, v5
	v_pk_add_f32 v[6:7], v[14:15], v[6:7]
	v_mov_b32_e32 v3, v4
	v_pk_add_f32 v[2:3], v[2:3], v[6:7]
	v_mul_f32_e32 v18, v1, v0
	v_fma_f32 v4, |v2|, s84, 1.0
	v_rcp_f32_e32 v4, v4
	v_fma_f32 v0, -v1, v0, v1
	v_cmp_gt_f32_e32 vcc, 0, v1
	s_nop 1
	v_cndmask_b32_e32 v0, v0, v18, vcc
	v_mul_f32_e32 v5, v11, v0
	v_fmamk_f32 v0, v4, 0x3f07dc22, v241
	v_fmaak_f32 v6, v4, v0, 0x3f35f0e3
	v_pk_mul_f32 v[0:1], v[2:3], v[2:3]
	v_fmaak_f32 v6, v4, v6, 0xbe11a98e
	v_mul_f32_e32 v0, 0xbf38aa3b, v0
	v_exp_f32_e32 v0, v0
	v_fmaak_f32 v6, v4, v6, 0x3e027906
	v_mul_f32_e32 v4, v4, v6
	v_fma_f32 v6, |v3|, s84, 1.0
	v_rcp_f32_e32 v6, v6
	v_mul_f32_e32 v0, v0, v4
	v_mul_f32_e32 v4, v2, v0
	v_fma_f32 v0, -v2, v0, v2
	v_cmp_gt_f32_e32 vcc, 0, v2
	v_mul_f32_e32 v1, 0xbf38aa3b, v1
	v_exp_f32_e32 v1, v1
	v_cndmask_b32_e32 v0, v0, v4, vcc
	v_mul_f32_e32 v4, v12, v0
	v_fmamk_f32 v0, v6, 0x3f07dc22, v241
	v_fmaak_f32 v0, v6, v0, 0x3f35f0e3
	v_fmaak_f32 v0, v6, v0, 0xbe11a98e
	v_fmaak_f32 v0, v6, v0, 0x3e027906
	v_mul_f32_e32 v0, v6, v0
	v_mul_f32_e32 v0, v1, v0
	v_mul_f32_e32 v1, v3, v0
	v_fma_f32 v0, -v3, v0, v3
	v_cmp_gt_f32_e32 vcc, 0, v3
	v_cvt_pk_bf16_f32 v2, v10, v5
	s_nop 1
	v_cndmask_b32_e32 v0, v0, v1, vcc
	v_mul_f32_e32 v3, v13, v0
	v_cvt_pk_bf16_f32 v3, v4, v3
	v_lshl_add_u64 v[4:5], s[80:81], 0, v[30:31]
	v_lshl_add_u64 v[4:5], v[184:185], 1, v[4:5]
	v_cvt_pk_bf16_f32 v0, v40, v24
	v_cvt_pk_bf16_f32 v1, v16, v17
	global_store_dwordx4 v[4:5], v[0:3], off offset:256 sc1

;     __device__ __forceinline__ void operator()(EPI_ARGS) const {
;         const int col0 = u.pn * 256 + wc * 32 + 4 * fq;
;         if (u.pm == 32) {
;             float* pb = srow + (size_t)u.pc * 128 * ldc;
; #pragma unroll
;             for (int m = 0; m < 4; ++m) { float* rowp = pb + (size_t)(wr * 64 + fr + m * 16) * ldc + col0;
; #pragma unroll
;                 for (int bj = 0; bj < 2; ++bj)
; #pragma unroll
;                     for (int n = 0; n < 2; ++n) *(f32x4*)(rowp + bj * 128 + n * 16) = acc[0][bj][m][n]; }
;         } else {
;             const int row0 = u.pm * 256 + wr * 64 + fr;
; #pragma unroll
;             for (int ai = 0; ai < 2; ++ai)
; #pragma unroll
;                 for (int m = 0; m < 4; ++m) { float* rowp = C + (size_t)(row0 + ai * 128 + m * 16) * ldc + col0;
; #pragma unroll
;                     for (int bj = 0; bj < 2; ++bj)
; #pragma unroll
;                         for (int n = 0; n < 2; ++n) *(f32x4*)(rowp + bj * 128 + n * 16) = acc[ai][bj][m][n]; }
;         }
;     }
.LBB0_2018:
	v_lshl_or_b32 v146, s3, 8, v133
	s_mov_b64 s[14:15], -1
	s_cmp_lg_u32 s26, 32
	v_ashrrev_i32_e32 v147, 31, v146
	s_cbranch_scc0 .LBB0_2020
	v_lshl_add_u32 v148, s26, 8, v132
	v_or_b32_e32 v156, 16, v148
	v_ashrrev_i32_e32 v149, 31, v148
	v_readlane_b32 s14, v252, 62
	v_ashrrev_i32_e32 v157, 31, v156
	v_lshlrev_b64 v[152:153], 13, v[148:149]
	v_readlane_b32 s15, v252, 63
	v_lshlrev_b64 v[156:157], 13, v[156:157]
	v_lshlrev_b64 v[154:155], 2, v[146:147]
	v_lshl_add_u64 v[152:153], s[14:15], 0, v[152:153]
	v_lshl_add_u64 v[156:157], s[14:15], 0, v[156:157]
	v_lshl_add_u64 v[152:153], v[152:153], 0, v[154:155]
	v_lshl_add_u64 v[156:157], v[156:157], 0, v[154:155]
	global_store_dwordx4 v[152:153], v[118:121], off sc1
	global_store_dwordx4 v[152:153], v[110:113], off offset:64 sc1
	global_store_dwordx4 v[152:153], v[74:77], off offset:512 sc1
	global_store_dwordx4 v[152:153], v[62:65], off offset:576 sc1
	global_store_dwordx4 v[156:157], v[98:101], off sc1
	global_store_dwordx4 v[156:157], v[90:93], off offset:64 sc1
	global_store_dwordx4 v[156:157], v[50:53], off offset:512 sc1
	global_store_dwordx4 v[156:157], v[42:45], off offset:576 sc1
	v_or_b32_e32 v156, 32, v148
	v_or_b32_e32 v148, 48, v148
	v_ashrrev_i32_e32 v157, 31, v156
	v_ashrrev_i32_e32 v149, 31, v148
	v_lshlrev_b64 v[156:157], 13, v[156:157]
	v_lshlrev_b64 v[148:149], 13, v[148:149]
	v_lshl_add_u64 v[156:157], s[14:15], 0, v[156:157]
	v_lshl_add_u64 v[148:149], s[14:15], 0, v[148:149]
	s_mov_b32 s3, 0x100000
	v_lshl_add_u64 v[156:157], v[156:157], 0, v[154:155]
	v_lshl_add_u64 v[148:149], v[148:149], 0, v[154:155]
	v_add_co_u32_e32 v154, vcc, s3, v152
	s_mov_b64 s[14:15], 0x100000
	s_nop 0
	v_addc_co_u32_e32 v155, vcc, 0, v153, vcc
	s_mov_b32 s3, 0x120000
	global_store_dwordx4 v[156:157], v[82:85], off sc1
	global_store_dwordx4 v[156:157], v[70:73], off offset:64 sc1
	global_store_dwordx4 v[156:157], v[34:37], off offset:512 sc1
	global_store_dwordx4 v[156:157], v[26:29], off offset:576 sc1
	global_store_dwordx4 v[148:149], v[54:57], off sc1
	global_store_dwordx4 v[148:149], v[10:13], off offset:64 sc1
	global_store_dwordx4 v[148:149], v[4:7], off offset:512 sc1
	global_store_dwordx4 v[148:149], v[0:3], off offset:576 sc1
	v_lshl_add_u64 v[148:149], v[152:153], 0, s[14:15]
	global_store_dwordx4 v[154:155], v[126:129], off sc1
	global_store_dwordx4 v[148:149], v[122:125], off offset:64 sc1
	global_store_dwordx4 v[148:149], v[102:105], off offset:512 sc1
	global_store_dwordx4 v[148:149], v[94:97], off offset:576 sc1
	s_mov_b64 s[14:15], 0x120000
	s_nop 0
	v_add_co_u32_e32 v96, vcc, s3, v152
	v_lshl_add_u64 v[94:95], v[152:153], 0, s[14:15]
	s_nop 0
	v_addc_co_u32_e32 v97, vcc, 0, v153, vcc
	global_store_dwordx4 v[96:97], v[114:117], off sc1
	global_store_dwordx4 v[94:95], v[106:109], off offset:64 sc1
	global_store_dwordx4 v[94:95], v[66:69], off offset:512 sc1
	global_store_dwordx4 v[94:95], v[58:61], off offset:576 sc1
	s_mov_b64 s[14:15], 0x140000
	s_nop 0
	v_add_co_u32_e32 v60, vcc, 0x140000, v152
	v_lshl_add_u64 v[58:59], v[152:153], 0, s[14:15]
	s_nop 0
	v_addc_co_u32_e32 v61, vcc, 0, v153, vcc
	global_store_dwordx4 v[60:61], v[86:89], off sc1
	global_store_dwordx4 v[58:59], v[78:81], off offset:64 sc1
	global_store_dwordx4 v[58:59], v[38:41], off offset:512 sc1
	global_store_dwordx4 v[58:59], v[30:33], off offset:576 sc1
	s_mov_b64 s[14:15], 0x160000
	v_lshl_add_u64 v[148:149], v[152:153], 0, s[14:15]
	v_add_co_u32_e32 v30, vcc, 0x160000, v152
	s_mov_b64 s[14:15], 0
	s_nop 0
	v_addc_co_u32_e32 v31, vcc, 0, v153, vcc
	global_store_dwordx4 v[30:31], v[46:49], off sc1
.LBB0_2020:
	s_andn2_b64 vcc, exec, s[14:15]
	s_cbranch_vccnz .LBB0_2022
	s_ashr_i32 s3, s2, 31
	s_lshl_b64 s[2:3], s[2:3], 20
	v_readlane_b32 s14, v254, 34
	v_readlane_b32 s15, v254, 35
	s_add_u32 s2, s14, s2
	s_addc_u32 s3, s15, s3
	v_lshl_add_u64 v[14:15], v[146:147], 2, s[2:3]
	v_lshl_add_u64 v[16:17], v[14:15], 0, v[134:135]
	global_store_dwordx4 v[16:17], v[118:121], off sc1
	global_store_dwordx4 v[16:17], v[110:113], off offset:64 sc1
	global_store_dwordx4 v[16:17], v[74:77], off offset:512 sc1
	global_store_dwordx4 v[16:17], v[62:65], off offset:576 sc1
	v_lshl_add_u64 v[16:17], v[14:15], 0, v[136:137]
	global_store_dwordx4 v[16:17], v[98:101], off sc1
	global_store_dwordx4 v[16:17], v[90:93], off offset:64 sc1
	global_store_dwordx4 v[16:17], v[50:53], off offset:512 sc1
	global_store_dwordx4 v[16:17], v[42:45], off offset:576 sc1
	v_lshl_add_u64 v[16:17], v[14:15], 0, v[138:139]
	global_store_dwordx4 v[16:17], v[82:85], off sc1
	global_store_dwordx4 v[16:17], v[70:73], off offset:64 sc1
	global_store_dwordx4 v[16:17], v[34:37], off offset:512 sc1
	global_store_dwordx4 v[16:17], v[26:29], off offset:576 sc1
	v_lshl_add_u64 v[148:149], v[14:15], 0, v[140:141]
	v_mov_b64_e32 v[16:17], v[2:3]
	v_mov_b64_e32 v[20:21], v[6:7]
	v_mov_b64_e32 v[24:25], v[12:13]
	v_mov_b64_e32 v[14:15], v[0:1]
	v_mov_b64_e32 v[18:19], v[4:5]
	v_mov_b64_e32 v[22:23], v[10:11]
	global_store_dwordx4 v[148:149], v[54:57], off sc1
.LBB0_2022:
	s_and_b64 vcc, exec, s[0:1]
	s_mov_b64 s[0:1], -1
	global_store_dwordx4 v[148:149], v[22:25], off offset:64 sc1
	global_store_dwordx4 v[148:149], v[18:21], off offset:512 sc1
	global_store_dwordx4 v[148:149], v[14:17], off offset:576 sc1
	s_cbranch_vccnz .LBB0_2000
	s_andn2_b64 vcc, exec, s[4:5]
	s_cbranch_vccnz .LBB0_1999
	s_barrier
	s_branch .LBB0_1999
